# packed f32 (v_pk_add/mul/fma_f32) unpacked to scalar pairs across the whole kernel (2901 sites: GEMM epilogues, norms, combine, HGRN)
# speedup vs baseline: 1.0045x; 1.0015x over previous
.LBB0_129:
	s_mul_i32 s1, s2, 0xb4000
	s_mul_hi_u32 s0, s2, 0xb4000
	s_add_u32 s4, s1, 0x100000
	s_addc_u32 s5, s0, 0
	s_cmp_eq_u32 s2, 0
	s_cselect_b64 s[14:15], -1, 0
	s_cmp_lg_u32 s2, 0
	s_cselect_b64 s[16:17], -1, 0
	v_writelane_b32 v253, s4, 60
	s_mov_b32 s24, s2
	s_and_b64 vcc, exec, s[16:17]
	v_writelane_b32 v253, s5, 61
	s_cbranch_vccnz .LBB0_187
	s_mov_b64 s[0:1], s[70:71]
	s_mov_b64 s[2:3], s[70:71]
	s_load_dwordx2 s[0:1], s[0:1], 0x0
	s_load_dwordx2 s[6:7], s[2:3], 0x48
	s_mov_b64 s[2:3], s[70:71]
	s_load_dwordx2 s[2:3], s[2:3], 0xd0
	v_lshlrev_b32_e32 v0, 2, v18
	v_lshlrev_b64 v[2:3], 2, v[0:1]
	s_waitcnt lgkmcnt(0)
	v_lshl_add_u64 v[6:7], s[6:7], 0, v[2:3]
	v_mov_b32_e32 v19, v1
	s_add_u32 s8, s2, s4
	s_addc_u32 s3, s3, s5
	s_lshl_b32 s2, s33, 7
	s_lshl_b32 s9, s44, 4
	s_add_i32 s2, s2, s9
	s_add_i32 s10, s2, 0xffff8000
	s_lshr_b32 s10, s10, 5
	s_ashr_i32 s9, s2, 13
	s_add_i32 s10, s10, 4
	s_cmp_lt_i32 s2, 0x8000
	s_cselect_b32 s9, s9, s10
	s_mul_hi_i32 s10, s9, 0x9000
	s_mul_i32 s9, s9, 0x9000
	s_add_u32 s8, s8, s9
	s_addc_u32 s9, s3, s10
	s_add_u32 s10, s8, 0x1000
	s_addc_u32 s11, s9, 0
	s_mov_b64 s[4:5], s[70:71]
	v_lshl_add_u64 v[4:5], s[10:11], 0, v[2:3]
	global_load_dwordx4 v[20:23], v[4:5], off
	v_or_b32_e32 v4, 0x100, v0
	v_mov_b32_e32 v5, v1
	v_lshl_add_u64 v[4:5], v[4:5], 2, s[10:11]
	global_load_dwordx4 v[24:27], v[4:5], off
	v_or_b32_e32 v4, 0x200, v0
	v_mov_b32_e32 v5, v1
	v_lshl_add_u64 v[4:5], v[4:5], 2, s[10:11]
	global_load_dwordx4 v[28:31], v[4:5], off
	v_or_b32_e32 v4, 0x300, v0
	v_mov_b32_e32 v5, v1
	v_lshl_add_u64 v[4:5], v[4:5], 2, s[10:11]
	global_load_dwordx4 v[38:41], v[4:5], off
	global_load_dwordx4 v[42:45], v[6:7], off
	global_load_dwordx4 v[46:49], v[6:7], off offset:1024
	v_lshl_add_u64 v[14:15], s[8:9], 0, v[2:3]
	global_load_dwordx4 v[50:53], v[6:7], off offset:2048
	global_load_dwordx4 v[2:5], v[14:15], off
	global_load_dwordx4 v[60:63], v[6:7], off offset:3072
	s_nop 0
	global_load_dwordx4 v[6:9], v[14:15], off offset:1024
	global_load_dwordx4 v[10:13], v[14:15], off offset:2048
	s_nop 0
	global_load_dwordx4 v[14:17], v[14:15], off offset:3072
	s_load_dwordx2 s[4:5], s[4:5], 0xd0
	s_ashr_i32 s3, s2, 31
	s_lshl_b64 s[6:7], s[2:3], 11
	v_xor_b32_e32 v54, 4, v0
	v_xor_b32_e32 v55, 8, v0
	s_waitcnt lgkmcnt(0)
	s_add_u32 s4, s4, s6
	s_addc_u32 s5, s5, s7
	s_lshl_b64 s[2:3], s[2:3], 12
	s_add_u32 s0, s0, s2
	s_addc_u32 s1, s1, s3
	v_lshl_add_u64 v[32:33], v[18:19], 3, s[4:5]
	s_mov_b64 s[4:5], 0x17200e00
	v_lshl_add_u64 v[18:19], v[18:19], 4, s[0:1]
	s_mov_b64 s[0:1], 0x1c00
	v_lshl_add_u64 v[34:35], v[32:33], 0, s[4:5]
	v_lshl_add_u64 v[36:37], v[18:19], 0, s[0:1]
	v_xor_b32_e32 v56, 16, v0
	v_xor_b32_e32 v57, 32, v0
	v_xor_b32_e32 v58, 64, v0
	v_xor_b32_e32 v0, 0x80, v0
	s_mov_b32 s0, -2
	s_mov_b64 s[2:3], 0x1000
	s_mov_b64 s[4:5], 0x2000
	s_waitcnt vmcnt(11)
	v_add_f32_e32 v18, 1.0, v22
	v_add_f32_e32 v19, 1.0, v23
	v_add_f32_e32 v20, 1.0, v20
	v_add_f32_e32 v21, 1.0, v21
	s_waitcnt vmcnt(10)
	v_add_f32_e32 v22, 1.0, v26
	v_add_f32_e32 v23, 1.0, v27
	v_add_f32_e32 v24, 1.0, v24
	v_add_f32_e32 v25, 1.0, v25
	s_waitcnt vmcnt(9)
	v_add_f32_e32 v26, 1.0, v30
	v_add_f32_e32 v27, 1.0, v31
	v_add_f32_e32 v28, 1.0, v28
	v_add_f32_e32 v29, 1.0, v29
	s_waitcnt vmcnt(8)
	v_add_f32_e32 v30, 1.0, v40
	v_add_f32_e32 v31, 1.0, v41
	v_add_f32_e32 v32, 1.0, v38
	v_add_f32_e32 v33, 1.0, v39
	s_waitcnt vmcnt(7)
	v_mul_f32_e32 v38, v44, v18
	v_mul_f32_e32 v39, v45, v19
	v_mul_f32_e32 v40, v42, v20
	v_mul_f32_e32 v41, v43, v21
	s_waitcnt vmcnt(6)
	v_mul_f32_e32 v42, v48, v22
	v_mul_f32_e32 v43, v49, v23
	v_mul_f32_e32 v44, v46, v24
	v_mul_f32_e32 v45, v47, v25
	s_waitcnt vmcnt(5)
	v_mul_f32_e32 v46, v52, v26
	v_mul_f32_e32 v47, v53, v27
	v_mul_f32_e32 v48, v50, v28
	v_mul_f32_e32 v49, v51, v29
	s_waitcnt vmcnt(3)
	v_mul_f32_e32 v50, v62, v30
	v_mul_f32_e32 v51, v63, v31
	v_mul_f32_e32 v52, v60, v32
	v_mul_f32_e32 v53, v61, v33
.LBB0_131:
	global_load_dwordx4 v[26:29], v[36:37], off offset:-3072
	global_load_dwordx4 v[22:25], v[36:37], off offset:-2048
	global_load_dwordx4 v[18:21], v[36:37], off
	global_load_dwordx4 v[30:33], v[36:37], off offset:-1024
	global_load_dwordx4 v[60:63], v[36:37], off offset:-4096
	v_add_co_u32_e32 v72, vcc, 0xfffff000, v36
	s_add_i32 s0, s0, 2
	s_nop 0
	v_addc_co_u32_e32 v73, vcc, -1, v37, vcc
	global_load_dwordx4 v[64:67], v[72:73], off offset:-3072
	global_load_dwordx4 v[68:71], v[72:73], off offset:-2048
	s_nop 0
	global_load_dwordx4 v[72:75], v[72:73], off offset:-1024
	s_cmp_lt_u32 s0, 14
	v_lshl_add_u64 v[36:37], v[36:37], 0, s[4:5]
	s_waitcnt vmcnt(7)
	v_mul_f32_e32 v76, v28, v28
	v_mul_f32_e32 v77, v29, v29
	v_mul_f32_e32 v78, v26, v26
	v_mul_f32_e32 v79, v27, v27
	s_waitcnt vmcnt(6)
	v_mul_f32_e32 v80, v24, v24
	v_mul_f32_e32 v81, v25, v25
	v_mul_f32_e32 v82, v22, v22
	v_mul_f32_e32 v83, v23, v23
	s_waitcnt vmcnt(5)
	v_mul_f32_e32 v87, v20, v20
	s_waitcnt vmcnt(4)
	v_mul_f32_e32 v84, v31, v31
	v_mul_f32_e32 v86, v33, v33
	v_mul_f32_e32 v90, v21, v21
	v_pk_mov_b32 v[88:89], v[78:79], v[76:77] op_sel:[1,0]
	v_mov_b32_e32 v79, v77
	v_pk_mov_b32 v[76:77], v[82:83], v[80:81] op_sel:[1,0]
	v_mov_b32_e32 v83, v81
	v_fma_f32 v80, v30, v30, v84
	v_fma_f32 v81, v31, v31, v84
	v_fma_f32 v84, v32, v32, v86
	v_fma_f32 v85, v33, v33, v86
	v_add_f32_e32 v78, v88, v78
	v_add_f32_e32 v79, v89, v79
	v_add_f32_e32 v76, v76, v82
	v_add_f32_e32 v77, v77, v83
	v_mov_b32_e32 v81, v87
	v_mov_b32_e32 v85, v90
	s_waitcnt vmcnt(2)
	v_mul_f32_e32 v82, v66, v66
	v_mul_f32_e32 v83, v67, v67
	v_mul_f32_e32 v86, v64, v64
	v_mul_f32_e32 v87, v65, v65
	s_waitcnt vmcnt(1)
	v_mul_f32_e32 v88, v70, v70
	v_mul_f32_e32 v89, v71, v71
	v_mul_f32_e32 v90, v68, v68
	v_mul_f32_e32 v91, v69, v69
	v_mul_f32_e32 v59, v18, v18
	v_mul_f32_e32 v95, v19, v19
	v_pk_add_f32 v[78:79], v[78:79], v[78:79] op_sel:[0,1] op_sel_hi:[1,0]
	v_pk_add_f32 v[76:77], v[76:77], v[76:77] op_sel:[0,1] op_sel_hi:[1,0]
	v_add_f32_e32 v80, v80, v84
	v_add_f32_e32 v81, v81, v85
	v_pk_mov_b32 v[84:85], v[86:87], v[82:83] op_sel:[1,0]
	v_mov_b32_e32 v87, v83
	v_pk_mov_b32 v[82:83], v[90:91], v[88:89] op_sel:[1,0]
	v_mov_b32_e32 v91, v89
	s_waitcnt vmcnt(0)
	v_mul_f32_e32 v92, v73, v73
	v_mul_f32_e32 v94, v75, v75
	v_mov_b32_e32 v79, v59
	v_mov_b32_e32 v77, v95
	v_add_f32_e32 v84, v84, v86
	v_add_f32_e32 v85, v85, v87
	v_add_f32_e32 v82, v82, v90
	v_add_f32_e32 v83, v83, v91
	v_mul_f32_e32 v96, v60, v60
	v_mul_f32_e32 v97, v61, v61
	v_mul_f32_e32 v98, v62, v62
	v_mul_f32_e32 v99, v63, v63
	v_fma_f32 v88, v72, v72, v92
	v_fma_f32 v89, v73, v73, v92
	v_fma_f32 v92, v74, v74, v94
	v_fma_f32 v93, v75, v75, v94
	v_add_f32_e32 v76, v78, v76
	v_add_f32_e32 v77, v79, v77
	v_add_f32_e32 v78, v84, v85
	v_add_f32_e32 v79, v85, v84
	v_pk_add_f32 v[82:83], v[82:83], v[82:83] op_sel:[0,1] op_sel_hi:[1,0]
	v_mov_b32_e32 v89, v98
	v_mov_b32_e32 v93, v99
	v_add_f32_e32 v76, v76, v80
	v_add_f32_e32 v77, v77, v81
	v_mov_b32_e32 v79, v96
	v_mov_b32_e32 v83, v97
	v_add_f32_e32 v84, v88, v92
	v_add_f32_e32 v85, v89, v93
	v_add_f32_e32 v59, v76, v77
	v_add_f32_e32 v76, v78, v82
	v_add_f32_e32 v77, v79, v83
	ds_bpermute_b32 v78, v54, v59
	v_add_f32_e32 v76, v76, v84
	v_add_f32_e32 v77, v77, v85
	s_waitcnt lgkmcnt(0)
	v_add_f32_e32 v59, v59, v78
	v_add_f32_e32 v76, v76, v77
	ds_bpermute_b32 v77, v54, v76
	ds_bpermute_b32 v78, v55, v59
	s_waitcnt lgkmcnt(1)
	v_add_f32_e32 v76, v76, v77
	ds_bpermute_b32 v77, v55, v76
	s_waitcnt lgkmcnt(1)
	v_add_f32_e32 v59, v59, v78
	ds_bpermute_b32 v78, v56, v59
	s_waitcnt lgkmcnt(1)
	v_add_f32_e32 v76, v76, v77
	ds_bpermute_b32 v77, v56, v76
	s_waitcnt lgkmcnt(1)
	v_add_f32_e32 v59, v59, v78
	ds_bpermute_b32 v78, v57, v59
	s_waitcnt lgkmcnt(1)
	v_add_f32_e32 v76, v76, v77
	ds_bpermute_b32 v77, v57, v76
	s_waitcnt lgkmcnt(1)
	v_add_f32_e32 v59, v59, v78
	ds_bpermute_b32 v78, v58, v59
	s_waitcnt lgkmcnt(1)
	v_add_f32_e32 v76, v76, v77
	ds_bpermute_b32 v77, v58, v76
	s_waitcnt lgkmcnt(1)
	v_add_f32_e32 v59, v59, v78
	ds_bpermute_b32 v78, v0, v59
	s_waitcnt lgkmcnt(1)
	v_add_f32_e32 v77, v76, v77
	ds_bpermute_b32 v79, v0, v77
	s_waitcnt lgkmcnt(1)
	v_add_f32_e32 v59, v59, v78
	v_fmamk_f32 v59, v59, 0x3a800000, v230
	v_rsq_f32_e32 v76, v59
	s_waitcnt lgkmcnt(0)
	v_add_f32_e32 v59, v77, v79
	v_fmamk_f32 v59, v59, 0x3a800000, v230
	v_rsq_f32_e32 v78, v59
	v_mul_f32_e32 v26, v26, v76
	v_mul_f32_e32 v27, v27, v76
	v_mul_f32_e32 v22, v22, v76
	v_mul_f32_e32 v23, v23, v76
	v_mul_f32_e32 v28, v28, v76
	v_mul_f32_e32 v29, v29, v76
	v_mul_f32_e32 v64, v64, v78
	v_mul_f32_e32 v65, v65, v78
	v_mul_f32_e32 v66, v66, v78
	v_mul_f32_e32 v67, v67, v78
	v_fma_f32 v64, v40, v64, v2
	v_fma_f32 v65, v41, v65, v3
	v_mul_f32_e32 v68, v68, v78
	v_mul_f32_e32 v69, v69, v78
	v_mul_f32_e32 v70, v70, v78
	v_mul_f32_e32 v71, v71, v78
	v_mul_f32_e32 v60, v60, v78
	v_mul_f32_e32 v61, v61, v78
	v_fma_f32 v66, v38, v66, v4
	v_fma_f32 v67, v39, v67, v5
	v_cvt_pk_bf16_f32 v64, v64, v65
	v_mul_f32_e32 v24, v24, v76
	v_mul_f32_e32 v25, v25, v76
	v_cvt_pk_bf16_f32 v65, v66, v67
	v_mul_f32_e32 v18, v18, v76
	v_mul_f32_e32 v19, v19, v76
	v_fma_f32 v26, v40, v26, v2
	v_fma_f32 v27, v41, v27, v3
	v_fma_f32 v22, v44, v22, v6
	v_fma_f32 v23, v45, v23, v7
	v_mul_f32_e32 v72, v72, v78
	v_mul_f32_e32 v73, v73, v78
	v_mul_f32_e32 v74, v74, v78
	v_mul_f32_e32 v75, v75, v78
	v_mul_f32_e32 v62, v62, v78
	v_mul_f32_e32 v63, v63, v78
	v_fma_f32 v70, v42, v70, v8
	v_fma_f32 v71, v43, v71, v9
	v_fma_f32 v68, v44, v68, v6
	v_fma_f32 v69, v45, v69, v7
	v_fma_f32 v60, v52, v60, v14
	v_fma_f32 v61, v53, v61, v15
	global_store_dwordx2 v[34:35], v[64:65], off offset:-3584
	v_cvt_pk_bf16_f32 v64, v68, v69
	v_cvt_pk_bf16_f32 v65, v70, v71
	v_mul_f32_e32 v30, v30, v76
	v_mul_f32_e32 v31, v31, v76
	v_mul_f32_e32 v32, v32, v76
	v_mul_f32_e32 v33, v33, v76
	v_mul_f32_e32 v20, v20, v76
	v_mul_f32_e32 v21, v21, v76
	v_fma_f32 v28, v38, v28, v4
	v_fma_f32 v29, v39, v29, v5
	v_fma_f32 v24, v42, v24, v8
	v_fma_f32 v25, v43, v25, v9
	v_fma_f32 v18, v52, v18, v14
	v_fma_f32 v19, v53, v19, v15
	v_fma_f32 v74, v46, v74, v12
	v_fma_f32 v75, v47, v75, v13
	v_fma_f32 v72, v48, v72, v10
	v_fma_f32 v73, v49, v73, v11
	v_fma_f32 v62, v50, v62, v16
	v_fma_f32 v63, v51, v63, v17
	global_store_dwordx2 v[34:35], v[64:65], off offset:-3072
	v_cvt_pk_bf16_f32 v64, v72, v73
	v_cvt_pk_bf16_f32 v65, v74, v75
	global_store_dwordx2 v[34:35], v[64:65], off offset:-2560
	v_cvt_pk_bf16_f32 v60, v60, v61
	v_cvt_pk_bf16_f32 v61, v62, v63
	global_store_dwordx2 v[34:35], v[60:61], off offset:-2048
	v_cvt_pk_bf16_f32 v26, v26, v27
	v_cvt_pk_bf16_f32 v27, v28, v29
	global_store_dwordx2 v[34:35], v[26:27], off offset:-1536
	v_cvt_pk_bf16_f32 v22, v22, v23
	v_cvt_pk_bf16_f32 v23, v24, v25
	v_fma_f32 v32, v46, v32, v12
	v_fma_f32 v33, v47, v33, v13
	v_fma_f32 v30, v48, v30, v10
	v_fma_f32 v31, v49, v31, v11
	v_fma_f32 v20, v50, v20, v16
	v_fma_f32 v21, v51, v21, v17
	global_store_dwordx2 v[34:35], v[22:23], off offset:-1024
	v_cvt_pk_bf16_f32 v22, v30, v31
	v_cvt_pk_bf16_f32 v23, v32, v33
	global_store_dwordx2 v[34:35], v[22:23], off offset:-512
	v_cvt_pk_bf16_f32 v18, v18, v19
	v_cvt_pk_bf16_f32 v19, v20, v21
	global_store_dwordx2 v[34:35], v[18:19], off
	v_lshl_add_u64 v[34:35], v[34:35], 0, s[2:3]
	s_cbranch_scc1 .LBB0_131
	s_waitcnt vmcnt(0)
	s_barrier
	s_getreg_b32 s0, hwreg(HW_REG_HW_ID, 0, 7)
	s_and_b32 s0, s0, 63
	s_lshl_b32 s0, s0, 2
	s_add_i32 s0, s0, 0x22240
	v_mov_b32_e32 v0, s0
	ds_read_b32 v0, v0
	v_mbcnt_lo_u32_b32 v2, -1, 0
	v_mbcnt_hi_u32_b32 v2, -1, v2
	s_waitcnt lgkmcnt(0)
	v_lshl_or_b32 v0, v0, 6, v2
	v_cmp_eq_u32_e32 vcc, 0, v0
	s_and_saveexec_b64 s[0:1], vcc
	s_cbranch_execz .LBB0_186
	v_readlane_b32 s2, v253, 23
	s_waitcnt vmcnt(0) expcnt(0) lgkmcnt(0)
	s_nop 0
	v_mov_b32_e32 v0, s2
	ds_read_b32 v3, v0
	v_readlane_b32 s2, v253, 24
	s_waitcnt lgkmcnt(0)
	v_cmp_eq_u32_e32 vcc, 0, v3
	v_mov_b32_e32 v0, s2
	ds_read_b32 v0, v0
	s_cbranch_vccnz .LBB0_135
	s_lshl_b32 s22, s74, 6
	s_cbranch_execz .LBB0_136
	s_branch .LBB0_150

.LBB0_297:
	s_waitcnt vmcnt(0)
	v_mul_f32_e32 v190, 0.5, v152
	v_mul_f32_e32 v191, 0.5, v153
	v_mul_f32_e32 v188, 0.5, v150
	v_mul_f32_e32 v189, 0.5, v151
	v_mul_f32_e32 v150, 0.5, v140
	v_mul_f32_e32 v151, 0.5, v141
	v_mul_f32_e32 v152, 0.5, v138
	v_mul_f32_e32 v153, 0.5, v139
	v_lshlrev_b32_e32 v138, 16, v154
	v_and_b32_e32 v139, 0xffff0000, v154
	v_lshlrev_b32_e32 v140, 16, v155
	v_and_b32_e32 v141, 0xffff0000, v155
	v_mul_f32_e32 v186, 0.5, v146
	v_mul_f32_e32 v187, 0.5, v147
	v_mul_f32_e32 v182, 0.5, v144
	v_mul_f32_e32 v183, 0.5, v145
	v_mul_f32_e32 v180, 0.5, v142
	v_mul_f32_e32 v181, 0.5, v143
	v_lshlrev_b32_e32 v146, 16, v156
	v_and_b32_e32 v147, 0xffff0000, v156
	v_fma_f32 v142, v128, v190, v140
	v_fma_f32 v143, v129, v191, v141
	v_fma_f32 v144, v126, v188, v138
	v_fma_f32 v145, v127, v189, v139
	v_mul_f32_e32 v184, 0.5, v148
	v_mul_f32_e32 v185, 0.5, v149
	v_lshlrev_b32_e32 v148, 16, v157
	v_and_b32_e32 v149, 0xffff0000, v157
	v_fma_f32 v140, v122, v186, v146
	v_fma_f32 v141, v123, v187, v147
	v_mul_f32_e32 v122, v145, v145
	v_mul_f32_e32 v123, v143, v143
	v_fma_f32 v138, v124, v184, v148
	v_fma_f32 v139, v125, v185, v149
	v_fmac_f32_e32 v122, v144, v144
	v_fmac_f32_e32 v123, v142, v142
	v_add_f32_e32 v122, v122, v123
	v_mul_f32_e32 v123, v141, v141
	v_mul_f32_e32 v124, v139, v139
	v_fmac_f32_e32 v123, v140, v140
	v_fmac_f32_e32 v124, v138, v138
	v_add_f32_e32 v123, v123, v124
	v_add_f32_e32 v156, v122, v123
	v_lshlrev_b32_e32 v122, 16, v158
	v_and_b32_e32 v123, 0xffff0000, v158
	v_lshlrev_b32_e32 v124, 16, v159
	v_and_b32_e32 v125, 0xffff0000, v159
	v_lshlrev_b32_e32 v148, 16, v160
	v_and_b32_e32 v149, 0xffff0000, v160
	v_fma_f32 v126, v120, v182, v124
	v_fma_f32 v127, v121, v183, v125
	v_fma_f32 v128, v118, v180, v122
	v_fma_f32 v129, v119, v181, v123
	v_lshlrev_b32_e32 v154, 16, v161
	v_and_b32_e32 v155, 0xffff0000, v161
	v_fma_f32 v124, v114, v152, v148
	v_fma_f32 v125, v115, v153, v149
	v_mul_f32_e32 v114, v129, v129
	v_mul_f32_e32 v115, v127, v127
	v_fma_f32 v122, v116, v150, v154
	v_fma_f32 v123, v117, v151, v155
	v_fmac_f32_e32 v114, v128, v128
	v_fmac_f32_e32 v115, v126, v126
	v_add_f32_e32 v114, v114, v115
	v_mul_f32_e32 v115, v125, v125
	v_mul_f32_e32 v116, v123, v123
	v_fmac_f32_e32 v115, v124, v124
	v_fmac_f32_e32 v116, v122, v122
	v_add_f32_e32 v115, v115, v116
	v_add_f32_e32 v114, v114, v115
	v_add_f32_e32 v114, v156, v114
	ds_bpermute_b32 v115, v195, v114
	v_cvt_pk_bf16_f32 v146, v144, v145
	v_cvt_pk_bf16_f32 v147, v142, v143
	v_cvt_pk_bf16_f32 v148, v140, v141
	v_cvt_pk_bf16_f32 v149, v138, v139
	s_waitcnt lgkmcnt(0)
	v_add_f32_e32 v114, v114, v115
	ds_bpermute_b32 v115, v196, v114
	global_store_dwordx4 v[178:179], v[146:149], off
	v_cvt_pk_bf16_f32 v116, v128, v129
	v_cvt_pk_bf16_f32 v117, v126, v127
	v_cvt_pk_bf16_f32 v118, v124, v125
	v_cvt_pk_bf16_f32 v119, v122, v123
	global_store_dwordx4 v[178:179], v[116:119], off offset:256
	s_and_saveexec_b64 s[42:43], s[12:13]
	s_cbranch_execz .LBB0_299
	s_waitcnt lgkmcnt(0)
	v_add_f32_e32 v114, v114, v115
	ds_write_b32 v205, v114

.LBB0_305:
	v_lshlrev_b32_e32 v146, 16, v134
	v_and_b32_e32 v147, 0xffff0000, v134
	v_lshlrev_b32_e32 v154, 16, v137
	v_and_b32_e32 v155, 0xffff0000, v137
	v_lshlrev_b32_e32 v134, 16, v135
	v_and_b32_e32 v135, 0xffff0000, v135
	v_lshlrev_b32_e32 v148, 16, v136
	v_and_b32_e32 v149, 0xffff0000, v136
	v_fma_f32 v136, v110, v188, v146
	v_fma_f32 v137, v111, v189, v147
	v_fma_f32 v146, v108, v184, v154
	v_fma_f32 v147, v109, v185, v155
	v_add_co_u32_e32 v154, vcc, s75, v178
	v_fma_f32 v134, v112, v190, v134
	v_fma_f32 v135, v113, v191, v135
	v_fma_f32 v148, v106, v186, v148
	v_fma_f32 v149, v107, v187, v149
	v_cvt_pk_bf16_f32 v106, v136, v137
	v_cvt_pk_bf16_f32 v107, v134, v135
	v_addc_co_u32_e32 v155, vcc, 0, v179, vcc
	v_cvt_pk_bf16_f32 v108, v148, v149
	v_cvt_pk_bf16_f32 v109, v146, v147
	global_store_dwordx4 v[154:155], v[106:109], off
	v_lshlrev_b32_e32 v110, 16, v132
	v_and_b32_e32 v111, 0xffff0000, v132
	v_mul_f32_e32 v106, v137, v137
	v_mul_f32_e32 v107, v135, v135
	v_fmac_f32_e32 v106, v136, v136
	v_fmac_f32_e32 v107, v134, v134
	v_add_f32_e32 v106, v106, v107
	v_mul_f32_e32 v107, v149, v149
	v_mul_f32_e32 v108, v147, v147
	v_fmac_f32_e32 v107, v148, v148
	v_fmac_f32_e32 v108, v146, v146
	v_add_f32_e32 v107, v107, v108
	v_add_f32_e32 v156, v106, v107
	v_lshlrev_b32_e32 v106, 16, v130
	v_and_b32_e32 v107, 0xffff0000, v130
	v_lshlrev_b32_e32 v108, 16, v131
	v_and_b32_e32 v109, 0xffff0000, v131
	v_lshlrev_b32_e32 v130, 16, v133
	v_and_b32_e32 v131, 0xffff0000, v133
	v_fma_f32 v108, v104, v182, v108
	v_fma_f32 v109, v105, v183, v109
	v_fma_f32 v112, v102, v180, v106
	v_fma_f32 v113, v103, v181, v107
	v_fma_f32 v110, v98, v152, v110
	v_fma_f32 v111, v99, v153, v111
	v_cvt_pk_bf16_f32 v98, v112, v113
	v_cvt_pk_bf16_f32 v99, v108, v109
	v_fma_f32 v106, v100, v150, v130
	v_fma_f32 v107, v101, v151, v131
	v_cvt_pk_bf16_f32 v100, v110, v111
	s_nop 0
	v_cvt_pk_bf16_f32 v101, v106, v107
	global_store_dwordx4 v[154:155], v[98:101], off offset:256
	s_nop 1
	v_mul_f32_e32 v98, v113, v113
	v_mul_f32_e32 v99, v109, v109
	v_fmac_f32_e32 v98, v112, v112
	v_fmac_f32_e32 v99, v108, v108
	v_add_f32_e32 v98, v98, v99
	v_mul_f32_e32 v99, v111, v111
	v_mul_f32_e32 v100, v107, v107
	v_fmac_f32_e32 v99, v110, v110
	v_fmac_f32_e32 v100, v106, v106
	v_add_f32_e32 v99, v99, v100
	v_add_f32_e32 v98, v98, v99
	v_add_f32_e32 v98, v156, v98
	ds_bpermute_b32 v99, v195, v98
	s_waitcnt lgkmcnt(0)
	v_add_f32_e32 v98, v98, v99
	ds_bpermute_b32 v99, v196, v98
	s_and_saveexec_b64 s[42:43], s[12:13]
	s_cbranch_execz .LBB0_307
	s_waitcnt lgkmcnt(0)
	v_add_f32_e32 v98, v98, v99
	ds_write_b32 v205, v98 offset:256

.LBB0_313:
	s_waitcnt vmcnt(2)
	v_lshlrev_b32_e32 v130, 16, v118
	v_and_b32_e32 v131, 0xffff0000, v118
	s_mov_b32 s37, 0x10000
	v_lshlrev_b32_e32 v118, 16, v119
	v_and_b32_e32 v119, 0xffff0000, v119
	v_fma_f32 v94, v94, v188, v130
	v_fma_f32 v95, v95, v189, v131
	v_add_co_u32_e32 v130, vcc, s37, v178
	v_lshlrev_b32_e32 v132, 16, v120
	v_and_b32_e32 v133, 0xffff0000, v120
	v_lshlrev_b32_e32 v120, 16, v121
	v_and_b32_e32 v121, 0xffff0000, v121
	v_fma_f32 v96, v96, v190, v118
	v_fma_f32 v97, v97, v191, v119
	v_cvt_pk_bf16_f32 v118, v94, v95
	v_addc_co_u32_e32 v131, vcc, 0, v179, vcc
	v_cvt_pk_bf16_f32 v119, v96, v97
	v_fma_f32 v92, v92, v184, v120
	v_fma_f32 v93, v93, v185, v121
	v_fma_f32 v90, v90, v186, v132
	v_fma_f32 v91, v91, v187, v133
	v_lshlrev_b32_e32 v132, 16, v117
	v_cvt_pk_bf16_f32 v120, v90, v91
	v_cvt_pk_bf16_f32 v121, v92, v93
	global_store_dwordx4 v[130:131], v[118:121], off
	v_and_b32_e32 v133, 0xffff0000, v117
	s_nop 0
	v_mul_f32_e32 v118, v95, v95
	v_mul_f32_e32 v119, v97, v97
	v_fmac_f32_e32 v118, v94, v94
	v_fmac_f32_e32 v119, v96, v96
	v_add_f32_e32 v118, v118, v119
	v_mul_f32_e32 v119, v91, v91
	v_mul_f32_e32 v120, v93, v93
	v_fmac_f32_e32 v119, v90, v90
	v_fmac_f32_e32 v120, v92, v92
	v_add_f32_e32 v119, v119, v120
	v_add_f32_e32 v154, v118, v119
	v_lshlrev_b32_e32 v118, 16, v114
	v_and_b32_e32 v119, 0xffff0000, v114
	v_lshlrev_b32_e32 v114, 16, v115
	v_and_b32_e32 v115, 0xffff0000, v115
	v_lshlrev_b32_e32 v120, 16, v116
	v_and_b32_e32 v121, 0xffff0000, v116
	v_fma_f32 v114, v88, v182, v114
	v_fma_f32 v115, v89, v183, v115
	v_fma_f32 v116, v86, v180, v118
	v_fma_f32 v117, v87, v181, v119
	v_fma_f32 v120, v82, v152, v120
	v_fma_f32 v121, v83, v153, v121
	v_cvt_pk_bf16_f32 v82, v116, v117
	v_cvt_pk_bf16_f32 v83, v114, v115
	v_fma_f32 v118, v84, v150, v132
	v_fma_f32 v119, v85, v151, v133
	v_cvt_pk_bf16_f32 v84, v120, v121
	s_nop 0
	v_cvt_pk_bf16_f32 v85, v118, v119
	global_store_dwordx4 v[130:131], v[82:85], off offset:256
	s_nop 1
	v_mul_f32_e32 v82, v117, v117
	v_mul_f32_e32 v83, v115, v115
	v_fmac_f32_e32 v82, v116, v116
	v_fmac_f32_e32 v83, v114, v114
	v_add_f32_e32 v82, v82, v83
	v_mul_f32_e32 v83, v121, v121
	v_mul_f32_e32 v84, v119, v119
	v_fmac_f32_e32 v83, v120, v120
	v_fmac_f32_e32 v84, v118, v118
	v_add_f32_e32 v83, v83, v84
	v_add_f32_e32 v82, v82, v83
	v_add_f32_e32 v82, v154, v82
	ds_bpermute_b32 v83, v195, v82
	s_waitcnt lgkmcnt(0)
	v_add_f32_e32 v82, v82, v83
	ds_bpermute_b32 v83, v196, v82
	s_and_saveexec_b64 s[42:43], s[12:13]
	s_cbranch_execz .LBB0_315
	s_waitcnt lgkmcnt(0)
	v_add_f32_e32 v82, v82, v83
	ds_write_b32 v205, v82 offset:512

.LBB0_321:
	s_waitcnt vmcnt(2)
	v_lshlrev_b32_e32 v130, 16, v102
	v_and_b32_e32 v131, 0xffff0000, v102
	s_mov_b32 s37, 0x18000
	v_lshlrev_b32_e32 v102, 16, v103
	v_and_b32_e32 v103, 0xffff0000, v103
	v_fma_f32 v78, v78, v188, v130
	v_fma_f32 v79, v79, v189, v131
	v_add_co_u32_e32 v130, vcc, s37, v178
	v_lshlrev_b32_e32 v132, 16, v104
	v_and_b32_e32 v133, 0xffff0000, v104
	v_lshlrev_b32_e32 v104, 16, v105
	v_and_b32_e32 v105, 0xffff0000, v105
	v_fma_f32 v80, v80, v190, v102
	v_fma_f32 v81, v81, v191, v103
	v_cvt_pk_bf16_f32 v102, v78, v79
	v_addc_co_u32_e32 v131, vcc, 0, v179, vcc
	v_cvt_pk_bf16_f32 v103, v80, v81
	v_fma_f32 v76, v76, v184, v104
	v_fma_f32 v77, v77, v185, v105
	v_fma_f32 v74, v74, v186, v132
	v_fma_f32 v75, v75, v187, v133
	v_lshlrev_b32_e32 v132, 16, v101
	v_cvt_pk_bf16_f32 v104, v74, v75
	v_cvt_pk_bf16_f32 v105, v76, v77
	global_store_dwordx4 v[130:131], v[102:105], off
	v_and_b32_e32 v133, 0xffff0000, v101
	s_nop 0
	v_mul_f32_e32 v102, v79, v79
	v_mul_f32_e32 v103, v81, v81
	v_fmac_f32_e32 v102, v78, v78
	v_fmac_f32_e32 v103, v80, v80
	v_add_f32_e32 v102, v102, v103
	v_mul_f32_e32 v103, v75, v75
	v_mul_f32_e32 v104, v77, v77
	v_fmac_f32_e32 v103, v74, v74
	v_fmac_f32_e32 v104, v76, v76
	v_add_f32_e32 v103, v103, v104
	v_add_f32_e32 v154, v102, v103
	v_lshlrev_b32_e32 v102, 16, v98
	v_and_b32_e32 v103, 0xffff0000, v98
	v_lshlrev_b32_e32 v98, 16, v99
	v_and_b32_e32 v99, 0xffff0000, v99
	v_lshlrev_b32_e32 v104, 16, v100
	v_and_b32_e32 v105, 0xffff0000, v100
	v_fma_f32 v98, v72, v182, v98
	v_fma_f32 v99, v73, v183, v99
	v_fma_f32 v100, v70, v180, v102
	v_fma_f32 v101, v71, v181, v103
	v_fma_f32 v104, v66, v152, v104
	v_fma_f32 v105, v67, v153, v105
	v_cvt_pk_bf16_f32 v66, v100, v101
	v_cvt_pk_bf16_f32 v67, v98, v99
	v_fma_f32 v102, v68, v150, v132
	v_fma_f32 v103, v69, v151, v133
	v_cvt_pk_bf16_f32 v68, v104, v105
	s_nop 0
	v_cvt_pk_bf16_f32 v69, v102, v103
	global_store_dwordx4 v[130:131], v[66:69], off offset:256
	s_nop 1
	v_mul_f32_e32 v66, v101, v101
	v_mul_f32_e32 v67, v99, v99
	v_fmac_f32_e32 v66, v100, v100
	v_fmac_f32_e32 v67, v98, v98
	v_add_f32_e32 v66, v66, v67
	v_mul_f32_e32 v67, v105, v105
	v_mul_f32_e32 v68, v103, v103
	v_fmac_f32_e32 v67, v104, v104
	v_fmac_f32_e32 v68, v102, v102
	v_add_f32_e32 v67, v67, v68
	v_add_f32_e32 v66, v66, v67
	v_add_f32_e32 v66, v154, v66
	ds_bpermute_b32 v67, v195, v66
	s_waitcnt lgkmcnt(0)
	v_add_f32_e32 v66, v66, v67
	ds_bpermute_b32 v67, v196, v66
	s_and_saveexec_b64 s[42:43], s[12:13]
	s_cbranch_execz .LBB0_323
	s_waitcnt lgkmcnt(0)
	v_add_f32_e32 v66, v66, v67
	ds_write_b32 v205, v66 offset:768

.LBB0_329:
	s_waitcnt vmcnt(2)
	v_lshlrev_b32_e32 v130, 16, v86
	v_and_b32_e32 v131, 0xffff0000, v86
	s_mov_b32 s37, 0x40000
	v_lshlrev_b32_e32 v86, 16, v87
	v_and_b32_e32 v87, 0xffff0000, v87
	v_fma_f32 v62, v62, v188, v130
	v_fma_f32 v63, v63, v189, v131
	v_add_co_u32_e32 v130, vcc, s37, v178
	v_lshlrev_b32_e32 v132, 16, v88
	v_and_b32_e32 v133, 0xffff0000, v88
	v_lshlrev_b32_e32 v88, 16, v89
	v_and_b32_e32 v89, 0xffff0000, v89
	v_fma_f32 v64, v64, v190, v86
	v_fma_f32 v65, v65, v191, v87
	v_cvt_pk_bf16_f32 v86, v62, v63
	v_addc_co_u32_e32 v131, vcc, 0, v179, vcc
	v_cvt_pk_bf16_f32 v87, v64, v65
	v_fma_f32 v60, v60, v184, v88
	v_fma_f32 v61, v61, v185, v89
	v_fma_f32 v58, v58, v186, v132
	v_fma_f32 v59, v59, v187, v133
	v_lshlrev_b32_e32 v132, 16, v85
	v_cvt_pk_bf16_f32 v88, v58, v59
	v_cvt_pk_bf16_f32 v89, v60, v61
	global_store_dwordx4 v[130:131], v[86:89], off
	v_and_b32_e32 v133, 0xffff0000, v85
	s_nop 0
	v_mul_f32_e32 v86, v63, v63
	v_mul_f32_e32 v87, v65, v65
	v_fmac_f32_e32 v86, v62, v62
	v_fmac_f32_e32 v87, v64, v64
	v_add_f32_e32 v86, v86, v87
	v_mul_f32_e32 v87, v59, v59
	v_mul_f32_e32 v88, v61, v61
	v_fmac_f32_e32 v87, v58, v58
	v_fmac_f32_e32 v88, v60, v60
	v_add_f32_e32 v87, v87, v88
	v_add_f32_e32 v154, v86, v87
	v_lshlrev_b32_e32 v86, 16, v82
	v_and_b32_e32 v87, 0xffff0000, v82
	v_lshlrev_b32_e32 v82, 16, v83
	v_and_b32_e32 v83, 0xffff0000, v83
	v_lshlrev_b32_e32 v88, 16, v84
	v_and_b32_e32 v89, 0xffff0000, v84
	v_fma_f32 v82, v56, v182, v82
	v_fma_f32 v83, v57, v183, v83
	v_fma_f32 v84, v54, v180, v86
	v_fma_f32 v85, v55, v181, v87
	v_fma_f32 v88, v50, v152, v88
	v_fma_f32 v89, v51, v153, v89
	v_cvt_pk_bf16_f32 v50, v84, v85
	v_cvt_pk_bf16_f32 v51, v82, v83
	v_fma_f32 v86, v52, v150, v132
	v_fma_f32 v87, v53, v151, v133
	v_cvt_pk_bf16_f32 v52, v88, v89
	s_nop 0
	v_cvt_pk_bf16_f32 v53, v86, v87
	global_store_dwordx4 v[130:131], v[50:53], off offset:256
	s_nop 1
	v_mul_f32_e32 v50, v85, v85
	v_mul_f32_e32 v51, v83, v83
	v_fmac_f32_e32 v50, v84, v84
	v_fmac_f32_e32 v51, v82, v82
	v_add_f32_e32 v50, v50, v51
	v_mul_f32_e32 v51, v89, v89
	v_mul_f32_e32 v52, v87, v87
	v_fmac_f32_e32 v51, v88, v88
	v_fmac_f32_e32 v52, v86, v86
	v_add_f32_e32 v51, v51, v52
	v_add_f32_e32 v50, v50, v51
	v_add_f32_e32 v50, v154, v50
	ds_bpermute_b32 v51, v195, v50
	s_waitcnt lgkmcnt(0)
	v_add_f32_e32 v50, v50, v51
	ds_bpermute_b32 v51, v196, v50
	s_and_saveexec_b64 s[42:43], s[12:13]
	s_cbranch_execz .LBB0_331
	s_waitcnt lgkmcnt(0)
	v_add_f32_e32 v50, v50, v51
	ds_write_b32 v200, v50

.LBB0_337:
	s_waitcnt vmcnt(2)
	v_lshlrev_b32_e32 v130, 16, v70
	v_and_b32_e32 v131, 0xffff0000, v70
	s_mov_b32 s37, 0x48000
	v_lshlrev_b32_e32 v70, 16, v71
	v_and_b32_e32 v71, 0xffff0000, v71
	v_fma_f32 v46, v46, v188, v130
	v_fma_f32 v47, v47, v189, v131
	v_add_co_u32_e32 v130, vcc, s37, v178
	v_lshlrev_b32_e32 v132, 16, v72
	v_and_b32_e32 v133, 0xffff0000, v72
	v_lshlrev_b32_e32 v72, 16, v73
	v_and_b32_e32 v73, 0xffff0000, v73
	v_fma_f32 v48, v48, v190, v70
	v_fma_f32 v49, v49, v191, v71
	v_cvt_pk_bf16_f32 v70, v46, v47
	v_addc_co_u32_e32 v131, vcc, 0, v179, vcc
	v_cvt_pk_bf16_f32 v71, v48, v49
	v_fma_f32 v44, v44, v184, v72
	v_fma_f32 v45, v45, v185, v73
	v_fma_f32 v42, v42, v186, v132
	v_fma_f32 v43, v43, v187, v133
	v_lshlrev_b32_e32 v132, 16, v69
	v_cvt_pk_bf16_f32 v72, v42, v43
	v_cvt_pk_bf16_f32 v73, v44, v45
	global_store_dwordx4 v[130:131], v[70:73], off
	v_and_b32_e32 v133, 0xffff0000, v69
	s_nop 0
	v_mul_f32_e32 v70, v47, v47
	v_mul_f32_e32 v71, v49, v49
	v_fmac_f32_e32 v70, v46, v46
	v_fmac_f32_e32 v71, v48, v48
	v_add_f32_e32 v70, v70, v71
	v_mul_f32_e32 v71, v43, v43
	v_mul_f32_e32 v72, v45, v45
	v_fmac_f32_e32 v71, v42, v42
	v_fmac_f32_e32 v72, v44, v44
	v_add_f32_e32 v71, v71, v72
	v_add_f32_e32 v154, v70, v71
	v_lshlrev_b32_e32 v70, 16, v66
	v_and_b32_e32 v71, 0xffff0000, v66
	v_lshlrev_b32_e32 v66, 16, v67
	v_and_b32_e32 v67, 0xffff0000, v67
	v_lshlrev_b32_e32 v72, 16, v68
	v_and_b32_e32 v73, 0xffff0000, v68
	v_fma_f32 v66, v40, v182, v66
	v_fma_f32 v67, v41, v183, v67
	v_fma_f32 v68, v38, v180, v70
	v_fma_f32 v69, v39, v181, v71
	v_fma_f32 v72, v34, v152, v72
	v_fma_f32 v73, v35, v153, v73
	v_cvt_pk_bf16_f32 v34, v68, v69
	v_cvt_pk_bf16_f32 v35, v66, v67
	v_fma_f32 v70, v36, v150, v132
	v_fma_f32 v71, v37, v151, v133
	v_cvt_pk_bf16_f32 v36, v72, v73
	s_nop 0
	v_cvt_pk_bf16_f32 v37, v70, v71
	global_store_dwordx4 v[130:131], v[34:37], off offset:256
	s_nop 1
	v_mul_f32_e32 v34, v69, v69
	v_mul_f32_e32 v35, v67, v67
	v_fmac_f32_e32 v34, v68, v68
	v_fmac_f32_e32 v35, v66, v66
	v_add_f32_e32 v34, v34, v35
	v_mul_f32_e32 v35, v73, v73
	v_mul_f32_e32 v36, v71, v71
	v_fmac_f32_e32 v35, v72, v72
	v_fmac_f32_e32 v36, v70, v70
	v_add_f32_e32 v35, v35, v36
	v_add_f32_e32 v34, v34, v35
	v_add_f32_e32 v34, v154, v34
	ds_bpermute_b32 v35, v195, v34
	s_waitcnt lgkmcnt(0)
	v_add_f32_e32 v34, v34, v35
	ds_bpermute_b32 v35, v196, v34
	s_and_saveexec_b64 s[42:43], s[12:13]
	s_cbranch_execz .LBB0_339
	s_waitcnt lgkmcnt(0)
	v_add_f32_e32 v34, v34, v35
	ds_write_b32 v201, v34

.LBB0_361:
	s_waitcnt vmcnt(2)
	v_lshlrev_b32_e32 v130, 16, v54
	v_and_b32_e32 v131, 0xffff0000, v54
	s_mov_b32 s10, 0x50000
	v_lshlrev_b32_e32 v54, 16, v55
	v_and_b32_e32 v55, 0xffff0000, v55
	v_fma_f32 v30, v30, v188, v130
	v_fma_f32 v31, v31, v189, v131
	v_add_co_u32_e32 v130, vcc, s10, v178
	v_lshlrev_b32_e32 v132, 16, v56
	v_and_b32_e32 v133, 0xffff0000, v56
	v_lshlrev_b32_e32 v56, 16, v57
	v_and_b32_e32 v57, 0xffff0000, v57
	v_fma_f32 v32, v32, v190, v54
	v_fma_f32 v33, v33, v191, v55
	v_cvt_pk_bf16_f32 v54, v30, v31
	v_addc_co_u32_e32 v131, vcc, 0, v179, vcc
	v_cvt_pk_bf16_f32 v55, v32, v33
	v_fma_f32 v28, v28, v184, v56
	v_fma_f32 v29, v29, v185, v57
	v_fma_f32 v26, v26, v186, v132
	v_fma_f32 v27, v27, v187, v133
	s_nop 0
	v_cvt_pk_bf16_f32 v56, v26, v27
	v_cvt_pk_bf16_f32 v57, v28, v29
	global_store_dwordx4 v[130:131], v[54:57], off
	s_nop 1
	v_mul_f32_e32 v54, v31, v31
	v_mul_f32_e32 v55, v33, v33
	v_fmac_f32_e32 v54, v30, v30
	v_fmac_f32_e32 v55, v32, v32
	v_add_f32_e32 v54, v54, v55
	v_mul_f32_e32 v55, v27, v27
	v_mul_f32_e32 v56, v29, v29
	v_fmac_f32_e32 v55, v26, v26
	v_fmac_f32_e32 v56, v28, v28
	v_add_f32_e32 v55, v55, v56
	v_add_f32_e32 v132, v54, v55
	v_lshlrev_b32_e32 v54, 16, v50
	v_and_b32_e32 v55, 0xffff0000, v50
	v_lshlrev_b32_e32 v50, 16, v51
	v_and_b32_e32 v51, 0xffff0000, v51
	v_lshlrev_b32_e32 v56, 16, v52
	v_and_b32_e32 v57, 0xffff0000, v52
	v_lshlrev_b32_e32 v52, 16, v53
	v_and_b32_e32 v53, 0xffff0000, v53
	v_fma_f32 v24, v24, v182, v50
	v_fma_f32 v25, v25, v183, v51
	v_fma_f32 v22, v22, v180, v54
	v_fma_f32 v23, v23, v181, v55
	v_fma_f32 v20, v20, v150, v52
	v_fma_f32 v21, v21, v151, v53
	v_cvt_pk_bf16_f32 v50, v22, v23
	v_cvt_pk_bf16_f32 v51, v24, v25
	v_fma_f32 v18, v18, v152, v56
	v_fma_f32 v19, v19, v153, v57
	s_nop 0
	v_cvt_pk_bf16_f32 v52, v18, v19
	v_cvt_pk_bf16_f32 v53, v20, v21
	global_store_dwordx4 v[130:131], v[50:53], off offset:256
	s_nop 1
	v_mul_f32_e32 v50, v23, v23
	v_mul_f32_e32 v51, v25, v25
	v_fmac_f32_e32 v50, v22, v22
	v_fmac_f32_e32 v51, v24, v24
	v_add_f32_e32 v50, v50, v51
	v_mul_f32_e32 v51, v19, v19
	v_mul_f32_e32 v52, v21, v21
	v_fmac_f32_e32 v51, v18, v18
	v_fmac_f32_e32 v52, v20, v20
	v_add_f32_e32 v51, v51, v52
	v_add_f32_e32 v50, v50, v51
	v_add_f32_e32 v50, v132, v50
	ds_bpermute_b32 v51, v195, v50
	s_waitcnt lgkmcnt(0)
	v_add_f32_e32 v50, v50, v51
	ds_bpermute_b32 v51, v196, v50
	s_and_saveexec_b64 s[10:11], s[12:13]
	s_cbranch_execz .LBB0_363
	s_waitcnt lgkmcnt(0)
	v_add_f32_e32 v50, v50, v51
	ds_write_b32 v202, v50
.LBB0_363:
	s_or_b64 exec, exec, s[10:11]
	s_waitcnt vmcnt(2)
	v_lshlrev_b32_e32 v50, 16, v34
	s_waitcnt lgkmcnt(0)
	v_and_b32_e32 v51, 0xffff0000, v34
	v_lshlrev_b32_e32 v34, 16, v35
	v_and_b32_e32 v35, 0xffff0000, v35
	v_lshlrev_b32_e32 v52, 16, v36
	v_and_b32_e32 v53, 0xffff0000, v36
	v_lshlrev_b32_e32 v54, 16, v37
	v_and_b32_e32 v55, 0xffff0000, v37
	v_fma_f32 v34, v16, v190, v34
	v_fma_f32 v35, v17, v191, v35
	v_fma_f32 v36, v14, v188, v50
	v_fma_f32 v37, v15, v189, v51
	v_mul_f32_e32 v15, v35, v35
	v_mul_f32_e32 v14, v37, v37
	v_fma_f32 v50, v12, v184, v54
	v_fma_f32 v51, v13, v185, v55
	v_fma_f32 v52, v10, v186, v52
	v_fma_f32 v53, v11, v187, v53
	v_fmac_f32_e32 v14, v36, v36
	v_fmac_f32_e32 v15, v34, v34
	v_add_f32_e32 v14, v14, v15
	v_mul_f32_e32 v15, v53, v53
	v_mul_f32_e32 v16, v51, v51
	v_fmac_f32_e32 v15, v52, v52
	v_fmac_f32_e32 v16, v50, v50
	v_add_f32_e32 v15, v15, v16
	v_add_f32_e32 v130, v14, v15
	v_lshlrev_b32_e32 v14, 16, v38
	v_and_b32_e32 v15, 0xffff0000, v38
	v_lshlrev_b32_e32 v16, 16, v39
	v_and_b32_e32 v17, 0xffff0000, v39
	v_lshlrev_b32_e32 v56, 16, v40
	v_and_b32_e32 v57, 0xffff0000, v40
	v_lshlrev_b32_e32 v54, 16, v41
	v_and_b32_e32 v55, 0xffff0000, v41
	v_fma_f32 v38, v8, v182, v16
	v_fma_f32 v39, v9, v183, v17
	v_fma_f32 v40, v6, v180, v14
	v_fma_f32 v41, v7, v181, v15
	v_fma_f32 v56, v2, v152, v56
	v_fma_f32 v57, v3, v153, v57
	v_mul_f32_e32 v2, v41, v41
	v_mul_f32_e32 v3, v39, v39
	v_fma_f32 v54, v4, v150, v54
	v_fma_f32 v55, v5, v151, v55
	v_fmac_f32_e32 v2, v40, v40
	v_fmac_f32_e32 v3, v38, v38
	v_add_f32_e32 v2, v2, v3
	v_mul_f32_e32 v3, v57, v57
	v_mul_f32_e32 v4, v55, v55
	v_fmac_f32_e32 v3, v56, v56
	v_fmac_f32_e32 v4, v54, v54
	v_add_f32_e32 v3, v3, v4
	v_add_f32_e32 v2, v2, v3
	v_add_f32_e32 v2, v130, v2
	ds_bpermute_b32 v3, v195, v2
	s_mov_b32 s10, 0x58000
	v_add_co_u32_e32 v8, vcc, s10, v178
	s_waitcnt lgkmcnt(0)
	v_add_f32_e32 v2, v2, v3
	ds_bpermute_b32 v3, v196, v2
	v_addc_co_u32_e32 v9, vcc, 0, v179, vcc
	v_cvt_pk_bf16_f32 v10, v36, v37
	v_cvt_pk_bf16_f32 v11, v34, v35
	v_cvt_pk_bf16_f32 v12, v52, v53
	v_cvt_pk_bf16_f32 v13, v50, v51
	global_store_dwordx4 v[8:9], v[10:13], off
	v_cvt_pk_bf16_f32 v4, v40, v41
	v_cvt_pk_bf16_f32 v5, v38, v39
	v_cvt_pk_bf16_f32 v6, v56, v57
	v_cvt_pk_bf16_f32 v7, v54, v55
	global_store_dwordx4 v[8:9], v[4:7], off offset:256
	s_and_saveexec_b64 s[10:11], s[12:13]
	s_cbranch_execz .LBB0_365
	s_waitcnt lgkmcnt(0)
	v_add_f32_e32 v2, v2, v3
	ds_write_b32 v203, v2
.LBB0_365:
	s_or_b64 exec, exec, s[10:11]
	s_waitcnt lgkmcnt(0)
	s_barrier
	s_ashr_i32 s39, s38, 31
	s_waitcnt lgkmcnt(0)
	v_lshl_add_u64 v[2:3], v[168:169], 0, s[38:39]
	v_lshl_add_u64 v[2:3], v[2:3], 4, s[26:27]
	s_and_saveexec_b64 s[10:11], s[4:5]
	s_cbranch_execz .LBB0_367
	ds_read_b128 v[4:7], v204
	s_ashr_i32 s37, s36, 31
	v_lshl_add_u64 v[8:9], s[36:37], 2, v[2:3]
	s_waitcnt lgkmcnt(0)
	v_mov_b32_e32 v10, v5
	v_mov_b32_e32 v11, v6
	v_mov_b32_e32 v5, v7
	v_add_f32_e32 v4, v10, v4
	v_add_f32_e32 v5, v11, v5
	s_nop 0
	v_pk_add_f32 v[4:5], v[4:5], v[4:5] op_sel:[0,1] op_sel_hi:[1,0]
	global_store_dword v[8:9], v4, off sc1

.LBB0_383:
	s_or_b64 exec, exec, s[10:11]
	v_lshlrev_b64 v[2:3], 2, v[176:177]
	v_lshl_add_u64 v[158:159], s[0:1], 0, v[2:3]
	s_mov_b64 s[0:1], 0x3000
	v_lshl_add_u64 v[184:185], v[158:159], 0, s[0:1]
	s_mov_b64 s[0:1], 0x4000
	v_lshl_add_u64 v[160:161], s[18:19], 0, v[2:3]
	v_lshl_add_u64 v[2:3], v[158:159], 0, s[0:1]
	s_movk_i32 s0, 0x4000
	v_add_co_u32_e32 v180, vcc, s0, v158
	s_waitcnt vmcnt(0) lgkmcnt(0)
	s_barrier
	global_load_dwordx4 v[10:13], v[160:161], off offset:16
	global_load_dwordx4 v[14:17], v[160:161], off
	v_addc_co_u32_e32 v181, vcc, 0, v159, vcc
	global_load_dwordx4 v[130:133], v[180:181], off
	global_load_dwordx4 v[154:157], v[2:3], off offset:16
	s_movk_i32 s0, 0x3000
	v_add_co_u32_e32 v2, vcc, s0, v158
	s_mov_b64 s[0:1], 0x4200
	s_nop 0
	v_addc_co_u32_e32 v3, vcc, 0, v159, vcc
	global_load_dwordx4 v[6:9], v[2:3], off
	s_nop 0
	global_load_dwordx4 v[2:5], v[184:185], off offset:16
	v_lshl_add_u64 v[174:175], v[174:175], 1, s[28:29]
	s_waitcnt vmcnt(3)
	v_add_f32_e32 v132, 1.0, v132
	v_add_f32_e32 v133, 1.0, v133
	v_add_f32_e32 v130, 1.0, v130
	v_add_f32_e32 v131, 1.0, v131
	v_mul_f32_e32 v150, v16, v132
	v_mul_f32_e32 v151, v17, v133
	s_waitcnt vmcnt(2)
	v_add_f32_e32 v16, 1.0, v154
	v_add_f32_e32 v17, 1.0, v155
	v_mul_f32_e32 v152, v14, v130
	v_mul_f32_e32 v153, v15, v131
	v_add_f32_e32 v14, 1.0, v156
	v_add_f32_e32 v15, 1.0, v157
	v_mul_f32_e32 v132, v10, v16
	v_mul_f32_e32 v133, v11, v17
	v_lshl_add_u64 v[10:11], v[158:159], 0, s[0:1]
	v_mul_f32_e32 v130, v12, v14
	v_mul_f32_e32 v131, v13, v15
	global_load_dwordx4 v[176:179], v[160:161], off offset:528
	global_load_dwordx4 v[154:157], v[160:161], off offset:512
	s_nop 0
	global_load_dwordx4 v[158:161], v[180:181], off offset:512
	s_nop 0
	global_load_dwordx4 v[180:183], v[10:11], off offset:16
	s_nop 0
	global_load_dwordx4 v[10:13], v[184:185], off offset:528
	global_load_dwordx4 v[14:17], v[184:185], off offset:512
	s_mov_b32 s0, 0x10000
	s_waitcnt vmcnt(3)
	v_add_f32_e32 v160, 1.0, v160
	v_add_f32_e32 v161, 1.0, v161
	v_add_f32_e32 v184, 1.0, v158
	v_add_f32_e32 v185, 1.0, v159
	v_mul_f32_e32 v158, v156, v160
	v_mul_f32_e32 v159, v157, v161
	s_waitcnt vmcnt(2)
	v_add_f32_e32 v156, 1.0, v180
	v_add_f32_e32 v157, 1.0, v181
	v_mul_f32_e32 v160, v154, v184
	v_mul_f32_e32 v161, v155, v185
	v_mul_f32_e32 v156, v176, v156
	v_mul_f32_e32 v157, v177, v157
	ds_read_b32 v176, v198
	v_add_f32_e32 v154, 1.0, v182
	v_add_f32_e32 v155, 1.0, v183
	s_waitcnt lgkmcnt(0)
	v_mul_f32_e32 v142, v142, v176
	v_mul_f32_e32 v143, v143, v176
	v_mul_f32_e32 v144, v144, v176
	v_mul_f32_e32 v145, v145, v176
	v_mul_f32_e32 v138, v138, v176
	v_mul_f32_e32 v139, v139, v176
	v_mul_f32_e32 v140, v140, v176
	v_mul_f32_e32 v141, v141, v176
	v_mul_f32_e32 v124, v124, v176
	v_mul_f32_e32 v125, v125, v176
	v_mul_f32_e32 v154, v178, v154
	v_mul_f32_e32 v155, v179, v155
	v_fma_f32 v142, v150, v142, v8
	v_fma_f32 v143, v151, v143, v9
	v_fma_f32 v144, v152, v144, v6
	v_fma_f32 v145, v153, v145, v7
	v_fma_f32 v178, v130, v138, v4
	v_fma_f32 v179, v131, v139, v5
	v_fma_f32 v140, v132, v140, v2
	v_fma_f32 v141, v133, v141, v3
	v_cvt_pk_bf16_f32 v138, v144, v145
	v_cvt_pk_bf16_f32 v139, v142, v143
	v_mul_f32_e32 v126, v126, v176
	v_mul_f32_e32 v127, v127, v176
	v_mul_f32_e32 v128, v128, v176
	v_mul_f32_e32 v129, v129, v176
	v_mul_f32_e32 v122, v122, v176
	v_mul_f32_e32 v123, v123, v176
	s_waitcnt vmcnt(1)
	v_fma_f32 v124, v156, v124, v10
	v_fma_f32 v125, v157, v125, v11
	v_cvt_pk_bf16_f32 v140, v140, v141
	v_cvt_pk_bf16_f32 v141, v178, v179
	global_store_dwordx4 v[174:175], v[138:141], off
	s_waitcnt vmcnt(1)
	v_fma_f32 v126, v158, v126, v16
	v_fma_f32 v127, v159, v127, v17
	v_fma_f32 v128, v160, v128, v14
	v_fma_f32 v129, v161, v129, v15
	v_fma_f32 v138, v154, v122, v12
	v_fma_f32 v139, v155, v123, v13
	v_cvt_pk_bf16_f32 v122, v128, v129
	v_cvt_pk_bf16_f32 v123, v126, v127
	v_cvt_pk_bf16_f32 v124, v124, v125
	s_nop 0
	v_cvt_pk_bf16_f32 v125, v138, v139
	global_store_dwordx4 v[174:175], v[122:125], off offset:256
	ds_read_b32 v126, v198 offset:64
	s_waitcnt lgkmcnt(0)
	v_mul_f32_e32 v108, v108, v126
	v_mul_f32_e32 v109, v109, v126
	v_mul_f32_e32 v122, v134, v126
	v_mul_f32_e32 v123, v135, v126
	v_mul_f32_e32 v124, v136, v126
	v_mul_f32_e32 v125, v137, v126
	v_fma_f32 v128, v150, v122, v8
	v_fma_f32 v129, v151, v123, v9
	v_fma_f32 v122, v152, v124, v6
	v_fma_f32 v123, v153, v125, v7
	v_mul_f32_e32 v124, v146, v126
	v_mul_f32_e32 v125, v147, v126
	v_mul_f32_e32 v134, v148, v126
	v_mul_f32_e32 v135, v149, v126
	v_cvt_pk_bf16_f32 v122, v122, v123
	v_cvt_pk_bf16_f32 v123, v128, v129
	v_add_co_u32_e32 v128, vcc, s75, v174
	v_fma_f32 v136, v130, v124, v4
	v_fma_f32 v137, v131, v125, v5
	v_fma_f32 v124, v132, v134, v2
	v_fma_f32 v125, v133, v135, v3
	v_addc_co_u32_e32 v129, vcc, 0, v175, vcc
	v_mul_f32_e32 v112, v112, v126
	v_mul_f32_e32 v113, v113, v126
	v_fma_f32 v108, v158, v108, v16
	v_fma_f32 v109, v159, v109, v17
	v_mul_f32_e32 v106, v106, v126
	v_mul_f32_e32 v107, v107, v126
	v_mul_f32_e32 v110, v110, v126
	v_mul_f32_e32 v111, v111, v126
	v_cvt_pk_bf16_f32 v124, v124, v125
	v_cvt_pk_bf16_f32 v125, v136, v137
	global_store_dwordx4 v[128:129], v[122:125], off
	v_fma_f32 v112, v160, v112, v14
	v_fma_f32 v113, v161, v113, v15
	v_fma_f32 v110, v156, v110, v10
	v_fma_f32 v111, v157, v111, v11
	v_fma_f32 v122, v154, v106, v12
	v_fma_f32 v123, v155, v107, v13
	v_cvt_pk_bf16_f32 v106, v112, v113
	v_cvt_pk_bf16_f32 v107, v108, v109
	v_cvt_pk_bf16_f32 v108, v110, v111
	s_nop 0
	v_cvt_pk_bf16_f32 v109, v122, v123
	global_store_dwordx4 v[128:129], v[106:109], off offset:256
	ds_read_b32 v106, v198 offset:128
	s_waitcnt lgkmcnt(0)
	v_mul_f32_e32 v94, v94, v106
	v_mul_f32_e32 v95, v95, v106
	s_nop 0
	v_fma_f32 v94, v152, v94, v6
	v_fma_f32 v95, v153, v95, v7
	v_mul_f32_e32 v92, v92, v106
	v_mul_f32_e32 v93, v93, v106
	v_mul_f32_e32 v90, v90, v106
	v_mul_f32_e32 v91, v91, v106
	v_mul_f32_e32 v96, v96, v106
	v_mul_f32_e32 v97, v97, v106
	v_fma_f32 v108, v130, v92, v4
	v_fma_f32 v109, v131, v93, v5
	v_fma_f32 v92, v132, v90, v2
	v_fma_f32 v93, v133, v91, v3
	v_cvt_pk_bf16_f32 v90, v94, v95
	v_add_co_u32_e32 v94, vcc, s0, v174
	v_fma_f32 v96, v150, v96, v8
	v_fma_f32 v97, v151, v97, v9
	s_nop 0
	v_addc_co_u32_e32 v95, vcc, 0, v175, vcc
	v_cvt_pk_bf16_f32 v91, v96, v97
	v_cvt_pk_bf16_f32 v92, v92, v93
	v_cvt_pk_bf16_f32 v93, v108, v109
	global_store_dwordx4 v[94:95], v[90:93], off
	s_mov_b32 s0, 0x18000
	s_nop 0
	v_mul_f32_e32 v90, v114, v106
	v_mul_f32_e32 v91, v115, v106
	v_mul_f32_e32 v92, v116, v106
	v_mul_f32_e32 v93, v117, v106
	v_fma_f32 v96, v158, v90, v16
	v_fma_f32 v97, v159, v91, v17
	v_fma_f32 v90, v160, v92, v14
	v_fma_f32 v91, v161, v93, v15
	v_mul_f32_e32 v92, v118, v106
	v_mul_f32_e32 v93, v119, v106
	v_mul_f32_e32 v107, v121, v106
	v_mul_f32_e32 v106, v120, v106
	v_fma_f32 v108, v154, v92, v12
	v_fma_f32 v109, v155, v93, v13
	v_fma_f32 v92, v156, v106, v10
	v_fma_f32 v93, v157, v107, v11
	v_cvt_pk_bf16_f32 v90, v90, v91
	v_cvt_pk_bf16_f32 v91, v96, v97
	s_nop 0
	v_cvt_pk_bf16_f32 v92, v92, v93
	v_cvt_pk_bf16_f32 v93, v108, v109
	global_store_dwordx4 v[94:95], v[90:93], off offset:256
	ds_read_b32 v90, v198 offset:192
	s_waitcnt lgkmcnt(0)
	v_mul_f32_e32 v78, v78, v90
	v_mul_f32_e32 v79, v79, v90
	s_nop 0
	v_fma_f32 v78, v152, v78, v6
	v_fma_f32 v79, v153, v79, v7
	v_mul_f32_e32 v76, v76, v90
	v_mul_f32_e32 v77, v77, v90
	v_mul_f32_e32 v74, v74, v90
	v_mul_f32_e32 v75, v75, v90
	v_mul_f32_e32 v80, v80, v90
	v_mul_f32_e32 v81, v81, v90
	v_fma_f32 v92, v130, v76, v4
	v_fma_f32 v93, v131, v77, v5
	v_fma_f32 v76, v132, v74, v2
	v_fma_f32 v77, v133, v75, v3
	v_cvt_pk_bf16_f32 v74, v78, v79
	v_add_co_u32_e32 v78, vcc, s0, v174
	v_fma_f32 v80, v150, v80, v8
	v_fma_f32 v81, v151, v81, v9
	s_nop 0
	v_addc_co_u32_e32 v79, vcc, 0, v175, vcc
	v_cvt_pk_bf16_f32 v75, v80, v81
	v_cvt_pk_bf16_f32 v76, v76, v77
	v_cvt_pk_bf16_f32 v77, v92, v93
	global_store_dwordx4 v[78:79], v[74:77], off
	s_mov_b32 s0, 0x40000
	s_nop 0
	v_mul_f32_e32 v74, v98, v90
	v_mul_f32_e32 v75, v99, v90
	v_mul_f32_e32 v76, v100, v90
	v_mul_f32_e32 v77, v101, v90
	v_fma_f32 v80, v158, v74, v16
	v_fma_f32 v81, v159, v75, v17
	v_fma_f32 v74, v160, v76, v14
	v_fma_f32 v75, v161, v77, v15
	v_mul_f32_e32 v76, v102, v90
	v_mul_f32_e32 v77, v103, v90
	v_mul_f32_e32 v91, v105, v90
	v_mul_f32_e32 v90, v104, v90
	v_fma_f32 v92, v154, v76, v12
	v_fma_f32 v93, v155, v77, v13
	v_fma_f32 v76, v156, v90, v10
	v_fma_f32 v77, v157, v91, v11
	v_cvt_pk_bf16_f32 v74, v74, v75
	v_cvt_pk_bf16_f32 v75, v80, v81
	s_nop 0
	v_cvt_pk_bf16_f32 v76, v76, v77
	v_cvt_pk_bf16_f32 v77, v92, v93
	global_store_dwordx4 v[78:79], v[74:77], off offset:256
	ds_read_b32 v74, v198 offset:512
	s_waitcnt lgkmcnt(0)
	v_mul_f32_e32 v62, v62, v74
	v_mul_f32_e32 v63, v63, v74
	s_nop 0
	v_fma_f32 v62, v152, v62, v6
	v_fma_f32 v63, v153, v63, v7
	v_mul_f32_e32 v60, v60, v74
	v_mul_f32_e32 v61, v61, v74
	v_mul_f32_e32 v58, v58, v74
	v_mul_f32_e32 v59, v59, v74
	v_mul_f32_e32 v64, v64, v74
	v_mul_f32_e32 v65, v65, v74
	v_fma_f32 v76, v130, v60, v4
	v_fma_f32 v77, v131, v61, v5
	v_fma_f32 v60, v132, v58, v2
	v_fma_f32 v61, v133, v59, v3
	v_cvt_pk_bf16_f32 v58, v62, v63
	v_add_co_u32_e32 v62, vcc, s0, v174
	v_fma_f32 v64, v150, v64, v8
	v_fma_f32 v65, v151, v65, v9
	s_nop 0
	v_addc_co_u32_e32 v63, vcc, 0, v175, vcc
	v_cvt_pk_bf16_f32 v59, v64, v65
	v_cvt_pk_bf16_f32 v60, v60, v61
	v_cvt_pk_bf16_f32 v61, v76, v77
	global_store_dwordx4 v[62:63], v[58:61], off
	s_mov_b32 s0, 0x48000
	s_nop 0
	v_mul_f32_e32 v58, v82, v74
	v_mul_f32_e32 v59, v83, v74
	v_mul_f32_e32 v60, v84, v74
	v_mul_f32_e32 v61, v85, v74
	v_fma_f32 v64, v158, v58, v16
	v_fma_f32 v65, v159, v59, v17
	v_fma_f32 v58, v160, v60, v14
	v_fma_f32 v59, v161, v61, v15
	v_mul_f32_e32 v60, v86, v74
	v_mul_f32_e32 v61, v87, v74
	v_mul_f32_e32 v75, v89, v74
	v_mul_f32_e32 v74, v88, v74
	v_fma_f32 v76, v154, v60, v12
	v_fma_f32 v77, v155, v61, v13
	v_fma_f32 v60, v156, v74, v10
	v_fma_f32 v61, v157, v75, v11
	v_cvt_pk_bf16_f32 v58, v58, v59
	v_cvt_pk_bf16_f32 v59, v64, v65
	s_nop 0
	v_cvt_pk_bf16_f32 v60, v60, v61
	v_cvt_pk_bf16_f32 v61, v76, v77
	global_store_dwordx4 v[62:63], v[58:61], off offset:256
	ds_read_b32 v58, v198 offset:576
	s_waitcnt lgkmcnt(0)
	v_mul_f32_e32 v46, v46, v58
	v_mul_f32_e32 v47, v47, v58
	s_nop 0
	v_fma_f32 v46, v152, v46, v6
	v_fma_f32 v47, v153, v47, v7
	v_mul_f32_e32 v44, v44, v58
	v_mul_f32_e32 v45, v45, v58
	v_mul_f32_e32 v42, v42, v58
	v_mul_f32_e32 v43, v43, v58
	v_mul_f32_e32 v48, v48, v58
	v_mul_f32_e32 v49, v49, v58
	v_fma_f32 v60, v130, v44, v4
	v_fma_f32 v61, v131, v45, v5
	v_fma_f32 v44, v132, v42, v2
	v_fma_f32 v45, v133, v43, v3
	v_cvt_pk_bf16_f32 v42, v46, v47
	v_add_co_u32_e32 v46, vcc, s0, v174
	v_fma_f32 v48, v150, v48, v8
	v_fma_f32 v49, v151, v49, v9
	s_nop 0
	v_addc_co_u32_e32 v47, vcc, 0, v175, vcc
	v_cvt_pk_bf16_f32 v43, v48, v49
	v_cvt_pk_bf16_f32 v44, v44, v45
	v_cvt_pk_bf16_f32 v45, v60, v61
	global_store_dwordx4 v[46:47], v[42:45], off
	s_mov_b32 s0, 0x50000
	s_nop 0
	v_mul_f32_e32 v42, v66, v58
	v_mul_f32_e32 v43, v67, v58
	v_mul_f32_e32 v44, v68, v58
	v_mul_f32_e32 v45, v69, v58
	v_fma_f32 v48, v158, v42, v16
	v_fma_f32 v49, v159, v43, v17
	v_fma_f32 v42, v160, v44, v14
	v_fma_f32 v43, v161, v45, v15
	v_mul_f32_e32 v44, v70, v58
	v_mul_f32_e32 v45, v71, v58
	v_mul_f32_e32 v59, v73, v58
	v_mul_f32_e32 v58, v72, v58
	v_fma_f32 v60, v154, v44, v12
	v_fma_f32 v61, v155, v45, v13
	v_fma_f32 v44, v156, v58, v10
	v_fma_f32 v45, v157, v59, v11
	v_cvt_pk_bf16_f32 v42, v42, v43
	v_cvt_pk_bf16_f32 v43, v48, v49
	s_nop 0
	v_cvt_pk_bf16_f32 v44, v44, v45
	v_cvt_pk_bf16_f32 v45, v60, v61
	global_store_dwordx4 v[46:47], v[42:45], off offset:256
	ds_read_b32 v42, v198 offset:640
	s_waitcnt lgkmcnt(0)
	v_mul_f32_e32 v30, v30, v42
	v_mul_f32_e32 v31, v31, v42
	s_nop 0
	v_fma_f32 v30, v152, v30, v6
	v_fma_f32 v31, v153, v31, v7
	v_mul_f32_e32 v28, v28, v42
	v_mul_f32_e32 v29, v29, v42
	v_mul_f32_e32 v26, v26, v42
	v_mul_f32_e32 v27, v27, v42
	v_mul_f32_e32 v32, v32, v42
	v_mul_f32_e32 v33, v33, v42
	v_fma_f32 v44, v130, v28, v4
	v_fma_f32 v45, v131, v29, v5
	v_fma_f32 v28, v132, v26, v2
	v_fma_f32 v29, v133, v27, v3
	v_cvt_pk_bf16_f32 v26, v30, v31
	v_add_co_u32_e32 v30, vcc, s0, v174
	v_fma_f32 v32, v150, v32, v8
	v_fma_f32 v33, v151, v33, v9
	s_nop 0
	v_addc_co_u32_e32 v31, vcc, 0, v175, vcc
	v_cvt_pk_bf16_f32 v27, v32, v33
	v_mul_f32_e32 v20, v20, v42
	v_mul_f32_e32 v21, v21, v42
	v_mul_f32_e32 v18, v18, v42
	v_mul_f32_e32 v19, v19, v42
	v_cvt_pk_bf16_f32 v28, v28, v29
	v_cvt_pk_bf16_f32 v29, v44, v45
	global_store_dwordx4 v[30:31], v[26:29], off
	v_mul_f32_e32 v24, v24, v42
	v_mul_f32_e32 v25, v25, v42
	v_mul_f32_e32 v22, v22, v42
	v_mul_f32_e32 v23, v23, v42
	v_fma_f32 v26, v154, v20, v12
	v_fma_f32 v27, v155, v21, v13
	v_fma_f32 v20, v156, v18, v10
	v_fma_f32 v21, v157, v19, v11
	v_fma_f32 v24, v158, v24, v16
	v_fma_f32 v25, v159, v25, v17
	v_fma_f32 v22, v160, v22, v14
	v_fma_f32 v23, v161, v23, v15
	s_mov_b32 s0, 0x58000
	v_cvt_pk_bf16_f32 v18, v22, v23
	v_cvt_pk_bf16_f32 v19, v24, v25
	v_cvt_pk_bf16_f32 v20, v20, v21
	v_cvt_pk_bf16_f32 v21, v26, v27
	global_store_dwordx4 v[30:31], v[18:21], off offset:256
	ds_read_b32 v18, v198 offset:704
	s_waitcnt lgkmcnt(0)
	v_mul_f32_e32 v22, v36, v18
	v_mul_f32_e32 v23, v37, v18
	v_mul_f32_e32 v20, v34, v18
	v_mul_f32_e32 v21, v35, v18
	v_fma_f32 v6, v152, v22, v6
	v_fma_f32 v7, v153, v23, v7
	v_fma_f32 v8, v150, v20, v8
	v_fma_f32 v9, v151, v21, v9
	v_mul_f32_e32 v20, v50, v18
	v_mul_f32_e32 v21, v51, v18
	v_mul_f32_e32 v22, v52, v18
	v_mul_f32_e32 v23, v53, v18
	v_fma_f32 v20, v130, v20, v4
	v_fma_f32 v21, v131, v21, v5
	v_fma_f32 v4, v132, v22, v2
	v_fma_f32 v5, v133, v23, v3
	v_cvt_pk_bf16_f32 v2, v6, v7
	v_add_co_u32_e32 v6, vcc, s0, v174
	v_cvt_pk_bf16_f32 v3, v8, v9
	v_cvt_pk_bf16_f32 v4, v4, v5
	v_cvt_pk_bf16_f32 v5, v20, v21
	s_mov_b64 s[0:1], -1
	s_nop 0
	v_addc_co_u32_e32 v7, vcc, 0, v175, vcc
	global_store_dwordx4 v[6:7], v[2:5], off
	s_and_b64 vcc, exec, s[8:9]
	s_nop 0
	v_mul_f32_e32 v2, v38, v18
	v_mul_f32_e32 v3, v39, v18
	v_mul_f32_e32 v4, v40, v18
	v_mul_f32_e32 v5, v41, v18
	v_fma_f32 v8, v158, v2, v16
	v_fma_f32 v9, v159, v3, v17
	v_fma_f32 v2, v160, v4, v14
	v_fma_f32 v3, v161, v5, v15
	v_mul_f32_e32 v4, v54, v18
	v_mul_f32_e32 v5, v55, v18
	v_mul_f32_e32 v14, v56, v18
	v_mul_f32_e32 v15, v57, v18
	v_fma_f32 v12, v154, v4, v12
	v_fma_f32 v13, v155, v5, v13
	v_fma_f32 v4, v156, v14, v10
	v_fma_f32 v5, v157, v15, v11
	v_cvt_pk_bf16_f32 v2, v2, v3
	v_cvt_pk_bf16_f32 v3, v8, v9
	s_nop 0
	v_cvt_pk_bf16_f32 v4, v4, v5
	v_cvt_pk_bf16_f32 v5, v12, v13
	global_store_dwordx4 v[6:7], v[2:5], off offset:256
	s_cbranch_vccnz .LBB0_268
	s_andn2_b64 vcc, exec, s[2:3]
	s_cbranch_vccnz .LBB0_267
	s_barrier
	s_branch .LBB0_267

.LBB0_474:
	v_mul_f32_e32 v0, 0xbfb8aa3b, v142
	v_exp_f32_e32 v0, v0
	v_mul_f32_e32 v166, 0xbfb8aa3b, v138
	v_mul_f32_e32 v167, 0xbfb8aa3b, v143
	v_exp_f32_e32 v168, v166
	v_exp_f32_e32 v167, v167
	v_add_f32_e32 v0, 1.0, v0
	v_rcp_f32_e32 v166, v0
	v_add_f32_e32 v0, 1.0, v168
	v_rcp_f32_e32 v170, v0
	v_add_f32_e32 v0, 1.0, v167
	v_mul_f32_e32 v169, 0xbfb8aa3b, v140
	v_rcp_f32_e32 v167, v0
	v_mul_f32_e32 v0, 0xbfb8aa3b, v139
	v_mul_f32_e32 v168, 0xbfb8aa3b, v144
	v_exp_f32_e32 v169, v169
	v_mul_f32_e32 v171, 0xbfb8aa3b, v145
	v_mul_f32_e32 v172, 0xbfb8aa3b, v141
	v_exp_f32_e32 v0, v0
	v_exp_f32_e32 v168, v168
	v_exp_f32_e32 v171, v171
	v_exp_f32_e32 v172, v172
	v_add_f32_e32 v169, 1.0, v169
	v_add_f32_e32 v0, 1.0, v0
	v_add_f32_e32 v168, 1.0, v168
	v_rcp_f32_e32 v174, v169
	v_add_f32_e32 v169, 1.0, v171
	v_add_f32_e32 v171, 1.0, v172
	v_rcp_f32_e32 v168, v168
	v_rcp_f32_e32 v169, v169
	v_rcp_f32_e32 v175, v171
	v_rcp_f32_e32 v171, v0
	v_mul_f32_e32 v172, v144, v168
	v_mul_f32_e32 v173, v145, v169
	v_mul_f32_e32 v168, v142, v166
	v_mul_f32_e32 v169, v143, v167
	v_mul_f32_e32 v174, v140, v174
	v_mul_f32_e32 v175, v141, v175
	v_mul_f32_e32 v170, v138, v170
	v_mul_f32_e32 v171, v139, v171

.LBB0_476:
	s_and_b64 vcc, exec, s[2:3]
	s_waitcnt vmcnt(0)
	v_sub_f32_e32 v166, 1.0, v34
	v_sub_f32_e32 v167, 1.0, v35
	s_cbranch_vccz .LBB0_478
	v_mul_f32_e64 v0, |v142|, s33
	v_exp_f32_e32 v34, v0
	v_mul_f32_e64 v0, |v138|, s33
	v_mul_f32_e64 v35, |v143|, s33
	v_exp_f32_e32 v170, v0
	v_exp_f32_e32 v35, v35
	v_add_f32_e32 v0, 1.0, v34
	v_rcp_f32_e32 v168, v0
	v_add_f32_e32 v0, 1.0, v170
	v_rcp_f32_e32 v172, v0
	v_add_f32_e32 v0, 1.0, v35
	v_rcp_f32_e32 v169, v0
	v_mul_f32_e64 v0, |v139|, s33
	v_exp_f32_e32 v171, v0
	v_cmp_le_f32_e32 vcc, 0, v143
	v_mul_f32_e32 v34, v34, v168
	v_mul_f32_e32 v35, v35, v169
	v_sub_f32_e32 v174, 1.0, v38
	v_sub_f32_e32 v175, 1.0, v39
	v_add_f32_e32 v0, 1.0, v171
	v_rcp_f32_e32 v173, v0
	v_mul_f32_e64 v0, |v144|, s33
	v_cndmask_b32_e32 v35, v169, v35, vcc
	v_cmp_le_f32_e32 vcc, 0, v142
	v_exp_f32_e32 v142, v0
	v_sub_f32_e32 v180, 1.0, v40
	v_sub_f32_e32 v181, 1.0, v41
	v_cndmask_b32_e32 v34, v168, v34, vcc
	v_mul_f32_e32 v168, v34, v166
	v_mul_f32_e32 v169, v35, v167
	v_mul_f32_e32 v34, v170, v172
	v_mul_f32_e32 v35, v171, v173
	v_cmp_le_f32_e32 vcc, 0, v139
	v_add_f32_e32 v0, 1.0, v142
	s_nop 0
	v_cndmask_b32_e32 v35, v173, v35, vcc
	v_cmp_le_f32_e32 vcc, 0, v138
	s_nop 1
	v_cndmask_b32_e32 v34, v172, v34, vcc
	v_mul_f32_e32 v170, v34, v174
	v_mul_f32_e32 v171, v35, v175
	v_rcp_f32_e32 v34, v0
	v_mul_f32_e64 v0, |v140|, s33
	v_exp_f32_e32 v138, v0
	v_mul_f32_e64 v0, |v145|, s33
	v_exp_f32_e32 v143, v0
	v_cmp_le_f32_e32 vcc, 0, v145
	v_add_f32_e32 v0, 1.0, v138
	v_rcp_f32_e32 v174, v0
	v_add_f32_e32 v0, 1.0, v143
	v_rcp_f32_e32 v35, v0
	v_mul_f32_e64 v0, |v141|, s33
	v_exp_f32_e32 v139, v0
	v_sub_f32_e32 v172, 1.0, v36
	v_sub_f32_e32 v173, 1.0, v37
	v_mul_f32_e32 v142, v142, v34
	v_mul_f32_e32 v143, v143, v35
	v_add_f32_e32 v0, 1.0, v139
	v_rcp_f32_e32 v175, v0
	v_cndmask_b32_e32 v35, v35, v143, vcc
	v_cmp_le_f32_e32 vcc, 0, v144
	s_nop 1
	v_cndmask_b32_e32 v34, v34, v142, vcc
	v_mul_f32_e32 v172, v34, v172
	v_mul_f32_e32 v173, v35, v173
	v_mul_f32_e32 v34, v138, v174
	v_mul_f32_e32 v35, v139, v175
	v_cmp_le_f32_e32 vcc, 0, v141
	s_nop 1
	v_cndmask_b32_e32 v35, v175, v35, vcc
	v_cmp_le_f32_e32 vcc, 0, v140
	s_nop 1
	v_cndmask_b32_e32 v34, v174, v34, vcc
	v_mul_f32_e32 v174, v34, v180
	v_mul_f32_e32 v175, v35, v181

.LBB0_484:
	v_mov_b32_e32 v166, v164
	v_mov_b32_e32 v167, v164
	v_mul_f32_e32 v172, v166, v144
	v_mul_f32_e32 v173, v167, v145
	v_mul_f32_e32 v168, v164, v142
	v_mul_f32_e32 v169, v165, v143
	v_mul_f32_e32 v174, v166, v140
	v_mul_f32_e32 v175, v167, v141
	v_mul_f32_e32 v170, v164, v138
	v_mul_f32_e32 v171, v165, v139
	s_mov_b64 s[2:3], 0

.LBB0_492:
	v_mul_f32_e32 v0, 0xbfb8aa3b, v134
	v_exp_f32_e32 v0, v0
	v_mul_f32_e32 v138, 0xbfb8aa3b, v130
	v_mul_f32_e32 v141, 0xbfb8aa3b, v136
	v_mul_f32_e32 v139, 0xbfb8aa3b, v135
	v_exp_f32_e32 v140, v138
	v_exp_f32_e32 v141, v141
	v_mul_f32_e32 v142, 0xbfb8aa3b, v132
	v_exp_f32_e32 v139, v139
	v_exp_f32_e32 v143, v142
	v_add_f32_e32 v0, 1.0, v0
	v_rcp_f32_e32 v138, v0
	v_add_f32_e32 v0, 1.0, v140
	v_add_f32_e32 v141, 1.0, v141
	v_rcp_f32_e32 v140, v0
	v_add_f32_e32 v0, 1.0, v139
	v_rcp_f32_e32 v142, v141
	v_add_f32_e32 v141, 1.0, v143
	v_mul_f32_e32 v143, 0xbfb8aa3b, v137
	v_rcp_f32_e32 v139, v0
	v_mul_f32_e32 v0, 0xbfb8aa3b, v131
	v_exp_f32_e32 v143, v143
	v_mul_f32_e32 v144, 0xbfb8aa3b, v133
	v_exp_f32_e32 v0, v0
	v_exp_f32_e32 v145, v144
	v_rcp_f32_e32 v144, v141
	v_add_f32_e32 v141, 1.0, v143
	v_add_f32_e32 v0, 1.0, v0
	v_rcp_f32_e32 v143, v141
	v_add_f32_e32 v141, 1.0, v145
	v_rcp_f32_e32 v145, v141
	v_rcp_f32_e32 v141, v0
	v_mul_f32_e32 v142, v136, v142
	v_mul_f32_e32 v143, v137, v143
	v_mul_f32_e32 v138, v134, v138
	v_mul_f32_e32 v139, v135, v139
	v_mul_f32_e32 v144, v132, v144
	v_mul_f32_e32 v145, v133, v145
	v_mul_f32_e32 v140, v130, v140
	v_mul_f32_e32 v141, v131, v141

.LBB0_494:
	s_and_b64 vcc, exec, s[0:1]
	s_cbranch_vccz .LBB0_496
	v_mul_f32_e64 v0, |v134|, s33
	v_exp_f32_e32 v138, v0
	v_mul_f32_e64 v0, |v130|, s33
	v_mul_f32_e64 v139, |v135|, s33
	v_exp_f32_e32 v140, v0
	v_exp_f32_e32 v139, v139
	v_add_f32_e32 v0, 1.0, v138
	v_rcp_f32_e32 v142, v0
	v_add_f32_e32 v0, 1.0, v140
	v_rcp_f32_e32 v168, v0
	v_add_f32_e32 v0, 1.0, v139
	v_rcp_f32_e32 v143, v0
	v_mul_f32_e64 v0, |v131|, s33
	v_exp_f32_e32 v141, v0
	v_cmp_le_f32_e32 vcc, 0, v135
	v_mul_f32_e32 v138, v138, v142
	v_mul_f32_e32 v139, v139, v143
	v_sub_f32_e32 v144, 1.0, v18
	v_sub_f32_e32 v145, 1.0, v19
	v_add_f32_e32 v0, 1.0, v141
	v_rcp_f32_e32 v169, v0
	v_cndmask_b32_e32 v135, v143, v139, vcc
	v_cmp_le_f32_e32 vcc, 0, v134
	v_mul_f32_e64 v0, |v136|, s33
	v_sub_f32_e32 v170, 1.0, v22
	v_sub_f32_e32 v171, 1.0, v23
	v_cndmask_b32_e32 v134, v142, v138, vcc
	v_exp_f32_e32 v142, v0
	v_mul_f32_e32 v138, v134, v144
	v_mul_f32_e32 v139, v135, v145
	v_mul_f32_e32 v134, v140, v168
	v_mul_f32_e32 v135, v141, v169
	v_cmp_le_f32_e32 vcc, 0, v131
	v_add_f32_e32 v0, 1.0, v142
	v_sub_f32_e32 v144, 1.0, v20
	v_sub_f32_e32 v145, 1.0, v21
	v_cndmask_b32_e32 v131, v169, v135, vcc
	v_cmp_le_f32_e32 vcc, 0, v130
	s_nop 1
	v_cndmask_b32_e32 v130, v168, v134, vcc
	v_mul_f32_e32 v140, v130, v170
	v_mul_f32_e32 v141, v131, v171
	v_rcp_f32_e32 v130, v0
	v_mul_f32_e64 v0, |v132|, s33
	v_exp_f32_e32 v134, v0
	v_mul_f32_e64 v0, |v137|, s33
	v_exp_f32_e32 v143, v0
	v_cmp_le_f32_e32 vcc, 0, v137
	v_add_f32_e32 v0, 1.0, v134
	v_rcp_f32_e32 v168, v0
	v_add_f32_e32 v0, 1.0, v143
	v_rcp_f32_e32 v131, v0
	v_mul_f32_e64 v0, |v133|, s33
	v_exp_f32_e32 v135, v0
	v_sub_f32_e32 v170, 1.0, v24
	v_sub_f32_e32 v171, 1.0, v25
	v_mul_f32_e32 v142, v142, v130
	v_mul_f32_e32 v143, v143, v131
	v_add_f32_e32 v0, 1.0, v135
	v_rcp_f32_e32 v169, v0
	v_cndmask_b32_e32 v131, v131, v143, vcc
	v_cmp_le_f32_e32 vcc, 0, v136
	s_nop 1
	v_cndmask_b32_e32 v130, v130, v142, vcc
	v_mul_f32_e32 v142, v130, v144
	v_mul_f32_e32 v143, v131, v145
	v_mul_f32_e32 v130, v134, v168
	v_mul_f32_e32 v131, v135, v169
	v_cmp_le_f32_e32 vcc, 0, v133
	s_nop 1
	v_cndmask_b32_e32 v131, v169, v131, vcc
	v_cmp_le_f32_e32 vcc, 0, v132
	s_nop 1
	v_cndmask_b32_e32 v130, v168, v130, vcc
	v_mul_f32_e32 v144, v130, v170
	v_mul_f32_e32 v145, v131, v171

.LBB0_502:
	v_mov_b32_e32 v140, v164
	v_mov_b32_e32 v141, v164
	v_mul_f32_e32 v142, v140, v136
	v_mul_f32_e32 v143, v141, v137
	v_mul_f32_e32 v138, v164, v134
	v_mul_f32_e32 v139, v165, v135
	v_mul_f32_e32 v144, v140, v132
	v_mul_f32_e32 v145, v141, v133
	v_mul_f32_e32 v140, v164, v130
	v_mul_f32_e32 v141, v165, v131
	s_mov_b64 s[0:1], 0

.LBB0_510:
	v_mul_f32_e32 v0, 0xbfb8aa3b, v126
	v_exp_f32_e32 v0, v0
	v_mul_f32_e32 v130, 0xbfb8aa3b, v122
	v_mul_f32_e32 v133, 0xbfb8aa3b, v128
	v_mul_f32_e32 v131, 0xbfb8aa3b, v127
	v_exp_f32_e32 v132, v130
	v_exp_f32_e32 v133, v133
	v_mul_f32_e32 v134, 0xbfb8aa3b, v124
	v_exp_f32_e32 v131, v131
	v_exp_f32_e32 v135, v134
	v_add_f32_e32 v0, 1.0, v0
	v_rcp_f32_e32 v130, v0
	v_add_f32_e32 v0, 1.0, v132
	v_add_f32_e32 v133, 1.0, v133
	v_rcp_f32_e32 v132, v0
	v_add_f32_e32 v0, 1.0, v131
	v_rcp_f32_e32 v134, v133
	v_add_f32_e32 v133, 1.0, v135
	v_mul_f32_e32 v135, 0xbfb8aa3b, v129
	v_rcp_f32_e32 v131, v0
	v_mul_f32_e32 v0, 0xbfb8aa3b, v123
	v_exp_f32_e32 v135, v135
	v_mul_f32_e32 v136, 0xbfb8aa3b, v125
	v_exp_f32_e32 v0, v0
	v_exp_f32_e32 v137, v136
	v_rcp_f32_e32 v136, v133
	v_add_f32_e32 v133, 1.0, v135
	v_add_f32_e32 v0, 1.0, v0
	v_rcp_f32_e32 v135, v133
	v_add_f32_e32 v133, 1.0, v137
	v_rcp_f32_e32 v137, v133
	v_rcp_f32_e32 v133, v0
	v_mul_f32_e32 v134, v128, v134
	v_mul_f32_e32 v135, v129, v135
	v_mul_f32_e32 v130, v126, v130
	v_mul_f32_e32 v131, v127, v131
	v_mul_f32_e32 v136, v124, v136
	v_mul_f32_e32 v137, v125, v137
	v_mul_f32_e32 v132, v122, v132
	v_mul_f32_e32 v133, v123, v133

.LBB0_512:
	s_and_b64 vcc, exec, s[0:1]
	s_cbranch_vccz .LBB0_514
	v_mul_f32_e64 v0, |v126|, s33
	v_exp_f32_e32 v130, v0
	v_mul_f32_e64 v0, |v122|, s33
	v_mul_f32_e64 v131, |v127|, s33
	v_exp_f32_e32 v132, v0
	v_exp_f32_e32 v131, v131
	v_add_f32_e32 v0, 1.0, v130
	v_rcp_f32_e32 v134, v0
	v_add_f32_e32 v0, 1.0, v132
	v_rcp_f32_e32 v136, v0
	v_add_f32_e32 v0, 1.0, v131
	v_rcp_f32_e32 v135, v0
	v_mul_f32_e64 v0, |v123|, s33
	v_exp_f32_e32 v133, v0
	v_cmp_le_f32_e32 vcc, 0, v127
	v_mul_f32_e32 v130, v130, v134
	v_mul_f32_e32 v131, v131, v135
	v_sub_f32_e32 v138, 1.0, v38
	v_sub_f32_e32 v139, 1.0, v39
	v_add_f32_e32 v0, 1.0, v133
	v_rcp_f32_e32 v137, v0
	v_cndmask_b32_e32 v127, v135, v131, vcc
	v_cmp_le_f32_e32 vcc, 0, v126
	v_mul_f32_e64 v0, |v128|, s33
	v_sub_f32_e32 v140, 1.0, v40
	v_sub_f32_e32 v141, 1.0, v41
	v_cndmask_b32_e32 v126, v134, v130, vcc
	v_exp_f32_e32 v134, v0
	v_mul_f32_e32 v130, v126, v166
	v_mul_f32_e32 v131, v127, v167
	v_mul_f32_e32 v126, v132, v136
	v_mul_f32_e32 v127, v133, v137
	v_cmp_le_f32_e32 vcc, 0, v123
	v_add_f32_e32 v0, 1.0, v134
	s_nop 0
	v_cndmask_b32_e32 v123, v137, v127, vcc
	v_cmp_le_f32_e32 vcc, 0, v122
	s_nop 1
	v_cndmask_b32_e32 v122, v136, v126, vcc
	v_mul_f32_e32 v132, v122, v138
	v_mul_f32_e32 v133, v123, v139
	v_rcp_f32_e32 v122, v0
	v_mul_f32_e64 v0, |v124|, s33
	v_exp_f32_e32 v126, v0
	v_mul_f32_e64 v0, |v129|, s33
	v_exp_f32_e32 v135, v0
	v_cmp_le_f32_e32 vcc, 0, v129
	v_add_f32_e32 v0, 1.0, v126
	v_rcp_f32_e32 v138, v0
	v_add_f32_e32 v0, 1.0, v135
	v_rcp_f32_e32 v123, v0
	v_mul_f32_e64 v0, |v125|, s33
	v_exp_f32_e32 v127, v0
	v_sub_f32_e32 v136, 1.0, v36
	v_sub_f32_e32 v137, 1.0, v37
	v_mul_f32_e32 v134, v134, v122
	v_mul_f32_e32 v135, v135, v123
	v_add_f32_e32 v0, 1.0, v127
	v_rcp_f32_e32 v139, v0
	v_cndmask_b32_e32 v123, v123, v135, vcc
	v_cmp_le_f32_e32 vcc, 0, v128
	s_nop 1
	v_cndmask_b32_e32 v122, v122, v134, vcc
	v_mul_f32_e32 v134, v122, v136
	v_mul_f32_e32 v135, v123, v137
	v_mul_f32_e32 v122, v126, v138
	v_mul_f32_e32 v123, v127, v139
	v_cmp_le_f32_e32 vcc, 0, v125
	s_nop 1
	v_cndmask_b32_e32 v123, v139, v123, vcc
	v_cmp_le_f32_e32 vcc, 0, v124
	s_nop 1
	v_cndmask_b32_e32 v122, v138, v122, vcc
	v_mul_f32_e32 v136, v122, v140
	v_mul_f32_e32 v137, v123, v141

.LBB0_520:
	v_mov_b32_e32 v132, v164
	v_mov_b32_e32 v133, v164
	v_mul_f32_e32 v134, v132, v128
	v_mul_f32_e32 v135, v133, v129
	v_mul_f32_e32 v130, v164, v126
	v_mul_f32_e32 v131, v165, v127
	v_mul_f32_e32 v136, v132, v124
	v_mul_f32_e32 v137, v133, v125
	v_mul_f32_e32 v132, v164, v122
	v_mul_f32_e32 v133, v165, v123
	s_mov_b64 s[0:1], 0

.LBB0_528:
	v_mul_f32_e32 v0, 0xbfb8aa3b, v118
	v_exp_f32_e32 v0, v0
	v_mul_f32_e32 v122, 0xbfb8aa3b, v114
	v_mul_f32_e32 v125, 0xbfb8aa3b, v120
	v_mul_f32_e32 v123, 0xbfb8aa3b, v119
	v_exp_f32_e32 v124, v122
	v_exp_f32_e32 v125, v125
	v_mul_f32_e32 v126, 0xbfb8aa3b, v116
	v_exp_f32_e32 v123, v123
	v_exp_f32_e32 v127, v126
	v_add_f32_e32 v0, 1.0, v0
	v_rcp_f32_e32 v122, v0
	v_add_f32_e32 v0, 1.0, v124
	v_add_f32_e32 v125, 1.0, v125
	v_rcp_f32_e32 v124, v0
	v_add_f32_e32 v0, 1.0, v123
	v_rcp_f32_e32 v126, v125
	v_add_f32_e32 v125, 1.0, v127
	v_mul_f32_e32 v127, 0xbfb8aa3b, v121
	v_rcp_f32_e32 v123, v0
	v_mul_f32_e32 v0, 0xbfb8aa3b, v115
	v_exp_f32_e32 v127, v127
	v_mul_f32_e32 v128, 0xbfb8aa3b, v117
	v_exp_f32_e32 v0, v0
	v_exp_f32_e32 v129, v128
	v_rcp_f32_e32 v128, v125
	v_add_f32_e32 v125, 1.0, v127
	v_add_f32_e32 v0, 1.0, v0
	v_rcp_f32_e32 v127, v125
	v_add_f32_e32 v125, 1.0, v129
	v_rcp_f32_e32 v129, v125
	v_rcp_f32_e32 v125, v0
	v_mul_f32_e32 v126, v120, v126
	v_mul_f32_e32 v127, v121, v127
	v_mul_f32_e32 v122, v118, v122
	v_mul_f32_e32 v123, v119, v123
	v_mul_f32_e32 v128, v116, v128
	v_mul_f32_e32 v129, v117, v129
	v_mul_f32_e32 v124, v114, v124
	v_mul_f32_e32 v125, v115, v125

.LBB0_530:
	s_and_b64 vcc, exec, s[0:1]
	s_cbranch_vccz .LBB0_532
	v_mul_f32_e64 v0, |v118|, s33
	v_exp_f32_e32 v122, v0
	v_cmp_le_f32_e32 vcc, 0, v118
	v_cmp_le_f32_e64 s[6:7], 0, v119
	v_sub_f32_e32 v126, 1.0, v18
	v_sub_f32_e32 v127, 1.0, v19
	v_add_f32_e32 v0, 1.0, v122
	v_rcp_f32_e32 v124, v0
	v_mul_f32_e64 v0, |v114|, s33
	v_exp_f32_e32 v128, v0
	v_sub_f32_e32 v132, 1.0, v22
	v_sub_f32_e32 v133, 1.0, v23
	v_add_f32_e32 v0, 1.0, v128
	v_rcp_f32_e32 v130, v0
	v_mul_f32_e64 v0, |v119|, s33
	v_exp_f32_e32 v123, v0
	s_nop 0
	v_add_f32_e32 v0, 1.0, v123
	v_rcp_f32_e32 v125, v0
	v_mul_f32_e64 v0, |v115|, s33
	v_exp_f32_e32 v129, v0
	v_mul_f32_e32 v122, v122, v124
	v_mul_f32_e32 v123, v123, v125
	s_nop 0
	v_cndmask_b32_e64 v119, v125, v123, s[6:7]
	v_add_f32_e32 v0, 1.0, v129
	v_rcp_f32_e32 v131, v0
	v_cndmask_b32_e32 v118, v124, v122, vcc
	v_mul_f32_e32 v122, v118, v126
	v_mul_f32_e32 v123, v119, v127
	v_cmp_le_f32_e32 vcc, 0, v114
	v_mul_f32_e32 v118, v128, v130
	v_mul_f32_e32 v119, v129, v131
	v_cmp_le_f32_e64 s[6:7], 0, v115
	v_cndmask_b32_e32 v114, v130, v118, vcc
	v_mul_f32_e64 v0, |v120|, s33
	v_cndmask_b32_e64 v115, v131, v119, s[6:7]
	v_mul_f32_e32 v124, v114, v132
	v_mul_f32_e32 v125, v115, v133
	v_exp_f32_e32 v114, v0
	v_cmp_le_f32_e32 vcc, 0, v120
	v_cmp_le_f32_e64 s[6:7], 0, v121
	v_sub_f32_e32 v126, 1.0, v20
	v_sub_f32_e32 v127, 1.0, v21
	v_add_f32_e32 v0, 1.0, v114
	v_rcp_f32_e32 v118, v0
	v_mul_f32_e64 v0, |v116|, s33
	v_exp_f32_e32 v128, v0
	v_sub_f32_e32 v132, 1.0, v24
	v_sub_f32_e32 v133, 1.0, v25
	v_add_f32_e32 v0, 1.0, v128
	v_rcp_f32_e32 v130, v0
	v_mul_f32_e64 v0, |v121|, s33
	v_exp_f32_e32 v115, v0
	s_nop 0
	v_add_f32_e32 v0, 1.0, v115
	v_rcp_f32_e32 v119, v0
	v_mul_f32_e64 v0, |v117|, s33
	v_exp_f32_e32 v129, v0
	v_mul_f32_e32 v114, v114, v118
	v_mul_f32_e32 v115, v115, v119
	s_nop 0
	v_cndmask_b32_e64 v115, v119, v115, s[6:7]
	v_add_f32_e32 v0, 1.0, v129
	v_rcp_f32_e32 v131, v0
	v_cndmask_b32_e32 v114, v118, v114, vcc
	v_mul_f32_e32 v126, v114, v126
	v_mul_f32_e32 v127, v115, v127
	v_cmp_le_f32_e32 vcc, 0, v116
	v_mul_f32_e32 v114, v128, v130
	v_mul_f32_e32 v115, v129, v131
	v_cmp_le_f32_e64 s[6:7], 0, v117
	v_cndmask_b32_e32 v114, v130, v114, vcc
	s_nop 0
	v_cndmask_b32_e64 v115, v131, v115, s[6:7]
	v_mul_f32_e32 v128, v114, v132
	v_mul_f32_e32 v129, v115, v133

.LBB0_538:
	v_mov_b32_e32 v124, v164
	v_mov_b32_e32 v125, v164
	v_mul_f32_e32 v126, v124, v120
	v_mul_f32_e32 v127, v125, v121
	v_mul_f32_e32 v122, v164, v118
	v_mul_f32_e32 v123, v165, v119
	v_mul_f32_e32 v128, v124, v116
	v_mul_f32_e32 v129, v125, v117
	v_mul_f32_e32 v124, v164, v114
	v_mul_f32_e32 v125, v165, v115
	s_mov_b64 s[0:1], 0

.LBB0_546:
	v_mul_f32_e32 v0, 0xbfb8aa3b, v110
	v_exp_f32_e32 v0, v0
	v_mul_f32_e32 v114, 0xbfb8aa3b, v106
	v_mul_f32_e32 v117, 0xbfb8aa3b, v112
	v_mul_f32_e32 v115, 0xbfb8aa3b, v111
	v_exp_f32_e32 v116, v114
	v_exp_f32_e32 v117, v117
	v_mul_f32_e32 v118, 0xbfb8aa3b, v108
	v_exp_f32_e32 v115, v115
	v_exp_f32_e32 v119, v118
	v_add_f32_e32 v0, 1.0, v0
	v_rcp_f32_e32 v114, v0
	v_add_f32_e32 v0, 1.0, v116
	v_add_f32_e32 v117, 1.0, v117
	v_rcp_f32_e32 v116, v0
	v_add_f32_e32 v0, 1.0, v115
	v_rcp_f32_e32 v118, v117
	v_add_f32_e32 v117, 1.0, v119
	v_mul_f32_e32 v119, 0xbfb8aa3b, v113
	v_rcp_f32_e32 v115, v0
	v_mul_f32_e32 v0, 0xbfb8aa3b, v107
	v_exp_f32_e32 v119, v119
	v_mul_f32_e32 v120, 0xbfb8aa3b, v109
	v_exp_f32_e32 v0, v0
	v_exp_f32_e32 v121, v120
	v_rcp_f32_e32 v120, v117
	v_add_f32_e32 v117, 1.0, v119
	v_add_f32_e32 v0, 1.0, v0
	v_rcp_f32_e32 v119, v117
	v_add_f32_e32 v117, 1.0, v121
	v_rcp_f32_e32 v121, v117
	v_rcp_f32_e32 v117, v0
	v_mul_f32_e32 v118, v112, v118
	v_mul_f32_e32 v119, v113, v119
	v_mul_f32_e32 v114, v110, v114
	v_mul_f32_e32 v115, v111, v115
	v_mul_f32_e32 v120, v108, v120
	v_mul_f32_e32 v121, v109, v121
	v_mul_f32_e32 v116, v106, v116
	v_mul_f32_e32 v117, v107, v117

.LBB0_548:
	s_and_b64 vcc, exec, s[0:1]
	s_cbranch_vccz .LBB0_550
	v_mul_f32_e64 v0, |v110|, s33
	v_exp_f32_e32 v114, v0
	v_mul_f32_e64 v0, |v106|, s33
	v_mul_f32_e64 v115, |v111|, s33
	v_exp_f32_e32 v116, v0
	v_exp_f32_e32 v115, v115
	v_add_f32_e32 v0, 1.0, v114
	v_rcp_f32_e32 v118, v0
	v_add_f32_e32 v0, 1.0, v116
	v_rcp_f32_e32 v120, v0
	v_add_f32_e32 v0, 1.0, v115
	v_rcp_f32_e32 v119, v0
	v_mul_f32_e64 v0, |v107|, s33
	v_exp_f32_e32 v117, v0
	v_cmp_le_f32_e32 vcc, 0, v111
	v_mul_f32_e32 v114, v114, v118
	v_mul_f32_e32 v115, v115, v119
	v_sub_f32_e32 v122, 1.0, v38
	v_sub_f32_e32 v123, 1.0, v39
	v_add_f32_e32 v0, 1.0, v117
	v_rcp_f32_e32 v121, v0
	v_cndmask_b32_e32 v111, v119, v115, vcc
	v_cmp_le_f32_e32 vcc, 0, v110
	v_mul_f32_e64 v0, |v112|, s33
	v_sub_f32_e32 v124, 1.0, v40
	v_sub_f32_e32 v125, 1.0, v41
	v_cndmask_b32_e32 v110, v118, v114, vcc
	v_exp_f32_e32 v118, v0
	v_mul_f32_e32 v114, v110, v166
	v_mul_f32_e32 v115, v111, v167
	v_mul_f32_e32 v110, v116, v120
	v_mul_f32_e32 v111, v117, v121
	v_cmp_le_f32_e32 vcc, 0, v107
	v_add_f32_e32 v0, 1.0, v118
	s_nop 0
	v_cndmask_b32_e32 v107, v121, v111, vcc
	v_cmp_le_f32_e32 vcc, 0, v106
	s_nop 1
	v_cndmask_b32_e32 v106, v120, v110, vcc
	v_mul_f32_e32 v116, v106, v122
	v_mul_f32_e32 v117, v107, v123
	v_rcp_f32_e32 v106, v0
	v_mul_f32_e64 v0, |v108|, s33
	v_exp_f32_e32 v110, v0
	v_mul_f32_e64 v0, |v113|, s33
	v_exp_f32_e32 v119, v0
	v_cmp_le_f32_e32 vcc, 0, v113
	v_add_f32_e32 v0, 1.0, v110
	v_rcp_f32_e32 v122, v0
	v_add_f32_e32 v0, 1.0, v119
	v_rcp_f32_e32 v107, v0
	v_mul_f32_e64 v0, |v109|, s33
	v_exp_f32_e32 v111, v0
	v_sub_f32_e32 v120, 1.0, v36
	v_sub_f32_e32 v121, 1.0, v37
	v_mul_f32_e32 v118, v118, v106
	v_mul_f32_e32 v119, v119, v107
	v_add_f32_e32 v0, 1.0, v111
	v_rcp_f32_e32 v123, v0
	v_cndmask_b32_e32 v107, v107, v119, vcc
	v_cmp_le_f32_e32 vcc, 0, v112
	s_nop 1
	v_cndmask_b32_e32 v106, v106, v118, vcc
	v_mul_f32_e32 v118, v106, v120
	v_mul_f32_e32 v119, v107, v121
	v_mul_f32_e32 v106, v110, v122
	v_mul_f32_e32 v107, v111, v123
	v_cmp_le_f32_e32 vcc, 0, v109
	s_nop 1
	v_cndmask_b32_e32 v107, v123, v107, vcc
	v_cmp_le_f32_e32 vcc, 0, v108
	s_nop 1
	v_cndmask_b32_e32 v106, v122, v106, vcc
	v_mul_f32_e32 v120, v106, v124
	v_mul_f32_e32 v121, v107, v125

.LBB0_556:
	v_mov_b32_e32 v116, v164
	v_mov_b32_e32 v117, v164
	v_mul_f32_e32 v118, v116, v112
	v_mul_f32_e32 v119, v117, v113
	v_mul_f32_e32 v114, v164, v110
	v_mul_f32_e32 v115, v165, v111
	v_mul_f32_e32 v120, v116, v108
	v_mul_f32_e32 v121, v117, v109
	v_mul_f32_e32 v116, v164, v106
	v_mul_f32_e32 v117, v165, v107
	s_mov_b64 s[0:1], 0

.LBB0_564:
	v_mul_f32_e32 v0, 0xbfb8aa3b, v102
	v_exp_f32_e32 v0, v0
	v_mul_f32_e32 v106, 0xbfb8aa3b, v98
	v_mul_f32_e32 v109, 0xbfb8aa3b, v104
	v_mul_f32_e32 v107, 0xbfb8aa3b, v103
	v_exp_f32_e32 v108, v106
	v_exp_f32_e32 v109, v109
	v_mul_f32_e32 v110, 0xbfb8aa3b, v100
	v_exp_f32_e32 v107, v107
	v_exp_f32_e32 v111, v110
	v_add_f32_e32 v0, 1.0, v0
	v_rcp_f32_e32 v106, v0
	v_add_f32_e32 v0, 1.0, v108
	v_add_f32_e32 v109, 1.0, v109
	v_rcp_f32_e32 v108, v0
	v_add_f32_e32 v0, 1.0, v107
	v_rcp_f32_e32 v110, v109
	v_add_f32_e32 v109, 1.0, v111
	v_mul_f32_e32 v111, 0xbfb8aa3b, v105
	v_rcp_f32_e32 v107, v0
	v_mul_f32_e32 v0, 0xbfb8aa3b, v99
	v_exp_f32_e32 v111, v111
	v_mul_f32_e32 v112, 0xbfb8aa3b, v101
	v_exp_f32_e32 v0, v0
	v_exp_f32_e32 v113, v112
	v_rcp_f32_e32 v112, v109
	v_add_f32_e32 v109, 1.0, v111
	v_add_f32_e32 v0, 1.0, v0
	v_rcp_f32_e32 v111, v109
	v_add_f32_e32 v109, 1.0, v113
	v_rcp_f32_e32 v113, v109
	v_rcp_f32_e32 v109, v0
	v_mul_f32_e32 v110, v104, v110
	v_mul_f32_e32 v111, v105, v111
	v_mul_f32_e32 v106, v102, v106
	v_mul_f32_e32 v107, v103, v107
	v_mul_f32_e32 v112, v100, v112
	v_mul_f32_e32 v113, v101, v113
	v_mul_f32_e32 v108, v98, v108
	v_mul_f32_e32 v109, v99, v109

.LBB0_566:
	s_and_b64 vcc, exec, s[0:1]
	s_cbranch_vccz .LBB0_568
	v_mul_f32_e64 v0, |v102|, s33
	v_exp_f32_e32 v106, v0
	v_mul_f32_e64 v0, |v98|, s33
	v_mul_f32_e64 v107, |v103|, s33
	v_exp_f32_e32 v108, v0
	v_exp_f32_e32 v107, v107
	v_add_f32_e32 v0, 1.0, v106
	v_rcp_f32_e32 v110, v0
	v_add_f32_e32 v0, 1.0, v108
	v_rcp_f32_e32 v114, v0
	v_add_f32_e32 v0, 1.0, v107
	v_rcp_f32_e32 v111, v0
	v_mul_f32_e64 v0, |v99|, s33
	v_exp_f32_e32 v109, v0
	v_cmp_le_f32_e32 vcc, 0, v103
	v_mul_f32_e32 v106, v106, v110
	v_mul_f32_e32 v107, v107, v111
	v_sub_f32_e32 v112, 1.0, v18
	v_sub_f32_e32 v113, 1.0, v19
	v_add_f32_e32 v0, 1.0, v109
	v_rcp_f32_e32 v115, v0
	v_cndmask_b32_e32 v103, v111, v107, vcc
	v_cmp_le_f32_e32 vcc, 0, v102
	v_mul_f32_e64 v0, |v104|, s33
	v_sub_f32_e32 v116, 1.0, v22
	v_sub_f32_e32 v117, 1.0, v23
	v_cndmask_b32_e32 v102, v110, v106, vcc
	v_exp_f32_e32 v110, v0
	v_mul_f32_e32 v106, v102, v112
	v_mul_f32_e32 v107, v103, v113
	v_mul_f32_e32 v102, v108, v114
	v_mul_f32_e32 v103, v109, v115
	v_cmp_le_f32_e32 vcc, 0, v99
	v_add_f32_e32 v0, 1.0, v110
	v_sub_f32_e32 v112, 1.0, v20
	v_sub_f32_e32 v113, 1.0, v21
	v_cndmask_b32_e32 v99, v115, v103, vcc
	v_cmp_le_f32_e32 vcc, 0, v98
	s_nop 1
	v_cndmask_b32_e32 v98, v114, v102, vcc
	v_mul_f32_e32 v108, v98, v116
	v_mul_f32_e32 v109, v99, v117
	v_rcp_f32_e32 v98, v0
	v_mul_f32_e64 v0, |v100|, s33
	v_exp_f32_e32 v102, v0
	v_mul_f32_e64 v0, |v105|, s33
	v_exp_f32_e32 v111, v0
	v_cmp_le_f32_e32 vcc, 0, v105
	v_add_f32_e32 v0, 1.0, v102
	v_rcp_f32_e32 v114, v0
	v_add_f32_e32 v0, 1.0, v111
	v_rcp_f32_e32 v99, v0
	v_mul_f32_e64 v0, |v101|, s33
	v_exp_f32_e32 v103, v0
	v_sub_f32_e32 v116, 1.0, v24
	v_sub_f32_e32 v117, 1.0, v25
	v_mul_f32_e32 v110, v110, v98
	v_mul_f32_e32 v111, v111, v99
	v_add_f32_e32 v0, 1.0, v103
	v_rcp_f32_e32 v115, v0
	v_cndmask_b32_e32 v99, v99, v111, vcc
	v_cmp_le_f32_e32 vcc, 0, v104
	s_nop 1
	v_cndmask_b32_e32 v98, v98, v110, vcc
	v_mul_f32_e32 v110, v98, v112
	v_mul_f32_e32 v111, v99, v113
	v_mul_f32_e32 v98, v102, v114
	v_mul_f32_e32 v99, v103, v115
	v_cmp_le_f32_e32 vcc, 0, v101
	s_nop 1
	v_cndmask_b32_e32 v99, v115, v99, vcc
	v_cmp_le_f32_e32 vcc, 0, v100
	s_nop 1
	v_cndmask_b32_e32 v98, v114, v98, vcc
	v_mul_f32_e32 v112, v98, v116
	v_mul_f32_e32 v113, v99, v117

.LBB0_574:
	v_mov_b32_e32 v108, v164
	v_mov_b32_e32 v109, v164
	v_mul_f32_e32 v110, v108, v104
	v_mul_f32_e32 v111, v109, v105
	v_mul_f32_e32 v106, v164, v102
	v_mul_f32_e32 v107, v165, v103
	v_mul_f32_e32 v112, v108, v100
	v_mul_f32_e32 v113, v109, v101
	v_mul_f32_e32 v108, v164, v98
	v_mul_f32_e32 v109, v165, v99
	s_mov_b64 s[0:1], 0

.LBB0_582:
	v_mul_f32_e32 v0, 0xbfb8aa3b, v94
	v_exp_f32_e32 v0, v0
	v_mul_f32_e32 v98, 0xbfb8aa3b, v90
	v_mul_f32_e32 v101, 0xbfb8aa3b, v96
	v_mul_f32_e32 v99, 0xbfb8aa3b, v95
	v_exp_f32_e32 v100, v98
	v_exp_f32_e32 v101, v101
	v_mul_f32_e32 v102, 0xbfb8aa3b, v92
	v_exp_f32_e32 v99, v99
	v_exp_f32_e32 v103, v102
	v_add_f32_e32 v0, 1.0, v0
	v_rcp_f32_e32 v98, v0
	v_add_f32_e32 v0, 1.0, v100
	v_add_f32_e32 v101, 1.0, v101
	v_rcp_f32_e32 v100, v0
	v_add_f32_e32 v0, 1.0, v99
	v_rcp_f32_e32 v102, v101
	v_add_f32_e32 v101, 1.0, v103
	v_mul_f32_e32 v103, 0xbfb8aa3b, v97
	v_rcp_f32_e32 v99, v0
	v_mul_f32_e32 v0, 0xbfb8aa3b, v91
	v_exp_f32_e32 v103, v103
	v_mul_f32_e32 v104, 0xbfb8aa3b, v93
	v_exp_f32_e32 v0, v0
	v_exp_f32_e32 v105, v104
	v_rcp_f32_e32 v104, v101
	v_add_f32_e32 v101, 1.0, v103
	v_add_f32_e32 v0, 1.0, v0
	v_rcp_f32_e32 v103, v101
	v_add_f32_e32 v101, 1.0, v105
	v_rcp_f32_e32 v105, v101
	v_rcp_f32_e32 v101, v0
	v_mul_f32_e32 v102, v96, v102
	v_mul_f32_e32 v103, v97, v103
	v_mul_f32_e32 v98, v94, v98
	v_mul_f32_e32 v99, v95, v99
	v_mul_f32_e32 v104, v92, v104
	v_mul_f32_e32 v105, v93, v105
	v_mul_f32_e32 v100, v90, v100
	v_mul_f32_e32 v101, v91, v101

.LBB0_584:
	s_and_b64 vcc, exec, s[0:1]
	s_cbranch_vccz .LBB0_586
	v_mul_f32_e64 v0, |v94|, s33
	v_exp_f32_e32 v98, v0
	v_mul_f32_e64 v0, |v90|, s33
	v_mul_f32_e64 v99, |v95|, s33
	v_exp_f32_e32 v100, v0
	v_exp_f32_e32 v99, v99
	v_add_f32_e32 v0, 1.0, v98
	v_rcp_f32_e32 v102, v0
	v_add_f32_e32 v0, 1.0, v100
	v_rcp_f32_e32 v104, v0
	v_add_f32_e32 v0, 1.0, v99
	v_rcp_f32_e32 v103, v0
	v_mul_f32_e64 v0, |v91|, s33
	v_exp_f32_e32 v101, v0
	v_cmp_le_f32_e32 vcc, 0, v95
	v_mul_f32_e32 v98, v98, v102
	v_mul_f32_e32 v99, v99, v103
	v_sub_f32_e32 v106, 1.0, v38
	v_sub_f32_e32 v107, 1.0, v39
	v_add_f32_e32 v0, 1.0, v101
	v_rcp_f32_e32 v105, v0
	v_cndmask_b32_e32 v95, v103, v99, vcc
	v_cmp_le_f32_e32 vcc, 0, v94
	v_mul_f32_e64 v0, |v96|, s33
	v_sub_f32_e32 v108, 1.0, v40
	v_sub_f32_e32 v109, 1.0, v41
	v_cndmask_b32_e32 v94, v102, v98, vcc
	v_exp_f32_e32 v102, v0
	v_mul_f32_e32 v98, v94, v166
	v_mul_f32_e32 v99, v95, v167
	v_mul_f32_e32 v94, v100, v104
	v_mul_f32_e32 v95, v101, v105
	v_cmp_le_f32_e32 vcc, 0, v91
	v_add_f32_e32 v0, 1.0, v102
	s_nop 0
	v_cndmask_b32_e32 v91, v105, v95, vcc
	v_cmp_le_f32_e32 vcc, 0, v90
	s_nop 1
	v_cndmask_b32_e32 v90, v104, v94, vcc
	v_mul_f32_e32 v100, v90, v106
	v_mul_f32_e32 v101, v91, v107
	v_rcp_f32_e32 v90, v0
	v_mul_f32_e64 v0, |v92|, s33
	v_exp_f32_e32 v94, v0
	v_mul_f32_e64 v0, |v97|, s33
	v_exp_f32_e32 v103, v0
	v_cmp_le_f32_e32 vcc, 0, v97
	v_add_f32_e32 v0, 1.0, v94
	v_rcp_f32_e32 v106, v0
	v_add_f32_e32 v0, 1.0, v103
	v_rcp_f32_e32 v91, v0
	v_mul_f32_e64 v0, |v93|, s33
	v_exp_f32_e32 v95, v0
	v_sub_f32_e32 v104, 1.0, v36
	v_sub_f32_e32 v105, 1.0, v37
	v_mul_f32_e32 v102, v102, v90
	v_mul_f32_e32 v103, v103, v91
	v_add_f32_e32 v0, 1.0, v95
	v_rcp_f32_e32 v107, v0
	v_cndmask_b32_e32 v91, v91, v103, vcc
	v_cmp_le_f32_e32 vcc, 0, v96
	s_nop 1
	v_cndmask_b32_e32 v90, v90, v102, vcc
	v_mul_f32_e32 v102, v90, v104
	v_mul_f32_e32 v103, v91, v105
	v_mul_f32_e32 v90, v94, v106
	v_mul_f32_e32 v91, v95, v107
	v_cmp_le_f32_e32 vcc, 0, v93
	s_nop 1
	v_cndmask_b32_e32 v91, v107, v91, vcc
	v_cmp_le_f32_e32 vcc, 0, v92
	s_nop 1
	v_cndmask_b32_e32 v90, v106, v90, vcc
	v_mul_f32_e32 v104, v90, v108
	v_mul_f32_e32 v105, v91, v109

.LBB0_592:
	v_mov_b32_e32 v100, v164
	v_mov_b32_e32 v101, v164
	v_mul_f32_e32 v102, v100, v96
	v_mul_f32_e32 v103, v101, v97
	v_mul_f32_e32 v98, v164, v94
	v_mul_f32_e32 v99, v165, v95
	v_mul_f32_e32 v104, v100, v92
	v_mul_f32_e32 v105, v101, v93
	v_mul_f32_e32 v100, v164, v90
	v_mul_f32_e32 v101, v165, v91
	s_mov_b64 s[0:1], 0

.LBB0_600:
	v_mul_f32_e32 v0, 0xbfb8aa3b, v86
	v_exp_f32_e32 v0, v0
	v_mul_f32_e32 v90, 0xbfb8aa3b, v82
	v_mul_f32_e32 v93, 0xbfb8aa3b, v88
	v_mul_f32_e32 v91, 0xbfb8aa3b, v87
	v_exp_f32_e32 v92, v90
	v_exp_f32_e32 v93, v93
	v_mul_f32_e32 v94, 0xbfb8aa3b, v84
	v_exp_f32_e32 v91, v91
	v_exp_f32_e32 v95, v94
	v_add_f32_e32 v0, 1.0, v0
	v_rcp_f32_e32 v90, v0
	v_add_f32_e32 v0, 1.0, v92
	v_add_f32_e32 v93, 1.0, v93
	v_rcp_f32_e32 v92, v0
	v_add_f32_e32 v0, 1.0, v91
	v_rcp_f32_e32 v94, v93
	v_add_f32_e32 v93, 1.0, v95
	v_mul_f32_e32 v95, 0xbfb8aa3b, v89
	v_rcp_f32_e32 v91, v0
	v_mul_f32_e32 v0, 0xbfb8aa3b, v83
	v_exp_f32_e32 v95, v95
	v_mul_f32_e32 v96, 0xbfb8aa3b, v85
	v_exp_f32_e32 v0, v0
	v_exp_f32_e32 v97, v96
	v_rcp_f32_e32 v96, v93
	v_add_f32_e32 v93, 1.0, v95
	v_add_f32_e32 v0, 1.0, v0
	v_rcp_f32_e32 v95, v93
	v_add_f32_e32 v93, 1.0, v97
	v_rcp_f32_e32 v97, v93
	v_rcp_f32_e32 v93, v0
	v_mul_f32_e32 v94, v88, v94
	v_mul_f32_e32 v95, v89, v95
	v_mul_f32_e32 v90, v86, v90
	v_mul_f32_e32 v91, v87, v91
	v_mul_f32_e32 v96, v84, v96
	v_mul_f32_e32 v97, v85, v97
	v_mul_f32_e32 v92, v82, v92
	v_mul_f32_e32 v93, v83, v93

.LBB0_602:
	s_and_b64 vcc, exec, s[0:1]
	s_cbranch_vccz .LBB0_604
	v_mul_f32_e64 v0, |v86|, s33
	v_exp_f32_e32 v90, v0
	v_mul_f32_e64 v0, |v82|, s33
	v_mul_f32_e64 v91, |v87|, s33
	v_exp_f32_e32 v92, v0
	v_exp_f32_e32 v91, v91
	v_add_f32_e32 v0, 1.0, v90
	v_rcp_f32_e32 v94, v0
	v_add_f32_e32 v0, 1.0, v92
	v_rcp_f32_e32 v98, v0
	v_add_f32_e32 v0, 1.0, v91
	v_rcp_f32_e32 v95, v0
	v_mul_f32_e64 v0, |v83|, s33
	v_exp_f32_e32 v93, v0
	v_cmp_le_f32_e32 vcc, 0, v87
	v_mul_f32_e32 v90, v90, v94
	v_mul_f32_e32 v91, v91, v95
	v_sub_f32_e32 v96, 1.0, v18
	v_sub_f32_e32 v97, 1.0, v19
	v_add_f32_e32 v0, 1.0, v93
	v_rcp_f32_e32 v99, v0
	v_cndmask_b32_e32 v87, v95, v91, vcc
	v_cmp_le_f32_e32 vcc, 0, v86
	v_mul_f32_e64 v0, |v88|, s33
	v_sub_f32_e32 v100, 1.0, v22
	v_sub_f32_e32 v101, 1.0, v23
	v_cndmask_b32_e32 v86, v94, v90, vcc
	v_exp_f32_e32 v94, v0
	v_mul_f32_e32 v90, v86, v96
	v_mul_f32_e32 v91, v87, v97
	v_mul_f32_e32 v86, v92, v98
	v_mul_f32_e32 v87, v93, v99
	v_cmp_le_f32_e32 vcc, 0, v83
	v_add_f32_e32 v0, 1.0, v94
	v_sub_f32_e32 v96, 1.0, v20
	v_sub_f32_e32 v97, 1.0, v21
	v_cndmask_b32_e32 v83, v99, v87, vcc
	v_cmp_le_f32_e32 vcc, 0, v82
	s_nop 1
	v_cndmask_b32_e32 v82, v98, v86, vcc
	v_mul_f32_e32 v92, v82, v100
	v_mul_f32_e32 v93, v83, v101
	v_rcp_f32_e32 v82, v0
	v_mul_f32_e64 v0, |v84|, s33
	v_exp_f32_e32 v86, v0
	v_mul_f32_e64 v0, |v89|, s33
	v_exp_f32_e32 v95, v0
	v_cmp_le_f32_e32 vcc, 0, v89
	v_add_f32_e32 v0, 1.0, v86
	v_rcp_f32_e32 v98, v0
	v_add_f32_e32 v0, 1.0, v95
	v_rcp_f32_e32 v83, v0
	v_mul_f32_e64 v0, |v85|, s33
	v_exp_f32_e32 v87, v0
	v_sub_f32_e32 v100, 1.0, v24
	v_sub_f32_e32 v101, 1.0, v25
	v_mul_f32_e32 v94, v94, v82
	v_mul_f32_e32 v95, v95, v83
	v_add_f32_e32 v0, 1.0, v87
	v_rcp_f32_e32 v99, v0
	v_cndmask_b32_e32 v83, v83, v95, vcc
	v_cmp_le_f32_e32 vcc, 0, v88
	s_nop 1
	v_cndmask_b32_e32 v82, v82, v94, vcc
	v_mul_f32_e32 v94, v82, v96
	v_mul_f32_e32 v95, v83, v97
	v_mul_f32_e32 v82, v86, v98
	v_mul_f32_e32 v83, v87, v99
	v_cmp_le_f32_e32 vcc, 0, v85
	s_nop 1
	v_cndmask_b32_e32 v83, v99, v83, vcc
	v_cmp_le_f32_e32 vcc, 0, v84
	s_nop 1
	v_cndmask_b32_e32 v82, v98, v82, vcc
	v_mul_f32_e32 v96, v82, v100
	v_mul_f32_e32 v97, v83, v101

.LBB0_610:
	v_mov_b32_e32 v92, v164
	v_mov_b32_e32 v93, v164
	v_mul_f32_e32 v94, v92, v88
	v_mul_f32_e32 v95, v93, v89
	v_mul_f32_e32 v90, v164, v86
	v_mul_f32_e32 v91, v165, v87
	v_mul_f32_e32 v96, v92, v84
	v_mul_f32_e32 v97, v93, v85
	v_mul_f32_e32 v92, v164, v82
	v_mul_f32_e32 v93, v165, v83
	s_mov_b64 s[0:1], 0

.LBB0_618:
	v_mul_f32_e32 v0, 0xbfb8aa3b, v78
	v_exp_f32_e32 v0, v0
	v_mul_f32_e32 v82, 0xbfb8aa3b, v74
	v_mul_f32_e32 v85, 0xbfb8aa3b, v80
	v_mul_f32_e32 v83, 0xbfb8aa3b, v79
	v_exp_f32_e32 v84, v82
	v_exp_f32_e32 v85, v85
	v_mul_f32_e32 v86, 0xbfb8aa3b, v76
	v_exp_f32_e32 v83, v83
	v_exp_f32_e32 v87, v86
	v_add_f32_e32 v0, 1.0, v0
	v_rcp_f32_e32 v82, v0
	v_add_f32_e32 v0, 1.0, v84
	v_add_f32_e32 v85, 1.0, v85
	v_rcp_f32_e32 v84, v0
	v_add_f32_e32 v0, 1.0, v83
	v_rcp_f32_e32 v86, v85
	v_add_f32_e32 v85, 1.0, v87
	v_mul_f32_e32 v87, 0xbfb8aa3b, v81
	v_rcp_f32_e32 v83, v0
	v_mul_f32_e32 v0, 0xbfb8aa3b, v75
	v_exp_f32_e32 v87, v87
	v_mul_f32_e32 v88, 0xbfb8aa3b, v77
	v_exp_f32_e32 v0, v0
	v_exp_f32_e32 v89, v88
	v_rcp_f32_e32 v88, v85
	v_add_f32_e32 v85, 1.0, v87
	v_add_f32_e32 v0, 1.0, v0
	v_rcp_f32_e32 v87, v85
	v_add_f32_e32 v85, 1.0, v89
	v_rcp_f32_e32 v89, v85
	v_rcp_f32_e32 v85, v0
	v_mul_f32_e32 v86, v80, v86
	v_mul_f32_e32 v87, v81, v87
	v_mul_f32_e32 v82, v78, v82
	v_mul_f32_e32 v83, v79, v83
	v_mul_f32_e32 v88, v76, v88
	v_mul_f32_e32 v89, v77, v89
	v_mul_f32_e32 v84, v74, v84
	v_mul_f32_e32 v85, v75, v85

.LBB0_620:
	s_and_b64 vcc, exec, s[0:1]
	s_cbranch_vccz .LBB0_622
	v_mul_f32_e64 v0, |v78|, s33
	v_exp_f32_e32 v82, v0
	v_cmp_le_f32_e32 vcc, 0, v78
	v_cmp_le_f32_e64 s[6:7], 0, v79
	v_sub_f32_e32 v90, 1.0, v38
	v_sub_f32_e32 v91, 1.0, v39
	v_add_f32_e32 v0, 1.0, v82
	v_rcp_f32_e32 v84, v0
	v_mul_f32_e64 v0, |v74|, s33
	v_exp_f32_e32 v86, v0
	v_sub_f32_e32 v92, 1.0, v40
	v_sub_f32_e32 v93, 1.0, v41
	v_add_f32_e32 v0, 1.0, v86
	v_rcp_f32_e32 v88, v0
	v_mul_f32_e64 v0, |v79|, s33
	v_exp_f32_e32 v83, v0
	s_nop 0
	v_add_f32_e32 v0, 1.0, v83
	v_rcp_f32_e32 v85, v0
	v_mul_f32_e64 v0, |v75|, s33
	v_exp_f32_e32 v87, v0
	v_mul_f32_e32 v82, v82, v84
	v_mul_f32_e32 v83, v83, v85
	s_nop 0
	v_cndmask_b32_e64 v79, v85, v83, s[6:7]
	v_add_f32_e32 v0, 1.0, v87
	v_rcp_f32_e32 v89, v0
	v_cndmask_b32_e32 v78, v84, v82, vcc
	v_mul_f32_e32 v82, v78, v166
	v_mul_f32_e32 v83, v79, v167
	v_cmp_le_f32_e32 vcc, 0, v74
	v_mul_f32_e32 v78, v86, v88
	v_mul_f32_e32 v79, v87, v89
	v_cmp_le_f32_e64 s[6:7], 0, v75
	v_cndmask_b32_e32 v74, v88, v78, vcc
	v_mul_f32_e64 v0, |v80|, s33
	v_cndmask_b32_e64 v75, v89, v79, s[6:7]
	v_mul_f32_e32 v84, v74, v90
	v_mul_f32_e32 v85, v75, v91
	v_exp_f32_e32 v74, v0
	v_cmp_le_f32_e32 vcc, 0, v80
	v_cmp_le_f32_e64 s[6:7], 0, v81
	v_sub_f32_e32 v86, 1.0, v36
	v_sub_f32_e32 v87, 1.0, v37
	v_add_f32_e32 v0, 1.0, v74
	v_rcp_f32_e32 v78, v0
	v_mul_f32_e64 v0, |v76|, s33
	v_exp_f32_e32 v88, v0
	s_nop 0
	v_add_f32_e32 v0, 1.0, v88
	v_rcp_f32_e32 v90, v0
	v_mul_f32_e64 v0, |v81|, s33
	v_exp_f32_e32 v75, v0
	s_nop 0
	v_add_f32_e32 v0, 1.0, v75
	v_rcp_f32_e32 v79, v0
	v_mul_f32_e64 v0, |v77|, s33
	v_exp_f32_e32 v89, v0
	v_mul_f32_e32 v74, v74, v78
	v_mul_f32_e32 v75, v75, v79
	s_nop 0
	v_cndmask_b32_e64 v75, v79, v75, s[6:7]
	v_add_f32_e32 v0, 1.0, v89
	v_rcp_f32_e32 v91, v0
	v_cndmask_b32_e32 v74, v78, v74, vcc
	v_mul_f32_e32 v86, v74, v86
	v_mul_f32_e32 v87, v75, v87
	v_cmp_le_f32_e32 vcc, 0, v76
	v_mul_f32_e32 v74, v88, v90
	v_mul_f32_e32 v75, v89, v91
	v_cmp_le_f32_e64 s[6:7], 0, v77
	v_cndmask_b32_e32 v74, v90, v74, vcc
	s_nop 0
	v_cndmask_b32_e64 v75, v91, v75, s[6:7]
	v_mul_f32_e32 v88, v74, v92
	v_mul_f32_e32 v89, v75, v93

.LBB0_628:
	v_mov_b32_e32 v84, v164
	v_mov_b32_e32 v85, v164
	v_mul_f32_e32 v86, v84, v80
	v_mul_f32_e32 v87, v85, v81
	v_mul_f32_e32 v82, v164, v78
	v_mul_f32_e32 v83, v165, v79
	v_mul_f32_e32 v88, v84, v76
	v_mul_f32_e32 v89, v85, v77
	v_mul_f32_e32 v84, v164, v74
	v_mul_f32_e32 v85, v165, v75
	s_mov_b64 s[0:1], 0

.LBB0_636:
	v_mul_f32_e32 v0, 0xbfb8aa3b, v70
	v_exp_f32_e32 v0, v0
	v_mul_f32_e32 v74, 0xbfb8aa3b, v66
	v_mul_f32_e32 v77, 0xbfb8aa3b, v72
	v_mul_f32_e32 v75, 0xbfb8aa3b, v71
	v_exp_f32_e32 v76, v74
	v_exp_f32_e32 v77, v77
	v_mul_f32_e32 v78, 0xbfb8aa3b, v68
	v_exp_f32_e32 v75, v75
	v_exp_f32_e32 v79, v78
	v_add_f32_e32 v0, 1.0, v0
	v_rcp_f32_e32 v74, v0
	v_add_f32_e32 v0, 1.0, v76
	v_add_f32_e32 v77, 1.0, v77
	v_rcp_f32_e32 v76, v0
	v_add_f32_e32 v0, 1.0, v75
	v_rcp_f32_e32 v78, v77
	v_add_f32_e32 v77, 1.0, v79
	v_mul_f32_e32 v79, 0xbfb8aa3b, v73
	v_rcp_f32_e32 v75, v0
	v_mul_f32_e32 v0, 0xbfb8aa3b, v67
	v_exp_f32_e32 v79, v79
	v_mul_f32_e32 v80, 0xbfb8aa3b, v69
	v_exp_f32_e32 v0, v0
	v_exp_f32_e32 v81, v80
	v_rcp_f32_e32 v80, v77
	v_add_f32_e32 v77, 1.0, v79
	v_add_f32_e32 v0, 1.0, v0
	v_rcp_f32_e32 v79, v77
	v_add_f32_e32 v77, 1.0, v81
	v_rcp_f32_e32 v81, v77
	v_rcp_f32_e32 v77, v0
	v_mul_f32_e32 v78, v72, v78
	v_mul_f32_e32 v79, v73, v79
	v_mul_f32_e32 v74, v70, v74
	v_mul_f32_e32 v75, v71, v75
	v_mul_f32_e32 v80, v68, v80
	v_mul_f32_e32 v81, v69, v81
	v_mul_f32_e32 v76, v66, v76
	v_mul_f32_e32 v77, v67, v77

.LBB0_638:
	s_and_b64 vcc, exec, s[0:1]
	s_cbranch_vccz .LBB0_640
	v_mul_f32_e64 v0, |v70|, s33
	v_exp_f32_e32 v74, v0
	v_mul_f32_e64 v0, |v66|, s33
	v_mul_f32_e64 v75, |v71|, s33
	v_exp_f32_e32 v76, v0
	v_exp_f32_e32 v75, v75
	v_add_f32_e32 v0, 1.0, v74
	v_rcp_f32_e32 v78, v0
	v_add_f32_e32 v0, 1.0, v76
	v_rcp_f32_e32 v82, v0
	v_add_f32_e32 v0, 1.0, v75
	v_rcp_f32_e32 v79, v0
	v_mul_f32_e64 v0, |v67|, s33
	v_exp_f32_e32 v77, v0
	v_cmp_le_f32_e32 vcc, 0, v71
	v_mul_f32_e32 v74, v74, v78
	v_mul_f32_e32 v75, v75, v79
	v_sub_f32_e32 v80, 1.0, v18
	v_sub_f32_e32 v81, 1.0, v19
	v_add_f32_e32 v0, 1.0, v77
	v_rcp_f32_e32 v83, v0
	v_cndmask_b32_e32 v71, v79, v75, vcc
	v_cmp_le_f32_e32 vcc, 0, v70
	v_mul_f32_e64 v0, |v72|, s33
	v_sub_f32_e32 v84, 1.0, v22
	v_sub_f32_e32 v85, 1.0, v23
	v_cndmask_b32_e32 v70, v78, v74, vcc
	v_exp_f32_e32 v78, v0
	v_mul_f32_e32 v74, v70, v80
	v_mul_f32_e32 v75, v71, v81
	v_mul_f32_e32 v70, v76, v82
	v_mul_f32_e32 v71, v77, v83
	v_cmp_le_f32_e32 vcc, 0, v67
	v_add_f32_e32 v0, 1.0, v78
	v_sub_f32_e32 v80, 1.0, v20
	v_sub_f32_e32 v81, 1.0, v21
	v_cndmask_b32_e32 v67, v83, v71, vcc
	v_cmp_le_f32_e32 vcc, 0, v66
	s_nop 1
	v_cndmask_b32_e32 v66, v82, v70, vcc
	v_mul_f32_e32 v76, v66, v84
	v_mul_f32_e32 v77, v67, v85
	v_rcp_f32_e32 v66, v0
	v_mul_f32_e64 v0, |v68|, s33
	v_exp_f32_e32 v70, v0
	v_mul_f32_e64 v0, |v73|, s33
	v_exp_f32_e32 v79, v0
	v_cmp_le_f32_e32 vcc, 0, v73
	v_add_f32_e32 v0, 1.0, v70
	v_rcp_f32_e32 v82, v0
	v_add_f32_e32 v0, 1.0, v79
	v_rcp_f32_e32 v67, v0
	v_mul_f32_e64 v0, |v69|, s33
	v_exp_f32_e32 v71, v0
	v_sub_f32_e32 v84, 1.0, v24
	v_sub_f32_e32 v85, 1.0, v25
	v_mul_f32_e32 v78, v78, v66
	v_mul_f32_e32 v79, v79, v67
	v_add_f32_e32 v0, 1.0, v71
	v_rcp_f32_e32 v83, v0
	v_cndmask_b32_e32 v67, v67, v79, vcc
	v_cmp_le_f32_e32 vcc, 0, v72
	s_nop 1
	v_cndmask_b32_e32 v66, v66, v78, vcc
	v_mul_f32_e32 v78, v66, v80
	v_mul_f32_e32 v79, v67, v81
	v_mul_f32_e32 v66, v70, v82
	v_mul_f32_e32 v67, v71, v83
	v_cmp_le_f32_e32 vcc, 0, v69
	s_nop 1
	v_cndmask_b32_e32 v67, v83, v67, vcc
	v_cmp_le_f32_e32 vcc, 0, v68
	s_nop 1
	v_cndmask_b32_e32 v66, v82, v66, vcc
	v_mul_f32_e32 v80, v66, v84
	v_mul_f32_e32 v81, v67, v85

.LBB0_646:
	v_mov_b32_e32 v76, v164
	v_mov_b32_e32 v77, v164
	v_mul_f32_e32 v78, v76, v72
	v_mul_f32_e32 v79, v77, v73
	v_mul_f32_e32 v74, v164, v70
	v_mul_f32_e32 v75, v165, v71
	v_mul_f32_e32 v80, v76, v68
	v_mul_f32_e32 v81, v77, v69
	v_mul_f32_e32 v76, v164, v66
	v_mul_f32_e32 v77, v165, v67
	s_mov_b64 s[0:1], 0

.LBB0_654:
	v_mul_f32_e32 v0, 0xbfb8aa3b, v62
	v_exp_f32_e32 v0, v0
	v_mul_f32_e32 v66, 0xbfb8aa3b, v58
	v_mul_f32_e32 v69, 0xbfb8aa3b, v64
	v_mul_f32_e32 v67, 0xbfb8aa3b, v63
	v_exp_f32_e32 v68, v66
	v_exp_f32_e32 v69, v69
	v_mul_f32_e32 v70, 0xbfb8aa3b, v60
	v_exp_f32_e32 v67, v67
	v_exp_f32_e32 v71, v70
	v_add_f32_e32 v0, 1.0, v0
	v_rcp_f32_e32 v66, v0
	v_add_f32_e32 v0, 1.0, v68
	v_add_f32_e32 v69, 1.0, v69
	v_rcp_f32_e32 v68, v0
	v_add_f32_e32 v0, 1.0, v67
	v_rcp_f32_e32 v70, v69
	v_add_f32_e32 v69, 1.0, v71
	v_mul_f32_e32 v71, 0xbfb8aa3b, v65
	v_rcp_f32_e32 v67, v0
	v_mul_f32_e32 v0, 0xbfb8aa3b, v59
	v_exp_f32_e32 v71, v71
	v_mul_f32_e32 v72, 0xbfb8aa3b, v61
	v_exp_f32_e32 v0, v0
	v_exp_f32_e32 v73, v72
	v_rcp_f32_e32 v72, v69
	v_add_f32_e32 v69, 1.0, v71
	v_add_f32_e32 v0, 1.0, v0
	v_rcp_f32_e32 v71, v69
	v_add_f32_e32 v69, 1.0, v73
	v_rcp_f32_e32 v73, v69
	v_rcp_f32_e32 v69, v0
	v_mul_f32_e32 v70, v64, v70
	v_mul_f32_e32 v71, v65, v71
	v_mul_f32_e32 v66, v62, v66
	v_mul_f32_e32 v67, v63, v67
	v_mul_f32_e32 v72, v60, v72
	v_mul_f32_e32 v73, v61, v73
	v_mul_f32_e32 v68, v58, v68
	v_mul_f32_e32 v69, v59, v69

.LBB0_656:
	s_and_b64 vcc, exec, s[0:1]
	s_cbranch_vccz .LBB0_658
	v_mul_f32_e64 v0, |v62|, s33
	v_exp_f32_e32 v66, v0
	v_mul_f32_e64 v0, |v58|, s33
	v_mul_f32_e64 v67, |v63|, s33
	v_exp_f32_e32 v68, v0
	v_exp_f32_e32 v67, v67
	v_add_f32_e32 v0, 1.0, v66
	v_rcp_f32_e32 v70, v0
	v_add_f32_e32 v0, 1.0, v68
	v_rcp_f32_e32 v72, v0
	v_add_f32_e32 v0, 1.0, v67
	v_rcp_f32_e32 v71, v0
	v_mul_f32_e64 v0, |v59|, s33
	v_exp_f32_e32 v69, v0
	v_cmp_le_f32_e32 vcc, 0, v63
	v_mul_f32_e32 v66, v66, v70
	v_mul_f32_e32 v67, v67, v71
	v_sub_f32_e32 v74, 1.0, v38
	v_sub_f32_e32 v75, 1.0, v39
	v_add_f32_e32 v0, 1.0, v69
	v_rcp_f32_e32 v73, v0
	v_cndmask_b32_e32 v63, v71, v67, vcc
	v_cmp_le_f32_e32 vcc, 0, v62
	v_mul_f32_e64 v0, |v64|, s33
	v_sub_f32_e32 v76, 1.0, v40
	v_sub_f32_e32 v77, 1.0, v41
	v_cndmask_b32_e32 v62, v70, v66, vcc
	v_exp_f32_e32 v70, v0
	v_mul_f32_e32 v66, v62, v166
	v_mul_f32_e32 v67, v63, v167
	v_mul_f32_e32 v62, v68, v72
	v_mul_f32_e32 v63, v69, v73
	v_cmp_le_f32_e32 vcc, 0, v59
	v_add_f32_e32 v0, 1.0, v70
	s_nop 0
	v_cndmask_b32_e32 v59, v73, v63, vcc
	v_cmp_le_f32_e32 vcc, 0, v58
	s_nop 1
	v_cndmask_b32_e32 v58, v72, v62, vcc
	v_mul_f32_e32 v68, v58, v74
	v_mul_f32_e32 v69, v59, v75
	v_rcp_f32_e32 v58, v0
	v_mul_f32_e64 v0, |v60|, s33
	v_exp_f32_e32 v62, v0
	v_mul_f32_e64 v0, |v65|, s33
	v_exp_f32_e32 v71, v0
	v_cmp_le_f32_e32 vcc, 0, v65
	v_add_f32_e32 v0, 1.0, v62
	v_rcp_f32_e32 v74, v0
	v_add_f32_e32 v0, 1.0, v71
	v_rcp_f32_e32 v59, v0
	v_mul_f32_e64 v0, |v61|, s33
	v_exp_f32_e32 v63, v0
	v_sub_f32_e32 v72, 1.0, v36
	v_sub_f32_e32 v73, 1.0, v37
	v_mul_f32_e32 v70, v70, v58
	v_mul_f32_e32 v71, v71, v59
	v_add_f32_e32 v0, 1.0, v63
	v_rcp_f32_e32 v75, v0
	v_cndmask_b32_e32 v59, v59, v71, vcc
	v_cmp_le_f32_e32 vcc, 0, v64
	s_nop 1
	v_cndmask_b32_e32 v58, v58, v70, vcc
	v_mul_f32_e32 v70, v58, v72
	v_mul_f32_e32 v71, v59, v73
	v_mul_f32_e32 v58, v62, v74
	v_mul_f32_e32 v59, v63, v75
	v_cmp_le_f32_e32 vcc, 0, v61
	s_nop 1
	v_cndmask_b32_e32 v59, v75, v59, vcc
	v_cmp_le_f32_e32 vcc, 0, v60
	s_nop 1
	v_cndmask_b32_e32 v58, v74, v58, vcc
	v_mul_f32_e32 v72, v58, v76
	v_mul_f32_e32 v73, v59, v77

.LBB0_664:
	v_mov_b32_e32 v68, v164
	v_mov_b32_e32 v69, v164
	v_mul_f32_e32 v70, v68, v64
	v_mul_f32_e32 v71, v69, v65
	v_mul_f32_e32 v66, v164, v62
	v_mul_f32_e32 v67, v165, v63
	v_mul_f32_e32 v72, v68, v60
	v_mul_f32_e32 v73, v69, v61
	v_mul_f32_e32 v68, v164, v58
	v_mul_f32_e32 v69, v165, v59
	s_mov_b64 s[0:1], 0

.LBB0_672:
	v_mul_f32_e32 v0, 0xbfb8aa3b, v54
	v_exp_f32_e32 v0, v0
	v_mul_f32_e32 v58, 0xbfb8aa3b, v50
	v_mul_f32_e32 v61, 0xbfb8aa3b, v56
	v_mul_f32_e32 v59, 0xbfb8aa3b, v55
	v_exp_f32_e32 v60, v58
	v_exp_f32_e32 v61, v61
	v_mul_f32_e32 v62, 0xbfb8aa3b, v52
	v_exp_f32_e32 v59, v59
	v_exp_f32_e32 v63, v62
	v_add_f32_e32 v0, 1.0, v0
	v_rcp_f32_e32 v58, v0
	v_add_f32_e32 v0, 1.0, v60
	v_add_f32_e32 v61, 1.0, v61
	v_rcp_f32_e32 v60, v0
	v_add_f32_e32 v0, 1.0, v59
	v_rcp_f32_e32 v62, v61
	v_add_f32_e32 v61, 1.0, v63
	v_mul_f32_e32 v63, 0xbfb8aa3b, v57
	v_rcp_f32_e32 v59, v0
	v_mul_f32_e32 v0, 0xbfb8aa3b, v51
	v_exp_f32_e32 v63, v63
	v_mul_f32_e32 v64, 0xbfb8aa3b, v53
	v_exp_f32_e32 v0, v0
	v_exp_f32_e32 v65, v64
	v_rcp_f32_e32 v64, v61
	v_add_f32_e32 v61, 1.0, v63
	v_add_f32_e32 v0, 1.0, v0
	v_rcp_f32_e32 v63, v61
	v_add_f32_e32 v61, 1.0, v65
	v_rcp_f32_e32 v65, v61
	v_rcp_f32_e32 v61, v0
	v_mul_f32_e32 v62, v56, v62
	v_mul_f32_e32 v63, v57, v63
	v_mul_f32_e32 v58, v54, v58
	v_mul_f32_e32 v59, v55, v59
	v_mul_f32_e32 v64, v52, v64
	v_mul_f32_e32 v65, v53, v65
	v_mul_f32_e32 v60, v50, v60
	v_mul_f32_e32 v61, v51, v61

.LBB0_674:
	s_and_b64 vcc, exec, s[0:1]
	s_cbranch_vccz .LBB0_676
	v_mul_f32_e64 v0, |v54|, s33
	v_exp_f32_e32 v58, v0
	v_mul_f32_e64 v0, |v50|, s33
	v_mul_f32_e64 v59, |v55|, s33
	v_exp_f32_e32 v60, v0
	v_exp_f32_e32 v59, v59
	v_add_f32_e32 v0, 1.0, v58
	v_rcp_f32_e32 v62, v0
	v_add_f32_e32 v0, 1.0, v60
	v_rcp_f32_e32 v66, v0
	v_add_f32_e32 v0, 1.0, v59
	v_rcp_f32_e32 v63, v0
	v_mul_f32_e64 v0, |v51|, s33
	v_exp_f32_e32 v61, v0
	v_cmp_le_f32_e32 vcc, 0, v55
	v_mul_f32_e32 v58, v58, v62
	v_mul_f32_e32 v59, v59, v63
	v_sub_f32_e32 v64, 1.0, v18
	v_sub_f32_e32 v65, 1.0, v19
	v_add_f32_e32 v0, 1.0, v61
	v_rcp_f32_e32 v67, v0
	v_cndmask_b32_e32 v55, v63, v59, vcc
	v_cmp_le_f32_e32 vcc, 0, v54
	v_mul_f32_e64 v0, |v56|, s33
	v_sub_f32_e32 v68, 1.0, v22
	v_sub_f32_e32 v69, 1.0, v23
	v_cndmask_b32_e32 v54, v62, v58, vcc
	v_exp_f32_e32 v62, v0
	v_mul_f32_e32 v58, v54, v64
	v_mul_f32_e32 v59, v55, v65
	v_mul_f32_e32 v54, v60, v66
	v_mul_f32_e32 v55, v61, v67
	v_cmp_le_f32_e32 vcc, 0, v51
	v_add_f32_e32 v0, 1.0, v62
	v_sub_f32_e32 v64, 1.0, v20
	v_sub_f32_e32 v65, 1.0, v21
	v_cndmask_b32_e32 v51, v67, v55, vcc
	v_cmp_le_f32_e32 vcc, 0, v50
	s_nop 1
	v_cndmask_b32_e32 v50, v66, v54, vcc
	v_mul_f32_e32 v60, v50, v68
	v_mul_f32_e32 v61, v51, v69
	v_rcp_f32_e32 v50, v0
	v_mul_f32_e64 v0, |v52|, s33
	v_exp_f32_e32 v54, v0
	v_mul_f32_e64 v0, |v57|, s33
	v_exp_f32_e32 v63, v0
	v_cmp_le_f32_e32 vcc, 0, v57
	v_add_f32_e32 v0, 1.0, v54
	v_rcp_f32_e32 v66, v0
	v_add_f32_e32 v0, 1.0, v63
	v_rcp_f32_e32 v51, v0
	v_mul_f32_e64 v0, |v53|, s33
	v_exp_f32_e32 v55, v0
	v_sub_f32_e32 v68, 1.0, v24
	v_sub_f32_e32 v69, 1.0, v25
	v_mul_f32_e32 v62, v62, v50
	v_mul_f32_e32 v63, v63, v51
	v_add_f32_e32 v0, 1.0, v55
	v_rcp_f32_e32 v67, v0
	v_cndmask_b32_e32 v51, v51, v63, vcc
	v_cmp_le_f32_e32 vcc, 0, v56
	s_nop 1
	v_cndmask_b32_e32 v50, v50, v62, vcc
	v_mul_f32_e32 v62, v50, v64
	v_mul_f32_e32 v63, v51, v65
	v_mul_f32_e32 v50, v54, v66
	v_mul_f32_e32 v51, v55, v67
	v_cmp_le_f32_e32 vcc, 0, v53
	s_nop 1
	v_cndmask_b32_e32 v51, v67, v51, vcc
	v_cmp_le_f32_e32 vcc, 0, v52
	s_nop 1
	v_cndmask_b32_e32 v50, v66, v50, vcc
	v_mul_f32_e32 v64, v50, v68
	v_mul_f32_e32 v65, v51, v69

.LBB0_682:
	v_mov_b32_e32 v60, v164
	v_mov_b32_e32 v61, v164
	v_mul_f32_e32 v62, v60, v56
	v_mul_f32_e32 v63, v61, v57
	v_mul_f32_e32 v58, v164, v54
	v_mul_f32_e32 v59, v165, v55
	v_mul_f32_e32 v64, v60, v52
	v_mul_f32_e32 v65, v61, v53
	v_mul_f32_e32 v60, v164, v50
	v_mul_f32_e32 v61, v165, v51
	s_mov_b64 s[0:1], 0

.LBB0_690:
	v_mul_f32_e32 v0, 0xbfb8aa3b, v46
	v_exp_f32_e32 v0, v0
	v_mul_f32_e32 v50, 0xbfb8aa3b, v42
	v_mul_f32_e32 v53, 0xbfb8aa3b, v48
	v_mul_f32_e32 v51, 0xbfb8aa3b, v47
	v_exp_f32_e32 v52, v50
	v_exp_f32_e32 v53, v53
	v_mul_f32_e32 v54, 0xbfb8aa3b, v44
	v_exp_f32_e32 v51, v51
	v_exp_f32_e32 v55, v54
	v_add_f32_e32 v0, 1.0, v0
	v_rcp_f32_e32 v50, v0
	v_add_f32_e32 v0, 1.0, v52
	v_add_f32_e32 v53, 1.0, v53
	v_rcp_f32_e32 v52, v0
	v_add_f32_e32 v0, 1.0, v51
	v_rcp_f32_e32 v54, v53
	v_add_f32_e32 v53, 1.0, v55
	v_mul_f32_e32 v55, 0xbfb8aa3b, v49
	v_rcp_f32_e32 v51, v0
	v_mul_f32_e32 v0, 0xbfb8aa3b, v43
	v_exp_f32_e32 v55, v55
	v_mul_f32_e32 v56, 0xbfb8aa3b, v45
	v_exp_f32_e32 v0, v0
	v_exp_f32_e32 v57, v56
	v_rcp_f32_e32 v56, v53
	v_add_f32_e32 v53, 1.0, v55
	v_add_f32_e32 v0, 1.0, v0
	v_rcp_f32_e32 v55, v53
	v_add_f32_e32 v53, 1.0, v57
	v_rcp_f32_e32 v57, v53
	v_rcp_f32_e32 v53, v0
	v_mul_f32_e32 v54, v48, v54
	v_mul_f32_e32 v55, v49, v55
	v_mul_f32_e32 v50, v46, v50
	v_mul_f32_e32 v51, v47, v51
	v_mul_f32_e32 v56, v44, v56
	v_mul_f32_e32 v57, v45, v57
	v_mul_f32_e32 v52, v42, v52
	v_mul_f32_e32 v53, v43, v53

.LBB0_692:
	s_and_b64 vcc, exec, s[0:1]
	s_cbranch_vccz .LBB0_694
	v_mul_f32_e64 v0, |v46|, s33
	v_exp_f32_e32 v50, v0
	v_cmp_le_f32_e32 vcc, 0, v46
	v_cmp_le_f32_e64 s[6:7], 0, v47
	v_sub_f32_e32 v58, 1.0, v38
	v_sub_f32_e32 v59, 1.0, v39
	v_add_f32_e32 v0, 1.0, v50
	v_rcp_f32_e32 v52, v0
	v_mul_f32_e64 v0, |v42|, s33
	v_exp_f32_e32 v54, v0
	v_sub_f32_e32 v60, 1.0, v40
	v_sub_f32_e32 v61, 1.0, v41
	v_add_f32_e32 v0, 1.0, v54
	v_rcp_f32_e32 v56, v0
	v_mul_f32_e64 v0, |v47|, s33
	v_exp_f32_e32 v51, v0
	s_nop 0
	v_add_f32_e32 v0, 1.0, v51
	v_rcp_f32_e32 v53, v0
	v_mul_f32_e64 v0, |v43|, s33
	v_exp_f32_e32 v55, v0
	v_mul_f32_e32 v50, v50, v52
	v_mul_f32_e32 v51, v51, v53
	s_nop 0
	v_cndmask_b32_e64 v47, v53, v51, s[6:7]
	v_add_f32_e32 v0, 1.0, v55
	v_rcp_f32_e32 v57, v0
	v_cndmask_b32_e32 v46, v52, v50, vcc
	v_mul_f32_e32 v50, v46, v166
	v_mul_f32_e32 v51, v47, v167
	v_cmp_le_f32_e32 vcc, 0, v42
	v_mul_f32_e32 v46, v54, v56
	v_mul_f32_e32 v47, v55, v57
	v_cmp_le_f32_e64 s[6:7], 0, v43
	v_cndmask_b32_e32 v42, v56, v46, vcc
	v_mul_f32_e64 v0, |v48|, s33
	v_cndmask_b32_e64 v43, v57, v47, s[6:7]
	v_mul_f32_e32 v52, v42, v58
	v_mul_f32_e32 v53, v43, v59
	v_exp_f32_e32 v42, v0
	v_cmp_le_f32_e32 vcc, 0, v48
	v_cmp_le_f32_e64 s[6:7], 0, v49
	v_sub_f32_e32 v54, 1.0, v36
	v_sub_f32_e32 v55, 1.0, v37
	v_add_f32_e32 v0, 1.0, v42
	v_rcp_f32_e32 v46, v0
	v_mul_f32_e64 v0, |v44|, s33
	v_exp_f32_e32 v56, v0
	s_nop 0
	v_add_f32_e32 v0, 1.0, v56
	v_rcp_f32_e32 v58, v0
	v_mul_f32_e64 v0, |v49|, s33
	v_exp_f32_e32 v43, v0
	s_nop 0
	v_add_f32_e32 v0, 1.0, v43
	v_rcp_f32_e32 v47, v0
	v_mul_f32_e64 v0, |v45|, s33
	v_exp_f32_e32 v57, v0
	v_mul_f32_e32 v42, v42, v46
	v_mul_f32_e32 v43, v43, v47
	s_nop 0
	v_cndmask_b32_e64 v43, v47, v43, s[6:7]
	v_add_f32_e32 v0, 1.0, v57
	v_rcp_f32_e32 v59, v0
	v_cndmask_b32_e32 v42, v46, v42, vcc
	v_mul_f32_e32 v54, v42, v54
	v_mul_f32_e32 v55, v43, v55
	v_cmp_le_f32_e32 vcc, 0, v44
	v_mul_f32_e32 v42, v56, v58
	v_mul_f32_e32 v43, v57, v59
	v_cmp_le_f32_e64 s[6:7], 0, v45
	v_cndmask_b32_e32 v42, v58, v42, vcc
	s_nop 0
	v_cndmask_b32_e64 v43, v59, v43, s[6:7]
	v_mul_f32_e32 v56, v42, v60
	v_mul_f32_e32 v57, v43, v61

.LBB0_700:
	v_mov_b32_e32 v52, v164
	v_mov_b32_e32 v53, v164
	v_mul_f32_e32 v54, v52, v48
	v_mul_f32_e32 v55, v53, v49
	v_mul_f32_e32 v50, v164, v46
	v_mul_f32_e32 v51, v165, v47
	v_mul_f32_e32 v56, v52, v44
	v_mul_f32_e32 v57, v53, v45
	v_mul_f32_e32 v52, v164, v42
	v_mul_f32_e32 v53, v165, v43
	s_mov_b64 s[0:1], 0

.LBB0_708:
	v_mul_f32_e32 v0, 0xbfb8aa3b, v30
	v_exp_f32_e32 v0, v0
	v_mul_f32_e32 v42, 0xbfb8aa3b, v26
	v_mul_f32_e32 v45, 0xbfb8aa3b, v32
	v_mul_f32_e32 v43, 0xbfb8aa3b, v31
	v_exp_f32_e32 v44, v42
	v_exp_f32_e32 v45, v45
	v_mul_f32_e32 v46, 0xbfb8aa3b, v28
	v_exp_f32_e32 v43, v43
	v_exp_f32_e32 v47, v46
	v_add_f32_e32 v0, 1.0, v0
	v_rcp_f32_e32 v42, v0
	v_add_f32_e32 v0, 1.0, v44
	v_add_f32_e32 v45, 1.0, v45
	v_rcp_f32_e32 v44, v0
	v_add_f32_e32 v0, 1.0, v43
	v_rcp_f32_e32 v46, v45
	v_add_f32_e32 v45, 1.0, v47
	v_mul_f32_e32 v47, 0xbfb8aa3b, v33
	v_rcp_f32_e32 v43, v0
	v_mul_f32_e32 v0, 0xbfb8aa3b, v27
	v_exp_f32_e32 v47, v47
	v_mul_f32_e32 v48, 0xbfb8aa3b, v29
	v_exp_f32_e32 v0, v0
	v_exp_f32_e32 v49, v48
	v_rcp_f32_e32 v48, v45
	v_add_f32_e32 v45, 1.0, v47
	v_add_f32_e32 v0, 1.0, v0
	v_rcp_f32_e32 v47, v45
	v_add_f32_e32 v45, 1.0, v49
	v_rcp_f32_e32 v49, v45
	v_rcp_f32_e32 v45, v0
	v_mul_f32_e32 v46, v32, v46
	v_mul_f32_e32 v47, v33, v47
	v_mul_f32_e32 v42, v30, v42
	v_mul_f32_e32 v43, v31, v43
	v_mul_f32_e32 v48, v28, v48
	v_mul_f32_e32 v49, v29, v49
	v_mul_f32_e32 v44, v26, v44
	v_mul_f32_e32 v45, v27, v45

.LBB0_710:
	s_and_b64 vcc, exec, s[0:1]
	s_cbranch_vccz .LBB0_712
	v_mul_f32_e64 v0, |v30|, s33
	v_exp_f32_e32 v42, v0
	v_mul_f32_e64 v0, |v26|, s33
	v_mul_f32_e64 v43, |v31|, s33
	v_exp_f32_e32 v44, v0
	v_exp_f32_e32 v43, v43
	v_add_f32_e32 v0, 1.0, v42
	v_rcp_f32_e32 v46, v0
	v_add_f32_e32 v0, 1.0, v44
	v_rcp_f32_e32 v50, v0
	v_add_f32_e32 v0, 1.0, v43
	v_rcp_f32_e32 v47, v0
	v_mul_f32_e64 v0, |v27|, s33
	v_exp_f32_e32 v45, v0
	v_cmp_le_f32_e32 vcc, 0, v31
	v_mul_f32_e32 v42, v42, v46
	v_mul_f32_e32 v43, v43, v47
	v_sub_f32_e32 v48, 1.0, v18
	v_sub_f32_e32 v49, 1.0, v19
	v_add_f32_e32 v0, 1.0, v45
	v_rcp_f32_e32 v51, v0
	v_cndmask_b32_e32 v31, v47, v43, vcc
	v_cmp_le_f32_e32 vcc, 0, v30
	v_mul_f32_e64 v0, |v32|, s33
	v_sub_f32_e32 v52, 1.0, v22
	v_sub_f32_e32 v53, 1.0, v23
	v_cndmask_b32_e32 v30, v46, v42, vcc
	v_exp_f32_e32 v46, v0
	v_mul_f32_e32 v42, v30, v48
	v_mul_f32_e32 v43, v31, v49
	v_mul_f32_e32 v30, v44, v50
	v_mul_f32_e32 v31, v45, v51
	v_cmp_le_f32_e32 vcc, 0, v27
	v_add_f32_e32 v0, 1.0, v46
	v_sub_f32_e32 v48, 1.0, v20
	v_sub_f32_e32 v49, 1.0, v21
	v_cndmask_b32_e32 v27, v51, v31, vcc
	v_cmp_le_f32_e32 vcc, 0, v26
	s_nop 1
	v_cndmask_b32_e32 v26, v50, v30, vcc
	v_mul_f32_e32 v44, v26, v52
	v_mul_f32_e32 v45, v27, v53
	v_rcp_f32_e32 v26, v0
	v_mul_f32_e64 v0, |v28|, s33
	v_exp_f32_e32 v30, v0
	v_mul_f32_e64 v0, |v33|, s33
	v_exp_f32_e32 v47, v0
	v_cmp_le_f32_e32 vcc, 0, v33
	v_add_f32_e32 v0, 1.0, v30
	v_rcp_f32_e32 v50, v0
	v_add_f32_e32 v0, 1.0, v47
	v_rcp_f32_e32 v27, v0
	v_mul_f32_e64 v0, |v29|, s33
	v_exp_f32_e32 v31, v0
	v_sub_f32_e32 v52, 1.0, v24
	v_sub_f32_e32 v53, 1.0, v25
	v_mul_f32_e32 v46, v46, v26
	v_mul_f32_e32 v47, v47, v27
	v_add_f32_e32 v0, 1.0, v31
	v_rcp_f32_e32 v51, v0
	v_cndmask_b32_e32 v27, v27, v47, vcc
	v_cmp_le_f32_e32 vcc, 0, v32
	s_nop 1
	v_cndmask_b32_e32 v26, v26, v46, vcc
	v_mul_f32_e32 v46, v26, v48
	v_mul_f32_e32 v47, v27, v49
	v_mul_f32_e32 v26, v30, v50
	v_mul_f32_e32 v27, v31, v51
	v_cmp_le_f32_e32 vcc, 0, v29
	s_nop 1
	v_cndmask_b32_e32 v27, v51, v27, vcc
	v_cmp_le_f32_e32 vcc, 0, v28
	s_nop 1
	v_cndmask_b32_e32 v26, v50, v26, vcc
	v_mul_f32_e32 v48, v26, v52
	v_mul_f32_e32 v49, v27, v53

.LBB0_718:
	v_mov_b32_e32 v44, v164
	v_mov_b32_e32 v45, v164
	v_mul_f32_e32 v46, v44, v32
	v_mul_f32_e32 v47, v45, v33
	v_mul_f32_e32 v42, v164, v30
	v_mul_f32_e32 v43, v165, v31
	v_mul_f32_e32 v48, v44, v28
	v_mul_f32_e32 v49, v45, v29
	v_mul_f32_e32 v44, v164, v26
	v_mul_f32_e32 v45, v165, v27
	s_mov_b64 s[0:1], 0

.LBB0_726:
	v_mul_f32_e32 v0, 0xbfb8aa3b, v14
	v_exp_f32_e32 v0, v0
	v_mul_f32_e32 v26, 0xbfb8aa3b, v10
	v_mul_f32_e32 v29, 0xbfb8aa3b, v16
	v_mul_f32_e32 v27, 0xbfb8aa3b, v15
	v_exp_f32_e32 v28, v26
	v_exp_f32_e32 v29, v29
	v_mul_f32_e32 v30, 0xbfb8aa3b, v12
	v_exp_f32_e32 v27, v27
	v_exp_f32_e32 v31, v30
	v_add_f32_e32 v0, 1.0, v0
	v_rcp_f32_e32 v26, v0
	v_add_f32_e32 v0, 1.0, v28
	v_add_f32_e32 v29, 1.0, v29
	v_rcp_f32_e32 v28, v0
	v_add_f32_e32 v0, 1.0, v27
	v_rcp_f32_e32 v30, v29
	v_add_f32_e32 v29, 1.0, v31
	v_mul_f32_e32 v31, 0xbfb8aa3b, v17
	v_rcp_f32_e32 v27, v0
	v_mul_f32_e32 v0, 0xbfb8aa3b, v11
	v_exp_f32_e32 v31, v31
	v_mul_f32_e32 v32, 0xbfb8aa3b, v13
	v_exp_f32_e32 v0, v0
	v_exp_f32_e32 v33, v32
	v_rcp_f32_e32 v32, v29
	v_add_f32_e32 v29, 1.0, v31
	v_add_f32_e32 v0, 1.0, v0
	v_rcp_f32_e32 v31, v29
	v_add_f32_e32 v29, 1.0, v33
	v_rcp_f32_e32 v33, v29
	v_rcp_f32_e32 v29, v0
	v_mul_f32_e32 v30, v16, v30
	v_mul_f32_e32 v31, v17, v31
	v_mul_f32_e32 v26, v14, v26
	v_mul_f32_e32 v27, v15, v27
	v_mul_f32_e32 v32, v12, v32
	v_mul_f32_e32 v33, v13, v33
	v_mul_f32_e32 v28, v10, v28
	v_mul_f32_e32 v29, v11, v29

.LBB0_728:
	s_and_b64 vcc, exec, s[0:1]
	s_cbranch_vccz .LBB0_730
	v_mul_f32_e64 v0, |v14|, s33
	v_exp_f32_e32 v26, v0
	v_mul_f32_e64 v0, |v10|, s33
	v_mul_f32_e64 v27, |v15|, s33
	v_exp_f32_e32 v28, v0
	v_exp_f32_e32 v27, v27
	v_add_f32_e32 v0, 1.0, v26
	v_rcp_f32_e32 v30, v0
	v_add_f32_e32 v0, 1.0, v28
	v_rcp_f32_e32 v32, v0
	v_add_f32_e32 v0, 1.0, v27
	v_rcp_f32_e32 v31, v0
	v_mul_f32_e64 v0, |v11|, s33
	v_exp_f32_e32 v29, v0
	v_cmp_le_f32_e32 vcc, 0, v15
	v_mul_f32_e32 v26, v26, v30
	v_mul_f32_e32 v27, v27, v31
	v_sub_f32_e32 v38, 1.0, v38
	v_sub_f32_e32 v39, 1.0, v39
	v_add_f32_e32 v0, 1.0, v29
	v_rcp_f32_e32 v33, v0
	v_cndmask_b32_e32 v15, v31, v27, vcc
	v_cmp_le_f32_e32 vcc, 0, v14
	v_mul_f32_e64 v0, |v16|, s33
	s_nop 0
	v_cndmask_b32_e32 v14, v30, v26, vcc
	v_exp_f32_e32 v30, v0
	v_mul_f32_e32 v26, v14, v166
	v_mul_f32_e32 v27, v15, v167
	v_mul_f32_e32 v14, v28, v32
	v_mul_f32_e32 v15, v29, v33
	v_cmp_le_f32_e32 vcc, 0, v11
	v_add_f32_e32 v0, 1.0, v30
	s_nop 0
	v_cndmask_b32_e32 v11, v33, v15, vcc
	v_cmp_le_f32_e32 vcc, 0, v10
	s_nop 1
	v_cndmask_b32_e32 v10, v32, v14, vcc
	v_mul_f32_e32 v28, v10, v38
	v_mul_f32_e32 v29, v11, v39
	v_rcp_f32_e32 v10, v0
	v_mul_f32_e64 v0, |v12|, s33
	v_exp_f32_e32 v14, v0
	v_mul_f32_e64 v0, |v17|, s33
	v_exp_f32_e32 v31, v0
	v_sub_f32_e32 v32, 1.0, v36
	v_sub_f32_e32 v33, 1.0, v37
	v_add_f32_e32 v0, 1.0, v14
	v_rcp_f32_e32 v36, v0
	v_add_f32_e32 v0, 1.0, v31
	v_rcp_f32_e32 v11, v0
	v_mul_f32_e64 v0, |v13|, s33
	v_exp_f32_e32 v15, v0
	v_cmp_le_f32_e32 vcc, 0, v17
	v_mul_f32_e32 v30, v30, v10
	v_mul_f32_e32 v31, v31, v11
	v_sub_f32_e32 v38, 1.0, v40
	v_sub_f32_e32 v39, 1.0, v41
	v_add_f32_e32 v0, 1.0, v15
	v_rcp_f32_e32 v37, v0
	v_cndmask_b32_e32 v11, v11, v31, vcc
	v_cmp_le_f32_e32 vcc, 0, v16
	s_nop 1
	v_cndmask_b32_e32 v10, v10, v30, vcc
	v_mul_f32_e32 v30, v10, v32
	v_mul_f32_e32 v31, v11, v33
	v_mul_f32_e32 v10, v14, v36
	v_mul_f32_e32 v11, v15, v37
	v_cmp_le_f32_e32 vcc, 0, v13
	s_nop 1
	v_cndmask_b32_e32 v11, v37, v11, vcc
	v_cmp_le_f32_e32 vcc, 0, v12
	s_nop 1
	v_cndmask_b32_e32 v10, v36, v10, vcc
	v_mul_f32_e32 v32, v10, v38
	v_mul_f32_e32 v33, v11, v39

.LBB0_736:
	v_mov_b32_e32 v28, v164
	v_mov_b32_e32 v29, v164
	v_mul_f32_e32 v30, v28, v16
	v_mul_f32_e32 v31, v29, v17
	v_mul_f32_e32 v26, v164, v14
	v_mul_f32_e32 v27, v165, v15
	v_mul_f32_e32 v32, v28, v12
	v_mul_f32_e32 v33, v29, v13
	v_mul_f32_e32 v28, v164, v10
	v_mul_f32_e32 v29, v165, v11
	s_mov_b64 s[0:1], 0

.LBB0_744:
	v_mul_f32_e32 v0, 0xbfb8aa3b, v6
	v_exp_f32_e32 v0, v0
	v_mul_f32_e32 v10, 0xbfb8aa3b, v2
	v_mul_f32_e32 v13, 0xbfb8aa3b, v8
	v_mul_f32_e32 v11, 0xbfb8aa3b, v7
	v_exp_f32_e32 v12, v10
	v_exp_f32_e32 v13, v13
	v_mul_f32_e32 v14, 0xbfb8aa3b, v4
	v_exp_f32_e32 v11, v11
	v_exp_f32_e32 v15, v14
	v_add_f32_e32 v0, 1.0, v0
	v_rcp_f32_e32 v10, v0
	v_add_f32_e32 v0, 1.0, v12
	v_add_f32_e32 v13, 1.0, v13
	v_rcp_f32_e32 v12, v0
	v_add_f32_e32 v0, 1.0, v11
	v_rcp_f32_e32 v14, v13
	v_add_f32_e32 v13, 1.0, v15
	v_mul_f32_e32 v15, 0xbfb8aa3b, v9
	v_rcp_f32_e32 v11, v0
	v_mul_f32_e32 v0, 0xbfb8aa3b, v3
	v_exp_f32_e32 v15, v15
	v_mul_f32_e32 v16, 0xbfb8aa3b, v5
	v_exp_f32_e32 v0, v0
	v_exp_f32_e32 v17, v16
	v_rcp_f32_e32 v16, v13
	v_add_f32_e32 v13, 1.0, v15
	v_add_f32_e32 v0, 1.0, v0
	v_rcp_f32_e32 v15, v13
	v_add_f32_e32 v13, 1.0, v17
	v_rcp_f32_e32 v17, v13
	v_rcp_f32_e32 v13, v0
	v_mul_f32_e32 v14, v8, v14
	v_mul_f32_e32 v15, v9, v15
	v_mul_f32_e32 v10, v6, v10
	v_mul_f32_e32 v11, v7, v11
	v_mul_f32_e32 v16, v4, v16
	v_mul_f32_e32 v17, v5, v17
	v_mul_f32_e32 v12, v2, v12
	v_mul_f32_e32 v13, v3, v13

.LBB0_746:
	s_and_b64 vcc, exec, s[0:1]
	s_cbranch_vccz .LBB0_748
	v_mul_f32_e64 v0, |v6|, s33
	v_exp_f32_e32 v10, v0
	v_mul_f32_e64 v0, |v2|, s33
	v_mul_f32_e64 v11, |v7|, s33
	v_exp_f32_e32 v12, v0
	v_exp_f32_e32 v11, v11
	v_add_f32_e32 v0, 1.0, v10
	v_rcp_f32_e32 v14, v0
	v_add_f32_e32 v0, 1.0, v12
	v_sub_f32_e32 v16, 1.0, v18
	v_sub_f32_e32 v17, 1.0, v19
	v_rcp_f32_e32 v18, v0
	v_add_f32_e32 v0, 1.0, v11
	v_rcp_f32_e32 v15, v0
	v_mul_f32_e64 v0, |v3|, s33
	v_exp_f32_e32 v13, v0
	v_cmp_le_f32_e32 vcc, 0, v7
	v_mul_f32_e32 v10, v10, v14
	v_mul_f32_e32 v11, v11, v15
	v_sub_f32_e32 v22, 1.0, v22
	v_sub_f32_e32 v23, 1.0, v23
	v_add_f32_e32 v0, 1.0, v13
	v_rcp_f32_e32 v19, v0
	v_cndmask_b32_e32 v7, v15, v11, vcc
	v_cmp_le_f32_e32 vcc, 0, v6
	v_mul_f32_e64 v0, |v8|, s33
	s_nop 0
	v_cndmask_b32_e32 v6, v14, v10, vcc
	v_exp_f32_e32 v14, v0
	v_mul_f32_e32 v10, v6, v16
	v_mul_f32_e32 v11, v7, v17
	v_mul_f32_e32 v6, v12, v18
	v_mul_f32_e32 v7, v13, v19
	v_cmp_le_f32_e32 vcc, 0, v3
	v_add_f32_e32 v0, 1.0, v14
	v_sub_f32_e32 v16, 1.0, v20
	v_sub_f32_e32 v17, 1.0, v21
	v_cndmask_b32_e32 v3, v19, v7, vcc
	v_cmp_le_f32_e32 vcc, 0, v2
	v_sub_f32_e32 v20, 1.0, v24
	v_sub_f32_e32 v21, 1.0, v25
	s_nop 0
	v_cndmask_b32_e32 v2, v18, v6, vcc
	v_mul_f32_e32 v12, v2, v22
	v_mul_f32_e32 v13, v3, v23
	v_rcp_f32_e32 v2, v0
	v_mul_f32_e64 v0, |v4|, s33
	v_exp_f32_e32 v6, v0
	v_mul_f32_e64 v0, |v9|, s33
	v_exp_f32_e32 v15, v0
	v_cmp_le_f32_e32 vcc, 0, v9
	v_add_f32_e32 v0, 1.0, v6
	v_rcp_f32_e32 v18, v0
	v_add_f32_e32 v0, 1.0, v15
	v_rcp_f32_e32 v3, v0
	v_mul_f32_e64 v0, |v5|, s33
	v_exp_f32_e32 v7, v0
	v_mul_f32_e32 v14, v14, v2
	v_mul_f32_e32 v15, v15, v3
	s_nop 0
	v_cndmask_b32_e32 v3, v3, v15, vcc
	v_add_f32_e32 v0, 1.0, v7
	v_rcp_f32_e32 v19, v0
	v_cmp_le_f32_e32 vcc, 0, v8
	s_nop 1
	v_cndmask_b32_e32 v2, v2, v14, vcc
	v_mul_f32_e32 v14, v2, v16
	v_mul_f32_e32 v15, v3, v17
	v_mul_f32_e32 v2, v6, v18
	v_mul_f32_e32 v3, v7, v19
	v_cmp_le_f32_e32 vcc, 0, v5
	s_nop 1
	v_cndmask_b32_e32 v3, v19, v3, vcc
	v_cmp_le_f32_e32 vcc, 0, v4
	s_nop 1
	v_cndmask_b32_e32 v2, v18, v2, vcc
	v_mul_f32_e32 v16, v2, v20
	v_mul_f32_e32 v17, v3, v21

.LBB0_754:
	v_mov_b32_e32 v12, v164
	v_mov_b32_e32 v13, v164
	v_mul_f32_e32 v14, v12, v8
	v_mul_f32_e32 v15, v13, v9
	v_mul_f32_e32 v10, v164, v6
	v_mul_f32_e32 v11, v165, v7
	v_mul_f32_e32 v16, v12, v4
	v_mul_f32_e32 v17, v13, v5
	v_mul_f32_e32 v12, v164, v2
	v_mul_f32_e32 v13, v165, v3
	s_mov_b64 s[0:1], 0

.LBB0_826:
	v_lshlrev_b32_e32 v88, 2, v86
	s_waitcnt vmcnt(9)
	v_add_f32_e32 v80, 1.0, v80
	v_add_f32_e32 v81, 1.0, v81
	v_add_f32_e32 v86, 1.0, v78
	v_add_f32_e32 v87, 1.0, v79
	v_mul_f32_e32 v78, v68, v80
	v_mul_f32_e32 v79, v69, v81
	v_mul_f32_e32 v80, v66, v86
	v_mul_f32_e32 v81, v67, v87
	s_waitcnt vmcnt(8)
	v_add_f32_e32 v66, 1.0, v72
	v_add_f32_e32 v67, 1.0, v73
	v_add_f32_e32 v68, 1.0, v70
	v_add_f32_e32 v69, 1.0, v71
	s_waitcnt vmcnt(7)
	v_mul_f32_e32 v70, v48, v48
	v_mul_f32_e32 v71, v49, v49
	v_mul_f32_e32 v72, v46, v46
	v_mul_f32_e32 v73, v47, v47
	v_mul_f32_e32 v66, v56, v66
	v_mul_f32_e32 v67, v57, v67
	s_waitcnt vmcnt(3)
	v_add_f32_e32 v56, 1.0, v74
	v_add_f32_e32 v57, 1.0, v75
	v_pk_mov_b32 v[74:75], v[72:73], v[70:71] op_sel:[1,0]
	v_mov_b32_e32 v73, v71
	v_add_f32_e32 v70, v74, v72
	v_add_f32_e32 v71, v75, v73
	v_mul_f32_e32 v72, v40, v40
	v_mul_f32_e32 v73, v41, v41
	v_mul_f32_e32 v74, v38, v38
	v_mul_f32_e32 v75, v39, v39
	v_mul_f32_e32 v68, v54, v68
	v_mul_f32_e32 v69, v55, v69
	v_add_f32_e32 v54, 1.0, v76
	v_add_f32_e32 v55, 1.0, v77
	v_pk_mov_b32 v[76:77], v[74:75], v[72:73] op_sel:[1,0]
	v_mov_b32_e32 v75, v73
	v_mul_f32_e32 v56, v58, v56
	v_mul_f32_e32 v57, v59, v57
	s_waitcnt vmcnt(2)
	v_add_f32_e32 v58, 1.0, v64
	v_add_f32_e32 v59, 1.0, v65
	v_add_f32_e32 v72, v76, v74
	v_add_f32_e32 v73, v77, v75
	v_mul_f32_e32 v52, v52, v58
	v_mul_f32_e32 v53, v53, v59
	s_waitcnt lgkmcnt(0)
	v_lshl_add_u64 v[58:59], s[6:7], 0, v[0:1]
	v_mul_f32_e32 v0, v34, v34
	v_mul_f32_e32 v74, v35, v35
	v_pk_add_f32 v[70:71], v[70:71], v[70:71] op_sel:[0,1] op_sel_hi:[1,0]
	v_pk_add_f32 v[72:73], v[72:73], v[72:73] op_sel:[0,1] op_sel_hi:[1,0]
	v_mov_b32_e32 v71, v0
	v_mov_b32_e32 v73, v74
	v_mul_f32_e32 v0, v43, v43
	v_mul_f32_e32 v75, v36, v36
	v_add_f32_e32 v70, v70, v72
	v_add_f32_e32 v71, v71, v73
	v_fma_f32 v72, v42, v42, v0
	v_fma_f32 v73, v43, v43, v0
	v_mul_f32_e32 v0, v45, v45
	v_mul_f32_e32 v76, v37, v37
	v_mov_b32_e32 v73, v75
	v_fma_f32 v74, v44, v44, v0
	v_fma_f32 v75, v45, v45, v0
	v_xor_b32_e32 v65, 4, v88
	v_mov_b32_e32 v75, v76
	v_add_f32_e32 v72, v72, v74
	v_add_f32_e32 v73, v73, v75
	v_xor_b32_e32 v64, 8, v88
	v_add_f32_e32 v70, v70, v72
	v_add_f32_e32 v71, v71, v73
	v_mul_f32_e32 v72, v30, v30
	v_mul_f32_e32 v73, v31, v31
	v_add_f32_e32 v0, v70, v71
	ds_bpermute_b32 v76, v65, v0
	v_mul_f32_e32 v70, v32, v32
	v_mul_f32_e32 v71, v33, v33
	v_mul_f32_e32 v54, v60, v54
	v_mul_f32_e32 v55, v61, v55
	v_pk_mov_b32 v[74:75], v[72:73], v[70:71] op_sel:[1,0]
	v_mov_b32_e32 v73, v71
	s_waitcnt lgkmcnt(0)
	v_add_f32_e32 v0, v0, v76
	ds_bpermute_b32 v86, v64, v0
	v_add_f32_e32 v70, v74, v72
	v_add_f32_e32 v71, v75, v73
	v_mul_f32_e32 v72, v28, v28
	v_mul_f32_e32 v73, v29, v29
	v_mul_f32_e32 v74, v26, v26
	v_mul_f32_e32 v75, v27, v27
	v_add_f32_e32 v60, 1.0, v62
	v_add_f32_e32 v61, 1.0, v63
	v_xor_b32_e32 v63, 16, v88
	v_pk_mov_b32 v[76:77], v[74:75], v[72:73] op_sel:[1,0]
	v_mov_b32_e32 v75, v73
	s_waitcnt lgkmcnt(0)
	v_add_f32_e32 v0, v0, v86
	v_add_f32_e32 v72, v76, v74
	v_add_f32_e32 v73, v77, v75
	ds_bpermute_b32 v74, v63, v0
	v_xor_b32_e32 v62, 32, v88
	v_mul_f32_e32 v50, v50, v60
	v_mul_f32_e32 v51, v51, v61
	v_xor_b32_e32 v61, 64, v88
	s_waitcnt vmcnt(0)
	v_mul_f32_e32 v75, v18, v18
	s_waitcnt lgkmcnt(0)
	v_add_f32_e32 v0, v0, v74
	ds_bpermute_b32 v74, v62, v0
	v_pk_add_f32 v[70:71], v[70:71], v[70:71] op_sel:[0,1] op_sel_hi:[1,0]
	v_mul_f32_e32 v76, v19, v19
	v_mov_b32_e32 v71, v75
	v_pk_add_f32 v[72:73], v[72:73], v[72:73] op_sel:[0,1] op_sel_hi:[1,0]
	s_waitcnt lgkmcnt(0)
	v_add_f32_e32 v74, v0, v74
	ds_bpermute_b32 v75, v61, v74
	v_mov_b32_e32 v73, v76
	v_mul_f32_e32 v0, v23, v23
	v_xor_b32_e32 v60, 0x80, v88
	v_mul_f32_e32 v77, v20, v20
	v_add_f32_e32 v70, v70, v72
	v_add_f32_e32 v71, v71, v73
	v_fma_f32 v72, v22, v22, v0
	v_fma_f32 v73, v23, v23, v0
	s_waitcnt lgkmcnt(0)
	v_add_f32_e32 v76, v74, v75
	v_mov_b32_e32 v73, v77
	ds_bpermute_b32 v77, v60, v76
	v_mul_f32_e32 v0, v25, v25
	v_mul_f32_e32 v86, v21, v21
	v_fma_f32 v74, v24, v24, v0
	v_fma_f32 v75, v25, v25, v0
	s_mov_b64 s[6:7], 0x17200000
	v_mov_b32_e32 v75, v86
	s_waitcnt lgkmcnt(0)
	v_add_f32_e32 v0, v76, v77
	v_add_f32_e32 v72, v72, v74
	v_add_f32_e32 v73, v73, v75
	v_fmamk_f32 v0, v0, 0x3a800000, v230
	v_rsq_f32_e32 v0, v0
	v_add_f32_e32 v70, v70, v72
	v_add_f32_e32 v71, v71, v73
	v_lshl_add_u64 v[58:59], v[58:59], 0, s[6:7]
	v_add_f32_e32 v72, v70, v71
	ds_bpermute_b32 v73, v65, v72
	v_mul_f32_e32 v46, v0, v46
	v_mul_f32_e32 v47, v0, v47
	v_fma_f32 v46, v80, v46, v14
	v_fma_f32 v47, v81, v47, v15
	v_lshl_add_u64 v[70:71], v[58:59], 0, s[2:3]
	v_mul_f32_e32 v48, v0, v48
	v_mul_f32_e32 v49, v0, v49
	v_cvt_pk_bf16_f32 v46, v46, v47
	v_fma_f32 v48, v78, v48, v16
	v_fma_f32 v49, v79, v49, v17
	v_mul_f32_e32 v38, v0, v38
	v_mul_f32_e32 v39, v0, v39
	v_cvt_pk_bf16_f32 v47, v48, v49
	global_store_dwordx2 v[70:71], v[46:47], off
	s_waitcnt lgkmcnt(0)
	v_add_f32_e32 v46, v72, v73
	ds_bpermute_b32 v47, v64, v46
	v_mul_f32_e32 v40, v0, v40
	v_mul_f32_e32 v41, v0, v41
	v_fma_f32 v38, v68, v38, v10
	v_fma_f32 v39, v69, v39, v11
	v_fma_f32 v40, v66, v40, v12
	v_fma_f32 v41, v67, v41, v13
	v_cvt_pk_bf16_f32 v38, v38, v39
	s_waitcnt lgkmcnt(0)
	v_add_f32_e32 v46, v46, v47
	ds_bpermute_b32 v47, v63, v46
	v_cvt_pk_bf16_f32 v39, v40, v41
	global_store_dwordx2 v[70:71], v[38:39], off offset:512
	v_mul_f32_e32 v38, v0, v42
	v_mul_f32_e32 v39, v0, v43
	v_mul_f32_e32 v40, v0, v44
	v_mul_f32_e32 v41, v0, v45
	s_waitcnt lgkmcnt(0)
	v_add_f32_e32 v42, v46, v47
	ds_bpermute_b32 v43, v62, v42
	v_fma_f32 v40, v54, v40, v8
	v_fma_f32 v41, v55, v41, v9
	v_fma_f32 v38, v56, v38, v6
	v_fma_f32 v39, v57, v39, v7
	v_mul_f32_e32 v34, v0, v34
	v_mul_f32_e32 v35, v0, v35
	v_cvt_pk_bf16_f32 v38, v38, v39
	v_cvt_pk_bf16_f32 v39, v40, v41
	s_waitcnt lgkmcnt(0)
	v_add_f32_e32 v40, v42, v43
	ds_bpermute_b32 v41, v61, v40
	v_mul_f32_e32 v36, v0, v36
	v_mul_f32_e32 v37, v0, v37
	global_store_dwordx2 v[70:71], v[38:39], off offset:1024
	s_or_b32 s0, s0, 1
	v_fma_f32 v34, v50, v34, v2
	v_fma_f32 v35, v51, v35, v3
	s_waitcnt lgkmcnt(0)
	v_add_f32_e32 v0, v40, v41
	ds_bpermute_b32 v38, v60, v0
	s_ashr_i32 s1, s0, 31
	v_fma_f32 v36, v52, v36, v4
	v_fma_f32 v37, v53, v37, v5
	v_cvt_pk_bf16_f32 v34, v34, v35
	s_lshl_b64 s[0:1], s[0:1], 11
	s_waitcnt lgkmcnt(0)
	v_add_f32_e32 v0, v0, v38
	v_fmamk_f32 v0, v0, 0x3a800000, v230
	v_rsq_f32_e32 v0, v0
	v_cvt_pk_bf16_f32 v35, v36, v37
	global_store_dwordx2 v[70:71], v[34:35], off offset:1536
	v_lshl_add_u64 v[34:35], v[58:59], 0, s[0:1]
	v_mul_f32_e32 v30, v0, v30
	v_mul_f32_e32 v31, v0, v31
	v_mul_f32_e32 v26, v0, v26
	v_mul_f32_e32 v27, v0, v27
	v_mul_f32_e32 v22, v0, v22
	v_mul_f32_e32 v23, v0, v23
	v_mul_f32_e32 v18, v0, v18
	v_mul_f32_e32 v19, v0, v19
	v_mul_f32_e32 v32, v0, v32
	v_mul_f32_e32 v33, v0, v33
	v_fma_f32 v30, v80, v30, v14
	v_fma_f32 v31, v81, v31, v15
	v_mul_f32_e32 v28, v0, v28
	v_mul_f32_e32 v29, v0, v29
	v_fma_f32 v26, v68, v26, v10
	v_fma_f32 v27, v69, v27, v11
	v_mul_f32_e32 v24, v0, v24
	v_mul_f32_e32 v25, v0, v25
	v_fma_f32 v22, v56, v22, v6
	v_fma_f32 v23, v57, v23, v7
	v_mul_f32_e32 v20, v0, v20
	v_mul_f32_e32 v21, v0, v21
	v_fma_f32 v18, v50, v18, v2
	v_fma_f32 v19, v51, v19, v3
	s_add_i32 s0, s10, 0x8002
	v_fma_f32 v32, v78, v32, v16
	v_fma_f32 v33, v79, v33, v17
	v_cvt_pk_bf16_f32 v30, v30, v31
	v_fma_f32 v28, v66, v28, v12
	v_fma_f32 v29, v67, v29, v13
	v_cvt_pk_bf16_f32 v31, v32, v33
	global_store_dwordx2 v[34:35], v[30:31], off
	v_cvt_pk_bf16_f32 v26, v26, v27
	v_cvt_pk_bf16_f32 v27, v28, v29
	global_store_dwordx2 v[34:35], v[26:27], off offset:512
	v_fma_f32 v24, v54, v24, v8
	v_fma_f32 v25, v55, v25, v9
	v_cvt_pk_bf16_f32 v22, v22, v23
	v_fma_f32 v20, v52, v20, v4
	v_fma_f32 v21, v53, v21, v5
	v_cvt_pk_bf16_f32 v23, v24, v25
	global_store_dwordx2 v[34:35], v[22:23], off offset:1024
	v_cvt_pk_bf16_f32 v18, v18, v19
	v_cvt_pk_bf16_f32 v19, v20, v21
	s_ashr_i32 s1, s0, 31
	s_andn2_b64 vcc, exec, s[16:17]
	s_mov_b64 s[6:7], -1
	global_store_dwordx2 v[34:35], v[18:19], off offset:1536
	s_cbranch_vccnz .LBB0_828
	s_lshl_b64 s[2:3], s[0:1], 11
	v_lshl_add_u64 v[18:19], v[82:83], 0, s[2:3]
	global_load_dwordx2 v[20:21], v[18:19], off
	global_load_dwordx2 v[22:23], v[18:19], off offset:512
	global_load_dwordx2 v[24:25], v[18:19], off offset:1024
	global_load_dwordx2 v[26:27], v[18:19], off offset:1536
	global_load_dwordx2 v[28:29], v[18:19], off offset:2048
	global_load_dwordx2 v[70:71], v[18:19], off offset:2560
	global_load_dwordx2 v[72:73], v[18:19], off offset:3072
	global_load_dwordx2 v[74:75], v[18:19], off offset:3584
	s_mov_b64 s[6:7], 0
	s_waitcnt vmcnt(7)
	v_lshlrev_b32_e32 v38, 16, v20
	v_and_b32_e32 v39, 0xffff0000, v20
	v_lshlrev_b32_e32 v40, 16, v21
	v_and_b32_e32 v41, 0xffff0000, v21
	s_waitcnt vmcnt(6)
	v_lshlrev_b32_e32 v34, 16, v22
	v_and_b32_e32 v35, 0xffff0000, v22
	v_lshlrev_b32_e32 v36, 16, v23
	v_and_b32_e32 v37, 0xffff0000, v23
	s_waitcnt vmcnt(5)
	v_lshlrev_b32_e32 v42, 16, v24
	v_and_b32_e32 v43, 0xffff0000, v24
	v_lshlrev_b32_e32 v44, 16, v25
	v_and_b32_e32 v45, 0xffff0000, v25
	s_waitcnt vmcnt(4)
	v_lshlrev_b32_e32 v46, 16, v26
	v_and_b32_e32 v47, 0xffff0000, v26
	v_lshlrev_b32_e32 v48, 16, v27
	v_and_b32_e32 v49, 0xffff0000, v27
	s_waitcnt vmcnt(3)
	v_lshlrev_b32_e32 v30, 16, v28
	v_and_b32_e32 v31, 0xffff0000, v28
	v_lshlrev_b32_e32 v32, 16, v29
	v_and_b32_e32 v33, 0xffff0000, v29
	s_waitcnt vmcnt(2)
	v_lshlrev_b32_e32 v26, 16, v70
	v_and_b32_e32 v27, 0xffff0000, v70
	v_lshlrev_b32_e32 v28, 16, v71
	v_and_b32_e32 v29, 0xffff0000, v71
	s_waitcnt vmcnt(1)
	v_lshlrev_b32_e32 v22, 16, v72
	v_and_b32_e32 v23, 0xffff0000, v72
	v_lshlrev_b32_e32 v24, 16, v73
	v_and_b32_e32 v25, 0xffff0000, v73
	s_waitcnt vmcnt(0)
	v_lshlrev_b32_e32 v18, 16, v74
	v_and_b32_e32 v19, 0xffff0000, v74
	v_lshlrev_b32_e32 v20, 16, v75
	v_and_b32_e32 v21, 0xffff0000, v75

.LBB0_830:
	s_waitcnt vmcnt(7)
	v_mul_f32_e32 v70, v40, v40
	v_mul_f32_e32 v71, v41, v41
	v_mul_f32_e32 v72, v38, v38
	v_mul_f32_e32 v73, v39, v39
	s_waitcnt vmcnt(4)
	v_mul_f32_e32 v0, v46, v46
	v_pk_mov_b32 v[74:75], v[72:73], v[70:71] op_sel:[1,0]
	v_mov_b32_e32 v73, v71
	v_add_f32_e32 v70, v74, v72
	v_add_f32_e32 v71, v75, v73
	v_mul_f32_e32 v72, v36, v36
	v_mul_f32_e32 v73, v37, v37
	v_mul_f32_e32 v74, v34, v34
	v_mul_f32_e32 v75, v35, v35
	v_pk_add_f32 v[70:71], v[70:71], v[70:71] op_sel:[0,1] op_sel_hi:[1,0]
	v_pk_mov_b32 v[76:77], v[74:75], v[72:73] op_sel:[1,0]
	v_mov_b32_e32 v75, v73
	v_add_f32_e32 v72, v76, v74
	v_add_f32_e32 v73, v77, v75
	v_mul_f32_e32 v74, v47, v47
	v_pk_add_f32 v[72:73], v[72:73], v[72:73] op_sel:[0,1] op_sel_hi:[1,0]
	v_mov_b32_e32 v71, v0
	v_mov_b32_e32 v73, v74
	v_mul_f32_e32 v0, v43, v43
	v_mul_f32_e32 v75, v48, v48
	v_add_f32_e32 v70, v70, v72
	v_add_f32_e32 v71, v71, v73
	v_fma_f32 v72, v42, v42, v0
	v_fma_f32 v73, v43, v43, v0
	v_mul_f32_e32 v0, v45, v45
	v_mul_f32_e32 v76, v49, v49
	v_mov_b32_e32 v73, v75
	v_fma_f32 v74, v44, v44, v0
	v_fma_f32 v75, v45, v45, v0
	s_waitcnt vmcnt(0)
	v_mul_f32_e32 v0, v18, v18
	v_mov_b32_e32 v75, v76
	v_add_f32_e32 v72, v72, v74
	v_add_f32_e32 v73, v73, v75
	s_or_b32 s0, s0, 1
	v_add_f32_e32 v70, v70, v72
	v_add_f32_e32 v71, v71, v73
	v_mul_f32_e32 v72, v30, v30
	v_mul_f32_e32 v73, v31, v31
	v_add_f32_e32 v82, v70, v71
	v_mul_f32_e32 v70, v32, v32
	v_mul_f32_e32 v71, v33, v33
	s_ashr_i32 s1, s0, 31
	v_pk_mov_b32 v[74:75], v[72:73], v[70:71] op_sel:[1,0]
	v_mov_b32_e32 v73, v71
	v_add_f32_e32 v70, v74, v72
	v_add_f32_e32 v71, v75, v73
	v_mul_f32_e32 v72, v28, v28
	v_mul_f32_e32 v73, v29, v29
	v_mul_f32_e32 v74, v26, v26
	v_mul_f32_e32 v75, v27, v27
	v_pk_add_f32 v[70:71], v[70:71], v[70:71] op_sel:[0,1] op_sel_hi:[1,0]
	v_pk_mov_b32 v[76:77], v[74:75], v[72:73] op_sel:[1,0]
	v_mov_b32_e32 v75, v73
	v_add_f32_e32 v72, v76, v74
	v_add_f32_e32 v73, v77, v75
	v_mul_f32_e32 v74, v19, v19
	v_pk_add_f32 v[72:73], v[72:73], v[72:73] op_sel:[0,1] op_sel_hi:[1,0]
	v_mov_b32_e32 v71, v0
	v_mov_b32_e32 v73, v74
	v_mul_f32_e32 v0, v23, v23
	v_mul_f32_e32 v75, v20, v20
	v_add_f32_e32 v70, v70, v72
	v_add_f32_e32 v71, v71, v73
	v_fma_f32 v72, v22, v22, v0
	v_fma_f32 v73, v23, v23, v0
	v_mul_f32_e32 v0, v25, v25
	v_mov_b32_e32 v73, v75
	v_fma_f32 v74, v24, v24, v0
	v_fma_f32 v75, v25, v25, v0
	ds_bpermute_b32 v0, v65, v82
	v_mul_f32_e32 v76, v21, v21
	v_mov_b32_e32 v75, v76
	v_add_f32_e32 v72, v72, v74
	v_add_f32_e32 v73, v73, v75
	s_lshl_b64 s[0:1], s[0:1], 11
	v_add_f32_e32 v70, v70, v72
	v_add_f32_e32 v71, v71, v73
	s_waitcnt lgkmcnt(0)
	v_add_f32_e32 v0, v82, v0
	v_add_f32_e32 v72, v70, v71
	ds_bpermute_b32 v70, v64, v0
	s_waitcnt lgkmcnt(0)
	v_add_f32_e32 v0, v0, v70
	ds_bpermute_b32 v70, v63, v0
	s_waitcnt lgkmcnt(0)
	v_add_f32_e32 v0, v0, v70
	ds_bpermute_b32 v70, v62, v0
	s_waitcnt lgkmcnt(0)
	v_add_f32_e32 v0, v0, v70
	ds_bpermute_b32 v70, v61, v0
	s_waitcnt lgkmcnt(0)
	v_add_f32_e32 v0, v0, v70
	ds_bpermute_b32 v70, v60, v0
	s_waitcnt lgkmcnt(0)
	v_add_f32_e32 v0, v0, v70
	v_fmamk_f32 v0, v0, 0x3a800000, v230
	v_rsq_f32_e32 v0, v0
	v_lshl_add_u64 v[70:71], v[58:59], 0, s[2:3]
	v_mul_f32_e32 v38, v0, v38
	v_mul_f32_e32 v39, v0, v39
	v_mul_f32_e32 v34, v0, v34
	v_mul_f32_e32 v35, v0, v35
	v_mul_f32_e32 v40, v0, v40
	v_mul_f32_e32 v41, v0, v41
	v_fma_f32 v38, v80, v38, v14
	v_fma_f32 v39, v81, v39, v15
	v_mul_f32_e32 v36, v0, v36
	v_mul_f32_e32 v37, v0, v37
	v_fma_f32 v34, v68, v34, v10
	v_fma_f32 v35, v69, v35, v11
	v_fma_f32 v40, v78, v40, v16
	v_fma_f32 v41, v79, v41, v17
	v_cvt_pk_bf16_f32 v38, v38, v39
	v_fma_f32 v36, v66, v36, v12
	v_fma_f32 v37, v67, v37, v13
	v_cvt_pk_bf16_f32 v39, v40, v41
	global_store_dwordx2 v[70:71], v[38:39], off
	v_cvt_pk_bf16_f32 v34, v34, v35
	v_cvt_pk_bf16_f32 v35, v36, v37
	global_store_dwordx2 v[70:71], v[34:35], off offset:512
	v_mul_f32_e32 v34, v0, v42
	v_mul_f32_e32 v35, v0, v43
	v_mul_f32_e32 v36, v0, v44
	v_mul_f32_e32 v37, v0, v45
	v_fma_f32 v34, v56, v34, v6
	v_fma_f32 v35, v57, v35, v7
	v_fma_f32 v36, v54, v36, v8
	v_fma_f32 v37, v55, v37, v9
	v_cvt_pk_bf16_f32 v34, v34, v35
	s_nop 0
	v_cvt_pk_bf16_f32 v35, v36, v37
	global_store_dwordx2 v[70:71], v[34:35], off offset:1024
	v_mul_f32_e32 v34, v0, v46
	v_mul_f32_e32 v35, v0, v47
	v_mul_f32_e32 v36, v0, v48
	v_mul_f32_e32 v37, v0, v49
	ds_bpermute_b32 v0, v65, v72
	v_fma_f32 v34, v50, v34, v2
	v_fma_f32 v35, v51, v35, v3
	v_fma_f32 v36, v52, v36, v4
	v_fma_f32 v37, v53, v37, v5
	v_cvt_pk_bf16_f32 v34, v34, v35
	s_waitcnt lgkmcnt(0)
	v_add_f32_e32 v0, v72, v0
	v_cvt_pk_bf16_f32 v35, v36, v37
	global_store_dwordx2 v[70:71], v[34:35], off offset:1536
	ds_bpermute_b32 v34, v64, v0
	s_waitcnt lgkmcnt(0)
	v_add_f32_e32 v0, v0, v34
	ds_bpermute_b32 v34, v63, v0
	s_waitcnt lgkmcnt(0)
	v_add_f32_e32 v0, v0, v34
	ds_bpermute_b32 v34, v62, v0
	s_waitcnt lgkmcnt(0)
	v_add_f32_e32 v0, v0, v34
	ds_bpermute_b32 v34, v61, v0
	s_waitcnt lgkmcnt(0)
	v_add_f32_e32 v0, v0, v34
	ds_bpermute_b32 v34, v60, v0
	s_waitcnt lgkmcnt(0)
	v_add_f32_e32 v0, v0, v34
	v_fmamk_f32 v0, v0, 0x3a800000, v230
	v_rsq_f32_e32 v0, v0
	v_lshl_add_u64 v[34:35], v[58:59], 0, s[0:1]
	v_mul_f32_e32 v30, v0, v30
	v_mul_f32_e32 v31, v0, v31
	v_mul_f32_e32 v32, v0, v32
	v_mul_f32_e32 v33, v0, v33
	v_fma_f32 v14, v80, v30, v14
	v_fma_f32 v15, v81, v31, v15
	v_fma_f32 v16, v78, v32, v16
	v_fma_f32 v17, v79, v33, v17
	v_cvt_pk_bf16_f32 v14, v14, v15
	s_nop 0
	v_cvt_pk_bf16_f32 v15, v16, v17
	global_store_dwordx2 v[34:35], v[14:15], off
	v_mul_f32_e32 v14, v0, v26
	v_mul_f32_e32 v15, v0, v27
	v_mul_f32_e32 v16, v0, v28
	v_mul_f32_e32 v17, v0, v29
	v_fma_f32 v10, v68, v14, v10
	v_fma_f32 v11, v69, v15, v11
	v_fma_f32 v12, v66, v16, v12
	v_fma_f32 v13, v67, v17, v13
	v_cvt_pk_bf16_f32 v10, v10, v11
	s_nop 0
	v_cvt_pk_bf16_f32 v11, v12, v13
	global_store_dwordx2 v[34:35], v[10:11], off offset:512
	v_mul_f32_e32 v10, v0, v22
	v_mul_f32_e32 v11, v0, v23
	v_mul_f32_e32 v12, v0, v24
	v_mul_f32_e32 v13, v0, v25
	v_fma_f32 v6, v56, v10, v6
	v_fma_f32 v7, v57, v11, v7
	v_fma_f32 v8, v54, v12, v8
	v_fma_f32 v9, v55, v13, v9
	v_cvt_pk_bf16_f32 v6, v6, v7
	s_nop 0
	v_cvt_pk_bf16_f32 v7, v8, v9
	global_store_dwordx2 v[34:35], v[6:7], off offset:1024
	v_mul_f32_e32 v6, v0, v18
	v_mul_f32_e32 v7, v0, v19
	v_mul_f32_e32 v8, v0, v20
	v_mul_f32_e32 v9, v0, v21
	v_fma_f32 v2, v50, v6, v2
	v_fma_f32 v3, v51, v7, v3
	v_fma_f32 v4, v52, v8, v4
	v_fma_f32 v5, v53, v9, v5
	v_cvt_pk_bf16_f32 v2, v2, v3
	s_nop 0
	v_cvt_pk_bf16_f32 v3, v4, v5
	global_store_dwordx2 v[34:35], v[2:3], off offset:1536
	s_waitcnt vmcnt(0)
	s_barrier
	s_and_saveexec_b64 s[0:1], s[4:5]
	s_cbranch_execz .LBB0_844
	s_mov_b64 s[2:3], exec
	buffer_wbl2 sc1
	s_waitcnt vmcnt(0)
	s_waitcnt vmcnt(0)
	v_mbcnt_lo_u32_b32 v0, s2, 0
	v_mbcnt_hi_u32_b32 v0, s3, v0
	v_cmp_eq_u32_e32 vcc, 0, v0
	s_and_saveexec_b64 s[4:5], vcc
	s_cbranch_execz .LBB0_833
	s_bcnt1_i32_b64 s2, s[2:3]
	v_mov_b32_e32 v0, s2
	global_atomic_add v1, v0, s[36:37] offset:2560

.LBB0_900:
	s_waitcnt vmcnt(0)
	v_mul_f32_e32 v136, 0.5, v136
	v_mul_f32_e32 v137, 0.5, v137
	v_mul_f32_e32 v130, 0.5, v130
	v_mul_f32_e32 v131, 0.5, v131
	v_mul_f32_e32 v132, 0.5, v132
	v_mul_f32_e32 v133, 0.5, v133
	v_lshlrev_b32_e32 v154, 16, v138
	v_and_b32_e32 v155, 0xffff0000, v138
	v_lshlrev_b32_e32 v138, 16, v139
	v_and_b32_e32 v139, 0xffff0000, v139
	v_lshlrev_b32_e32 v156, 16, v140
	v_and_b32_e32 v157, 0xffff0000, v140
	v_lshlrev_b32_e32 v140, 16, v141
	v_and_b32_e32 v141, 0xffff0000, v141
	v_mul_f32_e32 v134, 0.5, v134
	v_mul_f32_e32 v135, 0.5, v135
	v_fma_f32 v136, v128, v136, v138
	v_fma_f32 v137, v129, v137, v139
	v_fma_f32 v138, v124, v132, v140
	v_fma_f32 v139, v125, v133, v141
	v_fma_f32 v132, v122, v130, v156
	v_fma_f32 v133, v123, v131, v157
	v_fma_f32 v134, v126, v134, v154
	v_fma_f32 v135, v127, v135, v155
	s_andn2_b64 vcc, exec, s[0:1]
	v_cvt_pk_bf16_f32 v130, v134, v135
	v_cvt_pk_bf16_f32 v131, v136, v137
	v_cvt_pk_bf16_f32 v132, v132, v133
	v_cvt_pk_bf16_f32 v133, v138, v139
	global_store_dwordx4 v[152:153], v[130:133], off
	global_load_dwordx4 v[130:133], v[150:151], off offset:528
	global_load_dwordx4 v[134:137], v[150:151], off offset:512
	v_cndmask_b32_e64 v138, 0, 1, s[0:1]
	v_cmp_ne_u32_e64 s[6:7], 1, v138
	s_cbranch_vccnz .LBB0_903
	global_load_dwordx4 v[138:141], v[144:145], off offset:512
	global_load_dwordx4 v[150:153], v[144:145], off offset:528
	s_mov_b64 s[0:1], 0
	s_waitcnt vmcnt(1)
	v_cvt_pk_bf16_f32 v138, v138, v139
	v_cvt_pk_bf16_f32 v139, v140, v141
	s_waitcnt vmcnt(0)
	v_cvt_pk_bf16_f32 v140, v150, v151
	v_cvt_pk_bf16_f32 v141, v152, v153
	s_branch .LBB0_904

.LBB0_906:
	s_waitcnt vmcnt(0)
	v_mul_f32_e32 v136, 0.5, v136
	v_mul_f32_e32 v137, 0.5, v137
	v_mul_f32_e32 v130, 0.5, v130
	v_mul_f32_e32 v131, 0.5, v131
	v_mul_f32_e32 v132, 0.5, v132
	v_mul_f32_e32 v133, 0.5, v133
	v_lshlrev_b32_e32 v150, 16, v138
	v_and_b32_e32 v151, 0xffff0000, v138
	v_lshlrev_b32_e32 v138, 16, v139
	v_and_b32_e32 v139, 0xffff0000, v139
	v_lshlrev_b32_e32 v152, 16, v140
	v_and_b32_e32 v153, 0xffff0000, v140
	v_lshlrev_b32_e32 v140, 16, v141
	v_and_b32_e32 v141, 0xffff0000, v141
	s_add_i32 s0, s22, 0xffff8010
	v_mul_f32_e32 v134, 0.5, v134
	v_mul_f32_e32 v135, 0.5, v135
	v_fma_f32 v136, v120, v136, v138
	v_fma_f32 v137, v121, v137, v139
	v_fma_f32 v138, v116, v132, v140
	v_fma_f32 v139, v117, v133, v141
	v_fma_f32 v132, v114, v130, v152
	v_fma_f32 v133, v115, v131, v153
	s_lshr_b32 s0, s0, 5
	v_fma_f32 v134, v118, v134, v150
	v_fma_f32 v135, v119, v135, v151
	s_add_i32 s0, s0, 4
	v_cvt_pk_bf16_f32 v130, v134, v135
	v_cvt_pk_bf16_f32 v131, v136, v137
	v_cvt_pk_bf16_f32 v132, v132, v133
	v_cvt_pk_bf16_f32 v133, v138, v139
	v_or_b32_e32 v138, 16, v146
	global_store_dwordx4 v[148:149], v[130:133], off
	v_cmp_gt_i32_e32 vcc, s75, v138
	v_ashrrev_i32_e32 v139, 31, v138
	v_mov_b32_e32 v130, s0
	v_mov_b32_e32 v131, s23
	v_cndmask_b32_e32 v132, v130, v131, vcc
	v_mov_b64_e32 v[130:131], s[10:11]
	v_mad_i64_i32 v[130:131], s[0:1], v132, s96, v[130:131]
	v_lshl_add_u64 v[152:153], v[142:143], 2, v[130:131]
	global_load_dwordx4 v[130:133], v[152:153], off offset:16
	global_load_dwordx4 v[134:137], v[152:153], off
	v_lshlrev_b64 v[148:149], 10, v[138:139]
	v_lshl_add_u64 v[154:155], v[148:149], 0, v[142:143]
	s_and_b64 vcc, exec, s[6:7]
	v_lshl_add_u64 v[150:151], v[154:155], 2, s[20:21]
	s_cbranch_vccnz .LBB0_1000
	global_load_dwordx4 v[138:141], v[150:151], off
	global_load_dwordx4 v[156:159], v[150:151], off offset:16
	s_waitcnt vmcnt(1)
	v_cvt_pk_bf16_f32 v138, v138, v139
	v_cvt_pk_bf16_f32 v139, v140, v141
	s_waitcnt vmcnt(0)
	v_cvt_pk_bf16_f32 v140, v156, v157
	v_cvt_pk_bf16_f32 v141, v158, v159
	v_lshl_add_u64 v[154:155], v[154:155], 1, s[8:9]
	s_cbranch_execnz .LBB0_909

.LBB0_909:
	s_waitcnt vmcnt(0)
	v_mul_f32_e32 v136, 0.5, v136
	v_mul_f32_e32 v137, 0.5, v137
	v_mul_f32_e32 v130, 0.5, v130
	v_mul_f32_e32 v131, 0.5, v131
	v_mul_f32_e32 v132, 0.5, v132
	v_mul_f32_e32 v133, 0.5, v133
	v_lshlrev_b32_e32 v156, 16, v138
	v_and_b32_e32 v157, 0xffff0000, v138
	v_lshlrev_b32_e32 v138, 16, v139
	v_and_b32_e32 v139, 0xffff0000, v139
	v_lshlrev_b32_e32 v158, 16, v140
	v_and_b32_e32 v159, 0xffff0000, v140
	v_lshlrev_b32_e32 v140, 16, v141
	v_and_b32_e32 v141, 0xffff0000, v141
	v_mul_f32_e32 v134, 0.5, v134
	v_mul_f32_e32 v135, 0.5, v135
	v_fma_f32 v136, v112, v136, v138
	v_fma_f32 v137, v113, v137, v139
	v_fma_f32 v138, v108, v132, v140
	v_fma_f32 v139, v109, v133, v141
	v_fma_f32 v132, v106, v130, v158
	v_fma_f32 v133, v107, v131, v159
	v_fma_f32 v134, v110, v134, v156
	v_fma_f32 v135, v111, v135, v157
	s_and_b64 vcc, exec, s[6:7]
	v_cvt_pk_bf16_f32 v130, v134, v135
	v_cvt_pk_bf16_f32 v131, v136, v137
	v_cvt_pk_bf16_f32 v132, v132, v133
	v_cvt_pk_bf16_f32 v133, v138, v139
	global_store_dwordx4 v[154:155], v[130:133], off
	global_load_dwordx4 v[130:133], v[152:153], off offset:528
	global_load_dwordx4 v[134:137], v[152:153], off offset:512
	s_cbranch_vccnz .LBB0_1001
	global_load_dwordx4 v[138:141], v[150:151], off offset:512
	s_nop 0
	global_load_dwordx4 v[150:153], v[150:151], off offset:528
	s_waitcnt vmcnt(1)
	v_cvt_pk_bf16_f32 v138, v138, v139
	v_cvt_pk_bf16_f32 v139, v140, v141
	s_waitcnt vmcnt(0)
	v_cvt_pk_bf16_f32 v140, v150, v151
	v_cvt_pk_bf16_f32 v141, v152, v153
	v_lshl_add_u64 v[148:149], v[148:149], 0, v[144:145]
	v_lshl_add_u64 v[148:149], v[148:149], 1, s[8:9]
	s_cbranch_execnz .LBB0_912

.LBB0_912:
	s_waitcnt vmcnt(0)
	v_mul_f32_e32 v136, 0.5, v136
	v_mul_f32_e32 v137, 0.5, v137
	v_mul_f32_e32 v130, 0.5, v130
	v_mul_f32_e32 v131, 0.5, v131
	v_mul_f32_e32 v132, 0.5, v132
	v_mul_f32_e32 v133, 0.5, v133
	v_lshlrev_b32_e32 v150, 16, v138
	v_and_b32_e32 v151, 0xffff0000, v138
	v_lshlrev_b32_e32 v138, 16, v139
	v_and_b32_e32 v139, 0xffff0000, v139
	v_lshlrev_b32_e32 v152, 16, v140
	v_and_b32_e32 v153, 0xffff0000, v140
	v_lshlrev_b32_e32 v140, 16, v141
	v_and_b32_e32 v141, 0xffff0000, v141
	s_add_i32 s0, s22, 0xffff8020
	v_mul_f32_e32 v134, 0.5, v134
	v_mul_f32_e32 v135, 0.5, v135
	v_fma_f32 v136, v104, v136, v138
	v_fma_f32 v137, v105, v137, v139
	v_fma_f32 v138, v100, v132, v140
	v_fma_f32 v139, v101, v133, v141
	v_fma_f32 v132, v98, v130, v152
	v_fma_f32 v133, v99, v131, v153
	s_lshr_b32 s0, s0, 5
	v_fma_f32 v134, v102, v134, v150
	v_fma_f32 v135, v103, v135, v151
	s_add_i32 s0, s0, 4
	v_cvt_pk_bf16_f32 v130, v134, v135
	v_cvt_pk_bf16_f32 v131, v136, v137
	v_cvt_pk_bf16_f32 v132, v132, v133
	v_cvt_pk_bf16_f32 v133, v138, v139
	v_or_b32_e32 v138, 32, v146
	global_store_dwordx4 v[148:149], v[130:133], off
	v_cmp_gt_i32_e32 vcc, s75, v138
	v_ashrrev_i32_e32 v139, 31, v138
	v_mov_b32_e32 v130, s0
	v_mov_b32_e32 v131, s23
	v_cndmask_b32_e32 v132, v130, v131, vcc
	v_mov_b64_e32 v[130:131], s[10:11]
	v_mad_i64_i32 v[130:131], s[0:1], v132, s96, v[130:131]
	v_lshl_add_u64 v[152:153], v[142:143], 2, v[130:131]
	global_load_dwordx4 v[130:133], v[152:153], off offset:16
	global_load_dwordx4 v[134:137], v[152:153], off
	v_lshlrev_b64 v[148:149], 10, v[138:139]
	v_lshl_add_u64 v[154:155], v[148:149], 0, v[142:143]
	s_and_b64 vcc, exec, s[6:7]
	v_lshl_add_u64 v[150:151], v[154:155], 2, s[20:21]
	s_cbranch_vccnz .LBB0_1002
	global_load_dwordx4 v[138:141], v[150:151], off
	global_load_dwordx4 v[156:159], v[150:151], off offset:16
	s_waitcnt vmcnt(1)
	v_cvt_pk_bf16_f32 v138, v138, v139
	v_cvt_pk_bf16_f32 v139, v140, v141
	s_waitcnt vmcnt(0)
	v_cvt_pk_bf16_f32 v140, v156, v157
	v_cvt_pk_bf16_f32 v141, v158, v159
	v_lshl_add_u64 v[154:155], v[154:155], 1, s[8:9]
	s_cbranch_execnz .LBB0_915

.LBB0_915:
	s_waitcnt vmcnt(0)
	v_mul_f32_e32 v136, 0.5, v136
	v_mul_f32_e32 v137, 0.5, v137
	v_mul_f32_e32 v130, 0.5, v130
	v_mul_f32_e32 v131, 0.5, v131
	v_mul_f32_e32 v132, 0.5, v132
	v_mul_f32_e32 v133, 0.5, v133
	v_lshlrev_b32_e32 v156, 16, v138
	v_and_b32_e32 v157, 0xffff0000, v138
	v_lshlrev_b32_e32 v138, 16, v139
	v_and_b32_e32 v139, 0xffff0000, v139
	v_lshlrev_b32_e32 v158, 16, v140
	v_and_b32_e32 v159, 0xffff0000, v140
	v_lshlrev_b32_e32 v140, 16, v141
	v_and_b32_e32 v141, 0xffff0000, v141
	v_mul_f32_e32 v134, 0.5, v134
	v_mul_f32_e32 v135, 0.5, v135
	v_fma_f32 v136, v96, v136, v138
	v_fma_f32 v137, v97, v137, v139
	v_fma_f32 v138, v92, v132, v140
	v_fma_f32 v139, v93, v133, v141
	v_fma_f32 v132, v90, v130, v158
	v_fma_f32 v133, v91, v131, v159
	v_fma_f32 v134, v94, v134, v156
	v_fma_f32 v135, v95, v135, v157
	s_and_b64 vcc, exec, s[6:7]
	v_cvt_pk_bf16_f32 v130, v134, v135
	v_cvt_pk_bf16_f32 v131, v136, v137
	v_cvt_pk_bf16_f32 v132, v132, v133
	v_cvt_pk_bf16_f32 v133, v138, v139
	global_store_dwordx4 v[154:155], v[130:133], off
	global_load_dwordx4 v[130:133], v[152:153], off offset:528
	global_load_dwordx4 v[134:137], v[152:153], off offset:512
	s_cbranch_vccnz .LBB0_1003
	global_load_dwordx4 v[138:141], v[150:151], off offset:512
	s_nop 0
	global_load_dwordx4 v[150:153], v[150:151], off offset:528
	s_waitcnt vmcnt(1)
	v_cvt_pk_bf16_f32 v138, v138, v139
	v_cvt_pk_bf16_f32 v139, v140, v141
	s_waitcnt vmcnt(0)
	v_cvt_pk_bf16_f32 v140, v150, v151
	v_cvt_pk_bf16_f32 v141, v152, v153
	v_lshl_add_u64 v[148:149], v[148:149], 0, v[144:145]
	v_lshl_add_u64 v[148:149], v[148:149], 1, s[8:9]
	s_cbranch_execnz .LBB0_918

.LBB0_918:
	s_waitcnt vmcnt(0)
	v_mul_f32_e32 v136, 0.5, v136
	v_mul_f32_e32 v137, 0.5, v137
	v_mul_f32_e32 v130, 0.5, v130
	v_mul_f32_e32 v131, 0.5, v131
	v_mul_f32_e32 v132, 0.5, v132
	v_mul_f32_e32 v133, 0.5, v133
	v_lshlrev_b32_e32 v150, 16, v138
	v_and_b32_e32 v151, 0xffff0000, v138
	v_lshlrev_b32_e32 v138, 16, v139
	v_and_b32_e32 v139, 0xffff0000, v139
	v_lshlrev_b32_e32 v152, 16, v140
	v_and_b32_e32 v153, 0xffff0000, v140
	v_lshlrev_b32_e32 v140, 16, v141
	v_and_b32_e32 v141, 0xffff0000, v141
	s_add_i32 s0, s22, 0xffff8030
	v_mul_f32_e32 v134, 0.5, v134
	v_mul_f32_e32 v135, 0.5, v135
	v_fma_f32 v136, v88, v136, v138
	v_fma_f32 v137, v89, v137, v139
	v_fma_f32 v138, v84, v132, v140
	v_fma_f32 v139, v85, v133, v141
	v_fma_f32 v132, v82, v130, v152
	v_fma_f32 v133, v83, v131, v153
	s_lshr_b32 s0, s0, 5
	v_fma_f32 v134, v86, v134, v150
	v_fma_f32 v135, v87, v135, v151
	s_add_i32 s0, s0, 4
	v_cvt_pk_bf16_f32 v130, v134, v135
	v_cvt_pk_bf16_f32 v131, v136, v137
	v_cvt_pk_bf16_f32 v132, v132, v133
	v_cvt_pk_bf16_f32 v133, v138, v139
	v_or_b32_e32 v138, 48, v146
	global_store_dwordx4 v[148:149], v[130:133], off
	v_cmp_gt_i32_e32 vcc, s75, v138
	v_ashrrev_i32_e32 v139, 31, v138
	v_mov_b32_e32 v130, s0
	v_mov_b32_e32 v131, s23
	v_cndmask_b32_e32 v132, v130, v131, vcc
	v_mov_b64_e32 v[130:131], s[10:11]
	v_mad_i64_i32 v[130:131], s[0:1], v132, s96, v[130:131]
	v_lshl_add_u64 v[150:151], v[142:143], 2, v[130:131]
	global_load_dwordx4 v[130:133], v[150:151], off offset:16
	global_load_dwordx4 v[134:137], v[150:151], off
	v_lshlrev_b64 v[146:147], 10, v[138:139]
	v_lshl_add_u64 v[152:153], v[146:147], 0, v[142:143]
	s_and_b64 vcc, exec, s[6:7]
	v_lshl_add_u64 v[148:149], v[152:153], 2, s[20:21]
	s_cbranch_vccnz .LBB0_1004
	global_load_dwordx4 v[138:141], v[148:149], off
	global_load_dwordx4 v[154:157], v[148:149], off offset:16
	s_waitcnt vmcnt(1)
	v_cvt_pk_bf16_f32 v138, v138, v139
	v_cvt_pk_bf16_f32 v139, v140, v141
	s_waitcnt vmcnt(0)
	v_cvt_pk_bf16_f32 v140, v154, v155
	v_cvt_pk_bf16_f32 v141, v156, v157
	v_lshl_add_u64 v[152:153], v[152:153], 1, s[8:9]
	s_cbranch_execnz .LBB0_921

.LBB0_921:
	s_waitcnt vmcnt(0)
	v_mul_f32_e32 v136, 0.5, v136
	v_mul_f32_e32 v137, 0.5, v137
	v_mul_f32_e32 v130, 0.5, v130
	v_mul_f32_e32 v131, 0.5, v131
	v_mul_f32_e32 v132, 0.5, v132
	v_mul_f32_e32 v133, 0.5, v133
	v_lshlrev_b32_e32 v154, 16, v138
	v_and_b32_e32 v155, 0xffff0000, v138
	v_lshlrev_b32_e32 v138, 16, v139
	v_and_b32_e32 v139, 0xffff0000, v139
	v_lshlrev_b32_e32 v156, 16, v140
	v_and_b32_e32 v157, 0xffff0000, v140
	v_lshlrev_b32_e32 v140, 16, v141
	v_and_b32_e32 v141, 0xffff0000, v141
	v_mul_f32_e32 v134, 0.5, v134
	v_mul_f32_e32 v135, 0.5, v135
	v_fma_f32 v136, v80, v136, v138
	v_fma_f32 v137, v81, v137, v139
	v_fma_f32 v138, v76, v132, v140
	v_fma_f32 v139, v77, v133, v141
	v_fma_f32 v132, v74, v130, v156
	v_fma_f32 v133, v75, v131, v157
	v_fma_f32 v134, v78, v134, v154
	v_fma_f32 v135, v79, v135, v155
	s_and_b64 vcc, exec, s[6:7]
	v_cvt_pk_bf16_f32 v130, v134, v135
	v_cvt_pk_bf16_f32 v131, v136, v137
	v_cvt_pk_bf16_f32 v132, v132, v133
	v_cvt_pk_bf16_f32 v133, v138, v139
	global_store_dwordx4 v[152:153], v[130:133], off
	global_load_dwordx4 v[130:133], v[150:151], off offset:528
	global_load_dwordx4 v[134:137], v[150:151], off offset:512
	s_cbranch_vccnz .LBB0_1005
	global_load_dwordx4 v[138:141], v[148:149], off offset:512
	s_nop 0
	global_load_dwordx4 v[148:151], v[148:149], off offset:528
	s_waitcnt vmcnt(1)
	v_cvt_pk_bf16_f32 v138, v138, v139
	v_cvt_pk_bf16_f32 v139, v140, v141
	s_waitcnt vmcnt(0)
	v_cvt_pk_bf16_f32 v140, v148, v149
	v_cvt_pk_bf16_f32 v141, v150, v151
	v_lshl_add_u64 v[146:147], v[146:147], 0, v[144:145]
	v_lshl_add_u64 v[146:147], v[146:147], 1, s[8:9]
	s_cbranch_execnz .LBB0_924

.LBB0_924:
	s_waitcnt vmcnt(0)
	v_mul_f32_e32 v136, 0.5, v136
	v_mul_f32_e32 v137, 0.5, v137
	v_mul_f32_e32 v130, 0.5, v130
	v_mul_f32_e32 v131, 0.5, v131
	v_mul_f32_e32 v132, 0.5, v132
	v_mul_f32_e32 v133, 0.5, v133
	v_lshlrev_b32_e32 v148, 16, v138
	v_and_b32_e32 v149, 0xffff0000, v138
	v_lshlrev_b32_e32 v138, 16, v139
	v_and_b32_e32 v139, 0xffff0000, v139
	v_lshlrev_b32_e32 v150, 16, v140
	v_and_b32_e32 v151, 0xffff0000, v140
	v_lshlrev_b32_e32 v140, 16, v141
	v_and_b32_e32 v141, 0xffff0000, v141
	s_add_i32 s46, s22, 0x80
	s_addk_i32 s22, 0x8080
	v_mul_f32_e32 v134, 0.5, v134
	v_mul_f32_e32 v135, 0.5, v135
	v_fma_f32 v136, v72, v136, v138
	v_fma_f32 v137, v73, v137, v139
	v_fma_f32 v138, v68, v132, v140
	v_fma_f32 v139, v69, v133, v141
	v_fma_f32 v132, v66, v130, v150
	v_fma_f32 v133, v67, v131, v151
	s_lshr_b32 s0, s22, 5
	v_fma_f32 v134, v70, v134, v148
	v_fma_f32 v135, v71, v135, v149
	s_ashr_i32 s23, s46, 13
	v_cvt_pk_bf16_f32 v130, v134, v135
	v_cvt_pk_bf16_f32 v131, v136, v137
	v_cvt_pk_bf16_f32 v132, v132, v133
	v_cvt_pk_bf16_f32 v133, v138, v139
	global_store_dwordx4 v[146:147], v[130:133], off
	v_or_b32_e32 v146, s46, v182
	s_add_i32 s0, s0, 4
	v_mov_b32_e32 v130, s0
	v_mov_b32_e32 v131, s23
	v_cmp_gt_i32_e32 vcc, s75, v146
	v_ashrrev_i32_e32 v147, 31, v146
	v_lshlrev_b64 v[148:149], 10, v[146:147]
	v_cndmask_b32_e32 v132, v130, v131, vcc
	v_mov_b64_e32 v[130:131], s[10:11]
	v_mad_i64_i32 v[130:131], s[0:1], v132, s96, v[130:131]
	v_lshl_add_u64 v[152:153], v[142:143], 2, v[130:131]
	global_load_dwordx4 v[130:133], v[152:153], off offset:16
	global_load_dwordx4 v[134:137], v[152:153], off
	v_lshl_add_u64 v[154:155], v[148:149], 0, v[142:143]
	s_and_b64 vcc, exec, s[6:7]
	v_lshl_add_u64 v[150:151], v[154:155], 2, s[20:21]
	s_cbranch_vccnz .LBB0_1006
	global_load_dwordx4 v[138:141], v[150:151], off
	global_load_dwordx4 v[156:159], v[150:151], off offset:16
	s_waitcnt vmcnt(1)
	v_cvt_pk_bf16_f32 v138, v138, v139
	v_cvt_pk_bf16_f32 v139, v140, v141
	s_waitcnt vmcnt(0)
	v_cvt_pk_bf16_f32 v140, v156, v157
	v_cvt_pk_bf16_f32 v141, v158, v159
	v_lshl_add_u64 v[154:155], v[154:155], 1, s[8:9]
	s_cbranch_execnz .LBB0_927

.LBB0_927:
	s_waitcnt vmcnt(0)
	v_mul_f32_e32 v136, 0.5, v136
	v_mul_f32_e32 v137, 0.5, v137
	v_mul_f32_e32 v130, 0.5, v130
	v_mul_f32_e32 v131, 0.5, v131
	v_mul_f32_e32 v132, 0.5, v132
	v_mul_f32_e32 v133, 0.5, v133
	v_lshlrev_b32_e32 v156, 16, v138
	v_and_b32_e32 v157, 0xffff0000, v138
	v_lshlrev_b32_e32 v138, 16, v139
	v_and_b32_e32 v139, 0xffff0000, v139
	v_lshlrev_b32_e32 v158, 16, v140
	v_and_b32_e32 v159, 0xffff0000, v140
	v_lshlrev_b32_e32 v140, 16, v141
	v_and_b32_e32 v141, 0xffff0000, v141
	v_mul_f32_e32 v134, 0.5, v134
	v_mul_f32_e32 v135, 0.5, v135
	v_fma_f32 v136, v64, v136, v138
	v_fma_f32 v137, v65, v137, v139
	v_fma_f32 v138, v60, v132, v140
	v_fma_f32 v139, v61, v133, v141
	v_fma_f32 v132, v58, v130, v158
	v_fma_f32 v133, v59, v131, v159
	v_fma_f32 v134, v62, v134, v156
	v_fma_f32 v135, v63, v135, v157
	s_and_b64 vcc, exec, s[6:7]
	v_cvt_pk_bf16_f32 v130, v134, v135
	v_cvt_pk_bf16_f32 v131, v136, v137
	v_cvt_pk_bf16_f32 v132, v132, v133
	v_cvt_pk_bf16_f32 v133, v138, v139
	global_store_dwordx4 v[154:155], v[130:133], off
	global_load_dwordx4 v[130:133], v[152:153], off offset:528
	global_load_dwordx4 v[134:137], v[152:153], off offset:512
	s_cbranch_vccnz .LBB0_1007
	global_load_dwordx4 v[138:141], v[150:151], off offset:512
	s_nop 0
	global_load_dwordx4 v[150:153], v[150:151], off offset:528
	s_waitcnt vmcnt(1)
	v_cvt_pk_bf16_f32 v138, v138, v139
	v_cvt_pk_bf16_f32 v139, v140, v141
	s_waitcnt vmcnt(0)
	v_cvt_pk_bf16_f32 v140, v150, v151
	v_cvt_pk_bf16_f32 v141, v152, v153
	v_lshl_add_u64 v[148:149], v[148:149], 0, v[144:145]
	v_lshl_add_u64 v[148:149], v[148:149], 1, s[8:9]
	s_cbranch_execnz .LBB0_930

.LBB0_930:
	s_waitcnt vmcnt(0)
	v_mul_f32_e32 v136, 0.5, v136
	v_mul_f32_e32 v137, 0.5, v137
	v_mul_f32_e32 v130, 0.5, v130
	v_mul_f32_e32 v131, 0.5, v131
	v_mul_f32_e32 v132, 0.5, v132
	v_mul_f32_e32 v133, 0.5, v133
	v_lshlrev_b32_e32 v150, 16, v138
	v_and_b32_e32 v151, 0xffff0000, v138
	v_lshlrev_b32_e32 v138, 16, v139
	v_and_b32_e32 v139, 0xffff0000, v139
	v_lshlrev_b32_e32 v152, 16, v140
	v_and_b32_e32 v153, 0xffff0000, v140
	v_lshlrev_b32_e32 v140, 16, v141
	v_and_b32_e32 v141, 0xffff0000, v141
	s_add_i32 s0, s46, 0xffff8010
	v_mul_f32_e32 v134, 0.5, v134
	v_mul_f32_e32 v135, 0.5, v135
	v_fma_f32 v136, v56, v136, v138
	v_fma_f32 v137, v57, v137, v139
	v_fma_f32 v138, v52, v132, v140
	v_fma_f32 v139, v53, v133, v141
	v_fma_f32 v132, v50, v130, v152
	v_fma_f32 v133, v51, v131, v153
	s_lshr_b32 s0, s0, 5
	v_fma_f32 v134, v54, v134, v150
	v_fma_f32 v135, v55, v135, v151
	s_add_i32 s0, s0, 4
	v_cvt_pk_bf16_f32 v130, v134, v135
	v_cvt_pk_bf16_f32 v131, v136, v137
	v_cvt_pk_bf16_f32 v132, v132, v133
	v_cvt_pk_bf16_f32 v133, v138, v139
	v_or_b32_e32 v138, 16, v146
	global_store_dwordx4 v[148:149], v[130:133], off
	v_cmp_gt_i32_e32 vcc, s75, v138
	v_ashrrev_i32_e32 v139, 31, v138
	v_mov_b32_e32 v130, s0
	v_mov_b32_e32 v131, s23
	v_cndmask_b32_e32 v132, v130, v131, vcc
	v_mov_b64_e32 v[130:131], s[10:11]
	v_mad_i64_i32 v[130:131], s[0:1], v132, s96, v[130:131]
	v_lshl_add_u64 v[152:153], v[142:143], 2, v[130:131]
	global_load_dwordx4 v[130:133], v[152:153], off offset:16
	global_load_dwordx4 v[134:137], v[152:153], off
	v_lshlrev_b64 v[148:149], 10, v[138:139]
	v_lshl_add_u64 v[154:155], v[148:149], 0, v[142:143]
	s_and_b64 vcc, exec, s[6:7]
	v_lshl_add_u64 v[150:151], v[154:155], 2, s[20:21]
	s_cbranch_vccnz .LBB0_1008
	global_load_dwordx4 v[138:141], v[150:151], off
	global_load_dwordx4 v[156:159], v[150:151], off offset:16
	s_waitcnt vmcnt(1)
	v_cvt_pk_bf16_f32 v138, v138, v139
	v_cvt_pk_bf16_f32 v139, v140, v141
	s_waitcnt vmcnt(0)
	v_cvt_pk_bf16_f32 v140, v156, v157
	v_cvt_pk_bf16_f32 v141, v158, v159
	v_lshl_add_u64 v[154:155], v[154:155], 1, s[8:9]
	s_cbranch_execnz .LBB0_933

.LBB0_933:
	s_waitcnt vmcnt(0)
	v_mul_f32_e32 v136, 0.5, v136
	v_mul_f32_e32 v137, 0.5, v137
	v_mul_f32_e32 v130, 0.5, v130
	v_mul_f32_e32 v131, 0.5, v131
	v_mul_f32_e32 v132, 0.5, v132
	v_mul_f32_e32 v133, 0.5, v133
	v_lshlrev_b32_e32 v156, 16, v138
	v_and_b32_e32 v157, 0xffff0000, v138
	v_lshlrev_b32_e32 v138, 16, v139
	v_and_b32_e32 v139, 0xffff0000, v139
	v_lshlrev_b32_e32 v158, 16, v140
	v_and_b32_e32 v159, 0xffff0000, v140
	v_lshlrev_b32_e32 v140, 16, v141
	v_and_b32_e32 v141, 0xffff0000, v141
	v_mul_f32_e32 v134, 0.5, v134
	v_mul_f32_e32 v135, 0.5, v135
	v_fma_f32 v136, v48, v136, v138
	v_fma_f32 v137, v49, v137, v139
	v_fma_f32 v138, v44, v132, v140
	v_fma_f32 v139, v45, v133, v141
	v_fma_f32 v132, v42, v130, v158
	v_fma_f32 v133, v43, v131, v159
	v_fma_f32 v134, v46, v134, v156
	v_fma_f32 v135, v47, v135, v157
	s_and_b64 vcc, exec, s[6:7]
	v_cvt_pk_bf16_f32 v130, v134, v135
	v_cvt_pk_bf16_f32 v131, v136, v137
	v_cvt_pk_bf16_f32 v132, v132, v133
	v_cvt_pk_bf16_f32 v133, v138, v139
	global_store_dwordx4 v[154:155], v[130:133], off
	global_load_dwordx4 v[130:133], v[152:153], off offset:528
	global_load_dwordx4 v[134:137], v[152:153], off offset:512
	s_cbranch_vccnz .LBB0_1009
	global_load_dwordx4 v[138:141], v[150:151], off offset:512
	s_nop 0
	global_load_dwordx4 v[150:153], v[150:151], off offset:528
	s_waitcnt vmcnt(1)
	v_cvt_pk_bf16_f32 v138, v138, v139
	v_cvt_pk_bf16_f32 v139, v140, v141
	s_waitcnt vmcnt(0)
	v_cvt_pk_bf16_f32 v140, v150, v151
	v_cvt_pk_bf16_f32 v141, v152, v153
	v_lshl_add_u64 v[148:149], v[148:149], 0, v[144:145]
	v_lshl_add_u64 v[148:149], v[148:149], 1, s[8:9]
	s_cbranch_execnz .LBB0_936

.LBB0_936:
	s_waitcnt vmcnt(0)
	v_mul_f32_e32 v136, 0.5, v136
	v_mul_f32_e32 v137, 0.5, v137
	v_mul_f32_e32 v130, 0.5, v130
	v_mul_f32_e32 v131, 0.5, v131
	v_mul_f32_e32 v132, 0.5, v132
	v_mul_f32_e32 v133, 0.5, v133
	v_lshlrev_b32_e32 v150, 16, v138
	v_and_b32_e32 v151, 0xffff0000, v138
	v_lshlrev_b32_e32 v138, 16, v139
	v_and_b32_e32 v139, 0xffff0000, v139
	v_lshlrev_b32_e32 v152, 16, v140
	v_and_b32_e32 v153, 0xffff0000, v140
	v_lshlrev_b32_e32 v140, 16, v141
	v_and_b32_e32 v141, 0xffff0000, v141
	s_add_i32 s0, s46, 0xffff8020
	v_mul_f32_e32 v134, 0.5, v134
	v_mul_f32_e32 v135, 0.5, v135
	v_fma_f32 v136, v40, v136, v138
	v_fma_f32 v137, v41, v137, v139
	v_fma_f32 v138, v36, v132, v140
	v_fma_f32 v139, v37, v133, v141
	v_fma_f32 v132, v34, v130, v152
	v_fma_f32 v133, v35, v131, v153
	s_lshr_b32 s0, s0, 5
	v_fma_f32 v134, v38, v134, v150
	v_fma_f32 v135, v39, v135, v151
	s_add_i32 s0, s0, 4
	v_cvt_pk_bf16_f32 v130, v134, v135
	v_cvt_pk_bf16_f32 v131, v136, v137
	v_cvt_pk_bf16_f32 v132, v132, v133
	v_cvt_pk_bf16_f32 v133, v138, v139
	v_or_b32_e32 v138, 32, v146
	global_store_dwordx4 v[148:149], v[130:133], off
	v_cmp_gt_i32_e32 vcc, s75, v138
	v_ashrrev_i32_e32 v139, 31, v138
	v_mov_b32_e32 v130, s0
	v_mov_b32_e32 v131, s23
	v_cndmask_b32_e32 v132, v130, v131, vcc
	v_mov_b64_e32 v[130:131], s[10:11]
	v_mad_i64_i32 v[130:131], s[0:1], v132, s96, v[130:131]
	v_lshl_add_u64 v[152:153], v[142:143], 2, v[130:131]
	global_load_dwordx4 v[130:133], v[152:153], off offset:16
	global_load_dwordx4 v[134:137], v[152:153], off
	v_lshlrev_b64 v[148:149], 10, v[138:139]
	v_lshl_add_u64 v[154:155], v[148:149], 0, v[142:143]
	s_and_b64 vcc, exec, s[6:7]
	v_lshl_add_u64 v[150:151], v[154:155], 2, s[20:21]
	s_cbranch_vccnz .LBB0_1010
	global_load_dwordx4 v[138:141], v[150:151], off
	global_load_dwordx4 v[156:159], v[150:151], off offset:16
	s_waitcnt vmcnt(1)
	v_cvt_pk_bf16_f32 v138, v138, v139
	v_cvt_pk_bf16_f32 v139, v140, v141
	s_waitcnt vmcnt(0)
	v_cvt_pk_bf16_f32 v140, v156, v157
	v_cvt_pk_bf16_f32 v141, v158, v159
	v_lshl_add_u64 v[154:155], v[154:155], 1, s[8:9]
	s_cbranch_execnz .LBB0_939

.LBB0_939:
	s_waitcnt vmcnt(0)
	v_mul_f32_e32 v136, 0.5, v136
	v_mul_f32_e32 v137, 0.5, v137
	v_mul_f32_e32 v130, 0.5, v130
	v_mul_f32_e32 v131, 0.5, v131
	v_mul_f32_e32 v132, 0.5, v132
	v_mul_f32_e32 v133, 0.5, v133
	v_lshlrev_b32_e32 v156, 16, v138
	v_and_b32_e32 v157, 0xffff0000, v138
	v_lshlrev_b32_e32 v138, 16, v139
	v_and_b32_e32 v139, 0xffff0000, v139
	v_lshlrev_b32_e32 v158, 16, v140
	v_and_b32_e32 v159, 0xffff0000, v140
	v_lshlrev_b32_e32 v140, 16, v141
	v_and_b32_e32 v141, 0xffff0000, v141
	v_mul_f32_e32 v134, 0.5, v134
	v_mul_f32_e32 v135, 0.5, v135
	v_fma_f32 v136, v32, v136, v138
	v_fma_f32 v137, v33, v137, v139
	v_fma_f32 v138, v28, v132, v140
	v_fma_f32 v139, v29, v133, v141
	v_fma_f32 v132, v26, v130, v158
	v_fma_f32 v133, v27, v131, v159
	v_fma_f32 v134, v30, v134, v156
	v_fma_f32 v135, v31, v135, v157
	s_and_b64 vcc, exec, s[6:7]
	v_cvt_pk_bf16_f32 v130, v134, v135
	v_cvt_pk_bf16_f32 v131, v136, v137
	v_cvt_pk_bf16_f32 v132, v132, v133
	v_cvt_pk_bf16_f32 v133, v138, v139
	global_store_dwordx4 v[154:155], v[130:133], off
	global_load_dwordx4 v[130:133], v[152:153], off offset:528
	global_load_dwordx4 v[134:137], v[152:153], off offset:512
	s_cbranch_vccnz .LBB0_1011
	global_load_dwordx4 v[138:141], v[150:151], off offset:512
	s_nop 0
	global_load_dwordx4 v[150:153], v[150:151], off offset:528
	s_waitcnt vmcnt(1)
	v_cvt_pk_bf16_f32 v138, v138, v139
	v_cvt_pk_bf16_f32 v139, v140, v141
	s_waitcnt vmcnt(0)
	v_cvt_pk_bf16_f32 v140, v150, v151
	v_cvt_pk_bf16_f32 v141, v152, v153
	v_lshl_add_u64 v[148:149], v[148:149], 0, v[144:145]
	v_lshl_add_u64 v[148:149], v[148:149], 1, s[8:9]
	s_cbranch_execnz .LBB0_942

.LBB0_942:
	s_waitcnt vmcnt(0)
	v_mul_f32_e32 v136, 0.5, v136
	v_mul_f32_e32 v137, 0.5, v137
	v_mul_f32_e32 v130, 0.5, v130
	v_mul_f32_e32 v131, 0.5, v131
	v_mul_f32_e32 v132, 0.5, v132
	v_mul_f32_e32 v133, 0.5, v133
	v_lshlrev_b32_e32 v150, 16, v138
	v_and_b32_e32 v151, 0xffff0000, v138
	v_lshlrev_b32_e32 v138, 16, v139
	v_and_b32_e32 v139, 0xffff0000, v139
	v_lshlrev_b32_e32 v152, 16, v140
	v_and_b32_e32 v153, 0xffff0000, v140
	v_lshlrev_b32_e32 v140, 16, v141
	v_and_b32_e32 v141, 0xffff0000, v141
	s_addk_i32 s46, 0x8030
	v_mul_f32_e32 v134, 0.5, v134
	v_mul_f32_e32 v135, 0.5, v135
	v_fma_f32 v136, v24, v136, v138
	v_fma_f32 v137, v25, v137, v139
	v_fma_f32 v138, v20, v132, v140
	v_fma_f32 v139, v21, v133, v141
	v_fma_f32 v132, v18, v130, v152
	v_fma_f32 v133, v19, v131, v153
	s_lshr_b32 s0, s46, 5
	v_fma_f32 v134, v22, v134, v150
	v_fma_f32 v135, v23, v135, v151
	s_add_i32 s0, s0, 4
	v_cvt_pk_bf16_f32 v130, v134, v135
	v_cvt_pk_bf16_f32 v131, v136, v137
	v_cvt_pk_bf16_f32 v132, v132, v133
	v_cvt_pk_bf16_f32 v133, v138, v139
	v_or_b32_e32 v138, 48, v146
	global_store_dwordx4 v[148:149], v[130:133], off
	v_cmp_gt_i32_e32 vcc, s75, v138
	v_ashrrev_i32_e32 v139, 31, v138
	v_mov_b32_e32 v130, s0
	v_mov_b32_e32 v131, s23
	v_cndmask_b32_e32 v132, v130, v131, vcc
	v_mov_b64_e32 v[130:131], s[10:11]
	v_mad_i64_i32 v[130:131], s[0:1], v132, s96, v[130:131]
	v_lshl_add_u64 v[148:149], v[142:143], 2, v[130:131]
	global_load_dwordx4 v[130:133], v[148:149], off offset:16
	global_load_dwordx4 v[134:137], v[148:149], off
	v_lshlrev_b64 v[146:147], 10, v[138:139]
	v_lshl_add_u64 v[150:151], v[146:147], 0, v[142:143]
	s_and_b64 vcc, exec, s[6:7]
	v_lshl_add_u64 v[142:143], v[150:151], 2, s[20:21]
	s_cbranch_vccnz .LBB0_1012
	global_load_dwordx4 v[138:141], v[142:143], off
	global_load_dwordx4 v[152:155], v[142:143], off offset:16
	s_waitcnt vmcnt(1)
	v_cvt_pk_bf16_f32 v138, v138, v139
	v_cvt_pk_bf16_f32 v139, v140, v141
	s_waitcnt vmcnt(0)
	v_cvt_pk_bf16_f32 v140, v152, v153
	v_cvt_pk_bf16_f32 v141, v154, v155
	v_lshl_add_u64 v[150:151], v[150:151], 1, s[8:9]
	s_cbranch_execnz .LBB0_945

.LBB0_945:
	s_waitcnt vmcnt(0)
	v_mul_f32_e32 v136, 0.5, v136
	v_mul_f32_e32 v137, 0.5, v137
	v_mul_f32_e32 v130, 0.5, v130
	v_mul_f32_e32 v131, 0.5, v131
	v_mul_f32_e32 v132, 0.5, v132
	v_mul_f32_e32 v133, 0.5, v133
	v_lshlrev_b32_e32 v152, 16, v138
	v_and_b32_e32 v153, 0xffff0000, v138
	v_lshlrev_b32_e32 v138, 16, v139
	v_and_b32_e32 v139, 0xffff0000, v139
	v_lshlrev_b32_e32 v154, 16, v140
	v_and_b32_e32 v155, 0xffff0000, v140
	v_lshlrev_b32_e32 v140, 16, v141
	v_and_b32_e32 v141, 0xffff0000, v141
	v_mul_f32_e32 v134, 0.5, v134
	v_mul_f32_e32 v135, 0.5, v135
	v_fma_f32 v136, v16, v136, v138
	v_fma_f32 v137, v17, v137, v139
	v_fma_f32 v138, v12, v132, v140
	v_fma_f32 v139, v13, v133, v141
	v_fma_f32 v132, v10, v130, v154
	v_fma_f32 v133, v11, v131, v155
	v_fma_f32 v134, v14, v134, v152
	v_fma_f32 v135, v15, v135, v153
	s_and_b64 vcc, exec, s[6:7]
	v_cvt_pk_bf16_f32 v130, v134, v135
	v_cvt_pk_bf16_f32 v131, v136, v137
	v_cvt_pk_bf16_f32 v132, v132, v133
	v_cvt_pk_bf16_f32 v133, v138, v139
	global_store_dwordx4 v[150:151], v[130:133], off
	global_load_dwordx4 v[130:133], v[148:149], off offset:528
	global_load_dwordx4 v[134:137], v[148:149], off offset:512
	s_cbranch_vccnz .LBB0_1013
	global_load_dwordx4 v[138:141], v[142:143], off offset:512
	global_load_dwordx4 v[148:151], v[142:143], off offset:528
	s_waitcnt vmcnt(1)
	v_cvt_pk_bf16_f32 v138, v138, v139
	v_cvt_pk_bf16_f32 v139, v140, v141
	s_waitcnt vmcnt(0)
	v_cvt_pk_bf16_f32 v140, v148, v149
	v_cvt_pk_bf16_f32 v141, v150, v151
	v_lshl_add_u64 v[142:143], v[146:147], 0, v[144:145]
	v_lshl_add_u64 v[142:143], v[142:143], 1, s[8:9]
	s_cbranch_execnz .LBB0_948

.LBB0_948:
	s_waitcnt vmcnt(0)
	v_mul_f32_e32 v136, 0.5, v136
	v_mul_f32_e32 v137, 0.5, v137
	v_mul_f32_e32 v130, 0.5, v130
	v_mul_f32_e32 v131, 0.5, v131
	v_mul_f32_e32 v132, 0.5, v132
	v_mul_f32_e32 v133, 0.5, v133
	v_lshlrev_b32_e32 v144, 16, v138
	v_and_b32_e32 v145, 0xffff0000, v138
	v_lshlrev_b32_e32 v138, 16, v139
	v_and_b32_e32 v139, 0xffff0000, v139
	v_lshlrev_b32_e32 v146, 16, v140
	v_and_b32_e32 v147, 0xffff0000, v140
	v_lshlrev_b32_e32 v140, 16, v141
	v_and_b32_e32 v141, 0xffff0000, v141
	v_mul_f32_e32 v134, 0.5, v134
	v_mul_f32_e32 v135, 0.5, v135
	v_fma_f32 v136, v8, v136, v138
	v_fma_f32 v137, v9, v137, v139
	v_fma_f32 v138, v4, v132, v140
	v_fma_f32 v139, v5, v133, v141
	v_fma_f32 v132, v2, v130, v146
	v_fma_f32 v133, v3, v131, v147
	v_fma_f32 v134, v6, v134, v144
	v_fma_f32 v135, v7, v135, v145
	s_nop 0
	v_cvt_pk_bf16_f32 v130, v134, v135
	v_cvt_pk_bf16_f32 v131, v136, v137
	v_cvt_pk_bf16_f32 v132, v132, v133
	v_cvt_pk_bf16_f32 v133, v138, v139
	global_store_dwordx4 v[142:143], v[130:133], off
	s_branch .LBB0_894

.LBB0_961:
	s_waitcnt vmcnt(0)
	v_mul_f32_e32 v152, 0.5, v152
	v_mul_f32_e32 v153, 0.5, v153
	v_mul_f32_e32 v150, 0.5, v150
	v_mul_f32_e32 v151, 0.5, v151
	v_mul_f32_e32 v148, 0.5, v148
	v_mul_f32_e32 v149, 0.5, v149
	v_mul_f32_e32 v146, 0.5, v146
	v_mul_f32_e32 v147, 0.5, v147
	v_lshlrev_b32_e32 v178, 16, v154
	v_and_b32_e32 v179, 0xffff0000, v154
	v_lshlrev_b32_e32 v154, 16, v155
	v_and_b32_e32 v155, 0xffff0000, v155
	v_lshlrev_b32_e32 v188, 16, v156
	v_and_b32_e32 v189, 0xffff0000, v156
	v_lshlrev_b32_e32 v156, 16, v157
	v_and_b32_e32 v157, 0xffff0000, v157
	v_fma_f32 v128, v128, v152, v154
	v_fma_f32 v129, v129, v153, v155
	v_fma_f32 v126, v126, v150, v178
	v_fma_f32 v127, v127, v151, v179
	v_fma_f32 v154, v124, v148, v156
	v_fma_f32 v155, v125, v149, v157
	v_fma_f32 v124, v122, v146, v188
	v_fma_f32 v125, v123, v147, v189
	v_cvt_pk_bf16_f32 v122, v126, v127
	v_cvt_pk_bf16_f32 v123, v128, v129
	v_mul_f32_e32 v142, 0.5, v142
	v_mul_f32_e32 v143, 0.5, v143
	v_mul_f32_e32 v140, 0.5, v140
	v_mul_f32_e32 v141, 0.5, v141
	v_mul_f32_e32 v138, 0.5, v138
	v_mul_f32_e32 v139, 0.5, v139
	v_cvt_pk_bf16_f32 v124, v124, v125
	v_cvt_pk_bf16_f32 v125, v154, v155
	global_store_dwordx4 v[174:175], v[122:125], off
	v_lshlrev_b32_e32 v126, 16, v160
	v_and_b32_e32 v127, 0xffff0000, v160
	v_lshlrev_b32_e32 v122, 16, v158
	v_and_b32_e32 v123, 0xffff0000, v158
	v_lshlrev_b32_e32 v128, 16, v161
	v_and_b32_e32 v129, 0xffff0000, v161
	v_mul_f32_e32 v144, 0.5, v144
	v_mul_f32_e32 v145, 0.5, v145
	v_lshlrev_b32_e32 v124, 16, v159
	v_and_b32_e32 v125, 0xffff0000, v159
	v_fma_f32 v118, v118, v142, v122
	v_fma_f32 v119, v119, v143, v123
	v_fma_f32 v122, v116, v140, v128
	v_fma_f32 v123, v117, v141, v129
	v_fma_f32 v116, v114, v138, v126
	v_fma_f32 v117, v115, v139, v127
	v_fma_f32 v120, v120, v144, v124
	v_fma_f32 v121, v121, v145, v125
	v_cvt_pk_bf16_f32 v114, v118, v119
	s_mov_b64 s[0:1], 0x8000
	v_cvt_pk_bf16_f32 v115, v120, v121
	v_cvt_pk_bf16_f32 v116, v116, v117
	v_cvt_pk_bf16_f32 v117, v122, v123
	global_store_dwordx4 v[174:175], v[114:117], off offset:256
	s_and_b64 vcc, exec, s[6:7]
	v_lshl_add_u64 v[118:119], v[176:177], 0, s[0:1]
	s_cbranch_vccnz .LBB0_1018
	v_lshl_add_u64 v[120:121], v[118:119], 2, s[20:21]
	global_load_dwordx4 v[114:117], v[120:121], off
	s_nop 0
	global_load_dwordx4 v[120:123], v[120:121], off offset:16
	s_waitcnt vmcnt(1)
	v_cvt_pk_bf16_f32 v114, v114, v115
	v_cvt_pk_bf16_f32 v115, v116, v117
	s_waitcnt vmcnt(0)
	v_cvt_pk_bf16_f32 v116, v120, v121
	v_cvt_pk_bf16_f32 v117, v122, v123
	s_cbranch_execnz .LBB0_964

.LBB0_967:
	v_lshlrev_b32_e32 v122, 16, v130
	v_and_b32_e32 v123, 0xffff0000, v130
	v_lshlrev_b32_e32 v126, 16, v132
	v_and_b32_e32 v127, 0xffff0000, v132
	v_lshlrev_b32_e32 v128, 16, v133
	v_and_b32_e32 v129, 0xffff0000, v133
	v_fma_f32 v110, v110, v150, v122
	v_fma_f32 v111, v111, v151, v123
	v_lshlrev_b32_e32 v124, 16, v131
	v_and_b32_e32 v125, 0xffff0000, v131
	v_fma_f32 v122, v108, v148, v128
	v_fma_f32 v123, v109, v149, v129
	v_fma_f32 v108, v106, v146, v126
	v_fma_f32 v109, v107, v147, v127
	v_cvt_pk_bf16_f32 v106, v110, v111
	v_add_co_u32_e32 v110, vcc, s75, v174
	v_fma_f32 v112, v112, v152, v124
	v_fma_f32 v113, v113, v153, v125
	s_nop 0
	v_addc_co_u32_e32 v111, vcc, 0, v175, vcc
	v_cvt_pk_bf16_f32 v107, v112, v113
	v_cvt_pk_bf16_f32 v108, v108, v109
	v_cvt_pk_bf16_f32 v109, v122, v123
	global_store_dwordx4 v[110:111], v[106:109], off
	v_lshlrev_b32_e32 v112, 16, v136
	v_and_b32_e32 v113, 0xffff0000, v136
	v_lshlrev_b32_e32 v106, 16, v134
	v_and_b32_e32 v107, 0xffff0000, v134
	v_lshlrev_b32_e32 v122, 16, v137
	v_and_b32_e32 v123, 0xffff0000, v137
	v_lshlrev_b32_e32 v108, 16, v135
	v_and_b32_e32 v109, 0xffff0000, v135
	v_fma_f32 v102, v102, v142, v106
	v_fma_f32 v103, v103, v143, v107
	v_fma_f32 v106, v100, v140, v122
	v_fma_f32 v107, v101, v141, v123
	v_fma_f32 v100, v98, v138, v112
	v_fma_f32 v101, v99, v139, v113
	v_fma_f32 v104, v104, v144, v108
	v_fma_f32 v105, v105, v145, v109
	v_cvt_pk_bf16_f32 v98, v102, v103
	s_mov_b64 s[0:1], 0xc000
	v_cvt_pk_bf16_f32 v99, v104, v105
	v_cvt_pk_bf16_f32 v100, v100, v101
	v_cvt_pk_bf16_f32 v101, v106, v107
	global_store_dwordx4 v[110:111], v[98:101], off offset:256
	s_and_b64 vcc, exec, s[6:7]
	v_lshl_add_u64 v[102:103], v[176:177], 0, s[0:1]
	s_cbranch_vccnz .LBB0_1020
	v_lshl_add_u64 v[104:105], v[102:103], 2, s[20:21]
	global_load_dwordx4 v[98:101], v[104:105], off
	s_nop 0
	global_load_dwordx4 v[104:107], v[104:105], off offset:16
	s_waitcnt vmcnt(1)
	v_cvt_pk_bf16_f32 v98, v98, v99
	v_cvt_pk_bf16_f32 v99, v100, v101
	s_waitcnt vmcnt(0)
	v_cvt_pk_bf16_f32 v100, v104, v105
	v_cvt_pk_bf16_f32 v101, v106, v107
	s_cbranch_execnz .LBB0_970

.LBB0_973:
	s_waitcnt vmcnt(2)
	v_lshlrev_b32_e32 v106, 16, v114
	v_and_b32_e32 v107, 0xffff0000, v114
	v_lshlrev_b32_e32 v110, 16, v116
	v_and_b32_e32 v111, 0xffff0000, v116
	v_lshlrev_b32_e32 v112, 16, v117
	v_and_b32_e32 v113, 0xffff0000, v117
	v_fma_f32 v94, v94, v150, v106
	v_fma_f32 v95, v95, v151, v107
	s_mov_b32 s0, 0x10000
	v_lshlrev_b32_e32 v108, 16, v115
	v_and_b32_e32 v109, 0xffff0000, v115
	v_fma_f32 v106, v92, v148, v112
	v_fma_f32 v107, v93, v149, v113
	v_fma_f32 v92, v90, v146, v110
	v_fma_f32 v93, v91, v147, v111
	v_cvt_pk_bf16_f32 v90, v94, v95
	v_add_co_u32_e32 v94, vcc, s0, v174
	v_fma_f32 v96, v96, v152, v108
	v_fma_f32 v97, v97, v153, v109
	s_nop 0
	v_addc_co_u32_e32 v95, vcc, 0, v175, vcc
	v_cvt_pk_bf16_f32 v91, v96, v97
	v_cvt_pk_bf16_f32 v92, v92, v93
	v_cvt_pk_bf16_f32 v93, v106, v107
	global_store_dwordx4 v[94:95], v[90:93], off
	v_lshlrev_b32_e32 v96, 16, v120
	v_and_b32_e32 v97, 0xffff0000, v120
	v_lshlrev_b32_e32 v90, 16, v118
	v_and_b32_e32 v91, 0xffff0000, v118
	v_lshlrev_b32_e32 v106, 16, v121
	v_and_b32_e32 v107, 0xffff0000, v121
	v_lshlrev_b32_e32 v92, 16, v119
	v_and_b32_e32 v93, 0xffff0000, v119
	v_fma_f32 v86, v86, v142, v90
	v_fma_f32 v87, v87, v143, v91
	v_fma_f32 v90, v84, v140, v106
	v_fma_f32 v91, v85, v141, v107
	v_fma_f32 v84, v82, v138, v96
	v_fma_f32 v85, v83, v139, v97
	v_fma_f32 v88, v88, v144, v92
	v_fma_f32 v89, v89, v145, v93
	v_cvt_pk_bf16_f32 v82, v86, v87
	s_mov_b64 s[0:1], 0x20000
	v_cvt_pk_bf16_f32 v83, v88, v89
	v_cvt_pk_bf16_f32 v84, v84, v85
	v_cvt_pk_bf16_f32 v85, v90, v91
	global_store_dwordx4 v[94:95], v[82:85], off offset:256
	s_and_b64 vcc, exec, s[6:7]
	v_lshl_add_u64 v[86:87], v[176:177], 0, s[0:1]
	s_cbranch_vccnz .LBB0_1022
	v_lshl_add_u64 v[88:89], v[86:87], 2, s[20:21]
	global_load_dwordx4 v[82:85], v[88:89], off
	s_nop 0
	global_load_dwordx4 v[88:91], v[88:89], off offset:16
	s_waitcnt vmcnt(1)
	v_cvt_pk_bf16_f32 v82, v82, v83
	v_cvt_pk_bf16_f32 v83, v84, v85
	s_waitcnt vmcnt(0)
	v_cvt_pk_bf16_f32 v84, v88, v89
	v_cvt_pk_bf16_f32 v85, v90, v91
	s_cbranch_execnz .LBB0_976

.LBB0_979:
	s_waitcnt vmcnt(2)
	v_lshlrev_b32_e32 v90, 16, v98
	v_and_b32_e32 v91, 0xffff0000, v98
	v_lshlrev_b32_e32 v94, 16, v100
	v_and_b32_e32 v95, 0xffff0000, v100
	v_lshlrev_b32_e32 v96, 16, v101
	v_and_b32_e32 v97, 0xffff0000, v101
	v_fma_f32 v78, v78, v150, v90
	v_fma_f32 v79, v79, v151, v91
	s_mov_b32 s0, 0x18000
	v_lshlrev_b32_e32 v92, 16, v99
	v_and_b32_e32 v93, 0xffff0000, v99
	v_fma_f32 v90, v76, v148, v96
	v_fma_f32 v91, v77, v149, v97
	v_fma_f32 v76, v74, v146, v94
	v_fma_f32 v77, v75, v147, v95
	v_cvt_pk_bf16_f32 v74, v78, v79
	v_add_co_u32_e32 v78, vcc, s0, v174
	v_fma_f32 v80, v80, v152, v92
	v_fma_f32 v81, v81, v153, v93
	s_nop 0
	v_addc_co_u32_e32 v79, vcc, 0, v175, vcc
	v_cvt_pk_bf16_f32 v75, v80, v81
	v_cvt_pk_bf16_f32 v76, v76, v77
	v_cvt_pk_bf16_f32 v77, v90, v91
	global_store_dwordx4 v[78:79], v[74:77], off
	v_lshlrev_b32_e32 v80, 16, v104
	v_and_b32_e32 v81, 0xffff0000, v104
	v_lshlrev_b32_e32 v74, 16, v102
	v_and_b32_e32 v75, 0xffff0000, v102
	v_lshlrev_b32_e32 v90, 16, v105
	v_and_b32_e32 v91, 0xffff0000, v105
	v_lshlrev_b32_e32 v76, 16, v103
	v_and_b32_e32 v77, 0xffff0000, v103
	v_fma_f32 v70, v70, v142, v74
	v_fma_f32 v71, v71, v143, v75
	v_fma_f32 v74, v68, v140, v90
	v_fma_f32 v75, v69, v141, v91
	v_fma_f32 v68, v66, v138, v80
	v_fma_f32 v69, v67, v139, v81
	v_fma_f32 v72, v72, v144, v76
	v_fma_f32 v73, v73, v145, v77
	v_cvt_pk_bf16_f32 v66, v70, v71
	s_mov_b64 s[0:1], 0x24000
	v_cvt_pk_bf16_f32 v67, v72, v73
	v_cvt_pk_bf16_f32 v68, v68, v69
	v_cvt_pk_bf16_f32 v69, v74, v75
	global_store_dwordx4 v[78:79], v[66:69], off offset:256
	s_and_b64 vcc, exec, s[6:7]
	v_lshl_add_u64 v[70:71], v[176:177], 0, s[0:1]
	s_cbranch_vccnz .LBB0_1024
	v_lshl_add_u64 v[72:73], v[70:71], 2, s[20:21]
	global_load_dwordx4 v[66:69], v[72:73], off
	s_nop 0
	global_load_dwordx4 v[72:75], v[72:73], off offset:16
	s_waitcnt vmcnt(1)
	v_cvt_pk_bf16_f32 v66, v66, v67
	v_cvt_pk_bf16_f32 v67, v68, v69
	s_waitcnt vmcnt(0)
	v_cvt_pk_bf16_f32 v68, v72, v73
	v_cvt_pk_bf16_f32 v69, v74, v75
	s_cbranch_execnz .LBB0_982

.LBB0_985:
	s_waitcnt vmcnt(2)
	v_lshlrev_b32_e32 v74, 16, v82
	v_and_b32_e32 v75, 0xffff0000, v82
	v_lshlrev_b32_e32 v78, 16, v84
	v_and_b32_e32 v79, 0xffff0000, v84
	v_lshlrev_b32_e32 v80, 16, v85
	v_and_b32_e32 v81, 0xffff0000, v85
	v_fma_f32 v62, v62, v150, v74
	v_fma_f32 v63, v63, v151, v75
	s_mov_b32 s0, 0x40000
	v_lshlrev_b32_e32 v76, 16, v83
	v_and_b32_e32 v77, 0xffff0000, v83
	v_fma_f32 v74, v60, v148, v80
	v_fma_f32 v75, v61, v149, v81
	v_fma_f32 v60, v58, v146, v78
	v_fma_f32 v61, v59, v147, v79
	v_cvt_pk_bf16_f32 v58, v62, v63
	v_add_co_u32_e32 v62, vcc, s0, v174
	v_fma_f32 v64, v64, v152, v76
	v_fma_f32 v65, v65, v153, v77
	s_nop 0
	v_addc_co_u32_e32 v63, vcc, 0, v175, vcc
	v_cvt_pk_bf16_f32 v59, v64, v65
	v_cvt_pk_bf16_f32 v60, v60, v61
	v_cvt_pk_bf16_f32 v61, v74, v75
	global_store_dwordx4 v[62:63], v[58:61], off
	v_lshlrev_b32_e32 v64, 16, v88
	v_and_b32_e32 v65, 0xffff0000, v88
	v_lshlrev_b32_e32 v58, 16, v86
	v_and_b32_e32 v59, 0xffff0000, v86
	v_lshlrev_b32_e32 v74, 16, v89
	v_and_b32_e32 v75, 0xffff0000, v89
	v_lshlrev_b32_e32 v60, 16, v87
	v_and_b32_e32 v61, 0xffff0000, v87
	v_fma_f32 v54, v54, v142, v58
	v_fma_f32 v55, v55, v143, v59
	v_fma_f32 v58, v52, v140, v74
	v_fma_f32 v59, v53, v141, v75
	v_fma_f32 v52, v50, v138, v64
	v_fma_f32 v53, v51, v139, v65
	v_fma_f32 v56, v56, v144, v60
	v_fma_f32 v57, v57, v145, v61
	v_cvt_pk_bf16_f32 v50, v54, v55
	s_mov_b64 s[0:1], 0x28000
	v_cvt_pk_bf16_f32 v51, v56, v57
	v_cvt_pk_bf16_f32 v52, v52, v53
	v_cvt_pk_bf16_f32 v53, v58, v59
	global_store_dwordx4 v[62:63], v[50:53], off offset:256
	s_and_b64 vcc, exec, s[6:7]
	v_lshl_add_u64 v[54:55], v[176:177], 0, s[0:1]
	s_cbranch_vccnz .LBB0_1026
	v_lshl_add_u64 v[56:57], v[54:55], 2, s[20:21]
	global_load_dwordx4 v[50:53], v[56:57], off
	s_nop 0
	global_load_dwordx4 v[56:59], v[56:57], off offset:16
	s_waitcnt vmcnt(1)
	v_cvt_pk_bf16_f32 v50, v50, v51
	v_cvt_pk_bf16_f32 v51, v52, v53
	s_waitcnt vmcnt(0)
	v_cvt_pk_bf16_f32 v52, v56, v57
	v_cvt_pk_bf16_f32 v53, v58, v59
	s_cbranch_execnz .LBB0_988

.LBB0_991:
	s_waitcnt vmcnt(2)
	v_lshlrev_b32_e32 v58, 16, v66
	v_and_b32_e32 v59, 0xffff0000, v66
	v_lshlrev_b32_e32 v62, 16, v68
	v_and_b32_e32 v63, 0xffff0000, v68
	v_lshlrev_b32_e32 v64, 16, v69
	v_and_b32_e32 v65, 0xffff0000, v69
	v_fma_f32 v46, v46, v150, v58
	v_fma_f32 v47, v47, v151, v59
	s_mov_b32 s0, 0x48000
	v_lshlrev_b32_e32 v60, 16, v67
	v_and_b32_e32 v61, 0xffff0000, v67
	v_fma_f32 v58, v44, v148, v64
	v_fma_f32 v59, v45, v149, v65
	v_fma_f32 v44, v42, v146, v62
	v_fma_f32 v45, v43, v147, v63
	v_cvt_pk_bf16_f32 v42, v46, v47
	v_add_co_u32_e32 v46, vcc, s0, v174
	v_fma_f32 v48, v48, v152, v60
	v_fma_f32 v49, v49, v153, v61
	s_nop 0
	v_addc_co_u32_e32 v47, vcc, 0, v175, vcc
	v_cvt_pk_bf16_f32 v43, v48, v49
	v_cvt_pk_bf16_f32 v44, v44, v45
	v_cvt_pk_bf16_f32 v45, v58, v59
	global_store_dwordx4 v[46:47], v[42:45], off
	v_lshlrev_b32_e32 v48, 16, v72
	v_and_b32_e32 v49, 0xffff0000, v72
	v_lshlrev_b32_e32 v42, 16, v70
	v_and_b32_e32 v43, 0xffff0000, v70
	v_lshlrev_b32_e32 v58, 16, v73
	v_and_b32_e32 v59, 0xffff0000, v73
	v_lshlrev_b32_e32 v44, 16, v71
	v_and_b32_e32 v45, 0xffff0000, v71
	v_fma_f32 v38, v38, v142, v42
	v_fma_f32 v39, v39, v143, v43
	v_fma_f32 v42, v36, v140, v58
	v_fma_f32 v43, v37, v141, v59
	v_fma_f32 v36, v34, v138, v48
	v_fma_f32 v37, v35, v139, v49
	v_fma_f32 v40, v40, v144, v44
	v_fma_f32 v41, v41, v145, v45
	v_cvt_pk_bf16_f32 v34, v38, v39
	s_mov_b64 s[0:1], 0x2c000
	v_cvt_pk_bf16_f32 v35, v40, v41
	v_cvt_pk_bf16_f32 v36, v36, v37
	v_cvt_pk_bf16_f32 v37, v42, v43
	global_store_dwordx4 v[46:47], v[34:37], off offset:256
	s_and_b64 vcc, exec, s[6:7]
	v_lshl_add_u64 v[38:39], v[176:177], 0, s[0:1]
	s_cbranch_vccnz .LBB0_1028
	v_lshl_add_u64 v[40:41], v[38:39], 2, s[20:21]
	global_load_dwordx4 v[34:37], v[40:41], off
	s_nop 0
	global_load_dwordx4 v[40:43], v[40:41], off offset:16
	s_waitcnt vmcnt(1)
	v_cvt_pk_bf16_f32 v34, v34, v35
	v_cvt_pk_bf16_f32 v35, v36, v37
	s_waitcnt vmcnt(0)
	v_cvt_pk_bf16_f32 v36, v40, v41
	v_cvt_pk_bf16_f32 v37, v42, v43
	s_cbranch_execnz .LBB0_994

.LBB0_997:
	s_waitcnt vmcnt(2)
	v_lshlrev_b32_e32 v42, 16, v50
	v_and_b32_e32 v43, 0xffff0000, v50
	v_lshlrev_b32_e32 v46, 16, v52
	v_and_b32_e32 v47, 0xffff0000, v52
	v_lshlrev_b32_e32 v48, 16, v53
	v_and_b32_e32 v49, 0xffff0000, v53
	v_fma_f32 v30, v30, v150, v42
	v_fma_f32 v31, v31, v151, v43
	s_mov_b32 s0, 0x50000
	v_lshlrev_b32_e32 v44, 16, v51
	v_and_b32_e32 v45, 0xffff0000, v51
	v_fma_f32 v42, v28, v148, v48
	v_fma_f32 v43, v29, v149, v49
	v_fma_f32 v28, v26, v146, v46
	v_fma_f32 v29, v27, v147, v47
	v_cvt_pk_bf16_f32 v26, v30, v31
	v_add_co_u32_e32 v30, vcc, s0, v174
	v_fma_f32 v32, v32, v152, v44
	v_fma_f32 v33, v33, v153, v45
	s_nop 0
	v_addc_co_u32_e32 v31, vcc, 0, v175, vcc
	v_cvt_pk_bf16_f32 v27, v32, v33
	v_cvt_pk_bf16_f32 v28, v28, v29
	v_cvt_pk_bf16_f32 v29, v42, v43
	global_store_dwordx4 v[30:31], v[26:29], off
	v_lshlrev_b32_e32 v32, 16, v56
	v_and_b32_e32 v33, 0xffff0000, v56
	v_lshlrev_b32_e32 v26, 16, v54
	v_and_b32_e32 v27, 0xffff0000, v54
	v_lshlrev_b32_e32 v28, 16, v55
	v_and_b32_e32 v29, 0xffff0000, v55
	v_lshlrev_b32_e32 v42, 16, v57
	v_and_b32_e32 v43, 0xffff0000, v57
	v_fma_f32 v24, v24, v144, v28
	v_fma_f32 v25, v25, v145, v29
	v_fma_f32 v22, v22, v142, v26
	v_fma_f32 v23, v23, v143, v27
	v_fma_f32 v26, v20, v140, v42
	v_fma_f32 v27, v21, v141, v43
	v_fma_f32 v20, v18, v138, v32
	v_fma_f32 v21, v19, v139, v33
	v_cvt_pk_bf16_f32 v18, v22, v23
	v_cvt_pk_bf16_f32 v19, v24, v25
	s_waitcnt vmcnt(1)
	v_lshlrev_b32_e32 v22, 16, v36
	v_cvt_pk_bf16_f32 v20, v20, v21
	v_cvt_pk_bf16_f32 v21, v26, v27
	global_store_dwordx4 v[30:31], v[18:21], off offset:256
	v_and_b32_e32 v23, 0xffff0000, v36
	v_lshlrev_b32_e32 v24, 16, v37
	v_lshlrev_b32_e32 v18, 16, v34
	v_and_b32_e32 v19, 0xffff0000, v34
	v_and_b32_e32 v25, 0xffff0000, v37
	v_fma_f32 v14, v14, v150, v18
	v_fma_f32 v15, v15, v151, v19
	s_mov_b32 s0, 0x58000
	v_lshlrev_b32_e32 v20, 16, v35
	v_and_b32_e32 v21, 0xffff0000, v35
	v_fma_f32 v18, v12, v148, v24
	v_fma_f32 v19, v13, v149, v25
	v_fma_f32 v12, v10, v146, v22
	v_fma_f32 v13, v11, v147, v23
	v_cvt_pk_bf16_f32 v10, v14, v15
	v_add_co_u32_e32 v14, vcc, s0, v174
	v_fma_f32 v16, v16, v152, v20
	v_fma_f32 v17, v17, v153, v21
	s_nop 0
	v_addc_co_u32_e32 v15, vcc, 0, v175, vcc
	v_cvt_pk_bf16_f32 v11, v16, v17
	v_cvt_pk_bf16_f32 v12, v12, v13
	v_cvt_pk_bf16_f32 v13, v18, v19
	global_store_dwordx4 v[14:15], v[10:13], off
	v_lshlrev_b32_e32 v16, 16, v40
	v_and_b32_e32 v17, 0xffff0000, v40
	v_lshlrev_b32_e32 v10, 16, v38
	v_and_b32_e32 v11, 0xffff0000, v38
	v_lshlrev_b32_e32 v18, 16, v41
	v_and_b32_e32 v19, 0xffff0000, v41
	v_lshlrev_b32_e32 v12, 16, v39
	v_and_b32_e32 v13, 0xffff0000, v39
	v_fma_f32 v6, v6, v142, v10
	v_fma_f32 v7, v7, v143, v11
	v_fma_f32 v10, v4, v140, v18
	v_fma_f32 v11, v5, v141, v19
	v_fma_f32 v4, v2, v138, v16
	v_fma_f32 v5, v3, v139, v17
	v_fma_f32 v8, v8, v144, v12
	v_fma_f32 v9, v9, v145, v13
	v_cvt_pk_bf16_f32 v2, v6, v7
	s_nop 0
	v_cvt_pk_bf16_f32 v3, v8, v9
	v_cvt_pk_bf16_f32 v4, v4, v5
	v_cvt_pk_bf16_f32 v5, v10, v11
	global_store_dwordx4 v[14:15], v[2:5], off offset:256
	s_and_b64 vcc, exec, s[4:5]
	s_mov_b64 s[0:1], -1
	s_cbranch_vccnz .LBB0_881

.LBB0_1045:
	s_or_b64 exec, exec, s[0:1]
	s_barrier
	s_getreg_b32 s0, hwreg(HW_REG_HW_ID, 0, 7)
	s_and_b32 s0, s0, 63
	s_lshl_b32 s0, s0, 2
	s_add_i32 s0, s0, 0x22240
	v_mov_b32_e32 v0, s0
	ds_read_b32 v0, v0
	v_mbcnt_lo_u32_b32 v2, -1, 0
	v_mbcnt_hi_u32_b32 v2, -1, v2
	s_mov_b64 s[2:3], s[70:71]
	v_readlane_b32 s6, v254, 5
	v_readlane_b32 s7, v254, 6
	s_waitcnt lgkmcnt(0)
	v_lshl_or_b32 v38, v0, 6, v2
	v_readlane_b32 s5, v253, 60
	v_readfirstlane_b32 s0, v38
	s_ashr_i32 s4, s0, 6
	s_mov_b32 s0, s72
	s_mov_b64 s[0:1], s[70:71]
	s_load_dwordx2 s[0:1], s[0:1], 0xd0
	s_load_dwordx2 s[2:3], s[2:3], 0x60
	v_and_b32_e32 v0, 63, v2
	v_lshlrev_b32_e32 v36, 4, v0
	v_lshlrev_b32_e32 v44, 2, v0
	v_lshlrev_b32_e32 v0, 3, v0
	s_waitcnt lgkmcnt(0)
	s_add_u32 s6, s2, s6
	s_addc_u32 s7, s3, s7
	s_mov_b64 s[2:3], s[70:71]
	s_load_dwordx2 s[2:3], s[2:3], 0xd0
	v_xor_b32_e32 v39, 4, v44
	s_waitcnt lgkmcnt(0)
	s_add_u32 s5, s2, s5
	v_readlane_b32 s2, v253, 61
	s_addc_u32 s8, s3, s2
	s_add_i32 s4, s4, s28
	s_lshl_b32 s10, s4, 2
	s_add_i32 s10, s10, 0x8000
	s_bfe_u32 s11, s4, 0x1b0003
	s_ashr_i32 s9, s10, 13
	s_add_i32 s12, s11, 4
	s_cmp_lt_i32 s4, 0
	s_cselect_b32 s4, s9, s12
	s_mul_hi_i32 s9, s4, 0x9000
	s_mul_i32 s4, s4, 0x9000
	s_add_u32 s12, s5, s4
	s_addc_u32 s9, s8, s9
	s_add_u32 s4, s12, 0x3000
	s_mov_b64 s[2:3], s[70:71]
	s_addc_u32 s5, s9, 0
	s_add_u32 s8, s12, 0x4000
	s_load_dwordx2 s[2:3], s[2:3], 0xd0
	s_addc_u32 s9, s9, 0
	global_load_dwordx4 v[6:9], v36, s[6:7]
	global_load_dwordx4 v[10:13], v36, s[8:9]
	global_load_dwordx4 v[2:5], v36, s[4:5]
	s_mov_b32 s11, 0
	s_waitcnt vmcnt(1)
	v_add_f32_e32 v10, 1.0, v10
	v_add_f32_e32 v11, 1.0, v11
	v_add_f32_e32 v12, 1.0, v12
	v_add_f32_e32 v13, 1.0, v13
	v_mul_f32_e32 v20, v6, v10
	v_mul_f32_e32 v21, v7, v11
	v_or_b32_e32 v6, 0x400, v36
	v_mul_f32_e32 v18, v8, v12
	v_mul_f32_e32 v19, v9, v13
	global_load_dwordx4 v[10:13], v36, s[6:7] offset:1024
	global_load_dwordx4 v[14:17], v6, s[8:9]
	s_nop 0
	global_load_dwordx4 v[6:9], v6, s[4:5]
	s_waitcnt vmcnt(1)
	v_add_f32_e32 v14, 1.0, v14
	v_add_f32_e32 v15, 1.0, v15
	v_add_f32_e32 v16, 1.0, v16
	v_add_f32_e32 v17, 1.0, v17
	v_mul_f32_e32 v24, v10, v14
	v_mul_f32_e32 v25, v11, v15
	v_or_b32_e32 v10, 0x800, v36
	v_mul_f32_e32 v22, v12, v16
	v_mul_f32_e32 v23, v13, v17
	global_load_dwordx4 v[14:17], v36, s[6:7] offset:2048
	global_load_dwordx4 v[26:29], v10, s[8:9]
	s_nop 0
	global_load_dwordx4 v[10:13], v10, s[4:5]
	s_waitcnt vmcnt(1)
	v_add_f32_e32 v28, 1.0, v28
	v_add_f32_e32 v29, 1.0, v29
	v_add_f32_e32 v30, 1.0, v26
	v_add_f32_e32 v31, 1.0, v27
	v_mul_f32_e32 v26, v16, v28
	v_mul_f32_e32 v27, v17, v29
	v_mul_f32_e32 v28, v14, v30
	v_mul_f32_e32 v29, v15, v31
	v_or_b32_e32 v14, 0xc00, v36
	global_load_dwordx4 v[32:35], v36, s[6:7] offset:3072
	global_load_dwordx4 v[40:43], v14, s[8:9]
	s_nop 0
	global_load_dwordx4 v[14:17], v14, s[4:5]
	s_waitcnt vmcnt(1)
	v_add_f32_e32 v30, 1.0, v42
	v_add_f32_e32 v31, 1.0, v43
	v_add_f32_e32 v36, 1.0, v40
	v_add_f32_e32 v37, 1.0, v41
	v_mul_f32_e32 v30, v34, v30
	v_mul_f32_e32 v31, v35, v31
	v_lshl_add_u64 v[34:35], s[0:1], 0, v[0:1]
	s_mov_b64 s[0:1], 0xf000000
	v_mul_f32_e32 v32, v32, v36
	v_mul_f32_e32 v33, v33, v37
	v_lshl_add_u64 v[34:35], v[34:35], 0, s[0:1]
	s_waitcnt lgkmcnt(0)
	v_lshl_add_u64 v[36:37], s[2:3], 0, v[0:1]
	s_mov_b64 s[0:1], 0x17200000
	v_xor_b32_e32 v40, 8, v44
	v_xor_b32_e32 v41, 16, v44
	v_xor_b32_e32 v42, 32, v44
	v_xor_b32_e32 v43, 64, v44
	v_xor_b32_e32 v44, 0x80, v44
	v_lshl_add_u64 v[36:37], v[36:37], 0, s[0:1]
	s_mov_b64 s[0:1], -1
.LBB0_1046:
	s_or_b32 s2, s11, s10
	s_ashr_i32 s3, s2, 31
	s_lshl_b64 s[4:5], s[2:3], 11
	v_lshl_add_u64 v[46:47], v[34:35], 0, s[4:5]
	global_load_dwordx2 v[48:49], v[46:47], off
	global_load_dwordx2 v[50:51], v[46:47], off offset:512
	global_load_dwordx2 v[52:53], v[46:47], off offset:1024
	global_load_dwordx2 v[54:55], v[46:47], off offset:1536
	global_load_dwordx2 v[56:57], v[46:47], off offset:2048
	global_load_dwordx2 v[58:59], v[46:47], off offset:2560
	global_load_dwordx2 v[60:61], v[46:47], off offset:3072
	s_nop 0
	global_load_dwordx2 v[46:47], v[46:47], off offset:3584
	s_or_b32 s2, s2, 1
	s_ashr_i32 s3, s2, 31
	s_lshl_b64 s[2:3], s[2:3], 11
	s_mov_b32 s11, 2
	s_and_b64 vcc, exec, s[0:1]
	s_mov_b64 s[0:1], 0
	s_waitcnt vmcnt(7)
	v_lshlrev_b32_e32 v70, 16, v48
	v_and_b32_e32 v71, 0xffff0000, v48
	v_lshlrev_b32_e32 v48, 16, v49
	v_and_b32_e32 v49, 0xffff0000, v49
	v_mul_f32_e32 v0, v49, v49
	v_fma_f32 v72, v48, v48, v0
	v_fma_f32 v73, v49, v49, v0
	s_waitcnt vmcnt(6)
	v_lshlrev_b32_e32 v75, 16, v51
	v_lshlrev_b32_e32 v74, 16, v50
	v_and_b32_e32 v51, 0xffff0000, v51
	v_and_b32_e32 v50, 0xffff0000, v50
	v_mul_f32_e32 v0, v71, v71
	s_waitcnt vmcnt(4)
	v_lshlrev_b32_e32 v63, 16, v54
	v_mul_f32_e32 v76, v50, v50
	v_mul_f32_e32 v77, v51, v51
	v_fma_f32 v80, v70, v70, v0
	v_fma_f32 v81, v71, v71, v0
	v_and_b32_e32 v65, 0xffff0000, v54
	v_fma_f32 v76, v74, v74, v76
	v_fma_f32 v77, v75, v75, v77
	v_mov_b32_e32 v62, v80
	v_mov_b32_e32 v82, v72
	v_mov_b32_e32 v83, v63
	v_and_b32_e32 v79, 0xffff0000, v52
	v_mul_f32_e32 v45, v65, v65
	v_add_f32_e32 v72, v80, v72
	v_add_f32_e32 v73, v81, v73
	v_mul_f32_e32 v80, v62, v82
	v_mul_f32_e32 v81, v63, v83
	v_pk_add_f32 v[76:77], v[76:77], v[76:77] op_sel:[0,1] op_sel_hi:[1,0]
	v_lshlrev_b32_e32 v78, 16, v52
	v_lshlrev_b32_e32 v52, 16, v53
	v_and_b32_e32 v53, 0xffff0000, v53
	v_mov_b32_e32 v73, v81
	v_mov_b32_e32 v77, v45
	v_mul_f32_e32 v0, v79, v79
	v_lshlrev_b32_e32 v54, 16, v55
	v_and_b32_e32 v55, 0xffff0000, v55
	v_add_f32_e32 v72, v72, v76
	v_add_f32_e32 v73, v73, v77
	v_fma_f32 v76, v78, v78, v0
	v_fma_f32 v77, v79, v79, v0
	v_mul_f32_e32 v0, v53, v53
	v_mul_f32_e32 v64, v54, v54
	v_mul_f32_e32 v66, v55, v55
	v_fma_f32 v80, v52, v52, v0
	v_fma_f32 v81, v53, v53, v0
	v_mov_b32_e32 v77, v64
	v_mov_b32_e32 v81, v66
	v_add_f32_e32 v76, v76, v80
	v_add_f32_e32 v77, v77, v81
	s_waitcnt vmcnt(2)
	v_lshlrev_b32_e32 v81, 16, v59
	v_add_f32_e32 v72, v72, v76
	v_add_f32_e32 v73, v73, v77
	v_lshlrev_b32_e32 v80, 16, v58
	v_add_f32_e32 v45, v72, v73
	v_lshlrev_b32_e32 v72, 16, v56
	v_and_b32_e32 v73, 0xffff0000, v56
	v_lshlrev_b32_e32 v56, 16, v57
	v_and_b32_e32 v57, 0xffff0000, v57
	v_mul_f32_e32 v0, v57, v57
	v_fma_f32 v76, v56, v56, v0
	v_fma_f32 v77, v57, v57, v0
	v_and_b32_e32 v59, 0xffff0000, v59
	v_and_b32_e32 v58, 0xffff0000, v58
	v_mul_f32_e32 v0, v73, v73
	s_waitcnt vmcnt(0)
	v_lshlrev_b32_e32 v67, 16, v46
	v_mul_f32_e32 v82, v58, v58
	v_mul_f32_e32 v83, v59, v59
	v_fma_f32 v86, v72, v72, v0
	v_fma_f32 v87, v73, v73, v0
	v_and_b32_e32 v69, 0xffff0000, v46
	v_fma_f32 v82, v80, v80, v82
	v_fma_f32 v83, v81, v81, v83
	v_mov_b32_e32 v66, v86
	v_mov_b32_e32 v88, v76
	v_mov_b32_e32 v89, v67
	v_and_b32_e32 v85, 0xffff0000, v60
	v_mul_f32_e32 v62, v69, v69
	v_add_f32_e32 v76, v86, v76
	v_add_f32_e32 v77, v87, v77
	v_mul_f32_e32 v86, v66, v88
	v_mul_f32_e32 v87, v67, v89
	v_pk_add_f32 v[82:83], v[82:83], v[82:83] op_sel:[0,1] op_sel_hi:[1,0]
	v_lshlrev_b32_e32 v84, 16, v60
	v_lshlrev_b32_e32 v60, 16, v61
	v_and_b32_e32 v61, 0xffff0000, v61
	v_mov_b32_e32 v77, v87
	v_mov_b32_e32 v83, v62
	v_mul_f32_e32 v0, v85, v85
	v_add_f32_e32 v76, v76, v82
	v_add_f32_e32 v77, v77, v83
	v_fma_f32 v82, v84, v84, v0
	v_fma_f32 v83, v85, v85, v0
	v_mul_f32_e32 v0, v61, v61
	v_fma_f32 v86, v60, v60, v0
	v_fma_f32 v87, v61, v61, v0
	ds_bpermute_b32 v0, v39, v45
	v_lshlrev_b32_e32 v46, 16, v47
	v_and_b32_e32 v47, 0xffff0000, v47
	v_mul_f32_e32 v64, v46, v46
	v_mul_f32_e32 v68, v47, v47
	s_waitcnt lgkmcnt(0)
	v_add_f32_e32 v0, v45, v0
	ds_bpermute_b32 v45, v40, v0
	v_mov_b32_e32 v83, v64
	v_mov_b32_e32 v87, v68
	v_add_f32_e32 v82, v82, v86
	v_add_f32_e32 v83, v83, v87
	v_mov_b32_e32 v64, v63
	s_waitcnt lgkmcnt(0)
	v_add_f32_e32 v0, v0, v45
	ds_bpermute_b32 v45, v41, v0
	v_add_f32_e32 v76, v76, v82
	v_add_f32_e32 v77, v77, v83
	v_mov_b32_e32 v68, v67
	v_add_f32_e32 v62, v76, v77
	v_lshl_add_u64 v[76:77], v[36:37], 0, s[4:5]
	s_waitcnt lgkmcnt(0)
	v_add_f32_e32 v0, v0, v45
	ds_bpermute_b32 v45, v42, v0
	s_waitcnt lgkmcnt(0)
	v_add_f32_e32 v0, v0, v45
	ds_bpermute_b32 v45, v43, v0
	s_waitcnt lgkmcnt(0)
	v_add_f32_e32 v0, v0, v45
	ds_bpermute_b32 v45, v44, v0
	s_waitcnt lgkmcnt(0)
	v_add_f32_e32 v0, v0, v45
	v_fmamk_f32 v0, v0, 0x3a800000, v230
	v_rsq_f32_e32 v0, v0
	s_nop 0
	v_mul_f32_e32 v70, v0, v70
	v_mul_f32_e32 v71, v0, v71
	v_mul_f32_e32 v48, v0, v48
	v_mul_f32_e32 v49, v0, v49
	v_fma_f32 v48, v18, v48, v4
	v_fma_f32 v49, v19, v49, v5
	v_fma_f32 v70, v20, v70, v2
	v_fma_f32 v71, v21, v71, v3
	s_nop 0
	v_cvt_pk_bf16_f32 v70, v70, v71
	v_cvt_pk_bf16_f32 v71, v48, v49
	v_mov_b32_e32 v48, v74
	v_mov_b32_e32 v49, v50
	v_mul_f32_e32 v48, v0, v48
	v_mul_f32_e32 v49, v0, v49
	v_mov_b32_e32 v50, v75
	v_mul_f32_e32 v50, v0, v50
	v_mul_f32_e32 v51, v0, v51
	v_fma_f32 v48, v24, v48, v6
	v_fma_f32 v49, v25, v49, v7
	global_store_dwordx2 v[76:77], v[70:71], off
	v_fma_f32 v50, v22, v50, v8
	v_fma_f32 v51, v23, v51, v9
	v_cvt_pk_bf16_f32 v48, v48, v49
	s_nop 0
	v_cvt_pk_bf16_f32 v49, v50, v51
	global_store_dwordx2 v[76:77], v[48:49], off offset:512
	v_mul_f32_e32 v48, v0, v78
	v_mul_f32_e32 v49, v0, v79
	v_mul_f32_e32 v50, v0, v52
	v_mul_f32_e32 v51, v0, v53
	v_fma_f32 v48, v28, v48, v10
	v_fma_f32 v49, v29, v49, v11
	v_fma_f32 v50, v26, v50, v12
	v_fma_f32 v51, v27, v51, v13
	v_cvt_pk_bf16_f32 v48, v48, v49
	s_nop 0
	v_cvt_pk_bf16_f32 v49, v50, v51
	global_store_dwordx2 v[76:77], v[48:49], off offset:1024
	v_mul_f32_e32 v48, v0, v64
	v_mul_f32_e32 v49, v0, v65
	v_mul_f32_e32 v50, v0, v54
	v_mul_f32_e32 v51, v0, v55
	ds_bpermute_b32 v0, v39, v62
	v_fma_f32 v50, v30, v50, v16
	v_fma_f32 v51, v31, v51, v17
	v_fma_f32 v48, v32, v48, v14
	v_fma_f32 v49, v33, v49, v15
	s_waitcnt lgkmcnt(0)
	v_add_f32_e32 v0, v62, v0
	ds_bpermute_b32 v45, v40, v0
	v_cvt_pk_bf16_f32 v48, v48, v49
	v_cvt_pk_bf16_f32 v49, v50, v51
	global_store_dwordx2 v[76:77], v[48:49], off offset:1536
	v_lshl_add_u64 v[48:49], v[36:37], 0, s[2:3]
	s_waitcnt lgkmcnt(0)
	v_add_f32_e32 v0, v0, v45
	ds_bpermute_b32 v45, v41, v0
	s_waitcnt lgkmcnt(0)
	v_add_f32_e32 v0, v0, v45
	ds_bpermute_b32 v45, v42, v0
	s_waitcnt lgkmcnt(0)
	v_add_f32_e32 v0, v0, v45
	ds_bpermute_b32 v45, v43, v0
	s_waitcnt lgkmcnt(0)
	v_add_f32_e32 v0, v0, v45
	ds_bpermute_b32 v45, v44, v0
	s_waitcnt lgkmcnt(0)
	v_add_f32_e32 v0, v0, v45
	v_fmamk_f32 v0, v0, 0x3a800000, v230
	v_rsq_f32_e32 v0, v0
	s_nop 0
	v_mul_f32_e32 v50, v0, v72
	v_mul_f32_e32 v51, v0, v73
	v_mul_f32_e32 v52, v0, v56
	v_mul_f32_e32 v53, v0, v57
	v_fma_f32 v50, v20, v50, v2
	v_fma_f32 v51, v21, v51, v3
	v_fma_f32 v52, v18, v52, v4
	v_fma_f32 v53, v19, v53, v5
	v_cvt_pk_bf16_f32 v50, v50, v51
	v_mul_f32_e32 v46, v0, v46
	v_mul_f32_e32 v47, v0, v47
	v_cvt_pk_bf16_f32 v51, v52, v53
	global_store_dwordx2 v[48:49], v[50:51], off
	v_mov_b32_e32 v50, v80
	v_mov_b32_e32 v51, v58
	v_mul_f32_e32 v50, v0, v50
	v_mul_f32_e32 v51, v0, v51
	v_mov_b32_e32 v58, v81
	v_mul_f32_e32 v52, v0, v58
	v_mul_f32_e32 v53, v0, v59
	v_fma_f32 v50, v24, v50, v6
	v_fma_f32 v51, v25, v51, v7
	v_fma_f32 v52, v22, v52, v8
	v_fma_f32 v53, v23, v53, v9
	v_cvt_pk_bf16_f32 v50, v50, v51
	v_fma_f32 v46, v30, v46, v16
	v_fma_f32 v47, v31, v47, v17
	v_cvt_pk_bf16_f32 v51, v52, v53
	global_store_dwordx2 v[48:49], v[50:51], off offset:512
	v_mul_f32_e32 v50, v0, v84
	v_mul_f32_e32 v51, v0, v85
	v_mul_f32_e32 v52, v0, v60
	v_mul_f32_e32 v53, v0, v61
	v_fma_f32 v50, v28, v50, v10
	v_fma_f32 v51, v29, v51, v11
	v_fma_f32 v52, v26, v52, v12
	v_fma_f32 v53, v27, v53, v13
	v_cvt_pk_bf16_f32 v50, v50, v51
	s_nop 0
	v_cvt_pk_bf16_f32 v51, v52, v53
	global_store_dwordx2 v[48:49], v[50:51], off offset:1024
	v_mul_f32_e32 v50, v0, v68
	v_mul_f32_e32 v51, v0, v69
	v_fma_f32 v50, v32, v50, v14
	v_fma_f32 v51, v33, v51, v15
	s_nop 0
	v_cvt_pk_bf16_f32 v50, v50, v51
	v_cvt_pk_bf16_f32 v51, v46, v47
	global_store_dwordx2 v[48:49], v[50:51], off offset:1536
	s_cbranch_vccnz .LBB0_1046
	s_waitcnt vmcnt(0)
	v_cmp_eq_u32_e32 vcc, 0, v38
	s_barrier
	s_and_saveexec_b64 s[0:1], vcc
	s_cbranch_execz .LBB0_1061
	s_mov_b64 s[2:3], exec
	buffer_wbl2 sc1
	s_waitcnt vmcnt(0)
	s_waitcnt vmcnt(0)
	v_mbcnt_lo_u32_b32 v0, s2, 0
	v_mbcnt_hi_u32_b32 v0, s3, v0
	v_cmp_eq_u32_e32 vcc, 0, v0
	s_and_saveexec_b64 s[4:5], vcc
	s_cbranch_execz .LBB0_1050
	s_bcnt1_i32_b64 s2, s[2:3]
	v_mov_b32_e32 v0, s2
	global_atomic_add v1, v0, s[36:37] offset:2560

.LBB0_1096:
	s_and_b64 vcc, exec, s[2:3]
	s_waitcnt vmcnt(0)
	v_sub_f32_e32 v166, 1.0, v34
	v_sub_f32_e32 v167, 1.0, v35
	s_cbranch_vccz .LBB0_1098
	v_mul_f32_e64 v0, |v142|, s33
	v_exp_f32_e32 v34, v0
	v_mul_f32_e64 v0, |v138|, s33
	v_mul_f32_e64 v35, |v143|, s33
	v_exp_f32_e32 v170, v0
	v_exp_f32_e32 v35, v35
	v_add_f32_e32 v0, 1.0, v34
	v_rcp_f32_e32 v168, v0
	v_add_f32_e32 v0, 1.0, v170
	v_rcp_f32_e32 v172, v0
	v_add_f32_e32 v0, 1.0, v35
	v_rcp_f32_e32 v169, v0
	v_mul_f32_e64 v0, |v139|, s33
	v_exp_f32_e32 v171, v0
	v_cmp_le_f32_e32 vcc, 0, v143
	v_mul_f32_e32 v34, v34, v168
	v_mul_f32_e32 v35, v35, v169
	v_sub_f32_e32 v174, 1.0, v38
	v_sub_f32_e32 v175, 1.0, v39
	v_add_f32_e32 v0, 1.0, v171
	v_rcp_f32_e32 v173, v0
	v_mul_f32_e64 v0, |v144|, s33
	v_cndmask_b32_e32 v35, v169, v35, vcc
	v_cmp_le_f32_e32 vcc, 0, v142
	v_exp_f32_e32 v142, v0
	v_sub_f32_e32 v182, 1.0, v40
	v_sub_f32_e32 v183, 1.0, v41
	v_cndmask_b32_e32 v34, v168, v34, vcc
	v_mul_f32_e32 v168, v34, v166
	v_mul_f32_e32 v169, v35, v167
	v_mul_f32_e32 v34, v170, v172
	v_mul_f32_e32 v35, v171, v173
	v_cmp_le_f32_e32 vcc, 0, v139
	v_add_f32_e32 v0, 1.0, v142
	s_nop 0
	v_cndmask_b32_e32 v35, v173, v35, vcc
	v_cmp_le_f32_e32 vcc, 0, v138
	s_nop 1
	v_cndmask_b32_e32 v34, v172, v34, vcc
	v_mul_f32_e32 v170, v34, v174
	v_mul_f32_e32 v171, v35, v175
	v_rcp_f32_e32 v34, v0
	v_mul_f32_e64 v0, |v140|, s33
	v_exp_f32_e32 v138, v0
	v_mul_f32_e64 v0, |v145|, s33
	v_exp_f32_e32 v143, v0
	v_cmp_le_f32_e32 vcc, 0, v145
	v_add_f32_e32 v0, 1.0, v138
	v_rcp_f32_e32 v174, v0
	v_add_f32_e32 v0, 1.0, v143
	v_rcp_f32_e32 v35, v0
	v_mul_f32_e64 v0, |v141|, s33
	v_exp_f32_e32 v139, v0
	v_sub_f32_e32 v172, 1.0, v36
	v_sub_f32_e32 v173, 1.0, v37
	v_mul_f32_e32 v142, v142, v34
	v_mul_f32_e32 v143, v143, v35
	v_add_f32_e32 v0, 1.0, v139
	v_rcp_f32_e32 v175, v0
	v_cndmask_b32_e32 v35, v35, v143, vcc
	v_cmp_le_f32_e32 vcc, 0, v144
	s_nop 1
	v_cndmask_b32_e32 v34, v34, v142, vcc
	v_mul_f32_e32 v172, v34, v172
	v_mul_f32_e32 v173, v35, v173
	v_mul_f32_e32 v34, v138, v174
	v_mul_f32_e32 v35, v139, v175
	v_cmp_le_f32_e32 vcc, 0, v141
	s_nop 1
	v_cndmask_b32_e32 v35, v175, v35, vcc
	v_cmp_le_f32_e32 vcc, 0, v140
	s_nop 1
	v_cndmask_b32_e32 v34, v174, v34, vcc
	v_mul_f32_e32 v174, v34, v182
	v_mul_f32_e32 v175, v35, v183

.LBB0_1150:
	s_and_b64 vcc, exec, s[0:1]
	s_cbranch_vccz .LBB0_1152
	v_mul_f32_e64 v0, |v118|, s33
	v_exp_f32_e32 v122, v0
	v_mul_f32_e64 v0, |v114|, s33
	v_mul_f32_e64 v123, |v119|, s33
	v_exp_f32_e32 v124, v0
	v_exp_f32_e32 v123, v123
	v_add_f32_e32 v0, 1.0, v122
	v_rcp_f32_e32 v126, v0
	v_add_f32_e32 v0, 1.0, v124
	v_rcp_f32_e32 v130, v0
	v_add_f32_e32 v0, 1.0, v123
	v_rcp_f32_e32 v127, v0
	v_mul_f32_e64 v0, |v115|, s33
	v_exp_f32_e32 v125, v0
	v_cmp_le_f32_e32 vcc, 0, v119
	v_mul_f32_e32 v122, v122, v126
	v_mul_f32_e32 v123, v123, v127
	v_sub_f32_e32 v128, 1.0, v18
	v_sub_f32_e32 v129, 1.0, v19
	v_add_f32_e32 v0, 1.0, v125
	v_rcp_f32_e32 v131, v0
	v_cndmask_b32_e32 v119, v127, v123, vcc
	v_cmp_le_f32_e32 vcc, 0, v118
	v_mul_f32_e64 v0, |v120|, s33
	v_sub_f32_e32 v132, 1.0, v22
	v_sub_f32_e32 v133, 1.0, v23
	v_cndmask_b32_e32 v118, v126, v122, vcc
	v_exp_f32_e32 v126, v0
	v_mul_f32_e32 v122, v118, v128
	v_mul_f32_e32 v123, v119, v129
	v_mul_f32_e32 v118, v124, v130
	v_mul_f32_e32 v119, v125, v131
	v_cmp_le_f32_e32 vcc, 0, v115
	v_add_f32_e32 v0, 1.0, v126
	v_sub_f32_e32 v128, 1.0, v20
	v_sub_f32_e32 v129, 1.0, v21
	v_cndmask_b32_e32 v115, v131, v119, vcc
	v_cmp_le_f32_e32 vcc, 0, v114
	s_nop 1
	v_cndmask_b32_e32 v114, v130, v118, vcc
	v_mul_f32_e32 v124, v114, v132
	v_mul_f32_e32 v125, v115, v133
	v_rcp_f32_e32 v114, v0
	v_mul_f32_e64 v0, |v116|, s33
	v_exp_f32_e32 v118, v0
	v_mul_f32_e64 v0, |v121|, s33
	v_exp_f32_e32 v127, v0
	v_cmp_le_f32_e32 vcc, 0, v121
	v_add_f32_e32 v0, 1.0, v118
	v_rcp_f32_e32 v130, v0
	v_add_f32_e32 v0, 1.0, v127
	v_rcp_f32_e32 v115, v0
	v_mul_f32_e64 v0, |v117|, s33
	v_exp_f32_e32 v119, v0
	v_sub_f32_e32 v132, 1.0, v24
	v_sub_f32_e32 v133, 1.0, v25
	v_mul_f32_e32 v126, v126, v114
	v_mul_f32_e32 v127, v127, v115
	v_add_f32_e32 v0, 1.0, v119
	v_rcp_f32_e32 v131, v0
	v_cndmask_b32_e32 v115, v115, v127, vcc
	v_cmp_le_f32_e32 vcc, 0, v120
	s_nop 1
	v_cndmask_b32_e32 v114, v114, v126, vcc
	v_mul_f32_e32 v126, v114, v128
	v_mul_f32_e32 v127, v115, v129
	v_mul_f32_e32 v114, v118, v130
	v_mul_f32_e32 v115, v119, v131
	v_cmp_le_f32_e32 vcc, 0, v117
	s_nop 1
	v_cndmask_b32_e32 v115, v131, v115, vcc
	v_cmp_le_f32_e32 vcc, 0, v116
	s_nop 1
	v_cndmask_b32_e32 v114, v130, v114, vcc
	v_mul_f32_e32 v128, v114, v132
	v_mul_f32_e32 v129, v115, v133

.LBB0_1240:
	s_and_b64 vcc, exec, s[0:1]
	s_cbranch_vccz .LBB0_1242
	v_mul_f32_e64 v0, |v78|, s33
	v_exp_f32_e32 v82, v0
	v_mul_f32_e64 v0, |v74|, s33
	v_mul_f32_e64 v83, |v79|, s33
	v_exp_f32_e32 v84, v0
	v_exp_f32_e32 v83, v83
	v_add_f32_e32 v0, 1.0, v82
	v_rcp_f32_e32 v86, v0
	v_add_f32_e32 v0, 1.0, v84
	v_rcp_f32_e32 v88, v0
	v_add_f32_e32 v0, 1.0, v83
	v_rcp_f32_e32 v87, v0
	v_mul_f32_e64 v0, |v75|, s33
	v_exp_f32_e32 v85, v0
	v_cmp_le_f32_e32 vcc, 0, v79
	v_mul_f32_e32 v82, v82, v86
	v_mul_f32_e32 v83, v83, v87
	v_sub_f32_e32 v90, 1.0, v38
	v_sub_f32_e32 v91, 1.0, v39
	v_add_f32_e32 v0, 1.0, v85
	v_rcp_f32_e32 v89, v0
	v_cndmask_b32_e32 v79, v87, v83, vcc
	v_cmp_le_f32_e32 vcc, 0, v78
	v_mul_f32_e64 v0, |v80|, s33
	v_sub_f32_e32 v92, 1.0, v40
	v_sub_f32_e32 v93, 1.0, v41
	v_cndmask_b32_e32 v78, v86, v82, vcc
	v_exp_f32_e32 v86, v0
	v_mul_f32_e32 v82, v78, v166
	v_mul_f32_e32 v83, v79, v167
	v_mul_f32_e32 v78, v84, v88
	v_mul_f32_e32 v79, v85, v89
	v_cmp_le_f32_e32 vcc, 0, v75
	v_add_f32_e32 v0, 1.0, v86
	s_nop 0
	v_cndmask_b32_e32 v75, v89, v79, vcc
	v_cmp_le_f32_e32 vcc, 0, v74
	s_nop 1
	v_cndmask_b32_e32 v74, v88, v78, vcc
	v_mul_f32_e32 v84, v74, v90
	v_mul_f32_e32 v85, v75, v91
	v_rcp_f32_e32 v74, v0
	v_mul_f32_e64 v0, |v76|, s33
	v_exp_f32_e32 v78, v0
	v_mul_f32_e64 v0, |v81|, s33
	v_exp_f32_e32 v87, v0
	v_cmp_le_f32_e32 vcc, 0, v81
	v_add_f32_e32 v0, 1.0, v78
	v_rcp_f32_e32 v90, v0
	v_add_f32_e32 v0, 1.0, v87
	v_rcp_f32_e32 v75, v0
	v_mul_f32_e64 v0, |v77|, s33
	v_exp_f32_e32 v79, v0
	v_sub_f32_e32 v88, 1.0, v36
	v_sub_f32_e32 v89, 1.0, v37
	v_mul_f32_e32 v86, v86, v74
	v_mul_f32_e32 v87, v87, v75
	v_add_f32_e32 v0, 1.0, v79
	v_rcp_f32_e32 v91, v0
	v_cndmask_b32_e32 v75, v75, v87, vcc
	v_cmp_le_f32_e32 vcc, 0, v80
	s_nop 1
	v_cndmask_b32_e32 v74, v74, v86, vcc
	v_mul_f32_e32 v86, v74, v88
	v_mul_f32_e32 v87, v75, v89
	v_mul_f32_e32 v74, v78, v90
	v_mul_f32_e32 v75, v79, v91
	v_cmp_le_f32_e32 vcc, 0, v77
	s_nop 1
	v_cndmask_b32_e32 v75, v91, v75, vcc
	v_cmp_le_f32_e32 vcc, 0, v76
	s_nop 1
	v_cndmask_b32_e32 v74, v90, v74, vcc
	v_mul_f32_e32 v88, v74, v92
	v_mul_f32_e32 v89, v75, v93

.LBB0_1312:
	s_and_b64 vcc, exec, s[0:1]
	s_cbranch_vccz .LBB0_1314
	v_mul_f32_e64 v0, |v46|, s33
	v_exp_f32_e32 v50, v0
	v_mul_f32_e64 v0, |v42|, s33
	v_mul_f32_e64 v51, |v47|, s33
	v_exp_f32_e32 v52, v0
	v_exp_f32_e32 v51, v51
	v_add_f32_e32 v0, 1.0, v50
	v_rcp_f32_e32 v54, v0
	v_add_f32_e32 v0, 1.0, v52
	v_rcp_f32_e32 v56, v0
	v_add_f32_e32 v0, 1.0, v51
	v_rcp_f32_e32 v55, v0
	v_mul_f32_e64 v0, |v43|, s33
	v_exp_f32_e32 v53, v0
	v_cmp_le_f32_e32 vcc, 0, v47
	v_mul_f32_e32 v50, v50, v54
	v_mul_f32_e32 v51, v51, v55
	v_sub_f32_e32 v58, 1.0, v38
	v_sub_f32_e32 v59, 1.0, v39
	v_add_f32_e32 v0, 1.0, v53
	v_rcp_f32_e32 v57, v0
	v_cndmask_b32_e32 v47, v55, v51, vcc
	v_cmp_le_f32_e32 vcc, 0, v46
	v_mul_f32_e64 v0, |v48|, s33
	v_sub_f32_e32 v60, 1.0, v40
	v_sub_f32_e32 v61, 1.0, v41
	v_cndmask_b32_e32 v46, v54, v50, vcc
	v_exp_f32_e32 v54, v0
	v_mul_f32_e32 v50, v46, v166
	v_mul_f32_e32 v51, v47, v167
	v_mul_f32_e32 v46, v52, v56
	v_mul_f32_e32 v47, v53, v57
	v_cmp_le_f32_e32 vcc, 0, v43
	v_add_f32_e32 v0, 1.0, v54
	s_nop 0
	v_cndmask_b32_e32 v43, v57, v47, vcc
	v_cmp_le_f32_e32 vcc, 0, v42
	s_nop 1
	v_cndmask_b32_e32 v42, v56, v46, vcc
	v_mul_f32_e32 v52, v42, v58
	v_mul_f32_e32 v53, v43, v59
	v_rcp_f32_e32 v42, v0
	v_mul_f32_e64 v0, |v44|, s33
	v_exp_f32_e32 v46, v0
	v_mul_f32_e64 v0, |v49|, s33
	v_exp_f32_e32 v55, v0
	v_cmp_le_f32_e32 vcc, 0, v49
	v_add_f32_e32 v0, 1.0, v46
	v_rcp_f32_e32 v58, v0
	v_add_f32_e32 v0, 1.0, v55
	v_rcp_f32_e32 v43, v0
	v_mul_f32_e64 v0, |v45|, s33
	v_exp_f32_e32 v47, v0
	v_sub_f32_e32 v56, 1.0, v36
	v_sub_f32_e32 v57, 1.0, v37
	v_mul_f32_e32 v54, v54, v42
	v_mul_f32_e32 v55, v55, v43
	v_add_f32_e32 v0, 1.0, v47
	v_rcp_f32_e32 v59, v0
	v_cndmask_b32_e32 v43, v43, v55, vcc
	v_cmp_le_f32_e32 vcc, 0, v48
	s_nop 1
	v_cndmask_b32_e32 v42, v42, v54, vcc
	v_mul_f32_e32 v54, v42, v56
	v_mul_f32_e32 v55, v43, v57
	v_mul_f32_e32 v42, v46, v58
	v_mul_f32_e32 v43, v47, v59
	v_cmp_le_f32_e32 vcc, 0, v45
	s_nop 1
	v_cndmask_b32_e32 v43, v59, v43, vcc
	v_cmp_le_f32_e32 vcc, 0, v44
	s_nop 1
	v_cndmask_b32_e32 v42, v58, v42, vcc
	v_mul_f32_e32 v56, v42, v60
	v_mul_f32_e32 v57, v43, v61

.LBB0_1491:
	s_mov_b32 s9, 0xffff2000
	v_add_co_u32_e32 v46, vcc, s9, v36
	v_lshl_add_u64 v[38:39], s[28:29], 2, v[34:35]
	s_nop 0
	v_addc_co_u32_e32 v47, vcc, -1, v37, vcc
	global_load_dwordx4 v[42:45], v[38:39], off
	global_load_dword v48, v[46:47], off offset:-1536
	global_load_dword v49, v[46:47], off offset:-1024
	global_load_dword v50, v[46:47], off offset:-512
	global_load_dword v51, v[46:47], off
	s_mov_b32 s9, 0xffff4000
	v_add_co_u32_e32 v46, vcc, s9, v36
	s_mov_b32 s9, 0xffff6000
	s_nop 0
	v_addc_co_u32_e32 v47, vcc, -1, v37, vcc
	s_add_i32 s8, s8, -1
	s_addk_i32 s28, 0x80
	s_cmp_eq_u32 s8, 0
	s_waitcnt vmcnt(2)
	v_fma_f32 v2, v2, v42, v48
	v_fma_f32 v3, v3, v43, v49
	s_waitcnt vmcnt(0)
	v_fma_f32 v32, v32, v44, v50
	v_fma_f32 v33, v33, v45, v51
	global_load_dwordx4 v[42:45], v[38:39], off offset:64
	global_load_dword v48, v[46:47], off offset:-1536
	global_load_dword v49, v[46:47], off offset:-1024
	global_load_dword v50, v[46:47], off offset:-512
	global_load_dword v51, v[46:47], off
	v_add_co_u32_e32 v46, vcc, s9, v36
	s_movk_i32 s9, 0x8000
	s_nop 0
	v_addc_co_u32_e32 v47, vcc, -1, v37, vcc
	s_waitcnt vmcnt(2)
	v_fma_f32 v4, v4, v42, v48
	v_fma_f32 v5, v5, v43, v49
	s_waitcnt vmcnt(0)
	v_fma_f32 v30, v30, v44, v50
	v_fma_f32 v31, v31, v45, v51
	global_load_dwordx4 v[42:45], v[38:39], off offset:128
	global_load_dword v48, v[46:47], off offset:-1536
	global_load_dword v49, v[46:47], off offset:-1024
	global_load_dword v50, v[46:47], off offset:-512
	global_load_dword v51, v[46:47], off
	v_add_co_u32_e32 v46, vcc, s9, v36
	s_movk_i32 s9, 0xa000
	s_nop 0
	v_addc_co_u32_e32 v47, vcc, -1, v37, vcc
	s_waitcnt vmcnt(2)
	v_fma_f32 v6, v6, v42, v48
	v_fma_f32 v7, v7, v43, v49
	s_waitcnt vmcnt(0)
	v_fma_f32 v28, v28, v44, v50
	v_fma_f32 v29, v29, v45, v51
	global_load_dwordx4 v[42:45], v[38:39], off offset:192
	global_load_dword v48, v[46:47], off offset:-1536
	global_load_dword v49, v[46:47], off offset:-1024
	global_load_dword v50, v[46:47], off offset:-512
	global_load_dword v51, v[46:47], off
	v_add_co_u32_e32 v46, vcc, s9, v36
	s_movk_i32 s9, 0xc000
	s_nop 0
	v_addc_co_u32_e32 v47, vcc, -1, v37, vcc
	s_waitcnt vmcnt(2)
	v_fma_f32 v8, v8, v42, v48
	v_fma_f32 v9, v9, v43, v49
	s_waitcnt vmcnt(0)
	v_fma_f32 v26, v26, v44, v50
	v_fma_f32 v27, v27, v45, v51
	global_load_dwordx4 v[42:45], v[38:39], off offset:256
	global_load_dword v48, v[46:47], off offset:-1536
	global_load_dword v49, v[46:47], off offset:-1024
	global_load_dword v50, v[46:47], off offset:-512
	global_load_dword v51, v[46:47], off
	v_add_co_u32_e32 v46, vcc, s9, v36
	s_movk_i32 s9, 0xe000
	s_nop 0
	v_addc_co_u32_e32 v47, vcc, -1, v37, vcc
	s_waitcnt vmcnt(2)
	v_fma_f32 v10, v10, v42, v48
	v_fma_f32 v11, v11, v43, v49
	s_waitcnt vmcnt(0)
	v_fma_f32 v24, v24, v44, v50
	v_fma_f32 v25, v25, v45, v51
	global_load_dwordx4 v[42:45], v[38:39], off offset:320
	global_load_dword v48, v[46:47], off offset:-1536
	global_load_dword v49, v[46:47], off offset:-1024
	global_load_dword v50, v[46:47], off offset:-512
	global_load_dword v51, v[46:47], off
	v_add_co_u32_e32 v46, vcc, s9, v36
	s_waitcnt vmcnt(2)
	v_fma_f32 v12, v12, v42, v48
	v_fma_f32 v13, v13, v43, v49
	v_addc_co_u32_e32 v47, vcc, -1, v37, vcc
	s_waitcnt vmcnt(0)
	v_fma_f32 v22, v22, v44, v50
	v_fma_f32 v23, v23, v45, v51
	global_load_dwordx4 v[42:45], v[38:39], off offset:384
	global_load_dword v48, v[46:47], off offset:-1536
	global_load_dword v49, v[46:47], off offset:-1024
	global_load_dword v50, v[46:47], off offset:-512
	global_load_dword v51, v[46:47], off
	s_waitcnt vmcnt(2)
	v_fma_f32 v14, v14, v42, v48
	v_fma_f32 v15, v15, v43, v49
	s_waitcnt vmcnt(0)
	v_fma_f32 v20, v20, v44, v50
	v_fma_f32 v21, v21, v45, v51
	global_load_dwordx4 v[42:45], v[38:39], off offset:448
	s_nop 0
	global_load_dword v38, v[36:37], off offset:-1536
	global_load_dword v39, v[36:37], off offset:-1024
	global_load_dword v46, v[36:37], off offset:-512
	global_load_dword v47, v[36:37], off
	v_lshl_add_u64 v[36:37], v[36:37], 0, s[50:51]
	s_waitcnt vmcnt(2)
	v_fma_f32 v16, v16, v42, v38
	v_fma_f32 v17, v17, v43, v39
	s_waitcnt vmcnt(0)
	v_fma_f32 v18, v18, v44, v46
	v_fma_f32 v19, v19, v45, v47
	s_cbranch_scc0 .LBB0_1491
	s_branch .LBB0_1493

.LBB0_1595:
	s_waitcnt vmcnt(11)
	v_mfma_f32_32x32x16_bf16 v[2:17], v[138:141], v[50:53], 0
	s_add_i32 s28, s28, 1
	v_add_u32_e32 v200, 32, v200
	s_cmp_eq_u32 s43, s28
	v_add_u32_e32 v202, 32, v202
	s_waitcnt vmcnt(10)
	v_mfma_f32_32x32x16_bf16 v[2:17], v[142:145], v[54:57], v[2:17]
	s_waitcnt vmcnt(9)
	v_mfma_f32_32x32x16_bf16 v[2:17], v[146:149], v[58:61], v[2:17]
	s_waitcnt vmcnt(8)
	v_mfma_f32_32x32x16_bf16 v[2:17], v[150:153], v[62:65], v[2:17]
	s_waitcnt vmcnt(7)
	s_nop 10
	v_max_f32_e32 v66, v3, v3
	v_max_f32_e32 v67, v2, v2
	v_max_f32_e32 v66, v67, v66
	v_max3_f32 v66, v66, v4, v5
	v_max3_f32 v66, v66, v6, v7
	v_max3_f32 v66, v66, v8, v9
	v_max3_f32 v66, v66, v10, v11
	v_max3_f32 v66, v66, v12, v13
	v_max3_f32 v66, v66, v14, v15
	v_max3_f32 v66, v66, v16, v17
	ds_bpermute_b32 v67, v155, v66
	s_waitcnt lgkmcnt(0)
	v_max3_f32 v138, v204, v66, v67
	v_sub_f32_e32 v2, v2, v138
	v_sub_f32_e32 v3, v3, v138
	v_exp_f32_e32 v2, v2
	v_sub_f32_e32 v4, v4, v138
	v_exp_f32_e32 v3, v3
	v_sub_f32_e32 v5, v5, v138
	v_exp_f32_e32 v4, v4
	v_sub_f32_e32 v66, v204, v138
	v_sub_f32_e32 v6, v6, v138
	v_exp_f32_e32 v5, v5
	v_sub_f32_e32 v7, v7, v138
	v_exp_f32_e32 v67, v6
	v_exp_f32_e32 v6, v66
	v_add_f32_e32 v66, 0, v2
	v_sub_f32_e32 v8, v8, v138
	v_exp_f32_e32 v7, v7
	v_add_f32_e32 v66, v3, v66
	v_sub_f32_e32 v9, v9, v138
	v_exp_f32_e32 v8, v8
	v_add_f32_e32 v66, v4, v66
	v_sub_f32_e32 v10, v10, v138
	v_exp_f32_e32 v9, v9
	v_add_f32_e32 v66, v5, v66
	v_sub_f32_e32 v11, v11, v138
	v_exp_f32_e32 v10, v10
	v_add_f32_e32 v66, v67, v66
	v_sub_f32_e32 v12, v12, v138
	v_exp_f32_e32 v11, v11
	v_add_f32_e32 v66, v7, v66
	v_sub_f32_e32 v13, v13, v138
	v_exp_f32_e32 v12, v12
	v_add_f32_e32 v66, v8, v66
	v_sub_f32_e32 v14, v14, v138
	v_exp_f32_e32 v13, v13
	v_add_f32_e32 v66, v9, v66
	v_sub_f32_e32 v15, v15, v138
	v_exp_f32_e32 v14, v14
	v_add_f32_e32 v66, v10, v66
	v_sub_f32_e32 v16, v16, v138
	v_exp_f32_e32 v15, v15
	v_add_f32_e32 v66, v11, v66
	v_sub_f32_e32 v17, v17, v138
	v_exp_f32_e32 v16, v16
	v_add_f32_e32 v66, v12, v66
	v_exp_f32_e32 v17, v17
	v_add_f32_e32 v66, v13, v66
	v_mul_f32_e32 v32, v32, v6
	v_mul_f32_e32 v33, v33, v6
	v_mul_f32_e32 v30, v30, v6
	v_mul_f32_e32 v31, v31, v6
	v_add_f32_e32 v66, v14, v66
	v_mul_f32_e32 v28, v28, v6
	v_mul_f32_e32 v29, v29, v6
	v_mul_f32_e32 v26, v26, v6
	v_mul_f32_e32 v27, v27, v6
	v_mul_f32_e32 v24, v24, v6
	v_mul_f32_e32 v25, v25, v6
	v_mul_f32_e32 v22, v22, v6
	v_mul_f32_e32 v23, v23, v6
	v_mul_f32_e32 v20, v20, v6
	v_mul_f32_e32 v21, v21, v6
	v_mul_f32_e32 v18, v18, v6
	v_mul_f32_e32 v19, v19, v6
	v_add_f32_e32 v66, v15, v66
	v_cvt_pk_bf16_f32 v2, v2, v3
	v_cvt_pk_bf16_f32 v3, v4, v5
	v_cvt_pk_bf16_f32 v4, v67, v7
	v_cvt_pk_bf16_f32 v5, v8, v9
	v_add_f32_e32 v66, v16, v66
	v_mfma_f32_32x32x16_bf16 v[18:33], v[98:101], v[2:5], v[18:33]
	v_add_f32_e32 v66, v17, v66
	ds_bpermute_b32 v2, v155, v66
	s_waitcnt lgkmcnt(0)
	v_add_f32_e32 v139, v66, v2
	v_cvt_pk_bf16_f32 v2, v10, v11
	v_cvt_pk_bf16_f32 v3, v12, v13
	v_cvt_pk_bf16_f32 v4, v14, v15
	v_cvt_pk_bf16_f32 v5, v16, v17
	v_fmac_f32_e32 v139, v197, v6
	v_mfma_f32_32x32x16_bf16 v[18:33], v[118:121], v[2:5], v[18:33]
	s_cbranch_scc1 .LBB0_1598
	v_mov_b64_e32 v[66:67], v[130:131]
	s_waitcnt vmcnt(6)
	v_mov_b64_e32 v[70:71], v[134:135]
	s_waitcnt vmcnt(5)
	v_mov_b64_e32 v[74:75], v[122:123]
	s_waitcnt vmcnt(4)
	v_mov_b64_e32 v[78:79], v[126:127]
	s_waitcnt vmcnt(3)
	v_mov_b64_e32 v[82:83], v[110:111]
	s_waitcnt vmcnt(2)
	v_mov_b64_e32 v[86:87], v[114:115]
	s_waitcnt vmcnt(1)
	v_mov_b64_e32 v[90:91], v[102:103]
	s_waitcnt vmcnt(0)
	v_mov_b64_e32 v[94:95], v[106:107]
	v_mov_b64_e32 v[2:3], v[34:35]
	v_mov_b64_e32 v[68:69], v[132:133]
	v_mov_b64_e32 v[72:73], v[136:137]
	v_mov_b64_e32 v[76:77], v[124:125]
	v_mov_b64_e32 v[80:81], v[128:129]
	v_mov_b64_e32 v[84:85], v[112:113]
	v_mov_b64_e32 v[88:89], v[116:117]
	v_mov_b64_e32 v[92:93], v[104:105]
	v_mov_b64_e32 v[96:97], v[108:109]
	v_mov_b32_e32 v204, v138
	v_mov_b32_e32 v197, v139
	v_mov_b64_e32 v[4:5], v[36:37]
	v_mov_b64_e32 v[6:7], v[38:39]
	v_mov_b64_e32 v[8:9], v[40:41]
	v_mov_b64_e32 v[10:11], v[42:43]
	v_mov_b64_e32 v[12:13], v[44:45]
	v_mov_b64_e32 v[14:15], v[46:47]
	v_mov_b64_e32 v[16:17], v[48:49]
	s_cmp_eq_u32 s28, 32
	s_mov_b64 s[6:7], -1
	s_cbranch_scc0 .LBB0_1590
	s_branch .LBB0_1593

.LBB0_1598:
	s_mov_b64 s[6:7], 0x1000
	v_lshl_add_u64 v[34:35], v[198:199], 0, s[6:7]
	s_mov_b64 s[6:7], 0x2000
	v_lshl_add_u64 v[36:37], v[198:199], 0, s[6:7]
	s_mov_b64 s[6:7], 0x3000
	v_lshl_add_u64 v[38:39], v[198:199], 0, s[6:7]
	s_mov_b64 s[6:7], 0x8000
	v_lshl_add_u64 v[40:41], v[198:199], 0, s[6:7]
	s_mov_b64 s[6:7], 0x9000
	s_waitcnt vmcnt(6)
	v_lshl_add_u64 v[42:43], v[198:199], 0, s[6:7]
	s_mov_b64 s[6:7], 0xa000
	s_waitcnt vmcnt(4)
	v_lshl_add_u64 v[44:45], v[198:199], 0, s[6:7]
	s_mov_b64 s[6:7], 0xb000
	s_waitcnt vmcnt(2)
	v_lshl_add_u64 v[46:47], v[198:199], 0, s[6:7]
	s_mov_b64 s[6:7], 0x11000
	v_lshl_add_u64 v[66:67], v[198:199], 0, s[6:7]
	s_mov_b64 s[6:7], 0x12000
	v_lshl_add_u64 v[68:69], v[198:199], 0, s[6:7]
	s_mov_b64 s[6:7], 0x13000
	v_lshl_add_u64 v[70:71], v[198:199], 0, s[6:7]
	s_mov_b64 s[6:7], 0x18000
	v_lshl_add_u64 v[72:73], v[198:199], 0, s[6:7]
	s_mov_b64 s[6:7], 0x19000
	s_lshl_b32 s47, s45, 5
	v_lshl_add_u64 v[74:75], v[198:199], 0, s[6:7]
	s_mov_b64 s[6:7], 0x1a000
	v_lshl_add_u64 v[76:77], v[198:199], 0, s[6:7]
	s_mov_b64 s[6:7], 0x1b000
	s_cmp_eq_u32 s45, 0
	v_lshl_add_u64 v[78:79], v[198:199], 0, s[6:7]
	s_cselect_b64 s[28:29], -1, 0
	v_cmp_gt_u32_e64 s[6:7], 32, v0
	s_and_b64 s[30:31], s[28:29], s[6:7]
	s_lshl_b32 s28, s46, 8
	s_add_i32 s28, s28, 0
	v_lshlrev_b32_e32 v2, 3, v0
	v_lshlrev_b32_e32 v220, 10, v196
	s_waitcnt vmcnt(0)
	v_lshl_add_u64 v[48:49], v[198:199], 0, s[50:51]
	v_add_u32_e32 v222, s28, v2
	s_and_saveexec_b64 s[28:29], s[30:31]
	ds_write_b64 v222, v[138:139] offset:16384
	s_or_b64 exec, exec, s[28:29]
	v_lshlrev_b32_e32 v2, 3, v214
	v_add_u32_e32 v2, 0, v2
	v_add_u32_e32 v224, 0x4000, v2
	s_waitcnt lgkmcnt(0)
	s_barrier
	ds_read2_b64 v[2:5], v224 offset1:32
	s_cmp_eq_u32 s46, 1
	v_lshl_add_u32 v51, v0, 2, 0
	s_cselect_b64 s[28:29], -1, 0
	s_lshl_b32 s34, s45, 12
	s_waitcnt lgkmcnt(0)
	v_max_f32_e32 v6, v4, v4
	v_max_f32_e32 v7, v2, v2
	v_max_f32_e32 v50, v7, v6
	v_sub_f32_e32 v6, v138, v50
	v_exp_f32_e32 v52, v6
	s_cmp_lg_u32 s46, 1
	v_add_u32_e32 v223, s34, v51
	v_mul_f32_e32 v6, v18, v52
	v_mul_f32_e32 v7, v19, v52
	v_mul_f32_e32 v8, v20, v52
	v_mul_f32_e32 v9, v21, v52
	v_mul_f32_e32 v10, v22, v52
	v_mul_f32_e32 v11, v23, v52
	v_mul_f32_e32 v12, v24, v52
	v_mul_f32_e32 v13, v25, v52
	v_mul_f32_e32 v14, v26, v52
	v_mul_f32_e32 v15, v27, v52
	v_mul_f32_e32 v16, v28, v52
	v_mul_f32_e32 v17, v29, v52
	v_mul_f32_e32 v18, v30, v52
	v_mul_f32_e32 v19, v31, v52
	v_mul_f32_e32 v20, v32, v52
	v_mul_f32_e32 v21, v33, v52
	s_cbranch_scc1 .LBB0_1602
	ds_write2st64_b32 v223, v6, v7 offset1:1
	ds_write2st64_b32 v223, v8, v9 offset0:2 offset1:3
	ds_write2st64_b32 v223, v10, v11 offset0:4 offset1:5
	ds_write2st64_b32 v223, v12, v13 offset0:6 offset1:7
	ds_write2st64_b32 v223, v14, v15 offset0:8 offset1:9
	ds_write2st64_b32 v223, v16, v17 offset0:10 offset1:11
	ds_write2st64_b32 v223, v18, v19 offset0:12 offset1:13
	ds_write2st64_b32 v223, v20, v21 offset0:14 offset1:15
.LBB0_1602:
	s_cmp_lt_u32 s33, 4
	s_cselect_b64 s[34:35], -1, 0
	s_lshl_b32 s45, s33, 12
	s_cmp_gt_u32 s33, 3
	v_mov_b32_e32 v139, 0
	v_add_u32_e32 v221, s45, v51
	v_mov_b32_e32 v212, 0
	v_mov_b32_e32 v213, 0
	v_mov_b32_e32 v210, 0
	v_mov_b32_e32 v211, 0
	v_mov_b32_e32 v208, 0
	v_mov_b32_e32 v209, 0
	v_mov_b32_e32 v206, 0
	v_mov_b32_e32 v207, 0
	v_mov_b32_e32 v204, 0
	v_mov_b32_e32 v205, 0
	v_mov_b32_e32 v202, 0
	v_mov_b32_e32 v203, 0
	v_mov_b32_e32 v200, 0
	v_mov_b32_e32 v201, 0
	v_mov_b32_e32 v196, 0
	v_mov_b32_e32 v197, 0
	s_waitcnt lgkmcnt(0)
	s_barrier
	s_cbranch_scc1 .LBB0_1604
	v_sub_f32_e32 v4, v4, v50
	v_sub_f32_e32 v2, v2, v50
	v_exp_f32_e32 v4, v4
	v_exp_f32_e32 v2, v2
	v_mul_f32_e32 v4, v5, v4
	v_fmac_f32_e32 v4, v3, v2
	v_div_scale_f32 v2, s[48:49], v4, v4, 1.0
	v_rcp_f32_e32 v3, v2
	v_div_scale_f32 v5, vcc, 1.0, v4, 1.0
	v_fma_f32 v22, -v2, v3, 1.0
	v_fmac_f32_e32 v3, v22, v3
	v_mul_f32_e32 v22, v5, v3
	v_fma_f32 v23, -v2, v22, v5
	v_fmac_f32_e32 v22, v23, v3
	v_fma_f32 v2, -v2, v22, v5
	v_div_fmas_f32 v2, v2, v3, v22
	v_div_fixup_f32 v2, v2, v4, 1.0
	ds_read2st64_b32 v[4:5], v221 offset1:1
	ds_read2st64_b32 v[22:23], v221 offset0:2 offset1:3
	ds_read2st64_b32 v[24:25], v221 offset0:4 offset1:5
	ds_read2st64_b32 v[26:27], v221 offset0:6 offset1:7
	ds_read2st64_b32 v[28:29], v221 offset0:8 offset1:9
	ds_read2st64_b32 v[30:31], v221 offset0:10 offset1:11
	ds_read2st64_b32 v[32:33], v221 offset0:12 offset1:13
	ds_read2st64_b32 v[50:51], v221 offset0:14 offset1:15
	s_waitcnt lgkmcnt(7)
	v_add_f32_e32 v4, v6, v4
	v_add_f32_e32 v5, v7, v5
	s_waitcnt lgkmcnt(6)
	v_add_f32_e32 v6, v8, v22
	v_add_f32_e32 v7, v9, v23
	s_waitcnt lgkmcnt(5)
	v_add_f32_e32 v8, v10, v24
	v_add_f32_e32 v9, v11, v25
	s_waitcnt lgkmcnt(4)
	v_add_f32_e32 v10, v12, v26
	v_add_f32_e32 v11, v13, v27
	s_waitcnt lgkmcnt(3)
	v_add_f32_e32 v12, v14, v28
	v_add_f32_e32 v13, v15, v29
	s_waitcnt lgkmcnt(2)
	v_add_f32_e32 v14, v16, v30
	v_add_f32_e32 v15, v17, v31
	s_waitcnt lgkmcnt(1)
	v_add_f32_e32 v16, v18, v32
	v_add_f32_e32 v17, v19, v33
	s_waitcnt lgkmcnt(0)
	v_add_f32_e32 v18, v20, v50
	v_add_f32_e32 v19, v21, v51
	v_mul_f32_e32 v200, v2, v16
	v_mul_f32_e32 v201, v2, v17
	v_mul_f32_e32 v196, v2, v18
	v_mul_f32_e32 v197, v2, v19
	v_mul_f32_e32 v202, v2, v14
	v_mul_f32_e32 v203, v2, v15
	v_mul_f32_e32 v204, v2, v12
	v_mul_f32_e32 v205, v2, v13
	v_mul_f32_e32 v206, v2, v10
	v_mul_f32_e32 v207, v2, v11
	v_mul_f32_e32 v208, v2, v8
	v_mul_f32_e32 v209, v2, v9
	v_mul_f32_e32 v210, v2, v6
	v_mul_f32_e32 v211, v2, v7
	v_mul_f32_e32 v212, v2, v4
	v_mul_f32_e32 v213, v2, v5

.LBB0_1611:
	s_waitcnt vmcnt(8)
	v_mfma_f32_32x32x16_bf16 v[18:33], v[138:141], v[50:53], 0
	s_add_i32 s44, s44, 1
	v_add_u32_e32 v164, 32, v164
	s_cmp_lg_u32 s43, s44
	v_add_u32_e32 v166, 32, v166
	v_mfma_f32_32x32x16_bf16 v[18:33], v[142:145], v[54:57], v[18:33]
	v_mfma_f32_32x32x16_bf16 v[18:33], v[146:149], v[58:61], v[18:33]
	v_mfma_f32_32x32x16_bf16 v[18:33], v[150:153], v[62:65], v[18:33]
	s_waitcnt vmcnt(7)
	s_nop 10
	v_max_f32_e32 v66, v19, v19
	v_max_f32_e32 v67, v18, v18
	v_max_f32_e32 v66, v67, v66
	v_max3_f32 v66, v66, v20, v21
	v_max3_f32 v66, v66, v22, v23
	v_max3_f32 v66, v66, v24, v25
	v_max3_f32 v66, v66, v26, v27
	v_max3_f32 v66, v66, v28, v29
	v_max3_f32 v66, v66, v30, v31
	v_max3_f32 v66, v66, v32, v33
	ds_bpermute_b32 v67, v155, v66
	s_waitcnt lgkmcnt(0)
	v_max3_f32 v138, v199, v66, v67
	v_sub_f32_e32 v18, v18, v138
	v_sub_f32_e32 v19, v19, v138
	v_exp_f32_e32 v18, v18
	v_sub_f32_e32 v20, v20, v138
	v_exp_f32_e32 v19, v19
	v_sub_f32_e32 v21, v21, v138
	v_exp_f32_e32 v20, v20
	v_sub_f32_e32 v66, v199, v138
	v_sub_f32_e32 v22, v22, v138
	v_exp_f32_e32 v21, v21
	v_sub_f32_e32 v23, v23, v138
	v_exp_f32_e32 v67, v22
	v_exp_f32_e32 v22, v66
	v_add_f32_e32 v66, 0, v18
	v_sub_f32_e32 v24, v24, v138
	v_exp_f32_e32 v23, v23
	v_add_f32_e32 v66, v19, v66
	v_sub_f32_e32 v25, v25, v138
	v_exp_f32_e32 v24, v24
	v_add_f32_e32 v66, v20, v66
	v_sub_f32_e32 v26, v26, v138
	v_exp_f32_e32 v25, v25
	v_add_f32_e32 v66, v21, v66
	v_sub_f32_e32 v27, v27, v138
	v_exp_f32_e32 v26, v26
	v_add_f32_e32 v66, v67, v66
	v_sub_f32_e32 v28, v28, v138
	v_exp_f32_e32 v27, v27
	v_add_f32_e32 v66, v23, v66
	v_sub_f32_e32 v29, v29, v138
	v_exp_f32_e32 v28, v28
	v_add_f32_e32 v66, v24, v66
	v_sub_f32_e32 v30, v30, v138
	v_exp_f32_e32 v29, v29
	v_add_f32_e32 v66, v25, v66
	v_sub_f32_e32 v31, v31, v138
	v_exp_f32_e32 v30, v30
	v_add_f32_e32 v66, v26, v66
	v_sub_f32_e32 v32, v32, v138
	v_exp_f32_e32 v31, v31
	v_add_f32_e32 v66, v27, v66
	v_sub_f32_e32 v33, v33, v138
	v_exp_f32_e32 v32, v32
	v_add_f32_e32 v66, v28, v66
	v_exp_f32_e32 v33, v33
	v_add_f32_e32 v66, v29, v66
	v_mul_f32_e32 v16, v16, v22
	v_mul_f32_e32 v17, v17, v22
	v_mul_f32_e32 v14, v14, v22
	v_mul_f32_e32 v15, v15, v22
	v_add_f32_e32 v66, v30, v66
	v_mul_f32_e32 v12, v12, v22
	v_mul_f32_e32 v13, v13, v22
	v_mul_f32_e32 v10, v10, v22
	v_mul_f32_e32 v11, v11, v22
	v_mul_f32_e32 v8, v8, v22
	v_mul_f32_e32 v9, v9, v22
	v_mul_f32_e32 v6, v6, v22
	v_mul_f32_e32 v7, v7, v22
	v_mul_f32_e32 v4, v4, v22
	v_mul_f32_e32 v5, v5, v22
	v_mul_f32_e32 v2, v2, v22
	v_mul_f32_e32 v3, v3, v22
	v_add_f32_e32 v66, v31, v66
	v_cvt_pk_bf16_f32 v18, v18, v19
	v_cvt_pk_bf16_f32 v19, v20, v21
	v_cvt_pk_bf16_f32 v20, v67, v23
	v_cvt_pk_bf16_f32 v21, v24, v25
	v_add_f32_e32 v66, v32, v66
	v_mfma_f32_32x32x16_bf16 v[2:17], v[98:101], v[18:21], v[2:17]
	v_add_f32_e32 v66, v33, v66
	ds_bpermute_b32 v18, v155, v66
	s_waitcnt lgkmcnt(0)
	v_add_f32_e32 v139, v66, v18
	v_cvt_pk_bf16_f32 v18, v26, v27
	v_cvt_pk_bf16_f32 v19, v28, v29
	v_cvt_pk_bf16_f32 v20, v30, v31
	v_cvt_pk_bf16_f32 v21, v32, v33
	v_fmac_f32_e32 v139, v198, v22
	v_mfma_f32_32x32x16_bf16 v[2:17], v[118:121], v[18:21], v[2:17]
	s_cbranch_scc0 .LBB0_1613
	v_mov_b64_e32 v[66:67], v[130:131]
	s_waitcnt vmcnt(6)
	v_mov_b64_e32 v[70:71], v[134:135]
	s_waitcnt vmcnt(5)
	v_mov_b64_e32 v[74:75], v[122:123]
	s_waitcnt vmcnt(4)
	v_mov_b64_e32 v[78:79], v[126:127]
	s_waitcnt vmcnt(3)
	v_mov_b64_e32 v[82:83], v[110:111]
	s_waitcnt vmcnt(2)
	v_mov_b64_e32 v[86:87], v[114:115]
	s_waitcnt vmcnt(1)
	v_mov_b64_e32 v[90:91], v[102:103]
	s_waitcnt vmcnt(0)
	v_mov_b64_e32 v[94:95], v[106:107]
	v_mov_b64_e32 v[18:19], v[34:35]
	v_mov_b64_e32 v[68:69], v[132:133]
	v_mov_b64_e32 v[72:73], v[136:137]
	v_mov_b64_e32 v[76:77], v[124:125]
	v_mov_b64_e32 v[80:81], v[128:129]
	v_mov_b64_e32 v[84:85], v[112:113]
	v_mov_b64_e32 v[88:89], v[116:117]
	v_mov_b64_e32 v[92:93], v[104:105]
	v_mov_b64_e32 v[96:97], v[108:109]
	v_mov_b32_e32 v199, v138
	v_mov_b32_e32 v198, v139
	v_mov_b64_e32 v[20:21], v[36:37]
	v_mov_b64_e32 v[22:23], v[38:39]
	v_mov_b64_e32 v[24:25], v[40:41]
	v_mov_b64_e32 v[26:27], v[42:43]
	v_mov_b64_e32 v[28:29], v[44:45]
	v_mov_b64_e32 v[30:31], v[46:47]
	v_mov_b64_e32 v[32:33], v[48:49]
	s_cmp_eq_u32 s44, 32
	s_mov_b64 s[8:9], -1
	s_cbranch_scc0 .LBB0_1606
	s_branch .LBB0_1609
.LBB0_1613:
	s_and_saveexec_b64 s[8:9], s[30:31]
	ds_write_b64 v222, v[138:139] offset:16384
	s_or_b64 exec, exec, s[8:9]
	s_waitcnt lgkmcnt(0)
	s_barrier
	ds_read2_b64 v[18:21], v224 offset1:32
	s_andn2_b64 vcc, exec, s[28:29]
	s_waitcnt lgkmcnt(0)
	v_max_f32_e32 v22, v20, v20
	v_max_f32_e32 v23, v18, v18
	v_max_f32_e32 v30, v23, v22
	v_sub_f32_e32 v22, v138, v30
	v_exp_f32_e32 v32, v22
	s_nop 0
	v_mul_f32_e32 v28, v2, v32
	v_mul_f32_e32 v29, v3, v32
	v_mul_f32_e32 v26, v4, v32
	v_mul_f32_e32 v27, v5, v32
	v_mul_f32_e32 v24, v6, v32
	v_mul_f32_e32 v25, v7, v32
	v_mul_f32_e32 v22, v8, v32
	v_mul_f32_e32 v23, v9, v32
	v_mul_f32_e32 v8, v10, v32
	v_mul_f32_e32 v9, v11, v32
	v_mul_f32_e32 v6, v12, v32
	v_mul_f32_e32 v7, v13, v32
	v_mul_f32_e32 v4, v14, v32
	v_mul_f32_e32 v5, v15, v32
	v_mul_f32_e32 v2, v16, v32
	v_mul_f32_e32 v3, v17, v32
	s_cbranch_vccnz .LBB0_1617
	ds_write2st64_b32 v223, v28, v29 offset1:1
	ds_write2st64_b32 v223, v26, v27 offset0:2 offset1:3
	ds_write2st64_b32 v223, v24, v25 offset0:4 offset1:5
	ds_write2st64_b32 v223, v22, v23 offset0:6 offset1:7
	ds_write2st64_b32 v223, v8, v9 offset0:8 offset1:9
	ds_write2st64_b32 v223, v6, v7 offset0:10 offset1:11
	ds_write2st64_b32 v223, v4, v5 offset0:12 offset1:13
	ds_write2st64_b32 v223, v2, v3 offset0:14 offset1:15
.LBB0_1617:
	v_cndmask_b32_e64 v10, 0, 1, s[34:35]
	v_cmp_ne_u32_e64 s[8:9], 1, v10
	s_andn2_b64 vcc, exec, s[34:35]
	s_waitcnt lgkmcnt(0)
	s_barrier
	s_cbranch_vccnz .LBB0_1621
	v_sub_f32_e32 v11, v20, v30
	v_sub_f32_e32 v10, v18, v30
	v_exp_f32_e32 v11, v11
	v_exp_f32_e32 v10, v10
	v_cvt_f32_i32_e32 v13, s42
	v_add_f32_e32 v12, v215, v216
	v_mul_f32_e32 v11, v21, v11
	v_fmac_f32_e32 v11, v19, v10
	v_add_f32_e32 v10, v218, v219
	v_mul_f32_e32 v13, 0xbe99999a, v13
	v_mul_f32_e32 v12, 0x3fb8aa3b, v12
	v_mul_f32_e32 v10, 0x3fb8aa3b, v10
	v_mul_f32_e32 v13, 0x3fb8aa3b, v13
	v_exp_f32_e32 v12, v12
	v_exp_f32_e32 v10, v10
	v_exp_f32_e32 v13, v13
	v_div_scale_f32 v14, s[28:29], v11, v11, 1.0
	v_rcp_f32_e32 v15, v14
	v_sub_f32_e32 v10, v12, v10
	v_fmamk_f32 v12, v13, 0xbf19999a, v235
	v_add_f32_e32 v10, v10, v12
	v_fma_f32 v12, -v14, v15, 1.0
	v_fmac_f32_e32 v15, v12, v15
	v_div_scale_f32 v12, vcc, 1.0, v11, 1.0
	v_mul_f32_e32 v13, v12, v15
	v_fma_f32 v16, -v14, v13, v12
	v_fmac_f32_e32 v13, v16, v15
	v_fma_f32 v12, -v14, v13, v12
	v_div_fmas_f32 v12, v12, v15, v13
	ds_read2st64_b32 v[14:15], v221 offset0:6 offset1:7
	ds_read2st64_b32 v[16:17], v221 offset0:4 offset1:5
	ds_read2st64_b32 v[18:19], v221 offset0:2 offset1:3
	ds_read2st64_b32 v[20:21], v221 offset1:1
	ds_read2st64_b32 v[30:31], v221 offset0:14 offset1:15
	ds_read2st64_b32 v[32:33], v221 offset0:12 offset1:13
	ds_read2st64_b32 v[34:35], v221 offset0:10 offset1:11
	ds_read2st64_b32 v[36:37], v221 offset0:8 offset1:9
	v_div_fixup_f32 v12, v12, v11, 1.0
	s_waitcnt lgkmcnt(4)
	v_add_f32_e32 v20, v28, v20
	v_add_f32_e32 v21, v29, v21
	v_add_f32_e32 v18, v26, v18
	v_add_f32_e32 v19, v27, v19
	v_mul_f32_e32 v20, v12, v20
	v_mul_f32_e32 v21, v12, v21
	v_fma_f32 v212, -v10, v20, v212
	v_fma_f32 v213, -v10, v21, v213
	v_mul_f32_e32 v18, v12, v18
	v_mul_f32_e32 v19, v12, v19
	v_add_f32_e32 v16, v24, v16
	v_add_f32_e32 v17, v25, v17
	v_add_f32_e32 v14, v22, v14
	v_add_f32_e32 v15, v23, v15
	s_waitcnt lgkmcnt(0)
	v_add_f32_e32 v8, v8, v36
	v_add_f32_e32 v9, v9, v37
	v_add_f32_e32 v6, v6, v34
	v_add_f32_e32 v7, v7, v35
	v_add_f32_e32 v4, v4, v32
	v_add_f32_e32 v5, v5, v33
	v_add_f32_e32 v2, v2, v30
	v_add_f32_e32 v3, v3, v31
	v_mul_f32_e32 v20, v212, v212
	v_mul_f32_e32 v21, v213, v213
	v_fma_f32 v210, -v10, v18, v210
	v_fma_f32 v211, -v10, v19, v211
	v_mul_f32_e32 v16, v12, v16
	v_mul_f32_e32 v17, v12, v17
	v_mul_f32_e32 v14, v12, v14
	v_mul_f32_e32 v15, v12, v15
	v_mul_f32_e32 v8, v12, v8
	v_mul_f32_e32 v9, v12, v9
	v_mul_f32_e32 v6, v12, v6
	v_mul_f32_e32 v7, v12, v7
	v_mul_f32_e32 v4, v12, v4
	v_mul_f32_e32 v5, v12, v5
	v_mul_f32_e32 v2, v12, v2
	v_mul_f32_e32 v3, v12, v3
	v_mul_f32_e32 v18, v210, v210
	v_mul_f32_e32 v19, v211, v211
	v_fma_f32 v208, -v10, v16, v208
	v_fma_f32 v209, -v10, v17, v209
	v_fma_f32 v206, -v10, v14, v206
	v_fma_f32 v207, -v10, v15, v207
	v_fma_f32 v204, -v10, v8, v204
	v_fma_f32 v205, -v10, v9, v205
	v_fma_f32 v202, -v10, v6, v202
	v_fma_f32 v203, -v10, v7, v203
	v_fma_f32 v200, -v10, v4, v200
	v_fma_f32 v201, -v10, v5, v201
	v_fma_f32 v196, -v10, v2, v196
	v_fma_f32 v197, -v10, v3, v197
	v_add_f32_e32 v10, v21, v20
	v_add_f32_e32 v10, v18, v10
	v_mul_f32_e32 v16, v208, v208
	v_mul_f32_e32 v17, v209, v209
	v_add_f32_e32 v10, v19, v10
	v_add_f32_e32 v10, v16, v10
	v_mul_f32_e32 v14, v206, v206
	v_mul_f32_e32 v15, v207, v207
	v_add_f32_e32 v10, v17, v10
	v_add_f32_e32 v10, v14, v10
	v_mul_f32_e32 v8, v204, v204
	v_mul_f32_e32 v9, v205, v205
	v_add_f32_e32 v10, v15, v10
	v_add_f32_e32 v8, v8, v10
	v_mul_f32_e32 v6, v202, v202
	v_mul_f32_e32 v7, v203, v203
	v_add_f32_e32 v8, v9, v8
	v_add_f32_e32 v6, v6, v8
	v_mul_f32_e32 v4, v200, v200
	v_mul_f32_e32 v5, v201, v201
	v_add_f32_e32 v6, v7, v6
	v_add_f32_e32 v4, v4, v6
	v_mul_f32_e32 v2, v196, v196
	v_mul_f32_e32 v3, v197, v197
	v_add_f32_e32 v4, v5, v4
	v_add_f32_e32 v2, v2, v4
	v_add_f32_e32 v2, v3, v2
	ds_bpermute_b32 v3, v155, v2
	s_and_saveexec_b64 s[28:29], s[6:7]
	s_cbranch_execz .LBB0_1620
	s_lshl_b32 s6, s47, 2
	s_add_i32 s6, s6, 0
	v_lshl_add_u32 v4, v0, 2, s6
	s_waitcnt lgkmcnt(0)
	v_add_f32_e32 v2, v2, v3
	ds_write_b32 v4, v2 offset:16896

.LBB0_1621:
	s_and_b64 vcc, exec, s[8:9]
	s_waitcnt lgkmcnt(0)
	s_barrier
	s_cbranch_vccnz .LBB0_1623
	v_cvt_f32_i32_e32 v2, s38
	s_lshl_b64 s[6:7], s[12:13], 2
	s_add_u32 s2, s2, s6
	s_addc_u32 s3, s3, s7
	v_mul_f32_e32 v2, 0xbe99999a, v2
	v_mul_f32_e32 v2, 0x3fb8aa3b, v2
	v_exp_f32_e32 v2, v2
	s_nop 0
	v_fmamk_f32 v2, v2, 0x3f19999a, v236
	v_add_f32_e32 v4, 1.0, v2
	v_lshl_add_u32 v2, v214, 2, 0
	v_add_u32_e32 v5, 0x4000, v2
	ds_read2_b32 v[2:3], v5 offset0:128 offset1:160
	s_waitcnt lgkmcnt(0)
	v_add_f32_e32 v6, v2, v3
	ds_read2_b32 v[2:3], v5 offset0:192 offset1:224
	v_mov_b32_e32 v5, v1
	s_waitcnt lgkmcnt(0)
	v_add_f32_e32 v2, v6, v2
	v_add_f32_e32 v2, v2, v3
	v_fmamk_f32 v2, v2, 0x3c000000, v230
	v_rsq_f32_e32 v2, v2
	v_or_b32_e32 v3, s39, v220
	v_mul_f32_e32 v6, v4, v2
	v_lshl_add_u32 v2, s33, 5, v217
	v_lshlrev_b32_e32 v4, 1, v3
	v_mov_b32_e32 v3, v1
	v_lshl_add_u64 v[8:9], s[0:1], 0, v[4:5]
	v_lshl_add_u64 v[4:5], v[2:3], 2, s[2:3]
	v_lshlrev_b32_e32 v2, 1, v2
	v_lshl_add_u64 v[12:13], v[8:9], 0, v[2:3]
	global_load_dwordx4 v[8:11], v[4:5], off
	v_mul_f32_e32 v16, v210, v6
	v_mul_f32_e32 v17, v211, v6
	s_mov_b64 s[0:1], 0x50000000
	v_mul_f32_e32 v14, v212, v6
	v_mul_f32_e32 v15, v213, v6
	v_lshl_add_u64 v[2:3], v[12:13], 0, s[0:1]
	s_movk_i32 s1, 0x7fff
	s_mov_b32 s2, 0x7060302
	s_brev_b32 s0, 10
	s_waitcnt vmcnt(0)
	v_mul_f32_e32 v10, v16, v10
	v_mul_f32_e32 v11, v17, v11
	v_mul_f32_e32 v8, v14, v8
	v_mul_f32_e32 v9, v15, v9
	v_bfe_u32 v7, v11, 16, 1
	v_bfe_u32 v14, v10, 16, 1
	v_bfe_u32 v15, v9, 16, 1
	v_bfe_u32 v16, v8, 16, 1
	v_add3_u32 v10, v10, v14, s1
	v_add3_u32 v7, v11, v7, s1
	v_add3_u32 v8, v8, v16, s1
	v_add3_u32 v11, v9, v15, s1
	v_perm_b32 v9, v7, v10, s2
	v_add_co_u32_e32 v10, vcc, s0, v12
	v_perm_b32 v8, v11, v8, s2
	s_nop 0
	v_addc_co_u32_e32 v11, vcc, 0, v13, vcc
	global_store_dwordx2 v[10:11], v[8:9], off
	global_load_dwordx4 v[8:11], v[4:5], off offset:32
	v_mul_f32_e32 v12, v208, v6
	v_mul_f32_e32 v13, v209, v6
	v_mul_f32_e32 v14, v206, v6
	v_mul_f32_e32 v15, v207, v6
	s_waitcnt vmcnt(0)
	v_mul_f32_e32 v8, v12, v8
	v_mul_f32_e32 v9, v13, v9
	v_mul_f32_e32 v10, v14, v10
	v_mul_f32_e32 v11, v15, v11
	v_bfe_u32 v13, v9, 16, 1
	v_bfe_u32 v7, v11, 16, 1
	v_bfe_u32 v12, v10, 16, 1
	v_bfe_u32 v14, v8, 16, 1
	v_add3_u32 v10, v10, v12, s1
	v_add3_u32 v7, v11, v7, s1
	v_add3_u32 v8, v8, v14, s1
	v_add3_u32 v11, v9, v13, s1
	v_perm_b32 v9, v7, v10, s2
	v_perm_b32 v8, v11, v8, s2
	global_store_dwordx2 v[2:3], v[8:9], off offset:16
	global_load_dwordx4 v[8:11], v[4:5], off offset:64
	v_mul_f32_e32 v12, v204, v6
	v_mul_f32_e32 v13, v205, v6
	v_mul_f32_e32 v14, v202, v6
	v_mul_f32_e32 v15, v203, v6
	s_waitcnt vmcnt(0)
	v_mul_f32_e32 v8, v12, v8
	v_mul_f32_e32 v9, v13, v9
	v_mul_f32_e32 v10, v14, v10
	v_mul_f32_e32 v11, v15, v11
	v_bfe_u32 v13, v9, 16, 1
	v_bfe_u32 v7, v11, 16, 1
	v_bfe_u32 v12, v10, 16, 1
	v_bfe_u32 v14, v8, 16, 1
	v_add3_u32 v10, v10, v12, s1
	v_add3_u32 v7, v11, v7, s1
	v_add3_u32 v8, v8, v14, s1
	v_add3_u32 v11, v9, v13, s1
	v_perm_b32 v9, v7, v10, s2
	v_perm_b32 v8, v11, v8, s2
	global_store_dwordx2 v[2:3], v[8:9], off offset:32
	v_mul_f32_e32 v8, v200, v6
	v_mul_f32_e32 v9, v201, v6
	v_mul_f32_e32 v10, v196, v6
	v_mul_f32_e32 v11, v197, v6
	global_load_dwordx4 v[4:7], v[4:5], off offset:96
	s_waitcnt vmcnt(0)
	v_mul_f32_e32 v6, v10, v6
	v_mul_f32_e32 v7, v11, v7
	v_mul_f32_e32 v4, v8, v4
	v_mul_f32_e32 v5, v9, v5
	v_bfe_u32 v8, v7, 16, 1
	v_bfe_u32 v9, v6, 16, 1
	v_bfe_u32 v10, v5, 16, 1
	v_bfe_u32 v11, v4, 16, 1
	v_add3_u32 v6, v6, v9, s1
	v_add3_u32 v7, v7, v8, s1
	v_add3_u32 v4, v4, v11, s1
	v_add3_u32 v8, v5, v10, s1
	v_perm_b32 v5, v7, v6, s2
	v_perm_b32 v4, v8, v4, s2
	global_store_dwordx2 v[2:3], v[4:5], off offset:48

.LBB0_1691:
	s_ashr_i32 s34, s33, 1
	s_cmp_eq_u32 s34, 2
	s_cselect_b64 vcc, -1, 0
	s_and_b64 s[6:7], vcc, exec
	s_cselect_b32 s10, 48, 0x60
	s_cmp_eq_u32 s34, 1
	s_cselect_b64 s[6:7], -1, 0
	s_waitcnt vmcnt(20)
	v_lshlrev_b32_e32 v57, 16, v3
	s_and_b64 s[8:9], s[6:7], exec
	v_sub_f32_e32 v5, 1.0, v57
	s_cselect_b32 s26, 16, s10
	s_lshl_b32 s8, s33, 2
	v_max_f32_e32 v5, 0x3a800000, v5
	s_mov_b32 s27, 0x800000
	s_add_i32 s25, s8, 0
	v_cmp_gt_f32_e64 s[8:9], s27, v5
	s_mov_b32 s35, 0x3f317217
	v_and_b32_e32 v63, 0xffff0000, v3
	v_cndmask_b32_e64 v6, 0, 32, s[8:9]
	v_ldexp_f32 v5, v5, v6
	v_log_f32_e32 v5, v5
	s_mov_b32 s38, 0x7f800000
	v_sub_f32_e32 v3, 1.0, v63
	v_max_f32_e32 v3, 0x3a800000, v3
	v_mul_f32_e32 v6, 0x3f317217, v5
	v_fma_f32 v6, v5, s35, -v6
	v_fmac_f32_e32 v6, 0x3377d1cf, v5
	v_fmac_f32_e32 v6, 0x3f317217, v5
	v_cmp_lt_f32_e64 s[10:11], |v5|, s38
	s_waitcnt vmcnt(19)
	v_lshlrev_b32_e32 v59, 16, v2
	v_and_b32_e32 v65, 0xffff0000, v2
	v_cndmask_b32_e64 v5, v5, v6, s[10:11]
	v_cndmask_b32_e64 v6, 0, v239, s[8:9]
	v_cmp_gt_f32_e64 s[8:9], s27, v3
	v_sub_f32_e32 v6, v5, v6
	v_sub_f32_e32 v2, 1.0, v65
	v_cndmask_b32_e64 v5, 0, 32, s[8:9]
	v_ldexp_f32 v3, v3, v5
	v_log_f32_e32 v3, v3
	v_max_f32_e32 v2, 0x3a800000, v2
	s_waitcnt vmcnt(4)
	v_lshlrev_b32_e32 v61, 16, v4
	v_and_b32_e32 v69, 0xffff0000, v4
	v_mul_f32_e32 v5, 0x3f317217, v3
	v_fma_f32 v5, v3, s35, -v5
	v_fmac_f32_e32 v5, 0x3377d1cf, v3
	v_fmac_f32_e32 v5, 0x3f317217, v3
	v_cmp_lt_f32_e64 s[10:11], |v3|, s38
	v_sub_f32_e32 v4, 1.0, v69
	v_max_f32_e32 v4, 0x3a800000, v4
	v_cndmask_b32_e64 v3, v3, v5, s[10:11]
	v_cndmask_b32_e64 v5, 0, v239, s[8:9]
	v_sub_f32_e32 v7, v3, v5
	v_sub_f32_e32 v3, 1.0, v59
	v_max_f32_e32 v3, 0x3a800000, v3
	v_cmp_gt_f32_e64 s[8:9], s27, v3
	v_add_f32_e32 v6, 0, v6
	v_add_f32_e32 v7, 0, v7
	v_lshlrev_b32_e32 v67, 16, v8
	v_cndmask_b32_e64 v5, 0, 32, s[8:9]
	v_ldexp_f32 v3, v3, v5
	v_log_f32_e32 v3, v3
	v_and_b32_e32 v73, 0xffff0000, v8
	v_sub_f32_e32 v8, 1.0, v73
	v_max_f32_e32 v8, 0x3a800000, v8
	v_mul_f32_e32 v5, 0x3f317217, v3
	v_fma_f32 v5, v3, s35, -v5
	v_fmac_f32_e32 v5, 0x3377d1cf, v3
	v_fmac_f32_e32 v5, 0x3f317217, v3
	v_cmp_lt_f32_e64 s[10:11], |v3|, s38
	s_waitcnt vmcnt(3)
	v_lshlrev_b32_e32 v71, 16, v10
	v_and_b32_e32 v77, 0xffff0000, v10
	v_cndmask_b32_e64 v3, v3, v5, s[10:11]
	v_cndmask_b32_e64 v5, 0, v239, s[8:9]
	v_cmp_gt_f32_e64 s[8:9], s27, v2
	v_sub_f32_e32 v18, v3, v5
	v_sub_f32_e32 v5, 1.0, v61
	v_cndmask_b32_e64 v3, 0, 32, s[8:9]
	v_ldexp_f32 v2, v2, v3
	v_log_f32_e32 v2, v2
	v_max_f32_e32 v5, 0x3a800000, v5
	v_sub_f32_e32 v10, 1.0, v77
	v_max_f32_e32 v10, 0x3a800000, v10
	v_mul_f32_e32 v3, 0x3f317217, v2
	v_fma_f32 v3, v2, s35, -v3
	v_fmac_f32_e32 v3, 0x3377d1cf, v2
	v_fmac_f32_e32 v3, 0x3f317217, v2
	v_cmp_lt_f32_e64 s[10:11], |v2|, s38
	s_waitcnt vmcnt(2)
	v_lshlrev_b32_e32 v75, 16, v12
	v_and_b32_e32 v83, 0xffff0000, v12
	v_cndmask_b32_e64 v2, v2, v3, s[10:11]
	v_cndmask_b32_e64 v3, 0, v239, s[8:9]
	v_cmp_gt_f32_e64 s[8:9], s27, v5
	v_sub_f32_e32 v19, v2, v3
	v_add_f32_e32 v2, v6, v18
	v_add_f32_e32 v3, v7, v19
	v_cndmask_b32_e64 v9, 0, 32, s[8:9]
	v_ldexp_f32 v5, v5, v9
	v_log_f32_e32 v5, v5
	v_sub_f32_e32 v12, 1.0, v83
	v_max_f32_e32 v12, 0x3a800000, v12
	s_waitcnt vmcnt(1)
	v_lshlrev_b32_e32 v79, 16, v14
	v_mul_f32_e32 v9, 0x3f317217, v5
	v_fma_f32 v9, v5, s35, -v9
	v_fmac_f32_e32 v9, 0x3377d1cf, v5
	v_fmac_f32_e32 v9, 0x3f317217, v5
	v_cmp_lt_f32_e64 s[10:11], |v5|, s38
	v_and_b32_e32 v87, 0xffff0000, v14
	v_sub_f32_e32 v14, 1.0, v87
	v_cndmask_b32_e64 v5, v5, v9, s[10:11]
	v_cndmask_b32_e64 v9, 0, v239, s[8:9]
	v_cmp_gt_f32_e64 s[8:9], s27, v4
	v_sub_f32_e32 v18, v5, v9
	v_sub_f32_e32 v9, 1.0, v67
	v_cndmask_b32_e64 v5, 0, 32, s[8:9]
	v_ldexp_f32 v4, v4, v5
	v_log_f32_e32 v4, v4
	v_max_f32_e32 v9, 0x3a800000, v9
	v_max_f32_e32 v14, 0x3a800000, v14
	v_lshlrev_b32_e32 v85, 16, v16
	v_mul_f32_e32 v5, 0x3f317217, v4
	v_fma_f32 v5, v4, s35, -v5
	v_fmac_f32_e32 v5, 0x3377d1cf, v4
	v_fmac_f32_e32 v5, 0x3f317217, v4
	v_cmp_lt_f32_e64 s[10:11], |v4|, s38
	v_and_b32_e32 v89, 0xffff0000, v16
	v_sub_f32_e32 v16, 1.0, v89
	v_cndmask_b32_e64 v4, v4, v5, s[10:11]
	v_cndmask_b32_e64 v5, 0, v239, s[8:9]
	v_cmp_gt_f32_e64 s[8:9], s27, v9
	v_sub_f32_e32 v19, v4, v5
	v_add_f32_e32 v4, v2, v18
	v_add_f32_e32 v5, v3, v19
	v_cndmask_b32_e64 v11, 0, 32, s[8:9]
	v_ldexp_f32 v9, v9, v11
	v_log_f32_e32 v9, v9
	v_max_f32_e32 v16, 0x3a800000, v16
	v_mul_f32_e32 v11, 0x3f317217, v9
	v_fma_f32 v11, v9, s35, -v11
	v_fmac_f32_e32 v11, 0x3377d1cf, v9
	v_fmac_f32_e32 v11, 0x3f317217, v9
	v_cmp_lt_f32_e64 s[10:11], |v9|, s38
	s_nop 1
	v_cndmask_b32_e64 v9, v9, v11, s[10:11]
	v_cndmask_b32_e64 v11, 0, v239, s[8:9]
	v_cmp_gt_f32_e64 s[8:9], s27, v8
	v_sub_f32_e32 v18, v9, v11
	v_sub_f32_e32 v11, 1.0, v71
	v_cndmask_b32_e64 v9, 0, 32, s[8:9]
	v_ldexp_f32 v8, v8, v9
	v_log_f32_e32 v8, v8
	v_max_f32_e32 v11, 0x3a800000, v11
	v_mul_f32_e32 v9, 0x3f317217, v8
	v_fma_f32 v9, v8, s35, -v9
	v_fmac_f32_e32 v9, 0x3377d1cf, v8
	v_fmac_f32_e32 v9, 0x3f317217, v8
	v_cmp_lt_f32_e64 s[10:11], |v8|, s38
	s_nop 1
	v_cndmask_b32_e64 v8, v8, v9, s[10:11]
	v_cndmask_b32_e64 v9, 0, v239, s[8:9]
	v_cmp_gt_f32_e64 s[8:9], s27, v11
	v_sub_f32_e32 v19, v8, v9
	v_add_f32_e32 v8, v4, v18
	v_add_f32_e32 v9, v5, v19
	v_cndmask_b32_e64 v13, 0, 32, s[8:9]
	v_ldexp_f32 v11, v11, v13
	v_log_f32_e32 v11, v11
	s_nop 0
	v_mul_f32_e32 v13, 0x3f317217, v11
	v_fma_f32 v13, v11, s35, -v13
	v_fmac_f32_e32 v13, 0x3377d1cf, v11
	v_fmac_f32_e32 v13, 0x3f317217, v11
	v_cmp_lt_f32_e64 s[10:11], |v11|, s38
	s_nop 1
	v_cndmask_b32_e64 v11, v11, v13, s[10:11]
	v_cndmask_b32_e64 v13, 0, v239, s[8:9]
	v_cmp_gt_f32_e64 s[8:9], s27, v10
	v_sub_f32_e32 v18, v11, v13
	v_sub_f32_e32 v13, 1.0, v75
	v_cndmask_b32_e64 v11, 0, 32, s[8:9]
	v_ldexp_f32 v10, v10, v11
	v_log_f32_e32 v10, v10
	v_max_f32_e32 v13, 0x3a800000, v13
	v_mul_f32_e32 v11, 0x3f317217, v10
	v_fma_f32 v11, v10, s35, -v11
	v_fmac_f32_e32 v11, 0x3377d1cf, v10
	v_fmac_f32_e32 v11, 0x3f317217, v10
	v_cmp_lt_f32_e64 s[10:11], |v10|, s38
	s_nop 1
	v_cndmask_b32_e64 v10, v10, v11, s[10:11]
	v_cndmask_b32_e64 v11, 0, v239, s[8:9]
	v_cmp_gt_f32_e64 s[8:9], s27, v13
	v_sub_f32_e32 v19, v10, v11
	v_add_f32_e32 v10, v8, v18
	v_add_f32_e32 v11, v9, v19
	v_cndmask_b32_e64 v15, 0, 32, s[8:9]
	v_ldexp_f32 v13, v13, v15
	v_log_f32_e32 v13, v13
	s_nop 0
	v_mul_f32_e32 v15, 0x3f317217, v13
	v_fma_f32 v15, v13, s35, -v15
	v_fmac_f32_e32 v15, 0x3377d1cf, v13
	v_fmac_f32_e32 v15, 0x3f317217, v13
	v_cmp_lt_f32_e64 s[10:11], |v13|, s38
	s_nop 1
	v_cndmask_b32_e64 v13, v13, v15, s[10:11]
	v_cndmask_b32_e64 v15, 0, v239, s[8:9]
	v_cmp_gt_f32_e64 s[8:9], s27, v12
	v_sub_f32_e32 v18, v13, v15
	v_sub_f32_e32 v15, 1.0, v79
	v_cndmask_b32_e64 v13, 0, 32, s[8:9]
	v_ldexp_f32 v12, v12, v13
	v_log_f32_e32 v12, v12
	v_max_f32_e32 v15, 0x3a800000, v15
	v_mul_f32_e32 v13, 0x3f317217, v12
	v_fma_f32 v13, v12, s35, -v13
	v_fmac_f32_e32 v13, 0x3377d1cf, v12
	v_fmac_f32_e32 v13, 0x3f317217, v12
	v_cmp_lt_f32_e64 s[10:11], |v12|, s38
	s_nop 1
	v_cndmask_b32_e64 v12, v12, v13, s[10:11]
	v_cndmask_b32_e64 v13, 0, v239, s[8:9]
	v_cmp_gt_f32_e64 s[8:9], s27, v15
	v_sub_f32_e32 v19, v12, v13
	v_add_f32_e32 v12, v10, v18
	v_add_f32_e32 v13, v11, v19
	v_cndmask_b32_e64 v17, 0, 32, s[8:9]
	v_ldexp_f32 v15, v15, v17
	v_log_f32_e32 v15, v15
	s_nop 0
	v_mul_f32_e32 v17, 0x3f317217, v15
	v_fma_f32 v17, v15, s35, -v17
	v_fmac_f32_e32 v17, 0x3377d1cf, v15
	v_fmac_f32_e32 v17, 0x3f317217, v15
	v_cmp_lt_f32_e64 s[10:11], |v15|, s38
	s_nop 1
	v_cndmask_b32_e64 v15, v15, v17, s[10:11]
	v_cndmask_b32_e64 v17, 0, v239, s[8:9]
	v_cmp_gt_f32_e64 s[8:9], s27, v14
	v_sub_f32_e32 v18, v15, v17
	v_sub_f32_e32 v17, 1.0, v85
	v_cndmask_b32_e64 v15, 0, 32, s[8:9]
	v_ldexp_f32 v14, v14, v15
	v_log_f32_e32 v14, v14
	v_max_f32_e32 v17, 0x3a800000, v17
	v_mul_f32_e32 v15, 0x3f317217, v14
	v_fma_f32 v15, v14, s35, -v15
	v_fmac_f32_e32 v15, 0x3377d1cf, v14
	v_fmac_f32_e32 v15, 0x3f317217, v14
	v_cmp_lt_f32_e64 s[10:11], |v14|, s38
	s_nop 1
	v_cndmask_b32_e64 v14, v14, v15, s[10:11]
	v_cndmask_b32_e64 v15, 0, v239, s[8:9]
	v_sub_f32_e32 v19, v14, v15
	v_cmp_gt_f32_e64 s[8:9], s27, v17
	v_add_f32_e32 v14, v12, v18
	v_add_f32_e32 v15, v13, v19
	s_nop 0
	v_cndmask_b32_e64 v18, 0, 32, s[8:9]
	v_ldexp_f32 v17, v17, v18
	v_log_f32_e32 v17, v17
	s_nop 0
	v_mul_f32_e32 v18, 0x3f317217, v17
	v_fma_f32 v18, v17, s35, -v18
	v_fmac_f32_e32 v18, 0x3377d1cf, v17
	v_fmac_f32_e32 v18, 0x3f317217, v17
	v_cmp_lt_f32_e64 s[10:11], |v17|, s38
	s_nop 1
	v_cndmask_b32_e64 v17, v17, v18, s[10:11]
	v_cndmask_b32_e64 v18, 0, v239, s[8:9]
	v_cmp_gt_f32_e64 s[8:9], s27, v16
	v_sub_f32_e32 v18, v17, v18
	s_nop 0
	v_cndmask_b32_e64 v17, 0, 32, s[8:9]
	v_ldexp_f32 v16, v16, v17
	v_log_f32_e32 v16, v16
	s_nop 0
	v_mul_f32_e32 v17, 0x3f317217, v16
	v_fma_f32 v17, v16, s35, -v17
	v_fmac_f32_e32 v17, 0x3377d1cf, v16
	v_fmac_f32_e32 v17, 0x3f317217, v16
	v_cmp_lt_f32_e64 s[10:11], |v16|, s38
	s_nop 1
	v_cndmask_b32_e64 v16, v16, v17, s[10:11]
	v_cndmask_b32_e64 v17, 0, v239, s[8:9]
	v_sub_f32_e32 v19, v16, v17
	s_mul_i32 s8, s33, 0x1fc
	v_add_f32_e32 v16, v14, v18
	v_add_f32_e32 v17, v15, v19
	s_add_i32 s8, s25, s8
	v_lshlrev_b32_e32 v18, 2, v38
	v_add_u32_e32 v19, s8, v18
	ds_write_b64 v19, v[16:17]
	s_waitcnt lgkmcnt(0)
	s_barrier
	v_add_u32_e32 v81, 0, v18
	ds_read2st64_b64 v[18:21], v81 offset1:1
	s_cmp_gt_u32 s33, 1
	s_cselect_b32 s38, s26, 0
	s_cmp_eq_u32 s33, 1
	s_cselect_b64 s[8:9], -1, 0
	s_waitcnt lgkmcnt(0)
	v_add_f32_e32 v18, 0, v18
	v_add_f32_e32 v19, 0, v19
	s_cmp_eq_u32 s33, 2
	v_cndmask_b32_e64 v24, 0, v19, s[8:9]
	v_cndmask_b32_e64 v25, 0, v18, s[8:9]
	v_add_f32_e32 v22, v18, v20
	v_add_f32_e32 v23, v19, v21
	ds_read2st64_b64 v[18:21], v81 offset0:2 offset1:3
	s_cselect_b64 s[8:9], -1, 0
	s_cmp_eq_u32 s33, 3
	v_cndmask_b32_e64 v25, v25, v22, s[8:9]
	v_cndmask_b32_e64 v24, v24, v23, s[8:9]
	s_waitcnt lgkmcnt(0)
	v_add_f32_e32 v18, v22, v18
	v_add_f32_e32 v19, v23, v19
	s_cselect_b64 s[8:9], -1, 0
	v_cndmask_b32_e64 v24, v24, v19, s[8:9]
	v_cndmask_b32_e64 v25, v25, v18, s[8:9]
	v_add_f32_e32 v26, v18, v20
	v_add_f32_e32 v27, v19, v21
	ds_read2st64_b64 v[18:21], v81 offset0:4 offset1:5
	s_cmp_eq_u32 s33, 4
	s_cselect_b64 s[8:9], -1, 0
	s_cmp_eq_u32 s33, 5
	v_cndmask_b32_e64 v25, v25, v26, s[8:9]
	s_waitcnt lgkmcnt(0)
	v_add_f32_e32 v18, v26, v18
	v_add_f32_e32 v19, v27, v19
	v_cndmask_b32_e64 v24, v24, v27, s[8:9]
	s_cselect_b64 s[8:9], -1, 0
	v_cndmask_b32_e64 v24, v24, v19, s[8:9]
	v_cndmask_b32_e64 v25, v25, v18, s[8:9]
	v_add_f32_e32 v28, v18, v20
	v_add_f32_e32 v29, v19, v21
	ds_read2st64_b64 v[18:21], v81 offset0:6 offset1:7
	s_cmp_eq_u32 s33, 6
	s_cselect_b64 s[8:9], -1, 0
	v_cndmask_b32_e64 v95, v25, v28, s[8:9]
	v_cndmask_b32_e64 v97, v24, v29, s[8:9]
	s_waitcnt lgkmcnt(0)
	v_add_f32_e32 v24, v28, v18
	v_add_f32_e32 v25, v29, v19
	s_cmp_eq_u32 s33, 7
	s_cselect_b64 s[8:9], -1, 0
	v_add_f32_e32 v18, v24, v20
	v_add_f32_e32 v19, v25, v21
	v_cndmask_b32_e64 v20, 0, v23, s[6:7]
	v_cndmask_b32_e64 v21, 0, v22, s[6:7]
	v_cndmask_b32_e64 v91, v23, v27, s[6:7]
	v_cndmask_b32_e64 v93, v22, v26, s[6:7]
	s_cmp_eq_u32 s34, 3
	v_cndmask_b32_e32 v21, v21, v26, vcc
	v_cndmask_b32_e32 v20, v20, v27, vcc
	v_cndmask_b32_e32 v93, v93, v28, vcc
	v_cndmask_b32_e32 v91, v91, v29, vcc
	s_cselect_b64 vcc, -1, 0
	v_cndmask_b32_e32 v147, v20, v29, vcc
	v_cndmask_b32_e32 v146, v21, v28, vcc
	v_cndmask_b32_e32 v21, v91, v19, vcc
	v_cndmask_b32_e32 v20, v93, v18, vcc
	v_sub_f32_e32 v22, v22, v20
	v_sub_f32_e32 v23, v23, v21
	v_mul_f32_e32 v99, 0x3fb8aa3b, v146
	v_min_f32_e32 v22, 0, v22
	v_mul_f32_e32 v22, 0x3fb8aa3b, v22
	v_exp_f32_e32 v91, v22
	v_min_f32_e32 v22, 0, v23
	v_mul_f32_e32 v22, 0x3fb8aa3b, v22
	v_exp_f32_e32 v93, v22
	v_cndmask_b32_e64 v23, v97, v25, s[8:9]
	v_cndmask_b32_e64 v22, v95, v24, s[8:9]
	v_sub_f32_e32 v24, v22, v146
	v_sub_f32_e32 v25, v23, v147
	v_sub_f32_e32 v22, v20, v146
	v_sub_f32_e32 v23, v21, v147
	v_add_f32_e32 v6, v6, v24
	v_add_f32_e32 v7, v7, v25
	v_mul_f32_e32 v101, 0x3fb8aa3b, v147
	v_mul_f32_e32 v103, 0x3fb8aa3b, v6
	v_mul_f32_e32 v105, 0x3fb8aa3b, v7
	v_exp_f32_e32 v103, v103
	v_exp_f32_e32 v105, v105
	v_sub_f32_e32 v6, v22, v6
	v_sub_f32_e32 v7, v23, v7
	v_exp_f32_e32 v97, v99
	v_rcp_f32_e32 v107, v103
	v_rcp_f32_e32 v109, v105
	v_mul_f32_e32 v6, 0x3fb8aa3b, v6
	v_mul_f32_e32 v7, 0x3fb8aa3b, v7
	v_exp_f32_e32 v6, v6
	v_exp_f32_e32 v7, v7
	v_exp_f32_e32 v99, v101
	v_lshlrev_b32_e32 v95, 1, v38
	v_lshlrev_b32_e32 v101, 16, v53
	s_add_i32 s35, s38, s24
	v_sub_u32_e32 v95, v81, v95
	v_and_b32_e32 v53, 0xffff0000, v53
	v_min_f32_e32 v107, 0x79297b5a, v107
	v_min_f32_e32 v109, 0x79297b5a, v109
	v_mul_f32_e32 v101, v103, v101
	s_mul_i32 s6, s33, 0x880
	s_cmp_lt_i32 s34, 1
	v_mul_f32_e32 v103, v105, v53
	v_cvt_pk_bf16_f32 v105, v101, v103
	v_add_u32_e32 v53, s6, v95
	v_mul_f32_e32 v101, v97, v101
	v_mul_f32_e32 v6, v6, v57
	v_mul_f32_e32 v7, v7, v63
	v_mul_f32_e32 v57, v107, v57
	v_mul_f32_e32 v63, v109, v63
	s_mulk_i32 s35, 0x110
	s_cselect_b64 s[8:9], -1, 0
	ds_write_b32 v53, v105 offset:8192
	v_mul_f32_e32 v103, v99, v103
	v_cvt_pk_bf16_f32 v101, v101, v103
	ds_write_b32 v53, v101 offset:25600
	v_cvt_pk_bf16_f32 v57, v57, v63
	v_add_u32_e32 v63, s35, v95
	s_and_b64 vcc, exec, s[8:9]
	ds_write_b32 v63, v57 offset:43008
	s_cbranch_vccz .LBB0_1693
	v_mul_f32_e32 v57, v93, v7
	v_mul_f32_e32 v63, v91, v6
	v_cvt_pk_bf16_f32 v57, v63, v57
	ds_write_b32 v53, v57 offset:47360
.LBB0_1693:
	v_sub_f32_e32 v26, v26, v20
	v_sub_f32_e32 v27, v27, v21
	s_cmp_lt_i32 s34, 2
	v_min_f32_e32 v26, 0, v26
	v_min_f32_e32 v27, 0, v27
	v_mul_f32_e32 v26, 0x3fb8aa3b, v26
	v_mul_f32_e32 v27, 0x3fb8aa3b, v27
	v_exp_f32_e32 v26, v26
	v_exp_f32_e32 v27, v27
	s_cselect_b64 s[10:11], -1, 0
	s_cmp_gt_i32 s34, 1
	s_cbranch_scc1 .LBB0_1695
	v_mul_f32_e32 v57, v27, v7
	v_mul_f32_e32 v63, v26, v6
	v_cvt_pk_bf16_f32 v57, v63, v57
	ds_write_b32 v53, v57 offset:56064
.LBB0_1695:
	v_sub_f32_e32 v28, v28, v20
	v_sub_f32_e32 v29, v29, v21
	s_cmp_lt_i32 s34, 3
	v_min_f32_e32 v28, 0, v28
	v_min_f32_e32 v29, 0, v29
	v_mul_f32_e32 v28, 0x3fb8aa3b, v28
	v_mul_f32_e32 v29, 0x3fb8aa3b, v29
	v_exp_f32_e32 v28, v28
	v_exp_f32_e32 v29, v29
	s_cselect_b64 s[26:27], -1, 0
	s_cmp_gt_i32 s34, 2
	s_cbranch_scc1 .LBB0_1697
	v_add_u32_e32 v57, 0x10e00, v53
	v_mul_f32_e32 v63, v29, v7
	v_mul_f32_e32 v101, v28, v6
	v_cvt_pk_bf16_f32 v63, v101, v63
	ds_write_b32 v57, v63
.LBB0_1697:
	v_add_f32_e32 v2, v2, v24
	v_add_f32_e32 v3, v3, v25
	s_or_b32 s6, s24, 1
	v_mul_f32_e32 v57, 0x3fb8aa3b, v2
	v_mul_f32_e32 v63, 0x3fb8aa3b, v3
	v_exp_f32_e32 v57, v57
	v_exp_f32_e32 v63, v63
	v_sub_f32_e32 v2, v22, v2
	v_sub_f32_e32 v3, v23, v3
	v_lshlrev_b32_e32 v105, 16, v52
	v_rcp_f32_e32 v101, v57
	v_rcp_f32_e32 v103, v63
	v_mul_f32_e32 v2, 0x3fb8aa3b, v2
	v_exp_f32_e32 v2, v2
	v_mul_f32_e32 v3, 0x3fb8aa3b, v3
	v_and_b32_e32 v52, 0xffff0000, v52
	v_exp_f32_e32 v3, v3
	v_mul_f32_e32 v57, v57, v105
	s_mul_i32 s7, s6, 0x110
	v_mul_f32_e32 v63, v63, v52
	v_cvt_pk_bf16_f32 v105, v57, v63
	v_add_u32_e32 v52, s7, v95
	v_mul_f32_e32 v57, v97, v57
	v_min_f32_e32 v101, 0x79297b5a, v101
	v_min_f32_e32 v103, 0x79297b5a, v103
	ds_write_b32 v52, v105 offset:8192
	v_mul_f32_e32 v63, v99, v63
	v_cvt_pk_bf16_f32 v57, v57, v63
	s_add_i32 s6, s38, s6
	ds_write_b32 v52, v57 offset:25600
	v_mul_f32_e32 v2, v2, v59
	v_mul_f32_e32 v57, v101, v59
	v_mul_f32_e32 v59, v103, v65
	s_mulk_i32 s6, 0x110
	v_cndmask_b32_e64 v63, 0, 1, s[8:9]
	v_mul_f32_e32 v3, v3, v65
	v_cvt_pk_bf16_f32 v57, v57, v59
	v_add_u32_e32 v59, s6, v95
	v_cmp_ne_u32_e64 s[6:7], 1, v63
	s_andn2_b64 vcc, exec, s[8:9]
	ds_write_b32 v59, v57 offset:43008
	s_cbranch_vccz .LBB0_1777
	v_cndmask_b32_e64 v57, 0, 1, s[10:11]
	v_cmp_ne_u32_e64 s[8:9], 1, v57
	s_andn2_b64 vcc, exec, s[10:11]
	s_cbranch_vccz .LBB0_1778

.LBB0_1701:
	v_add_f32_e32 v4, v4, v24
	v_add_f32_e32 v5, v5, v25
	v_lshlrev_b32_e32 v101, 16, v51
	v_mul_f32_e32 v57, 0x3fb8aa3b, v4
	v_mul_f32_e32 v59, 0x3fb8aa3b, v5
	v_exp_f32_e32 v57, v57
	v_exp_f32_e32 v59, v59
	v_sub_f32_e32 v4, v22, v4
	v_sub_f32_e32 v5, v23, v5
	v_and_b32_e32 v51, 0xffff0000, v51
	v_rcp_f32_e32 v63, v57
	v_rcp_f32_e32 v65, v59
	v_mul_f32_e32 v4, 0x3fb8aa3b, v4
	v_mul_f32_e32 v5, 0x3fb8aa3b, v5
	v_exp_f32_e32 v4, v4
	v_exp_f32_e32 v5, v5
	v_mul_f32_e32 v51, v59, v51
	v_mul_f32_e32 v57, v57, v101
	v_cvt_pk_bf16_f32 v59, v57, v51
	v_mul_f32_e32 v51, v99, v51
	v_min_f32_e32 v63, 0x79297b5a, v63
	v_min_f32_e32 v65, 0x79297b5a, v65
	ds_write_b32 v52, v59 offset:8464
	v_mul_f32_e32 v57, v97, v57
	v_cvt_pk_bf16_f32 v51, v57, v51
	ds_write_b32 v52, v51 offset:25872
	v_mul_f32_e32 v51, v63, v61
	v_mul_f32_e32 v57, v65, v69
	s_add_i32 s26, s35, 0x220
	v_mul_f32_e32 v4, v4, v61
	v_mul_f32_e32 v5, v5, v69
	v_cvt_pk_bf16_f32 v51, v51, v57
	v_add_u32_e32 v57, s26, v95
	s_and_b64 vcc, exec, s[6:7]
	ds_write_b32 v57, v51 offset:43008
	s_cbranch_vccz .LBB0_1779
	s_and_b64 vcc, exec, s[8:9]
	s_cbranch_vccz .LBB0_1780

.LBB0_1705:
	v_add_f32_e32 v8, v8, v24
	v_add_f32_e32 v9, v9, v25
	v_lshlrev_b32_e32 v63, 16, v50
	v_mul_f32_e32 v51, 0x3fb8aa3b, v8
	v_mul_f32_e32 v57, 0x3fb8aa3b, v9
	v_exp_f32_e32 v51, v51
	v_exp_f32_e32 v57, v57
	v_sub_f32_e32 v8, v22, v8
	v_sub_f32_e32 v9, v23, v9
	v_and_b32_e32 v50, 0xffff0000, v50
	v_rcp_f32_e32 v59, v51
	v_rcp_f32_e32 v61, v57
	v_mul_f32_e32 v8, 0x3fb8aa3b, v8
	v_mul_f32_e32 v9, 0x3fb8aa3b, v9
	v_exp_f32_e32 v8, v8
	v_exp_f32_e32 v9, v9
	v_mul_f32_e32 v50, v57, v50
	v_mul_f32_e32 v51, v51, v63
	v_cvt_pk_bf16_f32 v57, v51, v50
	v_mul_f32_e32 v50, v99, v50
	v_min_f32_e32 v59, 0x79297b5a, v59
	v_min_f32_e32 v61, 0x79297b5a, v61
	ds_write_b32 v52, v57 offset:8736
	v_mul_f32_e32 v51, v97, v51
	v_cvt_pk_bf16_f32 v50, v51, v50
	ds_write_b32 v52, v50 offset:26144
	v_mul_f32_e32 v50, v59, v67
	v_mul_f32_e32 v51, v61, v73
	s_add_i32 s26, s35, 0x330
	v_mul_f32_e32 v8, v8, v67
	v_mul_f32_e32 v9, v9, v73
	v_cvt_pk_bf16_f32 v50, v50, v51
	v_add_u32_e32 v51, s26, v95
	s_and_b64 vcc, exec, s[6:7]
	ds_write_b32 v51, v50 offset:43008
	s_cbranch_vccz .LBB0_1781
	s_and_b64 vcc, exec, s[8:9]
	s_cbranch_vccz .LBB0_1782

.LBB0_1709:
	v_add_f32_e32 v10, v10, v24
	v_add_f32_e32 v11, v11, v25
	v_lshlrev_b32_e32 v61, 16, v49
	v_mul_f32_e32 v50, 0x3fb8aa3b, v10
	v_mul_f32_e32 v51, 0x3fb8aa3b, v11
	v_exp_f32_e32 v50, v50
	v_exp_f32_e32 v51, v51
	v_sub_f32_e32 v10, v22, v10
	v_sub_f32_e32 v11, v23, v11
	v_and_b32_e32 v49, 0xffff0000, v49
	v_rcp_f32_e32 v57, v50
	v_rcp_f32_e32 v59, v51
	v_mul_f32_e32 v10, 0x3fb8aa3b, v10
	v_mul_f32_e32 v11, 0x3fb8aa3b, v11
	v_exp_f32_e32 v10, v10
	v_exp_f32_e32 v11, v11
	v_mul_f32_e32 v49, v51, v49
	v_mul_f32_e32 v50, v50, v61
	v_cvt_pk_bf16_f32 v51, v50, v49
	v_mul_f32_e32 v49, v99, v49
	v_min_f32_e32 v57, 0x79297b5a, v57
	v_min_f32_e32 v59, 0x79297b5a, v59
	ds_write_b32 v52, v51 offset:9008
	v_mul_f32_e32 v50, v97, v50
	v_cvt_pk_bf16_f32 v49, v50, v49
	ds_write_b32 v52, v49 offset:26416
	v_mul_f32_e32 v49, v57, v71
	v_mul_f32_e32 v50, v59, v77
	s_add_i32 s26, s35, 0x440
	v_mul_f32_e32 v10, v10, v71
	v_mul_f32_e32 v11, v11, v77
	v_cvt_pk_bf16_f32 v49, v49, v50
	v_add_u32_e32 v50, s26, v95
	s_and_b64 vcc, exec, s[6:7]
	ds_write_b32 v50, v49 offset:43008
	s_cbranch_vccz .LBB0_1783
	s_and_b64 vcc, exec, s[8:9]
	s_cbranch_vccz .LBB0_1784

.LBB0_1713:
	v_add_f32_e32 v12, v12, v24
	v_add_f32_e32 v13, v13, v25
	v_lshlrev_b32_e32 v59, 16, v48
	v_mul_f32_e32 v49, 0x3fb8aa3b, v12
	v_mul_f32_e32 v50, 0x3fb8aa3b, v13
	v_exp_f32_e32 v49, v49
	v_exp_f32_e32 v50, v50
	v_sub_f32_e32 v12, v22, v12
	v_sub_f32_e32 v13, v23, v13
	v_and_b32_e32 v48, 0xffff0000, v48
	v_rcp_f32_e32 v51, v49
	v_rcp_f32_e32 v57, v50
	v_mul_f32_e32 v12, 0x3fb8aa3b, v12
	v_mul_f32_e32 v13, 0x3fb8aa3b, v13
	v_exp_f32_e32 v12, v12
	v_exp_f32_e32 v13, v13
	v_mul_f32_e32 v48, v50, v48
	v_mul_f32_e32 v49, v49, v59
	v_cvt_pk_bf16_f32 v50, v49, v48
	v_mul_f32_e32 v48, v99, v48
	v_min_f32_e32 v51, 0x79297b5a, v51
	v_min_f32_e32 v57, 0x79297b5a, v57
	ds_write_b32 v52, v50 offset:9280
	v_mul_f32_e32 v49, v97, v49
	v_cvt_pk_bf16_f32 v48, v49, v48
	ds_write_b32 v52, v48 offset:26688
	v_mul_f32_e32 v48, v51, v75
	v_mul_f32_e32 v49, v57, v83
	s_add_i32 s26, s35, 0x550
	v_mul_f32_e32 v12, v12, v75
	v_mul_f32_e32 v13, v13, v83
	v_cvt_pk_bf16_f32 v48, v48, v49
	v_add_u32_e32 v49, s26, v95
	s_and_b64 vcc, exec, s[6:7]
	ds_write_b32 v49, v48 offset:43008
	s_cbranch_vccz .LBB0_1785
	s_and_b64 vcc, exec, s[8:9]
	s_cbranch_vccz .LBB0_1786

.LBB0_1717:
	v_add_f32_e32 v14, v14, v24
	v_add_f32_e32 v15, v15, v25
	v_lshlrev_b32_e32 v57, 16, v47
	v_mul_f32_e32 v48, 0x3fb8aa3b, v14
	v_mul_f32_e32 v49, 0x3fb8aa3b, v15
	v_exp_f32_e32 v48, v48
	v_exp_f32_e32 v49, v49
	v_sub_f32_e32 v14, v22, v14
	v_sub_f32_e32 v15, v23, v15
	v_and_b32_e32 v47, 0xffff0000, v47
	v_rcp_f32_e32 v50, v48
	v_rcp_f32_e32 v51, v49
	v_mul_f32_e32 v14, 0x3fb8aa3b, v14
	v_mul_f32_e32 v15, 0x3fb8aa3b, v15
	v_exp_f32_e32 v14, v14
	v_exp_f32_e32 v15, v15
	v_mul_f32_e32 v47, v49, v47
	v_mul_f32_e32 v48, v48, v57
	v_cvt_pk_bf16_f32 v49, v48, v47
	v_mul_f32_e32 v47, v99, v47
	v_min_f32_e32 v50, 0x79297b5a, v50
	v_min_f32_e32 v51, 0x79297b5a, v51
	ds_write_b32 v52, v49 offset:9552
	v_mul_f32_e32 v48, v97, v48
	v_cvt_pk_bf16_f32 v47, v48, v47
	ds_write_b32 v52, v47 offset:26960
	v_mul_f32_e32 v47, v50, v79
	v_mul_f32_e32 v48, v51, v87
	s_add_i32 s26, s35, 0x660
	v_mul_f32_e32 v14, v14, v79
	v_mul_f32_e32 v15, v15, v87
	v_cvt_pk_bf16_f32 v47, v47, v48
	v_add_u32_e32 v48, s26, v95
	s_and_b64 vcc, exec, s[6:7]
	ds_write_b32 v48, v47 offset:43008
	s_cbranch_vccz .LBB0_1787
	s_and_b64 vcc, exec, s[8:9]
	s_cbranch_vccz .LBB0_1788

.LBB0_1721:
	v_add_f32_e32 v16, v16, v24
	v_add_f32_e32 v17, v17, v25
	v_lshlrev_b32_e32 v49, 16, v46
	v_mul_f32_e32 v24, 0x3fb8aa3b, v16
	v_mul_f32_e32 v25, 0x3fb8aa3b, v17
	v_exp_f32_e32 v24, v24
	v_exp_f32_e32 v25, v25
	v_sub_f32_e32 v16, v22, v16
	v_sub_f32_e32 v17, v23, v17
	v_and_b32_e32 v46, 0xffff0000, v46
	v_rcp_f32_e32 v47, v24
	v_rcp_f32_e32 v48, v25
	v_mul_f32_e32 v16, 0x3fb8aa3b, v16
	v_mul_f32_e32 v17, 0x3fb8aa3b, v17
	v_exp_f32_e32 v16, v16
	v_exp_f32_e32 v17, v17
	v_mul_f32_e32 v22, v24, v49
	v_mul_f32_e32 v23, v25, v46
	v_cvt_pk_bf16_f32 v24, v22, v23
	v_mul_f32_e32 v22, v97, v22
	v_min_f32_e32 v47, 0x79297b5a, v47
	v_min_f32_e32 v48, 0x79297b5a, v48
	ds_write_b32 v52, v24 offset:9824
	v_mul_f32_e32 v23, v99, v23
	v_cvt_pk_bf16_f32 v22, v22, v23
	ds_write_b32 v52, v22 offset:27232
	v_mul_f32_e32 v22, v47, v85
	v_mul_f32_e32 v23, v48, v89
	s_addk_i32 s35, 0x770
	v_mul_f32_e32 v16, v16, v85
	v_mul_f32_e32 v17, v17, v89
	v_cvt_pk_bf16_f32 v22, v22, v23
	v_add_u32_e32 v23, s35, v95
	s_and_b64 vcc, exec, s[6:7]
	ds_write_b32 v23, v22 offset:43008
	s_cbranch_vccz .LBB0_1789
	s_and_b64 vcc, exec, s[8:9]
	s_cbranch_vccz .LBB0_1790

.LBB0_1725:
	v_sub_f32_e32 v20, v18, v20
	v_sub_f32_e32 v21, v19, v21
	s_lshl_b32 s6, s24, 1
	v_mul_f32_e32 v20, 0x3fb8aa3b, v20
	v_mul_f32_e32 v21, 0x3fb8aa3b, v21
	v_exp_f32_e32 v20, v20
	v_exp_f32_e32 v21, v21
	s_movk_i32 s7, 0x90
	s_add_i32 s6, s6, 0
	v_mul_f32_e32 v25, v20, v4
	v_mul_f32_e32 v23, v21, v13
	v_mul_f32_e32 v13, v20, v10
	v_mul_f32_e32 v10, v20, v2
	v_mul_lo_u32 v2, v38, s7
	v_mul_f32_e32 v27, v21, v3
	v_add_u32_e32 v38, s6, v2
	v_lshlrev_b32_e32 v2, 16, v39
	s_mov_b32 s6, 0xffff
	v_lshlrev_b32_e32 v3, 16, v41
	v_lshlrev_b32_e32 v4, 16, v43
	v_and_or_b32 v2, v0, s6, v2
	v_and_or_b32 v3, v40, s6, v3
	v_and_or_b32 v4, v42, s6, v4
	v_lshrrev_b32_e32 v0, 16, v0
	s_mov_b32 s6, 0xffff0000
	v_mul_f32_e32 v28, v20, v6
	v_and_or_b32 v6, v39, s6, v0
	v_lshrrev_b32_e32 v0, 16, v40
	v_mul_f32_e32 v29, v21, v7
	v_and_or_b32 v7, v41, s6, v0
	v_lshrrev_b32_e32 v0, 16, v42
	v_mul_f32_e32 v24, v21, v11
	v_mul_f32_e32 v11, v20, v8
	v_and_or_b32 v8, v43, s6, v0
	v_lshrrev_b32_e32 v0, 16, v44
	v_mul_f32_e32 v22, v21, v15
	v_mul_f32_e32 v12, v20, v12
	v_mul_f32_e32 v15, v21, v9
	s_waitcnt vmcnt(0)
	v_and_or_b32 v9, v45, s6, v0
	v_mul_f32_e32 v0, v20, v16
	v_mul_f32_e32 v14, v20, v14
	v_mul_f32_e32 v26, v21, v5
	v_and_b32_e32 v5, 0xffff, v44
	v_mul_f32_e32 v17, v21, v17
	v_cvt_pk_bf16_f32 v10, v28, v10
	v_cvt_pk_bf16_f32 v11, v25, v11
	v_cvt_pk_bf16_f32 v12, v13, v12
	v_cvt_pk_bf16_f32 v13, v14, v0
	v_add_u32_e32 v0, 0x19a00, v38
	v_lshl_or_b32 v5, v45, 16, v5
	s_cmp_lg_u32 s33, 0
	v_cvt_pk_bf16_f32 v14, v29, v27
	v_cvt_pk_bf16_f32 v15, v26, v15
	v_cvt_pk_bf16_f32 v16, v24, v23
	v_cvt_pk_bf16_f32 v17, v22, v17
	ds_write_b128 v0, v[10:13]
	ds_write_b128 v0, v[14:17] offset:144
	v_add_u32_e32 v0, 0x15200, v38
	ds_write_b128 v0, v[2:5]
	ds_write_b128 v0, v[6:9] offset:144
	s_cbranch_scc1 .LBB0_1727
	v_mul_f32_e32 v0, 0x3fb8aa3b, v18
	v_exp_f32_e32 v2, v0
	v_mul_f32_e32 v0, 0x3fb8aa3b, v19
	v_exp_f32_e32 v3, v0
	ds_write_b64 v81, v[2:3] offset:6144

.LBB0_1773:
	s_or_b64 exec, exec, s[6:7]
	s_lshl_b64 s[0:1], s[0:1], 2
	s_add_u32 s6, s20, s0
	s_addc_u32 s7, s21, s1
	s_add_i32 s0, 0, 0x19a00
	ds_read_b128 v[50:53], v0
	ds_read_b128 v[38:41], v0 offset:64
	v_add_u32_e32 v0, 0, v146
	v_add3_u32 v146, s0, v146, v147
	s_waitcnt lgkmcnt(2)
	ds_read_b128 v[6:9], v0 offset:6144
	ds_read_b128 v[10:13], v146
	s_add_u32 s0, s18, s8
	v_ashrrev_i32_e32 v155, 31, v154
	s_addc_u32 s1, s19, s9
	s_waitcnt lgkmcnt(1)
	v_mul_f32_e32 v6, v30, v6
	v_mul_f32_e32 v7, v31, v7
	v_mul_f32_e32 v8, v124, v8
	v_mul_f32_e32 v9, v125, v9
	s_mov_b64 s[8:9], 0x74f00000
	s_add_u32 s0, s0, s24
	s_waitcnt lgkmcnt(0)
	v_mfma_f32_16x16x32_bf16 v[6:9], v[10:13], v[50:53], v[6:9]
	ds_read_b128 v[10:13], v146 offset:64
	s_addc_u32 s1, s1, 0
	s_add_u32 s0, s0, s10
	s_addc_u32 s1, s1, s11
	s_waitcnt lgkmcnt(0)
	v_mfma_f32_16x16x32_bf16 v[6:9], v[10:13], v[38:41], v[6:9]
	ds_read_b128 v[10:13], v0 offset:6208
	ds_read_b128 v[18:21], v146 offset:2304
	s_add_u32 s0, s0, 0x54100000
	s_addc_u32 s1, s1, 0
	v_cmp_gt_i32_e32 vcc, 8, v145
	s_waitcnt lgkmcnt(1)
	v_mul_f32_e32 v10, v32, v10
	v_mul_f32_e32 v11, v33, v11
	v_mul_f32_e32 v12, v126, v12
	v_mul_f32_e32 v13, v127, v13
	ds_read_b128 v[22:25], v146 offset:4608
	ds_read_b128 v[26:29], v146 offset:6912
	s_waitcnt lgkmcnt(2)
	v_mfma_f32_16x16x32_bf16 v[10:13], v[18:21], v[50:53], v[10:13]
	ds_read_b128 v[18:21], v146 offset:2368
	ds_read_b128 v[30:33], v146 offset:9216
	ds_read_b128 v[124:127], v146 offset:16128
	s_waitcnt lgkmcnt(2)
	v_mfma_f32_16x16x32_bf16 v[10:13], v[18:21], v[38:41], v[10:13]
	ds_read_b128 v[18:21], v0 offset:6272
	s_waitcnt lgkmcnt(0)
	v_mul_f32_e32 v18, v34, v18
	v_mul_f32_e32 v19, v35, v19
	v_mul_f32_e32 v20, v132, v20
	v_mul_f32_e32 v21, v133, v21
	s_nop 1
	v_mfma_f32_16x16x32_bf16 v[18:21], v[22:25], v[50:53], v[18:21]
	ds_read_b128 v[22:25], v146 offset:4672
	s_waitcnt lgkmcnt(0)
	v_mfma_f32_16x16x32_bf16 v[18:21], v[22:25], v[38:41], v[18:21]
	ds_read_b128 v[22:25], v0 offset:6336
	s_waitcnt lgkmcnt(0)
	v_mul_f32_e32 v22, v36, v22
	v_mul_f32_e32 v23, v37, v23
	v_mul_f32_e32 v24, v134, v24
	v_mul_f32_e32 v25, v135, v25
	ds_read_b128 v[34:37], v146 offset:11520
	s_nop 0
	v_mfma_f32_16x16x32_bf16 v[22:25], v[26:29], v[50:53], v[22:25]
	ds_read_b128 v[26:29], v146 offset:6976
	s_waitcnt lgkmcnt(0)
	v_mfma_f32_16x16x32_bf16 v[22:25], v[26:29], v[38:41], v[22:25]
	ds_read_b128 v[26:29], v0 offset:6400
	s_waitcnt lgkmcnt(0)
	v_mul_f32_e32 v26, v120, v26
	v_mul_f32_e32 v27, v121, v27
	v_mul_f32_e32 v28, v136, v28
	v_mul_f32_e32 v29, v137, v29
	s_nop 1
	v_mfma_f32_16x16x32_bf16 v[26:29], v[30:33], v[50:53], v[26:29]
	ds_read_b128 v[30:33], v146 offset:9280
	s_waitcnt lgkmcnt(0)
	v_mfma_f32_16x16x32_bf16 v[26:29], v[30:33], v[38:41], v[26:29]
	ds_read_b128 v[30:33], v0 offset:6464
	s_waitcnt lgkmcnt(0)
	v_mul_f32_e32 v30, v122, v30
	v_mul_f32_e32 v31, v123, v31
	v_mul_f32_e32 v32, v138, v32
	v_mul_f32_e32 v33, v139, v33
	ds_read_b128 v[120:123], v146 offset:13824
	s_nop 0
	v_mfma_f32_16x16x32_bf16 v[30:33], v[34:37], v[50:53], v[30:33]
	ds_read_b128 v[34:37], v146 offset:11584
	s_waitcnt lgkmcnt(0)
	v_mfma_f32_16x16x32_bf16 v[30:33], v[34:37], v[38:41], v[30:33]
	ds_read_b128 v[34:37], v0 offset:6528
	s_waitcnt lgkmcnt(0)
	v_mul_f32_e32 v34, v130, v34
	v_mul_f32_e32 v35, v131, v35
	v_mul_f32_e32 v36, v142, v36
	v_mul_f32_e32 v37, v143, v37
	s_nop 1
	v_mfma_f32_16x16x32_bf16 v[34:37], v[120:123], v[50:53], v[34:37]
	ds_read_b128 v[120:123], v146 offset:13888
	s_waitcnt lgkmcnt(0)
	v_mfma_f32_16x16x32_bf16 v[34:37], v[120:123], v[38:41], v[34:37]
	ds_read_b128 v[120:123], v0 offset:6592
	s_waitcnt lgkmcnt(0)
	v_mul_f32_e32 v120, v128, v120
	v_mul_f32_e32 v121, v129, v121
	v_mul_f32_e32 v122, v140, v122
	v_mul_f32_e32 v123, v141, v123
	s_nop 1
	v_mfma_f32_16x16x32_bf16 v[50:53], v[124:127], v[50:53], v[120:123]
	s_nop 2
	ds_read_b128 v[120:123], v146 offset:16192
	s_waitcnt lgkmcnt(0)
	v_mfma_f32_16x16x32_bf16 v[38:41], v[120:123], v[38:41], v[50:53]
	s_nop 2
	v_lshl_add_u64 v[50:51], v[154:155], 1, s[16:17]
	v_lshl_add_u64 v[50:51], v[50:51], 0, s[8:9]
	s_movk_i32 s8, 0x70
	s_waitcnt lgkmcnt(0)
	s_barrier
	v_mad_u64_u32 v[52:53], s[8:9], v145, s8, v[0:1]
	ds_read_b128 v[120:123], v52 offset:4096
	ds_read_b128 v[124:127], v52 offset:4112
	s_movk_i32 s8, 0x7fff
	s_waitcnt lgkmcnt(1)
	v_mov_b32_e32 v52, v120
	s_waitcnt lgkmcnt(0)
	v_mov_b32_e32 v53, v124
	v_mov_b32_e32 v124, v121
	v_mov_b32_e32 v120, v122
	v_mov_b32_e32 v121, v126
	v_mov_b32_e32 v126, v123
	v_add_f32_e32 v52, v52, v124
	v_add_f32_e32 v53, v53, v125
	v_add_f32_e32 v120, v120, v126
	v_add_f32_e32 v121, v121, v127
	s_nop 0
	v_add_f32_e32 v52, v52, v120
	v_add_f32_e32 v53, v53, v121
	s_nop 0
	v_add_f32_e32 v0, v52, v53
	v_fmamk_f32 v0, v0, 0x3c000000, v230
	v_rsq_f32_e32 v0, v0
	s_nop 0
	v_mul_f32_e32 v0, v46, v0
	v_mul_f32_e32 v0, v55, v0
	s_waitcnt vmcnt(15)
	v_lshlrev_b32_e32 v46, 16, v117
	v_mul_f32_e32 v0, v0, v46
	v_bfe_u32 v46, v0, 16, 1
	v_add3_u32 v46, v0, v46, s8
	v_lshl_add_u32 v0, v145, 12, v144
	v_lshl_add_u64 v[52:53], v[0:1], 1, s[0:1]
	v_cndmask_b32_e32 v53, v51, v53, vcc
	v_cndmask_b32_e32 v52, v50, v52, vcc
	global_store_short_d16_hi v[52:53], v46, off
	v_lshl_add_u32 v0, v113, 5, 0
	ds_read_b128 v[120:123], v0 offset:4096
	ds_read_b128 v[124:127], v0 offset:4112
	s_waitcnt vmcnt(15)
	v_lshlrev_b32_e32 v46, 16, v115
	v_cmp_gt_i32_e32 vcc, 32, v113
	v_mov_b32_e32 v115, v1
	s_waitcnt lgkmcnt(1)
	v_mov_b32_e32 v52, v120
	s_waitcnt lgkmcnt(0)
	v_mov_b32_e32 v53, v124
	v_mov_b32_e32 v124, v121
	v_mov_b32_e32 v120, v122
	v_mov_b32_e32 v121, v126
	v_mov_b32_e32 v126, v123
	v_add_f32_e32 v52, v52, v124
	v_add_f32_e32 v53, v53, v125
	v_add_f32_e32 v120, v120, v126
	v_add_f32_e32 v121, v121, v127
	v_mov_b32_e32 v117, v1
	v_add_f32_e32 v52, v52, v120
	v_add_f32_e32 v53, v53, v121
	s_nop 0
	v_add_f32_e32 v0, v52, v53
	v_fmamk_f32 v0, v0, 0x3c000000, v230
	v_rsq_f32_e32 v0, v0
	s_nop 0
	v_mul_f32_e32 v0, v47, v0
	v_mul_f32_e32 v0, v55, v0
	v_mul_f32_e32 v0, v0, v46
	v_bfe_u32 v46, v0, 16, 1
	v_add3_u32 v52, v0, v46, s8
	v_lshl_add_u32 v0, v113, 10, v144
	v_lshl_add_u64 v[46:47], v[0:1], 1, s[0:1]
	v_cndmask_b32_e32 v47, v51, v47, vcc
	v_cndmask_b32_e32 v46, v50, v46, vcc
	global_store_short_d16_hi v[46:47], v52, off
	v_lshl_add_u32 v0, v109, 5, 0
	ds_read_b128 v[120:123], v0 offset:4096
	ds_read_b128 v[124:127], v0 offset:4112
	v_cmp_gt_i32_e32 vcc, 32, v109
	v_mov_b32_e32 v113, v1
	s_waitcnt lgkmcnt(1)
	v_mov_b32_e32 v46, v120
	s_waitcnt lgkmcnt(0)
	v_mov_b32_e32 v47, v124
	v_mov_b32_e32 v124, v121
	v_mov_b32_e32 v52, v122
	v_mov_b32_e32 v53, v126
	v_mov_b32_e32 v126, v123
	v_add_f32_e32 v46, v46, v124
	v_add_f32_e32 v47, v47, v125
	v_add_f32_e32 v52, v52, v126
	v_add_f32_e32 v53, v53, v127
	s_nop 0
	v_add_f32_e32 v46, v46, v52
	v_add_f32_e32 v47, v47, v53
	s_nop 0
	v_add_f32_e32 v0, v46, v47
	v_fmamk_f32 v0, v0, 0x3c000000, v230
	v_rsq_f32_e32 v0, v0
	s_waitcnt vmcnt(15)
	v_lshlrev_b32_e32 v46, 16, v111
	v_mov_b32_e32 v111, v1
	v_mul_f32_e32 v0, v48, v0
	v_mul_f32_e32 v0, v55, v0
	v_mul_f32_e32 v0, v0, v46
	v_bfe_u32 v46, v0, 16, 1
	v_add3_u32 v48, v0, v46, s8
	v_lshl_add_u32 v0, v109, 10, v144
	v_lshl_add_u64 v[46:47], v[0:1], 1, s[0:1]
	v_cndmask_b32_e32 v47, v51, v47, vcc
	v_cndmask_b32_e32 v46, v50, v46, vcc
	global_store_short_d16_hi v[46:47], v48, off
	v_lshl_add_u32 v0, v105, 5, 0
	ds_read_b128 v[120:123], v0 offset:4096
	ds_read_b128 v[124:127], v0 offset:4112
	v_cmp_gt_i32_e32 vcc, 32, v105
	v_mov_b32_e32 v109, v1
	s_waitcnt lgkmcnt(1)
	v_mov_b32_e32 v46, v120
	s_waitcnt lgkmcnt(0)
	v_mov_b32_e32 v47, v124
	v_mov_b32_e32 v124, v121
	v_mov_b32_e32 v52, v122
	v_mov_b32_e32 v53, v126
	v_mov_b32_e32 v126, v123
	v_add_f32_e32 v46, v46, v124
	v_add_f32_e32 v47, v47, v125
	v_add_f32_e32 v52, v52, v126
	v_add_f32_e32 v53, v53, v127
	s_nop 0
	v_add_f32_e32 v46, v46, v52
	v_add_f32_e32 v47, v47, v53
	s_nop 0
	v_add_f32_e32 v0, v46, v47
	v_fmamk_f32 v0, v0, 0x3c000000, v230
	v_rsq_f32_e32 v0, v0
	s_waitcnt vmcnt(15)
	v_lshlrev_b32_e32 v46, 16, v107
	v_mov_b32_e32 v107, v1
	v_mul_f32_e32 v0, v49, v0
	v_mul_f32_e32 v0, v55, v0
	v_mul_f32_e32 v0, v0, v46
	v_bfe_u32 v46, v0, 16, 1
	v_add3_u32 v48, v0, v46, s8
	v_lshl_add_u32 v0, v105, 10, v144
	v_lshl_add_u64 v[46:47], v[0:1], 1, s[0:1]
	v_cndmask_b32_e32 v47, v51, v47, vcc
	v_cndmask_b32_e32 v46, v50, v46, vcc
	global_store_short_d16_hi v[46:47], v48, off
	v_lshl_add_u32 v0, v101, 5, 0
	ds_read_b128 v[46:49], v0 offset:4096
	ds_read_b128 v[120:123], v0 offset:4112
	v_cmp_gt_i32_e32 vcc, 4, v145
	v_mov_b32_e32 v105, v1
	s_waitcnt lgkmcnt(1)
	v_mov_b32_e32 v52, v46
	s_waitcnt lgkmcnt(0)
	v_mov_b32_e32 v53, v120
	v_mov_b32_e32 v120, v47
	v_add_f32_e32 v46, v52, v120
	v_add_f32_e32 v47, v53, v121
	v_mov_b32_e32 v52, v48
	v_mov_b32_e32 v53, v122
	v_mov_b32_e32 v122, v49
	v_add_f32_e32 v48, v52, v122
	v_add_f32_e32 v49, v53, v123
	s_nop 0
	v_add_f32_e32 v46, v46, v48
	v_add_f32_e32 v47, v47, v49
	s_nop 0
	v_add_f32_e32 v0, v46, v47
	v_fmamk_f32 v0, v0, 0x3c000000, v230
	v_rsq_f32_e32 v0, v0
	s_nop 0
	v_mul_f32_e32 v0, v42, v0
	v_mul_f32_e32 v0, v55, v0
	s_waitcnt vmcnt(15)
	v_lshlrev_b32_e32 v42, 16, v103
	v_mul_f32_e32 v0, v0, v42
	v_bfe_u32 v42, v0, 16, 1
	v_add3_u32 v42, v0, v42, s8
	v_lshl_add_u32 v0, v101, 10, v144
	v_lshl_add_u64 v[46:47], v[0:1], 1, s[0:1]
	v_cndmask_b32_e32 v47, v51, v47, vcc
	v_cndmask_b32_e32 v46, v50, v46, vcc
	global_store_short_d16_hi v[46:47], v42, off
	v_lshl_add_u32 v0, v97, 5, 0
	ds_read_b128 v[46:49], v0 offset:4096
	ds_read_b128 v[120:123], v0 offset:4112
	s_waitcnt vmcnt(15)
	v_lshlrev_b32_e32 v42, 16, v99
	v_mov_b32_e32 v99, v1
	v_mov_b32_e32 v101, v1
	s_waitcnt lgkmcnt(1)
	v_mov_b32_e32 v52, v46
	s_waitcnt lgkmcnt(0)
	v_mov_b32_e32 v53, v120
	v_mov_b32_e32 v120, v47
	v_add_f32_e32 v46, v52, v120
	v_add_f32_e32 v47, v53, v121
	v_mov_b32_e32 v52, v48
	v_mov_b32_e32 v53, v122
	v_mov_b32_e32 v122, v49
	v_add_f32_e32 v48, v52, v122
	v_add_f32_e32 v49, v53, v123
	v_mov_b32_e32 v103, v1
	v_add_f32_e32 v46, v46, v48
	v_add_f32_e32 v47, v47, v49
	s_nop 0
	v_add_f32_e32 v0, v46, v47
	v_fmamk_f32 v0, v0, 0x3c000000, v230
	v_rsq_f32_e32 v0, v0
	s_nop 0
	v_mul_f32_e32 v0, v43, v0
	v_mul_f32_e32 v0, v55, v0
	v_mul_f32_e32 v0, v0, v42
	v_bfe_u32 v42, v0, 16, 1
	v_add3_u32 v46, v0, v42, s8
	v_lshl_add_u32 v0, v97, 10, v144
	v_lshl_add_u64 v[42:43], v[0:1], 1, s[0:1]
	v_cndmask_b32_e32 v43, v51, v43, vcc
	v_cndmask_b32_e32 v42, v50, v42, vcc
	global_store_short_d16_hi v[42:43], v46, off
	v_lshl_add_u32 v0, v93, 5, 0
	ds_read_b128 v[46:49], v0 offset:4096
	ds_read_b128 v[120:123], v0 offset:4112
	v_mov_b32_e32 v97, v1
	s_waitcnt lgkmcnt(1)
	v_mov_b32_e32 v42, v46
	s_waitcnt lgkmcnt(0)
	v_mov_b32_e32 v43, v120
	v_mov_b32_e32 v120, v47
	v_mov_b32_e32 v46, v48
	v_mov_b32_e32 v47, v122
	v_mov_b32_e32 v122, v49
	v_add_f32_e32 v42, v42, v120
	v_add_f32_e32 v43, v43, v121
	v_add_f32_e32 v46, v46, v122
	v_add_f32_e32 v47, v47, v123
	s_nop 0
	v_add_f32_e32 v42, v42, v46
	v_add_f32_e32 v43, v43, v47
	s_nop 0
	v_add_f32_e32 v0, v42, v43
	v_fmamk_f32 v0, v0, 0x3c000000, v230
	v_rsq_f32_e32 v0, v0
	s_waitcnt vmcnt(15)
	v_lshlrev_b32_e32 v42, 16, v95
	v_mov_b32_e32 v95, v1
	v_mul_f32_e32 v0, v44, v0
	v_mul_f32_e32 v0, v55, v0
	v_mul_f32_e32 v0, v0, v42
	v_bfe_u32 v42, v0, 16, 1
	v_add3_u32 v44, v0, v42, s8
	v_lshl_add_u32 v0, v93, 10, v144
	v_lshl_add_u64 v[42:43], v[0:1], 1, s[0:1]
	v_cndmask_b32_e32 v43, v51, v43, vcc
	v_cndmask_b32_e32 v42, v50, v42, vcc
	global_store_short_d16_hi v[42:43], v44, off
	v_lshl_add_u32 v0, v89, 5, 0
	ds_read_b128 v[46:49], v0 offset:4096
	ds_read_b128 v[120:123], v0 offset:4112
	v_mov_b32_e32 v93, v1
	s_waitcnt lgkmcnt(1)
	v_mov_b32_e32 v42, v46
	s_waitcnt lgkmcnt(0)
	v_mov_b32_e32 v43, v120
	v_mov_b32_e32 v120, v47
	v_mov_b32_e32 v46, v48
	v_mov_b32_e32 v47, v122
	v_mov_b32_e32 v122, v49
	v_add_f32_e32 v42, v42, v120
	v_add_f32_e32 v43, v43, v121
	v_add_f32_e32 v46, v46, v122
	v_add_f32_e32 v47, v47, v123
	s_nop 0
	v_add_f32_e32 v42, v42, v46
	v_add_f32_e32 v43, v43, v47
	s_nop 0
	v_add_f32_e32 v0, v42, v43
	v_fmamk_f32 v0, v0, 0x3c000000, v230
	v_rsq_f32_e32 v0, v0
	s_waitcnt vmcnt(15)
	v_lshlrev_b32_e32 v42, 16, v91
	v_mov_b32_e32 v91, v1
	v_mul_f32_e32 v0, v45, v0
	v_mul_f32_e32 v0, v55, v0
	v_mul_f32_e32 v0, v0, v42
	v_bfe_u32 v42, v0, 16, 1
	v_add3_u32 v44, v0, v42, s8
	v_lshl_add_u32 v0, v89, 10, v144
	v_lshl_add_u64 v[42:43], v[0:1], 1, s[0:1]
	v_cndmask_b32_e32 v43, v51, v43, vcc
	v_cndmask_b32_e32 v42, v50, v42, vcc
	global_store_short_d16_hi v[42:43], v44, off
	v_lshl_add_u32 v0, v85, 5, 0
	ds_read_b128 v[42:45], v0 offset:4096
	ds_read_b128 v[46:49], v0 offset:4112
	v_cmp_gt_i32_e32 vcc, 0, v145
	v_mov_b32_e32 v89, v1
	s_waitcnt lgkmcnt(1)
	v_mov_b32_e32 v52, v42
	s_waitcnt lgkmcnt(0)
	v_mov_b32_e32 v53, v46
	v_mov_b32_e32 v46, v43
	v_add_f32_e32 v42, v52, v46
	v_add_f32_e32 v43, v53, v47
	v_mov_b32_e32 v46, v44
	v_mov_b32_e32 v47, v48
	v_mov_b32_e32 v48, v45
	v_add_f32_e32 v44, v46, v48
	v_add_f32_e32 v45, v47, v49
	s_nop 0
	v_add_f32_e32 v42, v42, v44
	v_add_f32_e32 v43, v43, v45
	s_nop 0
	v_add_f32_e32 v0, v42, v43
	v_fmamk_f32 v0, v0, 0x3c000000, v230
	v_rsq_f32_e32 v0, v0
	s_nop 0
	v_mul_f32_e32 v0, v14, v0
	v_mul_f32_e32 v0, v55, v0
	s_waitcnt vmcnt(15)
	v_lshlrev_b32_e32 v14, 16, v87
	v_mul_f32_e32 v0, v0, v14
	v_bfe_u32 v14, v0, 16, 1
	v_add3_u32 v14, v0, v14, s8
	v_lshl_add_u32 v0, v85, 10, v144
	v_lshl_add_u64 v[42:43], v[0:1], 1, s[0:1]
	v_cndmask_b32_e32 v43, v51, v43, vcc
	v_cndmask_b32_e32 v42, v50, v42, vcc
	global_store_short_d16_hi v[42:43], v14, off
	v_lshl_add_u32 v0, v81, 5, 0
	ds_read_b128 v[42:45], v0 offset:4096
	ds_read_b128 v[46:49], v0 offset:4112
	s_waitcnt vmcnt(15)
	v_lshlrev_b32_e32 v14, 16, v83
	v_mov_b32_e32 v83, v1
	v_mov_b32_e32 v85, v1
	s_waitcnt lgkmcnt(1)
	v_mov_b32_e32 v52, v42
	s_waitcnt lgkmcnt(0)
	v_mov_b32_e32 v53, v46
	v_mov_b32_e32 v46, v43
	v_add_f32_e32 v42, v52, v46
	v_add_f32_e32 v43, v53, v47
	v_mov_b32_e32 v46, v44
	v_mov_b32_e32 v47, v48
	v_mov_b32_e32 v48, v45
	v_add_f32_e32 v44, v46, v48
	v_add_f32_e32 v45, v47, v49
	v_mov_b32_e32 v87, v1
	v_add_f32_e32 v42, v42, v44
	v_add_f32_e32 v43, v43, v45
	s_nop 0
	v_add_f32_e32 v0, v42, v43
	v_fmamk_f32 v0, v0, 0x3c000000, v230
	v_rsq_f32_e32 v0, v0
	s_nop 0
	v_mul_f32_e32 v0, v15, v0
	v_mul_f32_e32 v0, v55, v0
	v_mul_f32_e32 v0, v0, v14
	v_bfe_u32 v14, v0, 16, 1
	v_add3_u32 v42, v0, v14, s8
	v_lshl_add_u32 v0, v81, 10, v144
	v_lshl_add_u64 v[14:15], v[0:1], 1, s[0:1]
	v_cndmask_b32_e32 v15, v51, v15, vcc
	v_cndmask_b32_e32 v14, v50, v14, vcc
	global_store_short_d16_hi v[14:15], v42, off
	v_lshl_add_u32 v0, v77, 5, 0
	ds_read_b128 v[42:45], v0 offset:4096
	ds_read_b128 v[46:49], v0 offset:4112
	v_mov_b32_e32 v81, v1
	s_waitcnt lgkmcnt(1)
	v_mov_b32_e32 v14, v42
	s_waitcnt lgkmcnt(0)
	v_mov_b32_e32 v15, v46
	v_mov_b32_e32 v46, v43
	v_mov_b32_e32 v42, v44
	v_mov_b32_e32 v43, v48
	v_mov_b32_e32 v48, v45
	v_add_f32_e32 v14, v14, v46
	v_add_f32_e32 v15, v15, v47
	v_add_f32_e32 v42, v42, v48
	v_add_f32_e32 v43, v43, v49
	s_nop 0
	v_add_f32_e32 v14, v14, v42
	v_add_f32_e32 v15, v15, v43
	s_nop 0
	v_add_f32_e32 v0, v14, v15
	v_fmamk_f32 v0, v0, 0x3c000000, v230
	v_rsq_f32_e32 v0, v0
	s_waitcnt vmcnt(15)
	v_lshlrev_b32_e32 v14, 16, v79
	v_mov_b32_e32 v79, v1
	v_mul_f32_e32 v0, v16, v0
	v_mul_f32_e32 v0, v55, v0
	v_mul_f32_e32 v0, v0, v14
	v_bfe_u32 v14, v0, 16, 1
	v_add3_u32 v16, v0, v14, s8
	v_lshl_add_u32 v0, v77, 10, v144
	v_lshl_add_u64 v[14:15], v[0:1], 1, s[0:1]
	v_cndmask_b32_e32 v15, v51, v15, vcc
	v_cndmask_b32_e32 v14, v50, v14, vcc
	global_store_short_d16_hi v[14:15], v16, off
	v_lshl_add_u32 v0, v73, 5, 0
	ds_read_b128 v[42:45], v0 offset:4096
	ds_read_b128 v[46:49], v0 offset:4112
	v_mov_b32_e32 v77, v1
	s_waitcnt lgkmcnt(1)
	v_mov_b32_e32 v14, v42
	s_waitcnt lgkmcnt(0)
	v_mov_b32_e32 v15, v46
	v_mov_b32_e32 v46, v43
	v_mov_b32_e32 v42, v44
	v_mov_b32_e32 v43, v48
	v_mov_b32_e32 v48, v45
	v_add_f32_e32 v14, v14, v46
	v_add_f32_e32 v15, v15, v47
	v_add_f32_e32 v42, v42, v48
	v_add_f32_e32 v43, v43, v49
	s_nop 0
	v_add_f32_e32 v14, v14, v42
	v_add_f32_e32 v15, v15, v43
	s_nop 0
	v_add_f32_e32 v0, v14, v15
	v_fmamk_f32 v0, v0, 0x3c000000, v230
	v_rsq_f32_e32 v0, v0
	s_waitcnt vmcnt(15)
	v_lshlrev_b32_e32 v14, 16, v75
	v_mov_b32_e32 v75, v1
	v_mul_f32_e32 v0, v17, v0
	v_mul_f32_e32 v0, v55, v0
	v_mul_f32_e32 v0, v0, v14
	v_bfe_u32 v14, v0, 16, 1
	v_add3_u32 v16, v0, v14, s8
	v_lshl_add_u32 v0, v73, 10, v144
	v_lshl_add_u64 v[14:15], v[0:1], 1, s[0:1]
	v_cndmask_b32_e32 v15, v51, v15, vcc
	v_cndmask_b32_e32 v14, v50, v14, vcc
	global_store_short_d16_hi v[14:15], v16, off
	v_lshl_add_u32 v0, v69, 5, 0
	ds_read_b128 v[14:17], v0 offset:4096
	ds_read_b128 v[42:45], v0 offset:4112
	v_cmp_gt_i32_e32 vcc, -4, v145
	v_mov_b32_e32 v73, v1
	s_waitcnt lgkmcnt(1)
	v_mov_b32_e32 v46, v14
	s_waitcnt lgkmcnt(0)
	v_mov_b32_e32 v47, v42
	v_mov_b32_e32 v42, v15
	v_add_f32_e32 v14, v46, v42
	v_add_f32_e32 v15, v47, v43
	v_mov_b32_e32 v42, v16
	v_mov_b32_e32 v43, v44
	v_mov_b32_e32 v44, v17
	v_add_f32_e32 v16, v42, v44
	v_add_f32_e32 v17, v43, v45
	s_nop 0
	v_add_f32_e32 v14, v14, v16
	v_add_f32_e32 v15, v15, v17
	s_nop 0
	v_add_f32_e32 v0, v14, v15
	v_fmamk_f32 v0, v0, 0x3c000000, v230
	v_rsq_f32_e32 v0, v0
	s_nop 0
	v_mul_f32_e32 v0, v2, v0
	v_mul_f32_e32 v0, v55, v0
	s_waitcnt vmcnt(15)
	v_lshlrev_b32_e32 v2, 16, v71
	v_mul_f32_e32 v0, v0, v2
	v_bfe_u32 v2, v0, 16, 1
	v_add3_u32 v2, v0, v2, s8
	v_lshl_add_u32 v0, v69, 10, v144
	v_lshl_add_u64 v[14:15], v[0:1], 1, s[0:1]
	v_cndmask_b32_e32 v15, v51, v15, vcc
	v_cndmask_b32_e32 v14, v50, v14, vcc
	global_store_short_d16_hi v[14:15], v2, off
	v_lshl_add_u32 v0, v65, 5, 0
	ds_read_b128 v[14:17], v0 offset:4096
	ds_read_b128 v[42:45], v0 offset:4112
	s_waitcnt vmcnt(15)
	v_lshlrev_b32_e32 v2, 16, v67
	v_mov_b32_e32 v67, v1
	v_mov_b32_e32 v69, v1
	s_waitcnt lgkmcnt(1)
	v_mov_b32_e32 v46, v14
	s_waitcnt lgkmcnt(0)
	v_mov_b32_e32 v47, v42
	v_mov_b32_e32 v42, v15
	v_add_f32_e32 v14, v46, v42
	v_add_f32_e32 v15, v47, v43
	v_mov_b32_e32 v42, v16
	v_mov_b32_e32 v43, v44
	v_mov_b32_e32 v44, v17
	v_add_f32_e32 v16, v42, v44
	v_add_f32_e32 v17, v43, v45
	v_mov_b32_e32 v71, v1
	v_add_f32_e32 v14, v14, v16
	v_add_f32_e32 v15, v15, v17
	s_nop 0
	v_add_f32_e32 v0, v14, v15
	v_fmamk_f32 v0, v0, 0x3c000000, v230
	v_rsq_f32_e32 v0, v0
	s_nop 0
	v_mul_f32_e32 v0, v3, v0
	v_mul_f32_e32 v0, v55, v0
	v_mul_f32_e32 v0, v0, v2
	v_bfe_u32 v2, v0, 16, 1
	v_add3_u32 v14, v0, v2, s8
	v_lshl_add_u32 v0, v65, 10, v144
	v_lshl_add_u64 v[2:3], v[0:1], 1, s[0:1]
	v_cndmask_b32_e32 v3, v51, v3, vcc
	v_cndmask_b32_e32 v2, v50, v2, vcc
	global_store_short_d16_hi v[2:3], v14, off
	v_lshl_add_u32 v0, v61, 5, 0
	ds_read_b128 v[14:17], v0 offset:4096
	ds_read_b128 v[42:45], v0 offset:4112
	v_mov_b32_e32 v65, v1
	s_waitcnt lgkmcnt(1)
	v_mov_b32_e32 v2, v14
	s_waitcnt lgkmcnt(0)
	v_mov_b32_e32 v3, v42
	v_mov_b32_e32 v42, v15
	v_mov_b32_e32 v14, v16
	v_mov_b32_e32 v15, v44
	v_mov_b32_e32 v44, v17
	v_add_f32_e32 v2, v2, v42
	v_add_f32_e32 v3, v3, v43
	v_add_f32_e32 v14, v14, v44
	v_add_f32_e32 v15, v15, v45
	s_nop 0
	v_add_f32_e32 v2, v2, v14
	v_add_f32_e32 v3, v3, v15
	s_nop 0
	v_add_f32_e32 v0, v2, v3
	v_fmamk_f32 v0, v0, 0x3c000000, v230
	v_rsq_f32_e32 v0, v0
	s_waitcnt vmcnt(15)
	v_lshlrev_b32_e32 v2, 16, v63
	v_mov_b32_e32 v63, v1
	v_mul_f32_e32 v0, v4, v0
	v_mul_f32_e32 v0, v55, v0
	v_mul_f32_e32 v0, v0, v2
	v_bfe_u32 v2, v0, 16, 1
	v_add3_u32 v4, v0, v2, s8
	v_lshl_add_u32 v0, v61, 10, v144
	v_lshl_add_u64 v[2:3], v[0:1], 1, s[0:1]
	v_cndmask_b32_e32 v3, v51, v3, vcc
	v_cndmask_b32_e32 v2, v50, v2, vcc
	global_store_short_d16_hi v[2:3], v4, off
	v_add_u32_e32 v0, 0, v119
	ds_read_b128 v[14:17], v0 offset:4096
	ds_read_b128 v[42:45], v0 offset:4112
	v_lshl_add_u32 v0, v59, 10, v144
	v_lshl_add_u64 v[2:3], v[0:1], 1, s[0:1]
	s_waitcnt vmcnt(15)
	v_lshlrev_b32_e32 v4, 16, v57
	s_waitcnt lgkmcnt(1)
	v_mov_b32_e32 v46, v14
	s_waitcnt lgkmcnt(0)
	v_mov_b32_e32 v47, v42
	v_mov_b32_e32 v42, v15
	v_add_f32_e32 v14, v46, v42
	v_add_f32_e32 v15, v47, v43
	v_mov_b32_e32 v42, v16
	v_mov_b32_e32 v43, v44
	v_mov_b32_e32 v44, v17
	v_add_f32_e32 v16, v42, v44
	v_add_f32_e32 v17, v43, v45
	s_add_u32 s0, s6, s2
	v_add_f32_e32 v14, v14, v16
	v_add_f32_e32 v15, v15, v17
	v_cndmask_b32_e32 v3, v51, v3, vcc
	v_add_f32_e32 v0, v14, v15
	v_fmamk_f32 v0, v0, 0x3c000000, v230
	v_rsq_f32_e32 v0, v0
	v_cndmask_b32_e32 v2, v50, v2, vcc
	s_addc_u32 s1, s7, s3
	v_mov_b32_e32 v57, v1
	v_mul_f32_e32 v0, v5, v0
	v_mul_f32_e32 v0, v55, v0
	v_mul_f32_e32 v0, v0, v4
	v_bfe_u32 v4, v0, 16, 1
	v_add3_u32 v0, v0, v4, s8
	global_store_short_d16_hi v[2:3], v0, off
	v_lshl_add_u64 v[2:3], s[0:1], 0, v[56:57]
	s_mov_b64 s[0:1], 0x49a00000
	v_mov_b32_e32 v55, v1
	v_lshl_add_u64 v[2:3], v[2:3], 0, s[0:1]
	v_lshlrev_b64 v[4:5], 9, v[54:55]
	v_lshl_add_u64 v[4:5], v[2:3], 0, v[4:5]
	v_mov_b32_e32 v59, v1
	s_waitcnt lgkmcnt(0)
	s_barrier
	global_store_dword v[4:5], v6, off
	v_lshlrev_b64 v[4:5], 9, v[58:59]
	v_lshl_add_u64 v[4:5], v[2:3], 0, v[4:5]
	v_mov_b32_e32 v61, v1
	global_store_dword v[4:5], v7, off
	v_lshlrev_b64 v[4:5], 9, v[60:61]
	v_lshl_add_u64 v[4:5], v[2:3], 0, v[4:5]
	global_store_dword v[4:5], v8, off
	v_lshlrev_b64 v[4:5], 9, v[62:63]
	v_lshl_add_u64 v[4:5], v[2:3], 0, v[4:5]
	global_store_dword v[4:5], v9, off
	v_lshlrev_b64 v[4:5], 9, v[64:65]
	v_lshl_add_u64 v[4:5], v[2:3], 0, v[4:5]
	global_store_dword v[4:5], v10, off
	v_lshlrev_b64 v[4:5], 9, v[66:67]
	v_lshl_add_u64 v[4:5], v[2:3], 0, v[4:5]
	global_store_dword v[4:5], v11, off
	v_lshlrev_b64 v[4:5], 9, v[68:69]
	v_lshl_add_u64 v[4:5], v[2:3], 0, v[4:5]
	global_store_dword v[4:5], v12, off
	v_lshlrev_b64 v[4:5], 9, v[70:71]
	v_lshl_add_u64 v[4:5], v[2:3], 0, v[4:5]
	global_store_dword v[4:5], v13, off
	v_lshlrev_b64 v[4:5], 9, v[72:73]
	v_lshl_add_u64 v[4:5], v[2:3], 0, v[4:5]
	global_store_dword v[4:5], v18, off
	v_lshlrev_b64 v[4:5], 9, v[74:75]
	v_lshl_add_u64 v[4:5], v[2:3], 0, v[4:5]
	global_store_dword v[4:5], v19, off
	v_lshlrev_b64 v[4:5], 9, v[76:77]
	v_lshl_add_u64 v[4:5], v[2:3], 0, v[4:5]
	global_store_dword v[4:5], v20, off
	v_lshlrev_b64 v[4:5], 9, v[78:79]
	v_lshl_add_u64 v[4:5], v[2:3], 0, v[4:5]
	global_store_dword v[4:5], v21, off
	v_lshlrev_b64 v[4:5], 9, v[80:81]
	v_lshl_add_u64 v[4:5], v[2:3], 0, v[4:5]
	global_store_dword v[4:5], v22, off
	v_lshlrev_b64 v[4:5], 9, v[82:83]
	v_lshl_add_u64 v[4:5], v[2:3], 0, v[4:5]
	global_store_dword v[4:5], v23, off
	v_lshlrev_b64 v[4:5], 9, v[84:85]
	v_lshl_add_u64 v[4:5], v[2:3], 0, v[4:5]
	global_store_dword v[4:5], v24, off
	v_lshlrev_b64 v[4:5], 9, v[86:87]
	v_lshl_add_u64 v[4:5], v[2:3], 0, v[4:5]
	global_store_dword v[4:5], v25, off
	v_lshlrev_b64 v[4:5], 9, v[88:89]
	v_lshl_add_u64 v[4:5], v[2:3], 0, v[4:5]
	global_store_dword v[4:5], v26, off
	v_lshlrev_b64 v[4:5], 9, v[90:91]
	v_lshl_add_u64 v[4:5], v[2:3], 0, v[4:5]
	global_store_dword v[4:5], v27, off
	v_lshlrev_b64 v[4:5], 9, v[92:93]
	v_lshl_add_u64 v[4:5], v[2:3], 0, v[4:5]
	global_store_dword v[4:5], v28, off
	v_lshlrev_b64 v[4:5], 9, v[94:95]
	v_lshl_add_u64 v[4:5], v[2:3], 0, v[4:5]
	global_store_dword v[4:5], v29, off
	v_lshlrev_b64 v[4:5], 9, v[96:97]
	v_lshl_add_u64 v[4:5], v[2:3], 0, v[4:5]
	global_store_dword v[4:5], v30, off
	v_lshlrev_b64 v[4:5], 9, v[98:99]
	v_lshl_add_u64 v[4:5], v[2:3], 0, v[4:5]
	global_store_dword v[4:5], v31, off
	v_lshlrev_b64 v[4:5], 9, v[100:101]
	v_lshl_add_u64 v[4:5], v[2:3], 0, v[4:5]
	global_store_dword v[4:5], v32, off
	v_lshlrev_b64 v[4:5], 9, v[102:103]
	v_lshl_add_u64 v[4:5], v[2:3], 0, v[4:5]
	global_store_dword v[4:5], v33, off
	v_lshlrev_b64 v[4:5], 9, v[104:105]
	v_lshl_add_u64 v[4:5], v[2:3], 0, v[4:5]
	global_store_dword v[4:5], v34, off
	v_lshlrev_b64 v[4:5], 9, v[106:107]
	v_lshl_add_u64 v[4:5], v[2:3], 0, v[4:5]
	global_store_dword v[4:5], v35, off
	v_lshlrev_b64 v[4:5], 9, v[108:109]
	v_lshl_add_u64 v[4:5], v[2:3], 0, v[4:5]
	global_store_dword v[4:5], v36, off
	v_lshlrev_b64 v[4:5], 9, v[110:111]
	v_lshl_add_u64 v[4:5], v[2:3], 0, v[4:5]
	global_store_dword v[4:5], v37, off
	v_lshlrev_b64 v[4:5], 9, v[112:113]
	v_lshl_add_u64 v[4:5], v[2:3], 0, v[4:5]
	global_store_dword v[4:5], v38, off
	v_lshlrev_b64 v[4:5], 9, v[114:115]
	v_lshl_add_u64 v[4:5], v[2:3], 0, v[4:5]
	global_store_dword v[4:5], v39, off
	v_lshlrev_b64 v[4:5], 9, v[116:117]
	v_lshl_add_u64 v[4:5], v[2:3], 0, v[4:5]
	v_mov_b32_e32 v119, v1
	global_store_dword v[4:5], v40, off
	v_lshlrev_b64 v[4:5], 9, v[118:119]
	v_lshl_add_u64 v[2:3], v[2:3], 0, v[4:5]
	global_store_dword v[2:3], v41, off

.LBB0_1820:
	v_lshl_add_u32 v130, s22, 8, v150
	v_ashrrev_i32_e32 v131, 31, v130
	s_lshl_b32 s0, s0, 8
	v_lshlrev_b64 v[130:131], 10, v[130:131]
	s_ashr_i32 s1, s0, 31
	v_lshl_add_u64 v[130:131], v[130:131], 0, s[0:1]
	v_or_b32_e32 v130, v130, v140
	v_lshlrev_b64 v[146:147], 1, v[130:131]
	v_lshl_add_u64 v[148:149], s[8:9], 0, v[146:147]
	global_load_dwordx4 v[154:157], v[148:149], off
	global_load_dwordx4 v[158:161], v[148:149], off offset:256
	v_add_co_u32_e32 v162, vcc, s75, v148
	v_lshl_add_u64 v[146:147], s[6:7], 0, v[146:147]
	s_nop 0
	v_addc_co_u32_e32 v163, vcc, 0, v149, vcc
	global_load_dwordx4 v[130:133], v[162:163], off offset:256
	s_nop 0
	global_load_dwordx4 v[162:165], v[162:163], off
	s_mov_b32 s0, 0x10000
	s_mov_b32 s1, 0x18000
	s_mov_b64 s[50:51], 0x10000
	s_waitcnt vmcnt(0)
	v_lshlrev_b32_e32 v166, 16, v154
	v_and_b32_e32 v167, 0xffff0000, v154
	v_lshlrev_b32_e32 v154, 16, v155
	v_and_b32_e32 v155, 0xffff0000, v155
	v_lshlrev_b32_e32 v168, 16, v156
	v_and_b32_e32 v169, 0xffff0000, v156
	v_lshlrev_b32_e32 v156, 16, v157
	v_and_b32_e32 v157, 0xffff0000, v157
	v_mul_f32_e32 v128, v128, v154
	v_mul_f32_e32 v129, v129, v155
	v_mul_f32_e32 v126, v126, v166
	v_mul_f32_e32 v127, v127, v167
	v_mul_f32_e32 v154, v124, v156
	v_mul_f32_e32 v155, v125, v157
	v_mul_f32_e32 v124, v122, v168
	v_mul_f32_e32 v125, v123, v169
	v_cvt_pk_bf16_f32 v122, v126, v127
	v_cvt_pk_bf16_f32 v123, v128, v129
	v_lshlrev_b32_e32 v126, 16, v160
	v_cvt_pk_bf16_f32 v124, v124, v125
	v_cvt_pk_bf16_f32 v125, v154, v155
	global_store_dwordx4 v[146:147], v[122:125], off
	v_and_b32_e32 v127, 0xffff0000, v160
	v_lshlrev_b32_e32 v128, 16, v161
	v_lshlrev_b32_e32 v122, 16, v158
	v_and_b32_e32 v123, 0xffff0000, v158
	v_and_b32_e32 v129, 0xffff0000, v161
	v_lshlrev_b32_e32 v124, 16, v159
	v_and_b32_e32 v125, 0xffff0000, v159
	v_mul_f32_e32 v118, v118, v122
	v_mul_f32_e32 v119, v119, v123
	v_mul_f32_e32 v122, v116, v128
	v_mul_f32_e32 v123, v117, v129
	v_mul_f32_e32 v116, v114, v126
	v_mul_f32_e32 v117, v115, v127
	v_mul_f32_e32 v120, v120, v124
	v_mul_f32_e32 v121, v121, v125
	v_cvt_pk_bf16_f32 v114, v118, v119
	v_add_co_u32_e32 v118, vcc, s0, v148
	v_cvt_pk_bf16_f32 v115, v120, v121
	v_cvt_pk_bf16_f32 v116, v116, v117
	v_cvt_pk_bf16_f32 v117, v122, v123
	global_store_dwordx4 v[146:147], v[114:117], off offset:256
	v_lshlrev_b32_e32 v122, 16, v162
	v_and_b32_e32 v123, 0xffff0000, v162
	v_addc_co_u32_e32 v119, vcc, 0, v149, vcc
	v_lshlrev_b32_e32 v126, 16, v164
	v_and_b32_e32 v127, 0xffff0000, v164
	v_lshlrev_b32_e32 v128, 16, v165
	v_and_b32_e32 v129, 0xffff0000, v165
	v_mul_f32_e32 v110, v110, v122
	v_mul_f32_e32 v111, v111, v123
	global_load_dwordx4 v[114:117], v[118:119], off offset:256
	s_nop 0
	global_load_dwordx4 v[118:121], v[118:119], off
	v_lshlrev_b32_e32 v124, 16, v163
	v_and_b32_e32 v125, 0xffff0000, v163
	v_mul_f32_e32 v122, v108, v128
	v_mul_f32_e32 v123, v109, v129
	v_mul_f32_e32 v108, v106, v126
	v_mul_f32_e32 v109, v107, v127
	v_cvt_pk_bf16_f32 v106, v110, v111
	v_add_co_u32_e32 v110, vcc, s75, v146
	v_mul_f32_e32 v112, v112, v124
	v_mul_f32_e32 v113, v113, v125
	s_nop 0
	v_addc_co_u32_e32 v111, vcc, 0, v147, vcc
	v_cvt_pk_bf16_f32 v107, v112, v113
	v_cvt_pk_bf16_f32 v108, v108, v109
	v_cvt_pk_bf16_f32 v109, v122, v123
	global_store_dwordx4 v[110:111], v[106:109], off
	v_lshlrev_b32_e32 v112, 16, v132
	v_and_b32_e32 v113, 0xffff0000, v132
	v_lshlrev_b32_e32 v106, 16, v130
	v_and_b32_e32 v107, 0xffff0000, v130
	v_lshlrev_b32_e32 v122, 16, v133
	v_and_b32_e32 v123, 0xffff0000, v133
	v_lshlrev_b32_e32 v108, 16, v131
	v_and_b32_e32 v109, 0xffff0000, v131
	v_mul_f32_e32 v102, v102, v106
	v_mul_f32_e32 v103, v103, v107
	v_mul_f32_e32 v106, v100, v122
	v_mul_f32_e32 v107, v101, v123
	v_mul_f32_e32 v100, v98, v112
	v_mul_f32_e32 v101, v99, v113
	v_mul_f32_e32 v104, v104, v108
	v_mul_f32_e32 v105, v105, v109
	v_cvt_pk_bf16_f32 v98, v102, v103
	v_add_co_u32_e32 v102, vcc, s1, v148
	v_cvt_pk_bf16_f32 v99, v104, v105
	v_cvt_pk_bf16_f32 v100, v100, v101
	v_cvt_pk_bf16_f32 v101, v106, v107
	global_store_dwordx4 v[110:111], v[98:101], off offset:256
	s_nop 0
	v_addc_co_u32_e32 v103, vcc, 0, v149, vcc
	global_load_dwordx4 v[98:101], v[102:103], off offset:256
	s_nop 0
	global_load_dwordx4 v[102:105], v[102:103], off
	s_waitcnt vmcnt(4)
	v_lshlrev_b32_e32 v106, 16, v118
	v_and_b32_e32 v107, 0xffff0000, v118
	v_lshlrev_b32_e32 v110, 16, v120
	v_and_b32_e32 v111, 0xffff0000, v120
	v_lshlrev_b32_e32 v112, 16, v121
	v_and_b32_e32 v113, 0xffff0000, v121
	v_mul_f32_e32 v94, v94, v106
	v_mul_f32_e32 v95, v95, v107
	v_lshlrev_b32_e32 v108, 16, v119
	v_and_b32_e32 v109, 0xffff0000, v119
	v_mul_f32_e32 v106, v92, v112
	v_mul_f32_e32 v107, v93, v113
	v_mul_f32_e32 v92, v90, v110
	v_mul_f32_e32 v93, v91, v111
	v_cvt_pk_bf16_f32 v90, v94, v95
	v_add_co_u32_e32 v94, vcc, s0, v146
	v_mul_f32_e32 v96, v96, v108
	v_mul_f32_e32 v97, v97, v109
	s_nop 0
	v_addc_co_u32_e32 v95, vcc, 0, v147, vcc
	v_cvt_pk_bf16_f32 v91, v96, v97
	v_cvt_pk_bf16_f32 v92, v92, v93
	v_cvt_pk_bf16_f32 v93, v106, v107
	global_store_dwordx4 v[94:95], v[90:93], off
	v_lshlrev_b32_e32 v96, 16, v116
	v_and_b32_e32 v97, 0xffff0000, v116
	v_lshlrev_b32_e32 v90, 16, v114
	v_and_b32_e32 v91, 0xffff0000, v114
	v_lshlrev_b32_e32 v106, 16, v117
	v_and_b32_e32 v107, 0xffff0000, v117
	v_lshlrev_b32_e32 v92, 16, v115
	v_and_b32_e32 v93, 0xffff0000, v115
	v_mul_f32_e32 v86, v86, v90
	v_mul_f32_e32 v87, v87, v91
	v_mul_f32_e32 v90, v84, v106
	v_mul_f32_e32 v91, v85, v107
	v_mul_f32_e32 v84, v82, v96
	v_mul_f32_e32 v85, v83, v97
	s_mov_b32 s0, 0x40000
	v_mul_f32_e32 v88, v88, v92
	v_mul_f32_e32 v89, v89, v93
	v_cvt_pk_bf16_f32 v82, v86, v87
	v_add_co_u32_e32 v86, vcc, s0, v148
	v_cvt_pk_bf16_f32 v83, v88, v89
	v_cvt_pk_bf16_f32 v84, v84, v85
	v_cvt_pk_bf16_f32 v85, v90, v91
	global_store_dwordx4 v[94:95], v[82:85], off offset:256
	s_waitcnt vmcnt(2)
	v_lshlrev_b32_e32 v90, 16, v102
	v_and_b32_e32 v91, 0xffff0000, v102
	v_addc_co_u32_e32 v87, vcc, 0, v149, vcc
	v_lshlrev_b32_e32 v94, 16, v104
	v_and_b32_e32 v95, 0xffff0000, v104
	v_lshlrev_b32_e32 v96, 16, v105
	v_and_b32_e32 v97, 0xffff0000, v105
	v_mul_f32_e32 v78, v78, v90
	v_mul_f32_e32 v79, v79, v91
	global_load_dwordx4 v[82:85], v[86:87], off offset:256
	s_nop 0
	global_load_dwordx4 v[86:89], v[86:87], off
	v_lshlrev_b32_e32 v92, 16, v103
	v_and_b32_e32 v93, 0xffff0000, v103
	v_mul_f32_e32 v90, v76, v96
	v_mul_f32_e32 v91, v77, v97
	v_mul_f32_e32 v76, v74, v94
	v_mul_f32_e32 v77, v75, v95
	v_cvt_pk_bf16_f32 v74, v78, v79
	v_add_co_u32_e32 v78, vcc, s1, v146
	v_mul_f32_e32 v80, v80, v92
	v_mul_f32_e32 v81, v81, v93
	s_nop 0
	v_addc_co_u32_e32 v79, vcc, 0, v147, vcc
	v_cvt_pk_bf16_f32 v75, v80, v81
	v_cvt_pk_bf16_f32 v76, v76, v77
	v_cvt_pk_bf16_f32 v77, v90, v91
	global_store_dwordx4 v[78:79], v[74:77], off
	v_lshlrev_b32_e32 v80, 16, v100
	v_and_b32_e32 v81, 0xffff0000, v100
	v_lshlrev_b32_e32 v74, 16, v98
	v_and_b32_e32 v75, 0xffff0000, v98
	v_lshlrev_b32_e32 v90, 16, v101
	v_and_b32_e32 v91, 0xffff0000, v101
	v_lshlrev_b32_e32 v76, 16, v99
	v_and_b32_e32 v77, 0xffff0000, v99
	v_mul_f32_e32 v70, v70, v74
	v_mul_f32_e32 v71, v71, v75
	v_mul_f32_e32 v74, v68, v90
	v_mul_f32_e32 v75, v69, v91
	v_mul_f32_e32 v68, v66, v80
	v_mul_f32_e32 v69, v67, v81
	s_mov_b32 s1, 0x48000
	v_mul_f32_e32 v72, v72, v76
	v_mul_f32_e32 v73, v73, v77
	v_cvt_pk_bf16_f32 v66, v70, v71
	v_add_co_u32_e32 v70, vcc, s1, v148
	v_cvt_pk_bf16_f32 v67, v72, v73
	v_cvt_pk_bf16_f32 v68, v68, v69
	v_cvt_pk_bf16_f32 v69, v74, v75
	global_store_dwordx4 v[78:79], v[66:69], off offset:256
	s_nop 0
	v_addc_co_u32_e32 v71, vcc, 0, v149, vcc
	global_load_dwordx4 v[66:69], v[70:71], off offset:256
	s_nop 0
	global_load_dwordx4 v[70:73], v[70:71], off
	s_waitcnt vmcnt(4)
	v_lshlrev_b32_e32 v74, 16, v86
	v_and_b32_e32 v75, 0xffff0000, v86
	v_lshlrev_b32_e32 v78, 16, v88
	v_and_b32_e32 v79, 0xffff0000, v88
	v_lshlrev_b32_e32 v80, 16, v89
	v_and_b32_e32 v81, 0xffff0000, v89
	v_mul_f32_e32 v62, v62, v74
	v_mul_f32_e32 v63, v63, v75
	v_lshlrev_b32_e32 v76, 16, v87
	v_and_b32_e32 v77, 0xffff0000, v87
	v_mul_f32_e32 v74, v60, v80
	v_mul_f32_e32 v75, v61, v81
	v_mul_f32_e32 v60, v58, v78
	v_mul_f32_e32 v61, v59, v79
	v_cvt_pk_bf16_f32 v58, v62, v63
	v_add_co_u32_e32 v62, vcc, s0, v146
	v_mul_f32_e32 v64, v64, v76
	v_mul_f32_e32 v65, v65, v77
	s_nop 0
	v_addc_co_u32_e32 v63, vcc, 0, v147, vcc
	v_cvt_pk_bf16_f32 v59, v64, v65
	v_cvt_pk_bf16_f32 v60, v60, v61
	v_cvt_pk_bf16_f32 v61, v74, v75
	global_store_dwordx4 v[62:63], v[58:61], off
	v_lshlrev_b32_e32 v64, 16, v84
	v_and_b32_e32 v65, 0xffff0000, v84
	v_lshlrev_b32_e32 v58, 16, v82
	v_and_b32_e32 v59, 0xffff0000, v82
	v_lshlrev_b32_e32 v74, 16, v85
	v_and_b32_e32 v75, 0xffff0000, v85
	v_lshlrev_b32_e32 v60, 16, v83
	v_and_b32_e32 v61, 0xffff0000, v83
	v_mul_f32_e32 v54, v54, v58
	v_mul_f32_e32 v55, v55, v59
	v_mul_f32_e32 v58, v52, v74
	v_mul_f32_e32 v59, v53, v75
	v_mul_f32_e32 v52, v50, v64
	v_mul_f32_e32 v53, v51, v65
	s_mov_b32 s0, 0x50000
	v_mul_f32_e32 v56, v56, v60
	v_mul_f32_e32 v57, v57, v61
	v_cvt_pk_bf16_f32 v50, v54, v55
	v_add_co_u32_e32 v54, vcc, s0, v148
	v_cvt_pk_bf16_f32 v51, v56, v57
	v_cvt_pk_bf16_f32 v52, v52, v53
	v_cvt_pk_bf16_f32 v53, v58, v59
	global_store_dwordx4 v[62:63], v[50:53], off offset:256
	s_waitcnt vmcnt(2)
	v_lshlrev_b32_e32 v58, 16, v70
	v_and_b32_e32 v59, 0xffff0000, v70
	v_addc_co_u32_e32 v55, vcc, 0, v149, vcc
	v_lshlrev_b32_e32 v62, 16, v72
	v_and_b32_e32 v63, 0xffff0000, v72
	v_lshlrev_b32_e32 v64, 16, v73
	v_and_b32_e32 v65, 0xffff0000, v73
	v_mul_f32_e32 v46, v46, v58
	v_mul_f32_e32 v47, v47, v59
	global_load_dwordx4 v[50:53], v[54:55], off offset:256
	s_nop 0
	global_load_dwordx4 v[54:57], v[54:55], off
	v_lshlrev_b32_e32 v60, 16, v71
	v_and_b32_e32 v61, 0xffff0000, v71
	v_mul_f32_e32 v58, v44, v64
	v_mul_f32_e32 v59, v45, v65
	v_mul_f32_e32 v44, v42, v62
	v_mul_f32_e32 v45, v43, v63
	v_cvt_pk_bf16_f32 v42, v46, v47
	v_add_co_u32_e32 v46, vcc, s1, v146
	v_mul_f32_e32 v48, v48, v60
	v_mul_f32_e32 v49, v49, v61
	s_nop 0
	v_addc_co_u32_e32 v47, vcc, 0, v147, vcc
	v_cvt_pk_bf16_f32 v43, v48, v49
	v_cvt_pk_bf16_f32 v44, v44, v45
	v_cvt_pk_bf16_f32 v45, v58, v59
	global_store_dwordx4 v[46:47], v[42:45], off
	v_lshlrev_b32_e32 v48, 16, v68
	v_and_b32_e32 v49, 0xffff0000, v68
	v_lshlrev_b32_e32 v42, 16, v66
	v_and_b32_e32 v43, 0xffff0000, v66
	v_lshlrev_b32_e32 v58, 16, v69
	v_and_b32_e32 v59, 0xffff0000, v69
	v_lshlrev_b32_e32 v44, 16, v67
	v_and_b32_e32 v45, 0xffff0000, v67
	v_mul_f32_e32 v38, v38, v42
	v_mul_f32_e32 v39, v39, v43
	v_mul_f32_e32 v42, v36, v58
	v_mul_f32_e32 v43, v37, v59
	v_mul_f32_e32 v36, v34, v48
	v_mul_f32_e32 v37, v35, v49
	s_mov_b32 s1, 0x58000
	v_mul_f32_e32 v40, v40, v44
	v_mul_f32_e32 v41, v41, v45
	v_cvt_pk_bf16_f32 v34, v38, v39
	v_add_co_u32_e32 v38, vcc, s1, v148
	v_cvt_pk_bf16_f32 v35, v40, v41
	v_cvt_pk_bf16_f32 v36, v36, v37
	v_cvt_pk_bf16_f32 v37, v42, v43
	global_store_dwordx4 v[46:47], v[34:37], off offset:256
	s_nop 0
	v_addc_co_u32_e32 v39, vcc, 0, v149, vcc
	global_load_dwordx4 v[34:37], v[38:39], off offset:256
	s_nop 0
	global_load_dwordx4 v[38:41], v[38:39], off
	s_waitcnt vmcnt(4)
	v_lshlrev_b32_e32 v42, 16, v54
	v_and_b32_e32 v43, 0xffff0000, v54
	v_lshlrev_b32_e32 v46, 16, v56
	v_and_b32_e32 v47, 0xffff0000, v56
	v_lshlrev_b32_e32 v48, 16, v57
	v_and_b32_e32 v49, 0xffff0000, v57
	v_mul_f32_e32 v30, v30, v42
	v_mul_f32_e32 v31, v31, v43
	v_lshlrev_b32_e32 v44, 16, v55
	v_and_b32_e32 v45, 0xffff0000, v55
	v_mul_f32_e32 v42, v28, v48
	v_mul_f32_e32 v43, v29, v49
	v_mul_f32_e32 v28, v26, v46
	v_mul_f32_e32 v29, v27, v47
	v_cvt_pk_bf16_f32 v26, v30, v31
	v_add_co_u32_e32 v30, vcc, s0, v146
	v_mul_f32_e32 v32, v32, v44
	v_mul_f32_e32 v33, v33, v45
	s_nop 0
	v_addc_co_u32_e32 v31, vcc, 0, v147, vcc
	v_cvt_pk_bf16_f32 v27, v32, v33
	v_cvt_pk_bf16_f32 v28, v28, v29
	v_cvt_pk_bf16_f32 v29, v42, v43
	global_store_dwordx4 v[30:31], v[26:29], off
	v_lshlrev_b32_e32 v32, 16, v52
	v_and_b32_e32 v33, 0xffff0000, v52
	v_lshlrev_b32_e32 v26, 16, v50
	v_and_b32_e32 v27, 0xffff0000, v50
	v_lshlrev_b32_e32 v28, 16, v51
	v_and_b32_e32 v29, 0xffff0000, v51
	v_lshlrev_b32_e32 v42, 16, v53
	v_and_b32_e32 v43, 0xffff0000, v53
	v_mul_f32_e32 v16, v16, v28
	v_mul_f32_e32 v17, v17, v29
	v_mul_f32_e32 v14, v14, v26
	v_mul_f32_e32 v15, v15, v27
	v_mul_f32_e32 v26, v12, v42
	v_mul_f32_e32 v27, v13, v43
	v_mul_f32_e32 v12, v10, v32
	v_mul_f32_e32 v13, v11, v33
	v_cvt_pk_bf16_f32 v10, v14, v15
	v_cvt_pk_bf16_f32 v11, v16, v17
	s_waitcnt vmcnt(1)
	v_lshlrev_b32_e32 v14, 16, v40
	v_cvt_pk_bf16_f32 v12, v12, v13
	v_cvt_pk_bf16_f32 v13, v26, v27
	global_store_dwordx4 v[30:31], v[10:13], off offset:256
	v_and_b32_e32 v15, 0xffff0000, v40
	v_lshlrev_b32_e32 v16, 16, v41
	v_lshlrev_b32_e32 v10, 16, v38
	v_and_b32_e32 v11, 0xffff0000, v38
	v_lshlrev_b32_e32 v12, 16, v39
	v_and_b32_e32 v13, 0xffff0000, v39
	v_mul_f32_e32 v10, v22, v10
	v_mul_f32_e32 v11, v23, v11
	v_and_b32_e32 v17, 0xffff0000, v41
	v_mul_f32_e32 v24, v24, v12
	v_mul_f32_e32 v25, v25, v13
	v_cvt_pk_bf16_f32 v12, v10, v11
	v_add_co_u32_e32 v10, vcc, s1, v146
	v_mul_f32_e32 v16, v20, v16
	v_mul_f32_e32 v17, v21, v17
	v_mul_f32_e32 v14, v18, v14
	v_mul_f32_e32 v15, v19, v15
	v_cvt_pk_bf16_f32 v13, v24, v25
	v_addc_co_u32_e32 v11, vcc, 0, v147, vcc
	v_cvt_pk_bf16_f32 v14, v14, v15
	v_cvt_pk_bf16_f32 v15, v16, v17
	global_store_dwordx4 v[10:11], v[12:15], off
	v_lshlrev_b32_e32 v16, 16, v36
	v_and_b32_e32 v17, 0xffff0000, v36
	v_lshlrev_b32_e32 v12, 16, v34
	v_and_b32_e32 v13, 0xffff0000, v34
	v_lshlrev_b32_e32 v18, 16, v37
	v_and_b32_e32 v19, 0xffff0000, v37
	v_lshlrev_b32_e32 v14, 16, v35
	v_and_b32_e32 v15, 0xffff0000, v35
	v_mul_f32_e32 v6, v6, v12
	v_mul_f32_e32 v7, v7, v13
	v_mul_f32_e32 v12, v4, v18
	v_mul_f32_e32 v13, v5, v19
	v_mul_f32_e32 v4, v2, v16
	v_mul_f32_e32 v5, v3, v17
	v_mul_f32_e32 v8, v8, v14
	v_mul_f32_e32 v9, v9, v15
	v_cvt_pk_bf16_f32 v2, v6, v7
	s_mov_b64 s[0:1], -1
	v_cvt_pk_bf16_f32 v3, v8, v9
	v_cvt_pk_bf16_f32 v4, v4, v5
	v_cvt_pk_bf16_f32 v5, v12, v13
	global_store_dwordx4 v[10:11], v[2:5], off offset:256
	s_andn2_b64 vcc, exec, s[18:19]
	s_cbranch_vccnz .LBB0_1813
	s_andn2_b64 vcc, exec, s[4:5]
	s_cbranch_vccnz .LBB0_1812
	s_barrier
	s_branch .LBB0_1812

.LBB0_1850:
	v_lshl_add_u32 v130, s24, 8, v165
	v_ashrrev_i32_e32 v131, 31, v130
	s_lshl_b32 s22, s22, 8
	v_lshlrev_b64 v[130:131], 10, v[130:131]
	s_ashr_i32 s23, s22, 31
	v_lshl_add_u64 v[130:131], v[130:131], 0, s[22:23]
	v_or_b32_e32 v130, v130, v152
	v_lshlrev_b64 v[158:159], 1, v[130:131]
	v_lshl_add_u64 v[160:161], s[6:7], 0, v[158:159]
	v_lshl_add_u64 v[162:163], s[2:3], 0, v[158:159]
	global_load_dwordx4 v[168:171], v[160:161], off
	global_load_dwordx4 v[172:175], v[162:163], off
	global_load_dwordx4 v[176:179], v[160:161], off offset:256
	global_load_dwordx4 v[180:183], v[162:163], off offset:256
	v_add_co_u32_e32 v138, vcc, s75, v162
	s_mov_b64 s[22:23], 0x8000
	s_nop 0
	v_addc_co_u32_e32 v139, vcc, 0, v163, vcc
	v_add_co_u32_e32 v142, vcc, s75, v160
	global_load_dwordx4 v[138:141], v[138:139], off
	s_nop 0
	v_addc_co_u32_e32 v143, vcc, 0, v161, vcc
	global_load_dwordx4 v[142:145], v[142:143], off
	v_lshl_add_u64 v[130:131], v[162:163], 0, s[22:23]
	v_lshl_add_u64 v[134:135], v[160:161], 0, s[22:23]
	global_load_dwordx4 v[130:133], v[130:131], off offset:256
	v_lshl_add_u64 v[158:159], s[8:9], 0, v[158:159]
	global_load_dwordx4 v[134:137], v[134:135], off offset:256
	s_mov_b32 s13, 0x10000
	s_mov_b64 s[50:51], 0x10000
	s_mov_b32 s15, 0x18000
	s_mov_b64 s[22:23], 0x18000
	s_waitcnt vmcnt(0)
	v_lshlrev_b32_e32 v184, 16, v168
	v_and_b32_e32 v185, 0xffff0000, v168
	v_lshlrev_b32_e32 v168, 16, v169
	v_and_b32_e32 v169, 0xffff0000, v169
	v_lshlrev_b32_e32 v186, 16, v170
	v_and_b32_e32 v187, 0xffff0000, v170
	v_lshlrev_b32_e32 v170, 16, v171
	v_and_b32_e32 v171, 0xffff0000, v171
	v_lshlrev_b32_e32 v188, 16, v172
	v_and_b32_e32 v189, 0xffff0000, v172
	v_lshlrev_b32_e32 v172, 16, v173
	v_and_b32_e32 v173, 0xffff0000, v173
	v_lshlrev_b32_e32 v190, 16, v174
	v_and_b32_e32 v191, 0xffff0000, v174
	v_lshlrev_b32_e32 v174, 16, v175
	v_and_b32_e32 v175, 0xffff0000, v175
	v_fma_f32 v128, v128, v168, v172
	v_fma_f32 v129, v129, v169, v173
	v_fma_f32 v126, v126, v184, v188
	v_fma_f32 v127, v127, v185, v189
	v_fma_f32 v168, v124, v170, v174
	v_fma_f32 v169, v125, v171, v175
	v_fma_f32 v124, v122, v186, v190
	v_fma_f32 v125, v123, v187, v191
	v_cvt_pk_bf16_f32 v122, v126, v127
	v_cvt_pk_bf16_f32 v123, v128, v129
	v_lshlrev_b32_e32 v126, 16, v178
	v_cvt_pk_bf16_f32 v124, v124, v125
	v_cvt_pk_bf16_f32 v125, v168, v169
	global_store_dwordx4 v[158:159], v[122:125], off
	v_and_b32_e32 v127, 0xffff0000, v178
	v_lshlrev_b32_e32 v128, 16, v179
	v_lshlrev_b32_e32 v122, 16, v176
	v_and_b32_e32 v123, 0xffff0000, v176
	v_and_b32_e32 v129, 0xffff0000, v179
	v_lshlrev_b32_e32 v168, 16, v180
	v_and_b32_e32 v169, 0xffff0000, v180
	v_lshlrev_b32_e32 v172, 16, v182
	v_and_b32_e32 v173, 0xffff0000, v182
	v_lshlrev_b32_e32 v174, 16, v183
	v_and_b32_e32 v175, 0xffff0000, v183
	v_lshlrev_b32_e32 v124, 16, v177
	v_and_b32_e32 v125, 0xffff0000, v177
	v_lshlrev_b32_e32 v170, 16, v181
	v_and_b32_e32 v171, 0xffff0000, v181
	v_fma_f32 v118, v118, v122, v168
	v_fma_f32 v119, v119, v123, v169
	v_fma_f32 v122, v116, v128, v174
	v_fma_f32 v123, v117, v129, v175
	v_fma_f32 v116, v114, v126, v172
	v_fma_f32 v117, v115, v127, v173
	v_fma_f32 v120, v120, v124, v170
	v_fma_f32 v121, v121, v125, v171
	v_cvt_pk_bf16_f32 v114, v118, v119
	v_lshlrev_b32_e32 v168, 16, v142
	v_cvt_pk_bf16_f32 v115, v120, v121
	v_cvt_pk_bf16_f32 v116, v116, v117
	v_cvt_pk_bf16_f32 v117, v122, v123
	v_add_co_u32_e32 v122, vcc, s13, v162
	global_store_dwordx4 v[158:159], v[114:117], off offset:256
	s_nop 0
	v_addc_co_u32_e32 v123, vcc, 0, v163, vcc
	v_add_co_u32_e32 v126, vcc, s13, v160
	v_and_b32_e32 v169, 0xffff0000, v142
	v_lshlrev_b32_e32 v172, 16, v138
	v_and_b32_e32 v173, 0xffff0000, v138
	v_lshl_add_u64 v[114:115], v[162:163], 0, s[50:51]
	v_lshl_add_u64 v[118:119], v[160:161], 0, s[50:51]
	v_addc_co_u32_e32 v127, vcc, 0, v161, vcc
	v_lshlrev_b32_e32 v142, 16, v143
	v_and_b32_e32 v143, 0xffff0000, v143
	v_lshlrev_b32_e32 v170, 16, v144
	v_and_b32_e32 v171, 0xffff0000, v144
	v_lshlrev_b32_e32 v144, 16, v145
	v_and_b32_e32 v145, 0xffff0000, v145
	v_lshlrev_b32_e32 v138, 16, v139
	v_and_b32_e32 v139, 0xffff0000, v139
	v_lshlrev_b32_e32 v174, 16, v140
	v_and_b32_e32 v175, 0xffff0000, v140
	v_lshlrev_b32_e32 v140, 16, v141
	v_and_b32_e32 v141, 0xffff0000, v141
	v_fma_f32 v110, v110, v168, v172
	v_fma_f32 v111, v111, v169, v173
	global_load_dwordx4 v[114:117], v[114:115], off offset:256
	v_fma_f32 v112, v112, v142, v138
	v_fma_f32 v113, v113, v143, v139
	global_load_dwordx4 v[118:121], v[118:119], off offset:256
	v_fma_f32 v138, v108, v144, v140
	v_fma_f32 v139, v109, v145, v141
	global_load_dwordx4 v[122:125], v[122:123], off
	v_fma_f32 v108, v106, v170, v174
	v_fma_f32 v109, v107, v171, v175
	global_load_dwordx4 v[126:129], v[126:127], off
	v_cvt_pk_bf16_f32 v106, v110, v111
	v_add_co_u32_e32 v110, vcc, s75, v158
	v_cvt_pk_bf16_f32 v107, v112, v113
	v_cvt_pk_bf16_f32 v108, v108, v109
	v_cvt_pk_bf16_f32 v109, v138, v139
	v_lshlrev_b32_e32 v112, 16, v136
	s_nop 0
	v_addc_co_u32_e32 v111, vcc, 0, v159, vcc
	global_store_dwordx4 v[110:111], v[106:109], off
	v_and_b32_e32 v113, 0xffff0000, v136
	v_lshlrev_b32_e32 v136, 16, v130
	v_lshlrev_b32_e32 v106, 16, v134
	v_and_b32_e32 v107, 0xffff0000, v134
	v_lshlrev_b32_e32 v108, 16, v135
	v_and_b32_e32 v109, 0xffff0000, v135
	v_lshlrev_b32_e32 v134, 16, v137
	v_and_b32_e32 v135, 0xffff0000, v137
	v_and_b32_e32 v137, 0xffff0000, v130
	v_lshlrev_b32_e32 v138, 16, v132
	v_and_b32_e32 v139, 0xffff0000, v132
	v_lshlrev_b32_e32 v132, 16, v133
	v_and_b32_e32 v133, 0xffff0000, v133
	v_lshlrev_b32_e32 v130, 16, v131
	v_and_b32_e32 v131, 0xffff0000, v131
	v_fma_f32 v102, v102, v106, v136
	v_fma_f32 v103, v103, v107, v137
	v_fma_f32 v106, v100, v134, v132
	v_fma_f32 v107, v101, v135, v133
	v_fma_f32 v100, v98, v112, v138
	v_fma_f32 v101, v99, v113, v139
	v_fma_f32 v104, v104, v108, v130
	v_fma_f32 v105, v105, v109, v131
	v_cvt_pk_bf16_f32 v98, v102, v103
	v_lshl_add_u64 v[102:103], v[160:161], 0, s[22:23]
	v_cvt_pk_bf16_f32 v99, v104, v105
	v_cvt_pk_bf16_f32 v100, v100, v101
	v_cvt_pk_bf16_f32 v101, v106, v107
	v_add_co_u32_e32 v106, vcc, s15, v162
	global_store_dwordx4 v[110:111], v[98:101], off offset:256
	s_nop 0
	v_addc_co_u32_e32 v107, vcc, 0, v163, vcc
	v_add_co_u32_e32 v110, vcc, s15, v160
	global_load_dwordx4 v[106:109], v[106:107], off
	s_nop 0
	v_addc_co_u32_e32 v111, vcc, 0, v161, vcc
	global_load_dwordx4 v[110:113], v[110:111], off
	v_lshl_add_u64 v[98:99], v[162:163], 0, s[22:23]
	global_load_dwordx4 v[98:101], v[98:99], off offset:256
	s_mov_b64 s[22:23], 0x40000
	global_load_dwordx4 v[102:105], v[102:103], off offset:256
	s_waitcnt vmcnt(7)
	v_lshlrev_b32_e32 v134, 16, v122
	v_and_b32_e32 v135, 0xffff0000, v122
	s_waitcnt vmcnt(6)
	v_lshlrev_b32_e32 v130, 16, v126
	v_and_b32_e32 v131, 0xffff0000, v126
	v_lshlrev_b32_e32 v126, 16, v127
	v_and_b32_e32 v127, 0xffff0000, v127
	v_lshlrev_b32_e32 v132, 16, v128
	v_and_b32_e32 v133, 0xffff0000, v128
	v_lshlrev_b32_e32 v128, 16, v129
	v_and_b32_e32 v129, 0xffff0000, v129
	v_lshlrev_b32_e32 v122, 16, v123
	v_and_b32_e32 v123, 0xffff0000, v123
	v_lshlrev_b32_e32 v136, 16, v124
	v_and_b32_e32 v137, 0xffff0000, v124
	v_lshlrev_b32_e32 v124, 16, v125
	v_and_b32_e32 v125, 0xffff0000, v125
	v_fma_f32 v94, v94, v130, v134
	v_fma_f32 v95, v95, v131, v135
	v_fma_f32 v96, v96, v126, v122
	v_fma_f32 v97, v97, v127, v123
	v_fma_f32 v122, v92, v128, v124
	v_fma_f32 v123, v93, v129, v125
	v_fma_f32 v92, v90, v132, v136
	v_fma_f32 v93, v91, v133, v137
	v_cvt_pk_bf16_f32 v90, v94, v95
	v_add_co_u32_e32 v94, vcc, s13, v158
	v_cvt_pk_bf16_f32 v91, v96, v97
	v_cvt_pk_bf16_f32 v92, v92, v93
	v_cvt_pk_bf16_f32 v93, v122, v123
	v_lshlrev_b32_e32 v96, 16, v120
	s_nop 0
	v_addc_co_u32_e32 v95, vcc, 0, v159, vcc
	global_store_dwordx4 v[94:95], v[90:93], off
	v_and_b32_e32 v97, 0xffff0000, v120
	v_lshlrev_b32_e32 v120, 16, v114
	v_lshlrev_b32_e32 v90, 16, v118
	v_and_b32_e32 v91, 0xffff0000, v118
	v_lshlrev_b32_e32 v92, 16, v119
	v_and_b32_e32 v93, 0xffff0000, v119
	v_lshlrev_b32_e32 v118, 16, v121
	v_and_b32_e32 v119, 0xffff0000, v121
	v_and_b32_e32 v121, 0xffff0000, v114
	v_lshlrev_b32_e32 v122, 16, v116
	v_and_b32_e32 v123, 0xffff0000, v116
	v_lshlrev_b32_e32 v116, 16, v117
	v_and_b32_e32 v117, 0xffff0000, v117
	v_lshlrev_b32_e32 v114, 16, v115
	v_and_b32_e32 v115, 0xffff0000, v115
	v_fma_f32 v86, v86, v90, v120
	v_fma_f32 v87, v87, v91, v121
	v_fma_f32 v90, v84, v118, v116
	v_fma_f32 v91, v85, v119, v117
	v_fma_f32 v84, v82, v96, v122
	v_fma_f32 v85, v83, v97, v123
	s_mov_b32 s13, 0x40000
	v_fma_f32 v88, v88, v92, v114
	v_fma_f32 v89, v89, v93, v115
	v_cvt_pk_bf16_f32 v82, v86, v87
	s_waitcnt vmcnt(3)
	v_lshlrev_b32_e32 v114, 16, v110
	v_cvt_pk_bf16_f32 v83, v88, v89
	v_cvt_pk_bf16_f32 v84, v84, v85
	v_cvt_pk_bf16_f32 v85, v90, v91
	v_add_co_u32_e32 v90, vcc, s13, v162
	global_store_dwordx4 v[94:95], v[82:85], off offset:256
	s_nop 0
	v_addc_co_u32_e32 v91, vcc, 0, v163, vcc
	v_add_co_u32_e32 v94, vcc, s13, v160
	v_and_b32_e32 v115, 0xffff0000, v110
	v_lshlrev_b32_e32 v118, 16, v106
	v_and_b32_e32 v119, 0xffff0000, v106
	v_lshl_add_u64 v[82:83], v[162:163], 0, s[22:23]
	v_lshl_add_u64 v[86:87], v[160:161], 0, s[22:23]
	v_addc_co_u32_e32 v95, vcc, 0, v161, vcc
	v_lshlrev_b32_e32 v110, 16, v111
	v_and_b32_e32 v111, 0xffff0000, v111
	v_lshlrev_b32_e32 v116, 16, v112
	v_and_b32_e32 v117, 0xffff0000, v112
	v_lshlrev_b32_e32 v112, 16, v113
	v_and_b32_e32 v113, 0xffff0000, v113
	v_lshlrev_b32_e32 v106, 16, v107
	v_and_b32_e32 v107, 0xffff0000, v107
	v_lshlrev_b32_e32 v120, 16, v108
	v_and_b32_e32 v121, 0xffff0000, v108
	v_lshlrev_b32_e32 v108, 16, v109
	v_and_b32_e32 v109, 0xffff0000, v109
	v_fma_f32 v78, v78, v114, v118
	v_fma_f32 v79, v79, v115, v119
	global_load_dwordx4 v[82:85], v[82:83], off offset:256
	v_fma_f32 v80, v80, v110, v106
	v_fma_f32 v81, v81, v111, v107
	global_load_dwordx4 v[86:89], v[86:87], off offset:256
	v_fma_f32 v106, v76, v112, v108
	v_fma_f32 v107, v77, v113, v109
	global_load_dwordx4 v[90:93], v[90:91], off
	v_fma_f32 v76, v74, v116, v120
	v_fma_f32 v77, v75, v117, v121
	global_load_dwordx4 v[94:97], v[94:95], off
	v_cvt_pk_bf16_f32 v74, v78, v79
	v_add_co_u32_e32 v78, vcc, s15, v158
	v_cvt_pk_bf16_f32 v75, v80, v81
	v_cvt_pk_bf16_f32 v76, v76, v77
	v_cvt_pk_bf16_f32 v77, v106, v107
	s_waitcnt vmcnt(6)
	v_lshlrev_b32_e32 v80, 16, v104
	v_addc_co_u32_e32 v79, vcc, 0, v159, vcc
	global_store_dwordx4 v[78:79], v[74:77], off
	v_and_b32_e32 v81, 0xffff0000, v104
	v_lshlrev_b32_e32 v104, 16, v98
	v_lshlrev_b32_e32 v74, 16, v102
	v_and_b32_e32 v75, 0xffff0000, v102
	v_lshlrev_b32_e32 v76, 16, v103
	v_and_b32_e32 v77, 0xffff0000, v103
	v_lshlrev_b32_e32 v102, 16, v105
	v_and_b32_e32 v103, 0xffff0000, v105
	v_and_b32_e32 v105, 0xffff0000, v98
	v_lshlrev_b32_e32 v106, 16, v100
	v_and_b32_e32 v107, 0xffff0000, v100
	v_lshlrev_b32_e32 v100, 16, v101
	v_and_b32_e32 v101, 0xffff0000, v101
	v_lshlrev_b32_e32 v98, 16, v99
	v_and_b32_e32 v99, 0xffff0000, v99
	v_fma_f32 v70, v70, v74, v104
	v_fma_f32 v71, v71, v75, v105
	v_fma_f32 v74, v68, v102, v100
	v_fma_f32 v75, v69, v103, v101
	v_fma_f32 v68, v66, v80, v106
	v_fma_f32 v69, v67, v81, v107
	s_mov_b32 s15, 0x48000
	v_fma_f32 v72, v72, v76, v98
	v_fma_f32 v73, v73, v77, v99
	v_cvt_pk_bf16_f32 v66, v70, v71
	s_mov_b64 s[22:23], 0x48000
	v_cvt_pk_bf16_f32 v67, v72, v73
	v_cvt_pk_bf16_f32 v68, v68, v69
	v_cvt_pk_bf16_f32 v69, v74, v75
	v_add_co_u32_e32 v74, vcc, s15, v162
	global_store_dwordx4 v[78:79], v[66:69], off offset:256
	s_nop 0
	v_addc_co_u32_e32 v75, vcc, 0, v163, vcc
	v_add_co_u32_e32 v78, vcc, s15, v160
	global_load_dwordx4 v[74:77], v[74:75], off
	s_nop 0
	v_addc_co_u32_e32 v79, vcc, 0, v161, vcc
	global_load_dwordx4 v[78:81], v[78:79], off
	v_lshl_add_u64 v[66:67], v[162:163], 0, s[22:23]
	v_lshl_add_u64 v[70:71], v[160:161], 0, s[22:23]
	global_load_dwordx4 v[66:69], v[66:67], off offset:256
	s_mov_b64 s[22:23], 0x50000
	global_load_dwordx4 v[70:73], v[70:71], off offset:256
	s_waitcnt vmcnt(7)
	v_lshlrev_b32_e32 v102, 16, v90
	v_and_b32_e32 v103, 0xffff0000, v90
	s_waitcnt vmcnt(6)
	v_lshlrev_b32_e32 v98, 16, v94
	v_and_b32_e32 v99, 0xffff0000, v94
	v_lshlrev_b32_e32 v94, 16, v95
	v_and_b32_e32 v95, 0xffff0000, v95
	v_lshlrev_b32_e32 v100, 16, v96
	v_and_b32_e32 v101, 0xffff0000, v96
	v_lshlrev_b32_e32 v96, 16, v97
	v_and_b32_e32 v97, 0xffff0000, v97
	v_lshlrev_b32_e32 v90, 16, v91
	v_and_b32_e32 v91, 0xffff0000, v91
	v_lshlrev_b32_e32 v104, 16, v92
	v_and_b32_e32 v105, 0xffff0000, v92
	v_lshlrev_b32_e32 v92, 16, v93
	v_and_b32_e32 v93, 0xffff0000, v93
	v_fma_f32 v62, v62, v98, v102
	v_fma_f32 v63, v63, v99, v103
	v_fma_f32 v64, v64, v94, v90
	v_fma_f32 v65, v65, v95, v91
	v_fma_f32 v90, v60, v96, v92
	v_fma_f32 v91, v61, v97, v93
	v_fma_f32 v60, v58, v100, v104
	v_fma_f32 v61, v59, v101, v105
	v_cvt_pk_bf16_f32 v58, v62, v63
	v_add_co_u32_e32 v62, vcc, s13, v158
	v_cvt_pk_bf16_f32 v59, v64, v65
	v_cvt_pk_bf16_f32 v60, v60, v61
	v_cvt_pk_bf16_f32 v61, v90, v91
	v_lshlrev_b32_e32 v64, 16, v88
	s_nop 0
	v_addc_co_u32_e32 v63, vcc, 0, v159, vcc
	global_store_dwordx4 v[62:63], v[58:61], off
	v_and_b32_e32 v65, 0xffff0000, v88
	v_lshlrev_b32_e32 v88, 16, v82
	v_lshlrev_b32_e32 v58, 16, v86
	v_and_b32_e32 v59, 0xffff0000, v86
	v_lshlrev_b32_e32 v60, 16, v87
	v_and_b32_e32 v61, 0xffff0000, v87
	v_lshlrev_b32_e32 v86, 16, v89
	v_and_b32_e32 v87, 0xffff0000, v89
	v_and_b32_e32 v89, 0xffff0000, v82
	v_lshlrev_b32_e32 v90, 16, v84
	v_and_b32_e32 v91, 0xffff0000, v84
	v_lshlrev_b32_e32 v84, 16, v85
	v_and_b32_e32 v85, 0xffff0000, v85
	v_lshlrev_b32_e32 v82, 16, v83
	v_and_b32_e32 v83, 0xffff0000, v83
	v_fma_f32 v54, v54, v58, v88
	v_fma_f32 v55, v55, v59, v89
	v_fma_f32 v58, v52, v86, v84
	v_fma_f32 v59, v53, v87, v85
	v_fma_f32 v52, v50, v64, v90
	v_fma_f32 v53, v51, v65, v91
	s_mov_b32 s13, 0x50000
	v_fma_f32 v56, v56, v60, v82
	v_fma_f32 v57, v57, v61, v83
	v_cvt_pk_bf16_f32 v50, v54, v55
	s_waitcnt vmcnt(3)
	v_lshlrev_b32_e32 v82, 16, v78
	v_cvt_pk_bf16_f32 v51, v56, v57
	v_cvt_pk_bf16_f32 v52, v52, v53
	v_cvt_pk_bf16_f32 v53, v58, v59
	v_add_co_u32_e32 v58, vcc, s13, v162
	global_store_dwordx4 v[62:63], v[50:53], off offset:256
	s_nop 0
	v_addc_co_u32_e32 v59, vcc, 0, v163, vcc
	v_add_co_u32_e32 v62, vcc, s13, v160
	v_and_b32_e32 v83, 0xffff0000, v78
	v_lshlrev_b32_e32 v86, 16, v74
	v_and_b32_e32 v87, 0xffff0000, v74
	v_lshl_add_u64 v[50:51], v[162:163], 0, s[22:23]
	v_lshl_add_u64 v[54:55], v[160:161], 0, s[22:23]
	v_addc_co_u32_e32 v63, vcc, 0, v161, vcc
	v_lshlrev_b32_e32 v78, 16, v79
	v_and_b32_e32 v79, 0xffff0000, v79
	v_lshlrev_b32_e32 v84, 16, v80
	v_and_b32_e32 v85, 0xffff0000, v80
	v_lshlrev_b32_e32 v80, 16, v81
	v_and_b32_e32 v81, 0xffff0000, v81
	v_lshlrev_b32_e32 v74, 16, v75
	v_and_b32_e32 v75, 0xffff0000, v75
	v_lshlrev_b32_e32 v88, 16, v76
	v_and_b32_e32 v89, 0xffff0000, v76
	v_lshlrev_b32_e32 v76, 16, v77
	v_and_b32_e32 v77, 0xffff0000, v77
	v_fma_f32 v46, v46, v82, v86
	v_fma_f32 v47, v47, v83, v87
	global_load_dwordx4 v[50:53], v[50:51], off offset:256
	v_fma_f32 v48, v48, v78, v74
	v_fma_f32 v49, v49, v79, v75
	global_load_dwordx4 v[54:57], v[54:55], off offset:256
	v_fma_f32 v74, v44, v80, v76
	v_fma_f32 v75, v45, v81, v77
	global_load_dwordx4 v[58:61], v[58:59], off
	v_fma_f32 v44, v42, v84, v88
	v_fma_f32 v45, v43, v85, v89
	global_load_dwordx4 v[62:65], v[62:63], off
	v_cvt_pk_bf16_f32 v42, v46, v47
	v_add_co_u32_e32 v46, vcc, s15, v158
	v_cvt_pk_bf16_f32 v43, v48, v49
	v_cvt_pk_bf16_f32 v44, v44, v45
	v_cvt_pk_bf16_f32 v45, v74, v75
	s_waitcnt vmcnt(6)
	v_lshlrev_b32_e32 v48, 16, v72
	v_addc_co_u32_e32 v47, vcc, 0, v159, vcc
	global_store_dwordx4 v[46:47], v[42:45], off
	v_and_b32_e32 v49, 0xffff0000, v72
	v_lshlrev_b32_e32 v72, 16, v66
	v_lshlrev_b32_e32 v42, 16, v70
	v_and_b32_e32 v43, 0xffff0000, v70
	v_lshlrev_b32_e32 v44, 16, v71
	v_and_b32_e32 v45, 0xffff0000, v71
	v_lshlrev_b32_e32 v70, 16, v73
	v_and_b32_e32 v71, 0xffff0000, v73
	v_and_b32_e32 v73, 0xffff0000, v66
	v_lshlrev_b32_e32 v74, 16, v68
	v_and_b32_e32 v75, 0xffff0000, v68
	v_lshlrev_b32_e32 v68, 16, v69
	v_and_b32_e32 v69, 0xffff0000, v69
	v_fma_f32 v38, v38, v42, v72
	v_fma_f32 v39, v39, v43, v73
	s_mov_b32 s15, 0x58000
	v_lshlrev_b32_e32 v66, 16, v67
	v_and_b32_e32 v67, 0xffff0000, v67
	v_fma_f32 v42, v36, v70, v68
	v_fma_f32 v43, v37, v71, v69
	v_fma_f32 v36, v34, v48, v74
	v_fma_f32 v37, v35, v49, v75
	v_cvt_pk_bf16_f32 v34, v38, v39
	v_add_co_u32_e32 v38, vcc, s15, v162
	v_fma_f32 v40, v40, v44, v66
	v_fma_f32 v41, v41, v45, v67
	s_mov_b64 s[22:23], 0x58000
	v_cvt_pk_bf16_f32 v35, v40, v41
	v_cvt_pk_bf16_f32 v36, v36, v37
	v_cvt_pk_bf16_f32 v37, v42, v43
	global_store_dwordx4 v[46:47], v[34:37], off offset:256
	v_addc_co_u32_e32 v39, vcc, 0, v163, vcc
	s_nop 0
	v_lshl_add_u64 v[34:35], v[162:163], 0, s[22:23]
	v_add_co_u32_e32 v46, vcc, s15, v160
	global_load_dwordx4 v[34:37], v[34:35], off offset:256
	s_nop 0
	v_addc_co_u32_e32 v47, vcc, 0, v161, vcc
	global_load_dwordx4 v[42:45], v[38:39], off
	v_lshl_add_u64 v[38:39], v[160:161], 0, s[22:23]
	global_load_dwordx4 v[38:41], v[38:39], off offset:256
	s_mov_b64 s[22:23], -1
	global_load_dwordx4 v[46:49], v[46:47], off
	s_waitcnt vmcnt(7)
	v_lshlrev_b32_e32 v70, 16, v58
	v_and_b32_e32 v71, 0xffff0000, v58
	s_waitcnt vmcnt(6)
	v_lshlrev_b32_e32 v66, 16, v62
	v_and_b32_e32 v67, 0xffff0000, v62
	v_lshlrev_b32_e32 v62, 16, v63
	v_and_b32_e32 v63, 0xffff0000, v63
	v_lshlrev_b32_e32 v68, 16, v64
	v_and_b32_e32 v69, 0xffff0000, v64
	v_lshlrev_b32_e32 v64, 16, v65
	v_and_b32_e32 v65, 0xffff0000, v65
	v_lshlrev_b32_e32 v58, 16, v59
	v_and_b32_e32 v59, 0xffff0000, v59
	v_lshlrev_b32_e32 v72, 16, v60
	v_and_b32_e32 v73, 0xffff0000, v60
	v_lshlrev_b32_e32 v60, 16, v61
	v_and_b32_e32 v61, 0xffff0000, v61
	v_fma_f32 v30, v30, v66, v70
	v_fma_f32 v31, v31, v67, v71
	v_fma_f32 v32, v32, v62, v58
	v_fma_f32 v33, v33, v63, v59
	v_fma_f32 v58, v28, v64, v60
	v_fma_f32 v59, v29, v65, v61
	v_fma_f32 v28, v26, v68, v72
	v_fma_f32 v29, v27, v69, v73
	v_cvt_pk_bf16_f32 v26, v30, v31
	v_add_co_u32_e32 v30, vcc, s13, v158
	v_cvt_pk_bf16_f32 v27, v32, v33
	v_cvt_pk_bf16_f32 v28, v28, v29
	v_cvt_pk_bf16_f32 v29, v58, v59
	v_lshlrev_b32_e32 v32, 16, v56
	s_nop 0
	v_addc_co_u32_e32 v31, vcc, 0, v159, vcc
	global_store_dwordx4 v[30:31], v[26:29], off
	v_and_b32_e32 v33, 0xffff0000, v56
	v_lshlrev_b32_e32 v56, 16, v50
	v_lshlrev_b32_e32 v26, 16, v54
	v_and_b32_e32 v27, 0xffff0000, v54
	v_lshlrev_b32_e32 v28, 16, v55
	v_and_b32_e32 v29, 0xffff0000, v55
	v_lshlrev_b32_e32 v54, 16, v57
	v_and_b32_e32 v55, 0xffff0000, v57
	v_and_b32_e32 v57, 0xffff0000, v50
	v_lshlrev_b32_e32 v50, 16, v51
	v_and_b32_e32 v51, 0xffff0000, v51
	v_lshlrev_b32_e32 v58, 16, v52
	v_and_b32_e32 v59, 0xffff0000, v52
	v_lshlrev_b32_e32 v52, 16, v53
	v_and_b32_e32 v53, 0xffff0000, v53
	v_fma_f32 v24, v24, v28, v50
	v_fma_f32 v25, v25, v29, v51
	v_fma_f32 v22, v22, v26, v56
	v_fma_f32 v23, v23, v27, v57
	v_fma_f32 v26, v20, v54, v52
	v_fma_f32 v27, v21, v55, v53
	v_fma_f32 v20, v18, v32, v58
	v_fma_f32 v21, v19, v33, v59
	v_cvt_pk_bf16_f32 v18, v22, v23
	v_cvt_pk_bf16_f32 v19, v24, v25
	s_waitcnt vmcnt(3)
	v_lshlrev_b32_e32 v32, 16, v45
	v_cvt_pk_bf16_f32 v20, v20, v21
	v_cvt_pk_bf16_f32 v21, v26, v27
	global_store_dwordx4 v[30:31], v[18:21], off offset:256
	v_lshlrev_b32_e32 v26, 16, v42
	v_and_b32_e32 v27, 0xffff0000, v42
	s_waitcnt vmcnt(2)
	v_lshlrev_b32_e32 v18, 16, v46
	v_and_b32_e32 v19, 0xffff0000, v46
	v_lshlrev_b32_e32 v22, 16, v48
	v_and_b32_e32 v23, 0xffff0000, v48
	v_lshlrev_b32_e32 v24, 16, v49
	v_and_b32_e32 v25, 0xffff0000, v49
	v_lshlrev_b32_e32 v30, 16, v44
	v_and_b32_e32 v31, 0xffff0000, v44
	v_and_b32_e32 v33, 0xffff0000, v45
	v_fma_f32 v14, v14, v18, v26
	v_fma_f32 v15, v15, v19, v27
	v_lshlrev_b32_e32 v20, 16, v47
	v_and_b32_e32 v21, 0xffff0000, v47
	v_lshlrev_b32_e32 v28, 16, v43
	v_and_b32_e32 v29, 0xffff0000, v43
	v_fma_f32 v18, v12, v24, v32
	v_fma_f32 v19, v13, v25, v33
	v_fma_f32 v12, v10, v22, v30
	v_fma_f32 v13, v11, v23, v31
	v_cvt_pk_bf16_f32 v10, v14, v15
	v_add_co_u32_e32 v14, vcc, s15, v158
	v_fma_f32 v16, v16, v20, v28
	v_fma_f32 v17, v17, v21, v29
	s_nop 0
	v_addc_co_u32_e32 v15, vcc, 0, v159, vcc
	v_cvt_pk_bf16_f32 v11, v16, v17
	v_cvt_pk_bf16_f32 v12, v12, v13
	v_cvt_pk_bf16_f32 v13, v18, v19
	global_store_dwordx4 v[14:15], v[10:13], off
	v_lshlrev_b32_e32 v16, 16, v40
	v_and_b32_e32 v17, 0xffff0000, v40
	v_lshlrev_b32_e32 v10, 16, v38
	v_and_b32_e32 v11, 0xffff0000, v38
	v_lshlrev_b32_e32 v18, 16, v41
	v_and_b32_e32 v19, 0xffff0000, v41
	v_lshlrev_b32_e32 v20, 16, v34
	v_and_b32_e32 v21, 0xffff0000, v34
	v_lshlrev_b32_e32 v24, 16, v36
	v_and_b32_e32 v25, 0xffff0000, v36
	v_lshlrev_b32_e32 v26, 16, v37
	v_and_b32_e32 v27, 0xffff0000, v37
	v_lshlrev_b32_e32 v12, 16, v39
	v_and_b32_e32 v13, 0xffff0000, v39
	v_lshlrev_b32_e32 v22, 16, v35
	v_and_b32_e32 v23, 0xffff0000, v35
	v_fma_f32 v6, v6, v10, v20
	v_fma_f32 v7, v7, v11, v21
	v_fma_f32 v10, v4, v18, v26
	v_fma_f32 v11, v5, v19, v27
	v_fma_f32 v4, v2, v16, v24
	v_fma_f32 v5, v3, v17, v25
	v_fma_f32 v8, v8, v12, v22
	v_fma_f32 v9, v9, v13, v23
	v_cvt_pk_bf16_f32 v2, v6, v7
	s_andn2_b64 vcc, exec, s[18:19]
	v_cvt_pk_bf16_f32 v3, v8, v9
	v_cvt_pk_bf16_f32 v4, v4, v5
	v_cvt_pk_bf16_f32 v5, v10, v11
	global_store_dwordx4 v[14:15], v[2:5], off offset:256
	s_cbranch_vccnz .LBB0_1843
	s_andn2_b64 vcc, exec, s[0:1]
	s_cbranch_vccnz .LBB0_1842
	s_barrier
	s_branch .LBB0_1842

.LBB0_1883:
	s_lshl_b32 s1, s0, 8
	s_add_i32 s1, s1, s41
	v_or_b32_e32 v104, s1, v169
	s_add_i32 s15, s1, 0xffff8000
	s_lshr_b32 s15, s15, 5
	v_ashrrev_i32_e32 v105, 31, v104
	v_lshl_or_b32 v100, s22, 8, v172
	s_ashr_i32 s13, s1, 13
	s_add_i32 s15, s15, 4
	v_ashrrev_i32_e32 v101, 31, v100
	v_lshlrev_b64 v[98:99], 11, v[104:105]
	v_mov_b32_e32 v0, s15
	v_mov_b32_e32 v180, s13
	v_lshl_add_u64 v[98:99], s[6:7], 0, v[98:99]
	v_lshlrev_b64 v[102:103], 1, v[100:101]
	v_cmp_gt_i32_e32 vcc, s75, v104
	v_lshl_add_u64 v[164:165], v[98:99], 0, v[102:103]
	v_mov_b64_e32 v[98:99], s[8:9]
	v_cndmask_b32_e32 v0, v0, v180, vcc
	v_mad_i64_i32 v[110:111], s[24:25], v0, s96, v[98:99]
	v_lshlrev_b64 v[100:101], 2, v[100:101]
	global_load_dwordx4 v[106:109], v[164:165], off
	v_lshl_add_u64 v[166:167], v[110:111], 0, v[100:101]
	global_load_dwordx4 v[110:113], v[166:167], off
	global_load_dwordx4 v[146:149], v[166:167], off offset:16
	s_add_i32 s13, s1, 0xffff8010
	s_lshr_b32 s13, s13, 5
	s_add_i32 s13, s13, 4
	v_mov_b32_e32 v0, s13
	s_add_i32 s13, s1, 0xffff8020
	s_lshr_b32 s13, s13, 5
	s_add_i32 s13, s13, 4
	s_add_i32 s15, s1, 0xffff8080
	s_lshr_b32 s15, s15, 5
	s_add_i32 s15, s15, 4
	s_waitcnt vmcnt(0)
	v_lshlrev_b32_e32 v174, 16, v106
	v_and_b32_e32 v175, 0xffff0000, v106
	v_lshlrev_b32_e32 v106, 16, v107
	v_and_b32_e32 v107, 0xffff0000, v107
	v_lshlrev_b32_e32 v176, 16, v108
	v_and_b32_e32 v177, 0xffff0000, v108
	v_lshlrev_b32_e32 v108, 16, v109
	v_and_b32_e32 v109, 0xffff0000, v109
	v_fma_f32 v112, v144, v112, v106
	v_fma_f32 v113, v145, v113, v107
	v_fma_f32 v106, v142, v110, v174
	v_fma_f32 v107, v143, v111, v175
	v_fma_f32 v110, v140, v148, v108
	v_fma_f32 v111, v141, v149, v109
	v_fma_f32 v108, v138, v146, v176
	v_fma_f32 v109, v139, v147, v177
	v_cvt_pk_bf16_f32 v106, v106, v107
	v_cvt_pk_bf16_f32 v107, v112, v113
	s_nop 0
	v_cvt_pk_bf16_f32 v108, v108, v109
	v_cvt_pk_bf16_f32 v109, v110, v111
	global_store_dwordx4 v[164:165], v[106:109], off
	global_load_dwordx4 v[106:109], v[164:165], off offset:256
	global_load_dwordx4 v[110:113], v[166:167], off offset:512
	global_load_dwordx4 v[146:149], v[166:167], off offset:528
	v_or_b32_e32 v166, 16, v104
	v_ashrrev_i32_e32 v167, 31, v166
	v_lshlrev_b64 v[174:175], 11, v[166:167]
	v_cmp_gt_i32_e32 vcc, s75, v166
	v_lshl_add_u64 v[174:175], s[6:7], 0, v[174:175]
	v_lshl_add_u64 v[174:175], v[174:175], 0, v[102:103]
	v_cndmask_b32_e32 v0, v0, v180, vcc
	s_waitcnt vmcnt(2)
	v_lshlrev_b32_e32 v176, 16, v106
	v_and_b32_e32 v177, 0xffff0000, v106
	v_lshlrev_b32_e32 v106, 16, v107
	v_and_b32_e32 v107, 0xffff0000, v107
	v_lshlrev_b32_e32 v178, 16, v108
	v_and_b32_e32 v179, 0xffff0000, v108
	v_lshlrev_b32_e32 v108, 16, v109
	v_and_b32_e32 v109, 0xffff0000, v109
	s_waitcnt vmcnt(1)
	v_fma_f32 v112, v136, v112, v106
	v_fma_f32 v113, v137, v113, v107
	v_fma_f32 v106, v134, v110, v176
	v_fma_f32 v107, v135, v111, v177
	s_waitcnt vmcnt(0)
	v_fma_f32 v110, v132, v148, v108
	v_fma_f32 v111, v133, v149, v109
	v_fma_f32 v108, v130, v146, v178
	v_fma_f32 v109, v131, v147, v179
	v_cvt_pk_bf16_f32 v106, v106, v107
	v_cvt_pk_bf16_f32 v107, v112, v113
	s_nop 0
	v_cvt_pk_bf16_f32 v108, v108, v109
	v_cvt_pk_bf16_f32 v109, v110, v111
	global_store_dwordx4 v[164:165], v[106:109], off offset:256
	v_mad_i64_i32 v[110:111], s[24:25], v0, s96, v[98:99]
	global_load_dwordx4 v[106:109], v[174:175], off
	v_lshl_add_u64 v[164:165], v[110:111], 0, v[100:101]
	global_load_dwordx4 v[110:113], v[164:165], off
	global_load_dwordx4 v[146:149], v[164:165], off offset:16
	v_mov_b32_e32 v0, s13
	s_add_i32 s13, s1, 0xffff8030
	s_lshr_b32 s13, s13, 5
	s_add_i32 s13, s13, 4
	s_waitcnt vmcnt(2)
	v_lshlrev_b32_e32 v166, 16, v106
	v_and_b32_e32 v167, 0xffff0000, v106
	v_lshlrev_b32_e32 v106, 16, v107
	v_and_b32_e32 v107, 0xffff0000, v107
	v_lshlrev_b32_e32 v176, 16, v108
	v_and_b32_e32 v177, 0xffff0000, v108
	v_lshlrev_b32_e32 v108, 16, v109
	v_and_b32_e32 v109, 0xffff0000, v109
	s_waitcnt vmcnt(1)
	v_fma_f32 v112, v128, v112, v106
	v_fma_f32 v113, v129, v113, v107
	v_fma_f32 v106, v126, v110, v166
	v_fma_f32 v107, v127, v111, v167
	s_waitcnt vmcnt(0)
	v_fma_f32 v110, v124, v148, v108
	v_fma_f32 v111, v125, v149, v109
	v_fma_f32 v108, v122, v146, v176
	v_fma_f32 v109, v123, v147, v177
	v_cvt_pk_bf16_f32 v106, v106, v107
	v_cvt_pk_bf16_f32 v107, v112, v113
	s_nop 0
	v_cvt_pk_bf16_f32 v108, v108, v109
	v_cvt_pk_bf16_f32 v109, v110, v111
	global_store_dwordx4 v[174:175], v[106:109], off
	global_load_dwordx4 v[106:109], v[174:175], off offset:256
	global_load_dwordx4 v[110:113], v[164:165], off offset:512
	global_load_dwordx4 v[146:149], v[164:165], off offset:528
	v_or_b32_e32 v164, 32, v104
	v_ashrrev_i32_e32 v165, 31, v164
	v_lshlrev_b64 v[166:167], 11, v[164:165]
	v_cmp_gt_i32_e32 vcc, s75, v164
	v_lshl_add_u64 v[166:167], s[6:7], 0, v[166:167]
	v_lshl_add_u64 v[166:167], v[166:167], 0, v[102:103]
	v_cndmask_b32_e32 v0, v0, v180, vcc
	s_waitcnt vmcnt(2)
	v_lshlrev_b32_e32 v176, 16, v106
	v_and_b32_e32 v177, 0xffff0000, v106
	v_lshlrev_b32_e32 v106, 16, v107
	v_and_b32_e32 v107, 0xffff0000, v107
	v_lshlrev_b32_e32 v178, 16, v108
	v_and_b32_e32 v179, 0xffff0000, v108
	v_lshlrev_b32_e32 v108, 16, v109
	v_and_b32_e32 v109, 0xffff0000, v109
	s_waitcnt vmcnt(1)
	v_fma_f32 v112, v120, v112, v106
	v_fma_f32 v113, v121, v113, v107
	v_fma_f32 v106, v118, v110, v176
	v_fma_f32 v107, v119, v111, v177
	s_waitcnt vmcnt(0)
	v_fma_f32 v110, v116, v148, v108
	v_fma_f32 v111, v117, v149, v109
	v_fma_f32 v108, v114, v146, v178
	v_fma_f32 v109, v115, v147, v179
	v_cvt_pk_bf16_f32 v106, v106, v107
	v_cvt_pk_bf16_f32 v107, v112, v113
	s_nop 0
	v_cvt_pk_bf16_f32 v108, v108, v109
	v_cvt_pk_bf16_f32 v109, v110, v111
	global_store_dwordx4 v[174:175], v[106:109], off offset:256
	v_mad_i64_i32 v[110:111], s[24:25], v0, s96, v[98:99]
	global_load_dwordx4 v[106:109], v[166:167], off
	v_lshl_add_u64 v[164:165], v[110:111], 0, v[100:101]
	global_load_dwordx4 v[110:113], v[164:165], off
	global_load_dwordx4 v[146:149], v[164:165], off offset:16
	v_mov_b32_e32 v0, s13
	s_add_i32 s13, s1, 0x80
	s_waitcnt vmcnt(2)
	v_lshlrev_b32_e32 v174, 16, v106
	v_and_b32_e32 v175, 0xffff0000, v106
	v_lshlrev_b32_e32 v106, 16, v107
	v_and_b32_e32 v107, 0xffff0000, v107
	v_lshlrev_b32_e32 v176, 16, v108
	v_and_b32_e32 v177, 0xffff0000, v108
	v_lshlrev_b32_e32 v108, 16, v109
	v_and_b32_e32 v109, 0xffff0000, v109
	s_waitcnt vmcnt(1)
	v_fma_f32 v112, v96, v112, v106
	v_fma_f32 v113, v97, v113, v107
	v_fma_f32 v106, v94, v110, v174
	v_fma_f32 v107, v95, v111, v175
	s_waitcnt vmcnt(0)
	v_fma_f32 v110, v92, v148, v108
	v_fma_f32 v111, v93, v149, v109
	v_fma_f32 v108, v90, v146, v176
	v_fma_f32 v109, v91, v147, v177
	v_cvt_pk_bf16_f32 v106, v106, v107
	v_cvt_pk_bf16_f32 v107, v112, v113
	s_nop 0
	v_cvt_pk_bf16_f32 v108, v108, v109
	v_cvt_pk_bf16_f32 v109, v110, v111
	global_store_dwordx4 v[166:167], v[106:109], off
	global_load_dwordx4 v[106:109], v[166:167], off offset:256
	global_load_dwordx4 v[110:113], v[164:165], off offset:512
	global_load_dwordx4 v[146:149], v[164:165], off offset:528
	v_or_b32_e32 v164, 48, v104
	v_ashrrev_i32_e32 v165, 31, v164
	v_lshlrev_b64 v[104:105], 11, v[164:165]
	v_lshl_add_u64 v[104:105], s[6:7], 0, v[104:105]
	v_lshl_add_u64 v[174:175], v[104:105], 0, v[102:103]
	v_cmp_gt_i32_e32 vcc, s75, v164
	s_waitcnt vmcnt(2)
	v_lshlrev_b32_e32 v104, 16, v106
	v_and_b32_e32 v105, 0xffff0000, v106
	v_lshlrev_b32_e32 v106, 16, v107
	v_and_b32_e32 v107, 0xffff0000, v107
	v_lshlrev_b32_e32 v176, 16, v108
	v_and_b32_e32 v177, 0xffff0000, v108
	v_lshlrev_b32_e32 v108, 16, v109
	v_and_b32_e32 v109, 0xffff0000, v109
	s_waitcnt vmcnt(1)
	v_fma_f32 v106, v88, v112, v106
	v_fma_f32 v107, v89, v113, v107
	v_fma_f32 v104, v86, v110, v104
	v_fma_f32 v105, v87, v111, v105
	s_waitcnt vmcnt(0)
	v_fma_f32 v108, v84, v148, v108
	v_fma_f32 v109, v85, v149, v109
	v_fma_f32 v110, v82, v146, v176
	v_fma_f32 v111, v83, v147, v177
	v_cvt_pk_bf16_f32 v104, v104, v105
	v_cvt_pk_bf16_f32 v105, v106, v107
	v_cndmask_b32_e32 v0, v0, v180, vcc
	v_cvt_pk_bf16_f32 v106, v110, v111
	v_cvt_pk_bf16_f32 v107, v108, v109
	global_store_dwordx4 v[166:167], v[104:107], off offset:256
	v_mad_i64_i32 v[108:109], s[24:25], v0, s96, v[98:99]
	global_load_dwordx4 v[104:107], v[174:175], off
	v_lshl_add_u64 v[164:165], v[108:109], 0, v[100:101]
	global_load_dwordx4 v[108:111], v[164:165], off
	global_load_dwordx4 v[146:149], v[164:165], off offset:16
	s_waitcnt vmcnt(2)
	v_lshlrev_b32_e32 v112, 16, v104
	v_and_b32_e32 v113, 0xffff0000, v104
	v_lshlrev_b32_e32 v104, 16, v105
	v_and_b32_e32 v105, 0xffff0000, v105
	v_lshlrev_b32_e32 v166, 16, v106
	v_and_b32_e32 v167, 0xffff0000, v106
	v_lshlrev_b32_e32 v106, 16, v107
	v_and_b32_e32 v107, 0xffff0000, v107
	s_waitcnt vmcnt(1)
	v_fma_f32 v110, v80, v110, v104
	v_fma_f32 v111, v81, v111, v105
	v_fma_f32 v104, v78, v108, v112
	v_fma_f32 v105, v79, v109, v113
	s_waitcnt vmcnt(0)
	v_fma_f32 v108, v76, v148, v106
	v_fma_f32 v109, v77, v149, v107
	v_fma_f32 v106, v74, v146, v166
	v_fma_f32 v107, v75, v147, v167
	v_cvt_pk_bf16_f32 v104, v104, v105
	v_cvt_pk_bf16_f32 v105, v110, v111
	s_nop 0
	v_cvt_pk_bf16_f32 v106, v106, v107
	v_cvt_pk_bf16_f32 v107, v108, v109
	global_store_dwordx4 v[174:175], v[104:107], off
	global_load_dwordx4 v[106:109], v[174:175], off offset:256
	global_load_dwordx4 v[110:113], v[164:165], off offset:512
	global_load_dwordx4 v[146:149], v[164:165], off offset:528
	v_or_b32_e32 v104, s13, v169
	s_ashr_i32 s13, s13, 13
	v_ashrrev_i32_e32 v105, 31, v104
	v_lshlrev_b64 v[164:165], 11, v[104:105]
	v_mov_b32_e32 v0, s13
	v_mov_b32_e32 v105, s15
	v_cmp_gt_i32_e32 vcc, s75, v104
	v_lshl_add_u64 v[164:165], s[6:7], 0, v[164:165]
	v_lshl_add_u64 v[164:165], v[164:165], 0, v[102:103]
	v_cndmask_b32_e32 v105, v105, v0, vcc
	s_add_i32 s13, s1, 0xffff8090
	s_lshr_b32 s13, s13, 5
	s_add_i32 s13, s13, 4
	s_waitcnt vmcnt(2)
	v_lshlrev_b32_e32 v166, 16, v106
	v_and_b32_e32 v167, 0xffff0000, v106
	v_lshlrev_b32_e32 v106, 16, v107
	v_and_b32_e32 v107, 0xffff0000, v107
	v_lshlrev_b32_e32 v176, 16, v108
	v_and_b32_e32 v177, 0xffff0000, v108
	v_lshlrev_b32_e32 v108, 16, v109
	v_and_b32_e32 v109, 0xffff0000, v109
	s_waitcnt vmcnt(1)
	v_fma_f32 v112, v72, v112, v106
	v_fma_f32 v113, v73, v113, v107
	v_fma_f32 v106, v70, v110, v166
	v_fma_f32 v107, v71, v111, v167
	s_waitcnt vmcnt(0)
	v_fma_f32 v110, v68, v148, v108
	v_fma_f32 v111, v69, v149, v109
	v_fma_f32 v108, v66, v146, v176
	v_fma_f32 v109, v67, v147, v177
	v_cvt_pk_bf16_f32 v106, v106, v107
	v_cvt_pk_bf16_f32 v107, v112, v113
	s_nop 0
	v_cvt_pk_bf16_f32 v108, v108, v109
	v_cvt_pk_bf16_f32 v109, v110, v111
	global_store_dwordx4 v[174:175], v[106:109], off offset:256
	v_mad_i64_i32 v[110:111], s[24:25], v105, s96, v[98:99]
	global_load_dwordx4 v[106:109], v[164:165], off
	v_lshl_add_u64 v[166:167], v[110:111], 0, v[100:101]
	global_load_dwordx4 v[110:113], v[166:167], off
	global_load_dwordx4 v[146:149], v[166:167], off offset:16
	v_mov_b32_e32 v105, s13
	s_add_i32 s13, s1, 0xffff80a0
	s_lshr_b32 s13, s13, 5
	s_add_i32 s13, s13, 4
	s_addk_i32 s1, 0x80b0
	s_lshr_b32 s1, s1, 5
	s_add_i32 s1, s1, 4
	s_waitcnt vmcnt(2)
	v_lshlrev_b32_e32 v174, 16, v106
	v_and_b32_e32 v175, 0xffff0000, v106
	v_lshlrev_b32_e32 v106, 16, v107
	v_and_b32_e32 v107, 0xffff0000, v107
	v_lshlrev_b32_e32 v176, 16, v108
	v_and_b32_e32 v177, 0xffff0000, v108
	v_lshlrev_b32_e32 v108, 16, v109
	v_and_b32_e32 v109, 0xffff0000, v109
	s_waitcnt vmcnt(1)
	v_fma_f32 v112, v64, v112, v106
	v_fma_f32 v113, v65, v113, v107
	v_fma_f32 v106, v62, v110, v174
	v_fma_f32 v107, v63, v111, v175
	s_waitcnt vmcnt(0)
	v_fma_f32 v110, v60, v148, v108
	v_fma_f32 v111, v61, v149, v109
	v_fma_f32 v108, v58, v146, v176
	v_fma_f32 v109, v59, v147, v177
	v_cvt_pk_bf16_f32 v106, v106, v107
	v_cvt_pk_bf16_f32 v107, v112, v113
	s_nop 0
	v_cvt_pk_bf16_f32 v108, v108, v109
	v_cvt_pk_bf16_f32 v109, v110, v111
	global_store_dwordx4 v[164:165], v[106:109], off
	global_load_dwordx4 v[106:109], v[164:165], off offset:256
	global_load_dwordx4 v[110:113], v[166:167], off offset:512
	global_load_dwordx4 v[146:149], v[166:167], off offset:528
	v_or_b32_e32 v166, 16, v104
	v_ashrrev_i32_e32 v167, 31, v166
	v_lshlrev_b64 v[174:175], 11, v[166:167]
	v_cmp_gt_i32_e32 vcc, s75, v166
	v_lshl_add_u64 v[174:175], s[6:7], 0, v[174:175]
	v_lshl_add_u64 v[174:175], v[174:175], 0, v[102:103]
	v_cndmask_b32_e32 v105, v105, v0, vcc
	s_waitcnt vmcnt(2)
	v_lshlrev_b32_e32 v176, 16, v106
	v_and_b32_e32 v177, 0xffff0000, v106
	v_lshlrev_b32_e32 v106, 16, v107
	v_and_b32_e32 v107, 0xffff0000, v107
	v_lshlrev_b32_e32 v178, 16, v108
	v_and_b32_e32 v179, 0xffff0000, v108
	v_lshlrev_b32_e32 v108, 16, v109
	v_and_b32_e32 v109, 0xffff0000, v109
	s_waitcnt vmcnt(1)
	v_fma_f32 v112, v56, v112, v106
	v_fma_f32 v113, v57, v113, v107
	v_fma_f32 v106, v54, v110, v176
	v_fma_f32 v107, v55, v111, v177
	s_waitcnt vmcnt(0)
	v_fma_f32 v110, v52, v148, v108
	v_fma_f32 v111, v53, v149, v109
	v_fma_f32 v108, v50, v146, v178
	v_fma_f32 v109, v51, v147, v179
	v_cvt_pk_bf16_f32 v106, v106, v107
	v_cvt_pk_bf16_f32 v107, v112, v113
	s_nop 0
	v_cvt_pk_bf16_f32 v108, v108, v109
	v_cvt_pk_bf16_f32 v109, v110, v111
	global_store_dwordx4 v[164:165], v[106:109], off offset:256
	v_mad_i64_i32 v[110:111], s[24:25], v105, s96, v[98:99]
	global_load_dwordx4 v[106:109], v[174:175], off
	v_lshl_add_u64 v[164:165], v[110:111], 0, v[100:101]
	global_load_dwordx4 v[110:113], v[164:165], off
	global_load_dwordx4 v[146:149], v[164:165], off offset:16
	v_mov_b32_e32 v105, s13
	s_waitcnt vmcnt(2)
	v_lshlrev_b32_e32 v166, 16, v106
	v_and_b32_e32 v167, 0xffff0000, v106
	v_lshlrev_b32_e32 v106, 16, v107
	v_and_b32_e32 v107, 0xffff0000, v107
	v_lshlrev_b32_e32 v176, 16, v108
	v_and_b32_e32 v177, 0xffff0000, v108
	v_lshlrev_b32_e32 v108, 16, v109
	v_and_b32_e32 v109, 0xffff0000, v109
	s_waitcnt vmcnt(1)
	v_fma_f32 v112, v48, v112, v106
	v_fma_f32 v113, v49, v113, v107
	v_fma_f32 v106, v46, v110, v166
	v_fma_f32 v107, v47, v111, v167
	s_waitcnt vmcnt(0)
	v_fma_f32 v110, v44, v148, v108
	v_fma_f32 v111, v45, v149, v109
	v_fma_f32 v108, v42, v146, v176
	v_fma_f32 v109, v43, v147, v177
	v_cvt_pk_bf16_f32 v106, v106, v107
	v_cvt_pk_bf16_f32 v107, v112, v113
	s_nop 0
	v_cvt_pk_bf16_f32 v108, v108, v109
	v_cvt_pk_bf16_f32 v109, v110, v111
	global_store_dwordx4 v[174:175], v[106:109], off
	global_load_dwordx4 v[106:109], v[174:175], off offset:256
	global_load_dwordx4 v[110:113], v[164:165], off offset:512
	global_load_dwordx4 v[146:149], v[164:165], off offset:528
	v_or_b32_e32 v164, 32, v104
	v_ashrrev_i32_e32 v165, 31, v164
	v_lshlrev_b64 v[166:167], 11, v[164:165]
	v_cmp_gt_i32_e32 vcc, s75, v164
	v_lshl_add_u64 v[166:167], s[6:7], 0, v[166:167]
	v_lshl_add_u64 v[166:167], v[166:167], 0, v[102:103]
	v_cndmask_b32_e32 v105, v105, v0, vcc
	s_waitcnt vmcnt(2)
	v_lshlrev_b32_e32 v176, 16, v106
	v_and_b32_e32 v177, 0xffff0000, v106
	v_lshlrev_b32_e32 v106, 16, v107
	v_and_b32_e32 v107, 0xffff0000, v107
	v_lshlrev_b32_e32 v178, 16, v108
	v_and_b32_e32 v179, 0xffff0000, v108
	v_lshlrev_b32_e32 v108, 16, v109
	v_and_b32_e32 v109, 0xffff0000, v109
	s_waitcnt vmcnt(1)
	v_fma_f32 v112, v40, v112, v106
	v_fma_f32 v113, v41, v113, v107
	v_fma_f32 v106, v38, v110, v176
	v_fma_f32 v107, v39, v111, v177
	s_waitcnt vmcnt(0)
	v_fma_f32 v110, v36, v148, v108
	v_fma_f32 v111, v37, v149, v109
	v_fma_f32 v108, v34, v146, v178
	v_fma_f32 v109, v35, v147, v179
	v_cvt_pk_bf16_f32 v106, v106, v107
	v_cvt_pk_bf16_f32 v107, v112, v113
	s_nop 0
	v_cvt_pk_bf16_f32 v108, v108, v109
	v_cvt_pk_bf16_f32 v109, v110, v111
	global_store_dwordx4 v[174:175], v[106:109], off offset:256
	v_mad_i64_i32 v[110:111], s[24:25], v105, s96, v[98:99]
	global_load_dwordx4 v[106:109], v[166:167], off
	v_lshl_add_u64 v[164:165], v[110:111], 0, v[100:101]
	global_load_dwordx4 v[110:113], v[164:165], off
	global_load_dwordx4 v[146:149], v[164:165], off offset:16
	s_waitcnt vmcnt(2)
	v_lshlrev_b32_e32 v174, 16, v106
	v_and_b32_e32 v175, 0xffff0000, v106
	v_lshlrev_b32_e32 v106, 16, v107
	v_and_b32_e32 v107, 0xffff0000, v107
	v_lshlrev_b32_e32 v176, 16, v108
	v_and_b32_e32 v177, 0xffff0000, v108
	v_lshlrev_b32_e32 v108, 16, v109
	v_and_b32_e32 v109, 0xffff0000, v109
	s_waitcnt vmcnt(1)
	v_fma_f32 v112, v32, v112, v106
	v_fma_f32 v113, v33, v113, v107
	v_fma_f32 v106, v30, v110, v174
	v_fma_f32 v107, v31, v111, v175
	s_waitcnt vmcnt(0)
	v_fma_f32 v110, v28, v148, v108
	v_fma_f32 v111, v29, v149, v109
	v_fma_f32 v108, v26, v146, v176
	v_fma_f32 v109, v27, v147, v177
	v_cvt_pk_bf16_f32 v106, v106, v107
	v_cvt_pk_bf16_f32 v107, v112, v113
	s_nop 0
	v_cvt_pk_bf16_f32 v108, v108, v109
	v_cvt_pk_bf16_f32 v109, v110, v111
	global_store_dwordx4 v[166:167], v[106:109], off
	global_load_dwordx4 v[106:109], v[166:167], off offset:256
	global_load_dwordx4 v[110:113], v[164:165], off offset:512
	global_load_dwordx4 v[146:149], v[164:165], off offset:528
	v_or_b32_e32 v164, 48, v104
	v_ashrrev_i32_e32 v165, 31, v164
	v_lshlrev_b64 v[104:105], 11, v[164:165]
	v_lshl_add_u64 v[104:105], s[6:7], 0, v[104:105]
	v_lshl_add_u64 v[174:175], v[104:105], 0, v[102:103]
	v_cmp_gt_i32_e32 vcc, s75, v164
	s_waitcnt vmcnt(2)
	v_lshlrev_b32_e32 v102, 16, v106
	v_and_b32_e32 v103, 0xffff0000, v106
	v_lshlrev_b32_e32 v104, 16, v107
	v_and_b32_e32 v105, 0xffff0000, v107
	v_lshlrev_b32_e32 v106, 16, v108
	v_and_b32_e32 v107, 0xffff0000, v108
	v_lshlrev_b32_e32 v108, 16, v109
	v_and_b32_e32 v109, 0xffff0000, v109
	s_waitcnt vmcnt(1)
	v_fma_f32 v104, v24, v112, v104
	v_fma_f32 v105, v25, v113, v105
	v_fma_f32 v102, v22, v110, v102
	v_fma_f32 v103, v23, v111, v103
	s_waitcnt vmcnt(0)
	v_fma_f32 v106, v18, v146, v106
	v_fma_f32 v107, v19, v147, v107
	v_fma_f32 v108, v20, v148, v108
	v_fma_f32 v109, v21, v149, v109
	v_cvt_pk_bf16_f32 v102, v102, v103
	v_cvt_pk_bf16_f32 v103, v104, v105
	v_cvt_pk_bf16_f32 v104, v106, v107
	v_mov_b32_e32 v106, s1
	v_cvt_pk_bf16_f32 v105, v108, v109
	global_store_dwordx4 v[166:167], v[102:105], off offset:256
	v_cndmask_b32_e32 v0, v106, v0, vcc
	global_load_dwordx4 v[102:105], v[174:175], off
	v_mad_i64_i32 v[98:99], s[24:25], v0, s96, v[98:99]
	v_lshl_add_u64 v[110:111], v[98:99], 0, v[100:101]
	global_load_dwordx4 v[98:101], v[110:111], off
	global_load_dwordx4 v[106:109], v[110:111], off offset:16
	s_waitcnt vmcnt(2)
	v_lshlrev_b32_e32 v112, 16, v102
	v_and_b32_e32 v113, 0xffff0000, v102
	v_lshlrev_b32_e32 v102, 16, v103
	v_and_b32_e32 v103, 0xffff0000, v103
	v_lshlrev_b32_e32 v146, 16, v104
	v_and_b32_e32 v147, 0xffff0000, v104
	v_lshlrev_b32_e32 v104, 16, v105
	v_and_b32_e32 v105, 0xffff0000, v105
	s_waitcnt vmcnt(1)
	v_fma_f32 v100, v16, v100, v102
	v_fma_f32 v101, v17, v101, v103
	v_fma_f32 v98, v14, v98, v112
	v_fma_f32 v99, v15, v99, v113
	s_waitcnt vmcnt(0)
	v_fma_f32 v102, v12, v108, v104
	v_fma_f32 v103, v13, v109, v105
	v_fma_f32 v104, v10, v106, v146
	v_fma_f32 v105, v11, v107, v147
	v_cvt_pk_bf16_f32 v98, v98, v99
	v_cvt_pk_bf16_f32 v99, v100, v101
	s_nop 0
	v_cvt_pk_bf16_f32 v100, v104, v105
	v_cvt_pk_bf16_f32 v101, v102, v103
	global_store_dwordx4 v[174:175], v[98:101], off
	global_load_dwordx4 v[98:101], v[174:175], off offset:256
	global_load_dwordx4 v[102:105], v[110:111], off offset:512
	global_load_dwordx4 v[106:109], v[110:111], off offset:528
	s_waitcnt vmcnt(2)
	v_lshlrev_b32_e32 v110, 16, v98
	v_and_b32_e32 v111, 0xffff0000, v98
	v_lshlrev_b32_e32 v98, 16, v99
	v_and_b32_e32 v99, 0xffff0000, v99
	v_lshlrev_b32_e32 v112, 16, v100
	v_and_b32_e32 v113, 0xffff0000, v100
	v_lshlrev_b32_e32 v100, 16, v101
	v_and_b32_e32 v101, 0xffff0000, v101
	s_waitcnt vmcnt(1)
	v_fma_f32 v104, v8, v104, v98
	v_fma_f32 v105, v9, v105, v99
	v_fma_f32 v98, v6, v102, v110
	v_fma_f32 v99, v7, v103, v111
	s_waitcnt vmcnt(0)
	v_fma_f32 v102, v4, v108, v100
	v_fma_f32 v103, v5, v109, v101
	v_fma_f32 v100, v2, v106, v112
	v_fma_f32 v101, v3, v107, v113
	v_cvt_pk_bf16_f32 v98, v98, v99
	v_cvt_pk_bf16_f32 v99, v104, v105
	s_nop 0
	v_cvt_pk_bf16_f32 v100, v100, v101
	v_cvt_pk_bf16_f32 v101, v102, v103
	global_store_dwordx4 v[174:175], v[98:101], off offset:256
	s_mov_b64 s[50:51], 0x10000
	s_cbranch_execnz .LBB0_1881
.LBB0_1884:
	s_ashr_i32 s1, s0, 5
	s_mul_hi_i32 s13, s1, 0x9000
	s_mul_i32 s1, s1, 0x9000
	s_add_u32 s1, s8, s1
	s_addc_u32 s13, s9, s13
	s_lshl_b32 s24, s22, 8
	s_ashr_i32 s25, s24, 31
	s_lshl_b64 s[26:27], s[24:25], 2
	s_add_u32 s1, s1, s26
	v_lshl_add_u32 v146, s0, 8, v170
	s_addc_u32 s13, s13, s27
	s_lshl_b32 s15, s42, 2
	v_ashrrev_i32_e32 v147, 31, v146
	s_add_u32 s26, s1, s15
	v_lshlrev_b64 v[146:147], 11, v[146:147]
	s_addc_u32 s27, s13, 0
	v_lshlrev_b32_e32 v0, 2, v158
	v_lshl_add_u64 v[146:147], s[6:7], 0, v[146:147]
	global_load_dwordx4 v[106:109], v0, s[26:27] offset:16
	global_load_dwordx4 v[110:113], v0, s[26:27]
	global_load_dwordx4 v[98:101], v0, s[26:27] offset:528
	global_load_dwordx4 v[102:105], v0, s[26:27] offset:512
	v_lshl_add_u64 v[146:147], s[24:25], 1, v[146:147]
	v_lshlrev_b32_e32 v0, 1, v158
	v_lshl_add_u64 v[146:147], v[146:147], 0, v[0:1]
	s_mov_b32 s1, s53
	s_lshl_b32 s0, s42, 1
	v_lshl_add_u64 v[164:165], v[146:147], 0, s[0:1]
	global_load_dwordx4 v[174:177], v[164:165], off
	global_load_dwordx4 v[178:181], v[164:165], off offset:256
	v_add_co_u32_e32 v166, vcc, s75, v164
	s_mov_b32 s0, 0x10000
	s_nop 0
	v_addc_co_u32_e32 v167, vcc, 0, v165, vcc
	global_load_dwordx4 v[182:185], v[166:167], off
	global_load_dwordx4 v[146:149], v[166:167], off offset:256
	s_waitcnt vmcnt(0)
	v_lshlrev_b32_e32 v186, 16, v174
	v_and_b32_e32 v187, 0xffff0000, v174
	v_lshlrev_b32_e32 v174, 16, v175
	v_and_b32_e32 v175, 0xffff0000, v175
	v_lshlrev_b32_e32 v188, 16, v176
	v_and_b32_e32 v189, 0xffff0000, v176
	v_lshlrev_b32_e32 v176, 16, v177
	v_and_b32_e32 v177, 0xffff0000, v177
	v_fma_f32 v144, v144, v112, v174
	v_fma_f32 v145, v145, v113, v175
	v_fma_f32 v142, v142, v110, v186
	v_fma_f32 v143, v143, v111, v187
	v_fma_f32 v174, v140, v108, v176
	v_fma_f32 v175, v141, v109, v177
	v_fma_f32 v140, v138, v106, v188
	v_fma_f32 v141, v139, v107, v189
	v_cvt_pk_bf16_f32 v138, v142, v143
	v_cvt_pk_bf16_f32 v139, v144, v145
	v_lshlrev_b32_e32 v142, 16, v180
	v_cvt_pk_bf16_f32 v140, v140, v141
	v_cvt_pk_bf16_f32 v141, v174, v175
	global_store_dwordx4 v[164:165], v[138:141], off
	v_and_b32_e32 v143, 0xffff0000, v180
	v_lshlrev_b32_e32 v144, 16, v181
	v_lshlrev_b32_e32 v138, 16, v178
	v_and_b32_e32 v139, 0xffff0000, v178
	v_and_b32_e32 v145, 0xffff0000, v181
	v_lshlrev_b32_e32 v140, 16, v179
	v_and_b32_e32 v141, 0xffff0000, v179
	v_fma_f32 v134, v134, v102, v138
	v_fma_f32 v135, v135, v103, v139
	v_fma_f32 v138, v132, v100, v144
	v_fma_f32 v139, v133, v101, v145
	v_fma_f32 v132, v130, v98, v142
	v_fma_f32 v133, v131, v99, v143
	v_fma_f32 v136, v136, v104, v140
	v_fma_f32 v137, v137, v105, v141
	v_cvt_pk_bf16_f32 v130, v134, v135
	v_lshlrev_b32_e32 v140, 16, v182
	v_cvt_pk_bf16_f32 v131, v136, v137
	v_cvt_pk_bf16_f32 v132, v132, v133
	v_cvt_pk_bf16_f32 v133, v138, v139
	global_store_dwordx4 v[164:165], v[130:133], off offset:256
	v_add_co_u32_e32 v138, vcc, s0, v164
	v_and_b32_e32 v141, 0xffff0000, v182
	s_nop 0
	v_addc_co_u32_e32 v139, vcc, 0, v165, vcc
	v_lshlrev_b32_e32 v142, 16, v183
	v_and_b32_e32 v143, 0xffff0000, v183
	v_lshlrev_b32_e32 v144, 16, v184
	v_and_b32_e32 v145, 0xffff0000, v184
	v_lshlrev_b32_e32 v174, 16, v185
	v_and_b32_e32 v175, 0xffff0000, v185
	global_load_dwordx4 v[134:137], v[138:139], off
	global_load_dwordx4 v[130:133], v[138:139], off offset:256
	v_fma_f32 v128, v128, v112, v142
	v_fma_f32 v129, v129, v113, v143
	v_fma_f32 v126, v126, v110, v140
	v_fma_f32 v127, v127, v111, v141
	v_fma_f32 v140, v124, v108, v174
	v_fma_f32 v141, v125, v109, v175
	v_fma_f32 v124, v122, v106, v144
	v_fma_f32 v125, v123, v107, v145
	v_cvt_pk_bf16_f32 v122, v126, v127
	v_cvt_pk_bf16_f32 v123, v128, v129
	v_lshlrev_b32_e32 v126, 16, v148
	v_cvt_pk_bf16_f32 v124, v124, v125
	v_cvt_pk_bf16_f32 v125, v140, v141
	global_store_dwordx4 v[166:167], v[122:125], off
	v_and_b32_e32 v127, 0xffff0000, v148
	v_lshlrev_b32_e32 v128, 16, v149
	v_lshlrev_b32_e32 v122, 16, v146
	v_and_b32_e32 v123, 0xffff0000, v146
	v_and_b32_e32 v129, 0xffff0000, v149
	v_lshlrev_b32_e32 v124, 16, v147
	v_and_b32_e32 v125, 0xffff0000, v147
	v_fma_f32 v118, v118, v102, v122
	v_fma_f32 v119, v119, v103, v123
	v_fma_f32 v122, v116, v100, v128
	v_fma_f32 v123, v117, v101, v129
	v_fma_f32 v116, v114, v98, v126
	v_fma_f32 v117, v115, v99, v127
	s_mov_b32 s0, 0x18000
	v_fma_f32 v120, v120, v104, v124
	v_fma_f32 v121, v121, v105, v125
	v_cvt_pk_bf16_f32 v114, v118, v119
	v_add_co_u32_e32 v118, vcc, s0, v164
	v_cvt_pk_bf16_f32 v115, v120, v121
	v_cvt_pk_bf16_f32 v116, v116, v117
	v_cvt_pk_bf16_f32 v117, v122, v123
	global_store_dwordx4 v[166:167], v[114:117], off offset:256
	s_nop 0
	v_addc_co_u32_e32 v119, vcc, 0, v165, vcc
	global_load_dwordx4 v[120:123], v[118:119], off
	global_load_dwordx4 v[114:117], v[118:119], off offset:256
	s_mov_b32 s0, 0x40000
	s_waitcnt vmcnt(5)
	v_lshlrev_b32_e32 v124, 16, v134
	v_and_b32_e32 v125, 0xffff0000, v134
	v_lshlrev_b32_e32 v126, 16, v135
	v_and_b32_e32 v127, 0xffff0000, v135
	v_lshlrev_b32_e32 v128, 16, v136
	v_and_b32_e32 v129, 0xffff0000, v136
	v_lshlrev_b32_e32 v134, 16, v137
	v_and_b32_e32 v135, 0xffff0000, v137
	v_fma_f32 v96, v96, v112, v126
	v_fma_f32 v97, v97, v113, v127
	v_fma_f32 v94, v94, v110, v124
	v_fma_f32 v95, v95, v111, v125
	v_fma_f32 v124, v92, v108, v134
	v_fma_f32 v125, v93, v109, v135
	v_fma_f32 v92, v90, v106, v128
	v_fma_f32 v93, v91, v107, v129
	v_cvt_pk_bf16_f32 v90, v94, v95
	v_cvt_pk_bf16_f32 v91, v96, v97
	s_waitcnt vmcnt(4)
	v_lshlrev_b32_e32 v94, 16, v132
	v_cvt_pk_bf16_f32 v92, v92, v93
	v_cvt_pk_bf16_f32 v93, v124, v125
	global_store_dwordx4 v[138:139], v[90:93], off
	v_and_b32_e32 v95, 0xffff0000, v132
	v_lshlrev_b32_e32 v96, 16, v133
	v_lshlrev_b32_e32 v90, 16, v130
	v_and_b32_e32 v91, 0xffff0000, v130
	v_and_b32_e32 v97, 0xffff0000, v133
	v_lshlrev_b32_e32 v92, 16, v131
	v_and_b32_e32 v93, 0xffff0000, v131
	v_fma_f32 v86, v86, v102, v90
	v_fma_f32 v87, v87, v103, v91
	v_fma_f32 v90, v84, v100, v96
	v_fma_f32 v91, v85, v101, v97
	v_fma_f32 v84, v82, v98, v94
	v_fma_f32 v85, v83, v99, v95
	v_fma_f32 v88, v88, v104, v92
	v_fma_f32 v89, v89, v105, v93
	v_cvt_pk_bf16_f32 v82, v86, v87
	s_waitcnt vmcnt(2)
	v_lshlrev_b32_e32 v92, 16, v120
	v_cvt_pk_bf16_f32 v83, v88, v89
	v_cvt_pk_bf16_f32 v84, v84, v85
	v_cvt_pk_bf16_f32 v85, v90, v91
	global_store_dwordx4 v[138:139], v[82:85], off offset:256
	v_add_co_u32_e32 v90, vcc, s0, v164
	v_and_b32_e32 v93, 0xffff0000, v120
	s_nop 0
	v_addc_co_u32_e32 v91, vcc, 0, v165, vcc
	v_lshlrev_b32_e32 v94, 16, v121
	v_and_b32_e32 v95, 0xffff0000, v121
	v_lshlrev_b32_e32 v96, 16, v122
	v_and_b32_e32 v97, 0xffff0000, v122
	v_lshlrev_b32_e32 v120, 16, v123
	v_and_b32_e32 v121, 0xffff0000, v123
	global_load_dwordx4 v[86:89], v[90:91], off
	global_load_dwordx4 v[82:85], v[90:91], off offset:256
	v_fma_f32 v80, v80, v112, v94
	v_fma_f32 v81, v81, v113, v95
	v_fma_f32 v78, v78, v110, v92
	v_fma_f32 v79, v79, v111, v93
	v_fma_f32 v92, v76, v108, v120
	v_fma_f32 v93, v77, v109, v121
	v_fma_f32 v76, v74, v106, v96
	v_fma_f32 v77, v75, v107, v97
	v_cvt_pk_bf16_f32 v74, v78, v79
	v_cvt_pk_bf16_f32 v75, v80, v81
	s_waitcnt vmcnt(4)
	v_lshlrev_b32_e32 v78, 16, v116
	v_cvt_pk_bf16_f32 v76, v76, v77
	v_cvt_pk_bf16_f32 v77, v92, v93
	global_store_dwordx4 v[118:119], v[74:77], off
	v_and_b32_e32 v79, 0xffff0000, v116
	v_lshlrev_b32_e32 v80, 16, v117
	v_lshlrev_b32_e32 v74, 16, v114
	v_and_b32_e32 v75, 0xffff0000, v114
	v_and_b32_e32 v81, 0xffff0000, v117
	v_lshlrev_b32_e32 v76, 16, v115
	v_and_b32_e32 v77, 0xffff0000, v115
	v_fma_f32 v70, v70, v102, v74
	v_fma_f32 v71, v71, v103, v75
	v_fma_f32 v74, v68, v100, v80
	v_fma_f32 v75, v69, v101, v81
	v_fma_f32 v68, v66, v98, v78
	v_fma_f32 v69, v67, v99, v79
	s_mov_b32 s0, 0x48000
	v_fma_f32 v72, v72, v104, v76
	v_fma_f32 v73, v73, v105, v77
	v_cvt_pk_bf16_f32 v66, v70, v71
	v_add_co_u32_e32 v70, vcc, s0, v164
	v_cvt_pk_bf16_f32 v67, v72, v73
	v_cvt_pk_bf16_f32 v68, v68, v69
	v_cvt_pk_bf16_f32 v69, v74, v75
	global_store_dwordx4 v[118:119], v[66:69], off offset:256
	s_nop 0
	v_addc_co_u32_e32 v71, vcc, 0, v165, vcc
	global_load_dwordx4 v[72:75], v[70:71], off
	global_load_dwordx4 v[66:69], v[70:71], off offset:256
	s_mov_b32 s0, 0x50000
	s_waitcnt vmcnt(5)
	v_lshlrev_b32_e32 v76, 16, v86
	v_and_b32_e32 v77, 0xffff0000, v86
	v_lshlrev_b32_e32 v78, 16, v87
	v_and_b32_e32 v79, 0xffff0000, v87
	v_lshlrev_b32_e32 v80, 16, v88
	v_and_b32_e32 v81, 0xffff0000, v88
	v_lshlrev_b32_e32 v86, 16, v89
	v_and_b32_e32 v87, 0xffff0000, v89
	v_fma_f32 v64, v64, v112, v78
	v_fma_f32 v65, v65, v113, v79
	v_fma_f32 v62, v62, v110, v76
	v_fma_f32 v63, v63, v111, v77
	v_fma_f32 v76, v60, v108, v86
	v_fma_f32 v77, v61, v109, v87
	v_fma_f32 v60, v58, v106, v80
	v_fma_f32 v61, v59, v107, v81
	v_cvt_pk_bf16_f32 v58, v62, v63
	v_cvt_pk_bf16_f32 v59, v64, v65
	s_waitcnt vmcnt(4)
	v_lshlrev_b32_e32 v62, 16, v84
	v_cvt_pk_bf16_f32 v60, v60, v61
	v_cvt_pk_bf16_f32 v61, v76, v77
	global_store_dwordx4 v[90:91], v[58:61], off
	v_and_b32_e32 v63, 0xffff0000, v84
	v_lshlrev_b32_e32 v64, 16, v85
	v_lshlrev_b32_e32 v58, 16, v82
	v_and_b32_e32 v59, 0xffff0000, v82
	v_and_b32_e32 v65, 0xffff0000, v85
	v_lshlrev_b32_e32 v60, 16, v83
	v_and_b32_e32 v61, 0xffff0000, v83
	v_fma_f32 v54, v54, v102, v58
	v_fma_f32 v55, v55, v103, v59
	v_fma_f32 v58, v52, v100, v64
	v_fma_f32 v59, v53, v101, v65
	v_fma_f32 v52, v50, v98, v62
	v_fma_f32 v53, v51, v99, v63
	v_fma_f32 v56, v56, v104, v60
	v_fma_f32 v57, v57, v105, v61
	v_cvt_pk_bf16_f32 v50, v54, v55
	s_waitcnt vmcnt(2)
	v_lshlrev_b32_e32 v60, 16, v72
	v_cvt_pk_bf16_f32 v51, v56, v57
	v_cvt_pk_bf16_f32 v52, v52, v53
	v_cvt_pk_bf16_f32 v53, v58, v59
	global_store_dwordx4 v[90:91], v[50:53], off offset:256
	v_add_co_u32_e32 v58, vcc, s0, v164
	v_and_b32_e32 v61, 0xffff0000, v72
	s_nop 0
	v_addc_co_u32_e32 v59, vcc, 0, v165, vcc
	v_lshlrev_b32_e32 v62, 16, v73
	v_and_b32_e32 v63, 0xffff0000, v73
	v_lshlrev_b32_e32 v64, 16, v74
	v_and_b32_e32 v65, 0xffff0000, v74
	v_lshlrev_b32_e32 v72, 16, v75
	v_and_b32_e32 v73, 0xffff0000, v75
	global_load_dwordx4 v[54:57], v[58:59], off
	global_load_dwordx4 v[50:53], v[58:59], off offset:256
	v_fma_f32 v48, v48, v112, v62
	v_fma_f32 v49, v49, v113, v63
	v_fma_f32 v46, v46, v110, v60
	v_fma_f32 v47, v47, v111, v61
	v_fma_f32 v60, v44, v108, v72
	v_fma_f32 v61, v45, v109, v73
	v_fma_f32 v44, v42, v106, v64
	v_fma_f32 v45, v43, v107, v65
	v_cvt_pk_bf16_f32 v42, v46, v47
	v_cvt_pk_bf16_f32 v43, v48, v49
	s_waitcnt vmcnt(4)
	v_lshlrev_b32_e32 v46, 16, v68
	v_cvt_pk_bf16_f32 v44, v44, v45
	v_cvt_pk_bf16_f32 v45, v60, v61
	global_store_dwordx4 v[70:71], v[42:45], off
	v_and_b32_e32 v47, 0xffff0000, v68
	v_lshlrev_b32_e32 v48, 16, v69
	v_lshlrev_b32_e32 v42, 16, v66
	v_and_b32_e32 v43, 0xffff0000, v66
	v_and_b32_e32 v49, 0xffff0000, v69
	v_lshlrev_b32_e32 v44, 16, v67
	v_and_b32_e32 v45, 0xffff0000, v67
	v_fma_f32 v38, v38, v102, v42
	v_fma_f32 v39, v39, v103, v43
	v_fma_f32 v42, v36, v100, v48
	v_fma_f32 v43, v37, v101, v49
	v_fma_f32 v36, v34, v98, v46
	v_fma_f32 v37, v35, v99, v47
	v_cvt_pk_bf16_f32 v34, v38, v39
	s_mov_b32 s0, 0x58000
	v_fma_f32 v40, v40, v104, v44
	v_fma_f32 v41, v41, v105, v45
	s_waitcnt vmcnt(2)
	v_lshlrev_b32_e32 v44, 16, v54
	v_cvt_pk_bf16_f32 v35, v40, v41
	v_cvt_pk_bf16_f32 v36, v36, v37
	v_cvt_pk_bf16_f32 v37, v42, v43
	global_store_dwordx4 v[70:71], v[34:37], off offset:256
	v_and_b32_e32 v45, 0xffff0000, v54
	v_lshlrev_b32_e32 v46, 16, v55
	v_add_co_u32_e32 v34, vcc, s0, v164
	v_and_b32_e32 v47, 0xffff0000, v55
	s_nop 0
	v_addc_co_u32_e32 v35, vcc, 0, v165, vcc
	global_load_dwordx4 v[36:39], v[34:35], off
	global_load_dwordx4 v[40:43], v[34:35], off offset:256
	v_lshlrev_b32_e32 v48, 16, v56
	v_and_b32_e32 v49, 0xffff0000, v56
	v_lshlrev_b32_e32 v54, 16, v57
	v_and_b32_e32 v55, 0xffff0000, v57
	v_fma_f32 v32, v32, v112, v46
	v_fma_f32 v33, v33, v113, v47
	v_fma_f32 v30, v30, v110, v44
	v_fma_f32 v31, v31, v111, v45
	v_fma_f32 v44, v28, v108, v54
	v_fma_f32 v45, v29, v109, v55
	v_fma_f32 v28, v26, v106, v48
	v_fma_f32 v29, v27, v107, v49
	v_cvt_pk_bf16_f32 v26, v30, v31
	v_cvt_pk_bf16_f32 v27, v32, v33
	s_waitcnt vmcnt(4)
	v_lshlrev_b32_e32 v30, 16, v52
	v_cvt_pk_bf16_f32 v28, v28, v29
	v_cvt_pk_bf16_f32 v29, v44, v45
	global_store_dwordx4 v[58:59], v[26:29], off
	v_and_b32_e32 v31, 0xffff0000, v52
	v_lshlrev_b32_e32 v32, 16, v53
	v_lshlrev_b32_e32 v26, 16, v50
	v_and_b32_e32 v27, 0xffff0000, v50
	v_and_b32_e32 v33, 0xffff0000, v53
	v_lshlrev_b32_e32 v28, 16, v51
	v_and_b32_e32 v29, 0xffff0000, v51
	v_fma_f32 v22, v22, v102, v26
	v_fma_f32 v23, v23, v103, v27
	v_fma_f32 v26, v20, v100, v32
	v_fma_f32 v27, v21, v101, v33
	v_fma_f32 v20, v18, v98, v30
	v_fma_f32 v21, v19, v99, v31
	v_fma_f32 v24, v24, v104, v28
	v_fma_f32 v25, v25, v105, v29
	v_cvt_pk_bf16_f32 v18, v22, v23
	s_waitcnt vmcnt(2)
	v_lshlrev_b32_e32 v22, 16, v38
	v_cvt_pk_bf16_f32 v19, v24, v25
	v_cvt_pk_bf16_f32 v20, v20, v21
	v_cvt_pk_bf16_f32 v21, v26, v27
	global_store_dwordx4 v[58:59], v[18:21], off offset:256
	v_and_b32_e32 v23, 0xffff0000, v38
	v_lshlrev_b32_e32 v24, 16, v39
	v_lshlrev_b32_e32 v18, 16, v36
	v_and_b32_e32 v19, 0xffff0000, v36
	v_lshlrev_b32_e32 v20, 16, v37
	v_and_b32_e32 v21, 0xffff0000, v37
	v_and_b32_e32 v25, 0xffff0000, v39
	v_fma_f32 v16, v16, v112, v20
	v_fma_f32 v17, v17, v113, v21
	v_fma_f32 v14, v14, v110, v18
	v_fma_f32 v15, v15, v111, v19
	v_fma_f32 v18, v12, v108, v24
	v_fma_f32 v19, v13, v109, v25
	v_fma_f32 v12, v10, v106, v22
	v_fma_f32 v13, v11, v107, v23
	v_cvt_pk_bf16_f32 v10, v14, v15
	v_cvt_pk_bf16_f32 v11, v16, v17
	s_waitcnt vmcnt(2)
	v_lshlrev_b32_e32 v14, 16, v42
	v_cvt_pk_bf16_f32 v12, v12, v13
	v_cvt_pk_bf16_f32 v13, v18, v19
	global_store_dwordx4 v[34:35], v[10:13], off
	v_and_b32_e32 v15, 0xffff0000, v42
	v_lshlrev_b32_e32 v16, 16, v43
	v_lshlrev_b32_e32 v10, 16, v40
	v_and_b32_e32 v11, 0xffff0000, v40
	v_and_b32_e32 v17, 0xffff0000, v43
	v_lshlrev_b32_e32 v12, 16, v41
	v_and_b32_e32 v13, 0xffff0000, v41
	v_fma_f32 v6, v6, v102, v10
	v_fma_f32 v7, v7, v103, v11
	v_fma_f32 v10, v4, v100, v16
	v_fma_f32 v11, v5, v101, v17
	v_fma_f32 v4, v2, v98, v14
	v_fma_f32 v5, v3, v99, v15
	v_fma_f32 v8, v8, v104, v12
	v_fma_f32 v9, v9, v105, v13
	v_cvt_pk_bf16_f32 v2, v6, v7
	s_nop 0
	v_cvt_pk_bf16_f32 v3, v8, v9
	v_cvt_pk_bf16_f32 v4, v4, v5
	v_cvt_pk_bf16_f32 v5, v10, v11
	global_store_dwordx4 v[34:35], v[2:5], off offset:256
	s_andn2_b64 vcc, exec, s[18:19]
	s_mov_b64 s[0:1], -1
	s_cbranch_vccnz .LBB0_1873

.LBB0_1902:
	s_or_b64 exec, exec, s[0:1]
	s_barrier
	s_getreg_b32 s0, hwreg(HW_REG_HW_ID, 0, 7)
	s_and_b32 s0, s0, 63
	s_lshl_b32 s0, s0, 2
	s_add_i32 s0, s0, 0x22240
	v_mov_b32_e32 v0, s0
	s_mov_b32 s0, s72
	ds_read_b32 v0, v0
	v_mbcnt_lo_u32_b32 v2, -1, 0
	v_mbcnt_hi_u32_b32 v2, -1, v2
	s_mov_b64 s[0:1], s[70:71]
	s_mov_b64 s[2:3], s[70:71]
	s_load_dwordx2 s[0:1], s[0:1], 0xd0
	s_load_dwordx2 s[2:3], s[2:3], 0xa8
	v_readlane_b32 s8, v254, 5
	v_readlane_b32 s9, v254, 6
	v_readlane_b32 s7, v253, 60
	s_waitcnt lgkmcnt(0)
	v_lshl_or_b32 v38, v0, 6, v2
	s_add_u32 s8, s2, s8
	s_addc_u32 s9, s3, s9
	s_mov_b64 s[2:3], s[70:71]
	s_load_dwordx2 s[2:3], s[2:3], 0xd0
	v_readlane_b32 s10, v253, 61
	v_readfirstlane_b32 s6, v38
	v_and_b32_e32 v0, 63, v2
	v_lshlrev_b32_e32 v36, 4, v0
	s_waitcnt lgkmcnt(0)
	s_add_u32 s7, s2, s7
	s_addc_u32 s10, s3, s10
	s_ashr_i32 s6, s6, 4
	s_lshl_b32 s11, s62, 5
	s_and_b32 s6, s6, -4
	s_add_i32 s6, s6, s11
	s_add_i32 s12, s6, 0x8000
	s_lshr_b32 s13, s6, 5
	s_ashr_i32 s11, s12, 13
	s_add_i32 s14, s13, 4
	s_cmp_lt_i32 s6, 0
	s_cselect_b32 s6, s11, s14
	s_mul_hi_i32 s11, s6, 0x9000
	s_mul_i32 s6, s6, 0x9000
	s_add_u32 s14, s7, s6
	s_addc_u32 s11, s10, s11
	s_add_u32 s6, s14, 0x6000
	s_mov_b64 s[2:3], s[70:71]
	s_addc_u32 s7, s11, 0
	s_add_u32 s10, s14, 0x7000
	s_load_dwordx2 s[2:3], s[2:3], 0xd0
	s_addc_u32 s11, s11, 0
	global_load_dwordx4 v[6:9], v36, s[8:9]
	global_load_dwordx4 v[10:13], v36, s[10:11]
	global_load_dwordx4 v[2:5], v36, s[6:7]
	v_lshlrev_b32_e32 v44, 2, v0
	v_lshlrev_b32_e32 v0, 3, v0
	s_mov_b32 s13, 0
	v_xor_b32_e32 v39, 4, v44
	s_waitcnt vmcnt(1)
	v_add_f32_e32 v10, 1.0, v10
	v_add_f32_e32 v11, 1.0, v11
	v_add_f32_e32 v12, 1.0, v12
	v_add_f32_e32 v13, 1.0, v13
	v_mul_f32_e32 v20, v6, v10
	v_mul_f32_e32 v21, v7, v11
	v_or_b32_e32 v6, 0x400, v36
	v_mul_f32_e32 v18, v8, v12
	v_mul_f32_e32 v19, v9, v13
	global_load_dwordx4 v[10:13], v36, s[8:9] offset:1024
	global_load_dwordx4 v[14:17], v6, s[10:11]
	s_nop 0
	global_load_dwordx4 v[6:9], v6, s[6:7]
	s_waitcnt vmcnt(1)
	v_add_f32_e32 v14, 1.0, v14
	v_add_f32_e32 v15, 1.0, v15
	v_add_f32_e32 v16, 1.0, v16
	v_add_f32_e32 v17, 1.0, v17
	v_mul_f32_e32 v24, v10, v14
	v_mul_f32_e32 v25, v11, v15
	v_or_b32_e32 v10, 0x800, v36
	v_mul_f32_e32 v22, v12, v16
	v_mul_f32_e32 v23, v13, v17
	global_load_dwordx4 v[14:17], v36, s[8:9] offset:2048
	global_load_dwordx4 v[26:29], v10, s[10:11]
	s_nop 0
	global_load_dwordx4 v[10:13], v10, s[6:7]
	s_waitcnt vmcnt(1)
	v_add_f32_e32 v28, 1.0, v28
	v_add_f32_e32 v29, 1.0, v29
	v_add_f32_e32 v30, 1.0, v26
	v_add_f32_e32 v31, 1.0, v27
	v_mul_f32_e32 v26, v16, v28
	v_mul_f32_e32 v27, v17, v29
	v_mul_f32_e32 v28, v14, v30
	v_mul_f32_e32 v29, v15, v31
	v_or_b32_e32 v14, 0xc00, v36
	global_load_dwordx4 v[32:35], v36, s[8:9] offset:3072
	global_load_dwordx4 v[40:43], v14, s[10:11]
	s_nop 0
	global_load_dwordx4 v[14:17], v14, s[6:7]
	s_waitcnt vmcnt(1)
	v_add_f32_e32 v30, 1.0, v42
	v_add_f32_e32 v31, 1.0, v43
	v_add_f32_e32 v36, 1.0, v40
	v_add_f32_e32 v37, 1.0, v41
	v_mul_f32_e32 v30, v34, v30
	v_mul_f32_e32 v31, v35, v31
	v_lshl_add_u64 v[34:35], s[0:1], 0, v[0:1]
	s_mov_b64 s[0:1], 0xf000000
	v_mul_f32_e32 v32, v32, v36
	v_mul_f32_e32 v33, v33, v37
	v_lshl_add_u64 v[34:35], v[34:35], 0, s[0:1]
	s_waitcnt lgkmcnt(0)
	v_lshl_add_u64 v[36:37], s[2:3], 0, v[0:1]
	s_mov_b64 s[0:1], 0x17200000
	v_xor_b32_e32 v40, 8, v44
	v_xor_b32_e32 v41, 16, v44
	v_xor_b32_e32 v42, 32, v44
	v_xor_b32_e32 v43, 64, v44
	v_xor_b32_e32 v44, 0x80, v44
	v_lshl_add_u64 v[36:37], v[36:37], 0, s[0:1]
	s_mov_b64 s[0:1], -1
.LBB0_1903:
	s_or_b32 s2, s13, s12
	s_ashr_i32 s3, s2, 31
	s_lshl_b64 s[6:7], s[2:3], 11
	v_lshl_add_u64 v[46:47], v[34:35], 0, s[6:7]
	global_load_dwordx2 v[48:49], v[46:47], off
	global_load_dwordx2 v[50:51], v[46:47], off offset:512
	global_load_dwordx2 v[52:53], v[46:47], off offset:1024
	global_load_dwordx2 v[54:55], v[46:47], off offset:1536
	global_load_dwordx2 v[56:57], v[46:47], off offset:2048
	global_load_dwordx2 v[58:59], v[46:47], off offset:2560
	global_load_dwordx2 v[60:61], v[46:47], off offset:3072
	s_nop 0
	global_load_dwordx2 v[46:47], v[46:47], off offset:3584
	s_or_b32 s2, s2, 1
	s_ashr_i32 s3, s2, 31
	s_lshl_b64 s[2:3], s[2:3], 11
	s_mov_b32 s13, 2
	s_and_b64 vcc, exec, s[0:1]
	s_mov_b64 s[0:1], 0
	s_waitcnt vmcnt(7)
	v_lshlrev_b32_e32 v70, 16, v48
	v_and_b32_e32 v71, 0xffff0000, v48
	v_lshlrev_b32_e32 v48, 16, v49
	v_and_b32_e32 v49, 0xffff0000, v49
	v_mul_f32_e32 v0, v49, v49
	v_fma_f32 v72, v48, v48, v0
	v_fma_f32 v73, v49, v49, v0
	s_waitcnt vmcnt(6)
	v_lshlrev_b32_e32 v75, 16, v51
	v_lshlrev_b32_e32 v74, 16, v50
	v_and_b32_e32 v51, 0xffff0000, v51
	v_and_b32_e32 v50, 0xffff0000, v50
	v_mul_f32_e32 v0, v71, v71
	s_waitcnt vmcnt(4)
	v_lshlrev_b32_e32 v63, 16, v54
	v_mul_f32_e32 v76, v50, v50
	v_mul_f32_e32 v77, v51, v51
	v_fma_f32 v80, v70, v70, v0
	v_fma_f32 v81, v71, v71, v0
	v_and_b32_e32 v65, 0xffff0000, v54
	v_fma_f32 v76, v74, v74, v76
	v_fma_f32 v77, v75, v75, v77
	v_mov_b32_e32 v62, v80
	v_mov_b32_e32 v82, v72
	v_mov_b32_e32 v83, v63
	v_and_b32_e32 v79, 0xffff0000, v52
	v_mul_f32_e32 v45, v65, v65
	v_add_f32_e32 v72, v80, v72
	v_add_f32_e32 v73, v81, v73
	v_mul_f32_e32 v80, v62, v82
	v_mul_f32_e32 v81, v63, v83
	v_pk_add_f32 v[76:77], v[76:77], v[76:77] op_sel:[0,1] op_sel_hi:[1,0]
	v_lshlrev_b32_e32 v78, 16, v52
	v_lshlrev_b32_e32 v52, 16, v53
	v_and_b32_e32 v53, 0xffff0000, v53
	v_mov_b32_e32 v73, v81
	v_mov_b32_e32 v77, v45
	v_mul_f32_e32 v0, v79, v79
	v_lshlrev_b32_e32 v54, 16, v55
	v_and_b32_e32 v55, 0xffff0000, v55
	v_add_f32_e32 v72, v72, v76
	v_add_f32_e32 v73, v73, v77
	v_fma_f32 v76, v78, v78, v0
	v_fma_f32 v77, v79, v79, v0
	v_mul_f32_e32 v0, v53, v53
	v_mul_f32_e32 v64, v54, v54
	v_mul_f32_e32 v66, v55, v55
	v_fma_f32 v80, v52, v52, v0
	v_fma_f32 v81, v53, v53, v0
	v_mov_b32_e32 v77, v64
	v_mov_b32_e32 v81, v66
	v_add_f32_e32 v76, v76, v80
	v_add_f32_e32 v77, v77, v81
	s_waitcnt vmcnt(2)
	v_lshlrev_b32_e32 v81, 16, v59
	v_add_f32_e32 v72, v72, v76
	v_add_f32_e32 v73, v73, v77
	v_lshlrev_b32_e32 v80, 16, v58
	v_add_f32_e32 v45, v72, v73
	v_lshlrev_b32_e32 v72, 16, v56
	v_and_b32_e32 v73, 0xffff0000, v56
	v_lshlrev_b32_e32 v56, 16, v57
	v_and_b32_e32 v57, 0xffff0000, v57
	v_mul_f32_e32 v0, v57, v57
	v_fma_f32 v76, v56, v56, v0
	v_fma_f32 v77, v57, v57, v0
	v_and_b32_e32 v59, 0xffff0000, v59
	v_and_b32_e32 v58, 0xffff0000, v58
	v_mul_f32_e32 v0, v73, v73
	s_waitcnt vmcnt(0)
	v_lshlrev_b32_e32 v67, 16, v46
	v_mul_f32_e32 v82, v58, v58
	v_mul_f32_e32 v83, v59, v59
	v_fma_f32 v86, v72, v72, v0
	v_fma_f32 v87, v73, v73, v0
	v_and_b32_e32 v69, 0xffff0000, v46
	v_fma_f32 v82, v80, v80, v82
	v_fma_f32 v83, v81, v81, v83
	v_mov_b32_e32 v66, v86
	v_mov_b32_e32 v88, v76
	v_mov_b32_e32 v89, v67
	v_and_b32_e32 v85, 0xffff0000, v60
	v_mul_f32_e32 v62, v69, v69
	v_add_f32_e32 v76, v86, v76
	v_add_f32_e32 v77, v87, v77
	v_mul_f32_e32 v86, v66, v88
	v_mul_f32_e32 v87, v67, v89
	v_pk_add_f32 v[82:83], v[82:83], v[82:83] op_sel:[0,1] op_sel_hi:[1,0]
	v_lshlrev_b32_e32 v84, 16, v60
	v_lshlrev_b32_e32 v60, 16, v61
	v_and_b32_e32 v61, 0xffff0000, v61
	v_mov_b32_e32 v77, v87
	v_mov_b32_e32 v83, v62
	v_mul_f32_e32 v0, v85, v85
	v_add_f32_e32 v76, v76, v82
	v_add_f32_e32 v77, v77, v83
	v_fma_f32 v82, v84, v84, v0
	v_fma_f32 v83, v85, v85, v0
	v_mul_f32_e32 v0, v61, v61
	v_fma_f32 v86, v60, v60, v0
	v_fma_f32 v87, v61, v61, v0
	ds_bpermute_b32 v0, v39, v45
	v_lshlrev_b32_e32 v46, 16, v47
	v_and_b32_e32 v47, 0xffff0000, v47
	v_mul_f32_e32 v64, v46, v46
	v_mul_f32_e32 v68, v47, v47
	s_waitcnt lgkmcnt(0)
	v_add_f32_e32 v0, v45, v0
	ds_bpermute_b32 v45, v40, v0
	v_mov_b32_e32 v83, v64
	v_mov_b32_e32 v87, v68
	v_add_f32_e32 v82, v82, v86
	v_add_f32_e32 v83, v83, v87
	v_mov_b32_e32 v64, v63
	s_waitcnt lgkmcnt(0)
	v_add_f32_e32 v0, v0, v45
	ds_bpermute_b32 v45, v41, v0
	v_add_f32_e32 v76, v76, v82
	v_add_f32_e32 v77, v77, v83
	v_mov_b32_e32 v68, v67
	v_add_f32_e32 v62, v76, v77
	v_lshl_add_u64 v[76:77], v[36:37], 0, s[6:7]
	s_waitcnt lgkmcnt(0)
	v_add_f32_e32 v0, v0, v45
	ds_bpermute_b32 v45, v42, v0
	s_waitcnt lgkmcnt(0)
	v_add_f32_e32 v0, v0, v45
	ds_bpermute_b32 v45, v43, v0
	s_waitcnt lgkmcnt(0)
	v_add_f32_e32 v0, v0, v45
	ds_bpermute_b32 v45, v44, v0
	s_waitcnt lgkmcnt(0)
	v_add_f32_e32 v0, v0, v45
	v_fmamk_f32 v0, v0, 0x3a800000, v230
	v_rsq_f32_e32 v0, v0
	s_nop 0
	v_mul_f32_e32 v70, v0, v70
	v_mul_f32_e32 v71, v0, v71
	v_mul_f32_e32 v48, v0, v48
	v_mul_f32_e32 v49, v0, v49
	v_fma_f32 v48, v18, v48, v4
	v_fma_f32 v49, v19, v49, v5
	v_fma_f32 v70, v20, v70, v2
	v_fma_f32 v71, v21, v71, v3
	s_nop 0
	v_cvt_pk_bf16_f32 v70, v70, v71
	v_cvt_pk_bf16_f32 v71, v48, v49
	v_mov_b32_e32 v48, v74
	v_mov_b32_e32 v49, v50
	v_mul_f32_e32 v48, v0, v48
	v_mul_f32_e32 v49, v0, v49
	v_mov_b32_e32 v50, v75
	v_mul_f32_e32 v50, v0, v50
	v_mul_f32_e32 v51, v0, v51
	v_fma_f32 v48, v24, v48, v6
	v_fma_f32 v49, v25, v49, v7
	global_store_dwordx2 v[76:77], v[70:71], off
	v_fma_f32 v50, v22, v50, v8
	v_fma_f32 v51, v23, v51, v9
	v_cvt_pk_bf16_f32 v48, v48, v49
	s_nop 0
	v_cvt_pk_bf16_f32 v49, v50, v51
	global_store_dwordx2 v[76:77], v[48:49], off offset:512
	v_mul_f32_e32 v48, v0, v78
	v_mul_f32_e32 v49, v0, v79
	v_mul_f32_e32 v50, v0, v52
	v_mul_f32_e32 v51, v0, v53
	v_fma_f32 v48, v28, v48, v10
	v_fma_f32 v49, v29, v49, v11
	v_fma_f32 v50, v26, v50, v12
	v_fma_f32 v51, v27, v51, v13
	v_cvt_pk_bf16_f32 v48, v48, v49
	s_nop 0
	v_cvt_pk_bf16_f32 v49, v50, v51
	global_store_dwordx2 v[76:77], v[48:49], off offset:1024
	v_mul_f32_e32 v48, v0, v64
	v_mul_f32_e32 v49, v0, v65
	v_mul_f32_e32 v50, v0, v54
	v_mul_f32_e32 v51, v0, v55
	ds_bpermute_b32 v0, v39, v62
	v_fma_f32 v50, v30, v50, v16
	v_fma_f32 v51, v31, v51, v17
	v_fma_f32 v48, v32, v48, v14
	v_fma_f32 v49, v33, v49, v15
	s_waitcnt lgkmcnt(0)
	v_add_f32_e32 v0, v62, v0
	ds_bpermute_b32 v45, v40, v0
	v_cvt_pk_bf16_f32 v48, v48, v49
	v_cvt_pk_bf16_f32 v49, v50, v51
	global_store_dwordx2 v[76:77], v[48:49], off offset:1536
	v_lshl_add_u64 v[48:49], v[36:37], 0, s[2:3]
	s_waitcnt lgkmcnt(0)
	v_add_f32_e32 v0, v0, v45
	ds_bpermute_b32 v45, v41, v0
	s_waitcnt lgkmcnt(0)
	v_add_f32_e32 v0, v0, v45
	ds_bpermute_b32 v45, v42, v0
	s_waitcnt lgkmcnt(0)
	v_add_f32_e32 v0, v0, v45
	ds_bpermute_b32 v45, v43, v0
	s_waitcnt lgkmcnt(0)
	v_add_f32_e32 v0, v0, v45
	ds_bpermute_b32 v45, v44, v0
	s_waitcnt lgkmcnt(0)
	v_add_f32_e32 v0, v0, v45
	v_fmamk_f32 v0, v0, 0x3a800000, v230
	v_rsq_f32_e32 v0, v0
	s_nop 0
	v_mul_f32_e32 v50, v0, v72
	v_mul_f32_e32 v51, v0, v73
	v_mul_f32_e32 v52, v0, v56
	v_mul_f32_e32 v53, v0, v57
	v_fma_f32 v50, v20, v50, v2
	v_fma_f32 v51, v21, v51, v3
	v_fma_f32 v52, v18, v52, v4
	v_fma_f32 v53, v19, v53, v5
	v_cvt_pk_bf16_f32 v50, v50, v51
	v_mul_f32_e32 v46, v0, v46
	v_mul_f32_e32 v47, v0, v47
	v_cvt_pk_bf16_f32 v51, v52, v53
	global_store_dwordx2 v[48:49], v[50:51], off
	v_mov_b32_e32 v50, v80
	v_mov_b32_e32 v51, v58
	v_mul_f32_e32 v50, v0, v50
	v_mul_f32_e32 v51, v0, v51
	v_mov_b32_e32 v58, v81
	v_mul_f32_e32 v52, v0, v58
	v_mul_f32_e32 v53, v0, v59
	v_fma_f32 v50, v24, v50, v6
	v_fma_f32 v51, v25, v51, v7
	v_fma_f32 v52, v22, v52, v8
	v_fma_f32 v53, v23, v53, v9
	v_cvt_pk_bf16_f32 v50, v50, v51
	v_fma_f32 v46, v30, v46, v16
	v_fma_f32 v47, v31, v47, v17
	v_cvt_pk_bf16_f32 v51, v52, v53
	global_store_dwordx2 v[48:49], v[50:51], off offset:512
	v_mul_f32_e32 v50, v0, v84
	v_mul_f32_e32 v51, v0, v85
	v_mul_f32_e32 v52, v0, v60
	v_mul_f32_e32 v53, v0, v61
	v_fma_f32 v50, v28, v50, v10
	v_fma_f32 v51, v29, v51, v11
	v_fma_f32 v52, v26, v52, v12
	v_fma_f32 v53, v27, v53, v13
	v_cvt_pk_bf16_f32 v50, v50, v51
	s_nop 0
	v_cvt_pk_bf16_f32 v51, v52, v53
	global_store_dwordx2 v[48:49], v[50:51], off offset:1024
	v_mul_f32_e32 v50, v0, v68
	v_mul_f32_e32 v51, v0, v69
	v_fma_f32 v50, v32, v50, v14
	v_fma_f32 v51, v33, v51, v15
	s_nop 0
	v_cvt_pk_bf16_f32 v50, v50, v51
	v_cvt_pk_bf16_f32 v51, v46, v47
	global_store_dwordx2 v[48:49], v[50:51], off offset:1536
	s_cbranch_vccnz .LBB0_1903
	s_waitcnt vmcnt(0)
	v_cmp_eq_u32_e32 vcc, 0, v38
	s_barrier
	s_and_saveexec_b64 s[0:1], vcc
	s_cbranch_execz .LBB0_1918
	s_mov_b64 s[2:3], exec
	buffer_wbl2 sc1
	s_waitcnt vmcnt(0)
	s_waitcnt vmcnt(0)
	v_mbcnt_lo_u32_b32 v0, s2, 0
	v_mbcnt_hi_u32_b32 v0, s3, v0
	v_cmp_eq_u32_e32 vcc, 0, v0
	s_and_saveexec_b64 s[6:7], vcc
	s_cbranch_execz .LBB0_1907
	s_bcnt1_i32_b64 s2, s[2:3]
	v_mov_b32_e32 v0, s2
	global_atomic_add v1, v0, s[36:37] offset:2560

.LBB0_1967:
	s_lshl_b32 s0, s41, 8
	s_add_i32 s0, s0, s31
	v_or_b32_e32 v150, s0, v143
	s_add_i32 s16, s0, 0xffff8000
	s_lshr_b32 s16, s16, 5
	v_ashrrev_i32_e32 v151, 31, v150
	v_lshl_or_b32 v148, s42, 8, v170
	s_ashr_i32 s1, s0, 13
	s_add_i32 s16, s16, 4
	v_ashrrev_i32_e32 v149, 31, v148
	v_lshlrev_b64 v[130:131], 11, v[150:151]
	v_mov_b32_e32 v156, s16
	v_mov_b32_e32 v0, s1
	v_lshl_add_u64 v[132:133], s[6:7], 0, v[130:131]
	v_lshlrev_b64 v[130:131], 1, v[148:149]
	v_cmp_gt_i32_e32 vcc, s75, v150
	v_lshl_add_u64 v[164:165], v[132:133], 0, v[130:131]
	v_mov_b64_e32 v[132:133], s[8:9]
	v_cndmask_b32_e32 v151, v156, v0, vcc
	v_mad_i64_i32 v[156:157], s[16:17], v151, s96, v[132:133]
	v_lshlrev_b64 v[148:149], 2, v[148:149]
	v_lshl_add_u64 v[166:167], v[156:157], 0, v[148:149]
	global_load_dwordx4 v[152:155], v[164:165], off
	global_load_dwordx4 v[156:159], v[166:167], off
	global_load_dwordx4 v[160:163], v[166:167], off offset:16
	s_add_i32 s1, s0, 0xffff8010
	s_lshr_b32 s1, s1, 5
	s_add_i32 s1, s1, 4
	v_mov_b32_e32 v151, s1
	s_add_i32 s1, s0, 0xffff8020
	s_lshr_b32 s1, s1, 5
	s_add_i32 s1, s1, 4
	s_waitcnt vmcnt(0)
	v_lshlrev_b32_e32 v172, 16, v152
	v_and_b32_e32 v173, 0xffff0000, v152
	v_lshlrev_b32_e32 v152, 16, v153
	v_and_b32_e32 v153, 0xffff0000, v153
	v_lshlrev_b32_e32 v174, 16, v154
	v_and_b32_e32 v175, 0xffff0000, v154
	v_lshlrev_b32_e32 v154, 16, v155
	v_and_b32_e32 v155, 0xffff0000, v155
	v_mul_f32_e32 v158, 0.5, v158
	v_mul_f32_e32 v159, 0.5, v159
	v_mul_f32_e32 v156, 0.5, v156
	v_mul_f32_e32 v157, 0.5, v157
	v_mul_f32_e32 v162, 0.5, v162
	v_mul_f32_e32 v163, 0.5, v163
	v_mul_f32_e32 v160, 0.5, v160
	v_mul_f32_e32 v161, 0.5, v161
	v_fma_f32 v158, v128, v158, v152
	v_fma_f32 v159, v129, v159, v153
	v_fma_f32 v152, v126, v156, v172
	v_fma_f32 v153, v127, v157, v173
	v_fma_f32 v156, v124, v162, v154
	v_fma_f32 v157, v125, v163, v155
	v_fma_f32 v154, v122, v160, v174
	v_fma_f32 v155, v123, v161, v175
	v_cvt_pk_bf16_f32 v152, v152, v153
	v_cvt_pk_bf16_f32 v153, v158, v159
	s_nop 0
	v_cvt_pk_bf16_f32 v154, v154, v155
	v_cvt_pk_bf16_f32 v155, v156, v157
	global_store_dwordx4 v[164:165], v[152:155], off
	global_load_dwordx4 v[152:155], v[166:167], off offset:512
	global_load_dwordx4 v[156:159], v[166:167], off offset:528
	global_load_dwordx4 v[160:163], v[164:165], off offset:256
	v_or_b32_e32 v166, 16, v150
	v_ashrrev_i32_e32 v167, 31, v166
	v_cmp_gt_i32_e32 vcc, s75, v166
	s_waitcnt vmcnt(2)
	v_mul_f32_e32 v154, 0.5, v154
	v_mul_f32_e32 v155, 0.5, v155
	v_mul_f32_e32 v152, 0.5, v152
	v_mul_f32_e32 v153, 0.5, v153
	s_waitcnt vmcnt(0)
	v_lshlrev_b32_e32 v174, 16, v160
	v_and_b32_e32 v175, 0xffff0000, v160
	v_lshlrev_b32_e32 v160, 16, v161
	v_and_b32_e32 v161, 0xffff0000, v161
	v_cndmask_b32_e32 v151, v151, v0, vcc
	v_mul_f32_e32 v158, 0.5, v158
	v_mul_f32_e32 v159, 0.5, v159
	v_mul_f32_e32 v156, 0.5, v156
	v_mul_f32_e32 v157, 0.5, v157
	v_lshlrev_b32_e32 v176, 16, v162
	v_and_b32_e32 v177, 0xffff0000, v162
	v_lshlrev_b32_e32 v162, 16, v163
	v_and_b32_e32 v163, 0xffff0000, v163
	v_fma_f32 v154, v120, v154, v160
	v_fma_f32 v155, v121, v155, v161
	v_fma_f32 v152, v118, v152, v174
	v_fma_f32 v153, v119, v153, v175
	v_lshlrev_b64 v[160:161], 11, v[166:167]
	v_mad_i64_i32 v[172:173], s[16:17], v151, s96, v[132:133]
	v_fma_f32 v158, v116, v158, v162
	v_fma_f32 v159, v117, v159, v163
	v_fma_f32 v156, v114, v156, v176
	v_fma_f32 v157, v115, v157, v177
	v_cvt_pk_bf16_f32 v152, v152, v153
	v_cvt_pk_bf16_f32 v153, v154, v155
	v_lshl_add_u64 v[160:161], s[6:7], 0, v[160:161]
	v_cvt_pk_bf16_f32 v154, v156, v157
	v_cvt_pk_bf16_f32 v155, v158, v159
	global_store_dwordx4 v[164:165], v[152:155], off offset:256
	v_lshl_add_u64 v[172:173], v[172:173], 0, v[148:149]
	v_lshl_add_u64 v[164:165], v[160:161], 0, v[130:131]
	global_load_dwordx4 v[152:155], v[172:173], off offset:16
	global_load_dwordx4 v[156:159], v[172:173], off
	global_load_dwordx4 v[160:163], v[164:165], off
	v_mov_b32_e32 v151, s1
	s_add_i32 s1, s0, 0xffff8030
	s_lshr_b32 s1, s1, 5
	s_add_i32 s1, s1, 4
	s_waitcnt vmcnt(2)
	v_mul_f32_e32 v154, 0.5, v154
	v_mul_f32_e32 v155, 0.5, v155
	s_waitcnt vmcnt(1)
	v_mul_f32_e32 v158, 0.5, v158
	v_mul_f32_e32 v159, 0.5, v159
	v_mul_f32_e32 v152, 0.5, v152
	v_mul_f32_e32 v153, 0.5, v153
	s_waitcnt vmcnt(0)
	v_lshlrev_b32_e32 v166, 16, v160
	v_and_b32_e32 v167, 0xffff0000, v160
	v_lshlrev_b32_e32 v160, 16, v161
	v_and_b32_e32 v161, 0xffff0000, v161
	v_lshlrev_b32_e32 v174, 16, v162
	v_and_b32_e32 v175, 0xffff0000, v162
	v_lshlrev_b32_e32 v162, 16, v163
	v_and_b32_e32 v163, 0xffff0000, v163
	v_mul_f32_e32 v156, 0.5, v156
	v_mul_f32_e32 v157, 0.5, v157
	v_fma_f32 v158, v112, v158, v160
	v_fma_f32 v159, v113, v159, v161
	v_fma_f32 v160, v108, v154, v162
	v_fma_f32 v161, v109, v155, v163
	v_fma_f32 v154, v106, v152, v174
	v_fma_f32 v155, v107, v153, v175
	v_fma_f32 v156, v110, v156, v166
	v_fma_f32 v157, v111, v157, v167
	v_or_b32_e32 v166, 32, v150
	v_cvt_pk_bf16_f32 v152, v156, v157
	v_cvt_pk_bf16_f32 v153, v158, v159
	v_cvt_pk_bf16_f32 v154, v154, v155
	v_cvt_pk_bf16_f32 v155, v160, v161
	global_store_dwordx4 v[164:165], v[152:155], off
	global_load_dwordx4 v[152:155], v[172:173], off offset:512
	global_load_dwordx4 v[156:159], v[172:173], off offset:528
	global_load_dwordx4 v[160:163], v[164:165], off offset:256
	v_ashrrev_i32_e32 v167, 31, v166
	v_cmp_gt_i32_e32 vcc, s75, v166
	s_waitcnt vmcnt(2)
	v_mul_f32_e32 v154, 0.5, v154
	v_mul_f32_e32 v155, 0.5, v155
	v_mul_f32_e32 v152, 0.5, v152
	v_mul_f32_e32 v153, 0.5, v153
	s_waitcnt vmcnt(0)
	v_lshlrev_b32_e32 v174, 16, v160
	v_and_b32_e32 v175, 0xffff0000, v160
	v_lshlrev_b32_e32 v160, 16, v161
	v_and_b32_e32 v161, 0xffff0000, v161
	v_cndmask_b32_e32 v151, v151, v0, vcc
	v_mul_f32_e32 v158, 0.5, v158
	v_mul_f32_e32 v159, 0.5, v159
	v_mul_f32_e32 v156, 0.5, v156
	v_mul_f32_e32 v157, 0.5, v157
	v_lshlrev_b32_e32 v176, 16, v162
	v_and_b32_e32 v177, 0xffff0000, v162
	v_lshlrev_b32_e32 v162, 16, v163
	v_and_b32_e32 v163, 0xffff0000, v163
	v_fma_f32 v154, v104, v154, v160
	v_fma_f32 v155, v105, v155, v161
	v_fma_f32 v152, v102, v152, v174
	v_fma_f32 v153, v103, v153, v175
	v_lshlrev_b64 v[160:161], 11, v[166:167]
	v_mad_i64_i32 v[172:173], s[16:17], v151, s96, v[132:133]
	v_fma_f32 v158, v100, v158, v162
	v_fma_f32 v159, v101, v159, v163
	v_fma_f32 v156, v98, v156, v176
	v_fma_f32 v157, v99, v157, v177
	v_cvt_pk_bf16_f32 v152, v152, v153
	v_cvt_pk_bf16_f32 v153, v154, v155
	v_lshl_add_u64 v[160:161], s[6:7], 0, v[160:161]
	v_cvt_pk_bf16_f32 v154, v156, v157
	v_cvt_pk_bf16_f32 v155, v158, v159
	global_store_dwordx4 v[164:165], v[152:155], off offset:256
	v_lshl_add_u64 v[172:173], v[172:173], 0, v[148:149]
	v_lshl_add_u64 v[164:165], v[160:161], 0, v[130:131]
	global_load_dwordx4 v[152:155], v[172:173], off offset:16
	global_load_dwordx4 v[156:159], v[172:173], off
	global_load_dwordx4 v[160:163], v[164:165], off
	s_waitcnt vmcnt(2)
	v_mul_f32_e32 v154, 0.5, v154
	v_mul_f32_e32 v155, 0.5, v155
	s_waitcnt vmcnt(1)
	v_mul_f32_e32 v158, 0.5, v158
	v_mul_f32_e32 v159, 0.5, v159
	v_mul_f32_e32 v152, 0.5, v152
	v_mul_f32_e32 v153, 0.5, v153
	s_waitcnt vmcnt(0)
	v_lshlrev_b32_e32 v166, 16, v160
	v_and_b32_e32 v167, 0xffff0000, v160
	v_lshlrev_b32_e32 v160, 16, v161
	v_and_b32_e32 v161, 0xffff0000, v161
	v_lshlrev_b32_e32 v174, 16, v162
	v_and_b32_e32 v175, 0xffff0000, v162
	v_lshlrev_b32_e32 v162, 16, v163
	v_and_b32_e32 v163, 0xffff0000, v163
	v_mul_f32_e32 v156, 0.5, v156
	v_mul_f32_e32 v157, 0.5, v157
	v_fma_f32 v158, v96, v158, v160
	v_fma_f32 v159, v97, v159, v161
	v_fma_f32 v160, v92, v154, v162
	v_fma_f32 v161, v93, v155, v163
	v_fma_f32 v154, v90, v152, v174
	v_fma_f32 v155, v91, v153, v175
	v_fma_f32 v156, v94, v156, v166
	v_fma_f32 v157, v95, v157, v167
	v_or_b32_e32 v166, 48, v150
	v_cvt_pk_bf16_f32 v152, v156, v157
	v_cvt_pk_bf16_f32 v153, v158, v159
	v_cvt_pk_bf16_f32 v154, v154, v155
	v_cvt_pk_bf16_f32 v155, v160, v161
	global_store_dwordx4 v[164:165], v[152:155], off
	global_load_dwordx4 v[152:155], v[172:173], off offset:512
	global_load_dwordx4 v[156:159], v[172:173], off offset:528
	global_load_dwordx4 v[160:163], v[164:165], off offset:256
	v_mov_b32_e32 v150, s1
	v_cmp_gt_i32_e32 vcc, s75, v166
	v_ashrrev_i32_e32 v167, 31, v166
	s_add_i32 s1, s0, 0x80
	v_cndmask_b32_e32 v0, v150, v0, vcc
	v_mad_i64_i32 v[150:151], s[16:17], v0, s96, v[132:133]
	v_lshl_add_u64 v[172:173], v[150:151], 0, v[148:149]
	s_add_i32 s16, s0, 0xffff8080
	s_lshr_b32 s16, s16, 5
	s_add_i32 s16, s16, 4
	s_waitcnt vmcnt(2)
	v_mul_f32_e32 v150, 0.5, v154
	v_mul_f32_e32 v151, 0.5, v155
	v_mul_f32_e32 v152, 0.5, v152
	v_mul_f32_e32 v153, 0.5, v153
	s_waitcnt vmcnt(1)
	v_mul_f32_e32 v154, 0.5, v158
	v_mul_f32_e32 v155, 0.5, v159
	v_mul_f32_e32 v156, 0.5, v156
	v_mul_f32_e32 v157, 0.5, v157
	s_waitcnt vmcnt(0)
	v_lshlrev_b32_e32 v158, 16, v160
	v_and_b32_e32 v159, 0xffff0000, v160
	v_lshlrev_b32_e32 v160, 16, v161
	v_and_b32_e32 v161, 0xffff0000, v161
	v_lshlrev_b32_e32 v174, 16, v162
	v_and_b32_e32 v175, 0xffff0000, v162
	v_lshlrev_b32_e32 v162, 16, v163
	v_and_b32_e32 v163, 0xffff0000, v163
	v_fma_f32 v160, v88, v150, v160
	v_fma_f32 v161, v89, v151, v161
	v_fma_f32 v150, v86, v152, v158
	v_fma_f32 v151, v87, v153, v159
	v_fma_f32 v152, v82, v156, v174
	v_fma_f32 v153, v83, v157, v175
	v_lshlrev_b64 v[158:159], 11, v[166:167]
	v_fma_f32 v154, v84, v154, v162
	v_fma_f32 v155, v85, v155, v163
	v_cvt_pk_bf16_f32 v150, v150, v151
	v_cvt_pk_bf16_f32 v151, v160, v161
	v_cvt_pk_bf16_f32 v152, v152, v153
	v_lshl_add_u64 v[158:159], s[6:7], 0, v[158:159]
	v_cvt_pk_bf16_f32 v153, v154, v155
	global_store_dwordx4 v[164:165], v[150:153], off offset:256
	v_lshl_add_u64 v[164:165], v[158:159], 0, v[130:131]
	global_load_dwordx4 v[150:153], v[172:173], off offset:16
	global_load_dwordx4 v[154:157], v[172:173], off
	global_load_dwordx4 v[158:161], v[164:165], off
	s_waitcnt vmcnt(2)
	v_mul_f32_e32 v152, 0.5, v152
	v_mul_f32_e32 v153, 0.5, v153
	s_waitcnt vmcnt(1)
	v_mul_f32_e32 v156, 0.5, v156
	v_mul_f32_e32 v157, 0.5, v157
	v_mul_f32_e32 v150, 0.5, v150
	v_mul_f32_e32 v151, 0.5, v151
	s_waitcnt vmcnt(0)
	v_lshlrev_b32_e32 v162, 16, v158
	v_and_b32_e32 v163, 0xffff0000, v158
	v_lshlrev_b32_e32 v158, 16, v159
	v_and_b32_e32 v159, 0xffff0000, v159
	v_lshlrev_b32_e32 v166, 16, v160
	v_and_b32_e32 v167, 0xffff0000, v160
	v_lshlrev_b32_e32 v160, 16, v161
	v_and_b32_e32 v161, 0xffff0000, v161
	v_mul_f32_e32 v154, 0.5, v154
	v_mul_f32_e32 v155, 0.5, v155
	v_fma_f32 v156, v80, v156, v158
	v_fma_f32 v157, v81, v157, v159
	v_fma_f32 v158, v76, v152, v160
	v_fma_f32 v159, v77, v153, v161
	v_fma_f32 v152, v74, v150, v166
	v_fma_f32 v153, v75, v151, v167
	v_fma_f32 v154, v78, v154, v162
	v_fma_f32 v155, v79, v155, v163
	v_mov_b32_e32 v166, s16
	v_cvt_pk_bf16_f32 v150, v154, v155
	v_cvt_pk_bf16_f32 v151, v156, v157
	v_cvt_pk_bf16_f32 v152, v152, v153
	v_cvt_pk_bf16_f32 v153, v158, v159
	global_store_dwordx4 v[164:165], v[150:153], off
	global_load_dwordx4 v[152:155], v[172:173], off offset:512
	global_load_dwordx4 v[156:159], v[172:173], off offset:528
	global_load_dwordx4 v[160:163], v[164:165], off offset:256
	v_or_b32_e32 v150, s1, v143
	s_ashr_i32 s1, s1, 13
	v_mov_b32_e32 v0, s1
	v_ashrrev_i32_e32 v151, 31, v150
	v_cmp_gt_i32_e32 vcc, s75, v150
	s_add_i32 s1, s0, 0xffff8090
	s_lshr_b32 s1, s1, 5
	v_cndmask_b32_e32 v166, v166, v0, vcc
	v_mad_i64_i32 v[166:167], s[16:17], v166, s96, v[132:133]
	v_lshl_add_u64 v[166:167], v[166:167], 0, v[148:149]
	s_add_i32 s1, s1, 4
	s_waitcnt vmcnt(2)
	v_mul_f32_e32 v154, 0.5, v154
	v_mul_f32_e32 v155, 0.5, v155
	v_mul_f32_e32 v152, 0.5, v152
	v_mul_f32_e32 v153, 0.5, v153
	s_waitcnt vmcnt(0)
	v_lshlrev_b32_e32 v172, 16, v160
	v_and_b32_e32 v173, 0xffff0000, v160
	v_lshlrev_b32_e32 v160, 16, v161
	v_and_b32_e32 v161, 0xffff0000, v161
	v_mul_f32_e32 v158, 0.5, v158
	v_mul_f32_e32 v159, 0.5, v159
	v_mul_f32_e32 v156, 0.5, v156
	v_mul_f32_e32 v157, 0.5, v157
	v_lshlrev_b32_e32 v174, 16, v162
	v_and_b32_e32 v175, 0xffff0000, v162
	v_lshlrev_b32_e32 v162, 16, v163
	v_and_b32_e32 v163, 0xffff0000, v163
	v_fma_f32 v154, v72, v154, v160
	v_fma_f32 v155, v73, v155, v161
	v_fma_f32 v152, v70, v152, v172
	v_fma_f32 v153, v71, v153, v173
	v_lshlrev_b64 v[160:161], 11, v[150:151]
	v_fma_f32 v158, v68, v158, v162
	v_fma_f32 v159, v69, v159, v163
	v_fma_f32 v156, v66, v156, v174
	v_fma_f32 v157, v67, v157, v175
	v_cvt_pk_bf16_f32 v152, v152, v153
	v_cvt_pk_bf16_f32 v153, v154, v155
	v_lshl_add_u64 v[160:161], s[6:7], 0, v[160:161]
	v_cvt_pk_bf16_f32 v154, v156, v157
	v_cvt_pk_bf16_f32 v155, v158, v159
	global_store_dwordx4 v[164:165], v[152:155], off offset:256
	v_lshl_add_u64 v[164:165], v[160:161], 0, v[130:131]
	global_load_dwordx4 v[152:155], v[166:167], off offset:16
	global_load_dwordx4 v[156:159], v[166:167], off
	global_load_dwordx4 v[160:163], v[164:165], off
	v_mov_b32_e32 v151, s1
	s_add_i32 s1, s0, 0xffff80a0
	s_lshr_b32 s1, s1, 5
	s_add_i32 s1, s1, 4
	s_addk_i32 s0, 0x80b0
	s_lshr_b32 s0, s0, 5
	s_add_i32 s0, s0, 4
	s_waitcnt vmcnt(2)
	v_mul_f32_e32 v154, 0.5, v154
	v_mul_f32_e32 v155, 0.5, v155
	s_waitcnt vmcnt(1)
	v_mul_f32_e32 v158, 0.5, v158
	v_mul_f32_e32 v159, 0.5, v159
	v_mul_f32_e32 v152, 0.5, v152
	v_mul_f32_e32 v153, 0.5, v153
	s_waitcnt vmcnt(0)
	v_lshlrev_b32_e32 v172, 16, v160
	v_and_b32_e32 v173, 0xffff0000, v160
	v_lshlrev_b32_e32 v160, 16, v161
	v_and_b32_e32 v161, 0xffff0000, v161
	v_lshlrev_b32_e32 v174, 16, v162
	v_and_b32_e32 v175, 0xffff0000, v162
	v_lshlrev_b32_e32 v162, 16, v163
	v_and_b32_e32 v163, 0xffff0000, v163
	v_mul_f32_e32 v156, 0.5, v156
	v_mul_f32_e32 v157, 0.5, v157
	v_fma_f32 v158, v64, v158, v160
	v_fma_f32 v159, v65, v159, v161
	v_fma_f32 v160, v60, v154, v162
	v_fma_f32 v161, v61, v155, v163
	v_fma_f32 v154, v58, v152, v174
	v_fma_f32 v155, v59, v153, v175
	v_fma_f32 v156, v62, v156, v172
	v_fma_f32 v157, v63, v157, v173
	s_nop 0
	v_cvt_pk_bf16_f32 v152, v156, v157
	v_cvt_pk_bf16_f32 v153, v158, v159
	v_cvt_pk_bf16_f32 v154, v154, v155
	v_cvt_pk_bf16_f32 v155, v160, v161
	global_store_dwordx4 v[164:165], v[152:155], off
	global_load_dwordx4 v[152:155], v[166:167], off offset:512
	global_load_dwordx4 v[156:159], v[166:167], off offset:528
	global_load_dwordx4 v[160:163], v[164:165], off offset:256
	v_or_b32_e32 v166, 16, v150
	v_ashrrev_i32_e32 v167, 31, v166
	v_cmp_gt_i32_e32 vcc, s75, v166
	s_waitcnt vmcnt(2)
	v_mul_f32_e32 v154, 0.5, v154
	v_mul_f32_e32 v155, 0.5, v155
	v_mul_f32_e32 v152, 0.5, v152
	v_mul_f32_e32 v153, 0.5, v153
	s_waitcnt vmcnt(0)
	v_lshlrev_b32_e32 v174, 16, v160
	v_and_b32_e32 v175, 0xffff0000, v160
	v_lshlrev_b32_e32 v160, 16, v161
	v_and_b32_e32 v161, 0xffff0000, v161
	v_cndmask_b32_e32 v151, v151, v0, vcc
	v_mul_f32_e32 v158, 0.5, v158
	v_mul_f32_e32 v159, 0.5, v159
	v_mul_f32_e32 v156, 0.5, v156
	v_mul_f32_e32 v157, 0.5, v157
	v_lshlrev_b32_e32 v176, 16, v162
	v_and_b32_e32 v177, 0xffff0000, v162
	v_lshlrev_b32_e32 v162, 16, v163
	v_and_b32_e32 v163, 0xffff0000, v163
	v_fma_f32 v154, v56, v154, v160
	v_fma_f32 v155, v57, v155, v161
	v_fma_f32 v152, v54, v152, v174
	v_fma_f32 v153, v55, v153, v175
	v_lshlrev_b64 v[160:161], 11, v[166:167]
	v_mad_i64_i32 v[172:173], s[16:17], v151, s96, v[132:133]
	v_fma_f32 v158, v52, v158, v162
	v_fma_f32 v159, v53, v159, v163
	v_fma_f32 v156, v50, v156, v176
	v_fma_f32 v157, v51, v157, v177
	v_cvt_pk_bf16_f32 v152, v152, v153
	v_cvt_pk_bf16_f32 v153, v154, v155
	v_lshl_add_u64 v[160:161], s[6:7], 0, v[160:161]
	v_cvt_pk_bf16_f32 v154, v156, v157
	v_cvt_pk_bf16_f32 v155, v158, v159
	global_store_dwordx4 v[164:165], v[152:155], off offset:256
	v_lshl_add_u64 v[172:173], v[172:173], 0, v[148:149]
	v_lshl_add_u64 v[164:165], v[160:161], 0, v[130:131]
	global_load_dwordx4 v[152:155], v[172:173], off offset:16
	global_load_dwordx4 v[156:159], v[172:173], off
	global_load_dwordx4 v[160:163], v[164:165], off
	v_mov_b32_e32 v151, s1
	s_waitcnt vmcnt(2)
	v_mul_f32_e32 v154, 0.5, v154
	v_mul_f32_e32 v155, 0.5, v155
	s_waitcnt vmcnt(1)
	v_mul_f32_e32 v158, 0.5, v158
	v_mul_f32_e32 v159, 0.5, v159
	v_mul_f32_e32 v152, 0.5, v152
	v_mul_f32_e32 v153, 0.5, v153
	s_waitcnt vmcnt(0)
	v_lshlrev_b32_e32 v166, 16, v160
	v_and_b32_e32 v167, 0xffff0000, v160
	v_lshlrev_b32_e32 v160, 16, v161
	v_and_b32_e32 v161, 0xffff0000, v161
	v_lshlrev_b32_e32 v174, 16, v162
	v_and_b32_e32 v175, 0xffff0000, v162
	v_lshlrev_b32_e32 v162, 16, v163
	v_and_b32_e32 v163, 0xffff0000, v163
	v_mul_f32_e32 v156, 0.5, v156
	v_mul_f32_e32 v157, 0.5, v157
	v_fma_f32 v158, v48, v158, v160
	v_fma_f32 v159, v49, v159, v161
	v_fma_f32 v160, v44, v154, v162
	v_fma_f32 v161, v45, v155, v163
	v_fma_f32 v154, v42, v152, v174
	v_fma_f32 v155, v43, v153, v175
	v_fma_f32 v156, v46, v156, v166
	v_fma_f32 v157, v47, v157, v167
	v_or_b32_e32 v166, 32, v150
	v_cvt_pk_bf16_f32 v152, v156, v157
	v_cvt_pk_bf16_f32 v153, v158, v159
	v_cvt_pk_bf16_f32 v154, v154, v155
	v_cvt_pk_bf16_f32 v155, v160, v161
	global_store_dwordx4 v[164:165], v[152:155], off
	global_load_dwordx4 v[152:155], v[172:173], off offset:512
	global_load_dwordx4 v[156:159], v[172:173], off offset:528
	global_load_dwordx4 v[160:163], v[164:165], off offset:256
	v_ashrrev_i32_e32 v167, 31, v166
	v_cmp_gt_i32_e32 vcc, s75, v166
	s_waitcnt vmcnt(2)
	v_mul_f32_e32 v154, 0.5, v154
	v_mul_f32_e32 v155, 0.5, v155
	v_mul_f32_e32 v152, 0.5, v152
	v_mul_f32_e32 v153, 0.5, v153
	s_waitcnt vmcnt(0)
	v_lshlrev_b32_e32 v174, 16, v160
	v_and_b32_e32 v175, 0xffff0000, v160
	v_lshlrev_b32_e32 v160, 16, v161
	v_and_b32_e32 v161, 0xffff0000, v161
	v_cndmask_b32_e32 v151, v151, v0, vcc
	v_mul_f32_e32 v158, 0.5, v158
	v_mul_f32_e32 v159, 0.5, v159
	v_mul_f32_e32 v156, 0.5, v156
	v_mul_f32_e32 v157, 0.5, v157
	v_lshlrev_b32_e32 v176, 16, v162
	v_and_b32_e32 v177, 0xffff0000, v162
	v_lshlrev_b32_e32 v162, 16, v163
	v_and_b32_e32 v163, 0xffff0000, v163
	v_fma_f32 v154, v40, v154, v160
	v_fma_f32 v155, v41, v155, v161
	v_fma_f32 v152, v38, v152, v174
	v_fma_f32 v153, v39, v153, v175
	v_lshlrev_b64 v[160:161], 11, v[166:167]
	v_mad_i64_i32 v[172:173], s[16:17], v151, s96, v[132:133]
	v_fma_f32 v158, v36, v158, v162
	v_fma_f32 v159, v37, v159, v163
	v_fma_f32 v156, v34, v156, v176
	v_fma_f32 v157, v35, v157, v177
	v_cvt_pk_bf16_f32 v152, v152, v153
	v_cvt_pk_bf16_f32 v153, v154, v155
	v_lshl_add_u64 v[160:161], s[6:7], 0, v[160:161]
	v_cvt_pk_bf16_f32 v154, v156, v157
	v_cvt_pk_bf16_f32 v155, v158, v159
	global_store_dwordx4 v[164:165], v[152:155], off offset:256
	v_lshl_add_u64 v[172:173], v[172:173], 0, v[148:149]
	v_lshl_add_u64 v[164:165], v[160:161], 0, v[130:131]
	global_load_dwordx4 v[152:155], v[172:173], off offset:16
	global_load_dwordx4 v[156:159], v[172:173], off
	global_load_dwordx4 v[160:163], v[164:165], off
	s_waitcnt vmcnt(2)
	v_mul_f32_e32 v154, 0.5, v154
	v_mul_f32_e32 v155, 0.5, v155
	s_waitcnt vmcnt(1)
	v_mul_f32_e32 v158, 0.5, v158
	v_mul_f32_e32 v159, 0.5, v159
	v_mul_f32_e32 v152, 0.5, v152
	v_mul_f32_e32 v153, 0.5, v153
	s_waitcnt vmcnt(0)
	v_lshlrev_b32_e32 v166, 16, v160
	v_and_b32_e32 v167, 0xffff0000, v160
	v_lshlrev_b32_e32 v160, 16, v161
	v_and_b32_e32 v161, 0xffff0000, v161
	v_lshlrev_b32_e32 v174, 16, v162
	v_and_b32_e32 v175, 0xffff0000, v162
	v_lshlrev_b32_e32 v162, 16, v163
	v_and_b32_e32 v163, 0xffff0000, v163
	v_mul_f32_e32 v156, 0.5, v156
	v_mul_f32_e32 v157, 0.5, v157
	v_fma_f32 v158, v32, v158, v160
	v_fma_f32 v159, v33, v159, v161
	v_fma_f32 v160, v28, v154, v162
	v_fma_f32 v161, v29, v155, v163
	v_fma_f32 v154, v26, v152, v174
	v_fma_f32 v155, v27, v153, v175
	v_fma_f32 v156, v30, v156, v166
	v_fma_f32 v157, v31, v157, v167
	v_or_b32_e32 v166, 48, v150
	v_cvt_pk_bf16_f32 v152, v156, v157
	v_cvt_pk_bf16_f32 v153, v158, v159
	v_cvt_pk_bf16_f32 v154, v154, v155
	v_cvt_pk_bf16_f32 v155, v160, v161
	global_store_dwordx4 v[164:165], v[152:155], off
	global_load_dwordx4 v[152:155], v[172:173], off offset:512
	global_load_dwordx4 v[156:159], v[172:173], off offset:528
	global_load_dwordx4 v[160:163], v[164:165], off offset:256
	v_mov_b32_e32 v150, s0
	v_cmp_gt_i32_e32 vcc, s75, v166
	v_ashrrev_i32_e32 v167, 31, v166
	s_nop 0
	v_cndmask_b32_e32 v0, v150, v0, vcc
	v_mad_i64_i32 v[132:133], s[0:1], v0, s96, v[132:133]
	v_lshl_add_u64 v[172:173], v[132:133], 0, v[148:149]
	s_waitcnt vmcnt(2)
	v_mul_f32_e32 v132, 0.5, v154
	v_mul_f32_e32 v133, 0.5, v155
	v_mul_f32_e32 v148, 0.5, v152
	v_mul_f32_e32 v149, 0.5, v153
	s_waitcnt vmcnt(1)
	v_mul_f32_e32 v152, 0.5, v156
	v_mul_f32_e32 v153, 0.5, v157
	s_waitcnt vmcnt(0)
	v_lshlrev_b32_e32 v154, 16, v160
	v_and_b32_e32 v155, 0xffff0000, v160
	v_lshlrev_b32_e32 v156, 16, v161
	v_and_b32_e32 v157, 0xffff0000, v161
	v_mul_f32_e32 v150, 0.5, v158
	v_mul_f32_e32 v151, 0.5, v159
	v_lshlrev_b32_e32 v158, 16, v162
	v_and_b32_e32 v159, 0xffff0000, v162
	v_lshlrev_b32_e32 v160, 16, v163
	v_and_b32_e32 v161, 0xffff0000, v163
	v_fma_f32 v132, v24, v132, v156
	v_fma_f32 v133, v25, v133, v157
	v_fma_f32 v148, v22, v148, v154
	v_fma_f32 v149, v23, v149, v155
	v_fma_f32 v154, v20, v150, v160
	v_fma_f32 v155, v21, v151, v161
	v_fma_f32 v150, v18, v152, v158
	v_fma_f32 v151, v19, v153, v159
	v_cvt_pk_bf16_f32 v148, v148, v149
	v_cvt_pk_bf16_f32 v149, v132, v133
	v_lshlrev_b64 v[132:133], 11, v[166:167]
	v_cvt_pk_bf16_f32 v150, v150, v151
	v_cvt_pk_bf16_f32 v151, v154, v155
	global_store_dwordx4 v[164:165], v[148:151], off offset:256
	v_lshl_add_u64 v[132:133], s[6:7], 0, v[132:133]
	v_lshl_add_u64 v[156:157], v[132:133], 0, v[130:131]
	global_load_dwordx4 v[148:151], v[172:173], off offset:16
	global_load_dwordx4 v[152:155], v[172:173], off
	global_load_dwordx4 v[130:133], v[156:157], off
	s_waitcnt vmcnt(2)
	v_mul_f32_e32 v150, 0.5, v150
	v_mul_f32_e32 v151, 0.5, v151
	s_waitcnt vmcnt(1)
	v_mul_f32_e32 v154, 0.5, v154
	v_mul_f32_e32 v155, 0.5, v155
	v_mul_f32_e32 v152, 0.5, v152
	v_mul_f32_e32 v153, 0.5, v153
	v_mul_f32_e32 v148, 0.5, v148
	v_mul_f32_e32 v149, 0.5, v149
	s_waitcnt vmcnt(0)
	v_lshlrev_b32_e32 v158, 16, v130
	v_and_b32_e32 v159, 0xffff0000, v130
	v_lshlrev_b32_e32 v130, 16, v131
	v_and_b32_e32 v131, 0xffff0000, v131
	v_lshlrev_b32_e32 v160, 16, v132
	v_and_b32_e32 v161, 0xffff0000, v132
	v_lshlrev_b32_e32 v132, 16, v133
	v_and_b32_e32 v133, 0xffff0000, v133
	v_fma_f32 v154, v16, v154, v130
	v_fma_f32 v155, v17, v155, v131
	v_fma_f32 v130, v14, v152, v158
	v_fma_f32 v131, v15, v153, v159
	v_fma_f32 v150, v12, v150, v132
	v_fma_f32 v151, v13, v151, v133
	v_fma_f32 v132, v10, v148, v160
	v_fma_f32 v133, v11, v149, v161
	v_cvt_pk_bf16_f32 v130, v130, v131
	v_cvt_pk_bf16_f32 v131, v154, v155
	s_nop 0
	v_cvt_pk_bf16_f32 v132, v132, v133
	v_cvt_pk_bf16_f32 v133, v150, v151
	global_store_dwordx4 v[156:157], v[130:133], off
	global_load_dwordx4 v[130:133], v[172:173], off offset:512
	global_load_dwordx4 v[148:151], v[172:173], off offset:528
	global_load_dwordx4 v[152:155], v[156:157], off offset:256
	s_waitcnt vmcnt(2)
	v_mul_f32_e32 v132, 0.5, v132
	v_mul_f32_e32 v133, 0.5, v133
	v_mul_f32_e32 v130, 0.5, v130
	v_mul_f32_e32 v131, 0.5, v131
	s_waitcnt vmcnt(0)
	v_lshlrev_b32_e32 v158, 16, v152
	v_and_b32_e32 v159, 0xffff0000, v152
	v_lshlrev_b32_e32 v152, 16, v153
	v_and_b32_e32 v153, 0xffff0000, v153
	v_mul_f32_e32 v150, 0.5, v150
	v_mul_f32_e32 v151, 0.5, v151
	v_mul_f32_e32 v148, 0.5, v148
	v_mul_f32_e32 v149, 0.5, v149
	v_lshlrev_b32_e32 v160, 16, v154
	v_and_b32_e32 v161, 0xffff0000, v154
	v_lshlrev_b32_e32 v154, 16, v155
	v_and_b32_e32 v155, 0xffff0000, v155
	v_fma_f32 v132, v8, v132, v152
	v_fma_f32 v133, v9, v133, v153
	v_fma_f32 v130, v6, v130, v158
	v_fma_f32 v131, v7, v131, v159
	v_fma_f32 v150, v4, v150, v154
	v_fma_f32 v151, v5, v151, v155
	v_fma_f32 v148, v2, v148, v160
	v_fma_f32 v149, v3, v149, v161
	v_cvt_pk_bf16_f32 v130, v130, v131
	v_cvt_pk_bf16_f32 v131, v132, v133
	s_nop 0
	v_cvt_pk_bf16_f32 v132, v148, v149
	v_cvt_pk_bf16_f32 v133, v150, v151
	global_store_dwordx4 v[156:157], v[130:133], off offset:256
	s_cbranch_execnz .LBB0_1965
.LBB0_1968:
	s_ashr_i32 s0, s41, 5
	s_mul_hi_i32 s1, s0, 0x9000
	s_mul_i32 s0, s0, 0x9000
	s_add_u32 s18, s8, s0
	s_addc_u32 s19, s9, s1
	s_lshl_b32 s0, s42, 8
	s_ashr_i32 s1, s0, 31
	s_lshl_b64 s[16:17], s[0:1], 2
	s_add_u32 s16, s18, s16
	s_addc_u32 s17, s19, s17
	s_lshl_b32 s18, s33, 2
	s_add_u32 s16, s16, s18
	s_addc_u32 s17, s17, 0
	v_lshlrev_b32_e32 v0, 2, v142
	global_load_dwordx4 v[130:133], v0, s[16:17] offset:16
	global_load_dwordx4 v[148:151], v0, s[16:17]
	s_waitcnt vmcnt(0)
	v_mul_f32_e32 v160, 0.5, v132
	v_mul_f32_e32 v161, 0.5, v133
	v_mul_f32_e32 v156, 0.5, v150
	v_mul_f32_e32 v157, 0.5, v151
	v_mul_f32_e32 v158, 0.5, v148
	v_mul_f32_e32 v159, 0.5, v149
	v_mul_f32_e32 v162, 0.5, v130
	v_mul_f32_e32 v163, 0.5, v131
	global_load_dwordx4 v[130:133], v0, s[16:17] offset:528
	global_load_dwordx4 v[148:151], v0, s[16:17] offset:512
	v_lshlrev_b32_e32 v0, 1, v142
	s_waitcnt vmcnt(0)
	v_mul_f32_e32 v152, 0.5, v148
	v_mul_f32_e32 v153, 0.5, v149
	v_mul_f32_e32 v148, 0.5, v130
	v_mul_f32_e32 v149, 0.5, v131
	v_lshl_add_u32 v130, s41, 8, v168
	v_ashrrev_i32_e32 v131, 31, v130
	v_lshlrev_b64 v[130:131], 11, v[130:131]
	v_lshl_add_u64 v[130:131], s[6:7], 0, v[130:131]
	v_lshl_add_u64 v[130:131], s[0:1], 1, v[130:131]
	v_lshl_add_u64 v[130:131], v[130:131], 0, v[0:1]
	s_mov_b32 s1, s49
	s_lshl_b32 s0, s33, 1
	v_lshl_add_u64 v[164:165], v[130:131], 0, s[0:1]
	global_load_dwordx4 v[172:175], v[164:165], off
	global_load_dwordx4 v[176:179], v[164:165], off offset:256
	v_add_co_u32_e32 v166, vcc, s75, v164
	v_mul_f32_e32 v154, 0.5, v150
	v_mul_f32_e32 v155, 0.5, v151
	s_nop 0
	v_addc_co_u32_e32 v167, vcc, 0, v165, vcc
	v_mul_f32_e32 v150, 0.5, v132
	v_mul_f32_e32 v151, 0.5, v133
	global_load_dwordx4 v[180:183], v[166:167], off
	global_load_dwordx4 v[130:133], v[166:167], off offset:256
	s_mov_b32 s0, 0x10000
	s_waitcnt vmcnt(3)
	v_lshlrev_b32_e32 v184, 16, v172
	v_and_b32_e32 v185, 0xffff0000, v172
	v_lshlrev_b32_e32 v172, 16, v173
	v_and_b32_e32 v173, 0xffff0000, v173
	v_lshlrev_b32_e32 v186, 16, v174
	v_and_b32_e32 v187, 0xffff0000, v174
	v_lshlrev_b32_e32 v174, 16, v175
	v_and_b32_e32 v175, 0xffff0000, v175
	v_fma_f32 v128, v128, v156, v172
	v_fma_f32 v129, v129, v157, v173
	v_fma_f32 v126, v126, v158, v184
	v_fma_f32 v127, v127, v159, v185
	v_fma_f32 v172, v124, v160, v174
	v_fma_f32 v173, v125, v161, v175
	v_fma_f32 v124, v122, v162, v186
	v_fma_f32 v125, v123, v163, v187
	v_cvt_pk_bf16_f32 v122, v126, v127
	v_cvt_pk_bf16_f32 v123, v128, v129
	s_waitcnt vmcnt(2)
	v_lshlrev_b32_e32 v126, 16, v178
	v_cvt_pk_bf16_f32 v124, v124, v125
	v_cvt_pk_bf16_f32 v125, v172, v173
	global_store_dwordx4 v[164:165], v[122:125], off
	v_and_b32_e32 v127, 0xffff0000, v178
	v_lshlrev_b32_e32 v128, 16, v179
	v_lshlrev_b32_e32 v122, 16, v176
	v_and_b32_e32 v123, 0xffff0000, v176
	v_and_b32_e32 v129, 0xffff0000, v179
	v_lshlrev_b32_e32 v124, 16, v177
	v_and_b32_e32 v125, 0xffff0000, v177
	v_fma_f32 v118, v118, v152, v122
	v_fma_f32 v119, v119, v153, v123
	v_fma_f32 v122, v116, v150, v128
	v_fma_f32 v123, v117, v151, v129
	v_fma_f32 v116, v114, v148, v126
	v_fma_f32 v117, v115, v149, v127
	v_fma_f32 v120, v120, v154, v124
	v_fma_f32 v121, v121, v155, v125
	v_cvt_pk_bf16_f32 v114, v118, v119
	s_waitcnt vmcnt(2)
	v_lshlrev_b32_e32 v124, 16, v180
	v_cvt_pk_bf16_f32 v115, v120, v121
	v_cvt_pk_bf16_f32 v116, v116, v117
	v_cvt_pk_bf16_f32 v117, v122, v123
	global_store_dwordx4 v[164:165], v[114:117], off offset:256
	v_add_co_u32_e32 v122, vcc, s0, v164
	v_and_b32_e32 v125, 0xffff0000, v180
	s_nop 0
	v_addc_co_u32_e32 v123, vcc, 0, v165, vcc
	v_lshlrev_b32_e32 v126, 16, v181
	v_and_b32_e32 v127, 0xffff0000, v181
	v_lshlrev_b32_e32 v128, 16, v182
	v_and_b32_e32 v129, 0xffff0000, v182
	v_lshlrev_b32_e32 v172, 16, v183
	v_and_b32_e32 v173, 0xffff0000, v183
	global_load_dwordx4 v[118:121], v[122:123], off
	global_load_dwordx4 v[114:117], v[122:123], off offset:256
	v_fma_f32 v112, v112, v156, v126
	v_fma_f32 v113, v113, v157, v127
	v_fma_f32 v110, v110, v158, v124
	v_fma_f32 v111, v111, v159, v125
	v_fma_f32 v124, v108, v160, v172
	v_fma_f32 v125, v109, v161, v173
	v_fma_f32 v108, v106, v162, v128
	v_fma_f32 v109, v107, v163, v129
	v_cvt_pk_bf16_f32 v106, v110, v111
	v_cvt_pk_bf16_f32 v107, v112, v113
	s_waitcnt vmcnt(4)
	v_lshlrev_b32_e32 v110, 16, v132
	v_cvt_pk_bf16_f32 v108, v108, v109
	v_cvt_pk_bf16_f32 v109, v124, v125
	global_store_dwordx4 v[166:167], v[106:109], off
	v_and_b32_e32 v111, 0xffff0000, v132
	v_lshlrev_b32_e32 v112, 16, v133
	v_lshlrev_b32_e32 v106, 16, v130
	v_and_b32_e32 v107, 0xffff0000, v130
	v_and_b32_e32 v113, 0xffff0000, v133
	v_lshlrev_b32_e32 v108, 16, v131
	v_and_b32_e32 v109, 0xffff0000, v131
	v_fma_f32 v102, v102, v152, v106
	v_fma_f32 v103, v103, v153, v107
	v_fma_f32 v106, v100, v150, v112
	v_fma_f32 v107, v101, v151, v113
	v_fma_f32 v100, v98, v148, v110
	v_fma_f32 v101, v99, v149, v111
	s_mov_b32 s0, 0x18000
	v_fma_f32 v104, v104, v154, v108
	v_fma_f32 v105, v105, v155, v109
	v_cvt_pk_bf16_f32 v98, v102, v103
	v_add_co_u32_e32 v102, vcc, s0, v164
	v_cvt_pk_bf16_f32 v99, v104, v105
	v_cvt_pk_bf16_f32 v100, v100, v101
	v_cvt_pk_bf16_f32 v101, v106, v107
	global_store_dwordx4 v[166:167], v[98:101], off offset:256
	s_nop 0
	v_addc_co_u32_e32 v103, vcc, 0, v165, vcc
	global_load_dwordx4 v[104:107], v[102:103], off
	global_load_dwordx4 v[98:101], v[102:103], off offset:256
	s_mov_b32 s0, 0x40000
	s_waitcnt vmcnt(5)
	v_lshlrev_b32_e32 v108, 16, v118
	v_and_b32_e32 v109, 0xffff0000, v118
	v_lshlrev_b32_e32 v110, 16, v119
	v_and_b32_e32 v111, 0xffff0000, v119
	v_lshlrev_b32_e32 v112, 16, v120
	v_and_b32_e32 v113, 0xffff0000, v120
	v_lshlrev_b32_e32 v118, 16, v121
	v_and_b32_e32 v119, 0xffff0000, v121
	v_fma_f32 v96, v96, v156, v110
	v_fma_f32 v97, v97, v157, v111
	v_fma_f32 v94, v94, v158, v108
	v_fma_f32 v95, v95, v159, v109
	v_fma_f32 v108, v92, v160, v118
	v_fma_f32 v109, v93, v161, v119
	v_fma_f32 v92, v90, v162, v112
	v_fma_f32 v93, v91, v163, v113
	v_cvt_pk_bf16_f32 v90, v94, v95
	v_cvt_pk_bf16_f32 v91, v96, v97
	s_waitcnt vmcnt(4)
	v_lshlrev_b32_e32 v94, 16, v116
	v_cvt_pk_bf16_f32 v92, v92, v93
	v_cvt_pk_bf16_f32 v93, v108, v109
	global_store_dwordx4 v[122:123], v[90:93], off
	v_and_b32_e32 v95, 0xffff0000, v116
	v_lshlrev_b32_e32 v96, 16, v117
	v_lshlrev_b32_e32 v90, 16, v114
	v_and_b32_e32 v91, 0xffff0000, v114
	v_and_b32_e32 v97, 0xffff0000, v117
	v_lshlrev_b32_e32 v92, 16, v115
	v_and_b32_e32 v93, 0xffff0000, v115
	v_fma_f32 v86, v86, v152, v90
	v_fma_f32 v87, v87, v153, v91
	v_fma_f32 v90, v84, v150, v96
	v_fma_f32 v91, v85, v151, v97
	v_fma_f32 v84, v82, v148, v94
	v_fma_f32 v85, v83, v149, v95
	v_fma_f32 v88, v88, v154, v92
	v_fma_f32 v89, v89, v155, v93
	v_cvt_pk_bf16_f32 v82, v86, v87
	s_waitcnt vmcnt(2)
	v_lshlrev_b32_e32 v92, 16, v104
	v_cvt_pk_bf16_f32 v83, v88, v89
	v_cvt_pk_bf16_f32 v84, v84, v85
	v_cvt_pk_bf16_f32 v85, v90, v91
	global_store_dwordx4 v[122:123], v[82:85], off offset:256
	v_add_co_u32_e32 v90, vcc, s0, v164
	v_and_b32_e32 v93, 0xffff0000, v104
	s_nop 0
	v_addc_co_u32_e32 v91, vcc, 0, v165, vcc
	v_lshlrev_b32_e32 v94, 16, v105
	v_and_b32_e32 v95, 0xffff0000, v105
	v_lshlrev_b32_e32 v96, 16, v106
	v_and_b32_e32 v97, 0xffff0000, v106
	v_lshlrev_b32_e32 v104, 16, v107
	v_and_b32_e32 v105, 0xffff0000, v107
	global_load_dwordx4 v[86:89], v[90:91], off
	global_load_dwordx4 v[82:85], v[90:91], off offset:256
	v_fma_f32 v80, v80, v156, v94
	v_fma_f32 v81, v81, v157, v95
	v_fma_f32 v78, v78, v158, v92
	v_fma_f32 v79, v79, v159, v93
	v_fma_f32 v92, v76, v160, v104
	v_fma_f32 v93, v77, v161, v105
	v_fma_f32 v76, v74, v162, v96
	v_fma_f32 v77, v75, v163, v97
	v_cvt_pk_bf16_f32 v74, v78, v79
	v_cvt_pk_bf16_f32 v75, v80, v81
	s_waitcnt vmcnt(4)
	v_lshlrev_b32_e32 v78, 16, v100
	v_cvt_pk_bf16_f32 v76, v76, v77
	v_cvt_pk_bf16_f32 v77, v92, v93
	global_store_dwordx4 v[102:103], v[74:77], off
	v_and_b32_e32 v79, 0xffff0000, v100
	v_lshlrev_b32_e32 v80, 16, v101
	v_lshlrev_b32_e32 v74, 16, v98
	v_and_b32_e32 v75, 0xffff0000, v98
	v_and_b32_e32 v81, 0xffff0000, v101
	v_lshlrev_b32_e32 v76, 16, v99
	v_and_b32_e32 v77, 0xffff0000, v99
	v_fma_f32 v70, v70, v152, v74
	v_fma_f32 v71, v71, v153, v75
	v_fma_f32 v74, v68, v150, v80
	v_fma_f32 v75, v69, v151, v81
	v_fma_f32 v68, v66, v148, v78
	v_fma_f32 v69, v67, v149, v79
	s_mov_b32 s0, 0x48000
	v_fma_f32 v72, v72, v154, v76
	v_fma_f32 v73, v73, v155, v77
	v_cvt_pk_bf16_f32 v66, v70, v71
	v_add_co_u32_e32 v70, vcc, s0, v164
	v_cvt_pk_bf16_f32 v67, v72, v73
	v_cvt_pk_bf16_f32 v68, v68, v69
	v_cvt_pk_bf16_f32 v69, v74, v75
	global_store_dwordx4 v[102:103], v[66:69], off offset:256
	s_nop 0
	v_addc_co_u32_e32 v71, vcc, 0, v165, vcc
	global_load_dwordx4 v[72:75], v[70:71], off
	global_load_dwordx4 v[66:69], v[70:71], off offset:256
	s_mov_b32 s0, 0x50000
	s_waitcnt vmcnt(5)
	v_lshlrev_b32_e32 v76, 16, v86
	v_and_b32_e32 v77, 0xffff0000, v86
	v_lshlrev_b32_e32 v78, 16, v87
	v_and_b32_e32 v79, 0xffff0000, v87
	v_lshlrev_b32_e32 v80, 16, v88
	v_and_b32_e32 v81, 0xffff0000, v88
	v_lshlrev_b32_e32 v86, 16, v89
	v_and_b32_e32 v87, 0xffff0000, v89
	v_fma_f32 v64, v64, v156, v78
	v_fma_f32 v65, v65, v157, v79
	v_fma_f32 v62, v62, v158, v76
	v_fma_f32 v63, v63, v159, v77
	v_fma_f32 v76, v60, v160, v86
	v_fma_f32 v77, v61, v161, v87
	v_fma_f32 v60, v58, v162, v80
	v_fma_f32 v61, v59, v163, v81
	v_cvt_pk_bf16_f32 v58, v62, v63
	v_cvt_pk_bf16_f32 v59, v64, v65
	s_waitcnt vmcnt(4)
	v_lshlrev_b32_e32 v62, 16, v84
	v_cvt_pk_bf16_f32 v60, v60, v61
	v_cvt_pk_bf16_f32 v61, v76, v77
	global_store_dwordx4 v[90:91], v[58:61], off
	v_and_b32_e32 v63, 0xffff0000, v84
	v_lshlrev_b32_e32 v64, 16, v85
	v_lshlrev_b32_e32 v58, 16, v82
	v_and_b32_e32 v59, 0xffff0000, v82
	v_and_b32_e32 v65, 0xffff0000, v85
	v_lshlrev_b32_e32 v60, 16, v83
	v_and_b32_e32 v61, 0xffff0000, v83
	v_fma_f32 v54, v54, v152, v58
	v_fma_f32 v55, v55, v153, v59
	v_fma_f32 v58, v52, v150, v64
	v_fma_f32 v59, v53, v151, v65
	v_fma_f32 v52, v50, v148, v62
	v_fma_f32 v53, v51, v149, v63
	v_fma_f32 v56, v56, v154, v60
	v_fma_f32 v57, v57, v155, v61
	v_cvt_pk_bf16_f32 v50, v54, v55
	s_waitcnt vmcnt(2)
	v_lshlrev_b32_e32 v60, 16, v72
	v_cvt_pk_bf16_f32 v51, v56, v57
	v_cvt_pk_bf16_f32 v52, v52, v53
	v_cvt_pk_bf16_f32 v53, v58, v59
	global_store_dwordx4 v[90:91], v[50:53], off offset:256
	v_add_co_u32_e32 v58, vcc, s0, v164
	v_and_b32_e32 v61, 0xffff0000, v72
	s_nop 0
	v_addc_co_u32_e32 v59, vcc, 0, v165, vcc
	v_lshlrev_b32_e32 v62, 16, v73
	v_and_b32_e32 v63, 0xffff0000, v73
	v_lshlrev_b32_e32 v64, 16, v74
	v_and_b32_e32 v65, 0xffff0000, v74
	v_lshlrev_b32_e32 v72, 16, v75
	v_and_b32_e32 v73, 0xffff0000, v75
	global_load_dwordx4 v[54:57], v[58:59], off
	global_load_dwordx4 v[50:53], v[58:59], off offset:256
	v_fma_f32 v48, v48, v156, v62
	v_fma_f32 v49, v49, v157, v63
	v_fma_f32 v46, v46, v158, v60
	v_fma_f32 v47, v47, v159, v61
	v_fma_f32 v60, v44, v160, v72
	v_fma_f32 v61, v45, v161, v73
	v_fma_f32 v44, v42, v162, v64
	v_fma_f32 v45, v43, v163, v65
	v_cvt_pk_bf16_f32 v42, v46, v47
	v_cvt_pk_bf16_f32 v43, v48, v49
	s_waitcnt vmcnt(4)
	v_lshlrev_b32_e32 v46, 16, v68
	v_cvt_pk_bf16_f32 v44, v44, v45
	v_cvt_pk_bf16_f32 v45, v60, v61
	global_store_dwordx4 v[70:71], v[42:45], off
	v_and_b32_e32 v47, 0xffff0000, v68
	v_lshlrev_b32_e32 v48, 16, v69
	v_lshlrev_b32_e32 v42, 16, v66
	v_and_b32_e32 v43, 0xffff0000, v66
	v_and_b32_e32 v49, 0xffff0000, v69
	v_lshlrev_b32_e32 v44, 16, v67
	v_and_b32_e32 v45, 0xffff0000, v67
	v_fma_f32 v38, v38, v152, v42
	v_fma_f32 v39, v39, v153, v43
	v_fma_f32 v42, v36, v150, v48
	v_fma_f32 v43, v37, v151, v49
	v_fma_f32 v36, v34, v148, v46
	v_fma_f32 v37, v35, v149, v47
	v_cvt_pk_bf16_f32 v34, v38, v39
	s_mov_b32 s0, 0x58000
	v_fma_f32 v40, v40, v154, v44
	v_fma_f32 v41, v41, v155, v45
	s_waitcnt vmcnt(2)
	v_lshlrev_b32_e32 v44, 16, v54
	v_cvt_pk_bf16_f32 v35, v40, v41
	v_cvt_pk_bf16_f32 v36, v36, v37
	v_cvt_pk_bf16_f32 v37, v42, v43
	global_store_dwordx4 v[70:71], v[34:37], off offset:256
	v_and_b32_e32 v45, 0xffff0000, v54
	v_lshlrev_b32_e32 v46, 16, v55
	v_add_co_u32_e32 v34, vcc, s0, v164
	v_and_b32_e32 v47, 0xffff0000, v55
	s_nop 0
	v_addc_co_u32_e32 v35, vcc, 0, v165, vcc
	global_load_dwordx4 v[36:39], v[34:35], off
	global_load_dwordx4 v[40:43], v[34:35], off offset:256
	v_lshlrev_b32_e32 v48, 16, v56
	v_and_b32_e32 v49, 0xffff0000, v56
	v_lshlrev_b32_e32 v54, 16, v57
	v_and_b32_e32 v55, 0xffff0000, v57
	v_fma_f32 v32, v32, v156, v46
	v_fma_f32 v33, v33, v157, v47
	v_fma_f32 v30, v30, v158, v44
	v_fma_f32 v31, v31, v159, v45
	v_fma_f32 v44, v28, v160, v54
	v_fma_f32 v45, v29, v161, v55
	v_fma_f32 v28, v26, v162, v48
	v_fma_f32 v29, v27, v163, v49
	v_cvt_pk_bf16_f32 v26, v30, v31
	v_cvt_pk_bf16_f32 v27, v32, v33
	s_waitcnt vmcnt(4)
	v_lshlrev_b32_e32 v30, 16, v52
	v_cvt_pk_bf16_f32 v28, v28, v29
	v_cvt_pk_bf16_f32 v29, v44, v45
	global_store_dwordx4 v[58:59], v[26:29], off
	v_and_b32_e32 v31, 0xffff0000, v52
	v_lshlrev_b32_e32 v32, 16, v53
	v_lshlrev_b32_e32 v26, 16, v50
	v_and_b32_e32 v27, 0xffff0000, v50
	v_and_b32_e32 v33, 0xffff0000, v53
	v_lshlrev_b32_e32 v28, 16, v51
	v_and_b32_e32 v29, 0xffff0000, v51
	v_fma_f32 v22, v22, v152, v26
	v_fma_f32 v23, v23, v153, v27
	v_fma_f32 v26, v20, v150, v32
	v_fma_f32 v27, v21, v151, v33
	v_fma_f32 v20, v18, v148, v30
	v_fma_f32 v21, v19, v149, v31
	v_fma_f32 v24, v24, v154, v28
	v_fma_f32 v25, v25, v155, v29
	v_cvt_pk_bf16_f32 v18, v22, v23
	s_waitcnt vmcnt(2)
	v_lshlrev_b32_e32 v22, 16, v38
	v_cvt_pk_bf16_f32 v19, v24, v25
	v_cvt_pk_bf16_f32 v20, v20, v21
	v_cvt_pk_bf16_f32 v21, v26, v27
	global_store_dwordx4 v[58:59], v[18:21], off offset:256
	v_and_b32_e32 v23, 0xffff0000, v38
	v_lshlrev_b32_e32 v24, 16, v39
	v_lshlrev_b32_e32 v18, 16, v36
	v_and_b32_e32 v19, 0xffff0000, v36
	v_lshlrev_b32_e32 v20, 16, v37
	v_and_b32_e32 v21, 0xffff0000, v37
	v_and_b32_e32 v25, 0xffff0000, v39
	v_fma_f32 v16, v16, v156, v20
	v_fma_f32 v17, v17, v157, v21
	v_fma_f32 v14, v14, v158, v18
	v_fma_f32 v15, v15, v159, v19
	v_fma_f32 v18, v12, v160, v24
	v_fma_f32 v19, v13, v161, v25
	v_fma_f32 v12, v10, v162, v22
	v_fma_f32 v13, v11, v163, v23
	v_cvt_pk_bf16_f32 v10, v14, v15
	v_cvt_pk_bf16_f32 v11, v16, v17
	s_waitcnt vmcnt(2)
	v_lshlrev_b32_e32 v14, 16, v42
	v_cvt_pk_bf16_f32 v12, v12, v13
	v_cvt_pk_bf16_f32 v13, v18, v19
	global_store_dwordx4 v[34:35], v[10:13], off
	v_and_b32_e32 v15, 0xffff0000, v42
	v_lshlrev_b32_e32 v16, 16, v43
	v_lshlrev_b32_e32 v10, 16, v40
	v_and_b32_e32 v11, 0xffff0000, v40
	v_and_b32_e32 v17, 0xffff0000, v43
	v_lshlrev_b32_e32 v12, 16, v41
	v_and_b32_e32 v13, 0xffff0000, v41
	v_fma_f32 v6, v6, v152, v10
	v_fma_f32 v7, v7, v153, v11
	v_fma_f32 v10, v4, v150, v16
	v_fma_f32 v11, v5, v151, v17
	v_fma_f32 v4, v2, v148, v14
	v_fma_f32 v5, v3, v149, v15
	v_fma_f32 v8, v8, v154, v12
	v_fma_f32 v9, v9, v155, v13
	v_cvt_pk_bf16_f32 v2, v6, v7
	s_nop 0
	v_cvt_pk_bf16_f32 v3, v8, v9
	v_cvt_pk_bf16_f32 v4, v4, v5
	v_cvt_pk_bf16_f32 v5, v10, v11
	global_store_dwordx4 v[34:35], v[2:5], off offset:256
	s_and_b64 vcc, exec, s[4:5]
	s_mov_b64 s[0:1], -1
	s_cbranch_vccnz .LBB0_1953

.LBB0_1990:
	s_waitcnt lgkmcnt(14)
	v_mfma_f32_32x32x16_bf16 v[64:79], v[160:163], v[208:211], v[64:79]
	v_exp_f32_e32 v128, v128
	v_exp_f32_e32 v129, v129
	ds_read_b64_tr_b16 v[92:93], v0 offset:32768
	ds_read_b64_tr_b16 v[94:95], v0 offset:33280
	s_waitcnt lgkmcnt(14)
	v_mfma_f32_32x32x16_bf16 v[48:63], v[160:163], v[204:207], v[48:63]
	v_exp_f32_e32 v130, v130
	v_exp_f32_e32 v131, v131
	ds_read_b64_tr_b16 v[104:105], v0 offset:36864
	ds_read_b64_tr_b16 v[106:107], v0 offset:37376
	v_add_u32_e32 v196, s27, v250
	ds_read_b128 v[84:87], v196
	ds_read_b128 v[80:83], v196 offset:512
	s_waitcnt lgkmcnt(14)
	v_mfma_f32_32x32x16_bf16 v[64:79], v[152:155], v[10:13], v[64:79]
	v_exp_f32_e32 v132, v132
	v_exp_f32_e32 v133, v133
	ds_read_b64_tr_b16 v[108:109], v0 offset:33792
	ds_read_b64_tr_b16 v[110:111], v0 offset:34304
	ds_read_b128 v[184:187], v196 offset:2048
	ds_read_b128 v[176:179], v196 offset:2560
	v_mfma_f32_32x32x16_bf16 v[48:63], v[152:155], v[6:9], v[48:63]
	v_exp_f32_e32 v134, v134
	v_exp_f32_e32 v135, v135
	ds_read_b64_tr_b16 v[188:189], v0 offset:37888
	ds_read_b64_tr_b16 v[190:191], v0 offset:38400
	ds_read_b128 v[180:183], v196 offset:4096
	ds_read_b128 v[6:9], v196 offset:4608
	s_waitcnt lgkmcnt(14)
	v_mfma_f32_32x32x16_bf16 v[64:79], v[148:151], v[2:5], v[64:79]
	v_exp_f32_e32 v136, v136
	v_exp_f32_e32 v137, v137
	ds_read_b64_tr_b16 v[192:193], v0 offset:34816
	ds_read_b64_tr_b16 v[194:195], v0 offset:35328
	ds_read_b128 v[10:13], v196 offset:6144
	ds_read_b128 v[2:5], v196 offset:6656
	v_mfma_f32_32x32x16_bf16 v[48:63], v[148:151], v[100:103], v[48:63]
	v_exp_f32_e32 v138, v138
	v_exp_f32_e32 v139, v139
	ds_read_b64_tr_b16 v[100:101], v0 offset:38912
	ds_read_b64_tr_b16 v[102:103], v0 offset:39424
	v_mfma_f32_32x32x16_bf16 v[64:79], v[144:147], v[96:99], v[64:79]
	v_exp_f32_e32 v140, v140
	v_exp_f32_e32 v141, v141
	ds_read_b64_tr_b16 v[96:97], v0 offset:35840
	ds_read_b64_tr_b16 v[98:99], v0 offset:36352
	v_mfma_f32_32x32x16_bf16 v[48:63], v[144:147], v[88:91], v[48:63]
	v_exp_f32_e32 v142, v142
	v_exp_f32_e32 v143, v143
	ds_read_b64_tr_b16 v[88:89], v0 offset:39936
	ds_read_b64_tr_b16 v[90:91], v0 offset:40448
	s_waitcnt lgkmcnt(14)
	v_mfma_f32_32x32x16_bf16 v[32:47], v[160:163], v[92:95], v[32:47]
	v_exp_f32_e32 v112, v112
	v_exp_f32_e32 v113, v113
	v_mfma_f32_32x32x16_bf16 v[16:31], v[160:163], v[104:107], v[16:31]
	v_exp_f32_e32 v114, v114
	v_exp_f32_e32 v115, v115
	v_mfma_f32_32x32x16_bf16 v[32:47], v[152:155], v[108:111], v[32:47]
	v_exp_f32_e32 v116, v116
	v_exp_f32_e32 v117, v117
	s_waitcnt lgkmcnt(12)
	v_mfma_f32_32x32x16_bf16 v[16:31], v[152:155], v[188:191], v[16:31]
	v_exp_f32_e32 v118, v118
	v_exp_f32_e32 v119, v119
	s_waitcnt lgkmcnt(8)
	v_mfma_f32_32x32x16_bf16 v[32:47], v[148:151], v[192:195], v[32:47]
	v_exp_f32_e32 v120, v120
	v_exp_f32_e32 v121, v121
	s_waitcnt lgkmcnt(4)
	v_mfma_f32_32x32x16_bf16 v[16:31], v[148:151], v[100:103], v[16:31]
	v_exp_f32_e32 v122, v122
	v_exp_f32_e32 v123, v123
	s_waitcnt lgkmcnt(2)
	v_mfma_f32_32x32x16_bf16 v[32:47], v[144:147], v[96:99], v[32:47]
	v_exp_f32_e32 v124, v124
	v_exp_f32_e32 v125, v125
	s_waitcnt lgkmcnt(0)
	v_mfma_f32_32x32x16_bf16 v[16:31], v[144:147], v[88:91], v[16:31]
	v_exp_f32_e32 v126, v126
	v_exp_f32_e32 v127, v127
	s_add_i32 s24, s27, 0x2000
	s_cmpk_lg_i32 s27, 0x4000
	s_cselect_b32 s52, s24, 0
	s_lshl_b32 s24, s29, 1
	s_waitcnt vmcnt(3) lgkmcnt(0)
	s_barrier
	s_andn2_b64 vcc, exec, s[20:21]
	v_add_u32_e32 v0, s46, v252
	s_cbranch_vccnz .LBB0_1992
	s_waitcnt lgkmcnt(0)
	ds_read_b128 v[88:91], v0 offset:96
	ds_read_b128 v[92:95], v0 offset:64
	ds_read_b128 v[96:99], v0 offset:32
	ds_read_b128 v[100:103], v0
	s_waitcnt lgkmcnt(3)
	v_mul_f32_e32 v76, v76, v88
	v_mul_f32_e32 v77, v77, v89
	s_waitcnt lgkmcnt(2)
	v_mul_f32_e32 v72, v72, v92
	v_mul_f32_e32 v73, v73, v93
	s_waitcnt lgkmcnt(1)
	v_mul_f32_e32 v68, v68, v96
	v_mul_f32_e32 v69, v69, v97
	v_mul_f32_e32 v78, v78, v90
	v_mul_f32_e32 v79, v79, v91
	v_mul_f32_e32 v74, v74, v94
	v_mul_f32_e32 v75, v75, v95
	v_mul_f32_e32 v70, v70, v98
	v_mul_f32_e32 v71, v71, v99
	s_waitcnt lgkmcnt(0)
	v_mul_f32_e32 v66, v66, v102
	v_mul_f32_e32 v67, v67, v103
	v_mul_f32_e32 v64, v64, v100
	v_mul_f32_e32 v65, v65, v101
	v_mul_f32_e32 v60, v60, v88
	v_mul_f32_e32 v61, v61, v89
	v_mul_f32_e32 v56, v56, v92
	v_mul_f32_e32 v57, v57, v93
	v_mul_f32_e32 v52, v52, v96
	v_mul_f32_e32 v53, v53, v97
	v_mul_f32_e32 v62, v62, v90
	v_mul_f32_e32 v63, v63, v91
	v_mul_f32_e32 v58, v58, v94
	v_mul_f32_e32 v59, v59, v95
	v_mul_f32_e32 v54, v54, v98
	v_mul_f32_e32 v55, v55, v99
	v_mul_f32_e32 v50, v50, v102
	v_mul_f32_e32 v51, v51, v103
	v_mul_f32_e32 v48, v48, v100
	v_mul_f32_e32 v49, v49, v101
	v_mul_f32_e32 v44, v44, v88
	v_mul_f32_e32 v45, v45, v89
	v_mul_f32_e32 v40, v40, v92
	v_mul_f32_e32 v41, v41, v93
	v_mul_f32_e32 v36, v36, v96
	v_mul_f32_e32 v37, v37, v97
	v_mul_f32_e32 v46, v46, v90
	v_mul_f32_e32 v47, v47, v91
	v_mul_f32_e32 v42, v42, v94
	v_mul_f32_e32 v43, v43, v95
	v_mul_f32_e32 v38, v38, v98
	v_mul_f32_e32 v39, v39, v99
	v_mul_f32_e32 v34, v34, v102
	v_mul_f32_e32 v35, v35, v103
	v_mul_f32_e32 v32, v32, v100
	v_mul_f32_e32 v33, v33, v101
	v_mul_f32_e32 v28, v28, v88
	v_mul_f32_e32 v29, v29, v89
	v_mul_f32_e32 v24, v24, v92
	v_mul_f32_e32 v25, v25, v93
	v_mul_f32_e32 v20, v20, v96
	v_mul_f32_e32 v21, v21, v97
	v_mul_f32_e32 v30, v30, v90
	v_mul_f32_e32 v31, v31, v91
	v_mul_f32_e32 v26, v26, v94
	v_mul_f32_e32 v27, v27, v95
	v_mul_f32_e32 v22, v22, v98
	v_mul_f32_e32 v23, v23, v99
	v_mul_f32_e32 v18, v18, v102
	v_mul_f32_e32 v19, v19, v103
	v_mul_f32_e32 v16, v16, v100
	v_mul_f32_e32 v17, v17, v101

.LBB0_1993:
	s_waitcnt lgkmcnt(14)
	v_mfma_f32_32x32x16_bf16 v[64:79], v[160:163], v[196:199], v[64:79]
	v_exp_f32_e32 v96, v96
	v_exp_f32_e32 v97, v97
	ds_read_b64_tr_b16 v[2:3], v208 offset:32768
	ds_read_b64_tr_b16 v[4:5], v208 offset:33280
	s_waitcnt lgkmcnt(14)
	v_mfma_f32_32x32x16_bf16 v[48:63], v[160:163], v[192:195], v[48:63]
	v_exp_f32_e32 v98, v98
	v_exp_f32_e32 v99, v99
	ds_read_b64_tr_b16 v[10:11], v208 offset:36864
	ds_read_b64_tr_b16 v[12:13], v208 offset:37376
	v_add_u32_e32 v14, s52, v250
	ds_read_b128 v[204:207], v14
	ds_read_b128 v[196:199], v14 offset:512
	s_waitcnt lgkmcnt(14)
	v_mfma_f32_32x32x16_bf16 v[64:79], v[152:155], v[188:191], v[64:79]
	v_exp_f32_e32 v100, v100
	v_exp_f32_e32 v101, v101
	ds_read_b64_tr_b16 v[116:117], v208 offset:33792
	ds_read_b64_tr_b16 v[118:119], v208 offset:34304
	ds_read_b128 v[200:203], v14 offset:2048
	ds_read_b128 v[192:195], v14 offset:2560
	v_mfma_f32_32x32x16_bf16 v[48:63], v[152:155], v[136:139], v[48:63]
	v_exp_f32_e32 v102, v102
	v_exp_f32_e32 v103, v103
	ds_read_b64_tr_b16 v[120:121], v208 offset:37888
	ds_read_b64_tr_b16 v[122:123], v208 offset:38400
	ds_read_b128 v[188:191], v14 offset:4096
	ds_read_b128 v[184:187], v14 offset:4608
	s_waitcnt lgkmcnt(14)
	v_mfma_f32_32x32x16_bf16 v[64:79], v[148:151], v[132:135], v[64:79]
	v_exp_f32_e32 v104, v104
	v_exp_f32_e32 v105, v105
	ds_read_b64_tr_b16 v[124:125], v208 offset:34816
	ds_read_b64_tr_b16 v[126:127], v208 offset:35328
	ds_read_b128 v[180:183], v14 offset:6144
	ds_read_b128 v[176:179], v14 offset:6656
	v_mfma_f32_32x32x16_bf16 v[48:63], v[148:151], v[128:131], v[48:63]
	v_exp_f32_e32 v106, v106
	v_exp_f32_e32 v107, v107
	ds_read_b64_tr_b16 v[128:129], v208 offset:38912
	ds_read_b64_tr_b16 v[130:131], v208 offset:39424
	v_mfma_f32_32x32x16_bf16 v[64:79], v[144:147], v[112:115], v[64:79]
	v_exp_f32_e32 v108, v108
	v_exp_f32_e32 v109, v109
	ds_read_b64_tr_b16 v[112:113], v208 offset:35840
	ds_read_b64_tr_b16 v[114:115], v208 offset:36352
	v_mfma_f32_32x32x16_bf16 v[48:63], v[144:147], v[6:9], v[48:63]
	v_exp_f32_e32 v110, v110
	v_exp_f32_e32 v111, v111
	ds_read_b64_tr_b16 v[6:7], v208 offset:39936
	ds_read_b64_tr_b16 v[8:9], v208 offset:40448
	s_waitcnt lgkmcnt(14)
	v_mfma_f32_32x32x16_bf16 v[32:47], v[160:163], v[2:5], v[32:47]
	v_exp_f32_e32 v80, v80
	v_exp_f32_e32 v81, v81
	v_mfma_f32_32x32x16_bf16 v[16:31], v[160:163], v[10:13], v[16:31]
	v_exp_f32_e32 v82, v82
	v_exp_f32_e32 v83, v83
	v_mfma_f32_32x32x16_bf16 v[32:47], v[152:155], v[116:119], v[32:47]
	v_exp_f32_e32 v84, v84
	v_exp_f32_e32 v85, v85
	s_waitcnt lgkmcnt(12)
	v_mfma_f32_32x32x16_bf16 v[16:31], v[152:155], v[120:123], v[16:31]
	v_exp_f32_e32 v86, v86
	v_exp_f32_e32 v87, v87
	s_waitcnt lgkmcnt(8)
	v_mfma_f32_32x32x16_bf16 v[32:47], v[148:151], v[124:127], v[32:47]
	v_exp_f32_e32 v88, v88
	v_exp_f32_e32 v89, v89
	s_waitcnt lgkmcnt(4)
	v_mfma_f32_32x32x16_bf16 v[16:31], v[148:151], v[128:131], v[16:31]
	v_exp_f32_e32 v90, v90
	v_exp_f32_e32 v91, v91
	s_waitcnt lgkmcnt(2)
	v_mfma_f32_32x32x16_bf16 v[32:47], v[144:147], v[112:115], v[32:47]
	v_exp_f32_e32 v92, v92
	v_exp_f32_e32 v93, v93
	s_waitcnt lgkmcnt(0)
	v_mfma_f32_32x32x16_bf16 v[16:31], v[144:147], v[6:9], v[16:31]
	v_exp_f32_e32 v94, v94
	v_exp_f32_e32 v95, v95
	s_add_i32 s24, s52, 0x2000
	s_cmpk_lg_i32 s52, 0x4000
	s_cselect_b32 s54, s24, 0
	s_add_u32 s2, s2, 0x40000
	s_addc_u32 s3, s3, 0
	s_add_i32 s24, s28, 2
	s_cmp_ge_u32 s24, s51
	s_cbranch_scc1 .Lrot_exit
	s_mov_b32 s28, s24
	s_mov_b32 s30, s27
	s_mov_b32 s29, s52
	s_mov_b32 s27, s54
	s_waitcnt vmcnt(3) lgkmcnt(0)
	s_barrier
	s_andn2_b64 vcc, exec, s[20:21]
	s_cbranch_vccnz .LBB0_1995
	s_waitcnt lgkmcnt(0)
	ds_read_b128 v[2:5], v0 offset:96
	ds_read_b128 v[6:9], v0 offset:64
	ds_read_b128 v[10:13], v0 offset:32
	ds_read_b128 v[112:115], v0
	s_waitcnt lgkmcnt(3)
	v_mul_f32_e32 v76, v76, v2
	v_mul_f32_e32 v77, v77, v3
	s_waitcnt lgkmcnt(2)
	v_mul_f32_e32 v72, v72, v6
	v_mul_f32_e32 v73, v73, v7
	s_waitcnt lgkmcnt(1)
	v_mul_f32_e32 v68, v68, v10
	v_mul_f32_e32 v69, v69, v11
	v_mul_f32_e32 v78, v78, v4
	v_mul_f32_e32 v79, v79, v5
	v_mul_f32_e32 v74, v74, v8
	v_mul_f32_e32 v75, v75, v9
	v_mul_f32_e32 v70, v70, v12
	v_mul_f32_e32 v71, v71, v13
	s_waitcnt lgkmcnt(0)
	v_mul_f32_e32 v66, v66, v114
	v_mul_f32_e32 v67, v67, v115
	v_mul_f32_e32 v64, v64, v112
	v_mul_f32_e32 v65, v65, v113
	v_mul_f32_e32 v60, v60, v2
	v_mul_f32_e32 v61, v61, v3
	v_mul_f32_e32 v56, v56, v6
	v_mul_f32_e32 v57, v57, v7
	v_mul_f32_e32 v52, v52, v10
	v_mul_f32_e32 v53, v53, v11
	v_mul_f32_e32 v62, v62, v4
	v_mul_f32_e32 v63, v63, v5
	v_mul_f32_e32 v58, v58, v8
	v_mul_f32_e32 v59, v59, v9
	v_mul_f32_e32 v54, v54, v12
	v_mul_f32_e32 v55, v55, v13
	v_mul_f32_e32 v50, v50, v114
	v_mul_f32_e32 v51, v51, v115
	v_mul_f32_e32 v48, v48, v112
	v_mul_f32_e32 v49, v49, v113
	v_mul_f32_e32 v44, v44, v2
	v_mul_f32_e32 v45, v45, v3
	v_mul_f32_e32 v40, v40, v6
	v_mul_f32_e32 v41, v41, v7
	v_mul_f32_e32 v36, v36, v10
	v_mul_f32_e32 v37, v37, v11
	v_mul_f32_e32 v46, v46, v4
	v_mul_f32_e32 v47, v47, v5
	v_mul_f32_e32 v42, v42, v8
	v_mul_f32_e32 v43, v43, v9
	v_mul_f32_e32 v38, v38, v12
	v_mul_f32_e32 v39, v39, v13
	v_mul_f32_e32 v34, v34, v114
	v_mul_f32_e32 v35, v35, v115
	v_mul_f32_e32 v32, v32, v112
	v_mul_f32_e32 v33, v33, v113
	v_mul_f32_e32 v28, v28, v2
	v_mul_f32_e32 v29, v29, v3
	v_mul_f32_e32 v24, v24, v6
	v_mul_f32_e32 v25, v25, v7
	v_mul_f32_e32 v20, v20, v10
	v_mul_f32_e32 v21, v21, v11
	v_mul_f32_e32 v30, v30, v4
	v_mul_f32_e32 v31, v31, v5
	v_mul_f32_e32 v26, v26, v8
	v_mul_f32_e32 v27, v27, v9
	v_mul_f32_e32 v22, v22, v12
	v_mul_f32_e32 v23, v23, v13
	v_mul_f32_e32 v18, v18, v114
	v_mul_f32_e32 v19, v19, v115
	v_mul_f32_e32 v16, v16, v112
	v_mul_f32_e32 v17, v17, v113

.Lrot_exit:
	s_waitcnt vmcnt(3) lgkmcnt(0)
	s_barrier
	s_andn2_b64 vcc, exec, s[20:21]
	s_mov_b32 s20, s24
	s_cbranch_vccnz .Lnegm_exit
	s_waitcnt lgkmcnt(0)
	ds_read_b128 v[2:5], v0 offset:96
	ds_read_b128 v[6:9], v0 offset:64
	ds_read_b128 v[10:13], v0 offset:32
	ds_read_b128 v[112:115], v0
	s_waitcnt lgkmcnt(3)
	v_mul_f32_e32 v76, v76, v2
	v_mul_f32_e32 v77, v77, v3
	s_waitcnt lgkmcnt(2)
	v_mul_f32_e32 v72, v72, v6
	v_mul_f32_e32 v73, v73, v7
	s_waitcnt lgkmcnt(1)
	v_mul_f32_e32 v68, v68, v10
	v_mul_f32_e32 v69, v69, v11
	v_mul_f32_e32 v78, v78, v4
	v_mul_f32_e32 v79, v79, v5
	v_mul_f32_e32 v74, v74, v8
	v_mul_f32_e32 v75, v75, v9
	v_mul_f32_e32 v70, v70, v12
	v_mul_f32_e32 v71, v71, v13
	s_waitcnt lgkmcnt(0)
	v_mul_f32_e32 v66, v66, v114
	v_mul_f32_e32 v67, v67, v115
	v_mul_f32_e32 v64, v64, v112
	v_mul_f32_e32 v65, v65, v113
	v_mul_f32_e32 v60, v60, v2
	v_mul_f32_e32 v61, v61, v3
	v_mul_f32_e32 v56, v56, v6
	v_mul_f32_e32 v57, v57, v7
	v_mul_f32_e32 v52, v52, v10
	v_mul_f32_e32 v53, v53, v11
	v_mul_f32_e32 v62, v62, v4
	v_mul_f32_e32 v63, v63, v5
	v_mul_f32_e32 v58, v58, v8
	v_mul_f32_e32 v59, v59, v9
	v_mul_f32_e32 v54, v54, v12
	v_mul_f32_e32 v55, v55, v13
	v_mul_f32_e32 v50, v50, v114
	v_mul_f32_e32 v51, v51, v115
	v_mul_f32_e32 v48, v48, v112
	v_mul_f32_e32 v49, v49, v113
	v_mul_f32_e32 v44, v44, v2
	v_mul_f32_e32 v45, v45, v3
	v_mul_f32_e32 v40, v40, v6
	v_mul_f32_e32 v41, v41, v7
	v_mul_f32_e32 v36, v36, v10
	v_mul_f32_e32 v37, v37, v11
	v_mul_f32_e32 v46, v46, v4
	v_mul_f32_e32 v47, v47, v5
	v_mul_f32_e32 v42, v42, v8
	v_mul_f32_e32 v43, v43, v9
	v_mul_f32_e32 v38, v38, v12
	v_mul_f32_e32 v39, v39, v13
	v_mul_f32_e32 v34, v34, v114
	v_mul_f32_e32 v35, v35, v115
	v_mul_f32_e32 v32, v32, v112
	v_mul_f32_e32 v33, v33, v113
	v_mul_f32_e32 v28, v28, v2
	v_mul_f32_e32 v29, v29, v3
	v_mul_f32_e32 v24, v24, v6
	v_mul_f32_e32 v25, v25, v7
	v_mul_f32_e32 v20, v20, v10
	v_mul_f32_e32 v21, v21, v11
	v_mul_f32_e32 v30, v30, v4
	v_mul_f32_e32 v31, v31, v5
	v_mul_f32_e32 v26, v26, v8
	v_mul_f32_e32 v27, v27, v9
	v_mul_f32_e32 v22, v22, v12
	v_mul_f32_e32 v23, v23, v13
	v_mul_f32_e32 v18, v18, v114
	v_mul_f32_e32 v19, v19, v115
	v_mul_f32_e32 v16, v16, v112
	v_mul_f32_e32 v17, v17, v113
	s_branch .Lnegm_exit

.LBB0_2019:
	s_waitcnt lgkmcnt(0)
	ds_read_b128 v[2:5], v0 offset:96
	ds_read_b128 v[6:9], v0 offset:64
	ds_read_b128 v[10:13], v0 offset:32
	ds_read_b128 v[80:83], v0
	s_waitcnt lgkmcnt(3)
	v_mul_f32_e32 v76, v76, v2
	v_mul_f32_e32 v77, v77, v3
	s_waitcnt lgkmcnt(2)
	v_mul_f32_e32 v72, v72, v6
	v_mul_f32_e32 v73, v73, v7
	s_waitcnt lgkmcnt(1)
	v_mul_f32_e32 v68, v68, v10
	v_mul_f32_e32 v69, v69, v11
	v_mul_f32_e32 v78, v78, v4
	v_mul_f32_e32 v79, v79, v5
	v_mul_f32_e32 v74, v74, v8
	v_mul_f32_e32 v75, v75, v9
	v_mul_f32_e32 v70, v70, v12
	v_mul_f32_e32 v71, v71, v13
	s_waitcnt lgkmcnt(0)
	v_mul_f32_e32 v66, v66, v82
	v_mul_f32_e32 v67, v67, v83
	v_mul_f32_e32 v64, v64, v80
	v_mul_f32_e32 v65, v65, v81
	v_mul_f32_e32 v60, v60, v2
	v_mul_f32_e32 v61, v61, v3
	v_mul_f32_e32 v56, v56, v6
	v_mul_f32_e32 v57, v57, v7
	v_mul_f32_e32 v52, v52, v10
	v_mul_f32_e32 v53, v53, v11
	v_mul_f32_e32 v62, v62, v4
	v_mul_f32_e32 v63, v63, v5
	v_mul_f32_e32 v58, v58, v8
	v_mul_f32_e32 v59, v59, v9
	v_mul_f32_e32 v54, v54, v12
	v_mul_f32_e32 v55, v55, v13
	v_mul_f32_e32 v50, v50, v82
	v_mul_f32_e32 v51, v51, v83
	v_mul_f32_e32 v48, v48, v80
	v_mul_f32_e32 v49, v49, v81
	v_mul_f32_e32 v44, v44, v2
	v_mul_f32_e32 v45, v45, v3
	v_mul_f32_e32 v40, v40, v6
	v_mul_f32_e32 v41, v41, v7
	v_mul_f32_e32 v36, v36, v10
	v_mul_f32_e32 v37, v37, v11
	v_mul_f32_e32 v46, v46, v4
	v_mul_f32_e32 v47, v47, v5
	v_mul_f32_e32 v42, v42, v8
	v_mul_f32_e32 v43, v43, v9
	v_mul_f32_e32 v38, v38, v12
	v_mul_f32_e32 v39, v39, v13
	v_mul_f32_e32 v34, v34, v82
	v_mul_f32_e32 v35, v35, v83
	v_mul_f32_e32 v32, v32, v80
	v_mul_f32_e32 v33, v33, v81
	v_mul_f32_e32 v28, v28, v2
	v_mul_f32_e32 v29, v29, v3
	v_mul_f32_e32 v24, v24, v6
	v_mul_f32_e32 v25, v25, v7
	v_mul_f32_e32 v20, v20, v10
	v_mul_f32_e32 v21, v21, v11
	v_mul_f32_e32 v30, v30, v4
	v_mul_f32_e32 v31, v31, v5
	v_mul_f32_e32 v26, v26, v8
	v_mul_f32_e32 v27, v27, v9
	v_mul_f32_e32 v22, v22, v12
	v_mul_f32_e32 v23, v23, v13
	v_mul_f32_e32 v18, v18, v82
	v_mul_f32_e32 v19, v19, v83
	v_mul_f32_e32 v16, v16, v80
	v_mul_f32_e32 v17, v17, v81

.LBB0_2038:
	s_waitcnt lgkmcnt(0)
	ds_read_b128 v[2:5], v0 offset:96
	ds_read_b128 v[6:9], v0 offset:64
	ds_read_b128 v[10:13], v0 offset:32
	ds_read_b128 v[112:115], v0
	s_waitcnt lgkmcnt(3)
	v_mul_f32_e32 v76, v76, v2
	v_mul_f32_e32 v77, v77, v3
	s_waitcnt lgkmcnt(2)
	v_mul_f32_e32 v72, v72, v6
	v_mul_f32_e32 v73, v73, v7
	s_waitcnt lgkmcnt(1)
	v_mul_f32_e32 v68, v68, v10
	v_mul_f32_e32 v69, v69, v11
	v_mul_f32_e32 v78, v78, v4
	v_mul_f32_e32 v79, v79, v5
	v_mul_f32_e32 v74, v74, v8
	v_mul_f32_e32 v75, v75, v9
	v_mul_f32_e32 v70, v70, v12
	v_mul_f32_e32 v71, v71, v13
	s_waitcnt lgkmcnt(0)
	v_mul_f32_e32 v66, v66, v114
	v_mul_f32_e32 v67, v67, v115
	v_mul_f32_e32 v64, v64, v112
	v_mul_f32_e32 v65, v65, v113
	v_mul_f32_e32 v60, v60, v2
	v_mul_f32_e32 v61, v61, v3
	v_mul_f32_e32 v56, v56, v6
	v_mul_f32_e32 v57, v57, v7
	v_mul_f32_e32 v52, v52, v10
	v_mul_f32_e32 v53, v53, v11
	v_mul_f32_e32 v62, v62, v4
	v_mul_f32_e32 v63, v63, v5
	v_mul_f32_e32 v58, v58, v8
	v_mul_f32_e32 v59, v59, v9
	v_mul_f32_e32 v54, v54, v12
	v_mul_f32_e32 v55, v55, v13
	v_mul_f32_e32 v50, v50, v114
	v_mul_f32_e32 v51, v51, v115
	v_mul_f32_e32 v48, v48, v112
	v_mul_f32_e32 v49, v49, v113
	v_mul_f32_e32 v44, v44, v2
	v_mul_f32_e32 v45, v45, v3
	v_mul_f32_e32 v40, v40, v6
	v_mul_f32_e32 v41, v41, v7
	v_mul_f32_e32 v36, v36, v10
	v_mul_f32_e32 v37, v37, v11
	v_mul_f32_e32 v46, v46, v4
	v_mul_f32_e32 v47, v47, v5
	v_mul_f32_e32 v42, v42, v8
	v_mul_f32_e32 v43, v43, v9
	v_mul_f32_e32 v38, v38, v12
	v_mul_f32_e32 v39, v39, v13
	v_mul_f32_e32 v34, v34, v114
	v_mul_f32_e32 v35, v35, v115
	v_mul_f32_e32 v32, v32, v112
	v_mul_f32_e32 v33, v33, v113
	v_mul_f32_e32 v28, v28, v2
	v_mul_f32_e32 v29, v29, v3
	v_mul_f32_e32 v24, v24, v6
	v_mul_f32_e32 v25, v25, v7
	v_mul_f32_e32 v20, v20, v10
	v_mul_f32_e32 v21, v21, v11
	v_mul_f32_e32 v30, v30, v4
	v_mul_f32_e32 v31, v31, v5
	v_mul_f32_e32 v26, v26, v8
	v_mul_f32_e32 v27, v27, v9
	v_mul_f32_e32 v22, v22, v12
	v_mul_f32_e32 v23, v23, v13
	v_mul_f32_e32 v18, v18, v114
	v_mul_f32_e32 v19, v19, v115
	v_mul_f32_e32 v16, v16, v112
	v_mul_f32_e32 v17, v17, v113

.LBB0_2062:
	s_waitcnt lgkmcnt(14)
	v_mfma_f32_32x32x16_bf16 v[64:79], v[160:163], v[208:211], v[64:79]
	v_sub_f32_e32 v96, v96, v249
	v_sub_f32_e32 v81, v81, v249
	v_exp_f32_e32 v96, v96
	v_exp_f32_e32 v97, v81
	ds_read_b64_tr_b16 v[112:113], v14 offset:32768
	ds_read_b64_tr_b16 v[114:115], v14 offset:33280
	s_waitcnt lgkmcnt(14)
	v_mfma_f32_32x32x16_bf16 v[48:63], v[160:163], v[204:207], v[48:63]
	v_sub_f32_e32 v81, v98, v249
	v_exp_f32_e32 v98, v81
	v_sub_f32_e32 v81, v99, v249
	v_exp_f32_e32 v99, v81
	ds_read_b64_tr_b16 v[116:117], v14 offset:36864
	ds_read_b64_tr_b16 v[118:119], v14 offset:37376
	s_waitcnt lgkmcnt(14)
	v_mfma_f32_32x32x16_bf16 v[64:79], v[152:155], v[196:199], v[64:79]
	v_sub_f32_e32 v81, v100, v249
	v_exp_f32_e32 v100, v81
	v_sub_f32_e32 v81, v101, v249
	v_exp_f32_e32 v101, v81
	ds_read_b64_tr_b16 v[120:121], v14 offset:33792
	ds_read_b64_tr_b16 v[122:123], v14 offset:34304
	s_waitcnt lgkmcnt(14)
	v_mfma_f32_32x32x16_bf16 v[48:63], v[152:155], v[172:175], v[48:63]
	v_sub_f32_e32 v81, v102, v249
	v_exp_f32_e32 v102, v81
	v_sub_f32_e32 v81, v103, v249
	v_exp_f32_e32 v103, v81
	ds_read_b64_tr_b16 v[124:125], v14 offset:37888
	ds_read_b64_tr_b16 v[126:127], v14 offset:38400
	s_waitcnt lgkmcnt(14)
	v_mfma_f32_32x32x16_bf16 v[64:79], v[148:151], v[168:171], v[64:79]
	v_sub_f32_e32 v81, v104, v249
	v_exp_f32_e32 v104, v81
	v_sub_f32_e32 v81, v105, v249
	v_exp_f32_e32 v105, v81
	ds_read_b64_tr_b16 v[128:129], v14 offset:34816
	ds_read_b64_tr_b16 v[130:131], v14 offset:35328
	s_waitcnt lgkmcnt(14)
	v_mfma_f32_32x32x16_bf16 v[48:63], v[148:151], v[10:13], v[48:63]
	v_sub_f32_e32 v10, v106, v249
	v_exp_f32_e32 v106, v10
	v_sub_f32_e32 v10, v107, v249
	v_exp_f32_e32 v107, v10
	ds_read_b64_tr_b16 v[10:11], v14 offset:38912
	ds_read_b64_tr_b16 v[12:13], v14 offset:39424
	s_waitcnt lgkmcnt(14)
	v_mfma_f32_32x32x16_bf16 v[64:79], v[144:147], v[6:9], v[64:79]
	v_sub_f32_e32 v6, v108, v249
	v_exp_f32_e32 v108, v6
	v_sub_f32_e32 v6, v109, v249
	v_exp_f32_e32 v109, v6
	ds_read_b64_tr_b16 v[6:7], v14 offset:35840
	ds_read_b64_tr_b16 v[8:9], v14 offset:36352
	s_waitcnt lgkmcnt(14)
	v_mfma_f32_32x32x16_bf16 v[48:63], v[144:147], v[2:5], v[48:63]
	v_sub_f32_e32 v2, v110, v249
	v_exp_f32_e32 v110, v2
	v_sub_f32_e32 v2, v111, v249
	v_exp_f32_e32 v111, v2
	ds_read_b64_tr_b16 v[2:3], v14 offset:39936
	ds_read_b64_tr_b16 v[4:5], v14 offset:40448
	s_waitcnt lgkmcnt(14)
	v_mfma_f32_32x32x16_bf16 v[32:47], v[160:163], v[112:115], v[32:47]
	v_sub_f32_e32 v14, v80, v249
	v_exp_f32_e32 v80, v14
	v_sub_f32_e32 v14, v15, v249
	v_exp_f32_e32 v81, v14
	s_waitcnt lgkmcnt(12)
	v_mfma_f32_32x32x16_bf16 v[16:31], v[160:163], v[116:119], v[16:31]
	v_sub_f32_e32 v14, v82, v249
	v_exp_f32_e32 v82, v14
	v_sub_f32_e32 v14, v83, v249
	v_exp_f32_e32 v83, v14
	s_waitcnt lgkmcnt(10)
	v_mfma_f32_32x32x16_bf16 v[32:47], v[152:155], v[120:123], v[32:47]
	v_sub_f32_e32 v14, v84, v249
	v_exp_f32_e32 v84, v14
	v_sub_f32_e32 v14, v85, v249
	v_exp_f32_e32 v85, v14
	s_waitcnt lgkmcnt(8)
	v_mfma_f32_32x32x16_bf16 v[16:31], v[152:155], v[124:127], v[16:31]
	v_sub_f32_e32 v14, v86, v249
	v_exp_f32_e32 v86, v14
	v_sub_f32_e32 v14, v87, v249
	v_exp_f32_e32 v87, v14
	s_waitcnt lgkmcnt(6)
	v_mfma_f32_32x32x16_bf16 v[32:47], v[148:151], v[128:131], v[32:47]
	v_sub_f32_e32 v14, v88, v249
	v_exp_f32_e32 v88, v14
	v_sub_f32_e32 v14, v89, v249
	v_exp_f32_e32 v89, v14
	s_waitcnt lgkmcnt(4)
	v_mfma_f32_32x32x16_bf16 v[16:31], v[148:151], v[10:13], v[16:31]
	v_sub_f32_e32 v10, v90, v249
	v_exp_f32_e32 v90, v10
	v_sub_f32_e32 v10, v91, v249
	v_exp_f32_e32 v91, v10
	s_waitcnt lgkmcnt(2)
	v_mfma_f32_32x32x16_bf16 v[32:47], v[144:147], v[6:9], v[32:47]
	v_sub_f32_e32 v6, v92, v249
	v_exp_f32_e32 v92, v6
	v_sub_f32_e32 v6, v93, v249
	v_exp_f32_e32 v93, v6
	s_waitcnt lgkmcnt(0)
	v_mfma_f32_32x32x16_bf16 v[16:31], v[144:147], v[2:5], v[16:31]
	v_sub_f32_e32 v2, v94, v249
	v_exp_f32_e32 v94, v2
	v_sub_f32_e32 v2, v95, v249
	v_exp_f32_e32 v95, v2
	s_andn2_b64 vcc, exec, s[2:3]
	v_lshl_add_u32 v2, v243, 4, s46
	s_cbranch_vccnz .LBB0_2064
	s_waitcnt lgkmcnt(0)
	ds_read_b128 v[4:7], v2 offset:96
	ds_read_b128 v[8:11], v2 offset:64
	ds_read_b128 v[12:15], v2 offset:32
	ds_read_b128 v[112:115], v2
	s_waitcnt lgkmcnt(3)
	v_mul_f32_e32 v78, v78, v6
	v_mul_f32_e32 v79, v79, v7
	s_waitcnt lgkmcnt(2)
	v_mul_f32_e32 v74, v74, v10
	v_mul_f32_e32 v75, v75, v11
	s_waitcnt lgkmcnt(1)
	v_mul_f32_e32 v70, v70, v14
	v_mul_f32_e32 v71, v71, v15
	s_waitcnt lgkmcnt(0)
	v_mul_f32_e32 v66, v66, v114
	v_mul_f32_e32 v67, v67, v115
	v_mul_f32_e32 v76, v76, v4
	v_mul_f32_e32 v77, v77, v5
	v_mul_f32_e32 v72, v72, v8
	v_mul_f32_e32 v73, v73, v9
	v_mul_f32_e32 v68, v68, v12
	v_mul_f32_e32 v69, v69, v13
	v_mul_f32_e32 v64, v64, v112
	v_mul_f32_e32 v65, v65, v113
	v_mul_f32_e32 v62, v62, v6
	v_mul_f32_e32 v63, v63, v7
	v_mul_f32_e32 v58, v58, v10
	v_mul_f32_e32 v59, v59, v11
	v_mul_f32_e32 v54, v54, v14
	v_mul_f32_e32 v55, v55, v15
	v_mul_f32_e32 v50, v50, v114
	v_mul_f32_e32 v51, v51, v115
	v_mul_f32_e32 v60, v60, v4
	v_mul_f32_e32 v61, v61, v5
	v_mul_f32_e32 v56, v56, v8
	v_mul_f32_e32 v57, v57, v9
	v_mul_f32_e32 v52, v52, v12
	v_mul_f32_e32 v53, v53, v13
	v_mul_f32_e32 v48, v48, v112
	v_mul_f32_e32 v49, v49, v113
	v_mul_f32_e32 v46, v46, v6
	v_mul_f32_e32 v47, v47, v7
	v_mul_f32_e32 v42, v42, v10
	v_mul_f32_e32 v43, v43, v11
	v_mul_f32_e32 v38, v38, v14
	v_mul_f32_e32 v39, v39, v15
	v_mul_f32_e32 v34, v34, v114
	v_mul_f32_e32 v35, v35, v115
	v_mul_f32_e32 v44, v44, v4
	v_mul_f32_e32 v45, v45, v5
	v_mul_f32_e32 v40, v40, v8
	v_mul_f32_e32 v41, v41, v9
	v_mul_f32_e32 v36, v36, v12
	v_mul_f32_e32 v37, v37, v13
	v_mul_f32_e32 v32, v32, v112
	v_mul_f32_e32 v33, v33, v113
	v_mul_f32_e32 v30, v30, v6
	v_mul_f32_e32 v31, v31, v7
	v_mul_f32_e32 v26, v26, v10
	v_mul_f32_e32 v27, v27, v11
	v_mul_f32_e32 v22, v22, v14
	v_mul_f32_e32 v23, v23, v15
	v_mul_f32_e32 v18, v18, v114
	v_mul_f32_e32 v19, v19, v115
	v_mul_f32_e32 v28, v28, v4
	v_mul_f32_e32 v29, v29, v5
	v_mul_f32_e32 v24, v24, v8
	v_mul_f32_e32 v25, v25, v9
	v_mul_f32_e32 v20, v20, v12
	v_mul_f32_e32 v21, v21, v13
	v_mul_f32_e32 v16, v16, v112
	v_mul_f32_e32 v17, v17, v113

.LBB0_2127:
	s_ashr_i32 s5, s4, 31
	s_lshl_b64 s[8:9], s[4:5], 11
	v_or_b32_e32 v2, s8, v0
	v_mov_b32_e32 v3, s9
	v_lshl_add_u64 v[4:5], s[0:1], 0, v[2:3]
	v_lshl_add_u64 v[2:3], s[2:3], 0, v[2:3]
	global_load_dwordx4 v[44:47], v[4:5], off offset:16
	global_load_dwordx4 v[48:51], v[4:5], off
	global_load_dwordx4 v[52:55], v[2:3], off offset:16
	global_load_dwordx4 v[56:59], v[2:3], off
	s_add_i32 s4, s4, s10
	s_ashr_i32 s5, s4, 31
	s_lshl_b64 s[6:7], s[4:5], 11
	v_or_b32_e32 v6, s6, v0
	v_mov_b32_e32 v7, s7
	v_lshl_add_u64 v[8:9], s[0:1], 0, v[6:7]
	v_lshl_add_u64 v[14:15], s[2:3], 0, v[6:7]
	global_load_dwordx4 v[2:5], v[8:9], off offset:16
	global_load_dwordx4 v[10:13], v[8:9], off
	s_nop 0
	global_load_dwordx4 v[6:9], v[14:15], off offset:16
	s_nop 0
	global_load_dwordx4 v[14:17], v[14:15], off
	s_add_i32 s4, s4, s10
	s_cmp_lt_i32 s4, 0x8000
	s_waitcnt vmcnt(6)
	v_lshlrev_b32_e32 v22, 16, v48
	s_waitcnt vmcnt(4)
	v_lshlrev_b32_e32 v23, 16, v56
	v_fma_f32 v43, -v18, v23, v22
	v_and_b32_e32 v22, 0xffff0000, v48
	v_and_b32_e32 v23, 0xffff0000, v56
	v_fma_f32 v48, -v18, v23, v22
	v_lshlrev_b32_e32 v23, 16, v49
	v_lshlrev_b32_e32 v56, 16, v57
	v_fma_f32 v56, -v18, v56, v23
	v_and_b32_e32 v23, 0xffff0000, v49
	v_and_b32_e32 v49, 0xffff0000, v57
	v_mul_f32_e32 v22, v43, v43
	v_fma_f32 v49, -v18, v49, v23
	v_mul_f32_e32 v23, v56, v56
	v_fmac_f32_e32 v22, v48, v48
	v_fmac_f32_e32 v23, v49, v49
	v_add_f32_e32 v22, v22, v23
	v_lshlrev_b32_e32 v23, 16, v50
	v_lshlrev_b32_e32 v57, 16, v58
	v_fma_f32 v57, -v18, v57, v23
	v_and_b32_e32 v23, 0xffff0000, v50
	v_and_b32_e32 v50, 0xffff0000, v58
	v_fma_f32 v58, -v18, v50, v23
	v_mul_f32_e32 v23, v57, v57
	v_fmac_f32_e32 v23, v58, v58
	v_add_f32_e32 v22, v23, v22
	v_lshlrev_b32_e32 v23, 16, v51
	v_lshlrev_b32_e32 v50, 16, v59
	v_fma_f32 v60, -v18, v50, v23
	v_and_b32_e32 v23, 0xffff0000, v51
	v_and_b32_e32 v50, 0xffff0000, v59
	v_fma_f32 v59, -v18, v50, v23
	v_mul_f32_e32 v23, v60, v60
	v_fmac_f32_e32 v23, v59, v59
	v_add_f32_e32 v22, v23, v22
	v_lshlrev_b32_e32 v23, 16, v44
	v_lshlrev_b32_e32 v50, 16, v52
	v_fma_f32 v61, -v18, v50, v23
	v_and_b32_e32 v23, 0xffff0000, v44
	v_and_b32_e32 v44, 0xffff0000, v52
	v_fma_f32 v52, -v18, v44, v23
	v_mul_f32_e32 v23, v61, v61
	v_fmac_f32_e32 v23, v52, v52
	v_add_f32_e32 v22, v23, v22
	v_lshlrev_b32_e32 v23, 16, v45
	v_lshlrev_b32_e32 v44, 16, v53
	v_fma_f32 v62, -v18, v44, v23
	v_and_b32_e32 v23, 0xffff0000, v45
	v_and_b32_e32 v44, 0xffff0000, v53
	v_fma_f32 v53, -v18, v44, v23
	v_mul_f32_e32 v23, v62, v62
	v_fmac_f32_e32 v23, v53, v53
	v_add_f32_e32 v63, v23, v22
	v_lshlrev_b32_e32 v23, 16, v47
	v_lshlrev_b32_e32 v22, 16, v46
	v_lshlrev_b32_e32 v45, 16, v55
	v_lshlrev_b32_e32 v44, 16, v54
	v_fma_f32 v22, -v18, v44, v22
	v_fma_f32 v23, -v19, v45, v23
	v_and_b32_e32 v45, 0xffff0000, v47
	v_and_b32_e32 v44, 0xffff0000, v46
	v_and_b32_e32 v47, 0xffff0000, v55
	v_and_b32_e32 v46, 0xffff0000, v54
	v_fma_f32 v50, -v18, v46, v44
	v_fma_f32 v51, -v19, v47, v45
	v_mul_f32_e32 v44, v22, v22
	v_mul_f32_e32 v45, v23, v23
	s_nop 0
	v_fma_f32 v44, v50, v50, v44
	v_fma_f32 v45, v51, v51, v45
	s_nop 0
	v_add_f32_e32 v44, v44, v63
	v_add_f32_e32 v44, v45, v44
	ds_bpermute_b32 v45, v24, v44
	s_waitcnt lgkmcnt(0)
	v_add_f32_e32 v44, v44, v45
	ds_bpermute_b32 v45, v25, v44
	s_waitcnt lgkmcnt(0)
	v_add_f32_e32 v44, v44, v45
	ds_bpermute_b32 v45, v26, v44
	s_waitcnt lgkmcnt(0)
	v_add_f32_e32 v44, v44, v45
	v_fmamk_f32 v44, v44, 0x3c000000, v230
	v_rsq_f32_e32 v54, v44
	s_nop 0
	v_mul_f32_e32 v43, v43, v54
	v_mul_f32_e32 v44, v48, v54
	v_mul_f32_e32 v43, v27, v43
	v_mul_f32_e32 v44, v28, v44
	v_cvt_pk_bf16_f32 v44, v43, v44
	v_mul_f32_e32 v43, v56, v54
	v_mul_f32_e32 v45, v49, v54
	v_mul_f32_e32 v43, v29, v43
	v_mul_f32_e32 v45, v30, v45
	v_cvt_pk_bf16_f32 v45, v43, v45
	v_mul_f32_e32 v43, v57, v54
	v_mul_f32_e32 v46, v58, v54
	v_mul_f32_e32 v43, v31, v43
	v_mul_f32_e32 v46, v32, v46
	v_cvt_pk_bf16_f32 v46, v43, v46
	v_mul_f32_e32 v43, v60, v54
	v_mul_f32_e32 v47, v59, v54
	v_mul_f32_e32 v43, v33, v43
	v_mul_f32_e32 v47, v34, v47
	v_cvt_pk_bf16_f32 v47, v43, v47
	v_mul_f32_e32 v43, v61, v54
	v_mul_f32_e32 v48, v52, v54
	v_mul_f32_e32 v43, v35, v43
	v_mul_f32_e32 v48, v36, v48
	v_cvt_pk_bf16_f32 v48, v43, v48
	v_mul_f32_e32 v43, v62, v54
	v_mul_f32_e32 v49, v53, v54
	v_mul_f32_e32 v43, v37, v43
	v_mul_f32_e32 v49, v38, v49
	v_mul_f32_e32 v22, v22, v54
	v_cvt_pk_bf16_f32 v49, v43, v49
	v_mul_f32_e32 v22, v39, v22
	v_mul_f32_e32 v43, v50, v54
	v_mul_f32_e32 v43, v40, v43
	v_cvt_pk_bf16_f32 v50, v22, v43
	v_mul_f32_e32 v22, v23, v54
	v_mul_f32_e32 v23, v51, v54
	v_mul_f32_e32 v22, v41, v22
	v_mul_f32_e32 v23, v42, v23
	v_cvt_pk_bf16_f32 v51, v22, v23
	v_lshl_add_u64 v[22:23], v[20:21], 0, s[8:9]
	global_store_dwordx4 v[22:23], v[44:47], off
	global_store_dwordx4 v[22:23], v[48:51], off offset:16
	s_waitcnt vmcnt(4)
	v_lshlrev_b32_e32 v22, 16, v10
	s_waitcnt vmcnt(2)
	v_lshlrev_b32_e32 v23, 16, v14
	v_fma_f32 v22, -v18, v23, v22
	v_lshlrev_b32_e32 v23, 16, v11
	v_lshlrev_b32_e32 v43, 16, v15
	v_and_b32_e32 v10, 0xffff0000, v10
	v_and_b32_e32 v14, 0xffff0000, v14
	v_fma_f32 v23, -v18, v43, v23
	v_and_b32_e32 v11, 0xffff0000, v11
	v_and_b32_e32 v15, 0xffff0000, v15
	v_fma_f32 v14, -v18, v14, v10
	v_mul_f32_e32 v10, v22, v22
	v_fma_f32 v15, -v18, v15, v11
	v_mul_f32_e32 v11, v23, v23
	v_fmac_f32_e32 v10, v14, v14
	v_fmac_f32_e32 v11, v15, v15
	v_add_f32_e32 v10, v10, v11
	v_lshlrev_b32_e32 v11, 16, v12
	v_lshlrev_b32_e32 v43, 16, v16
	v_fma_f32 v43, -v18, v43, v11
	v_and_b32_e32 v11, 0xffff0000, v12
	v_and_b32_e32 v12, 0xffff0000, v16
	v_fma_f32 v12, -v18, v12, v11
	v_mul_f32_e32 v11, v43, v43
	v_fmac_f32_e32 v11, v12, v12
	v_add_f32_e32 v10, v11, v10
	v_lshlrev_b32_e32 v11, 16, v13
	v_lshlrev_b32_e32 v16, 16, v17
	v_fma_f32 v16, -v18, v16, v11
	v_and_b32_e32 v11, 0xffff0000, v13
	v_and_b32_e32 v13, 0xffff0000, v17
	v_fma_f32 v13, -v18, v13, v11
	v_mul_f32_e32 v11, v16, v16
	v_fmac_f32_e32 v11, v13, v13
	v_add_f32_e32 v10, v11, v10
	v_lshlrev_b32_e32 v11, 16, v2
	v_lshlrev_b32_e32 v17, 16, v6
	v_fma_f32 v17, -v18, v17, v11
	v_and_b32_e32 v2, 0xffff0000, v2
	v_and_b32_e32 v6, 0xffff0000, v6
	v_fma_f32 v44, -v18, v6, v2
	v_mul_f32_e32 v2, v17, v17
	v_fmac_f32_e32 v2, v44, v44
	v_add_f32_e32 v2, v2, v10
	v_lshlrev_b32_e32 v6, 16, v3
	v_lshlrev_b32_e32 v10, 16, v7
	v_fma_f32 v45, -v18, v10, v6
	v_and_b32_e32 v3, 0xffff0000, v3
	v_and_b32_e32 v6, 0xffff0000, v7
	v_fma_f32 v46, -v18, v6, v3
	v_mul_f32_e32 v3, v45, v45
	v_fmac_f32_e32 v3, v46, v46
	v_add_f32_e32 v47, v3, v2
	v_lshlrev_b32_e32 v3, 16, v5
	v_lshlrev_b32_e32 v2, 16, v4
	v_lshlrev_b32_e32 v7, 16, v9
	v_lshlrev_b32_e32 v6, 16, v8
	v_fma_f32 v10, -v18, v6, v2
	v_fma_f32 v11, -v19, v7, v3
	v_and_b32_e32 v3, 0xffff0000, v5
	v_and_b32_e32 v2, 0xffff0000, v4
	v_and_b32_e32 v5, 0xffff0000, v9
	v_and_b32_e32 v4, 0xffff0000, v8
	v_fma_f32 v8, -v18, v4, v2
	v_fma_f32 v9, -v19, v5, v3
	v_mul_f32_e32 v2, v10, v10
	v_mul_f32_e32 v3, v11, v11
	s_nop 0
	v_fma_f32 v2, v8, v8, v2
	v_fma_f32 v3, v9, v9, v3
	s_nop 0
	v_add_f32_e32 v2, v2, v47
	v_add_f32_e32 v2, v3, v2
	ds_bpermute_b32 v3, v24, v2
	s_waitcnt lgkmcnt(0)
	v_add_f32_e32 v2, v2, v3
	ds_bpermute_b32 v3, v25, v2
	s_waitcnt lgkmcnt(0)
	v_add_f32_e32 v2, v2, v3
	ds_bpermute_b32 v3, v26, v2
	s_waitcnt lgkmcnt(0)
	v_add_f32_e32 v2, v2, v3
	v_fmamk_f32 v2, v2, 0x3c000000, v230
	v_rsq_f32_e32 v47, v2
	s_nop 0
	v_mul_f32_e32 v2, v22, v47
	v_mul_f32_e32 v3, v14, v47
	v_mul_f32_e32 v2, v27, v2
	v_mul_f32_e32 v3, v28, v3
	v_cvt_pk_bf16_f32 v2, v2, v3
	v_mul_f32_e32 v3, v23, v47
	v_mul_f32_e32 v4, v15, v47
	v_mul_f32_e32 v3, v29, v3
	v_mul_f32_e32 v4, v30, v4
	v_cvt_pk_bf16_f32 v3, v3, v4
	v_mul_f32_e32 v4, v43, v47
	v_mul_f32_e32 v5, v12, v47
	v_mul_f32_e32 v4, v31, v4
	v_mul_f32_e32 v5, v32, v5
	v_cvt_pk_bf16_f32 v4, v4, v5
	v_mul_f32_e32 v5, v16, v47
	v_mul_f32_e32 v6, v13, v47
	v_mul_f32_e32 v5, v33, v5
	v_mul_f32_e32 v6, v34, v6
	v_cvt_pk_bf16_f32 v5, v5, v6
	v_mul_f32_e32 v6, v17, v47
	v_mul_f32_e32 v7, v44, v47
	v_mul_f32_e32 v6, v35, v6
	v_mul_f32_e32 v7, v36, v7
	v_cvt_pk_bf16_f32 v6, v6, v7
	v_mul_f32_e32 v7, v45, v47
	v_mul_f32_e32 v10, v10, v47
	v_mul_f32_e32 v8, v8, v47
	v_mul_f32_e32 v7, v37, v7
	v_mul_f32_e32 v12, v46, v47
	v_mul_f32_e32 v10, v39, v10
	v_mul_f32_e32 v8, v40, v8
	v_mul_f32_e32 v12, v38, v12
	v_cvt_pk_bf16_f32 v7, v7, v12
	v_cvt_pk_bf16_f32 v8, v10, v8
	v_mul_f32_e32 v10, v11, v47
	v_mul_f32_e32 v9, v9, v47
	v_mul_f32_e32 v10, v41, v10
	v_mul_f32_e32 v9, v42, v9
	v_cvt_pk_bf16_f32 v9, v10, v9
	v_lshl_add_u64 v[10:11], v[20:21], 0, s[6:7]
	global_store_dwordx4 v[10:11], v[2:5], off
	global_store_dwordx4 v[10:11], v[6:9], off offset:16
	s_cbranch_scc1 .LBB0_2127

.LBB0_2202:
	v_lshl_add_u32 v130, s0, 8, v141
	v_ashrrev_i32_e32 v131, 31, v130
	s_lshl_b32 s0, s1, 8
	v_lshlrev_b64 v[130:131], 10, v[130:131]
	s_ashr_i32 s1, s0, 31
	v_lshl_add_u64 v[130:131], v[130:131], 0, s[0:1]
	v_or_b32_e32 v130, v130, v140
	v_lshlrev_b64 v[146:147], 1, v[130:131]
	v_lshl_add_u64 v[148:149], s[6:7], 0, v[146:147]
	global_load_dwordx4 v[152:155], v[148:149], off
	global_load_dwordx4 v[156:159], v[148:149], off offset:256
	v_add_co_u32_e32 v160, vcc, s75, v148
	v_lshl_add_u64 v[146:147], s[4:5], 0, v[146:147]
	s_nop 0
	v_addc_co_u32_e32 v161, vcc, 0, v149, vcc
	global_load_dwordx4 v[130:133], v[160:161], off offset:256
	s_nop 0
	global_load_dwordx4 v[160:163], v[160:161], off
	s_mov_b32 s0, 0x10000
	s_mov_b32 s1, 0x18000
	s_mov_b64 s[50:51], 0x10000
	s_waitcnt vmcnt(0)
	v_lshlrev_b32_e32 v164, 16, v152
	v_and_b32_e32 v165, 0xffff0000, v152
	v_lshlrev_b32_e32 v152, 16, v153
	v_and_b32_e32 v153, 0xffff0000, v153
	v_lshlrev_b32_e32 v166, 16, v154
	v_and_b32_e32 v167, 0xffff0000, v154
	v_lshlrev_b32_e32 v154, 16, v155
	v_and_b32_e32 v155, 0xffff0000, v155
	v_mul_f32_e32 v128, v128, v152
	v_mul_f32_e32 v129, v129, v153
	v_mul_f32_e32 v126, v126, v164
	v_mul_f32_e32 v127, v127, v165
	v_mul_f32_e32 v152, v124, v154
	v_mul_f32_e32 v153, v125, v155
	v_mul_f32_e32 v124, v122, v166
	v_mul_f32_e32 v125, v123, v167
	v_cvt_pk_bf16_f32 v122, v126, v127
	v_cvt_pk_bf16_f32 v123, v128, v129
	v_lshlrev_b32_e32 v126, 16, v158
	v_cvt_pk_bf16_f32 v124, v124, v125
	v_cvt_pk_bf16_f32 v125, v152, v153
	global_store_dwordx4 v[146:147], v[122:125], off
	v_and_b32_e32 v127, 0xffff0000, v158
	v_lshlrev_b32_e32 v128, 16, v159
	v_lshlrev_b32_e32 v122, 16, v156
	v_and_b32_e32 v123, 0xffff0000, v156
	v_and_b32_e32 v129, 0xffff0000, v159
	v_lshlrev_b32_e32 v124, 16, v157
	v_and_b32_e32 v125, 0xffff0000, v157
	v_mul_f32_e32 v118, v118, v122
	v_mul_f32_e32 v119, v119, v123
	v_mul_f32_e32 v122, v116, v128
	v_mul_f32_e32 v123, v117, v129
	v_mul_f32_e32 v116, v114, v126
	v_mul_f32_e32 v117, v115, v127
	v_mul_f32_e32 v120, v120, v124
	v_mul_f32_e32 v121, v121, v125
	v_cvt_pk_bf16_f32 v114, v118, v119
	v_add_co_u32_e32 v118, vcc, s0, v148
	v_cvt_pk_bf16_f32 v115, v120, v121
	v_cvt_pk_bf16_f32 v116, v116, v117
	v_cvt_pk_bf16_f32 v117, v122, v123
	global_store_dwordx4 v[146:147], v[114:117], off offset:256
	v_lshlrev_b32_e32 v122, 16, v160
	v_and_b32_e32 v123, 0xffff0000, v160
	v_addc_co_u32_e32 v119, vcc, 0, v149, vcc
	v_lshlrev_b32_e32 v126, 16, v162
	v_and_b32_e32 v127, 0xffff0000, v162
	v_lshlrev_b32_e32 v128, 16, v163
	v_and_b32_e32 v129, 0xffff0000, v163
	v_mul_f32_e32 v110, v110, v122
	v_mul_f32_e32 v111, v111, v123
	global_load_dwordx4 v[114:117], v[118:119], off offset:256
	s_nop 0
	global_load_dwordx4 v[118:121], v[118:119], off
	v_lshlrev_b32_e32 v124, 16, v161
	v_and_b32_e32 v125, 0xffff0000, v161
	v_mul_f32_e32 v122, v108, v128
	v_mul_f32_e32 v123, v109, v129
	v_mul_f32_e32 v108, v106, v126
	v_mul_f32_e32 v109, v107, v127
	v_cvt_pk_bf16_f32 v106, v110, v111
	v_add_co_u32_e32 v110, vcc, s75, v146
	v_mul_f32_e32 v112, v112, v124
	v_mul_f32_e32 v113, v113, v125
	s_nop 0
	v_addc_co_u32_e32 v111, vcc, 0, v147, vcc
	v_cvt_pk_bf16_f32 v107, v112, v113
	v_cvt_pk_bf16_f32 v108, v108, v109
	v_cvt_pk_bf16_f32 v109, v122, v123
	global_store_dwordx4 v[110:111], v[106:109], off
	v_lshlrev_b32_e32 v112, 16, v132
	v_and_b32_e32 v113, 0xffff0000, v132
	v_lshlrev_b32_e32 v106, 16, v130
	v_and_b32_e32 v107, 0xffff0000, v130
	v_lshlrev_b32_e32 v122, 16, v133
	v_and_b32_e32 v123, 0xffff0000, v133
	v_lshlrev_b32_e32 v108, 16, v131
	v_and_b32_e32 v109, 0xffff0000, v131
	v_mul_f32_e32 v102, v102, v106
	v_mul_f32_e32 v103, v103, v107
	v_mul_f32_e32 v106, v100, v122
	v_mul_f32_e32 v107, v101, v123
	v_mul_f32_e32 v100, v98, v112
	v_mul_f32_e32 v101, v99, v113
	v_mul_f32_e32 v104, v104, v108
	v_mul_f32_e32 v105, v105, v109
	v_cvt_pk_bf16_f32 v98, v102, v103
	v_add_co_u32_e32 v102, vcc, s1, v148
	v_cvt_pk_bf16_f32 v99, v104, v105
	v_cvt_pk_bf16_f32 v100, v100, v101
	v_cvt_pk_bf16_f32 v101, v106, v107
	global_store_dwordx4 v[110:111], v[98:101], off offset:256
	s_nop 0
	v_addc_co_u32_e32 v103, vcc, 0, v149, vcc
	global_load_dwordx4 v[98:101], v[102:103], off offset:256
	s_nop 0
	global_load_dwordx4 v[102:105], v[102:103], off
	s_waitcnt vmcnt(4)
	v_lshlrev_b32_e32 v106, 16, v118
	v_and_b32_e32 v107, 0xffff0000, v118
	v_lshlrev_b32_e32 v110, 16, v120
	v_and_b32_e32 v111, 0xffff0000, v120
	v_lshlrev_b32_e32 v112, 16, v121
	v_and_b32_e32 v113, 0xffff0000, v121
	v_mul_f32_e32 v94, v94, v106
	v_mul_f32_e32 v95, v95, v107
	v_lshlrev_b32_e32 v108, 16, v119
	v_and_b32_e32 v109, 0xffff0000, v119
	v_mul_f32_e32 v106, v92, v112
	v_mul_f32_e32 v107, v93, v113
	v_mul_f32_e32 v92, v90, v110
	v_mul_f32_e32 v93, v91, v111
	v_cvt_pk_bf16_f32 v90, v94, v95
	v_add_co_u32_e32 v94, vcc, s0, v146
	v_mul_f32_e32 v96, v96, v108
	v_mul_f32_e32 v97, v97, v109
	s_nop 0
	v_addc_co_u32_e32 v95, vcc, 0, v147, vcc
	v_cvt_pk_bf16_f32 v91, v96, v97
	v_cvt_pk_bf16_f32 v92, v92, v93
	v_cvt_pk_bf16_f32 v93, v106, v107
	global_store_dwordx4 v[94:95], v[90:93], off
	v_lshlrev_b32_e32 v96, 16, v116
	v_and_b32_e32 v97, 0xffff0000, v116
	v_lshlrev_b32_e32 v90, 16, v114
	v_and_b32_e32 v91, 0xffff0000, v114
	v_lshlrev_b32_e32 v106, 16, v117
	v_and_b32_e32 v107, 0xffff0000, v117
	v_lshlrev_b32_e32 v92, 16, v115
	v_and_b32_e32 v93, 0xffff0000, v115
	v_mul_f32_e32 v86, v86, v90
	v_mul_f32_e32 v87, v87, v91
	v_mul_f32_e32 v90, v84, v106
	v_mul_f32_e32 v91, v85, v107
	v_mul_f32_e32 v84, v82, v96
	v_mul_f32_e32 v85, v83, v97
	s_mov_b32 s0, 0x40000
	v_mul_f32_e32 v88, v88, v92
	v_mul_f32_e32 v89, v89, v93
	v_cvt_pk_bf16_f32 v82, v86, v87
	v_add_co_u32_e32 v86, vcc, s0, v148
	v_cvt_pk_bf16_f32 v83, v88, v89
	v_cvt_pk_bf16_f32 v84, v84, v85
	v_cvt_pk_bf16_f32 v85, v90, v91
	global_store_dwordx4 v[94:95], v[82:85], off offset:256
	s_waitcnt vmcnt(2)
	v_lshlrev_b32_e32 v90, 16, v102
	v_and_b32_e32 v91, 0xffff0000, v102
	v_addc_co_u32_e32 v87, vcc, 0, v149, vcc
	v_lshlrev_b32_e32 v94, 16, v104
	v_and_b32_e32 v95, 0xffff0000, v104
	v_lshlrev_b32_e32 v96, 16, v105
	v_and_b32_e32 v97, 0xffff0000, v105
	v_mul_f32_e32 v78, v78, v90
	v_mul_f32_e32 v79, v79, v91
	global_load_dwordx4 v[82:85], v[86:87], off offset:256
	s_nop 0
	global_load_dwordx4 v[86:89], v[86:87], off
	v_lshlrev_b32_e32 v92, 16, v103
	v_and_b32_e32 v93, 0xffff0000, v103
	v_mul_f32_e32 v90, v76, v96
	v_mul_f32_e32 v91, v77, v97
	v_mul_f32_e32 v76, v74, v94
	v_mul_f32_e32 v77, v75, v95
	v_cvt_pk_bf16_f32 v74, v78, v79
	v_add_co_u32_e32 v78, vcc, s1, v146
	v_mul_f32_e32 v80, v80, v92
	v_mul_f32_e32 v81, v81, v93
	s_nop 0
	v_addc_co_u32_e32 v79, vcc, 0, v147, vcc
	v_cvt_pk_bf16_f32 v75, v80, v81
	v_cvt_pk_bf16_f32 v76, v76, v77
	v_cvt_pk_bf16_f32 v77, v90, v91
	global_store_dwordx4 v[78:79], v[74:77], off
	v_lshlrev_b32_e32 v80, 16, v100
	v_and_b32_e32 v81, 0xffff0000, v100
	v_lshlrev_b32_e32 v74, 16, v98
	v_and_b32_e32 v75, 0xffff0000, v98
	v_lshlrev_b32_e32 v90, 16, v101
	v_and_b32_e32 v91, 0xffff0000, v101
	v_lshlrev_b32_e32 v76, 16, v99
	v_and_b32_e32 v77, 0xffff0000, v99
	v_mul_f32_e32 v70, v70, v74
	v_mul_f32_e32 v71, v71, v75
	v_mul_f32_e32 v74, v68, v90
	v_mul_f32_e32 v75, v69, v91
	v_mul_f32_e32 v68, v66, v80
	v_mul_f32_e32 v69, v67, v81
	s_mov_b32 s1, 0x48000
	v_mul_f32_e32 v72, v72, v76
	v_mul_f32_e32 v73, v73, v77
	v_cvt_pk_bf16_f32 v66, v70, v71
	v_add_co_u32_e32 v70, vcc, s1, v148
	v_cvt_pk_bf16_f32 v67, v72, v73
	v_cvt_pk_bf16_f32 v68, v68, v69
	v_cvt_pk_bf16_f32 v69, v74, v75
	global_store_dwordx4 v[78:79], v[66:69], off offset:256
	s_nop 0
	v_addc_co_u32_e32 v71, vcc, 0, v149, vcc
	global_load_dwordx4 v[66:69], v[70:71], off offset:256
	s_nop 0
	global_load_dwordx4 v[70:73], v[70:71], off
	s_waitcnt vmcnt(4)
	v_lshlrev_b32_e32 v74, 16, v86
	v_and_b32_e32 v75, 0xffff0000, v86
	v_lshlrev_b32_e32 v78, 16, v88
	v_and_b32_e32 v79, 0xffff0000, v88
	v_lshlrev_b32_e32 v80, 16, v89
	v_and_b32_e32 v81, 0xffff0000, v89
	v_mul_f32_e32 v62, v62, v74
	v_mul_f32_e32 v63, v63, v75
	v_lshlrev_b32_e32 v76, 16, v87
	v_and_b32_e32 v77, 0xffff0000, v87
	v_mul_f32_e32 v74, v60, v80
	v_mul_f32_e32 v75, v61, v81
	v_mul_f32_e32 v60, v58, v78
	v_mul_f32_e32 v61, v59, v79
	v_cvt_pk_bf16_f32 v58, v62, v63
	v_add_co_u32_e32 v62, vcc, s0, v146
	v_mul_f32_e32 v64, v64, v76
	v_mul_f32_e32 v65, v65, v77
	s_nop 0
	v_addc_co_u32_e32 v63, vcc, 0, v147, vcc
	v_cvt_pk_bf16_f32 v59, v64, v65
	v_cvt_pk_bf16_f32 v60, v60, v61
	v_cvt_pk_bf16_f32 v61, v74, v75
	global_store_dwordx4 v[62:63], v[58:61], off
	v_lshlrev_b32_e32 v64, 16, v84
	v_and_b32_e32 v65, 0xffff0000, v84
	v_lshlrev_b32_e32 v58, 16, v82
	v_and_b32_e32 v59, 0xffff0000, v82
	v_lshlrev_b32_e32 v74, 16, v85
	v_and_b32_e32 v75, 0xffff0000, v85
	v_lshlrev_b32_e32 v60, 16, v83
	v_and_b32_e32 v61, 0xffff0000, v83
	v_mul_f32_e32 v54, v54, v58
	v_mul_f32_e32 v55, v55, v59
	v_mul_f32_e32 v58, v52, v74
	v_mul_f32_e32 v59, v53, v75
	v_mul_f32_e32 v52, v50, v64
	v_mul_f32_e32 v53, v51, v65
	s_mov_b32 s0, 0x50000
	v_mul_f32_e32 v56, v56, v60
	v_mul_f32_e32 v57, v57, v61
	v_cvt_pk_bf16_f32 v50, v54, v55
	v_add_co_u32_e32 v54, vcc, s0, v148
	v_cvt_pk_bf16_f32 v51, v56, v57
	v_cvt_pk_bf16_f32 v52, v52, v53
	v_cvt_pk_bf16_f32 v53, v58, v59
	global_store_dwordx4 v[62:63], v[50:53], off offset:256
	s_waitcnt vmcnt(2)
	v_lshlrev_b32_e32 v58, 16, v70
	v_and_b32_e32 v59, 0xffff0000, v70
	v_addc_co_u32_e32 v55, vcc, 0, v149, vcc
	v_lshlrev_b32_e32 v62, 16, v72
	v_and_b32_e32 v63, 0xffff0000, v72
	v_lshlrev_b32_e32 v64, 16, v73
	v_and_b32_e32 v65, 0xffff0000, v73
	v_mul_f32_e32 v46, v46, v58
	v_mul_f32_e32 v47, v47, v59
	global_load_dwordx4 v[50:53], v[54:55], off offset:256
	s_nop 0
	global_load_dwordx4 v[54:57], v[54:55], off
	v_lshlrev_b32_e32 v60, 16, v71
	v_and_b32_e32 v61, 0xffff0000, v71
	v_mul_f32_e32 v58, v44, v64
	v_mul_f32_e32 v59, v45, v65
	v_mul_f32_e32 v44, v42, v62
	v_mul_f32_e32 v45, v43, v63
	v_cvt_pk_bf16_f32 v42, v46, v47
	v_add_co_u32_e32 v46, vcc, s1, v146
	v_mul_f32_e32 v48, v48, v60
	v_mul_f32_e32 v49, v49, v61
	s_nop 0
	v_addc_co_u32_e32 v47, vcc, 0, v147, vcc
	v_cvt_pk_bf16_f32 v43, v48, v49
	v_cvt_pk_bf16_f32 v44, v44, v45
	v_cvt_pk_bf16_f32 v45, v58, v59
	global_store_dwordx4 v[46:47], v[42:45], off
	v_lshlrev_b32_e32 v48, 16, v68
	v_and_b32_e32 v49, 0xffff0000, v68
	v_lshlrev_b32_e32 v42, 16, v66
	v_and_b32_e32 v43, 0xffff0000, v66
	v_lshlrev_b32_e32 v58, 16, v69
	v_and_b32_e32 v59, 0xffff0000, v69
	v_lshlrev_b32_e32 v44, 16, v67
	v_and_b32_e32 v45, 0xffff0000, v67
	v_mul_f32_e32 v38, v38, v42
	v_mul_f32_e32 v39, v39, v43
	v_mul_f32_e32 v42, v36, v58
	v_mul_f32_e32 v43, v37, v59
	v_mul_f32_e32 v36, v34, v48
	v_mul_f32_e32 v37, v35, v49
	s_mov_b32 s1, 0x58000
	v_mul_f32_e32 v40, v40, v44
	v_mul_f32_e32 v41, v41, v45
	v_cvt_pk_bf16_f32 v34, v38, v39
	v_add_co_u32_e32 v38, vcc, s1, v148
	v_cvt_pk_bf16_f32 v35, v40, v41
	v_cvt_pk_bf16_f32 v36, v36, v37
	v_cvt_pk_bf16_f32 v37, v42, v43
	global_store_dwordx4 v[46:47], v[34:37], off offset:256
	s_nop 0
	v_addc_co_u32_e32 v39, vcc, 0, v149, vcc
	global_load_dwordx4 v[34:37], v[38:39], off offset:256
	s_nop 0
	global_load_dwordx4 v[38:41], v[38:39], off
	s_waitcnt vmcnt(4)
	v_lshlrev_b32_e32 v42, 16, v54
	v_and_b32_e32 v43, 0xffff0000, v54
	v_lshlrev_b32_e32 v46, 16, v56
	v_and_b32_e32 v47, 0xffff0000, v56
	v_lshlrev_b32_e32 v48, 16, v57
	v_and_b32_e32 v49, 0xffff0000, v57
	v_mul_f32_e32 v30, v30, v42
	v_mul_f32_e32 v31, v31, v43
	v_lshlrev_b32_e32 v44, 16, v55
	v_and_b32_e32 v45, 0xffff0000, v55
	v_mul_f32_e32 v42, v28, v48
	v_mul_f32_e32 v43, v29, v49
	v_mul_f32_e32 v28, v26, v46
	v_mul_f32_e32 v29, v27, v47
	v_cvt_pk_bf16_f32 v26, v30, v31
	v_add_co_u32_e32 v30, vcc, s0, v146
	v_mul_f32_e32 v32, v32, v44
	v_mul_f32_e32 v33, v33, v45
	s_nop 0
	v_addc_co_u32_e32 v31, vcc, 0, v147, vcc
	v_cvt_pk_bf16_f32 v27, v32, v33
	v_cvt_pk_bf16_f32 v28, v28, v29
	v_cvt_pk_bf16_f32 v29, v42, v43
	global_store_dwordx4 v[30:31], v[26:29], off
	v_lshlrev_b32_e32 v32, 16, v52
	v_and_b32_e32 v33, 0xffff0000, v52
	v_lshlrev_b32_e32 v26, 16, v50
	v_and_b32_e32 v27, 0xffff0000, v50
	v_lshlrev_b32_e32 v28, 16, v51
	v_and_b32_e32 v29, 0xffff0000, v51
	v_lshlrev_b32_e32 v42, 16, v53
	v_and_b32_e32 v43, 0xffff0000, v53
	v_mul_f32_e32 v16, v16, v28
	v_mul_f32_e32 v17, v17, v29
	v_mul_f32_e32 v14, v14, v26
	v_mul_f32_e32 v15, v15, v27
	v_mul_f32_e32 v26, v12, v42
	v_mul_f32_e32 v27, v13, v43
	v_mul_f32_e32 v12, v10, v32
	v_mul_f32_e32 v13, v11, v33
	v_cvt_pk_bf16_f32 v10, v14, v15
	v_cvt_pk_bf16_f32 v11, v16, v17
	s_waitcnt vmcnt(1)
	v_lshlrev_b32_e32 v14, 16, v40
	v_cvt_pk_bf16_f32 v12, v12, v13
	v_cvt_pk_bf16_f32 v13, v26, v27
	global_store_dwordx4 v[30:31], v[10:13], off offset:256
	v_and_b32_e32 v15, 0xffff0000, v40
	v_lshlrev_b32_e32 v16, 16, v41
	v_lshlrev_b32_e32 v10, 16, v38
	v_and_b32_e32 v11, 0xffff0000, v38
	v_lshlrev_b32_e32 v12, 16, v39
	v_and_b32_e32 v13, 0xffff0000, v39
	v_mul_f32_e32 v10, v22, v10
	v_mul_f32_e32 v11, v23, v11
	v_and_b32_e32 v17, 0xffff0000, v41
	v_mul_f32_e32 v24, v24, v12
	v_mul_f32_e32 v25, v25, v13
	v_cvt_pk_bf16_f32 v12, v10, v11
	v_add_co_u32_e32 v10, vcc, s1, v146
	v_mul_f32_e32 v16, v20, v16
	v_mul_f32_e32 v17, v21, v17
	v_mul_f32_e32 v14, v18, v14
	v_mul_f32_e32 v15, v19, v15
	v_cvt_pk_bf16_f32 v13, v24, v25
	v_addc_co_u32_e32 v11, vcc, 0, v147, vcc
	v_cvt_pk_bf16_f32 v14, v14, v15
	v_cvt_pk_bf16_f32 v15, v16, v17
	global_store_dwordx4 v[10:11], v[12:15], off
	v_lshlrev_b32_e32 v16, 16, v36
	v_and_b32_e32 v17, 0xffff0000, v36
	v_lshlrev_b32_e32 v12, 16, v34
	v_and_b32_e32 v13, 0xffff0000, v34
	v_lshlrev_b32_e32 v18, 16, v37
	v_and_b32_e32 v19, 0xffff0000, v37
	v_lshlrev_b32_e32 v14, 16, v35
	v_and_b32_e32 v15, 0xffff0000, v35
	v_mul_f32_e32 v6, v6, v12
	v_mul_f32_e32 v7, v7, v13
	v_mul_f32_e32 v12, v4, v18
	v_mul_f32_e32 v13, v5, v19
	v_mul_f32_e32 v4, v2, v16
	v_mul_f32_e32 v5, v3, v17
	v_mul_f32_e32 v8, v8, v14
	v_mul_f32_e32 v9, v9, v15
	v_cvt_pk_bf16_f32 v2, v6, v7
	s_mov_b64 s[0:1], -1
	v_cvt_pk_bf16_f32 v3, v8, v9
	v_cvt_pk_bf16_f32 v4, v4, v5
	v_cvt_pk_bf16_f32 v5, v12, v13
	global_store_dwordx4 v[10:11], v[2:5], off offset:256
	s_andn2_b64 vcc, exec, s[16:17]
	s_cbranch_vccnz .LBB0_2191
	s_andn2_b64 vcc, exec, s[2:3]
	s_cbranch_vccnz .LBB0_2190
	s_barrier
	s_branch .LBB0_2190

.LBB0_2280:
	v_lshl_add_u32 v130, s22, 8, v153
	v_ashrrev_i32_e32 v131, 31, v130
	s_lshl_b32 s22, s23, 8
	v_lshlrev_b64 v[130:131], 10, v[130:131]
	s_ashr_i32 s23, s22, 31
	v_lshl_add_u64 v[130:131], v[130:131], 0, s[22:23]
	v_or_b32_e32 v130, v130, v152
	v_lshlrev_b64 v[158:159], 1, v[130:131]
	v_lshl_add_u64 v[160:161], s[4:5], 0, v[158:159]
	v_lshl_add_u64 v[162:163], s[2:3], 0, v[158:159]
	global_load_dwordx4 v[166:169], v[160:161], off
	global_load_dwordx4 v[170:173], v[162:163], off
	global_load_dwordx4 v[174:177], v[160:161], off offset:256
	global_load_dwordx4 v[178:181], v[162:163], off offset:256
	v_add_co_u32_e32 v138, vcc, s75, v162
	s_mov_b64 s[22:23], 0x8000
	s_nop 0
	v_addc_co_u32_e32 v139, vcc, 0, v163, vcc
	v_add_co_u32_e32 v142, vcc, s75, v160
	global_load_dwordx4 v[138:141], v[138:139], off
	s_nop 0
	v_addc_co_u32_e32 v143, vcc, 0, v161, vcc
	global_load_dwordx4 v[142:145], v[142:143], off
	v_lshl_add_u64 v[130:131], v[162:163], 0, s[22:23]
	v_lshl_add_u64 v[134:135], v[160:161], 0, s[22:23]
	global_load_dwordx4 v[130:133], v[130:131], off offset:256
	v_lshl_add_u64 v[158:159], s[6:7], 0, v[158:159]
	global_load_dwordx4 v[134:137], v[134:135], off offset:256
	s_mov_b32 s11, 0x10000
	s_mov_b64 s[50:51], 0x10000
	s_mov_b32 s15, 0x18000
	s_mov_b64 s[12:13], 0x18000
	s_mov_b64 s[22:23], -1
	s_waitcnt vmcnt(0)
	v_lshlrev_b32_e32 v182, 16, v166
	v_and_b32_e32 v183, 0xffff0000, v166
	v_lshlrev_b32_e32 v166, 16, v167
	v_and_b32_e32 v167, 0xffff0000, v167
	v_lshlrev_b32_e32 v184, 16, v168
	v_and_b32_e32 v185, 0xffff0000, v168
	v_lshlrev_b32_e32 v168, 16, v169
	v_and_b32_e32 v169, 0xffff0000, v169
	v_lshlrev_b32_e32 v186, 16, v170
	v_and_b32_e32 v187, 0xffff0000, v170
	v_lshlrev_b32_e32 v170, 16, v171
	v_and_b32_e32 v171, 0xffff0000, v171
	v_lshlrev_b32_e32 v188, 16, v172
	v_and_b32_e32 v189, 0xffff0000, v172
	v_lshlrev_b32_e32 v172, 16, v173
	v_and_b32_e32 v173, 0xffff0000, v173
	v_fma_f32 v128, v128, v166, v170
	v_fma_f32 v129, v129, v167, v171
	v_fma_f32 v126, v126, v182, v186
	v_fma_f32 v127, v127, v183, v187
	v_fma_f32 v166, v124, v168, v172
	v_fma_f32 v167, v125, v169, v173
	v_fma_f32 v124, v122, v184, v188
	v_fma_f32 v125, v123, v185, v189
	v_cvt_pk_bf16_f32 v122, v126, v127
	v_cvt_pk_bf16_f32 v123, v128, v129
	v_lshlrev_b32_e32 v126, 16, v176
	v_cvt_pk_bf16_f32 v124, v124, v125
	v_cvt_pk_bf16_f32 v125, v166, v167
	global_store_dwordx4 v[158:159], v[122:125], off
	v_and_b32_e32 v127, 0xffff0000, v176
	v_lshlrev_b32_e32 v128, 16, v177
	v_lshlrev_b32_e32 v122, 16, v174
	v_and_b32_e32 v123, 0xffff0000, v174
	v_and_b32_e32 v129, 0xffff0000, v177
	v_lshlrev_b32_e32 v166, 16, v178
	v_and_b32_e32 v167, 0xffff0000, v178
	v_lshlrev_b32_e32 v170, 16, v180
	v_and_b32_e32 v171, 0xffff0000, v180
	v_lshlrev_b32_e32 v172, 16, v181
	v_and_b32_e32 v173, 0xffff0000, v181
	v_lshlrev_b32_e32 v124, 16, v175
	v_and_b32_e32 v125, 0xffff0000, v175
	v_lshlrev_b32_e32 v168, 16, v179
	v_and_b32_e32 v169, 0xffff0000, v179
	v_fma_f32 v118, v118, v122, v166
	v_fma_f32 v119, v119, v123, v167
	v_fma_f32 v122, v116, v128, v172
	v_fma_f32 v123, v117, v129, v173
	v_fma_f32 v116, v114, v126, v170
	v_fma_f32 v117, v115, v127, v171
	v_fma_f32 v120, v120, v124, v168
	v_fma_f32 v121, v121, v125, v169
	v_cvt_pk_bf16_f32 v114, v118, v119
	v_lshlrev_b32_e32 v166, 16, v142
	v_cvt_pk_bf16_f32 v115, v120, v121
	v_cvt_pk_bf16_f32 v116, v116, v117
	v_cvt_pk_bf16_f32 v117, v122, v123
	v_add_co_u32_e32 v122, vcc, s11, v162
	global_store_dwordx4 v[158:159], v[114:117], off offset:256
	s_nop 0
	v_addc_co_u32_e32 v123, vcc, 0, v163, vcc
	v_add_co_u32_e32 v126, vcc, s11, v160
	v_and_b32_e32 v167, 0xffff0000, v142
	v_lshlrev_b32_e32 v170, 16, v138
	v_and_b32_e32 v171, 0xffff0000, v138
	v_lshl_add_u64 v[114:115], v[162:163], 0, s[50:51]
	v_lshl_add_u64 v[118:119], v[160:161], 0, s[50:51]
	v_addc_co_u32_e32 v127, vcc, 0, v161, vcc
	v_lshlrev_b32_e32 v142, 16, v143
	v_and_b32_e32 v143, 0xffff0000, v143
	v_lshlrev_b32_e32 v168, 16, v144
	v_and_b32_e32 v169, 0xffff0000, v144
	v_lshlrev_b32_e32 v144, 16, v145
	v_and_b32_e32 v145, 0xffff0000, v145
	v_lshlrev_b32_e32 v138, 16, v139
	v_and_b32_e32 v139, 0xffff0000, v139
	v_lshlrev_b32_e32 v172, 16, v140
	v_and_b32_e32 v173, 0xffff0000, v140
	v_lshlrev_b32_e32 v140, 16, v141
	v_and_b32_e32 v141, 0xffff0000, v141
	v_fma_f32 v110, v110, v166, v170
	v_fma_f32 v111, v111, v167, v171
	global_load_dwordx4 v[114:117], v[114:115], off offset:256
	v_fma_f32 v112, v112, v142, v138
	v_fma_f32 v113, v113, v143, v139
	global_load_dwordx4 v[118:121], v[118:119], off offset:256
	v_fma_f32 v138, v108, v144, v140
	v_fma_f32 v139, v109, v145, v141
	global_load_dwordx4 v[122:125], v[122:123], off
	v_fma_f32 v108, v106, v168, v172
	v_fma_f32 v109, v107, v169, v173
	global_load_dwordx4 v[126:129], v[126:127], off
	v_cvt_pk_bf16_f32 v106, v110, v111
	v_add_co_u32_e32 v110, vcc, s75, v158
	v_cvt_pk_bf16_f32 v107, v112, v113
	v_cvt_pk_bf16_f32 v108, v108, v109
	v_cvt_pk_bf16_f32 v109, v138, v139
	v_lshlrev_b32_e32 v112, 16, v136
	s_nop 0
	v_addc_co_u32_e32 v111, vcc, 0, v159, vcc
	global_store_dwordx4 v[110:111], v[106:109], off
	v_and_b32_e32 v113, 0xffff0000, v136
	v_lshlrev_b32_e32 v136, 16, v130
	v_lshlrev_b32_e32 v106, 16, v134
	v_and_b32_e32 v107, 0xffff0000, v134
	v_lshlrev_b32_e32 v108, 16, v135
	v_and_b32_e32 v109, 0xffff0000, v135
	v_lshlrev_b32_e32 v134, 16, v137
	v_and_b32_e32 v135, 0xffff0000, v137
	v_and_b32_e32 v137, 0xffff0000, v130
	v_lshlrev_b32_e32 v138, 16, v132
	v_and_b32_e32 v139, 0xffff0000, v132
	v_lshlrev_b32_e32 v132, 16, v133
	v_and_b32_e32 v133, 0xffff0000, v133
	v_lshlrev_b32_e32 v130, 16, v131
	v_and_b32_e32 v131, 0xffff0000, v131
	v_fma_f32 v102, v102, v106, v136
	v_fma_f32 v103, v103, v107, v137
	v_fma_f32 v106, v100, v134, v132
	v_fma_f32 v107, v101, v135, v133
	v_fma_f32 v100, v98, v112, v138
	v_fma_f32 v101, v99, v113, v139
	v_fma_f32 v104, v104, v108, v130
	v_fma_f32 v105, v105, v109, v131
	v_cvt_pk_bf16_f32 v98, v102, v103
	v_lshl_add_u64 v[102:103], v[160:161], 0, s[12:13]
	v_cvt_pk_bf16_f32 v99, v104, v105
	v_cvt_pk_bf16_f32 v100, v100, v101
	v_cvt_pk_bf16_f32 v101, v106, v107
	v_add_co_u32_e32 v106, vcc, s15, v162
	global_store_dwordx4 v[110:111], v[98:101], off offset:256
	s_nop 0
	v_addc_co_u32_e32 v107, vcc, 0, v163, vcc
	v_add_co_u32_e32 v110, vcc, s15, v160
	global_load_dwordx4 v[106:109], v[106:107], off
	s_nop 0
	v_addc_co_u32_e32 v111, vcc, 0, v161, vcc
	global_load_dwordx4 v[110:113], v[110:111], off
	v_lshl_add_u64 v[98:99], v[162:163], 0, s[12:13]
	global_load_dwordx4 v[98:101], v[98:99], off offset:256
	s_mov_b64 s[12:13], 0x40000
	global_load_dwordx4 v[102:105], v[102:103], off offset:256
	s_waitcnt vmcnt(7)
	v_lshlrev_b32_e32 v134, 16, v122
	v_and_b32_e32 v135, 0xffff0000, v122
	s_waitcnt vmcnt(6)
	v_lshlrev_b32_e32 v130, 16, v126
	v_and_b32_e32 v131, 0xffff0000, v126
	v_lshlrev_b32_e32 v126, 16, v127
	v_and_b32_e32 v127, 0xffff0000, v127
	v_lshlrev_b32_e32 v132, 16, v128
	v_and_b32_e32 v133, 0xffff0000, v128
	v_lshlrev_b32_e32 v128, 16, v129
	v_and_b32_e32 v129, 0xffff0000, v129
	v_lshlrev_b32_e32 v122, 16, v123
	v_and_b32_e32 v123, 0xffff0000, v123
	v_lshlrev_b32_e32 v136, 16, v124
	v_and_b32_e32 v137, 0xffff0000, v124
	v_lshlrev_b32_e32 v124, 16, v125
	v_and_b32_e32 v125, 0xffff0000, v125
	v_fma_f32 v94, v94, v130, v134
	v_fma_f32 v95, v95, v131, v135
	v_fma_f32 v96, v96, v126, v122
	v_fma_f32 v97, v97, v127, v123
	v_fma_f32 v122, v92, v128, v124
	v_fma_f32 v123, v93, v129, v125
	v_fma_f32 v92, v90, v132, v136
	v_fma_f32 v93, v91, v133, v137
	v_cvt_pk_bf16_f32 v90, v94, v95
	v_add_co_u32_e32 v94, vcc, s11, v158
	v_cvt_pk_bf16_f32 v91, v96, v97
	v_cvt_pk_bf16_f32 v92, v92, v93
	v_cvt_pk_bf16_f32 v93, v122, v123
	v_lshlrev_b32_e32 v96, 16, v120
	s_nop 0
	v_addc_co_u32_e32 v95, vcc, 0, v159, vcc
	global_store_dwordx4 v[94:95], v[90:93], off
	v_and_b32_e32 v97, 0xffff0000, v120
	v_lshlrev_b32_e32 v120, 16, v114
	v_lshlrev_b32_e32 v90, 16, v118
	v_and_b32_e32 v91, 0xffff0000, v118
	v_lshlrev_b32_e32 v92, 16, v119
	v_and_b32_e32 v93, 0xffff0000, v119
	v_lshlrev_b32_e32 v118, 16, v121
	v_and_b32_e32 v119, 0xffff0000, v121
	v_and_b32_e32 v121, 0xffff0000, v114
	v_lshlrev_b32_e32 v122, 16, v116
	v_and_b32_e32 v123, 0xffff0000, v116
	v_lshlrev_b32_e32 v116, 16, v117
	v_and_b32_e32 v117, 0xffff0000, v117
	v_lshlrev_b32_e32 v114, 16, v115
	v_and_b32_e32 v115, 0xffff0000, v115
	v_fma_f32 v86, v86, v90, v120
	v_fma_f32 v87, v87, v91, v121
	v_fma_f32 v90, v84, v118, v116
	v_fma_f32 v91, v85, v119, v117
	v_fma_f32 v84, v82, v96, v122
	v_fma_f32 v85, v83, v97, v123
	s_mov_b32 s11, 0x40000
	v_fma_f32 v88, v88, v92, v114
	v_fma_f32 v89, v89, v93, v115
	v_cvt_pk_bf16_f32 v82, v86, v87
	s_waitcnt vmcnt(3)
	v_lshlrev_b32_e32 v114, 16, v110
	v_cvt_pk_bf16_f32 v83, v88, v89
	v_cvt_pk_bf16_f32 v84, v84, v85
	v_cvt_pk_bf16_f32 v85, v90, v91
	v_add_co_u32_e32 v90, vcc, s11, v162
	global_store_dwordx4 v[94:95], v[82:85], off offset:256
	s_nop 0
	v_addc_co_u32_e32 v91, vcc, 0, v163, vcc
	v_add_co_u32_e32 v94, vcc, s11, v160
	v_and_b32_e32 v115, 0xffff0000, v110
	v_lshlrev_b32_e32 v118, 16, v106
	v_and_b32_e32 v119, 0xffff0000, v106
	v_lshl_add_u64 v[82:83], v[162:163], 0, s[12:13]
	v_lshl_add_u64 v[86:87], v[160:161], 0, s[12:13]
	v_addc_co_u32_e32 v95, vcc, 0, v161, vcc
	v_lshlrev_b32_e32 v110, 16, v111
	v_and_b32_e32 v111, 0xffff0000, v111
	v_lshlrev_b32_e32 v116, 16, v112
	v_and_b32_e32 v117, 0xffff0000, v112
	v_lshlrev_b32_e32 v112, 16, v113
	v_and_b32_e32 v113, 0xffff0000, v113
	v_lshlrev_b32_e32 v106, 16, v107
	v_and_b32_e32 v107, 0xffff0000, v107
	v_lshlrev_b32_e32 v120, 16, v108
	v_and_b32_e32 v121, 0xffff0000, v108
	v_lshlrev_b32_e32 v108, 16, v109
	v_and_b32_e32 v109, 0xffff0000, v109
	v_fma_f32 v78, v78, v114, v118
	v_fma_f32 v79, v79, v115, v119
	global_load_dwordx4 v[82:85], v[82:83], off offset:256
	v_fma_f32 v80, v80, v110, v106
	v_fma_f32 v81, v81, v111, v107
	global_load_dwordx4 v[86:89], v[86:87], off offset:256
	v_fma_f32 v106, v76, v112, v108
	v_fma_f32 v107, v77, v113, v109
	global_load_dwordx4 v[90:93], v[90:91], off
	v_fma_f32 v76, v74, v116, v120
	v_fma_f32 v77, v75, v117, v121
	global_load_dwordx4 v[94:97], v[94:95], off
	v_cvt_pk_bf16_f32 v74, v78, v79
	v_add_co_u32_e32 v78, vcc, s15, v158
	v_cvt_pk_bf16_f32 v75, v80, v81
	v_cvt_pk_bf16_f32 v76, v76, v77
	v_cvt_pk_bf16_f32 v77, v106, v107
	s_waitcnt vmcnt(6)
	v_lshlrev_b32_e32 v80, 16, v104
	v_addc_co_u32_e32 v79, vcc, 0, v159, vcc
	global_store_dwordx4 v[78:79], v[74:77], off
	v_and_b32_e32 v81, 0xffff0000, v104
	v_lshlrev_b32_e32 v104, 16, v98
	v_lshlrev_b32_e32 v74, 16, v102
	v_and_b32_e32 v75, 0xffff0000, v102
	v_lshlrev_b32_e32 v76, 16, v103
	v_and_b32_e32 v77, 0xffff0000, v103
	v_lshlrev_b32_e32 v102, 16, v105
	v_and_b32_e32 v103, 0xffff0000, v105
	v_and_b32_e32 v105, 0xffff0000, v98
	v_lshlrev_b32_e32 v106, 16, v100
	v_and_b32_e32 v107, 0xffff0000, v100
	v_lshlrev_b32_e32 v100, 16, v101
	v_and_b32_e32 v101, 0xffff0000, v101
	v_lshlrev_b32_e32 v98, 16, v99
	v_and_b32_e32 v99, 0xffff0000, v99
	v_fma_f32 v70, v70, v74, v104
	v_fma_f32 v71, v71, v75, v105
	v_fma_f32 v74, v68, v102, v100
	v_fma_f32 v75, v69, v103, v101
	v_fma_f32 v68, v66, v80, v106
	v_fma_f32 v69, v67, v81, v107
	s_mov_b32 s15, 0x48000
	v_fma_f32 v72, v72, v76, v98
	v_fma_f32 v73, v73, v77, v99
	v_cvt_pk_bf16_f32 v66, v70, v71
	s_mov_b64 s[12:13], 0x48000
	v_cvt_pk_bf16_f32 v67, v72, v73
	v_cvt_pk_bf16_f32 v68, v68, v69
	v_cvt_pk_bf16_f32 v69, v74, v75
	v_add_co_u32_e32 v74, vcc, s15, v162
	global_store_dwordx4 v[78:79], v[66:69], off offset:256
	s_nop 0
	v_addc_co_u32_e32 v75, vcc, 0, v163, vcc
	v_add_co_u32_e32 v78, vcc, s15, v160
	global_load_dwordx4 v[74:77], v[74:75], off
	s_nop 0
	v_addc_co_u32_e32 v79, vcc, 0, v161, vcc
	global_load_dwordx4 v[78:81], v[78:79], off
	v_lshl_add_u64 v[66:67], v[162:163], 0, s[12:13]
	v_lshl_add_u64 v[70:71], v[160:161], 0, s[12:13]
	global_load_dwordx4 v[66:69], v[66:67], off offset:256
	s_mov_b64 s[12:13], 0x50000
	global_load_dwordx4 v[70:73], v[70:71], off offset:256
	s_waitcnt vmcnt(7)
	v_lshlrev_b32_e32 v102, 16, v90
	v_and_b32_e32 v103, 0xffff0000, v90
	s_waitcnt vmcnt(6)
	v_lshlrev_b32_e32 v98, 16, v94
	v_and_b32_e32 v99, 0xffff0000, v94
	v_lshlrev_b32_e32 v94, 16, v95
	v_and_b32_e32 v95, 0xffff0000, v95
	v_lshlrev_b32_e32 v100, 16, v96
	v_and_b32_e32 v101, 0xffff0000, v96
	v_lshlrev_b32_e32 v96, 16, v97
	v_and_b32_e32 v97, 0xffff0000, v97
	v_lshlrev_b32_e32 v90, 16, v91
	v_and_b32_e32 v91, 0xffff0000, v91
	v_lshlrev_b32_e32 v104, 16, v92
	v_and_b32_e32 v105, 0xffff0000, v92
	v_lshlrev_b32_e32 v92, 16, v93
	v_and_b32_e32 v93, 0xffff0000, v93
	v_fma_f32 v62, v62, v98, v102
	v_fma_f32 v63, v63, v99, v103
	v_fma_f32 v64, v64, v94, v90
	v_fma_f32 v65, v65, v95, v91
	v_fma_f32 v90, v60, v96, v92
	v_fma_f32 v91, v61, v97, v93
	v_fma_f32 v60, v58, v100, v104
	v_fma_f32 v61, v59, v101, v105
	v_cvt_pk_bf16_f32 v58, v62, v63
	v_add_co_u32_e32 v62, vcc, s11, v158
	v_cvt_pk_bf16_f32 v59, v64, v65
	v_cvt_pk_bf16_f32 v60, v60, v61
	v_cvt_pk_bf16_f32 v61, v90, v91
	v_lshlrev_b32_e32 v64, 16, v88
	s_nop 0
	v_addc_co_u32_e32 v63, vcc, 0, v159, vcc
	global_store_dwordx4 v[62:63], v[58:61], off
	v_and_b32_e32 v65, 0xffff0000, v88
	v_lshlrev_b32_e32 v88, 16, v82
	v_lshlrev_b32_e32 v58, 16, v86
	v_and_b32_e32 v59, 0xffff0000, v86
	v_lshlrev_b32_e32 v60, 16, v87
	v_and_b32_e32 v61, 0xffff0000, v87
	v_lshlrev_b32_e32 v86, 16, v89
	v_and_b32_e32 v87, 0xffff0000, v89
	v_and_b32_e32 v89, 0xffff0000, v82
	v_lshlrev_b32_e32 v90, 16, v84
	v_and_b32_e32 v91, 0xffff0000, v84
	v_lshlrev_b32_e32 v84, 16, v85
	v_and_b32_e32 v85, 0xffff0000, v85
	v_lshlrev_b32_e32 v82, 16, v83
	v_and_b32_e32 v83, 0xffff0000, v83
	v_fma_f32 v54, v54, v58, v88
	v_fma_f32 v55, v55, v59, v89
	v_fma_f32 v58, v52, v86, v84
	v_fma_f32 v59, v53, v87, v85
	v_fma_f32 v52, v50, v64, v90
	v_fma_f32 v53, v51, v65, v91
	s_mov_b32 s11, 0x50000
	v_fma_f32 v56, v56, v60, v82
	v_fma_f32 v57, v57, v61, v83
	v_cvt_pk_bf16_f32 v50, v54, v55
	s_waitcnt vmcnt(3)
	v_lshlrev_b32_e32 v82, 16, v78
	v_cvt_pk_bf16_f32 v51, v56, v57
	v_cvt_pk_bf16_f32 v52, v52, v53
	v_cvt_pk_bf16_f32 v53, v58, v59
	v_add_co_u32_e32 v58, vcc, s11, v162
	global_store_dwordx4 v[62:63], v[50:53], off offset:256
	s_nop 0
	v_addc_co_u32_e32 v59, vcc, 0, v163, vcc
	v_add_co_u32_e32 v62, vcc, s11, v160
	v_and_b32_e32 v83, 0xffff0000, v78
	v_lshlrev_b32_e32 v86, 16, v74
	v_and_b32_e32 v87, 0xffff0000, v74
	v_lshl_add_u64 v[50:51], v[162:163], 0, s[12:13]
	v_lshl_add_u64 v[54:55], v[160:161], 0, s[12:13]
	v_addc_co_u32_e32 v63, vcc, 0, v161, vcc
	v_lshlrev_b32_e32 v78, 16, v79
	v_and_b32_e32 v79, 0xffff0000, v79
	v_lshlrev_b32_e32 v84, 16, v80
	v_and_b32_e32 v85, 0xffff0000, v80
	v_lshlrev_b32_e32 v80, 16, v81
	v_and_b32_e32 v81, 0xffff0000, v81
	v_lshlrev_b32_e32 v74, 16, v75
	v_and_b32_e32 v75, 0xffff0000, v75
	v_lshlrev_b32_e32 v88, 16, v76
	v_and_b32_e32 v89, 0xffff0000, v76
	v_lshlrev_b32_e32 v76, 16, v77
	v_and_b32_e32 v77, 0xffff0000, v77
	v_fma_f32 v46, v46, v82, v86
	v_fma_f32 v47, v47, v83, v87
	global_load_dwordx4 v[50:53], v[50:51], off offset:256
	v_fma_f32 v48, v48, v78, v74
	v_fma_f32 v49, v49, v79, v75
	global_load_dwordx4 v[54:57], v[54:55], off offset:256
	v_fma_f32 v74, v44, v80, v76
	v_fma_f32 v75, v45, v81, v77
	global_load_dwordx4 v[58:61], v[58:59], off
	v_fma_f32 v44, v42, v84, v88
	v_fma_f32 v45, v43, v85, v89
	global_load_dwordx4 v[62:65], v[62:63], off
	v_cvt_pk_bf16_f32 v42, v46, v47
	v_add_co_u32_e32 v46, vcc, s15, v158
	v_cvt_pk_bf16_f32 v43, v48, v49
	v_cvt_pk_bf16_f32 v44, v44, v45
	v_cvt_pk_bf16_f32 v45, v74, v75
	s_waitcnt vmcnt(6)
	v_lshlrev_b32_e32 v48, 16, v72
	v_addc_co_u32_e32 v47, vcc, 0, v159, vcc
	global_store_dwordx4 v[46:47], v[42:45], off
	v_and_b32_e32 v49, 0xffff0000, v72
	v_lshlrev_b32_e32 v72, 16, v66
	v_lshlrev_b32_e32 v42, 16, v70
	v_and_b32_e32 v43, 0xffff0000, v70
	v_lshlrev_b32_e32 v44, 16, v71
	v_and_b32_e32 v45, 0xffff0000, v71
	v_lshlrev_b32_e32 v70, 16, v73
	v_and_b32_e32 v71, 0xffff0000, v73
	v_and_b32_e32 v73, 0xffff0000, v66
	v_lshlrev_b32_e32 v74, 16, v68
	v_and_b32_e32 v75, 0xffff0000, v68
	v_lshlrev_b32_e32 v68, 16, v69
	v_and_b32_e32 v69, 0xffff0000, v69
	v_fma_f32 v38, v38, v42, v72
	v_fma_f32 v39, v39, v43, v73
	s_mov_b32 s15, 0x58000
	v_lshlrev_b32_e32 v66, 16, v67
	v_and_b32_e32 v67, 0xffff0000, v67
	v_fma_f32 v42, v36, v70, v68
	v_fma_f32 v43, v37, v71, v69
	v_fma_f32 v36, v34, v48, v74
	v_fma_f32 v37, v35, v49, v75
	v_cvt_pk_bf16_f32 v34, v38, v39
	v_add_co_u32_e32 v38, vcc, s15, v162
	v_fma_f32 v40, v40, v44, v66
	v_fma_f32 v41, v41, v45, v67
	s_mov_b64 s[12:13], 0x58000
	v_cvt_pk_bf16_f32 v35, v40, v41
	v_cvt_pk_bf16_f32 v36, v36, v37
	v_cvt_pk_bf16_f32 v37, v42, v43
	global_store_dwordx4 v[46:47], v[34:37], off offset:256
	v_addc_co_u32_e32 v39, vcc, 0, v163, vcc
	s_nop 0
	v_lshl_add_u64 v[34:35], v[162:163], 0, s[12:13]
	v_add_co_u32_e32 v46, vcc, s15, v160
	global_load_dwordx4 v[34:37], v[34:35], off offset:256
	s_nop 0
	v_addc_co_u32_e32 v47, vcc, 0, v161, vcc
	global_load_dwordx4 v[42:45], v[38:39], off
	v_lshl_add_u64 v[38:39], v[160:161], 0, s[12:13]
	global_load_dwordx4 v[38:41], v[38:39], off offset:256
	s_waitcnt vmcnt(6)
	v_lshlrev_b32_e32 v70, 16, v58
	global_load_dwordx4 v[46:49], v[46:47], off
	s_waitcnt vmcnt(6)
	v_lshlrev_b32_e32 v66, 16, v62
	v_and_b32_e32 v67, 0xffff0000, v62
	v_and_b32_e32 v71, 0xffff0000, v58
	v_lshlrev_b32_e32 v62, 16, v63
	v_and_b32_e32 v63, 0xffff0000, v63
	v_lshlrev_b32_e32 v68, 16, v64
	v_and_b32_e32 v69, 0xffff0000, v64
	v_lshlrev_b32_e32 v64, 16, v65
	v_and_b32_e32 v65, 0xffff0000, v65
	v_lshlrev_b32_e32 v58, 16, v59
	v_and_b32_e32 v59, 0xffff0000, v59
	v_lshlrev_b32_e32 v72, 16, v60
	v_and_b32_e32 v73, 0xffff0000, v60
	v_lshlrev_b32_e32 v60, 16, v61
	v_and_b32_e32 v61, 0xffff0000, v61
	v_fma_f32 v30, v30, v66, v70
	v_fma_f32 v31, v31, v67, v71
	v_fma_f32 v32, v32, v62, v58
	v_fma_f32 v33, v33, v63, v59
	v_fma_f32 v58, v28, v64, v60
	v_fma_f32 v59, v29, v65, v61
	v_fma_f32 v28, v26, v68, v72
	v_fma_f32 v29, v27, v69, v73
	v_cvt_pk_bf16_f32 v26, v30, v31
	v_add_co_u32_e32 v30, vcc, s11, v158
	v_cvt_pk_bf16_f32 v27, v32, v33
	v_cvt_pk_bf16_f32 v28, v28, v29
	v_cvt_pk_bf16_f32 v29, v58, v59
	v_lshlrev_b32_e32 v32, 16, v56
	s_nop 0
	v_addc_co_u32_e32 v31, vcc, 0, v159, vcc
	global_store_dwordx4 v[30:31], v[26:29], off
	v_and_b32_e32 v33, 0xffff0000, v56
	v_lshlrev_b32_e32 v56, 16, v50
	v_lshlrev_b32_e32 v26, 16, v54
	v_and_b32_e32 v27, 0xffff0000, v54
	v_lshlrev_b32_e32 v28, 16, v55
	v_and_b32_e32 v29, 0xffff0000, v55
	v_lshlrev_b32_e32 v54, 16, v57
	v_and_b32_e32 v55, 0xffff0000, v57
	v_and_b32_e32 v57, 0xffff0000, v50
	v_lshlrev_b32_e32 v50, 16, v51
	v_and_b32_e32 v51, 0xffff0000, v51
	v_lshlrev_b32_e32 v58, 16, v52
	v_and_b32_e32 v59, 0xffff0000, v52
	v_lshlrev_b32_e32 v52, 16, v53
	v_and_b32_e32 v53, 0xffff0000, v53
	v_fma_f32 v24, v24, v28, v50
	v_fma_f32 v25, v25, v29, v51
	v_fma_f32 v22, v22, v26, v56
	v_fma_f32 v23, v23, v27, v57
	v_fma_f32 v26, v20, v54, v52
	v_fma_f32 v27, v21, v55, v53
	v_fma_f32 v20, v18, v32, v58
	v_fma_f32 v21, v19, v33, v59
	v_cvt_pk_bf16_f32 v18, v22, v23
	v_cvt_pk_bf16_f32 v19, v24, v25
	s_waitcnt vmcnt(3)
	v_lshlrev_b32_e32 v32, 16, v45
	v_cvt_pk_bf16_f32 v20, v20, v21
	v_cvt_pk_bf16_f32 v21, v26, v27
	global_store_dwordx4 v[30:31], v[18:21], off offset:256
	v_lshlrev_b32_e32 v26, 16, v42
	v_and_b32_e32 v27, 0xffff0000, v42
	v_lshlrev_b32_e32 v30, 16, v44
	v_and_b32_e32 v31, 0xffff0000, v44
	v_and_b32_e32 v33, 0xffff0000, v45
	v_lshlrev_b32_e32 v28, 16, v43
	v_and_b32_e32 v29, 0xffff0000, v43
	s_waitcnt vmcnt(2)
	v_lshlrev_b32_e32 v18, 16, v46
	v_and_b32_e32 v19, 0xffff0000, v46
	v_lshlrev_b32_e32 v22, 16, v48
	v_and_b32_e32 v23, 0xffff0000, v48
	v_lshlrev_b32_e32 v24, 16, v49
	v_and_b32_e32 v25, 0xffff0000, v49
	v_fma_f32 v14, v14, v18, v26
	v_fma_f32 v15, v15, v19, v27
	v_lshlrev_b32_e32 v20, 16, v47
	v_and_b32_e32 v21, 0xffff0000, v47
	v_fma_f32 v18, v12, v24, v32
	v_fma_f32 v19, v13, v25, v33
	v_fma_f32 v12, v10, v22, v30
	v_fma_f32 v13, v11, v23, v31
	v_cvt_pk_bf16_f32 v10, v14, v15
	v_add_co_u32_e32 v14, vcc, s15, v158
	v_fma_f32 v16, v16, v20, v28
	v_fma_f32 v17, v17, v21, v29
	s_nop 0
	v_addc_co_u32_e32 v15, vcc, 0, v159, vcc
	v_cvt_pk_bf16_f32 v11, v16, v17
	v_cvt_pk_bf16_f32 v12, v12, v13
	v_cvt_pk_bf16_f32 v13, v18, v19
	global_store_dwordx4 v[14:15], v[10:13], off
	v_lshlrev_b32_e32 v16, 16, v40
	v_and_b32_e32 v17, 0xffff0000, v40
	v_lshlrev_b32_e32 v10, 16, v38
	v_and_b32_e32 v11, 0xffff0000, v38
	v_lshlrev_b32_e32 v18, 16, v41
	v_and_b32_e32 v19, 0xffff0000, v41
	v_lshlrev_b32_e32 v20, 16, v34
	v_and_b32_e32 v21, 0xffff0000, v34
	v_lshlrev_b32_e32 v24, 16, v36
	v_and_b32_e32 v25, 0xffff0000, v36
	v_lshlrev_b32_e32 v26, 16, v37
	v_and_b32_e32 v27, 0xffff0000, v37
	v_lshlrev_b32_e32 v12, 16, v39
	v_and_b32_e32 v13, 0xffff0000, v39
	v_lshlrev_b32_e32 v22, 16, v35
	v_and_b32_e32 v23, 0xffff0000, v35
	v_fma_f32 v6, v6, v10, v20
	v_fma_f32 v7, v7, v11, v21
	v_fma_f32 v10, v4, v18, v26
	v_fma_f32 v11, v5, v19, v27
	v_fma_f32 v4, v2, v16, v24
	v_fma_f32 v5, v3, v17, v25
	v_fma_f32 v8, v8, v12, v22
	v_fma_f32 v9, v9, v13, v23
	v_cvt_pk_bf16_f32 v2, v6, v7
	s_andn2_b64 vcc, exec, s[16:17]
	v_cvt_pk_bf16_f32 v3, v8, v9
	v_cvt_pk_bf16_f32 v4, v4, v5
	v_cvt_pk_bf16_f32 v5, v10, v11
	global_store_dwordx4 v[14:15], v[2:5], off offset:256
	s_cbranch_vccnz .LBB0_2269
	s_andn2_b64 vcc, exec, s[0:1]
	s_cbranch_vccnz .LBB0_2268
	s_barrier
	s_branch .LBB0_2268

.LBB0_2360:
	s_ashr_i32 s1, s0, 5
	s_lshl_b32 s40, s0, 8
	s_mul_hi_i32 s25, s1, 0x9000
	s_mul_i32 s1, s1, 0x9000
	v_lshl_or_b32 v168, s36, 8, v186
	v_add_u32_e32 v146, s40, v184
	s_add_u32 s38, s53, s1
	v_ashrrev_i32_e32 v147, 31, v146
	v_ashrrev_i32_e32 v169, 31, v168
	s_addc_u32 s39, s54, s25
	v_lshl_add_u64 v[86:87], v[168:169], 2, s[38:39]
	s_mov_b64 s[42:43], 0x5000
	s_movk_i32 s1, 0x5000
	v_lshlrev_b64 v[146:147], 10, v[146:147]
	v_lshl_add_u64 v[94:95], v[86:87], 0, s[42:43]
	v_add_co_u32_e32 v86, vcc, s1, v86
	v_lshl_add_u64 v[166:167], v[146:147], 0, v[168:169]
	s_nop 0
	v_addc_co_u32_e32 v87, vcc, 0, v87, vcc
	v_lshl_add_u64 v[182:183], v[166:167], 1, s[18:19]
	global_load_dwordx4 v[102:105], v[86:87], off
	global_load_dwordx4 v[98:101], v[94:95], off offset:16
	s_nop 0
	global_load_dwordx4 v[86:89], v[94:95], off offset:528
	s_nop 0
	global_load_dwordx4 v[94:97], v[94:95], off offset:512
	s_nop 0
	global_load_dwordx4 v[170:173], v[182:183], off
	global_load_dwordx4 v[174:177], v[182:183], off offset:256
	v_add_co_u32_e32 v146, vcc, s75, v182
	s_waitcnt vmcnt(0)
	v_lshlrev_b32_e32 v178, 16, v170
	v_addc_co_u32_e32 v147, vcc, 0, v183, vcc
	global_load_dwordx4 v[150:153], v[146:147], off
	s_nop 0
	global_load_dwordx4 v[146:149], v[146:147], off offset:256
	v_and_b32_e32 v179, 0xffff0000, v170
	v_lshlrev_b32_e32 v170, 16, v171
	v_and_b32_e32 v171, 0xffff0000, v171
	v_lshlrev_b32_e32 v180, 16, v172
	v_and_b32_e32 v181, 0xffff0000, v172
	v_lshlrev_b32_e32 v172, 16, v173
	v_and_b32_e32 v173, 0xffff0000, v173
	v_fma_f32 v144, v144, v104, v170
	v_fma_f32 v145, v145, v105, v171
	v_fma_f32 v142, v142, v102, v178
	v_fma_f32 v143, v143, v103, v179
	v_fma_f32 v140, v140, v100, v172
	v_fma_f32 v141, v141, v101, v173
	v_cvt_pk_bf16_f32 v170, v142, v143
	v_cvt_pk_bf16_f32 v171, v144, v145
	v_fma_f32 v138, v138, v98, v180
	v_fma_f32 v139, v139, v99, v181
	v_lshlrev_b32_e32 v178, 16, v177
	v_cvt_pk_bf16_f32 v172, v138, v139
	v_cvt_pk_bf16_f32 v173, v140, v141
	global_store_dwordx4 v[182:183], v[170:173], off
	v_and_b32_e32 v179, 0xffff0000, v177
	s_nop 0
	v_mul_f32_e32 v170, v143, v143
	v_mul_f32_e32 v171, v145, v145
	v_fmac_f32_e32 v170, v142, v142
	v_fmac_f32_e32 v171, v144, v144
	v_add_f32_e32 v170, v170, v171
	v_mul_f32_e32 v171, v139, v139
	v_mul_f32_e32 v172, v141, v141
	v_fmac_f32_e32 v171, v138, v138
	v_fmac_f32_e32 v172, v140, v140
	v_add_f32_e32 v171, v171, v172
	v_add_f32_e32 v180, v170, v171
	v_lshlrev_b32_e32 v170, 16, v174
	v_and_b32_e32 v171, 0xffff0000, v174
	v_lshlrev_b32_e32 v172, 16, v175
	v_and_b32_e32 v173, 0xffff0000, v175
	v_lshlrev_b32_e32 v174, 16, v176
	v_and_b32_e32 v175, 0xffff0000, v176
	v_fma_f32 v172, v136, v96, v172
	v_fma_f32 v173, v137, v97, v173
	v_fma_f32 v176, v134, v94, v170
	v_fma_f32 v177, v135, v95, v171
	v_fma_f32 v174, v130, v86, v174
	v_fma_f32 v175, v131, v87, v175
	v_cvt_pk_bf16_f32 v130, v176, v177
	v_cvt_pk_bf16_f32 v131, v172, v173
	v_fma_f32 v170, v132, v88, v178
	v_fma_f32 v171, v133, v89, v179
	v_cvt_pk_bf16_f32 v132, v174, v175
	s_nop 0
	v_cvt_pk_bf16_f32 v133, v170, v171
	global_store_dwordx4 v[182:183], v[130:133], off offset:256
	s_nop 1
	v_mul_f32_e32 v130, v177, v177
	v_mul_f32_e32 v131, v173, v173
	v_fmac_f32_e32 v130, v176, v176
	v_fmac_f32_e32 v131, v172, v172
	v_add_f32_e32 v130, v130, v131
	v_mul_f32_e32 v131, v175, v175
	v_mul_f32_e32 v132, v171, v171
	v_fmac_f32_e32 v131, v174, v174
	v_fmac_f32_e32 v132, v170, v170
	v_add_f32_e32 v131, v131, v132
	v_add_f32_e32 v130, v130, v131
	v_add_f32_e32 v130, v180, v130
	ds_bpermute_b32 v131, v187, v130
	s_waitcnt lgkmcnt(0)
	v_add_f32_e32 v130, v130, v131
	ds_bpermute_b32 v131, v188, v130
	s_and_saveexec_b64 s[42:43], s[4:5]
	s_cbranch_execz .LBB0_2362
	s_waitcnt lgkmcnt(0)
	v_add_f32_e32 v130, v130, v131
	ds_write_b32 v197, v130
.LBB0_2362:
	s_or_b64 exec, exec, s[42:43]
	s_mov_b32 s1, 0x10000
	v_add_co_u32_e32 v130, vcc, s1, v182
	s_waitcnt vmcnt(3)
	v_lshlrev_b32_e32 v178, 16, v150
	s_waitcnt lgkmcnt(0)
	v_addc_co_u32_e32 v131, vcc, 0, v183, vcc
	global_load_dwordx4 v[134:137], v[130:131], off
	s_nop 0
	global_load_dwordx4 v[130:133], v[130:131], off offset:256
	v_and_b32_e32 v179, 0xffff0000, v150
	v_lshlrev_b32_e32 v150, 16, v151
	v_and_b32_e32 v151, 0xffff0000, v151
	v_lshlrev_b32_e32 v180, 16, v152
	v_and_b32_e32 v181, 0xffff0000, v152
	v_lshlrev_b32_e32 v198, 16, v153
	v_and_b32_e32 v199, 0xffff0000, v153
	v_fma_f32 v150, v128, v104, v150
	v_fma_f32 v151, v129, v105, v151
	v_fma_f32 v152, v126, v102, v178
	v_fma_f32 v153, v127, v103, v179
	v_fma_f32 v180, v122, v98, v180
	v_fma_f32 v181, v123, v99, v181
	v_mul_f32_e32 v122, v153, v153
	v_mul_f32_e32 v123, v151, v151
	v_fma_f32 v178, v124, v100, v198
	v_fma_f32 v179, v125, v101, v199
	v_fmac_f32_e32 v122, v152, v152
	v_fmac_f32_e32 v123, v150, v150
	v_add_f32_e32 v122, v122, v123
	v_mul_f32_e32 v123, v181, v181
	v_mul_f32_e32 v124, v179, v179
	v_fmac_f32_e32 v123, v180, v180
	v_fmac_f32_e32 v124, v178, v178
	v_add_f32_e32 v123, v123, v124
	v_add_f32_e32 v200, v122, v123
	s_waitcnt vmcnt(4)
	v_lshlrev_b32_e32 v122, 16, v146
	v_and_b32_e32 v123, 0xffff0000, v146
	v_lshlrev_b32_e32 v124, 16, v147
	v_and_b32_e32 v125, 0xffff0000, v147
	v_lshlrev_b32_e32 v146, 16, v148
	v_and_b32_e32 v147, 0xffff0000, v148
	v_fma_f32 v128, v120, v96, v124
	v_fma_f32 v129, v121, v97, v125
	v_fma_f32 v126, v118, v94, v122
	v_fma_f32 v127, v119, v95, v123
	v_lshlrev_b32_e32 v148, 16, v149
	v_and_b32_e32 v149, 0xffff0000, v149
	v_fma_f32 v124, v114, v86, v146
	v_fma_f32 v125, v115, v87, v147
	v_mul_f32_e32 v114, v127, v127
	v_mul_f32_e32 v115, v129, v129
	v_fma_f32 v122, v116, v88, v148
	v_fma_f32 v123, v117, v89, v149
	v_fmac_f32_e32 v114, v126, v126
	v_fmac_f32_e32 v115, v128, v128
	v_add_f32_e32 v114, v114, v115
	v_mul_f32_e32 v115, v125, v125
	v_mul_f32_e32 v116, v123, v123
	v_fmac_f32_e32 v115, v124, v124
	v_fmac_f32_e32 v116, v122, v122
	v_add_f32_e32 v115, v115, v116
	v_add_f32_e32 v114, v114, v115
	v_add_f32_e32 v114, v200, v114
	ds_bpermute_b32 v115, v187, v114
	s_mov_b64 s[42:43], 0x8000
	v_lshl_add_u64 v[202:203], v[182:183], 0, s[42:43]
	s_mov_b64 s[42:43], 0x8100
	v_lshl_add_u64 v[204:205], v[182:183], 0, s[42:43]
	s_waitcnt lgkmcnt(0)
	v_add_f32_e32 v114, v114, v115
	ds_bpermute_b32 v115, v188, v114
	v_cvt_pk_bf16_f32 v198, v152, v153
	v_cvt_pk_bf16_f32 v199, v150, v151
	v_cvt_pk_bf16_f32 v200, v180, v181
	v_cvt_pk_bf16_f32 v201, v178, v179
	global_store_dwordx4 v[202:203], v[198:201], off
	v_cvt_pk_bf16_f32 v116, v126, v127
	v_cvt_pk_bf16_f32 v117, v128, v129
	v_cvt_pk_bf16_f32 v118, v124, v125
	v_cvt_pk_bf16_f32 v119, v122, v123
	global_store_dwordx4 v[204:205], v[116:119], off
	s_and_saveexec_b64 s[42:43], s[4:5]
	s_cbranch_execz .LBB0_2364
	s_waitcnt lgkmcnt(0)
	v_add_f32_e32 v114, v114, v115
	ds_write_b32 v197, v114 offset:256
.LBB0_2364:
	s_or_b64 exec, exec, s[42:43]
	v_add_co_u32_e32 v114, vcc, 0x18000, v182
	s_waitcnt vmcnt(3)
	v_lshlrev_b32_e32 v146, 16, v134
	s_waitcnt lgkmcnt(0)
	v_addc_co_u32_e32 v115, vcc, 0, v183, vcc
	global_load_dwordx4 v[118:121], v[114:115], off
	s_nop 0
	global_load_dwordx4 v[114:117], v[114:115], off offset:256
	v_and_b32_e32 v147, 0xffff0000, v134
	v_lshlrev_b32_e32 v134, 16, v135
	v_and_b32_e32 v135, 0xffff0000, v135
	v_fma_f32 v112, v112, v104, v134
	v_fma_f32 v113, v113, v105, v135
	v_fma_f32 v110, v110, v102, v146
	v_fma_f32 v111, v111, v103, v147
	v_lshlrev_b32_e32 v148, 16, v136
	v_and_b32_e32 v149, 0xffff0000, v136
	v_lshlrev_b32_e32 v136, 16, v137
	v_and_b32_e32 v137, 0xffff0000, v137
	v_mul_f32_e32 v134, v111, v111
	v_mul_f32_e32 v135, v113, v113
	v_fma_f32 v108, v108, v100, v136
	v_fma_f32 v109, v109, v101, v137
	v_fma_f32 v106, v106, v98, v148
	v_fma_f32 v107, v107, v99, v149
	v_fmac_f32_e32 v134, v110, v110
	v_fmac_f32_e32 v135, v112, v112
	v_add_f32_e32 v134, v134, v135
	v_mul_f32_e32 v135, v107, v107
	v_mul_f32_e32 v136, v109, v109
	v_fmac_f32_e32 v135, v106, v106
	v_fmac_f32_e32 v136, v108, v108
	v_add_f32_e32 v135, v135, v136
	v_add_f32_e32 v202, v134, v135
	s_waitcnt vmcnt(4)
	v_lshlrev_b32_e32 v134, 16, v130
	v_and_b32_e32 v135, 0xffff0000, v130
	v_lshlrev_b32_e32 v130, 16, v131
	v_and_b32_e32 v131, 0xffff0000, v131
	v_lshlrev_b32_e32 v136, 16, v132
	v_and_b32_e32 v137, 0xffff0000, v132
	v_lshlrev_b32_e32 v148, 16, v133
	v_and_b32_e32 v149, 0xffff0000, v133
	v_fma_f32 v130, v92, v96, v130
	v_fma_f32 v131, v93, v97, v131
	v_fma_f32 v132, v90, v94, v134
	v_fma_f32 v133, v91, v95, v135
	v_fma_f32 v136, v82, v86, v136
	v_fma_f32 v137, v83, v87, v137
	v_mul_f32_e32 v82, v133, v133
	v_mul_f32_e32 v83, v131, v131
	v_fma_f32 v134, v84, v88, v148
	v_fma_f32 v135, v85, v89, v149
	v_fmac_f32_e32 v82, v132, v132
	v_fmac_f32_e32 v83, v130, v130
	v_add_f32_e32 v82, v82, v83
	v_mul_f32_e32 v83, v137, v137
	v_mul_f32_e32 v84, v135, v135
	v_fmac_f32_e32 v83, v136, v136
	v_fmac_f32_e32 v84, v134, v134
	v_add_f32_e32 v83, v83, v84
	v_add_f32_e32 v82, v82, v83
	v_add_f32_e32 v82, v202, v82
	ds_bpermute_b32 v83, v187, v82
	s_mov_b64 s[42:43], 0x10100
	v_lshl_add_u64 v[198:199], v[182:183], 0, s[12:13]
	v_lshl_add_u64 v[200:201], v[182:183], 0, s[42:43]
	v_cvt_pk_bf16_f32 v146, v110, v111
	s_waitcnt lgkmcnt(0)
	v_add_f32_e32 v82, v82, v83
	ds_bpermute_b32 v83, v188, v82
	v_cvt_pk_bf16_f32 v147, v112, v113
	v_cvt_pk_bf16_f32 v148, v106, v107
	v_cvt_pk_bf16_f32 v149, v108, v109
	global_store_dwordx4 v[198:199], v[146:149], off
	v_cvt_pk_bf16_f32 v90, v132, v133
	v_cvt_pk_bf16_f32 v91, v130, v131
	v_cvt_pk_bf16_f32 v92, v136, v137
	v_cvt_pk_bf16_f32 v93, v134, v135
	global_store_dwordx4 v[200:201], v[90:93], off
	s_and_saveexec_b64 s[42:43], s[4:5]
	v_readlane_b32 s64, v253, 52
	v_readlane_b32 s66, v253, 58
	v_readlane_b32 s65, v253, 53
	v_readlane_b32 s67, v253, 59
	s_cbranch_execz .LBB0_2366
	s_waitcnt lgkmcnt(0)
	v_add_f32_e32 v82, v82, v83
	ds_write_b32 v197, v82 offset:512
.LBB0_2366:
	s_or_b64 exec, exec, s[42:43]
	v_add_co_u32_e32 v82, vcc, 0x40000, v182
	s_waitcnt vmcnt(3)
	v_lshlrev_b32_e32 v146, 16, v118
	s_waitcnt lgkmcnt(0)
	v_addc_co_u32_e32 v83, vcc, 0, v183, vcc
	global_load_dwordx4 v[90:93], v[82:83], off
	s_nop 0
	global_load_dwordx4 v[82:85], v[82:83], off offset:256
	v_and_b32_e32 v147, 0xffff0000, v118
	v_lshlrev_b32_e32 v118, 16, v119
	v_and_b32_e32 v119, 0xffff0000, v119
	v_fma_f32 v80, v80, v104, v118
	v_fma_f32 v81, v81, v105, v119
	v_fma_f32 v78, v78, v102, v146
	v_fma_f32 v79, v79, v103, v147
	v_lshlrev_b32_e32 v148, 16, v120
	v_and_b32_e32 v149, 0xffff0000, v120
	v_lshlrev_b32_e32 v120, 16, v121
	v_and_b32_e32 v121, 0xffff0000, v121
	v_mul_f32_e32 v118, v79, v79
	v_mul_f32_e32 v119, v81, v81
	v_fma_f32 v76, v76, v100, v120
	v_fma_f32 v77, v77, v101, v121
	v_fma_f32 v74, v74, v98, v148
	v_fma_f32 v75, v75, v99, v149
	v_fmac_f32_e32 v118, v78, v78
	v_fmac_f32_e32 v119, v80, v80
	v_add_f32_e32 v118, v118, v119
	v_mul_f32_e32 v119, v75, v75
	v_mul_f32_e32 v120, v77, v77
	v_fmac_f32_e32 v119, v74, v74
	v_fmac_f32_e32 v120, v76, v76
	v_add_f32_e32 v119, v119, v120
	v_add_f32_e32 v202, v118, v119
	s_waitcnt vmcnt(4)
	v_lshlrev_b32_e32 v118, 16, v114
	v_and_b32_e32 v119, 0xffff0000, v114
	v_lshlrev_b32_e32 v114, 16, v115
	v_and_b32_e32 v115, 0xffff0000, v115
	v_lshlrev_b32_e32 v120, 16, v116
	v_and_b32_e32 v121, 0xffff0000, v116
	v_lshlrev_b32_e32 v148, 16, v117
	v_and_b32_e32 v149, 0xffff0000, v117
	v_fma_f32 v114, v72, v96, v114
	v_fma_f32 v115, v73, v97, v115
	v_fma_f32 v116, v70, v94, v118
	v_fma_f32 v117, v71, v95, v119
	v_fma_f32 v120, v66, v86, v120
	v_fma_f32 v121, v67, v87, v121
	v_mul_f32_e32 v66, v117, v117
	v_mul_f32_e32 v67, v115, v115
	v_fma_f32 v118, v68, v88, v148
	v_fma_f32 v119, v69, v89, v149
	v_fmac_f32_e32 v66, v116, v116
	v_fmac_f32_e32 v67, v114, v114
	v_add_f32_e32 v66, v66, v67
	v_mul_f32_e32 v67, v121, v121
	v_mul_f32_e32 v68, v119, v119
	v_fmac_f32_e32 v67, v120, v120
	v_fmac_f32_e32 v68, v118, v118
	v_add_f32_e32 v67, v67, v68
	v_add_f32_e32 v66, v66, v67
	v_add_f32_e32 v66, v202, v66
	ds_bpermute_b32 v67, v187, v66
	s_mov_b64 s[42:43], 0x18000
	v_lshl_add_u64 v[198:199], v[182:183], 0, s[42:43]
	s_mov_b64 s[42:43], 0x18100
	v_lshl_add_u64 v[200:201], v[182:183], 0, s[42:43]
	s_waitcnt lgkmcnt(0)
	v_add_f32_e32 v66, v66, v67
	ds_bpermute_b32 v67, v188, v66
	v_cvt_pk_bf16_f32 v146, v78, v79
	v_cvt_pk_bf16_f32 v147, v80, v81
	v_cvt_pk_bf16_f32 v148, v74, v75
	v_cvt_pk_bf16_f32 v149, v76, v77
	global_store_dwordx4 v[198:199], v[146:149], off
	v_cvt_pk_bf16_f32 v68, v116, v117
	v_cvt_pk_bf16_f32 v69, v114, v115
	v_cvt_pk_bf16_f32 v70, v120, v121
	v_cvt_pk_bf16_f32 v71, v118, v119
	global_store_dwordx4 v[200:201], v[68:71], off
	s_and_saveexec_b64 s[42:43], s[4:5]
	s_cbranch_execz .LBB0_2368
	s_waitcnt lgkmcnt(0)
	v_add_f32_e32 v66, v66, v67
	ds_write_b32 v197, v66 offset:768
.LBB0_2368:
	s_or_b64 exec, exec, s[42:43]
	v_add_co_u32_e32 v66, vcc, 0x48000, v182
	s_waitcnt vmcnt(3)
	v_lshlrev_b32_e32 v146, 16, v90
	s_waitcnt lgkmcnt(0)
	v_addc_co_u32_e32 v67, vcc, 0, v183, vcc
	global_load_dwordx4 v[70:73], v[66:67], off
	s_nop 0
	global_load_dwordx4 v[66:69], v[66:67], off offset:256
	v_and_b32_e32 v147, 0xffff0000, v90
	v_lshlrev_b32_e32 v90, 16, v91
	v_and_b32_e32 v91, 0xffff0000, v91
	v_fma_f32 v64, v64, v104, v90
	v_fma_f32 v65, v65, v105, v91
	v_fma_f32 v62, v62, v102, v146
	v_fma_f32 v63, v63, v103, v147
	v_lshlrev_b32_e32 v148, 16, v92
	v_and_b32_e32 v149, 0xffff0000, v92
	v_lshlrev_b32_e32 v92, 16, v93
	v_and_b32_e32 v93, 0xffff0000, v93
	v_mul_f32_e32 v90, v63, v63
	v_mul_f32_e32 v91, v65, v65
	v_fma_f32 v60, v60, v100, v92
	v_fma_f32 v61, v61, v101, v93
	v_fma_f32 v58, v58, v98, v148
	v_fma_f32 v59, v59, v99, v149
	v_fmac_f32_e32 v90, v62, v62
	v_fmac_f32_e32 v91, v64, v64
	v_add_f32_e32 v90, v90, v91
	v_mul_f32_e32 v91, v59, v59
	v_mul_f32_e32 v92, v61, v61
	v_fmac_f32_e32 v91, v58, v58
	v_fmac_f32_e32 v92, v60, v60
	v_add_f32_e32 v91, v91, v92
	v_add_f32_e32 v202, v90, v91
	s_waitcnt vmcnt(4)
	v_lshlrev_b32_e32 v90, 16, v82
	v_and_b32_e32 v91, 0xffff0000, v82
	v_lshlrev_b32_e32 v82, 16, v83
	v_and_b32_e32 v83, 0xffff0000, v83
	v_lshlrev_b32_e32 v92, 16, v84
	v_and_b32_e32 v93, 0xffff0000, v84
	v_lshlrev_b32_e32 v148, 16, v85
	v_and_b32_e32 v149, 0xffff0000, v85
	v_fma_f32 v82, v56, v96, v82
	v_fma_f32 v83, v57, v97, v83
	v_fma_f32 v84, v54, v94, v90
	v_fma_f32 v85, v55, v95, v91
	v_fma_f32 v92, v50, v86, v92
	v_fma_f32 v93, v51, v87, v93
	v_mul_f32_e32 v50, v85, v85
	v_mul_f32_e32 v51, v83, v83
	v_fma_f32 v90, v52, v88, v148
	v_fma_f32 v91, v53, v89, v149
	v_fmac_f32_e32 v50, v84, v84
	v_fmac_f32_e32 v51, v82, v82
	v_add_f32_e32 v50, v50, v51
	v_mul_f32_e32 v51, v93, v93
	v_mul_f32_e32 v52, v91, v91
	v_fmac_f32_e32 v51, v92, v92
	v_fmac_f32_e32 v52, v90, v90
	v_add_f32_e32 v51, v51, v52
	v_add_f32_e32 v50, v50, v51
	v_add_f32_e32 v50, v202, v50
	ds_bpermute_b32 v51, v187, v50
	s_mov_b64 s[42:43], 0x40000
	v_lshl_add_u64 v[198:199], v[182:183], 0, s[42:43]
	s_mov_b64 s[42:43], 0x40100
	v_lshl_add_u64 v[200:201], v[182:183], 0, s[42:43]
	s_waitcnt lgkmcnt(0)
	v_add_f32_e32 v50, v50, v51
	ds_bpermute_b32 v51, v188, v50
	v_cvt_pk_bf16_f32 v146, v62, v63
	v_cvt_pk_bf16_f32 v147, v64, v65
	v_cvt_pk_bf16_f32 v148, v58, v59
	v_cvt_pk_bf16_f32 v149, v60, v61
	global_store_dwordx4 v[198:199], v[146:149], off
	v_cvt_pk_bf16_f32 v52, v84, v85
	v_cvt_pk_bf16_f32 v53, v82, v83
	v_cvt_pk_bf16_f32 v54, v92, v93
	v_cvt_pk_bf16_f32 v55, v90, v91
	global_store_dwordx4 v[200:201], v[52:55], off
	s_and_saveexec_b64 s[42:43], s[4:5]
	s_cbranch_execz .LBB0_2370
	s_waitcnt lgkmcnt(0)
	v_add_f32_e32 v50, v50, v51
	ds_write_b32 v192, v50
.LBB0_2370:
	s_or_b64 exec, exec, s[42:43]
	v_add_co_u32_e32 v50, vcc, 0x50000, v182
	s_waitcnt vmcnt(3)
	v_lshlrev_b32_e32 v146, 16, v70
	s_waitcnt lgkmcnt(0)
	v_addc_co_u32_e32 v51, vcc, 0, v183, vcc
	global_load_dwordx4 v[54:57], v[50:51], off
	s_nop 0
	global_load_dwordx4 v[50:53], v[50:51], off offset:256
	v_and_b32_e32 v147, 0xffff0000, v70
	v_lshlrev_b32_e32 v70, 16, v71
	v_and_b32_e32 v71, 0xffff0000, v71
	v_fma_f32 v48, v48, v104, v70
	v_fma_f32 v49, v49, v105, v71
	v_fma_f32 v46, v46, v102, v146
	v_fma_f32 v47, v47, v103, v147
	v_lshlrev_b32_e32 v148, 16, v72
	v_and_b32_e32 v149, 0xffff0000, v72
	v_lshlrev_b32_e32 v72, 16, v73
	v_and_b32_e32 v73, 0xffff0000, v73
	v_mul_f32_e32 v70, v47, v47
	v_mul_f32_e32 v71, v49, v49
	v_fma_f32 v44, v44, v100, v72
	v_fma_f32 v45, v45, v101, v73
	v_fma_f32 v42, v42, v98, v148
	v_fma_f32 v43, v43, v99, v149
	v_fmac_f32_e32 v70, v46, v46
	v_fmac_f32_e32 v71, v48, v48
	v_add_f32_e32 v70, v70, v71
	v_mul_f32_e32 v71, v43, v43
	v_mul_f32_e32 v72, v45, v45
	v_fmac_f32_e32 v71, v42, v42
	v_fmac_f32_e32 v72, v44, v44
	v_add_f32_e32 v71, v71, v72
	v_add_f32_e32 v202, v70, v71
	s_waitcnt vmcnt(4)
	v_lshlrev_b32_e32 v70, 16, v66
	v_and_b32_e32 v71, 0xffff0000, v66
	v_lshlrev_b32_e32 v66, 16, v67
	v_and_b32_e32 v67, 0xffff0000, v67
	v_lshlrev_b32_e32 v72, 16, v68
	v_and_b32_e32 v73, 0xffff0000, v68
	v_lshlrev_b32_e32 v148, 16, v69
	v_and_b32_e32 v149, 0xffff0000, v69
	v_fma_f32 v66, v40, v96, v66
	v_fma_f32 v67, v41, v97, v67
	v_fma_f32 v68, v38, v94, v70
	v_fma_f32 v69, v39, v95, v71
	v_fma_f32 v72, v34, v86, v72
	v_fma_f32 v73, v35, v87, v73
	v_mul_f32_e32 v34, v69, v69
	v_mul_f32_e32 v35, v67, v67
	v_fma_f32 v70, v36, v88, v148
	v_fma_f32 v71, v37, v89, v149
	v_fmac_f32_e32 v34, v68, v68
	v_fmac_f32_e32 v35, v66, v66
	v_add_f32_e32 v34, v34, v35
	v_mul_f32_e32 v35, v73, v73
	v_mul_f32_e32 v36, v71, v71
	v_fmac_f32_e32 v35, v72, v72
	v_fmac_f32_e32 v36, v70, v70
	v_add_f32_e32 v35, v35, v36
	v_add_f32_e32 v34, v34, v35
	v_add_f32_e32 v34, v202, v34
	ds_bpermute_b32 v35, v187, v34
	s_mov_b64 s[42:43], 0x48000
	v_lshl_add_u64 v[198:199], v[182:183], 0, s[42:43]
	s_mov_b64 s[42:43], 0x48100
	v_lshl_add_u64 v[200:201], v[182:183], 0, s[42:43]
	s_waitcnt lgkmcnt(0)
	v_add_f32_e32 v34, v34, v35
	ds_bpermute_b32 v35, v188, v34
	v_cvt_pk_bf16_f32 v146, v46, v47
	v_cvt_pk_bf16_f32 v147, v48, v49
	v_cvt_pk_bf16_f32 v148, v42, v43
	v_cvt_pk_bf16_f32 v149, v44, v45
	global_store_dwordx4 v[198:199], v[146:149], off
	v_cvt_pk_bf16_f32 v36, v68, v69
	v_cvt_pk_bf16_f32 v37, v66, v67
	v_cvt_pk_bf16_f32 v38, v72, v73
	v_cvt_pk_bf16_f32 v39, v70, v71
	global_store_dwordx4 v[200:201], v[36:39], off
	s_and_saveexec_b64 s[42:43], s[4:5]
	s_cbranch_execz .LBB0_2372
	s_waitcnt lgkmcnt(0)
	v_add_f32_e32 v34, v34, v35
	ds_write_b32 v193, v34
.LBB0_2372:
	s_or_b64 exec, exec, s[42:43]
	v_add_co_u32_e32 v34, vcc, 0x58000, v182
	s_waitcnt vmcnt(3)
	v_lshlrev_b32_e32 v198, 16, v54
	s_waitcnt lgkmcnt(0)
	v_addc_co_u32_e32 v35, vcc, 0, v183, vcc
	global_load_dwordx4 v[38:41], v[34:35], off
	s_nop 0
	global_load_dwordx4 v[34:37], v[34:35], off offset:256
	v_and_b32_e32 v199, 0xffff0000, v54
	v_lshlrev_b32_e32 v54, 16, v55
	v_and_b32_e32 v55, 0xffff0000, v55
	v_lshlrev_b32_e32 v200, 16, v56
	v_and_b32_e32 v201, 0xffff0000, v56
	v_lshlrev_b32_e32 v56, 16, v57
	v_and_b32_e32 v57, 0xffff0000, v57
	v_fma_f32 v32, v32, v104, v54
	v_fma_f32 v33, v33, v105, v55
	v_fma_f32 v30, v30, v102, v198
	v_fma_f32 v31, v31, v103, v199
	v_fma_f32 v28, v28, v100, v56
	v_fma_f32 v29, v29, v101, v57
	v_mul_f32_e32 v56, v31, v31
	v_mul_f32_e32 v57, v33, v33
	v_fma_f32 v26, v26, v98, v200
	v_fma_f32 v27, v27, v99, v201
	v_fmac_f32_e32 v56, v30, v30
	v_fmac_f32_e32 v57, v32, v32
	v_add_f32_e32 v56, v56, v57
	v_mul_f32_e32 v57, v27, v27
	v_mul_f32_e32 v198, v29, v29
	v_fmac_f32_e32 v57, v26, v26
	v_fmac_f32_e32 v198, v28, v28
	v_add_f32_e32 v57, v57, v198
	v_add_f32_e32 v200, v56, v57
	s_waitcnt vmcnt(4)
	v_lshlrev_b32_e32 v56, 16, v50
	v_and_b32_e32 v57, 0xffff0000, v50
	v_lshlrev_b32_e32 v50, 16, v51
	v_and_b32_e32 v51, 0xffff0000, v51
	v_fma_f32 v24, v24, v96, v50
	v_fma_f32 v25, v25, v97, v51
	v_fma_f32 v22, v22, v94, v56
	v_fma_f32 v23, v23, v95, v57
	v_lshlrev_b32_e32 v198, 16, v52
	v_and_b32_e32 v199, 0xffff0000, v52
	v_lshlrev_b32_e32 v52, 16, v53
	v_and_b32_e32 v53, 0xffff0000, v53
	v_mul_f32_e32 v50, v23, v23
	v_mul_f32_e32 v51, v25, v25
	v_fma_f32 v20, v20, v88, v52
	v_fma_f32 v21, v21, v89, v53
	v_fma_f32 v18, v18, v86, v198
	v_fma_f32 v19, v19, v87, v199
	v_fmac_f32_e32 v50, v22, v22
	v_fmac_f32_e32 v51, v24, v24
	v_add_f32_e32 v50, v50, v51
	v_mul_f32_e32 v51, v19, v19
	v_mul_f32_e32 v52, v21, v21
	v_fmac_f32_e32 v51, v18, v18
	v_fmac_f32_e32 v52, v20, v20
	v_add_f32_e32 v51, v51, v52
	v_add_f32_e32 v50, v50, v51
	v_add_f32_e32 v50, v200, v50
	ds_bpermute_b32 v51, v187, v50
	s_mov_b64 s[42:43], 0x50000
	v_lshl_add_u64 v[146:147], v[182:183], 0, s[42:43]
	s_mov_b64 s[42:43], 0x50100
	v_lshl_add_u64 v[148:149], v[182:183], 0, s[42:43]
	s_waitcnt lgkmcnt(0)
	v_add_f32_e32 v50, v50, v51
	ds_bpermute_b32 v51, v188, v50
	v_cvt_pk_bf16_f32 v54, v30, v31
	v_cvt_pk_bf16_f32 v55, v32, v33
	v_cvt_pk_bf16_f32 v56, v26, v27
	v_cvt_pk_bf16_f32 v57, v28, v29
	global_store_dwordx4 v[146:147], v[54:57], off
	v_cvt_pk_bf16_f32 v52, v22, v23
	v_cvt_pk_bf16_f32 v53, v24, v25
	s_nop 1
	v_cvt_pk_bf16_f32 v54, v18, v19
	v_cvt_pk_bf16_f32 v55, v20, v21
	global_store_dwordx4 v[148:149], v[52:55], off
	s_and_saveexec_b64 s[42:43], s[4:5]
	s_cbranch_execz .LBB0_2374
	s_waitcnt lgkmcnt(0)
	v_add_f32_e32 v50, v50, v51
	ds_write_b32 v194, v50
.LBB0_2374:
	s_or_b64 exec, exec, s[42:43]
	s_waitcnt vmcnt(3)
	v_lshlrev_b32_e32 v50, 16, v38
	s_waitcnt lgkmcnt(0)
	v_and_b32_e32 v51, 0xffff0000, v38
	v_lshlrev_b32_e32 v38, 16, v39
	v_and_b32_e32 v39, 0xffff0000, v39
	v_lshlrev_b32_e32 v52, 16, v40
	v_and_b32_e32 v53, 0xffff0000, v40
	v_lshlrev_b32_e32 v54, 16, v41
	v_and_b32_e32 v55, 0xffff0000, v41
	v_fma_f32 v38, v16, v104, v38
	v_fma_f32 v39, v17, v105, v39
	v_fma_f32 v40, v14, v102, v50
	v_fma_f32 v41, v15, v103, v51
	v_fma_f32 v50, v12, v100, v54
	v_fma_f32 v51, v13, v101, v55
	v_mul_f32_e32 v12, v41, v41
	v_mul_f32_e32 v13, v39, v39
	v_fma_f32 v52, v10, v98, v52
	v_fma_f32 v53, v11, v99, v53
	v_fmac_f32_e32 v12, v40, v40
	v_fmac_f32_e32 v13, v38, v38
	v_add_f32_e32 v12, v12, v13
	v_mul_f32_e32 v13, v53, v53
	v_mul_f32_e32 v14, v51, v51
	v_fmac_f32_e32 v13, v52, v52
	v_fmac_f32_e32 v14, v50, v50
	v_add_f32_e32 v13, v13, v14
	v_add_f32_e32 v98, v12, v13
	s_waitcnt vmcnt(2)
	v_lshlrev_b32_e32 v12, 16, v34
	v_and_b32_e32 v13, 0xffff0000, v34
	v_lshlrev_b32_e32 v14, 16, v35
	v_and_b32_e32 v15, 0xffff0000, v35
	v_lshlrev_b32_e32 v16, 16, v36
	v_and_b32_e32 v17, 0xffff0000, v36
	v_lshlrev_b32_e32 v54, 16, v37
	v_and_b32_e32 v55, 0xffff0000, v37
	v_fma_f32 v34, v8, v96, v14
	v_fma_f32 v35, v9, v97, v15
	v_fma_f32 v36, v6, v94, v12
	v_fma_f32 v37, v7, v95, v13
	v_fma_f32 v56, v2, v86, v16
	v_fma_f32 v57, v3, v87, v17
	v_mul_f32_e32 v2, v37, v37
	v_mul_f32_e32 v3, v35, v35
	v_fma_f32 v54, v4, v88, v54
	v_fma_f32 v55, v5, v89, v55
	v_fmac_f32_e32 v2, v36, v36
	v_fmac_f32_e32 v3, v34, v34
	v_add_f32_e32 v2, v2, v3
	v_mul_f32_e32 v3, v57, v57
	v_mul_f32_e32 v4, v55, v55
	v_fmac_f32_e32 v3, v56, v56
	v_fmac_f32_e32 v4, v54, v54
	v_add_f32_e32 v3, v3, v4
	v_add_f32_e32 v2, v2, v3
	v_add_f32_e32 v2, v98, v2
	ds_bpermute_b32 v3, v187, v2
	s_mov_b64 s[42:43], 0x58000
	v_lshl_add_u64 v[146:147], v[182:183], 0, s[42:43]
	s_mov_b64 s[42:43], 0x58100
	s_waitcnt lgkmcnt(0)
	v_add_f32_e32 v2, v2, v3
	ds_bpermute_b32 v3, v188, v2
	v_lshl_add_u64 v[148:149], v[182:183], 0, s[42:43]
	v_cvt_pk_bf16_f32 v10, v40, v41
	v_cvt_pk_bf16_f32 v11, v38, v39
	v_cvt_pk_bf16_f32 v12, v52, v53
	v_cvt_pk_bf16_f32 v13, v50, v51
	global_store_dwordx4 v[146:147], v[10:13], off
	v_cvt_pk_bf16_f32 v4, v36, v37
	v_cvt_pk_bf16_f32 v5, v34, v35
	v_cvt_pk_bf16_f32 v6, v56, v57
	v_cvt_pk_bf16_f32 v7, v54, v55
	global_store_dwordx4 v[148:149], v[4:7], off
	s_and_saveexec_b64 s[42:43], s[4:5]
	s_cbranch_execz .LBB0_2376
	s_waitcnt lgkmcnt(0)
	v_add_f32_e32 v2, v2, v3
	ds_write_b32 v195, v2
.LBB0_2376:
	s_or_b64 exec, exec, s[42:43]
	s_waitcnt lgkmcnt(0)
	s_barrier
	s_ashr_i32 s41, s40, 31
	s_waitcnt lgkmcnt(0)
	v_lshl_add_u64 v[2:3], v[160:161], 0, s[40:41]
	v_lshl_add_u64 v[2:3], v[2:3], 4, s[20:21]
	s_and_saveexec_b64 s[40:41], s[6:7]
	s_cbranch_execz .LBB0_2378
	ds_read_b128 v[4:7], v196
	s_ashr_i32 s37, s36, 31
	v_lshl_add_u64 v[8:9], s[36:37], 2, v[2:3]
	s_waitcnt lgkmcnt(0)
	v_mov_b32_e32 v10, v5
	v_mov_b32_e32 v11, v6
	v_mov_b32_e32 v5, v7
	v_add_f32_e32 v4, v10, v4
	v_add_f32_e32 v5, v11, v5
	s_nop 0
	v_pk_add_f32 v[4:5], v[4:5], v[4:5] op_sel:[0,1] op_sel_hi:[1,0]
	global_store_dword v[8:9], v4, off sc1

.LBB0_2393:
	s_or_b64 exec, exec, s[0:1]
	v_lshlrev_b64 v[2:3], 2, v[168:169]
	v_lshl_add_u64 v[102:103], s[38:39], 0, v[2:3]
	s_mov_b64 s[0:1], 0x6000
	v_lshl_add_u64 v[168:169], v[102:103], 0, s[0:1]
	s_mov_b64 s[0:1], 0x7000
	v_lshl_add_u64 v[104:105], s[10:11], 0, v[2:3]
	v_lshl_add_u64 v[2:3], v[102:103], 0, s[0:1]
	s_movk_i32 s0, 0x7000
	v_add_co_u32_e32 v182, vcc, s0, v102
	s_waitcnt vmcnt(0) lgkmcnt(0)
	s_barrier
	global_load_dwordx4 v[10:13], v[104:105], off offset:16
	global_load_dwordx4 v[14:17], v[104:105], off
	v_addc_co_u32_e32 v183, vcc, 0, v103, vcc
	global_load_dwordx4 v[86:89], v[182:183], off
	global_load_dwordx4 v[98:101], v[2:3], off offset:16
	s_movk_i32 s0, 0x6000
	v_add_co_u32_e32 v2, vcc, s0, v102
	s_mov_b64 s[0:1], 0x7200
	s_nop 0
	v_addc_co_u32_e32 v3, vcc, 0, v103, vcc
	global_load_dwordx4 v[6:9], v[2:3], off
	s_nop 0
	global_load_dwordx4 v[2:5], v[168:169], off offset:16
	s_waitcnt vmcnt(3)
	v_add_f32_e32 v88, 1.0, v88
	v_add_f32_e32 v89, 1.0, v89
	v_add_f32_e32 v86, 1.0, v86
	v_add_f32_e32 v87, 1.0, v87
	v_mul_f32_e32 v94, v16, v88
	v_mul_f32_e32 v95, v17, v89
	s_waitcnt vmcnt(2)
	v_add_f32_e32 v16, 1.0, v98
	v_add_f32_e32 v17, 1.0, v99
	v_mul_f32_e32 v96, v14, v86
	v_mul_f32_e32 v97, v15, v87
	v_add_f32_e32 v14, 1.0, v100
	v_add_f32_e32 v15, 1.0, v101
	v_mul_f32_e32 v88, v10, v16
	v_mul_f32_e32 v89, v11, v17
	v_lshl_add_u64 v[10:11], v[102:103], 0, s[0:1]
	v_mul_f32_e32 v86, v12, v14
	v_mul_f32_e32 v87, v13, v15
	global_load_dwordx4 v[146:149], v[104:105], off offset:528
	global_load_dwordx4 v[98:101], v[104:105], off offset:512
	s_nop 0
	global_load_dwordx4 v[102:105], v[182:183], off offset:512
	global_load_dwordx4 v[198:201], v[10:11], off offset:16
	s_nop 0
	global_load_dwordx4 v[10:13], v[168:169], off offset:528
	global_load_dwordx4 v[14:17], v[168:169], off offset:512
	s_mov_b32 s0, 0x10000
	s_waitcnt vmcnt(3)
	v_add_f32_e32 v104, 1.0, v104
	v_add_f32_e32 v105, 1.0, v105
	v_add_f32_e32 v168, 1.0, v102
	v_add_f32_e32 v169, 1.0, v103
	v_mul_f32_e32 v102, v100, v104
	v_mul_f32_e32 v103, v101, v105
	v_mul_f32_e32 v104, v98, v168
	v_mul_f32_e32 v105, v99, v169
	s_waitcnt vmcnt(2)
	v_add_f32_e32 v98, 1.0, v200
	v_add_f32_e32 v99, 1.0, v201
	v_add_f32_e32 v100, 1.0, v198
	v_add_f32_e32 v101, 1.0, v199
	v_mul_f32_e32 v98, v148, v98
	v_mul_f32_e32 v99, v149, v99
	ds_read_b32 v148, v190
	v_mul_f32_e32 v100, v146, v100
	v_mul_f32_e32 v101, v147, v101
	v_lshl_add_u64 v[146:147], v[166:167], 1, s[22:23]
	s_waitcnt lgkmcnt(0)
	v_mul_f32_e32 v140, v140, v148
	v_mul_f32_e32 v141, v141, v148
	v_mul_f32_e32 v138, v138, v148
	v_mul_f32_e32 v139, v139, v148
	v_mul_f32_e32 v144, v144, v148
	v_mul_f32_e32 v145, v145, v148
	v_mul_f32_e32 v142, v142, v148
	v_mul_f32_e32 v143, v143, v148
	v_fma_f32 v166, v86, v140, v4
	v_fma_f32 v167, v87, v141, v5
	v_fma_f32 v140, v88, v138, v2
	v_fma_f32 v141, v89, v139, v3
	v_fma_f32 v144, v94, v144, v8
	v_fma_f32 v145, v95, v145, v9
	v_fma_f32 v142, v96, v142, v6
	v_fma_f32 v143, v97, v143, v7
	s_nop 0
	v_cvt_pk_bf16_f32 v138, v142, v143
	v_cvt_pk_bf16_f32 v139, v144, v145
	v_cvt_pk_bf16_f32 v140, v140, v141
	v_cvt_pk_bf16_f32 v141, v166, v167
	global_store_dwordx4 v[146:147], v[138:141], off
	v_mul_f32_e32 v144, v174, v148
	v_mul_f32_e32 v145, v175, v148
	s_nop 0
	v_mul_f32_e32 v138, v172, v148
	v_mul_f32_e32 v139, v173, v148
	v_mul_f32_e32 v140, v176, v148
	v_mul_f32_e32 v141, v177, v148
	s_waitcnt vmcnt(1)
	v_fma_f32 v142, v102, v138, v16
	v_fma_f32 v143, v103, v139, v17
	v_fma_f32 v138, v104, v140, v14
	v_fma_f32 v139, v105, v141, v15
	v_mul_f32_e32 v140, v170, v148
	v_mul_f32_e32 v141, v171, v148
	v_cvt_pk_bf16_f32 v138, v138, v139
	v_cvt_pk_bf16_f32 v139, v142, v143
	s_nop 0
	v_fma_f32 v148, v98, v140, v12
	v_fma_f32 v149, v99, v141, v13
	v_fma_f32 v140, v100, v144, v10
	v_fma_f32 v141, v101, v145, v11
	s_nop 0
	v_cvt_pk_bf16_f32 v140, v140, v141
	v_cvt_pk_bf16_f32 v141, v148, v149
	global_store_dwordx4 v[146:147], v[138:141], off offset:256
	ds_read_b32 v142, v190 offset:64
	s_waitcnt lgkmcnt(0)
	v_mul_f32_e32 v148, v180, v142
	v_mul_f32_e32 v149, v181, v142
	v_mul_f32_e32 v138, v150, v142
	v_mul_f32_e32 v139, v151, v142
	v_mul_f32_e32 v140, v152, v142
	v_mul_f32_e32 v141, v153, v142
	v_fma_f32 v144, v94, v138, v8
	v_fma_f32 v145, v95, v139, v9
	v_fma_f32 v138, v96, v140, v6
	v_fma_f32 v139, v97, v141, v7
	v_mul_f32_e32 v140, v178, v142
	v_mul_f32_e32 v141, v179, v142
	v_cvt_pk_bf16_f32 v138, v138, v139
	v_cvt_pk_bf16_f32 v139, v144, v145
	v_add_co_u32_e32 v144, vcc, s75, v146
	v_mul_f32_e32 v124, v124, v142
	v_mul_f32_e32 v125, v125, v142
	v_fma_f32 v150, v86, v140, v4
	v_fma_f32 v151, v87, v141, v5
	v_fma_f32 v140, v88, v148, v2
	v_fma_f32 v141, v89, v149, v3
	v_addc_co_u32_e32 v145, vcc, 0, v147, vcc
	v_mul_f32_e32 v128, v128, v142
	v_mul_f32_e32 v129, v129, v142
	v_mul_f32_e32 v126, v126, v142
	v_mul_f32_e32 v127, v127, v142
	v_mul_f32_e32 v122, v122, v142
	v_mul_f32_e32 v123, v123, v142
	v_fma_f32 v124, v100, v124, v10
	v_fma_f32 v125, v101, v125, v11
	v_cvt_pk_bf16_f32 v140, v140, v141
	v_cvt_pk_bf16_f32 v141, v150, v151
	global_store_dwordx4 v[144:145], v[138:141], off
	v_fma_f32 v128, v102, v128, v16
	v_fma_f32 v129, v103, v129, v17
	v_fma_f32 v126, v104, v126, v14
	v_fma_f32 v127, v105, v127, v15
	v_fma_f32 v138, v98, v122, v12
	v_fma_f32 v139, v99, v123, v13
	v_cvt_pk_bf16_f32 v122, v126, v127
	v_cvt_pk_bf16_f32 v123, v128, v129
	v_cvt_pk_bf16_f32 v124, v124, v125
	s_nop 0
	v_cvt_pk_bf16_f32 v125, v138, v139
	global_store_dwordx4 v[144:145], v[122:125], off offset:256
	ds_read_b32 v122, v190 offset:128
	s_waitcnt lgkmcnt(0)
	v_mul_f32_e32 v110, v110, v122
	v_mul_f32_e32 v111, v111, v122
	s_nop 0
	v_fma_f32 v110, v96, v110, v6
	v_fma_f32 v111, v97, v111, v7
	v_mul_f32_e32 v108, v108, v122
	v_mul_f32_e32 v109, v109, v122
	v_mul_f32_e32 v106, v106, v122
	v_mul_f32_e32 v107, v107, v122
	v_mul_f32_e32 v112, v112, v122
	v_mul_f32_e32 v113, v113, v122
	v_fma_f32 v124, v86, v108, v4
	v_fma_f32 v125, v87, v109, v5
	v_fma_f32 v108, v88, v106, v2
	v_fma_f32 v109, v89, v107, v3
	v_cvt_pk_bf16_f32 v106, v110, v111
	v_add_co_u32_e32 v110, vcc, s0, v146
	v_fma_f32 v112, v94, v112, v8
	v_fma_f32 v113, v95, v113, v9
	s_nop 0
	v_addc_co_u32_e32 v111, vcc, 0, v147, vcc
	v_cvt_pk_bf16_f32 v107, v112, v113
	v_cvt_pk_bf16_f32 v108, v108, v109
	v_cvt_pk_bf16_f32 v109, v124, v125
	global_store_dwordx4 v[110:111], v[106:109], off
	s_mov_b32 s0, 0x18000
	s_nop 0
	v_mul_f32_e32 v106, v130, v122
	v_mul_f32_e32 v107, v131, v122
	v_mul_f32_e32 v108, v132, v122
	v_mul_f32_e32 v109, v133, v122
	v_fma_f32 v112, v102, v106, v16
	v_fma_f32 v113, v103, v107, v17
	v_fma_f32 v106, v104, v108, v14
	v_fma_f32 v107, v105, v109, v15
	v_mul_f32_e32 v108, v134, v122
	v_mul_f32_e32 v109, v135, v122
	v_mul_f32_e32 v123, v137, v122
	v_mul_f32_e32 v122, v136, v122
	v_fma_f32 v124, v98, v108, v12
	v_fma_f32 v125, v99, v109, v13
	v_fma_f32 v108, v100, v122, v10
	v_fma_f32 v109, v101, v123, v11
	v_cvt_pk_bf16_f32 v106, v106, v107
	v_cvt_pk_bf16_f32 v107, v112, v113
	s_nop 0
	v_cvt_pk_bf16_f32 v108, v108, v109
	v_cvt_pk_bf16_f32 v109, v124, v125
	global_store_dwordx4 v[110:111], v[106:109], off offset:256
	ds_read_b32 v106, v190 offset:192
	s_waitcnt lgkmcnt(0)
	v_mul_f32_e32 v78, v78, v106
	v_mul_f32_e32 v79, v79, v106
	s_nop 0
	v_fma_f32 v78, v96, v78, v6
	v_fma_f32 v79, v97, v79, v7
	v_mul_f32_e32 v76, v76, v106
	v_mul_f32_e32 v77, v77, v106
	v_mul_f32_e32 v74, v74, v106
	v_mul_f32_e32 v75, v75, v106
	v_mul_f32_e32 v80, v80, v106
	v_mul_f32_e32 v81, v81, v106
	v_fma_f32 v108, v86, v76, v4
	v_fma_f32 v109, v87, v77, v5
	v_fma_f32 v76, v88, v74, v2
	v_fma_f32 v77, v89, v75, v3
	v_cvt_pk_bf16_f32 v74, v78, v79
	v_add_co_u32_e32 v78, vcc, s0, v146
	v_fma_f32 v80, v94, v80, v8
	v_fma_f32 v81, v95, v81, v9
	s_nop 0
	v_addc_co_u32_e32 v79, vcc, 0, v147, vcc
	v_cvt_pk_bf16_f32 v75, v80, v81
	v_cvt_pk_bf16_f32 v76, v76, v77
	v_cvt_pk_bf16_f32 v77, v108, v109
	global_store_dwordx4 v[78:79], v[74:77], off
	s_mov_b32 s0, 0x40000
	s_nop 0
	v_mul_f32_e32 v74, v114, v106
	v_mul_f32_e32 v75, v115, v106
	v_mul_f32_e32 v76, v116, v106
	v_mul_f32_e32 v77, v117, v106
	v_fma_f32 v80, v102, v74, v16
	v_fma_f32 v81, v103, v75, v17
	v_fma_f32 v74, v104, v76, v14
	v_fma_f32 v75, v105, v77, v15
	v_mul_f32_e32 v76, v118, v106
	v_mul_f32_e32 v77, v119, v106
	v_mul_f32_e32 v107, v121, v106
	v_mul_f32_e32 v106, v120, v106
	v_fma_f32 v108, v98, v76, v12
	v_fma_f32 v109, v99, v77, v13
	v_fma_f32 v76, v100, v106, v10
	v_fma_f32 v77, v101, v107, v11
	v_cvt_pk_bf16_f32 v74, v74, v75
	v_cvt_pk_bf16_f32 v75, v80, v81
	s_nop 0
	v_cvt_pk_bf16_f32 v76, v76, v77
	v_cvt_pk_bf16_f32 v77, v108, v109
	global_store_dwordx4 v[78:79], v[74:77], off offset:256
	ds_read_b32 v74, v190 offset:512
	s_waitcnt lgkmcnt(0)
	v_mul_f32_e32 v62, v62, v74
	v_mul_f32_e32 v63, v63, v74
	s_nop 0
	v_fma_f32 v62, v96, v62, v6
	v_fma_f32 v63, v97, v63, v7
	v_mul_f32_e32 v60, v60, v74
	v_mul_f32_e32 v61, v61, v74
	v_mul_f32_e32 v58, v58, v74
	v_mul_f32_e32 v59, v59, v74
	v_mul_f32_e32 v64, v64, v74
	v_mul_f32_e32 v65, v65, v74
	v_fma_f32 v76, v86, v60, v4
	v_fma_f32 v77, v87, v61, v5
	v_fma_f32 v60, v88, v58, v2
	v_fma_f32 v61, v89, v59, v3
	v_cvt_pk_bf16_f32 v58, v62, v63
	v_add_co_u32_e32 v62, vcc, s0, v146
	v_fma_f32 v64, v94, v64, v8
	v_fma_f32 v65, v95, v65, v9
	s_nop 0
	v_addc_co_u32_e32 v63, vcc, 0, v147, vcc
	v_cvt_pk_bf16_f32 v59, v64, v65
	v_cvt_pk_bf16_f32 v60, v60, v61
	v_cvt_pk_bf16_f32 v61, v76, v77
	global_store_dwordx4 v[62:63], v[58:61], off
	s_mov_b32 s0, 0x48000
	s_nop 0
	v_mul_f32_e32 v58, v82, v74
	v_mul_f32_e32 v59, v83, v74
	v_mul_f32_e32 v60, v84, v74
	v_mul_f32_e32 v61, v85, v74
	v_fma_f32 v64, v102, v58, v16
	v_fma_f32 v65, v103, v59, v17
	v_fma_f32 v58, v104, v60, v14
	v_fma_f32 v59, v105, v61, v15
	v_mul_f32_e32 v60, v90, v74
	v_mul_f32_e32 v61, v91, v74
	v_mul_f32_e32 v75, v93, v74
	v_mul_f32_e32 v74, v92, v74
	v_fma_f32 v76, v98, v60, v12
	v_fma_f32 v77, v99, v61, v13
	v_fma_f32 v60, v100, v74, v10
	v_fma_f32 v61, v101, v75, v11
	v_cvt_pk_bf16_f32 v58, v58, v59
	v_cvt_pk_bf16_f32 v59, v64, v65
	s_nop 0
	v_cvt_pk_bf16_f32 v60, v60, v61
	v_cvt_pk_bf16_f32 v61, v76, v77
	global_store_dwordx4 v[62:63], v[58:61], off offset:256
	ds_read_b32 v58, v190 offset:576
	s_waitcnt lgkmcnt(0)
	v_mul_f32_e32 v46, v46, v58
	v_mul_f32_e32 v47, v47, v58
	s_nop 0
	v_fma_f32 v46, v96, v46, v6
	v_fma_f32 v47, v97, v47, v7
	v_mul_f32_e32 v44, v44, v58
	v_mul_f32_e32 v45, v45, v58
	v_mul_f32_e32 v42, v42, v58
	v_mul_f32_e32 v43, v43, v58
	v_mul_f32_e32 v48, v48, v58
	v_mul_f32_e32 v49, v49, v58
	v_fma_f32 v60, v86, v44, v4
	v_fma_f32 v61, v87, v45, v5
	v_fma_f32 v44, v88, v42, v2
	v_fma_f32 v45, v89, v43, v3
	v_cvt_pk_bf16_f32 v42, v46, v47
	v_add_co_u32_e32 v46, vcc, s0, v146
	v_fma_f32 v48, v94, v48, v8
	v_fma_f32 v49, v95, v49, v9
	s_nop 0
	v_addc_co_u32_e32 v47, vcc, 0, v147, vcc
	v_cvt_pk_bf16_f32 v43, v48, v49
	v_cvt_pk_bf16_f32 v44, v44, v45
	v_cvt_pk_bf16_f32 v45, v60, v61
	global_store_dwordx4 v[46:47], v[42:45], off
	s_mov_b32 s0, 0x50000
	s_nop 0
	v_mul_f32_e32 v42, v66, v58
	v_mul_f32_e32 v43, v67, v58
	v_mul_f32_e32 v44, v68, v58
	v_mul_f32_e32 v45, v69, v58
	v_fma_f32 v48, v102, v42, v16
	v_fma_f32 v49, v103, v43, v17
	v_fma_f32 v42, v104, v44, v14
	v_fma_f32 v43, v105, v45, v15
	v_mul_f32_e32 v44, v70, v58
	v_mul_f32_e32 v45, v71, v58
	v_mul_f32_e32 v59, v73, v58
	v_mul_f32_e32 v58, v72, v58
	v_fma_f32 v60, v98, v44, v12
	v_fma_f32 v61, v99, v45, v13
	v_fma_f32 v44, v100, v58, v10
	v_fma_f32 v45, v101, v59, v11
	v_cvt_pk_bf16_f32 v42, v42, v43
	v_cvt_pk_bf16_f32 v43, v48, v49
	s_nop 0
	v_cvt_pk_bf16_f32 v44, v44, v45
	v_cvt_pk_bf16_f32 v45, v60, v61
	global_store_dwordx4 v[46:47], v[42:45], off offset:256
	ds_read_b32 v42, v190 offset:640
	s_waitcnt lgkmcnt(0)
	v_mul_f32_e32 v30, v30, v42
	v_mul_f32_e32 v31, v31, v42
	s_nop 0
	v_fma_f32 v30, v96, v30, v6
	v_fma_f32 v31, v97, v31, v7
	v_mul_f32_e32 v28, v28, v42
	v_mul_f32_e32 v29, v29, v42
	v_mul_f32_e32 v26, v26, v42
	v_mul_f32_e32 v27, v27, v42
	v_mul_f32_e32 v32, v32, v42
	v_mul_f32_e32 v33, v33, v42
	v_fma_f32 v44, v86, v28, v4
	v_fma_f32 v45, v87, v29, v5
	v_fma_f32 v28, v88, v26, v2
	v_fma_f32 v29, v89, v27, v3
	v_cvt_pk_bf16_f32 v26, v30, v31
	v_add_co_u32_e32 v30, vcc, s0, v146
	v_fma_f32 v32, v94, v32, v8
	v_fma_f32 v33, v95, v33, v9
	s_nop 0
	v_addc_co_u32_e32 v31, vcc, 0, v147, vcc
	v_cvt_pk_bf16_f32 v27, v32, v33
	v_mul_f32_e32 v20, v20, v42
	v_mul_f32_e32 v21, v21, v42
	v_mul_f32_e32 v18, v18, v42
	v_mul_f32_e32 v19, v19, v42
	v_cvt_pk_bf16_f32 v28, v28, v29
	v_cvt_pk_bf16_f32 v29, v44, v45
	global_store_dwordx4 v[30:31], v[26:29], off
	v_mul_f32_e32 v24, v24, v42
	v_mul_f32_e32 v25, v25, v42
	v_mul_f32_e32 v22, v22, v42
	v_mul_f32_e32 v23, v23, v42
	v_fma_f32 v26, v98, v20, v12
	v_fma_f32 v27, v99, v21, v13
	v_fma_f32 v20, v100, v18, v10
	v_fma_f32 v21, v101, v19, v11
	v_fma_f32 v24, v102, v24, v16
	v_fma_f32 v25, v103, v25, v17
	v_fma_f32 v22, v104, v22, v14
	v_fma_f32 v23, v105, v23, v15
	s_mov_b32 s0, 0x58000
	v_cvt_pk_bf16_f32 v18, v22, v23
	v_cvt_pk_bf16_f32 v19, v24, v25
	v_cvt_pk_bf16_f32 v20, v20, v21
	v_cvt_pk_bf16_f32 v21, v26, v27
	global_store_dwordx4 v[30:31], v[18:21], off offset:256
	ds_read_b32 v18, v190 offset:704
	s_waitcnt lgkmcnt(0)
	v_mul_f32_e32 v22, v40, v18
	v_mul_f32_e32 v23, v41, v18
	v_mul_f32_e32 v20, v38, v18
	v_mul_f32_e32 v21, v39, v18
	v_fma_f32 v6, v96, v22, v6
	v_fma_f32 v7, v97, v23, v7
	v_fma_f32 v8, v94, v20, v8
	v_fma_f32 v9, v95, v21, v9
	v_mul_f32_e32 v20, v50, v18
	v_mul_f32_e32 v21, v51, v18
	v_mul_f32_e32 v22, v52, v18
	v_mul_f32_e32 v23, v53, v18
	v_fma_f32 v20, v86, v20, v4
	v_fma_f32 v21, v87, v21, v5
	v_fma_f32 v4, v88, v22, v2
	v_fma_f32 v5, v89, v23, v3
	v_cvt_pk_bf16_f32 v2, v6, v7
	v_add_co_u32_e32 v6, vcc, s0, v146
	v_cvt_pk_bf16_f32 v3, v8, v9
	v_cvt_pk_bf16_f32 v4, v4, v5
	v_cvt_pk_bf16_f32 v5, v20, v21
	s_mov_b64 s[0:1], -1
	s_nop 0
	v_addc_co_u32_e32 v7, vcc, 0, v147, vcc
	global_store_dwordx4 v[6:7], v[2:5], off
	s_andn2_b64 vcc, exec, s[28:29]
	s_nop 0
	v_mul_f32_e32 v2, v34, v18
	v_mul_f32_e32 v3, v35, v18
	v_mul_f32_e32 v4, v36, v18
	v_mul_f32_e32 v5, v37, v18
	v_fma_f32 v8, v102, v2, v16
	v_fma_f32 v9, v103, v3, v17
	v_fma_f32 v2, v104, v4, v14
	v_fma_f32 v3, v105, v5, v15
	v_mul_f32_e32 v4, v54, v18
	v_mul_f32_e32 v5, v55, v18
	v_mul_f32_e32 v14, v56, v18
	v_mul_f32_e32 v15, v57, v18
	v_fma_f32 v12, v98, v4, v12
	v_fma_f32 v13, v99, v5, v13
	v_fma_f32 v4, v100, v14, v10
	v_fma_f32 v5, v101, v15, v11
	v_cvt_pk_bf16_f32 v2, v2, v3
	v_cvt_pk_bf16_f32 v3, v8, v9
	s_nop 0
	v_cvt_pk_bf16_f32 v4, v4, v5
	v_cvt_pk_bf16_f32 v5, v12, v13
	global_store_dwordx4 v[6:7], v[2:5], off offset:256
	s_cbranch_vccnz .LBB0_2349
	s_andn2_b64 vcc, exec, s[2:3]
	s_cbranch_vccnz .LBB0_2348
	s_barrier
	s_branch .LBB0_2348

.LBB0_2548:
	s_ashr_i32 s1, s62, 5
	s_mul_hi_i32 s31, s1, 0x2400
	s_mul_i32 s30, s1, 0x2400
	s_lshl_b32 s34, s62, 8
	s_lshl_b64 s[30:31], s[30:31], 2
	v_lshl_or_b32 v152, s0, 8, v186
	s_add_u32 s36, s50, s30
	v_ashrrev_i32_e32 v153, 31, v152
	s_addc_u32 s37, s51, s31
	v_lshl_add_u64 v[130:131], v[152:153], 2, s[36:37]
	s_mov_b64 s[36:37], 0x8000
	v_lshl_add_u64 v[154:155], v[130:131], 0, s[36:37]
	v_add_co_u32_e32 v130, vcc, s75, v130
	v_add_u32_e32 v150, s34, v184
	s_nop 0
	v_addc_co_u32_e32 v131, vcc, 0, v131, vcc
	global_load_dwordx4 v[130:133], v[130:131], off
	s_nop 0
	global_load_dwordx4 v[134:137], v[154:155], off offset:16
	v_ashrrev_i32_e32 v151, 31, v150
	s_waitcnt vmcnt(0)
	v_mul_f32_e32 v180, 0.5, v132
	v_mul_f32_e32 v181, 0.5, v133
	v_mul_f32_e32 v178, 0.5, v130
	v_mul_f32_e32 v179, 0.5, v131
	v_mul_f32_e32 v176, 0.5, v136
	v_mul_f32_e32 v177, 0.5, v137
	v_mul_f32_e32 v174, 0.5, v134
	v_mul_f32_e32 v175, 0.5, v135
	global_load_dwordx4 v[130:133], v[154:155], off offset:528
	global_load_dwordx4 v[134:137], v[154:155], off offset:512
	s_waitcnt vmcnt(1)
	v_mul_f32_e32 v166, 0.5, v130
	v_mul_f32_e32 v167, 0.5, v131
	v_lshlrev_b64 v[130:131], 10, v[150:151]
	v_lshl_add_u64 v[150:151], v[130:131], 0, v[152:153]
	v_lshl_add_u64 v[182:183], v[150:151], 1, s[20:21]
	global_load_dwordx4 v[154:157], v[182:183], off
	global_load_dwordx4 v[158:161], v[182:183], off offset:256
	v_add_co_u32_e32 v130, vcc, s75, v182
	s_waitcnt vmcnt(2)
	v_mul_f32_e32 v172, 0.5, v136
	v_mul_f32_e32 v173, 0.5, v137
	v_addc_co_u32_e32 v131, vcc, 0, v183, vcc
	v_mul_f32_e32 v170, 0.5, v134
	v_mul_f32_e32 v171, 0.5, v135
	v_mul_f32_e32 v168, 0.5, v132
	v_mul_f32_e32 v169, 0.5, v133
	global_load_dwordx4 v[134:137], v[130:131], off
	s_nop 0
	global_load_dwordx4 v[130:133], v[130:131], off offset:256
	s_waitcnt vmcnt(3)
	v_lshlrev_b32_e32 v162, 16, v154
	v_and_b32_e32 v163, 0xffff0000, v154
	v_lshlrev_b32_e32 v154, 16, v155
	v_and_b32_e32 v155, 0xffff0000, v155
	v_lshlrev_b32_e32 v164, 16, v156
	v_and_b32_e32 v165, 0xffff0000, v156
	v_lshlrev_b32_e32 v156, 16, v157
	v_and_b32_e32 v157, 0xffff0000, v157
	v_fma_f32 v128, v128, v180, v154
	v_fma_f32 v129, v129, v181, v155
	v_fma_f32 v126, v126, v178, v162
	v_fma_f32 v127, v127, v179, v163
	v_fma_f32 v124, v124, v176, v156
	v_fma_f32 v125, v125, v177, v157
	v_cvt_pk_bf16_f32 v154, v126, v127
	v_cvt_pk_bf16_f32 v155, v128, v129
	v_fma_f32 v122, v122, v174, v164
	v_fma_f32 v123, v123, v175, v165
	s_waitcnt vmcnt(2)
	v_lshlrev_b32_e32 v162, 16, v160
	v_cvt_pk_bf16_f32 v156, v122, v123
	v_cvt_pk_bf16_f32 v157, v124, v125
	global_store_dwordx4 v[182:183], v[154:157], off
	v_and_b32_e32 v163, 0xffff0000, v160
	v_lshlrev_b32_e32 v164, 16, v161
	v_mul_f32_e32 v154, v127, v127
	v_mul_f32_e32 v155, v129, v129
	v_fmac_f32_e32 v154, v126, v126
	v_fmac_f32_e32 v155, v128, v128
	v_add_f32_e32 v154, v154, v155
	v_mul_f32_e32 v155, v123, v123
	v_mul_f32_e32 v156, v125, v125
	v_fmac_f32_e32 v155, v122, v122
	v_fmac_f32_e32 v156, v124, v124
	v_add_f32_e32 v155, v155, v156
	v_add_f32_e32 v198, v154, v155
	v_lshlrev_b32_e32 v154, 16, v158
	v_and_b32_e32 v155, 0xffff0000, v158
	v_lshlrev_b32_e32 v156, 16, v159
	v_and_b32_e32 v157, 0xffff0000, v159
	v_and_b32_e32 v165, 0xffff0000, v161
	v_fma_f32 v158, v120, v172, v156
	v_fma_f32 v159, v121, v173, v157
	v_fma_f32 v160, v118, v170, v154
	v_fma_f32 v161, v119, v171, v155
	v_fma_f32 v156, v114, v166, v162
	v_fma_f32 v157, v115, v167, v163
	v_cvt_pk_bf16_f32 v114, v160, v161
	v_cvt_pk_bf16_f32 v115, v158, v159
	v_fma_f32 v154, v116, v168, v164
	v_fma_f32 v155, v117, v169, v165
	v_cvt_pk_bf16_f32 v116, v156, v157
	s_nop 0
	v_cvt_pk_bf16_f32 v117, v154, v155
	global_store_dwordx4 v[182:183], v[114:117], off offset:256
	s_nop 1
	v_mul_f32_e32 v114, v161, v161
	v_mul_f32_e32 v115, v159, v159
	v_fmac_f32_e32 v114, v160, v160
	v_fmac_f32_e32 v115, v158, v158
	v_add_f32_e32 v114, v114, v115
	v_mul_f32_e32 v115, v157, v157
	v_mul_f32_e32 v116, v155, v155
	v_fmac_f32_e32 v115, v156, v156
	v_fmac_f32_e32 v116, v154, v154
	v_add_f32_e32 v115, v115, v116
	v_add_f32_e32 v114, v114, v115
	v_add_f32_e32 v114, v198, v114
	ds_bpermute_b32 v115, v187, v114
	s_waitcnt lgkmcnt(0)
	v_add_f32_e32 v114, v114, v115
	ds_bpermute_b32 v115, v188, v114
	s_and_saveexec_b64 s[36:37], s[4:5]
	v_readlane_b32 s64, v253, 52
	v_readlane_b32 s65, v253, 53
	s_cbranch_execz .LBB0_2550
	s_waitcnt lgkmcnt(0)
	v_add_f32_e32 v114, v114, v115
	ds_write_b32 v197, v114
.LBB0_2550:
	s_or_b64 exec, exec, s[36:37]
	s_mov_b32 s1, 0x10000
	v_add_co_u32_e32 v114, vcc, s1, v182
	s_waitcnt vmcnt(3)
	v_lshlrev_b32_e32 v162, 16, v134
	s_waitcnt lgkmcnt(0)
	v_addc_co_u32_e32 v115, vcc, 0, v183, vcc
	global_load_dwordx4 v[118:121], v[114:115], off
	s_nop 0
	global_load_dwordx4 v[114:117], v[114:115], off offset:256
	v_and_b32_e32 v163, 0xffff0000, v134
	v_lshlrev_b32_e32 v134, 16, v135
	v_and_b32_e32 v135, 0xffff0000, v135
	v_lshlrev_b32_e32 v164, 16, v136
	v_and_b32_e32 v165, 0xffff0000, v136
	v_lshlrev_b32_e32 v198, 16, v137
	v_and_b32_e32 v199, 0xffff0000, v137
	v_fma_f32 v134, v112, v180, v134
	v_fma_f32 v135, v113, v181, v135
	v_fma_f32 v136, v110, v178, v162
	v_fma_f32 v137, v111, v179, v163
	v_fma_f32 v164, v106, v174, v164
	v_fma_f32 v165, v107, v175, v165
	v_mul_f32_e32 v106, v137, v137
	v_mul_f32_e32 v107, v135, v135
	v_fma_f32 v162, v108, v176, v198
	v_fma_f32 v163, v109, v177, v199
	v_fmac_f32_e32 v106, v136, v136
	v_fmac_f32_e32 v107, v134, v134
	v_add_f32_e32 v106, v106, v107
	v_mul_f32_e32 v107, v165, v165
	v_mul_f32_e32 v108, v163, v163
	v_fmac_f32_e32 v107, v164, v164
	v_fmac_f32_e32 v108, v162, v162
	v_add_f32_e32 v107, v107, v108
	v_add_f32_e32 v200, v106, v107
	s_waitcnt vmcnt(4)
	v_lshlrev_b32_e32 v106, 16, v130
	v_and_b32_e32 v107, 0xffff0000, v130
	v_lshlrev_b32_e32 v108, 16, v131
	v_and_b32_e32 v109, 0xffff0000, v131
	v_lshlrev_b32_e32 v110, 16, v132
	v_and_b32_e32 v111, 0xffff0000, v132
	v_fma_f32 v108, v104, v172, v108
	v_fma_f32 v109, v105, v173, v109
	v_fma_f32 v112, v102, v170, v106
	v_fma_f32 v113, v103, v171, v107
	v_lshlrev_b32_e32 v130, 16, v133
	v_and_b32_e32 v131, 0xffff0000, v133
	v_fma_f32 v110, v98, v166, v110
	v_fma_f32 v111, v99, v167, v111
	v_mul_f32_e32 v98, v113, v113
	v_mul_f32_e32 v99, v109, v109
	v_fma_f32 v106, v100, v168, v130
	v_fma_f32 v107, v101, v169, v131
	v_fmac_f32_e32 v98, v112, v112
	v_fmac_f32_e32 v99, v108, v108
	v_add_f32_e32 v98, v98, v99
	v_mul_f32_e32 v99, v111, v111
	v_mul_f32_e32 v100, v107, v107
	v_fmac_f32_e32 v99, v110, v110
	v_fmac_f32_e32 v100, v106, v106
	v_add_f32_e32 v99, v99, v100
	v_add_f32_e32 v98, v98, v99
	v_add_f32_e32 v98, v200, v98
	ds_bpermute_b32 v99, v187, v98
	s_mov_b64 s[36:37], 0x8000
	v_lshl_add_u64 v[202:203], v[182:183], 0, s[36:37]
	s_mov_b64 s[36:37], 0x8100
	v_lshl_add_u64 v[204:205], v[182:183], 0, s[36:37]
	s_waitcnt lgkmcnt(0)
	v_add_f32_e32 v98, v98, v99
	ds_bpermute_b32 v99, v188, v98
	v_cvt_pk_bf16_f32 v198, v136, v137
	v_cvt_pk_bf16_f32 v199, v134, v135
	v_cvt_pk_bf16_f32 v200, v164, v165
	v_cvt_pk_bf16_f32 v201, v162, v163
	global_store_dwordx4 v[202:203], v[198:201], off
	v_cvt_pk_bf16_f32 v100, v112, v113
	v_cvt_pk_bf16_f32 v101, v108, v109
	v_cvt_pk_bf16_f32 v102, v110, v111
	v_cvt_pk_bf16_f32 v103, v106, v107
	global_store_dwordx4 v[204:205], v[100:103], off
	s_and_saveexec_b64 s[36:37], s[4:5]
	s_cbranch_execz .LBB0_2552
	s_waitcnt lgkmcnt(0)
	v_add_f32_e32 v98, v98, v99
	ds_write_b32 v197, v98 offset:256
.LBB0_2552:
	s_or_b64 exec, exec, s[36:37]
	v_add_co_u32_e32 v98, vcc, 0x18000, v182
	s_waitcnt vmcnt(3)
	v_lshlrev_b32_e32 v130, 16, v118
	s_waitcnt lgkmcnt(0)
	v_addc_co_u32_e32 v99, vcc, 0, v183, vcc
	global_load_dwordx4 v[102:105], v[98:99], off
	s_nop 0
	global_load_dwordx4 v[98:101], v[98:99], off offset:256
	v_and_b32_e32 v131, 0xffff0000, v118
	v_lshlrev_b32_e32 v118, 16, v119
	v_and_b32_e32 v119, 0xffff0000, v119
	v_fma_f32 v96, v96, v180, v118
	v_fma_f32 v97, v97, v181, v119
	v_fma_f32 v94, v94, v178, v130
	v_fma_f32 v95, v95, v179, v131
	v_lshlrev_b32_e32 v132, 16, v120
	v_and_b32_e32 v133, 0xffff0000, v120
	v_lshlrev_b32_e32 v120, 16, v121
	v_and_b32_e32 v121, 0xffff0000, v121
	v_mul_f32_e32 v118, v95, v95
	v_mul_f32_e32 v119, v97, v97
	v_fma_f32 v92, v92, v176, v120
	v_fma_f32 v93, v93, v177, v121
	v_fma_f32 v90, v90, v174, v132
	v_fma_f32 v91, v91, v175, v133
	v_fmac_f32_e32 v118, v94, v94
	v_fmac_f32_e32 v119, v96, v96
	v_add_f32_e32 v118, v118, v119
	v_mul_f32_e32 v119, v91, v91
	v_mul_f32_e32 v120, v93, v93
	v_fmac_f32_e32 v119, v90, v90
	v_fmac_f32_e32 v120, v92, v92
	v_add_f32_e32 v119, v119, v120
	v_add_f32_e32 v202, v118, v119
	s_waitcnt vmcnt(4)
	v_lshlrev_b32_e32 v118, 16, v114
	v_and_b32_e32 v119, 0xffff0000, v114
	v_lshlrev_b32_e32 v114, 16, v115
	v_and_b32_e32 v115, 0xffff0000, v115
	v_lshlrev_b32_e32 v120, 16, v116
	v_and_b32_e32 v121, 0xffff0000, v116
	v_lshlrev_b32_e32 v132, 16, v117
	v_and_b32_e32 v133, 0xffff0000, v117
	v_fma_f32 v114, v88, v172, v114
	v_fma_f32 v115, v89, v173, v115
	v_fma_f32 v116, v86, v170, v118
	v_fma_f32 v117, v87, v171, v119
	v_fma_f32 v120, v82, v166, v120
	v_fma_f32 v121, v83, v167, v121
	v_mul_f32_e32 v82, v117, v117
	v_mul_f32_e32 v83, v115, v115
	v_fma_f32 v118, v84, v168, v132
	v_fma_f32 v119, v85, v169, v133
	v_fmac_f32_e32 v82, v116, v116
	v_fmac_f32_e32 v83, v114, v114
	v_add_f32_e32 v82, v82, v83
	v_mul_f32_e32 v83, v121, v121
	v_mul_f32_e32 v84, v119, v119
	v_fmac_f32_e32 v83, v120, v120
	v_fmac_f32_e32 v84, v118, v118
	v_add_f32_e32 v83, v83, v84
	v_add_f32_e32 v82, v82, v83
	v_add_f32_e32 v82, v202, v82
	ds_bpermute_b32 v83, v187, v82
	s_mov_b64 s[36:37], 0x10100
	v_lshl_add_u64 v[198:199], v[182:183], 0, s[12:13]
	v_lshl_add_u64 v[200:201], v[182:183], 0, s[36:37]
	v_cvt_pk_bf16_f32 v130, v94, v95
	s_waitcnt lgkmcnt(0)
	v_add_f32_e32 v82, v82, v83
	ds_bpermute_b32 v83, v188, v82
	v_cvt_pk_bf16_f32 v131, v96, v97
	v_cvt_pk_bf16_f32 v132, v90, v91
	v_cvt_pk_bf16_f32 v133, v92, v93
	global_store_dwordx4 v[198:199], v[130:133], off
	v_cvt_pk_bf16_f32 v84, v116, v117
	v_cvt_pk_bf16_f32 v85, v114, v115
	v_cvt_pk_bf16_f32 v86, v120, v121
	v_cvt_pk_bf16_f32 v87, v118, v119
	global_store_dwordx4 v[200:201], v[84:87], off
	s_and_saveexec_b64 s[36:37], s[4:5]
	v_readlane_b32 s66, v253, 58
	v_readlane_b32 s67, v253, 59
	s_cbranch_execz .LBB0_2554
	s_waitcnt lgkmcnt(0)
	v_add_f32_e32 v82, v82, v83
	ds_write_b32 v197, v82 offset:512
.LBB0_2554:
	s_or_b64 exec, exec, s[36:37]
	v_add_co_u32_e32 v82, vcc, 0x40000, v182
	s_waitcnt vmcnt(3)
	v_lshlrev_b32_e32 v130, 16, v102
	s_waitcnt lgkmcnt(0)
	v_addc_co_u32_e32 v83, vcc, 0, v183, vcc
	global_load_dwordx4 v[86:89], v[82:83], off
	s_nop 0
	global_load_dwordx4 v[82:85], v[82:83], off offset:256
	v_and_b32_e32 v131, 0xffff0000, v102
	v_lshlrev_b32_e32 v102, 16, v103
	v_and_b32_e32 v103, 0xffff0000, v103
	v_fma_f32 v80, v80, v180, v102
	v_fma_f32 v81, v81, v181, v103
	v_fma_f32 v78, v78, v178, v130
	v_fma_f32 v79, v79, v179, v131
	v_lshlrev_b32_e32 v132, 16, v104
	v_and_b32_e32 v133, 0xffff0000, v104
	v_lshlrev_b32_e32 v104, 16, v105
	v_and_b32_e32 v105, 0xffff0000, v105
	v_mul_f32_e32 v102, v79, v79
	v_mul_f32_e32 v103, v81, v81
	v_fma_f32 v76, v76, v176, v104
	v_fma_f32 v77, v77, v177, v105
	v_fma_f32 v74, v74, v174, v132
	v_fma_f32 v75, v75, v175, v133
	v_fmac_f32_e32 v102, v78, v78
	v_fmac_f32_e32 v103, v80, v80
	v_add_f32_e32 v102, v102, v103
	v_mul_f32_e32 v103, v75, v75
	v_mul_f32_e32 v104, v77, v77
	v_fmac_f32_e32 v103, v74, v74
	v_fmac_f32_e32 v104, v76, v76
	v_add_f32_e32 v103, v103, v104
	v_add_f32_e32 v202, v102, v103
	s_waitcnt vmcnt(4)
	v_lshlrev_b32_e32 v102, 16, v98
	v_and_b32_e32 v103, 0xffff0000, v98
	v_lshlrev_b32_e32 v98, 16, v99
	v_and_b32_e32 v99, 0xffff0000, v99
	v_lshlrev_b32_e32 v104, 16, v100
	v_and_b32_e32 v105, 0xffff0000, v100
	v_lshlrev_b32_e32 v132, 16, v101
	v_and_b32_e32 v133, 0xffff0000, v101
	v_fma_f32 v98, v72, v172, v98
	v_fma_f32 v99, v73, v173, v99
	v_fma_f32 v100, v70, v170, v102
	v_fma_f32 v101, v71, v171, v103
	v_fma_f32 v104, v66, v166, v104
	v_fma_f32 v105, v67, v167, v105
	v_mul_f32_e32 v66, v101, v101
	v_mul_f32_e32 v67, v99, v99
	v_fma_f32 v102, v68, v168, v132
	v_fma_f32 v103, v69, v169, v133
	v_fmac_f32_e32 v66, v100, v100
	v_fmac_f32_e32 v67, v98, v98
	v_add_f32_e32 v66, v66, v67
	v_mul_f32_e32 v67, v105, v105
	v_mul_f32_e32 v68, v103, v103
	v_fmac_f32_e32 v67, v104, v104
	v_fmac_f32_e32 v68, v102, v102
	v_add_f32_e32 v67, v67, v68
	v_add_f32_e32 v66, v66, v67
	v_add_f32_e32 v66, v202, v66
	ds_bpermute_b32 v67, v187, v66
	s_mov_b64 s[36:37], 0x18000
	v_lshl_add_u64 v[198:199], v[182:183], 0, s[36:37]
	s_mov_b64 s[36:37], 0x18100
	v_lshl_add_u64 v[200:201], v[182:183], 0, s[36:37]
	s_waitcnt lgkmcnt(0)
	v_add_f32_e32 v66, v66, v67
	ds_bpermute_b32 v67, v188, v66
	v_cvt_pk_bf16_f32 v130, v78, v79
	v_cvt_pk_bf16_f32 v131, v80, v81
	v_cvt_pk_bf16_f32 v132, v74, v75
	v_cvt_pk_bf16_f32 v133, v76, v77
	global_store_dwordx4 v[198:199], v[130:133], off
	v_cvt_pk_bf16_f32 v68, v100, v101
	v_cvt_pk_bf16_f32 v69, v98, v99
	v_cvt_pk_bf16_f32 v70, v104, v105
	v_cvt_pk_bf16_f32 v71, v102, v103
	global_store_dwordx4 v[200:201], v[68:71], off
	s_and_saveexec_b64 s[36:37], s[4:5]
	s_cbranch_execz .LBB0_2556
	s_waitcnt lgkmcnt(0)
	v_add_f32_e32 v66, v66, v67
	ds_write_b32 v197, v66 offset:768
.LBB0_2556:
	s_or_b64 exec, exec, s[36:37]
	v_add_co_u32_e32 v66, vcc, 0x48000, v182
	s_waitcnt vmcnt(3)
	v_lshlrev_b32_e32 v130, 16, v86
	s_waitcnt lgkmcnt(0)
	v_addc_co_u32_e32 v67, vcc, 0, v183, vcc
	global_load_dwordx4 v[70:73], v[66:67], off
	s_nop 0
	global_load_dwordx4 v[66:69], v[66:67], off offset:256
	v_and_b32_e32 v131, 0xffff0000, v86
	v_lshlrev_b32_e32 v86, 16, v87
	v_and_b32_e32 v87, 0xffff0000, v87
	v_fma_f32 v64, v64, v180, v86
	v_fma_f32 v65, v65, v181, v87
	v_fma_f32 v62, v62, v178, v130
	v_fma_f32 v63, v63, v179, v131
	v_lshlrev_b32_e32 v132, 16, v88
	v_and_b32_e32 v133, 0xffff0000, v88
	v_lshlrev_b32_e32 v88, 16, v89
	v_and_b32_e32 v89, 0xffff0000, v89
	v_mul_f32_e32 v86, v63, v63
	v_mul_f32_e32 v87, v65, v65
	v_fma_f32 v60, v60, v176, v88
	v_fma_f32 v61, v61, v177, v89
	v_fma_f32 v58, v58, v174, v132
	v_fma_f32 v59, v59, v175, v133
	v_fmac_f32_e32 v86, v62, v62
	v_fmac_f32_e32 v87, v64, v64
	v_add_f32_e32 v86, v86, v87
	v_mul_f32_e32 v87, v59, v59
	v_mul_f32_e32 v88, v61, v61
	v_fmac_f32_e32 v87, v58, v58
	v_fmac_f32_e32 v88, v60, v60
	v_add_f32_e32 v87, v87, v88
	v_add_f32_e32 v202, v86, v87
	s_waitcnt vmcnt(4)
	v_lshlrev_b32_e32 v86, 16, v82
	v_and_b32_e32 v87, 0xffff0000, v82
	v_lshlrev_b32_e32 v82, 16, v83
	v_and_b32_e32 v83, 0xffff0000, v83
	v_lshlrev_b32_e32 v88, 16, v84
	v_and_b32_e32 v89, 0xffff0000, v84
	v_lshlrev_b32_e32 v132, 16, v85
	v_and_b32_e32 v133, 0xffff0000, v85
	v_fma_f32 v82, v56, v172, v82
	v_fma_f32 v83, v57, v173, v83
	v_fma_f32 v84, v54, v170, v86
	v_fma_f32 v85, v55, v171, v87
	v_fma_f32 v88, v50, v166, v88
	v_fma_f32 v89, v51, v167, v89
	v_mul_f32_e32 v50, v85, v85
	v_mul_f32_e32 v51, v83, v83
	v_fma_f32 v86, v52, v168, v132
	v_fma_f32 v87, v53, v169, v133
	v_fmac_f32_e32 v50, v84, v84
	v_fmac_f32_e32 v51, v82, v82
	v_add_f32_e32 v50, v50, v51
	v_mul_f32_e32 v51, v89, v89
	v_mul_f32_e32 v52, v87, v87
	v_fmac_f32_e32 v51, v88, v88
	v_fmac_f32_e32 v52, v86, v86
	v_add_f32_e32 v51, v51, v52
	v_add_f32_e32 v50, v50, v51
	v_add_f32_e32 v50, v202, v50
	ds_bpermute_b32 v51, v187, v50
	s_mov_b64 s[36:37], 0x40000
	v_lshl_add_u64 v[198:199], v[182:183], 0, s[36:37]
	s_mov_b64 s[36:37], 0x40100
	v_lshl_add_u64 v[200:201], v[182:183], 0, s[36:37]
	s_waitcnt lgkmcnt(0)
	v_add_f32_e32 v50, v50, v51
	ds_bpermute_b32 v51, v188, v50
	v_cvt_pk_bf16_f32 v130, v62, v63
	v_cvt_pk_bf16_f32 v131, v64, v65
	v_cvt_pk_bf16_f32 v132, v58, v59
	v_cvt_pk_bf16_f32 v133, v60, v61
	global_store_dwordx4 v[198:199], v[130:133], off
	v_cvt_pk_bf16_f32 v52, v84, v85
	v_cvt_pk_bf16_f32 v53, v82, v83
	v_cvt_pk_bf16_f32 v54, v88, v89
	v_cvt_pk_bf16_f32 v55, v86, v87
	global_store_dwordx4 v[200:201], v[52:55], off
	s_and_saveexec_b64 s[36:37], s[4:5]
	s_cbranch_execz .LBB0_2558
	s_waitcnt lgkmcnt(0)
	v_add_f32_e32 v50, v50, v51
	ds_write_b32 v192, v50
.LBB0_2558:
	s_or_b64 exec, exec, s[36:37]
	v_add_co_u32_e32 v50, vcc, 0x50000, v182
	s_waitcnt vmcnt(3)
	v_lshlrev_b32_e32 v130, 16, v70
	s_waitcnt lgkmcnt(0)
	v_addc_co_u32_e32 v51, vcc, 0, v183, vcc
	global_load_dwordx4 v[54:57], v[50:51], off
	s_nop 0
	global_load_dwordx4 v[50:53], v[50:51], off offset:256
	v_and_b32_e32 v131, 0xffff0000, v70
	v_lshlrev_b32_e32 v70, 16, v71
	v_and_b32_e32 v71, 0xffff0000, v71
	v_fma_f32 v48, v48, v180, v70
	v_fma_f32 v49, v49, v181, v71
	v_fma_f32 v46, v46, v178, v130
	v_fma_f32 v47, v47, v179, v131
	v_lshlrev_b32_e32 v132, 16, v72
	v_and_b32_e32 v133, 0xffff0000, v72
	v_lshlrev_b32_e32 v72, 16, v73
	v_and_b32_e32 v73, 0xffff0000, v73
	v_mul_f32_e32 v70, v47, v47
	v_mul_f32_e32 v71, v49, v49
	v_fma_f32 v44, v44, v176, v72
	v_fma_f32 v45, v45, v177, v73
	v_fma_f32 v42, v42, v174, v132
	v_fma_f32 v43, v43, v175, v133
	v_fmac_f32_e32 v70, v46, v46
	v_fmac_f32_e32 v71, v48, v48
	v_add_f32_e32 v70, v70, v71
	v_mul_f32_e32 v71, v43, v43
	v_mul_f32_e32 v72, v45, v45
	v_fmac_f32_e32 v71, v42, v42
	v_fmac_f32_e32 v72, v44, v44
	v_add_f32_e32 v71, v71, v72
	v_add_f32_e32 v202, v70, v71
	s_waitcnt vmcnt(4)
	v_lshlrev_b32_e32 v70, 16, v66
	v_and_b32_e32 v71, 0xffff0000, v66
	v_lshlrev_b32_e32 v66, 16, v67
	v_and_b32_e32 v67, 0xffff0000, v67
	v_lshlrev_b32_e32 v72, 16, v68
	v_and_b32_e32 v73, 0xffff0000, v68
	v_lshlrev_b32_e32 v132, 16, v69
	v_and_b32_e32 v133, 0xffff0000, v69
	v_fma_f32 v66, v40, v172, v66
	v_fma_f32 v67, v41, v173, v67
	v_fma_f32 v68, v38, v170, v70
	v_fma_f32 v69, v39, v171, v71
	v_fma_f32 v72, v34, v166, v72
	v_fma_f32 v73, v35, v167, v73
	v_mul_f32_e32 v34, v69, v69
	v_mul_f32_e32 v35, v67, v67
	v_fma_f32 v70, v36, v168, v132
	v_fma_f32 v71, v37, v169, v133
	v_fmac_f32_e32 v34, v68, v68
	v_fmac_f32_e32 v35, v66, v66
	v_add_f32_e32 v34, v34, v35
	v_mul_f32_e32 v35, v73, v73
	v_mul_f32_e32 v36, v71, v71
	v_fmac_f32_e32 v35, v72, v72
	v_fmac_f32_e32 v36, v70, v70
	v_add_f32_e32 v35, v35, v36
	v_add_f32_e32 v34, v34, v35
	v_add_f32_e32 v34, v202, v34
	ds_bpermute_b32 v35, v187, v34
	s_mov_b64 s[36:37], 0x48000
	v_lshl_add_u64 v[198:199], v[182:183], 0, s[36:37]
	s_mov_b64 s[36:37], 0x48100
	v_lshl_add_u64 v[200:201], v[182:183], 0, s[36:37]
	s_waitcnt lgkmcnt(0)
	v_add_f32_e32 v34, v34, v35
	ds_bpermute_b32 v35, v188, v34
	v_cvt_pk_bf16_f32 v130, v46, v47
	v_cvt_pk_bf16_f32 v131, v48, v49
	v_cvt_pk_bf16_f32 v132, v42, v43
	v_cvt_pk_bf16_f32 v133, v44, v45
	global_store_dwordx4 v[198:199], v[130:133], off
	v_cvt_pk_bf16_f32 v36, v68, v69
	v_cvt_pk_bf16_f32 v37, v66, v67
	v_cvt_pk_bf16_f32 v38, v72, v73
	v_cvt_pk_bf16_f32 v39, v70, v71
	global_store_dwordx4 v[200:201], v[36:39], off
	s_and_saveexec_b64 s[36:37], s[4:5]
	s_cbranch_execz .LBB0_2560
	s_waitcnt lgkmcnt(0)
	v_add_f32_e32 v34, v34, v35
	ds_write_b32 v193, v34
.LBB0_2560:
	s_or_b64 exec, exec, s[36:37]
	v_add_co_u32_e32 v34, vcc, 0x58000, v182
	s_waitcnt vmcnt(3)
	v_lshlrev_b32_e32 v198, 16, v54
	s_waitcnt lgkmcnt(0)
	v_addc_co_u32_e32 v35, vcc, 0, v183, vcc
	global_load_dwordx4 v[38:41], v[34:35], off
	s_nop 0
	global_load_dwordx4 v[34:37], v[34:35], off offset:256
	v_and_b32_e32 v199, 0xffff0000, v54
	v_lshlrev_b32_e32 v54, 16, v55
	v_and_b32_e32 v55, 0xffff0000, v55
	v_lshlrev_b32_e32 v200, 16, v56
	v_and_b32_e32 v201, 0xffff0000, v56
	v_lshlrev_b32_e32 v56, 16, v57
	v_and_b32_e32 v57, 0xffff0000, v57
	v_fma_f32 v32, v32, v180, v54
	v_fma_f32 v33, v33, v181, v55
	v_fma_f32 v30, v30, v178, v198
	v_fma_f32 v31, v31, v179, v199
	v_fma_f32 v28, v28, v176, v56
	v_fma_f32 v29, v29, v177, v57
	v_mul_f32_e32 v56, v31, v31
	v_mul_f32_e32 v57, v33, v33
	v_fma_f32 v26, v26, v174, v200
	v_fma_f32 v27, v27, v175, v201
	v_fmac_f32_e32 v56, v30, v30
	v_fmac_f32_e32 v57, v32, v32
	v_add_f32_e32 v56, v56, v57
	v_mul_f32_e32 v57, v27, v27
	v_mul_f32_e32 v198, v29, v29
	v_fmac_f32_e32 v57, v26, v26
	v_fmac_f32_e32 v198, v28, v28
	v_add_f32_e32 v57, v57, v198
	v_add_f32_e32 v200, v56, v57
	s_waitcnt vmcnt(4)
	v_lshlrev_b32_e32 v56, 16, v50
	v_and_b32_e32 v57, 0xffff0000, v50
	v_lshlrev_b32_e32 v50, 16, v51
	v_and_b32_e32 v51, 0xffff0000, v51
	v_fma_f32 v24, v24, v172, v50
	v_fma_f32 v25, v25, v173, v51
	v_fma_f32 v22, v22, v170, v56
	v_fma_f32 v23, v23, v171, v57
	v_lshlrev_b32_e32 v198, 16, v52
	v_and_b32_e32 v199, 0xffff0000, v52
	v_lshlrev_b32_e32 v52, 16, v53
	v_and_b32_e32 v53, 0xffff0000, v53
	v_mul_f32_e32 v50, v23, v23
	v_mul_f32_e32 v51, v25, v25
	v_fma_f32 v20, v20, v168, v52
	v_fma_f32 v21, v21, v169, v53
	v_fma_f32 v18, v18, v166, v198
	v_fma_f32 v19, v19, v167, v199
	v_fmac_f32_e32 v50, v22, v22
	v_fmac_f32_e32 v51, v24, v24
	v_add_f32_e32 v50, v50, v51
	v_mul_f32_e32 v51, v19, v19
	v_mul_f32_e32 v52, v21, v21
	v_fmac_f32_e32 v51, v18, v18
	v_fmac_f32_e32 v52, v20, v20
	v_add_f32_e32 v51, v51, v52
	v_add_f32_e32 v50, v50, v51
	v_add_f32_e32 v50, v200, v50
	ds_bpermute_b32 v51, v187, v50
	s_mov_b64 s[36:37], 0x50000
	v_lshl_add_u64 v[130:131], v[182:183], 0, s[36:37]
	s_mov_b64 s[36:37], 0x50100
	v_lshl_add_u64 v[132:133], v[182:183], 0, s[36:37]
	s_waitcnt lgkmcnt(0)
	v_add_f32_e32 v50, v50, v51
	ds_bpermute_b32 v51, v188, v50
	v_cvt_pk_bf16_f32 v54, v30, v31
	v_cvt_pk_bf16_f32 v55, v32, v33
	v_cvt_pk_bf16_f32 v56, v26, v27
	v_cvt_pk_bf16_f32 v57, v28, v29
	global_store_dwordx4 v[130:131], v[54:57], off
	v_cvt_pk_bf16_f32 v52, v22, v23
	v_cvt_pk_bf16_f32 v53, v24, v25
	s_nop 1
	v_cvt_pk_bf16_f32 v54, v18, v19
	v_cvt_pk_bf16_f32 v55, v20, v21
	global_store_dwordx4 v[132:133], v[52:55], off
	s_and_saveexec_b64 s[36:37], s[4:5]
	s_cbranch_execz .LBB0_2562
	s_waitcnt lgkmcnt(0)
	v_add_f32_e32 v50, v50, v51
	ds_write_b32 v194, v50
.LBB0_2562:
	s_or_b64 exec, exec, s[36:37]
	s_waitcnt vmcnt(3)
	v_lshlrev_b32_e32 v50, 16, v38
	s_waitcnt lgkmcnt(0)
	v_and_b32_e32 v51, 0xffff0000, v38
	v_lshlrev_b32_e32 v38, 16, v39
	v_and_b32_e32 v39, 0xffff0000, v39
	v_lshlrev_b32_e32 v52, 16, v40
	v_and_b32_e32 v53, 0xffff0000, v40
	v_lshlrev_b32_e32 v54, 16, v41
	v_and_b32_e32 v55, 0xffff0000, v41
	v_fma_f32 v38, v16, v180, v38
	v_fma_f32 v39, v17, v181, v39
	v_fma_f32 v40, v14, v178, v50
	v_fma_f32 v41, v15, v179, v51
	v_fma_f32 v50, v12, v176, v54
	v_fma_f32 v51, v13, v177, v55
	v_mul_f32_e32 v12, v41, v41
	v_mul_f32_e32 v13, v39, v39
	v_fma_f32 v52, v10, v174, v52
	v_fma_f32 v53, v11, v175, v53
	v_fmac_f32_e32 v12, v40, v40
	v_fmac_f32_e32 v13, v38, v38
	v_add_f32_e32 v12, v12, v13
	v_mul_f32_e32 v13, v53, v53
	v_mul_f32_e32 v14, v51, v51
	v_fmac_f32_e32 v13, v52, v52
	v_fmac_f32_e32 v14, v50, v50
	v_add_f32_e32 v13, v13, v14
	v_add_f32_e32 v174, v12, v13
	s_waitcnt vmcnt(2)
	v_lshlrev_b32_e32 v12, 16, v34
	v_and_b32_e32 v13, 0xffff0000, v34
	v_lshlrev_b32_e32 v14, 16, v35
	v_and_b32_e32 v15, 0xffff0000, v35
	v_lshlrev_b32_e32 v16, 16, v36
	v_and_b32_e32 v17, 0xffff0000, v36
	v_lshlrev_b32_e32 v54, 16, v37
	v_and_b32_e32 v55, 0xffff0000, v37
	v_fma_f32 v34, v8, v172, v14
	v_fma_f32 v35, v9, v173, v15
	v_fma_f32 v36, v6, v170, v12
	v_fma_f32 v37, v7, v171, v13
	v_fma_f32 v56, v2, v166, v16
	v_fma_f32 v57, v3, v167, v17
	v_mul_f32_e32 v2, v37, v37
	v_mul_f32_e32 v3, v35, v35
	v_fma_f32 v54, v4, v168, v54
	v_fma_f32 v55, v5, v169, v55
	v_fmac_f32_e32 v2, v36, v36
	v_fmac_f32_e32 v3, v34, v34
	v_add_f32_e32 v2, v2, v3
	v_mul_f32_e32 v3, v57, v57
	v_mul_f32_e32 v4, v55, v55
	v_fmac_f32_e32 v3, v56, v56
	v_fmac_f32_e32 v4, v54, v54
	v_add_f32_e32 v3, v3, v4
	v_add_f32_e32 v2, v2, v3
	v_add_f32_e32 v2, v174, v2
	ds_bpermute_b32 v3, v187, v2
	s_mov_b64 s[36:37], 0x58000
	v_lshl_add_u64 v[130:131], v[182:183], 0, s[36:37]
	s_mov_b64 s[36:37], 0x58100
	s_waitcnt lgkmcnt(0)
	v_add_f32_e32 v2, v2, v3
	ds_bpermute_b32 v3, v188, v2
	v_lshl_add_u64 v[132:133], v[182:183], 0, s[36:37]
	v_cvt_pk_bf16_f32 v10, v40, v41
	v_cvt_pk_bf16_f32 v11, v38, v39
	v_cvt_pk_bf16_f32 v12, v52, v53
	v_cvt_pk_bf16_f32 v13, v50, v51
	global_store_dwordx4 v[130:131], v[10:13], off
	v_cvt_pk_bf16_f32 v4, v36, v37
	v_cvt_pk_bf16_f32 v5, v34, v35
	v_cvt_pk_bf16_f32 v6, v56, v57
	v_cvt_pk_bf16_f32 v7, v54, v55
	global_store_dwordx4 v[132:133], v[4:7], off
	s_and_saveexec_b64 s[36:37], s[4:5]
	s_cbranch_execz .LBB0_2564
	s_waitcnt lgkmcnt(0)
	v_add_f32_e32 v2, v2, v3
	ds_write_b32 v195, v2
.LBB0_2564:
	s_or_b64 exec, exec, s[36:37]
	s_waitcnt lgkmcnt(0)
	s_barrier
	s_ashr_i32 s35, s34, 31
	s_waitcnt lgkmcnt(0)
	v_lshl_add_u64 v[2:3], v[144:145], 0, s[34:35]
	v_lshl_add_u64 v[2:3], v[2:3], 4, s[22:23]
	s_and_saveexec_b64 s[34:35], s[6:7]
	s_cbranch_execz .LBB0_2566
	ds_read_b128 v[4:7], v196
	s_ashr_i32 s1, s0, 31
	v_lshl_add_u64 v[8:9], s[0:1], 2, v[2:3]
	s_waitcnt lgkmcnt(0)
	v_mov_b32_e32 v10, v5
	v_mov_b32_e32 v11, v6
	v_mov_b32_e32 v5, v7
	v_add_f32_e32 v4, v10, v4
	v_add_f32_e32 v5, v11, v5
	s_nop 0
	v_pk_add_f32 v[4:5], v[4:5], v[4:5] op_sel:[0,1] op_sel_hi:[1,0]
	global_store_dword v[8:9], v4, off sc1

.LBB0_2581:
	s_or_b64 exec, exec, s[0:1]
	s_add_u32 s0, s58, s30
	s_addc_u32 s1, s59, s31
	v_lshlrev_b64 v[2:3], 2, v[152:153]
	v_lshl_add_u64 v[198:199], s[0:1], 0, v[2:3]
	s_mov_b64 s[0:1], 0x1000
	s_waitcnt vmcnt(0) lgkmcnt(0)
	s_barrier
	v_lshl_add_u64 v[172:173], s[14:15], 0, v[2:3]
	v_lshl_add_u64 v[2:3], v[198:199], 0, s[0:1]
	s_movk_i32 s0, 0x1000
	global_load_dwordx4 v[10:13], v[172:173], off offset:16
	global_load_dwordx4 v[14:17], v[172:173], off
	v_add_co_u32_e32 v174, vcc, s0, v198
	s_mov_b64 s[0:1], 0x1200
	s_nop 0
	v_addc_co_u32_e32 v175, vcc, 0, v199, vcc
	global_load_dwordx4 v[130:133], v[174:175], off
	global_load_dwordx4 v[168:171], v[2:3], off offset:16
	s_nop 0
	global_load_dwordx4 v[2:5], v[198:199], off offset:16
	global_load_dwordx4 v[6:9], v[198:199], off
	v_lshl_add_u64 v[150:151], v[150:151], 1, s[24:25]
	s_waitcnt vmcnt(3)
	v_add_f32_e32 v132, 1.0, v132
	v_add_f32_e32 v133, 1.0, v133
	v_add_f32_e32 v130, 1.0, v130
	v_add_f32_e32 v131, 1.0, v131
	v_mul_f32_e32 v152, v16, v132
	v_mul_f32_e32 v153, v17, v133
	s_waitcnt vmcnt(2)
	v_add_f32_e32 v16, 1.0, v168
	v_add_f32_e32 v17, 1.0, v169
	v_mul_f32_e32 v166, v14, v130
	v_mul_f32_e32 v167, v15, v131
	v_add_f32_e32 v14, 1.0, v170
	v_add_f32_e32 v15, 1.0, v171
	v_mul_f32_e32 v132, v10, v16
	v_mul_f32_e32 v133, v11, v17
	v_lshl_add_u64 v[10:11], v[198:199], 0, s[0:1]
	v_mul_f32_e32 v130, v12, v14
	v_mul_f32_e32 v131, v13, v15
	global_load_dwordx4 v[176:179], v[172:173], off offset:528
	global_load_dwordx4 v[168:171], v[172:173], off offset:512
	s_nop 0
	global_load_dwordx4 v[172:175], v[174:175], off offset:512
	s_nop 0
	global_load_dwordx4 v[180:183], v[10:11], off offset:16
	s_nop 0
	global_load_dwordx4 v[10:13], v[198:199], off offset:528
	global_load_dwordx4 v[14:17], v[198:199], off offset:512
	s_mov_b32 s0, 0x10000
	s_waitcnt vmcnt(3)
	v_add_f32_e32 v174, 1.0, v174
	v_add_f32_e32 v175, 1.0, v175
	v_add_f32_e32 v198, 1.0, v172
	v_add_f32_e32 v199, 1.0, v173
	v_mul_f32_e32 v172, v170, v174
	v_mul_f32_e32 v173, v171, v175
	s_waitcnt vmcnt(2)
	v_add_f32_e32 v170, 1.0, v180
	v_add_f32_e32 v171, 1.0, v181
	v_mul_f32_e32 v174, v168, v198
	v_mul_f32_e32 v175, v169, v199
	v_mul_f32_e32 v170, v176, v170
	v_mul_f32_e32 v171, v177, v171
	ds_read_b32 v176, v190
	v_add_f32_e32 v168, 1.0, v182
	v_add_f32_e32 v169, 1.0, v183
	s_waitcnt lgkmcnt(0)
	v_mul_f32_e32 v124, v124, v176
	v_mul_f32_e32 v125, v125, v176
	v_mul_f32_e32 v122, v122, v176
	v_mul_f32_e32 v123, v123, v176
	v_mul_f32_e32 v168, v178, v168
	v_mul_f32_e32 v169, v179, v169
	v_mul_f32_e32 v128, v128, v176
	v_mul_f32_e32 v129, v129, v176
	v_mul_f32_e32 v126, v126, v176
	v_mul_f32_e32 v127, v127, v176
	v_fma_f32 v178, v130, v124, v4
	v_fma_f32 v179, v131, v125, v5
	v_fma_f32 v124, v132, v122, v2
	v_fma_f32 v125, v133, v123, v3
	v_fma_f32 v128, v152, v128, v8
	v_fma_f32 v129, v153, v129, v9
	v_fma_f32 v126, v166, v126, v6
	v_fma_f32 v127, v167, v127, v7
	s_nop 0
	v_cvt_pk_bf16_f32 v122, v126, v127
	v_cvt_pk_bf16_f32 v123, v128, v129
	v_cvt_pk_bf16_f32 v124, v124, v125
	v_cvt_pk_bf16_f32 v125, v178, v179
	global_store_dwordx4 v[150:151], v[122:125], off
	v_mul_f32_e32 v128, v156, v176
	v_mul_f32_e32 v129, v157, v176
	s_nop 0
	v_mul_f32_e32 v122, v158, v176
	v_mul_f32_e32 v123, v159, v176
	v_mul_f32_e32 v124, v160, v176
	v_mul_f32_e32 v125, v161, v176
	s_waitcnt vmcnt(1)
	v_fma_f32 v126, v172, v122, v16
	v_fma_f32 v127, v173, v123, v17
	v_fma_f32 v122, v174, v124, v14
	v_fma_f32 v123, v175, v125, v15
	v_mul_f32_e32 v124, v154, v176
	v_mul_f32_e32 v125, v155, v176
	v_cvt_pk_bf16_f32 v122, v122, v123
	v_cvt_pk_bf16_f32 v123, v126, v127
	s_nop 0
	v_fma_f32 v154, v168, v124, v12
	v_fma_f32 v155, v169, v125, v13
	v_fma_f32 v124, v170, v128, v10
	v_fma_f32 v125, v171, v129, v11
	s_nop 0
	v_cvt_pk_bf16_f32 v124, v124, v125
	v_cvt_pk_bf16_f32 v125, v154, v155
	global_store_dwordx4 v[150:151], v[122:125], off offset:256
	ds_read_b32 v126, v190 offset:64
	s_waitcnt lgkmcnt(0)
	v_mul_f32_e32 v108, v108, v126
	v_mul_f32_e32 v109, v109, v126
	v_mul_f32_e32 v122, v134, v126
	v_mul_f32_e32 v123, v135, v126
	v_mul_f32_e32 v124, v136, v126
	v_mul_f32_e32 v125, v137, v126
	v_fma_f32 v128, v152, v122, v8
	v_fma_f32 v129, v153, v123, v9
	v_fma_f32 v122, v166, v124, v6
	v_fma_f32 v123, v167, v125, v7
	v_mul_f32_e32 v124, v162, v126
	v_mul_f32_e32 v125, v163, v126
	v_mul_f32_e32 v134, v164, v126
	v_mul_f32_e32 v135, v165, v126
	v_cvt_pk_bf16_f32 v122, v122, v123
	v_cvt_pk_bf16_f32 v123, v128, v129
	v_add_co_u32_e32 v128, vcc, s75, v150
	v_fma_f32 v136, v130, v124, v4
	v_fma_f32 v137, v131, v125, v5
	v_fma_f32 v124, v132, v134, v2
	v_fma_f32 v125, v133, v135, v3
	v_addc_co_u32_e32 v129, vcc, 0, v151, vcc
	v_mul_f32_e32 v112, v112, v126
	v_mul_f32_e32 v113, v113, v126
	v_fma_f32 v108, v172, v108, v16
	v_fma_f32 v109, v173, v109, v17
	v_mul_f32_e32 v106, v106, v126
	v_mul_f32_e32 v107, v107, v126
	v_mul_f32_e32 v110, v110, v126
	v_mul_f32_e32 v111, v111, v126
	v_cvt_pk_bf16_f32 v124, v124, v125
	v_cvt_pk_bf16_f32 v125, v136, v137
	global_store_dwordx4 v[128:129], v[122:125], off
	v_fma_f32 v112, v174, v112, v14
	v_fma_f32 v113, v175, v113, v15
	v_fma_f32 v110, v170, v110, v10
	v_fma_f32 v111, v171, v111, v11
	v_fma_f32 v122, v168, v106, v12
	v_fma_f32 v123, v169, v107, v13
	v_cvt_pk_bf16_f32 v106, v112, v113
	v_cvt_pk_bf16_f32 v107, v108, v109
	v_cvt_pk_bf16_f32 v108, v110, v111
	s_nop 0
	v_cvt_pk_bf16_f32 v109, v122, v123
	global_store_dwordx4 v[128:129], v[106:109], off offset:256
	ds_read_b32 v106, v190 offset:128
	s_waitcnt lgkmcnt(0)
	v_mul_f32_e32 v94, v94, v106
	v_mul_f32_e32 v95, v95, v106
	s_nop 0
	v_fma_f32 v94, v166, v94, v6
	v_fma_f32 v95, v167, v95, v7
	v_mul_f32_e32 v92, v92, v106
	v_mul_f32_e32 v93, v93, v106
	v_mul_f32_e32 v90, v90, v106
	v_mul_f32_e32 v91, v91, v106
	v_mul_f32_e32 v96, v96, v106
	v_mul_f32_e32 v97, v97, v106
	v_fma_f32 v108, v130, v92, v4
	v_fma_f32 v109, v131, v93, v5
	v_fma_f32 v92, v132, v90, v2
	v_fma_f32 v93, v133, v91, v3
	v_cvt_pk_bf16_f32 v90, v94, v95
	v_add_co_u32_e32 v94, vcc, s0, v150
	v_fma_f32 v96, v152, v96, v8
	v_fma_f32 v97, v153, v97, v9
	s_nop 0
	v_addc_co_u32_e32 v95, vcc, 0, v151, vcc
	v_cvt_pk_bf16_f32 v91, v96, v97
	v_cvt_pk_bf16_f32 v92, v92, v93
	v_cvt_pk_bf16_f32 v93, v108, v109
	global_store_dwordx4 v[94:95], v[90:93], off
	s_mov_b32 s0, 0x18000
	s_nop 0
	v_mul_f32_e32 v90, v114, v106
	v_mul_f32_e32 v91, v115, v106
	v_mul_f32_e32 v92, v116, v106
	v_mul_f32_e32 v93, v117, v106
	v_fma_f32 v96, v172, v90, v16
	v_fma_f32 v97, v173, v91, v17
	v_fma_f32 v90, v174, v92, v14
	v_fma_f32 v91, v175, v93, v15
	v_mul_f32_e32 v92, v118, v106
	v_mul_f32_e32 v93, v119, v106
	v_mul_f32_e32 v107, v121, v106
	v_mul_f32_e32 v106, v120, v106
	v_fma_f32 v108, v168, v92, v12
	v_fma_f32 v109, v169, v93, v13
	v_fma_f32 v92, v170, v106, v10
	v_fma_f32 v93, v171, v107, v11
	v_cvt_pk_bf16_f32 v90, v90, v91
	v_cvt_pk_bf16_f32 v91, v96, v97
	s_nop 0
	v_cvt_pk_bf16_f32 v92, v92, v93
	v_cvt_pk_bf16_f32 v93, v108, v109
	global_store_dwordx4 v[94:95], v[90:93], off offset:256
	ds_read_b32 v90, v190 offset:192
	s_waitcnt lgkmcnt(0)
	v_mul_f32_e32 v78, v78, v90
	v_mul_f32_e32 v79, v79, v90
	s_nop 0
	v_fma_f32 v78, v166, v78, v6
	v_fma_f32 v79, v167, v79, v7
	v_mul_f32_e32 v76, v76, v90
	v_mul_f32_e32 v77, v77, v90
	v_mul_f32_e32 v74, v74, v90
	v_mul_f32_e32 v75, v75, v90
	v_mul_f32_e32 v80, v80, v90
	v_mul_f32_e32 v81, v81, v90
	v_fma_f32 v92, v130, v76, v4
	v_fma_f32 v93, v131, v77, v5
	v_fma_f32 v76, v132, v74, v2
	v_fma_f32 v77, v133, v75, v3
	v_cvt_pk_bf16_f32 v74, v78, v79
	v_add_co_u32_e32 v78, vcc, s0, v150
	v_fma_f32 v80, v152, v80, v8
	v_fma_f32 v81, v153, v81, v9
	s_nop 0
	v_addc_co_u32_e32 v79, vcc, 0, v151, vcc
	v_cvt_pk_bf16_f32 v75, v80, v81
	v_cvt_pk_bf16_f32 v76, v76, v77
	v_cvt_pk_bf16_f32 v77, v92, v93
	global_store_dwordx4 v[78:79], v[74:77], off
	s_mov_b32 s0, 0x40000
	s_nop 0
	v_mul_f32_e32 v74, v98, v90
	v_mul_f32_e32 v75, v99, v90
	v_mul_f32_e32 v76, v100, v90
	v_mul_f32_e32 v77, v101, v90
	v_fma_f32 v80, v172, v74, v16
	v_fma_f32 v81, v173, v75, v17
	v_fma_f32 v74, v174, v76, v14
	v_fma_f32 v75, v175, v77, v15
	v_mul_f32_e32 v76, v102, v90
	v_mul_f32_e32 v77, v103, v90
	v_mul_f32_e32 v91, v105, v90
	v_mul_f32_e32 v90, v104, v90
	v_fma_f32 v92, v168, v76, v12
	v_fma_f32 v93, v169, v77, v13
	v_fma_f32 v76, v170, v90, v10
	v_fma_f32 v77, v171, v91, v11
	v_cvt_pk_bf16_f32 v74, v74, v75
	v_cvt_pk_bf16_f32 v75, v80, v81
	s_nop 0
	v_cvt_pk_bf16_f32 v76, v76, v77
	v_cvt_pk_bf16_f32 v77, v92, v93
	global_store_dwordx4 v[78:79], v[74:77], off offset:256
	ds_read_b32 v74, v190 offset:512
	s_waitcnt lgkmcnt(0)
	v_mul_f32_e32 v62, v62, v74
	v_mul_f32_e32 v63, v63, v74
	s_nop 0
	v_fma_f32 v62, v166, v62, v6
	v_fma_f32 v63, v167, v63, v7
	v_mul_f32_e32 v60, v60, v74
	v_mul_f32_e32 v61, v61, v74
	v_mul_f32_e32 v58, v58, v74
	v_mul_f32_e32 v59, v59, v74
	v_mul_f32_e32 v64, v64, v74
	v_mul_f32_e32 v65, v65, v74
	v_fma_f32 v76, v130, v60, v4
	v_fma_f32 v77, v131, v61, v5
	v_fma_f32 v60, v132, v58, v2
	v_fma_f32 v61, v133, v59, v3
	v_cvt_pk_bf16_f32 v58, v62, v63
	v_add_co_u32_e32 v62, vcc, s0, v150
	v_fma_f32 v64, v152, v64, v8
	v_fma_f32 v65, v153, v65, v9
	s_nop 0
	v_addc_co_u32_e32 v63, vcc, 0, v151, vcc
	v_cvt_pk_bf16_f32 v59, v64, v65
	v_cvt_pk_bf16_f32 v60, v60, v61
	v_cvt_pk_bf16_f32 v61, v76, v77
	global_store_dwordx4 v[62:63], v[58:61], off
	s_mov_b32 s0, 0x48000
	s_nop 0
	v_mul_f32_e32 v58, v82, v74
	v_mul_f32_e32 v59, v83, v74
	v_mul_f32_e32 v60, v84, v74
	v_mul_f32_e32 v61, v85, v74
	v_fma_f32 v64, v172, v58, v16
	v_fma_f32 v65, v173, v59, v17
	v_fma_f32 v58, v174, v60, v14
	v_fma_f32 v59, v175, v61, v15
	v_mul_f32_e32 v60, v86, v74
	v_mul_f32_e32 v61, v87, v74
	v_mul_f32_e32 v75, v89, v74
	v_mul_f32_e32 v74, v88, v74
	v_fma_f32 v76, v168, v60, v12
	v_fma_f32 v77, v169, v61, v13
	v_fma_f32 v60, v170, v74, v10
	v_fma_f32 v61, v171, v75, v11
	v_cvt_pk_bf16_f32 v58, v58, v59
	v_cvt_pk_bf16_f32 v59, v64, v65
	s_nop 0
	v_cvt_pk_bf16_f32 v60, v60, v61
	v_cvt_pk_bf16_f32 v61, v76, v77
	global_store_dwordx4 v[62:63], v[58:61], off offset:256
	ds_read_b32 v58, v190 offset:576
	s_waitcnt lgkmcnt(0)
	v_mul_f32_e32 v46, v46, v58
	v_mul_f32_e32 v47, v47, v58
	s_nop 0
	v_fma_f32 v46, v166, v46, v6
	v_fma_f32 v47, v167, v47, v7
	v_mul_f32_e32 v44, v44, v58
	v_mul_f32_e32 v45, v45, v58
	v_mul_f32_e32 v42, v42, v58
	v_mul_f32_e32 v43, v43, v58
	v_mul_f32_e32 v48, v48, v58
	v_mul_f32_e32 v49, v49, v58
	v_fma_f32 v60, v130, v44, v4
	v_fma_f32 v61, v131, v45, v5
	v_fma_f32 v44, v132, v42, v2
	v_fma_f32 v45, v133, v43, v3
	v_cvt_pk_bf16_f32 v42, v46, v47
	v_add_co_u32_e32 v46, vcc, s0, v150
	v_fma_f32 v48, v152, v48, v8
	v_fma_f32 v49, v153, v49, v9
	s_nop 0
	v_addc_co_u32_e32 v47, vcc, 0, v151, vcc
	v_cvt_pk_bf16_f32 v43, v48, v49
	v_cvt_pk_bf16_f32 v44, v44, v45
	v_cvt_pk_bf16_f32 v45, v60, v61
	global_store_dwordx4 v[46:47], v[42:45], off
	s_mov_b32 s0, 0x50000
	s_nop 0
	v_mul_f32_e32 v42, v66, v58
	v_mul_f32_e32 v43, v67, v58
	v_mul_f32_e32 v44, v68, v58
	v_mul_f32_e32 v45, v69, v58
	v_fma_f32 v48, v172, v42, v16
	v_fma_f32 v49, v173, v43, v17
	v_fma_f32 v42, v174, v44, v14
	v_fma_f32 v43, v175, v45, v15
	v_mul_f32_e32 v44, v70, v58
	v_mul_f32_e32 v45, v71, v58
	v_mul_f32_e32 v59, v73, v58
	v_mul_f32_e32 v58, v72, v58
	v_fma_f32 v60, v168, v44, v12
	v_fma_f32 v61, v169, v45, v13
	v_fma_f32 v44, v170, v58, v10
	v_fma_f32 v45, v171, v59, v11
	v_cvt_pk_bf16_f32 v42, v42, v43
	v_cvt_pk_bf16_f32 v43, v48, v49
	s_nop 0
	v_cvt_pk_bf16_f32 v44, v44, v45
	v_cvt_pk_bf16_f32 v45, v60, v61
	global_store_dwordx4 v[46:47], v[42:45], off offset:256
	ds_read_b32 v42, v190 offset:640
	s_waitcnt lgkmcnt(0)
	v_mul_f32_e32 v30, v30, v42
	v_mul_f32_e32 v31, v31, v42
	s_nop 0
	v_fma_f32 v30, v166, v30, v6
	v_fma_f32 v31, v167, v31, v7
	v_mul_f32_e32 v28, v28, v42
	v_mul_f32_e32 v29, v29, v42
	v_mul_f32_e32 v26, v26, v42
	v_mul_f32_e32 v27, v27, v42
	v_mul_f32_e32 v32, v32, v42
	v_mul_f32_e32 v33, v33, v42
	v_fma_f32 v44, v130, v28, v4
	v_fma_f32 v45, v131, v29, v5
	v_fma_f32 v28, v132, v26, v2
	v_fma_f32 v29, v133, v27, v3
	v_cvt_pk_bf16_f32 v26, v30, v31
	v_add_co_u32_e32 v30, vcc, s0, v150
	v_fma_f32 v32, v152, v32, v8
	v_fma_f32 v33, v153, v33, v9
	s_nop 0
	v_addc_co_u32_e32 v31, vcc, 0, v151, vcc
	v_cvt_pk_bf16_f32 v27, v32, v33
	v_mul_f32_e32 v20, v20, v42
	v_mul_f32_e32 v21, v21, v42
	v_mul_f32_e32 v18, v18, v42
	v_mul_f32_e32 v19, v19, v42
	v_cvt_pk_bf16_f32 v28, v28, v29
	v_cvt_pk_bf16_f32 v29, v44, v45
	global_store_dwordx4 v[30:31], v[26:29], off
	v_mul_f32_e32 v24, v24, v42
	v_mul_f32_e32 v25, v25, v42
	v_mul_f32_e32 v22, v22, v42
	v_mul_f32_e32 v23, v23, v42
	v_fma_f32 v26, v168, v20, v12
	v_fma_f32 v27, v169, v21, v13
	v_fma_f32 v20, v170, v18, v10
	v_fma_f32 v21, v171, v19, v11
	v_fma_f32 v24, v172, v24, v16
	v_fma_f32 v25, v173, v25, v17
	v_fma_f32 v22, v174, v22, v14
	v_fma_f32 v23, v175, v23, v15
	s_mov_b32 s0, 0x58000
	v_cvt_pk_bf16_f32 v18, v22, v23
	v_cvt_pk_bf16_f32 v19, v24, v25
	v_cvt_pk_bf16_f32 v20, v20, v21
	v_cvt_pk_bf16_f32 v21, v26, v27
	global_store_dwordx4 v[30:31], v[18:21], off offset:256
	ds_read_b32 v18, v190 offset:704
	s_waitcnt lgkmcnt(0)
	v_mul_f32_e32 v22, v40, v18
	v_mul_f32_e32 v23, v41, v18
	v_mul_f32_e32 v20, v38, v18
	v_mul_f32_e32 v21, v39, v18
	v_fma_f32 v6, v166, v22, v6
	v_fma_f32 v7, v167, v23, v7
	v_fma_f32 v8, v152, v20, v8
	v_fma_f32 v9, v153, v21, v9
	v_mul_f32_e32 v20, v50, v18
	v_mul_f32_e32 v21, v51, v18
	v_mul_f32_e32 v22, v52, v18
	v_mul_f32_e32 v23, v53, v18
	v_fma_f32 v20, v130, v20, v4
	v_fma_f32 v21, v131, v21, v5
	v_fma_f32 v4, v132, v22, v2
	v_fma_f32 v5, v133, v23, v3
	v_cvt_pk_bf16_f32 v2, v6, v7
	v_add_co_u32_e32 v6, vcc, s0, v150
	v_cvt_pk_bf16_f32 v3, v8, v9
	v_cvt_pk_bf16_f32 v4, v4, v5
	v_cvt_pk_bf16_f32 v5, v20, v21
	s_mov_b64 s[0:1], -1
	s_nop 0
	v_addc_co_u32_e32 v7, vcc, 0, v151, vcc
	global_store_dwordx4 v[6:7], v[2:5], off
	s_and_b64 vcc, exec, s[10:11]
	s_nop 0
	v_mul_f32_e32 v2, v34, v18
	v_mul_f32_e32 v3, v35, v18
	v_mul_f32_e32 v4, v36, v18
	v_mul_f32_e32 v5, v37, v18
	v_fma_f32 v8, v172, v2, v16
	v_fma_f32 v9, v173, v3, v17
	v_fma_f32 v2, v174, v4, v14
	v_fma_f32 v3, v175, v5, v15
	v_mul_f32_e32 v4, v54, v18
	v_mul_f32_e32 v5, v55, v18
	v_mul_f32_e32 v14, v56, v18
	v_mul_f32_e32 v15, v57, v18
	v_fma_f32 v12, v168, v4, v12
	v_fma_f32 v13, v169, v5, v13
	v_fma_f32 v4, v170, v14, v10
	v_fma_f32 v5, v171, v15, v11
	v_cvt_pk_bf16_f32 v2, v2, v3
	v_cvt_pk_bf16_f32 v3, v8, v9
	s_nop 0
	v_cvt_pk_bf16_f32 v4, v4, v5
	v_cvt_pk_bf16_f32 v5, v12, v13
	global_store_dwordx4 v[6:7], v[2:5], off offset:256
	s_cbranch_vccnz .LBB0_2533
	s_andn2_b64 vcc, exec, s[2:3]
	s_cbranch_vccnz .LBB0_2532
	s_barrier
	s_branch .LBB0_2532

.LBB0_2611:
	s_ashr_i32 s14, s36, 5
	s_mul_hi_i32 s15, s14, 0x9000
	s_mul_i32 s14, s14, 0x9000
	s_add_u32 s18, s27, s14
	s_addc_u32 s19, s28, s15
	s_lshl_b32 s14, s37, 8
	s_ashr_i32 s15, s14, 31
	s_lshl_b64 s[16:17], s[14:15], 2
	s_add_u32 s16, s18, s16
	s_addc_u32 s17, s19, s17
	s_lshl_b32 s18, s29, 2
	s_add_u32 s16, s16, s18
	s_addc_u32 s17, s17, 0
	v_lshlrev_b32_e32 v0, 2, v142
	global_load_dwordx4 v[130:133], v0, s[16:17] offset:16
	global_load_dwordx4 v[148:151], v0, s[16:17]
	s_mov_b32 s13, s77
	s_lshl_b32 s12, s29, 1
	s_waitcnt vmcnt(0)
	v_mul_f32_e32 v160, 0.5, v132
	v_mul_f32_e32 v161, 0.5, v133
	v_mul_f32_e32 v156, 0.5, v150
	v_mul_f32_e32 v157, 0.5, v151
	v_mul_f32_e32 v158, 0.5, v148
	v_mul_f32_e32 v159, 0.5, v149
	v_mul_f32_e32 v162, 0.5, v130
	v_mul_f32_e32 v163, 0.5, v131
	global_load_dwordx4 v[130:133], v0, s[16:17] offset:528
	global_load_dwordx4 v[148:151], v0, s[16:17] offset:512
	v_lshlrev_b32_e32 v0, 1, v142
	s_waitcnt vmcnt(0)
	v_mul_f32_e32 v152, 0.5, v148
	v_mul_f32_e32 v153, 0.5, v149
	v_mul_f32_e32 v148, 0.5, v130
	v_mul_f32_e32 v149, 0.5, v131
	v_lshl_add_u32 v130, s36, 8, v143
	v_ashrrev_i32_e32 v131, 31, v130
	v_lshlrev_b64 v[130:131], 11, v[130:131]
	v_lshl_add_u64 v[130:131], s[6:7], 0, v[130:131]
	v_lshl_add_u64 v[130:131], s[14:15], 1, v[130:131]
	v_lshl_add_u64 v[130:131], v[130:131], 0, v[0:1]
	v_lshl_add_u64 v[164:165], v[130:131], 0, s[12:13]
	global_load_dwordx4 v[170:173], v[164:165], off
	global_load_dwordx4 v[174:177], v[164:165], off offset:256
	v_add_co_u32_e32 v166, vcc, s75, v164
	v_mul_f32_e32 v154, 0.5, v150
	v_mul_f32_e32 v155, 0.5, v151
	s_nop 0
	v_addc_co_u32_e32 v167, vcc, 0, v165, vcc
	v_mul_f32_e32 v150, 0.5, v132
	v_mul_f32_e32 v151, 0.5, v133
	global_load_dwordx4 v[178:181], v[166:167], off
	global_load_dwordx4 v[130:133], v[166:167], off offset:256
	s_mov_b32 s14, 0x10000
	s_waitcnt vmcnt(3)
	v_lshlrev_b32_e32 v182, 16, v170
	v_and_b32_e32 v183, 0xffff0000, v170
	v_lshlrev_b32_e32 v170, 16, v171
	v_and_b32_e32 v171, 0xffff0000, v171
	v_lshlrev_b32_e32 v184, 16, v172
	v_and_b32_e32 v185, 0xffff0000, v172
	v_lshlrev_b32_e32 v172, 16, v173
	v_and_b32_e32 v173, 0xffff0000, v173
	v_fma_f32 v128, v128, v156, v170
	v_fma_f32 v129, v129, v157, v171
	v_fma_f32 v126, v126, v158, v182
	v_fma_f32 v127, v127, v159, v183
	v_fma_f32 v170, v124, v160, v172
	v_fma_f32 v171, v125, v161, v173
	v_fma_f32 v124, v122, v162, v184
	v_fma_f32 v125, v123, v163, v185
	v_cvt_pk_bf16_f32 v122, v126, v127
	v_cvt_pk_bf16_f32 v123, v128, v129
	s_waitcnt vmcnt(2)
	v_lshlrev_b32_e32 v126, 16, v176
	v_cvt_pk_bf16_f32 v124, v124, v125
	v_cvt_pk_bf16_f32 v125, v170, v171
	global_store_dwordx4 v[164:165], v[122:125], off
	v_and_b32_e32 v127, 0xffff0000, v176
	v_lshlrev_b32_e32 v128, 16, v177
	v_lshlrev_b32_e32 v122, 16, v174
	v_and_b32_e32 v123, 0xffff0000, v174
	v_and_b32_e32 v129, 0xffff0000, v177
	v_lshlrev_b32_e32 v124, 16, v175
	v_and_b32_e32 v125, 0xffff0000, v175
	v_fma_f32 v118, v118, v152, v122
	v_fma_f32 v119, v119, v153, v123
	v_fma_f32 v122, v116, v150, v128
	v_fma_f32 v123, v117, v151, v129
	v_fma_f32 v116, v114, v148, v126
	v_fma_f32 v117, v115, v149, v127
	v_fma_f32 v120, v120, v154, v124
	v_fma_f32 v121, v121, v155, v125
	v_cvt_pk_bf16_f32 v114, v118, v119
	s_waitcnt vmcnt(2)
	v_lshlrev_b32_e32 v124, 16, v178
	v_cvt_pk_bf16_f32 v115, v120, v121
	v_cvt_pk_bf16_f32 v116, v116, v117
	v_cvt_pk_bf16_f32 v117, v122, v123
	global_store_dwordx4 v[164:165], v[114:117], off offset:256
	v_add_co_u32_e32 v122, vcc, s14, v164
	v_and_b32_e32 v125, 0xffff0000, v178
	s_nop 0
	v_addc_co_u32_e32 v123, vcc, 0, v165, vcc
	v_lshlrev_b32_e32 v126, 16, v179
	v_and_b32_e32 v127, 0xffff0000, v179
	v_lshlrev_b32_e32 v128, 16, v180
	v_and_b32_e32 v129, 0xffff0000, v180
	v_lshlrev_b32_e32 v170, 16, v181
	v_and_b32_e32 v171, 0xffff0000, v181
	global_load_dwordx4 v[118:121], v[122:123], off
	global_load_dwordx4 v[114:117], v[122:123], off offset:256
	v_fma_f32 v112, v112, v156, v126
	v_fma_f32 v113, v113, v157, v127
	v_fma_f32 v110, v110, v158, v124
	v_fma_f32 v111, v111, v159, v125
	v_fma_f32 v124, v108, v160, v170
	v_fma_f32 v125, v109, v161, v171
	v_fma_f32 v108, v106, v162, v128
	v_fma_f32 v109, v107, v163, v129
	v_cvt_pk_bf16_f32 v106, v110, v111
	v_cvt_pk_bf16_f32 v107, v112, v113
	s_waitcnt vmcnt(4)
	v_lshlrev_b32_e32 v110, 16, v132
	v_cvt_pk_bf16_f32 v108, v108, v109
	v_cvt_pk_bf16_f32 v109, v124, v125
	global_store_dwordx4 v[166:167], v[106:109], off
	v_and_b32_e32 v111, 0xffff0000, v132
	v_lshlrev_b32_e32 v112, 16, v133
	v_lshlrev_b32_e32 v106, 16, v130
	v_and_b32_e32 v107, 0xffff0000, v130
	v_and_b32_e32 v113, 0xffff0000, v133
	v_lshlrev_b32_e32 v108, 16, v131
	v_and_b32_e32 v109, 0xffff0000, v131
	v_fma_f32 v102, v102, v152, v106
	v_fma_f32 v103, v103, v153, v107
	v_fma_f32 v106, v100, v150, v112
	v_fma_f32 v107, v101, v151, v113
	v_fma_f32 v100, v98, v148, v110
	v_fma_f32 v101, v99, v149, v111
	s_mov_b32 s14, 0x18000
	v_fma_f32 v104, v104, v154, v108
	v_fma_f32 v105, v105, v155, v109
	v_cvt_pk_bf16_f32 v98, v102, v103
	v_add_co_u32_e32 v102, vcc, s14, v164
	v_cvt_pk_bf16_f32 v99, v104, v105
	v_cvt_pk_bf16_f32 v100, v100, v101
	v_cvt_pk_bf16_f32 v101, v106, v107
	global_store_dwordx4 v[166:167], v[98:101], off offset:256
	s_nop 0
	v_addc_co_u32_e32 v103, vcc, 0, v165, vcc
	global_load_dwordx4 v[104:107], v[102:103], off
	global_load_dwordx4 v[98:101], v[102:103], off offset:256
	s_mov_b32 s14, 0x40000
	s_waitcnt vmcnt(5)
	v_lshlrev_b32_e32 v108, 16, v118
	v_and_b32_e32 v109, 0xffff0000, v118
	v_lshlrev_b32_e32 v110, 16, v119
	v_and_b32_e32 v111, 0xffff0000, v119
	v_lshlrev_b32_e32 v112, 16, v120
	v_and_b32_e32 v113, 0xffff0000, v120
	v_lshlrev_b32_e32 v118, 16, v121
	v_and_b32_e32 v119, 0xffff0000, v121
	v_fma_f32 v96, v96, v156, v110
	v_fma_f32 v97, v97, v157, v111
	v_fma_f32 v94, v94, v158, v108
	v_fma_f32 v95, v95, v159, v109
	v_fma_f32 v108, v92, v160, v118
	v_fma_f32 v109, v93, v161, v119
	v_fma_f32 v92, v90, v162, v112
	v_fma_f32 v93, v91, v163, v113
	v_cvt_pk_bf16_f32 v90, v94, v95
	v_cvt_pk_bf16_f32 v91, v96, v97
	s_waitcnt vmcnt(4)
	v_lshlrev_b32_e32 v94, 16, v116
	v_cvt_pk_bf16_f32 v92, v92, v93
	v_cvt_pk_bf16_f32 v93, v108, v109
	global_store_dwordx4 v[122:123], v[90:93], off
	v_and_b32_e32 v95, 0xffff0000, v116
	v_lshlrev_b32_e32 v96, 16, v117
	v_lshlrev_b32_e32 v90, 16, v114
	v_and_b32_e32 v91, 0xffff0000, v114
	v_and_b32_e32 v97, 0xffff0000, v117
	v_lshlrev_b32_e32 v92, 16, v115
	v_and_b32_e32 v93, 0xffff0000, v115
	v_fma_f32 v86, v86, v152, v90
	v_fma_f32 v87, v87, v153, v91
	v_fma_f32 v90, v84, v150, v96
	v_fma_f32 v91, v85, v151, v97
	v_fma_f32 v84, v82, v148, v94
	v_fma_f32 v85, v83, v149, v95
	v_fma_f32 v88, v88, v154, v92
	v_fma_f32 v89, v89, v155, v93
	v_cvt_pk_bf16_f32 v82, v86, v87
	s_waitcnt vmcnt(2)
	v_lshlrev_b32_e32 v92, 16, v104
	v_cvt_pk_bf16_f32 v83, v88, v89
	v_cvt_pk_bf16_f32 v84, v84, v85
	v_cvt_pk_bf16_f32 v85, v90, v91
	global_store_dwordx4 v[122:123], v[82:85], off offset:256
	v_add_co_u32_e32 v90, vcc, s14, v164
	v_and_b32_e32 v93, 0xffff0000, v104
	s_nop 0
	v_addc_co_u32_e32 v91, vcc, 0, v165, vcc
	v_lshlrev_b32_e32 v94, 16, v105
	v_and_b32_e32 v95, 0xffff0000, v105
	v_lshlrev_b32_e32 v96, 16, v106
	v_and_b32_e32 v97, 0xffff0000, v106
	v_lshlrev_b32_e32 v104, 16, v107
	v_and_b32_e32 v105, 0xffff0000, v107
	global_load_dwordx4 v[86:89], v[90:91], off
	global_load_dwordx4 v[82:85], v[90:91], off offset:256
	v_fma_f32 v80, v80, v156, v94
	v_fma_f32 v81, v81, v157, v95
	v_fma_f32 v78, v78, v158, v92
	v_fma_f32 v79, v79, v159, v93
	v_fma_f32 v92, v76, v160, v104
	v_fma_f32 v93, v77, v161, v105
	v_fma_f32 v76, v74, v162, v96
	v_fma_f32 v77, v75, v163, v97
	v_cvt_pk_bf16_f32 v74, v78, v79
	v_cvt_pk_bf16_f32 v75, v80, v81
	s_waitcnt vmcnt(4)
	v_lshlrev_b32_e32 v78, 16, v100
	v_cvt_pk_bf16_f32 v76, v76, v77
	v_cvt_pk_bf16_f32 v77, v92, v93
	global_store_dwordx4 v[102:103], v[74:77], off
	v_and_b32_e32 v79, 0xffff0000, v100
	v_lshlrev_b32_e32 v80, 16, v101
	v_lshlrev_b32_e32 v74, 16, v98
	v_and_b32_e32 v75, 0xffff0000, v98
	v_and_b32_e32 v81, 0xffff0000, v101
	v_lshlrev_b32_e32 v76, 16, v99
	v_and_b32_e32 v77, 0xffff0000, v99
	v_fma_f32 v70, v70, v152, v74
	v_fma_f32 v71, v71, v153, v75
	v_fma_f32 v74, v68, v150, v80
	v_fma_f32 v75, v69, v151, v81
	v_fma_f32 v68, v66, v148, v78
	v_fma_f32 v69, v67, v149, v79
	s_mov_b32 s14, 0x48000
	v_fma_f32 v72, v72, v154, v76
	v_fma_f32 v73, v73, v155, v77
	v_cvt_pk_bf16_f32 v66, v70, v71
	v_add_co_u32_e32 v70, vcc, s14, v164
	v_cvt_pk_bf16_f32 v67, v72, v73
	v_cvt_pk_bf16_f32 v68, v68, v69
	v_cvt_pk_bf16_f32 v69, v74, v75
	global_store_dwordx4 v[102:103], v[66:69], off offset:256
	s_nop 0
	v_addc_co_u32_e32 v71, vcc, 0, v165, vcc
	global_load_dwordx4 v[72:75], v[70:71], off
	global_load_dwordx4 v[66:69], v[70:71], off offset:256
	s_mov_b32 s14, 0x50000
	s_waitcnt vmcnt(5)
	v_lshlrev_b32_e32 v76, 16, v86
	v_and_b32_e32 v77, 0xffff0000, v86
	v_lshlrev_b32_e32 v78, 16, v87
	v_and_b32_e32 v79, 0xffff0000, v87
	v_lshlrev_b32_e32 v80, 16, v88
	v_and_b32_e32 v81, 0xffff0000, v88
	v_lshlrev_b32_e32 v86, 16, v89
	v_and_b32_e32 v87, 0xffff0000, v89
	v_fma_f32 v64, v64, v156, v78
	v_fma_f32 v65, v65, v157, v79
	v_fma_f32 v62, v62, v158, v76
	v_fma_f32 v63, v63, v159, v77
	v_fma_f32 v76, v60, v160, v86
	v_fma_f32 v77, v61, v161, v87
	v_fma_f32 v60, v58, v162, v80
	v_fma_f32 v61, v59, v163, v81
	v_cvt_pk_bf16_f32 v58, v62, v63
	v_cvt_pk_bf16_f32 v59, v64, v65
	s_waitcnt vmcnt(4)
	v_lshlrev_b32_e32 v62, 16, v84
	v_cvt_pk_bf16_f32 v60, v60, v61
	v_cvt_pk_bf16_f32 v61, v76, v77
	global_store_dwordx4 v[90:91], v[58:61], off
	v_and_b32_e32 v63, 0xffff0000, v84
	v_lshlrev_b32_e32 v64, 16, v85
	v_lshlrev_b32_e32 v58, 16, v82
	v_and_b32_e32 v59, 0xffff0000, v82
	v_and_b32_e32 v65, 0xffff0000, v85
	v_lshlrev_b32_e32 v60, 16, v83
	v_and_b32_e32 v61, 0xffff0000, v83
	v_fma_f32 v54, v54, v152, v58
	v_fma_f32 v55, v55, v153, v59
	v_fma_f32 v58, v52, v150, v64
	v_fma_f32 v59, v53, v151, v65
	v_fma_f32 v52, v50, v148, v62
	v_fma_f32 v53, v51, v149, v63
	v_fma_f32 v56, v56, v154, v60
	v_fma_f32 v57, v57, v155, v61
	v_cvt_pk_bf16_f32 v50, v54, v55
	s_waitcnt vmcnt(2)
	v_lshlrev_b32_e32 v60, 16, v72
	v_cvt_pk_bf16_f32 v51, v56, v57
	v_cvt_pk_bf16_f32 v52, v52, v53
	v_cvt_pk_bf16_f32 v53, v58, v59
	global_store_dwordx4 v[90:91], v[50:53], off offset:256
	v_add_co_u32_e32 v58, vcc, s14, v164
	v_and_b32_e32 v61, 0xffff0000, v72
	s_nop 0
	v_addc_co_u32_e32 v59, vcc, 0, v165, vcc
	v_lshlrev_b32_e32 v62, 16, v73
	v_and_b32_e32 v63, 0xffff0000, v73
	v_lshlrev_b32_e32 v64, 16, v74
	v_and_b32_e32 v65, 0xffff0000, v74
	v_lshlrev_b32_e32 v72, 16, v75
	v_and_b32_e32 v73, 0xffff0000, v75
	global_load_dwordx4 v[54:57], v[58:59], off
	global_load_dwordx4 v[50:53], v[58:59], off offset:256
	v_fma_f32 v48, v48, v156, v62
	v_fma_f32 v49, v49, v157, v63
	v_fma_f32 v46, v46, v158, v60
	v_fma_f32 v47, v47, v159, v61
	v_fma_f32 v60, v44, v160, v72
	v_fma_f32 v61, v45, v161, v73
	v_fma_f32 v44, v42, v162, v64
	v_fma_f32 v45, v43, v163, v65
	v_cvt_pk_bf16_f32 v42, v46, v47
	v_cvt_pk_bf16_f32 v43, v48, v49
	s_waitcnt vmcnt(4)
	v_lshlrev_b32_e32 v46, 16, v68
	v_cvt_pk_bf16_f32 v44, v44, v45
	v_cvt_pk_bf16_f32 v45, v60, v61
	global_store_dwordx4 v[70:71], v[42:45], off
	v_and_b32_e32 v47, 0xffff0000, v68
	v_lshlrev_b32_e32 v48, 16, v69
	v_lshlrev_b32_e32 v42, 16, v66
	v_and_b32_e32 v43, 0xffff0000, v66
	v_and_b32_e32 v49, 0xffff0000, v69
	v_lshlrev_b32_e32 v44, 16, v67
	v_and_b32_e32 v45, 0xffff0000, v67
	v_fma_f32 v38, v38, v152, v42
	v_fma_f32 v39, v39, v153, v43
	v_fma_f32 v42, v36, v150, v48
	v_fma_f32 v43, v37, v151, v49
	v_fma_f32 v36, v34, v148, v46
	v_fma_f32 v37, v35, v149, v47
	v_cvt_pk_bf16_f32 v34, v38, v39
	s_mov_b32 s14, 0x58000
	v_fma_f32 v40, v40, v154, v44
	v_fma_f32 v41, v41, v155, v45
	s_waitcnt vmcnt(2)
	v_lshlrev_b32_e32 v44, 16, v54
	v_cvt_pk_bf16_f32 v35, v40, v41
	v_cvt_pk_bf16_f32 v36, v36, v37
	v_cvt_pk_bf16_f32 v37, v42, v43
	global_store_dwordx4 v[70:71], v[34:37], off offset:256
	v_and_b32_e32 v45, 0xffff0000, v54
	v_lshlrev_b32_e32 v46, 16, v55
	v_add_co_u32_e32 v34, vcc, s14, v164
	v_and_b32_e32 v47, 0xffff0000, v55
	s_nop 0
	v_addc_co_u32_e32 v35, vcc, 0, v165, vcc
	global_load_dwordx4 v[36:39], v[34:35], off
	global_load_dwordx4 v[40:43], v[34:35], off offset:256
	v_lshlrev_b32_e32 v48, 16, v56
	v_and_b32_e32 v49, 0xffff0000, v56
	v_lshlrev_b32_e32 v54, 16, v57
	v_and_b32_e32 v55, 0xffff0000, v57
	v_fma_f32 v32, v32, v156, v46
	v_fma_f32 v33, v33, v157, v47
	v_fma_f32 v30, v30, v158, v44
	v_fma_f32 v31, v31, v159, v45
	v_fma_f32 v44, v28, v160, v54
	v_fma_f32 v45, v29, v161, v55
	v_fma_f32 v28, v26, v162, v48
	v_fma_f32 v29, v27, v163, v49
	v_cvt_pk_bf16_f32 v26, v30, v31
	v_cvt_pk_bf16_f32 v27, v32, v33
	s_waitcnt vmcnt(4)
	v_lshlrev_b32_e32 v30, 16, v52
	v_cvt_pk_bf16_f32 v28, v28, v29
	v_cvt_pk_bf16_f32 v29, v44, v45
	global_store_dwordx4 v[58:59], v[26:29], off
	v_and_b32_e32 v31, 0xffff0000, v52
	v_lshlrev_b32_e32 v32, 16, v53
	v_lshlrev_b32_e32 v26, 16, v50
	v_and_b32_e32 v27, 0xffff0000, v50
	v_and_b32_e32 v33, 0xffff0000, v53
	v_lshlrev_b32_e32 v28, 16, v51
	v_and_b32_e32 v29, 0xffff0000, v51
	v_fma_f32 v22, v22, v152, v26
	v_fma_f32 v23, v23, v153, v27
	v_fma_f32 v26, v20, v150, v32
	v_fma_f32 v27, v21, v151, v33
	v_fma_f32 v20, v18, v148, v30
	v_fma_f32 v21, v19, v149, v31
	v_fma_f32 v24, v24, v154, v28
	v_fma_f32 v25, v25, v155, v29
	v_cvt_pk_bf16_f32 v18, v22, v23
	s_mov_b64 s[14:15], -1
	v_cvt_pk_bf16_f32 v19, v24, v25
	v_cvt_pk_bf16_f32 v20, v20, v21
	v_cvt_pk_bf16_f32 v21, v26, v27
	global_store_dwordx4 v[58:59], v[18:21], off offset:256
	s_and_b64 vcc, exec, s[4:5]
	s_waitcnt vmcnt(3)
	v_lshlrev_b32_e32 v22, 16, v38
	v_lshlrev_b32_e32 v18, 16, v36
	v_and_b32_e32 v19, 0xffff0000, v36
	v_lshlrev_b32_e32 v20, 16, v37
	v_and_b32_e32 v21, 0xffff0000, v37
	v_and_b32_e32 v23, 0xffff0000, v38
	v_lshlrev_b32_e32 v24, 16, v39
	v_and_b32_e32 v25, 0xffff0000, v39
	v_fma_f32 v16, v16, v156, v20
	v_fma_f32 v17, v17, v157, v21
	v_fma_f32 v14, v14, v158, v18
	v_fma_f32 v15, v15, v159, v19
	v_fma_f32 v18, v12, v160, v24
	v_fma_f32 v19, v13, v161, v25
	v_fma_f32 v12, v10, v162, v22
	v_fma_f32 v13, v11, v163, v23
	v_cvt_pk_bf16_f32 v10, v14, v15
	v_cvt_pk_bf16_f32 v11, v16, v17
	s_waitcnt vmcnt(2)
	v_lshlrev_b32_e32 v14, 16, v42
	v_cvt_pk_bf16_f32 v12, v12, v13
	v_cvt_pk_bf16_f32 v13, v18, v19
	global_store_dwordx4 v[34:35], v[10:13], off
	v_and_b32_e32 v15, 0xffff0000, v42
	v_lshlrev_b32_e32 v16, 16, v43
	v_lshlrev_b32_e32 v10, 16, v40
	v_and_b32_e32 v11, 0xffff0000, v40
	v_and_b32_e32 v17, 0xffff0000, v43
	v_lshlrev_b32_e32 v12, 16, v41
	v_and_b32_e32 v13, 0xffff0000, v41
	v_fma_f32 v6, v6, v152, v10
	v_fma_f32 v7, v7, v153, v11
	v_fma_f32 v10, v4, v150, v16
	v_fma_f32 v11, v5, v151, v17
	v_fma_f32 v4, v2, v148, v14
	v_fma_f32 v5, v3, v149, v15
	v_fma_f32 v8, v8, v154, v12
	v_fma_f32 v9, v9, v155, v13
	v_cvt_pk_bf16_f32 v2, v6, v7
	s_nop 0
	v_cvt_pk_bf16_f32 v3, v8, v9
	v_cvt_pk_bf16_f32 v4, v4, v5
	v_cvt_pk_bf16_f32 v5, v10, v11
	global_store_dwordx4 v[34:35], v[2:5], off offset:256
	s_cbranch_vccnz .LBB0_2596
	s_andn2_b64 vcc, exec, s[2:3]
	s_cbranch_vccnz .LBB0_2595
	s_barrier
	s_branch .LBB0_2595

.LBB0_2675:
	global_load_dwordx2 v[18:19], v[4:5], off offset:-1536
	global_load_dwordx2 v[20:21], v[4:5], off offset:-1024
	global_load_dwordx2 v[22:23], v[4:5], off offset:-512
	global_load_dwordx2 v[24:25], v[4:5], off
	global_load_dwordx4 v[14:17], v[2:3], off
	s_add_i32 s8, s0, 0xffff8000
	s_lshl_b64 s[10:11], s[8:9], 10
	s_add_u32 s1, s10, 0x2000000
	s_addc_u32 s8, s11, 0
	s_cmp_lt_i32 s0, 0x8000
	s_cselect_b32 s11, s5, s8
	s_cselect_b32 s10, s4, s1
	v_lshl_add_u64 v[26:27], s[10:11], 2, v[0:1]
	s_add_i32 s0, s0, s12
	s_add_u32 s4, s4, s6
	s_addc_u32 s5, s5, s7
	v_lshl_add_u64 v[4:5], v[4:5], 0, s[2:3]
	s_cmp_lt_i32 s0, 0x8200
	s_waitcnt vmcnt(4)
	v_lshlrev_b32_e32 v28, 16, v18
	v_and_b32_e32 v29, 0xffff0000, v18
	v_lshlrev_b32_e32 v18, 16, v19
	v_and_b32_e32 v19, 0xffff0000, v19
	s_waitcnt vmcnt(3)
	v_lshlrev_b32_e32 v31, 16, v21
	v_lshlrev_b32_e32 v30, 16, v20
	v_and_b32_e32 v21, 0xffff0000, v21
	v_and_b32_e32 v20, 0xffff0000, v20
	s_waitcnt vmcnt(2)
	v_and_b32_e32 v33, 0xffff0000, v22
	s_waitcnt vmcnt(1)
	v_lshlrev_b32_e32 v35, 16, v24
	v_and_b32_e32 v37, 0xffff0000, v24
	v_mul_f32_e32 v34, v19, v19
	v_mul_f32_e32 v36, v29, v29
	v_lshlrev_b32_e32 v32, 16, v22
	v_lshlrev_b32_e32 v22, 16, v23
	v_and_b32_e32 v23, 0xffff0000, v23
	v_mul_f32_e32 v38, v20, v20
	v_mul_f32_e32 v39, v21, v21
	v_mov_b32_e32 v41, v35
	v_mul_f32_e32 v40, v33, v33
	v_fma_f32 v44, v18, v18, v34
	v_fma_f32 v45, v19, v19, v34
	v_fma_f32 v46, v28, v28, v36
	v_fma_f32 v47, v29, v29, v36
	v_lshlrev_b32_e32 v24, 16, v25
	v_and_b32_e32 v25, 0xffff0000, v25
	v_mul_f32_e32 v42, v23, v23
	v_fma_f32 v38, v30, v30, v38
	v_fma_f32 v39, v31, v31, v39
	v_fma_f32 v48, v32, v32, v40
	v_fma_f32 v49, v33, v33, v40
	v_mov_b32_e32 v34, v46
	v_mov_b32_e32 v40, v44
	v_mul_f32_e32 v13, v37, v37
	v_mul_f32_e32 v50, v24, v24
	v_mul_f32_e32 v51, v25, v25
	v_fma_f32 v43, v23, v23, v42
	v_fma_f32 v42, v22, v22, v42
	v_add_f32_e32 v44, v46, v44
	v_add_f32_e32 v45, v47, v45
	v_pk_add_f32 v[38:39], v[38:39], v[38:39] op_sel:[0,1] op_sel_hi:[1,0]
	v_mul_f32_e32 v40, v34, v40
	v_mul_f32_e32 v41, v35, v41
	v_mov_b32_e32 v49, v50
	v_mov_b32_e32 v43, v51
	v_mov_b32_e32 v39, v13
	v_mov_b32_e32 v45, v41
	v_add_f32_e32 v42, v48, v42
	v_add_f32_e32 v43, v49, v43
	v_add_f32_e32 v38, v44, v38
	v_add_f32_e32 v39, v45, v39
	v_mov_b32_e32 v36, v35
	v_add_f32_e32 v38, v38, v42
	v_add_f32_e32 v39, v39, v43
	s_nop 0
	v_add_f32_e32 v13, v38, v39
	ds_bpermute_b32 v34, v6, v13
	s_waitcnt lgkmcnt(0)
	v_add_f32_e32 v13, v13, v34
	ds_bpermute_b32 v34, v7, v13
	s_waitcnt lgkmcnt(0)
	v_add_f32_e32 v13, v13, v34
	ds_bpermute_b32 v34, v8, v13
	s_waitcnt lgkmcnt(0)
	v_add_f32_e32 v13, v13, v34
	ds_bpermute_b32 v34, v9, v13
	s_waitcnt lgkmcnt(0)
	v_add_f32_e32 v13, v13, v34
	ds_bpermute_b32 v34, v10, v13
	s_waitcnt lgkmcnt(0)
	v_add_f32_e32 v13, v13, v34
	ds_bpermute_b32 v34, v11, v13
	s_waitcnt lgkmcnt(0)
	v_add_f32_e32 v13, v13, v34
	v_fmamk_f32 v13, v13, 0x3a800000, v12
	v_rsq_f32_e32 v34, v13
	s_nop 0
	v_mul_f32_e32 v28, v34, v28
	v_mul_f32_e32 v29, v34, v29
	v_mul_f32_e32 v18, v34, v18
	v_mul_f32_e32 v19, v34, v19
	s_waitcnt vmcnt(0)
	v_mul_f32_e32 v16, v16, v18
	v_mul_f32_e32 v17, v17, v19
	v_mul_f32_e32 v14, v14, v28
	v_mul_f32_e32 v15, v15, v29
	global_store_dwordx4 v[26:27], v[14:17], off
	global_load_dwordx4 v[14:17], v[2:3], off offset:1024
	v_mov_b32_e32 v18, v31
	v_mov_b32_e32 v19, v21
	v_mov_b32_e32 v31, v20
	v_mul_f32_e32 v18, v34, v18
	v_mul_f32_e32 v19, v34, v19
	v_mul_f32_e32 v20, v34, v30
	v_mul_f32_e32 v21, v34, v31
	s_waitcnt vmcnt(0)
	v_mul_f32_e32 v14, v14, v20
	v_mul_f32_e32 v15, v15, v21
	v_mul_f32_e32 v16, v16, v18
	v_mul_f32_e32 v17, v17, v19
	global_store_dwordx4 v[26:27], v[14:17], off offset:1024
	global_load_dwordx4 v[14:17], v[2:3], off offset:2048
	v_mul_f32_e32 v18, v34, v22
	v_mul_f32_e32 v19, v34, v23
	v_mul_f32_e32 v20, v34, v32
	v_mul_f32_e32 v21, v34, v33
	s_waitcnt vmcnt(0)
	v_mul_f32_e32 v14, v14, v20
	v_mul_f32_e32 v15, v15, v21
	v_mul_f32_e32 v16, v16, v18
	v_mul_f32_e32 v17, v17, v19
	global_store_dwordx4 v[26:27], v[14:17], off offset:2048
	global_load_dwordx4 v[14:17], v[2:3], off offset:3072
	v_mul_f32_e32 v18, v24, v34
	v_mul_f32_e32 v19, v25, v34
	v_mul_f32_e32 v20, v36, v34
	v_mul_f32_e32 v21, v37, v34
	s_waitcnt vmcnt(0)
	v_mul_f32_e32 v16, v16, v18
	v_mul_f32_e32 v17, v17, v19
	v_mul_f32_e32 v14, v14, v20
	v_mul_f32_e32 v15, v15, v21
	global_store_dwordx4 v[26:27], v[14:17], off offset:3072
	s_cbranch_scc1 .LBB0_2675
